# all 8- and 16-byte global stores write-through (sc1), not only the GEMM epilogues
# baseline (speedup 1.0000x reference)
; DI void phase_prep(const Params& p, char* smem) {
;     ...
;     const int n4 = 2048 * 1024 / 4;
;     for (int i = blockIdx.x * 256 + threadIdx.x; i < n4; i += gridDim.x * 256) {
;       float4 v = ((const float4*)p.mem_prompt)[i];
;       uint2 o;
;       o.x = pack2(v.x, v.y);
;       o.y = pack2(v.z, v.w);
;       ((uint2*)p.MPB)[i] = o;
;     }
.LBB0_42:
	s_or_b64 exec, exec, s[0:1]
	s_mov_b32 s0, 0x80000
	v_cmp_gt_i32_e32 vcc, s0, v0
	s_and_saveexec_b64 s[0:1], vcc
	s_cbranch_execz .LBB0_45
	s_load_dwordx2 s[2:3], s[92:93], 0x40
	s_load_dwordx2 s[4:5], s[92:93], 0x180
	s_cmp_eq_u32 s34, 0x200
	s_cbranch_scc0 .Lprep_mp_slow
	v_lshlrev_b32_e32 v1, 4, v0
	v_lshlrev_b32_e32 v2, 3, v0
	s_waitcnt lgkmcnt(0)
	global_load_dwordx4 v[4:7], v1, s[2:3]
	s_add_u32 s2, s2, 0x200000
	s_addc_u32 s3, s3, 0
	global_load_dwordx4 v[8:11], v1, s[2:3]
	s_add_u32 s2, s2, 0x200000
	s_addc_u32 s3, s3, 0
	global_load_dwordx4 v[12:15], v1, s[2:3]
	s_add_u32 s2, s2, 0x200000
	s_addc_u32 s3, s3, 0
	global_load_dwordx4 v[16:19], v1, s[2:3]
	s_waitcnt vmcnt(3)
	v_cvt_pk_bf16_f32 v4, v4, v5
	v_cvt_pk_bf16_f32 v5, v6, v7
	s_waitcnt vmcnt(2)
	v_cvt_pk_bf16_f32 v8, v8, v9
	v_cvt_pk_bf16_f32 v9, v10, v11
	s_waitcnt vmcnt(1)
	v_cvt_pk_bf16_f32 v12, v12, v13
	v_cvt_pk_bf16_f32 v13, v14, v15
	s_waitcnt vmcnt(0)
	v_cvt_pk_bf16_f32 v16, v16, v17
	v_cvt_pk_bf16_f32 v17, v18, v19
	global_store_dwordx2 v2, v[4:5], s[4:5] sc1
	s_add_u32 s4, s4, 0x100000
	s_addc_u32 s5, s5, 0
	global_store_dwordx2 v2, v[8:9], s[4:5] sc1
	s_add_u32 s4, s4, 0x100000
	s_addc_u32 s5, s5, 0
	global_store_dwordx2 v2, v[12:13], s[4:5] sc1
	s_add_u32 s4, s4, 0x100000
	s_addc_u32 s5, s5, 0
	global_store_dwordx2 v2, v[16:17], s[4:5] sc1
	s_branch .LBB0_45

; DI void phase_prep(const Params& p, char* smem) {
;     ...
;     for (int i = blockIdx.x * 256 + threadIdx.x; i < n4; i += gridDim.x * 256) {
;       float4 v = ((const float4*)p.mem_prompt)[i];
;       uint2 o;
;       o.x = pack2(v.x, v.y);
;       o.y = pack2(v.z, v.w);
;       ((uint2*)p.MPB)[i] = o;
;     }
.LBB0_44:
	v_ashrrev_i32_e32 v1, 31, v0
	s_waitcnt lgkmcnt(0)
	v_lshl_add_u64 v[2:3], v[0:1], 4, s[2:3]
	global_load_dwordx4 v[2:5], v[2:3], off
	v_lshl_add_u64 v[6:7], v[0:1], 3, s[4:5]
	v_add_u32_e32 v0, s8, v0
	v_cmp_lt_i32_e32 vcc, s9, v0
	s_or_b64 s[6:7], vcc, s[6:7]
	s_waitcnt vmcnt(0)
	v_cvt_pk_bf16_f32 v2, v2, v3
	v_cvt_pk_bf16_f32 v3, v4, v5
	global_store_dwordx2 v[6:7], v[2:3], off sc1
	s_andn2_b64 exec, exec, s[6:7]
	s_cbranch_execnz .LBB0_44

; DI void phase_prep(const Params& p, char* smem) {
;     ...
;     for (int row = blockIdx.x * 4 + wid; row < NROW; row += gridDim.x * 4) {
;       const float* xr = row < NPR ? p.x_prompt + (size_t)row * DM : p.x_sample + (size_t)(row - NPR) * DM;
;       float4 v[4];
;       float ss = 0.f;
; #pragma unroll
;       for (int j = 0; j < 4; ++j) {
;         v[j] = ((const float4*)xr)[j * 64 + lane];
;         ss += v[j].x * v[j].x + v[j].y * v[j].y + v[j].z * v[j].z + v[j].w * v[j].w;
;       }
;       ss = wave_sum(ss);
;       float inv = rsqrtf(ss * (1.0f / 1024.0f) + EPSF);
;       float part[8];
; #pragma unroll
;       for (int c = 0; c < 8; ++c) part[c] = 0.f;
; #pragma unroll
;       for (int j = 0; j < 4; ++j) {
;         float4 g = ((const float4*)p.norm_mix)[j * 64 + lane];
;         uint2 o;
;         const float h0 = v[j].x * inv * g.x, h1 = v[j].y * inv * g.y, h2 = v[j].z * inv * g.z, h3 = v[j].w * inv * g.w;
;         o.x = pack2(h0, h1);
;         o.y = pack2(h2, h3);
;         ((uint2*)(p.H + (size_t)row * DM))[j * 64 + lane] = o;
; #pragma unroll
;         for (int c = 0; c < 8; ++c) {
;           float4 w = ((const float4*)(wT + c * 1024))[j * 64 + lane];
;           part[c] += h0 * w.x + h1 * w.y + h2 * w.z + h3 * w.w;
;         }
;       }
.Lprep_nopf:
	v_mov_b32_e32 v162, v200
	v_mov_b32_e32 v163, v201
	v_mov_b32_e32 v164, v202
	v_mov_b32_e32 v165, v203
	v_mov_b32_e32 v142, 0
	v_mov_b32_e32 v176, 0
	v_mov_b32_e32 v177, 0
	v_mov_b32_e32 v166, v137
	v_mov_b32_e32 v167, v157
	v_mov_b32_e32 v154, v136
	v_mov_b32_e32 v155, v156
	v_mov_b32_e32 v174, v129
	v_mov_b32_e32 v175, v133
	v_pk_mul_f32 v[166:167], v[166:167], v[166:167]
	v_mov_b32_e32 v150, v138
	v_mov_b32_e32 v151, v158
	v_mov_b32_e32 v172, v128
	v_mov_b32_e32 v173, v132
	v_pk_mul_f32 v[174:175], v[174:175], v[174:175]
	v_pk_fma_f32 v[154:155], v[154:155], v[154:155], v[166:167]
	v_mov_b32_e32 v152, v139
	v_mov_b32_e32 v153, v159
	v_mov_b32_e32 v168, v130
	v_mov_b32_e32 v169, v134
	v_pk_fma_f32 v[166:167], v[172:173], v[172:173], v[174:175]
	v_pk_fma_f32 v[150:151], v[150:151], v[150:151], v[154:155]
	v_mov_b32_e32 v170, v131
	v_mov_b32_e32 v171, v135
	v_pk_fma_f32 v[154:155], v[168:169], v[168:169], v[166:167]
	v_pk_fma_f32 v[150:151], v[152:153], v[152:153], v[150:151]
	v_pk_fma_f32 v[152:153], v[170:171], v[170:171], v[154:155]
	v_add_f32_e32 v150, v150, v151
	v_add_f32_e32 v150, v150, v152
	v_add_f32_e32 v150, v150, v153
	v_mov_b32_e32 v166, 0
	v_mov_b32_e32 v168, 0
	v_add_f32_dpp v150, v150, v150 quad_perm:[1,0,3,2] row_mask:0xf bank_mask:0xf bound_ctrl:1
	v_mov_b32_e32 v170, 0
	v_mov_b32_e32 v172, 0
	v_add_f32_dpp v150, v150, v150 quad_perm:[2,3,0,1] row_mask:0xf bank_mask:0xf bound_ctrl:1
	v_mov_b32_e32 v174, 0
	v_mov_b32_e32 v167, 0
	v_add_f32_dpp v150, v150, v150 row_half_mirror row_mask:0xf bank_mask:0xf bound_ctrl:1
	v_mov_b32_e32 v169, 0
	v_mov_b32_e32 v171, 0
	v_add_f32_dpp v150, v150, v150 row_mirror row_mask:0xf bank_mask:0xf bound_ctrl:1
	v_mov_b32_e32 v173, 0
	v_mov_b32_e32 v175, 0
	v_mov_b32_dpp v142, v150 row_bcast:15 row_mask:0xa bank_mask:0xf
	v_add_f32_e32 v142, v150, v142
	s_nop 1
	v_mov_b32_dpp v176, v142 row_bcast:31 row_mask:0xc bank_mask:0xf
	v_add_f32_e32 v142, v142, v176
	v_mov_b32_e32 v176, 0
	v_readlane_b32 s0, v142, 63
	s_nop 1
	v_fma_f32 v142, s0, v161, v160
	v_mul_f32_e32 v150, 0x4b800000, v142
	v_cmp_gt_f32_e64 s[0:1], s14, v142
	s_nop 1
	v_cndmask_b32_e64 v142, v142, v150, s[0:1]
	v_rsq_f32_e32 v142, v142
	v_lshlrev_b64 v[150:151], 11, v[140:141]
	v_lshl_add_u64 v[150:151], v[146:147], 0, v[150:151]
	v_mul_f32_e32 v152, 0x45800000, v142
	v_cndmask_b32_e64 v142, v142, v152, s[0:1]
	v_pk_mul_f32 v[136:137], v[136:137], v[142:143] op_sel_hi:[1,0]
	v_pk_mul_f32 v[138:139], v[138:139], v[142:143] op_sel_hi:[1,0]
	v_pk_mul_f32 v[154:155], v[162:163], v[136:137]
	v_pk_mul_f32 v[152:153], v[164:165], v[138:139]
	v_cvt_pk_bf16_f32 v136, v154, v155
	v_cvt_pk_bf16_f32 v137, v152, v153
	global_store_dwordx2 v[150:151], v[136:137], off sc1
	s_nop 1
	v_mov_b32_e32 v136, v204
	v_mov_b32_e32 v137, v205
	v_mov_b32_e32 v138, v206
	v_mov_b32_e32 v139, v207
	v_pk_mul_f32 v[156:157], v[156:157], v[142:143] op_sel_hi:[1,0]
	v_pk_mul_f32 v[162:163], v[158:159], v[142:143] op_sel_hi:[1,0]
	v_pk_mul_f32 v[128:129], v[128:129], v[142:143] op_sel_hi:[1,0]
	v_pk_mul_f32 v[130:131], v[130:131], v[142:143] op_sel_hi:[1,0]
	v_mul_f32_e32 v178, v155, v9
	v_mul_f32_e32 v179, v155, v17
	v_mul_f32_e32 v180, v155, v25
	v_mul_f32_e32 v181, v155, v33
	v_mul_f32_e32 v182, v155, v41
	v_mul_f32_e32 v183, v155, v49
	v_pk_mul_f32 v[132:133], v[132:133], v[142:143] op_sel_hi:[1,0]
	v_pk_mul_f32 v[134:135], v[134:135], v[142:143] op_sel_hi:[1,0]
	v_mul_f32_e32 v142, v155, v1
	v_mul_f32_e32 v155, v155, v57
	v_fmac_f32_e32 v178, v154, v8
	v_fmac_f32_e32 v179, v154, v16
	v_fmac_f32_e32 v180, v154, v24
	v_fmac_f32_e32 v181, v154, v32
	v_fmac_f32_e32 v182, v154, v40
	v_fmac_f32_e32 v183, v154, v48
	v_fmac_f32_e32 v142, v154, v0
	v_fmac_f32_e32 v155, v154, v56
	v_fmac_f32_e32 v178, v152, v10
	v_fmac_f32_e32 v179, v152, v18
	v_fmac_f32_e32 v180, v152, v26
	v_fmac_f32_e32 v181, v152, v34
	v_fmac_f32_e32 v182, v152, v42
	v_fmac_f32_e32 v183, v152, v50
	v_fmac_f32_e32 v142, v152, v2
	v_fmac_f32_e32 v155, v152, v58
	v_fmac_f32_e32 v178, v153, v11
	v_fmac_f32_e32 v179, v153, v19
	v_fmac_f32_e32 v180, v153, v27
	v_fmac_f32_e32 v181, v153, v35
	v_fmac_f32_e32 v182, v153, v43
	v_fmac_f32_e32 v183, v153, v51
	v_fmac_f32_e32 v142, v153, v3
	v_fmac_f32_e32 v155, v153, v59
	v_add_f32_e32 v152, 0, v178
	v_add_f32_e32 v153, 0, v179
	v_add_f32_e32 v154, 0, v180
	v_add_f32_e32 v178, 0, v181
	v_add_f32_e32 v179, 0, v182
	v_add_f32_e32 v180, 0, v183
	v_add_f32_e32 v142, 0, v142
	v_add_f32_e32 v155, 0, v155
	v_mov_b32_e32 v164, 0
	v_mov_b32_e32 v165, 0
	v_pk_mul_f32 v[158:159], v[156:157], v[136:137]
	v_pk_mul_f32 v[156:157], v[162:163], v[138:139]
	v_cvt_pk_bf16_f32 v136, v158, v159
	v_cvt_pk_bf16_f32 v137, v156, v157
	global_store_dwordx2 v[150:151], v[136:137], off offset:512 sc1
	s_nop 1
	v_mov_b32_e32 v136, v208
	v_mov_b32_e32 v137, v209
	v_mov_b32_e32 v138, v210
	v_mov_b32_e32 v139, v211
	v_mul_f32_e32 v181, v159, v5
	v_mul_f32_e32 v182, v159, v13
	v_mul_f32_e32 v183, v159, v21
	v_mul_f32_e32 v184, v159, v29
	v_mul_f32_e32 v185, v159, v37
	v_mul_f32_e32 v186, v159, v45
	v_mul_f32_e32 v187, v159, v53
	v_mul_f32_e32 v159, v159, v61
	v_fmac_f32_e32 v181, v158, v4
	v_fmac_f32_e32 v182, v158, v12
	v_fmac_f32_e32 v183, v158, v20
	v_fmac_f32_e32 v185, v158, v36
	v_fmac_f32_e32 v186, v158, v44
	v_fmac_f32_e32 v187, v158, v52
	v_fmac_f32_e32 v159, v158, v60
	v_fmac_f32_e32 v184, v158, v28
	v_fmac_f32_e32 v181, v156, v6
	v_fmac_f32_e32 v182, v156, v14
	v_fmac_f32_e32 v183, v156, v22
	v_fmac_f32_e32 v185, v156, v38
	v_fmac_f32_e32 v186, v156, v46
	v_fmac_f32_e32 v187, v156, v54
	v_fmac_f32_e32 v159, v156, v62
	v_fmac_f32_e32 v184, v156, v30
; DI void phase_prep(const Params& p, char* smem) {
;     ...
;       for (int j = 0; j < 4; ++j) {
;         float4 g = ((const float4*)p.norm_mix)[j * 64 + lane];
;         uint2 o;
;         const float h0 = v[j].x * inv * g.x, h1 = v[j].y * inv * g.y, h2 = v[j].z * inv * g.z, h3 = v[j].w * inv * g.w;
;         o.x = pack2(h0, h1);
;         o.y = pack2(h2, h3);
;         ((uint2*)(p.H + (size_t)row * DM))[j * 64 + lane] = o;
; #pragma unroll
;         for (int c = 0; c < 8; ++c) {
;           float4 w = ((const float4*)(wT + c * 1024))[j * 64 + lane];
;           part[c] += h0 * w.x + h1 * w.y + h2 * w.z + h3 * w.w;
;         }
;       }
	v_fmac_f32_e32 v181, v157, v7
	v_fmac_f32_e32 v182, v157, v15
	v_fmac_f32_e32 v183, v157, v23
	v_fmac_f32_e32 v185, v157, v39
	v_fmac_f32_e32 v186, v157, v47
	v_fmac_f32_e32 v187, v157, v55
	v_fmac_f32_e32 v159, v157, v63
	v_fmac_f32_e32 v184, v157, v31
	v_add_f32_e32 v142, v142, v181
	v_add_f32_e32 v152, v152, v182
	v_add_f32_e32 v153, v153, v183
	v_add_f32_e32 v156, v178, v185
	v_add_f32_e32 v157, v179, v186
	v_add_f32_e32 v158, v180, v187
	v_add_f32_e32 v155, v155, v159
	v_add_f32_e32 v154, v154, v184
	v_mov_b32_e32 v162, 0
	v_mov_b32_e32 v163, 0
	v_pk_mul_f32 v[136:137], v[128:129], v[136:137]
	v_pk_mul_f32 v[138:139], v[130:131], v[138:139]
	v_cvt_pk_bf16_f32 v128, v136, v137
	v_cvt_pk_bf16_f32 v129, v138, v139
	global_store_dwordx2 v[150:151], v[128:129], off offset:1024 sc1
	s_nop 1
	v_mov_b32_e32 v128, v212
	v_mov_b32_e32 v129, v213
	v_mov_b32_e32 v130, v214
	v_mov_b32_e32 v131, v215
	v_mul_f32_e32 v159, v137, v65
	v_mul_f32_e32 v178, v137, v73
	v_mul_f32_e32 v179, v137, v81
	v_mul_f32_e32 v180, v137, v89
	v_mul_f32_e32 v181, v137, v97
	v_mul_f32_e32 v182, v137, v105
	v_mul_f32_e32 v183, v137, v113
	v_mul_f32_e32 v137, v137, v121
	v_fmac_f32_e32 v159, v136, v64
	v_fmac_f32_e32 v178, v136, v72
	v_fmac_f32_e32 v179, v136, v80
	v_fmac_f32_e32 v180, v136, v88
	v_fmac_f32_e32 v181, v136, v96
	v_fmac_f32_e32 v182, v136, v104
	v_fmac_f32_e32 v183, v136, v112
	v_fmac_f32_e32 v137, v136, v120
	v_fmac_f32_e32 v159, v138, v66
	v_fmac_f32_e32 v178, v138, v74
	v_fmac_f32_e32 v179, v138, v82
	v_fmac_f32_e32 v180, v138, v90
	v_fmac_f32_e32 v181, v138, v98
	v_fmac_f32_e32 v182, v138, v106
	v_fmac_f32_e32 v183, v138, v114
	v_fmac_f32_e32 v137, v138, v122
	v_fmac_f32_e32 v159, v139, v67
	v_fmac_f32_e32 v178, v139, v75
	v_fmac_f32_e32 v179, v139, v83
	v_fmac_f32_e32 v180, v139, v91
	v_fmac_f32_e32 v181, v139, v99
	v_fmac_f32_e32 v182, v139, v107
	v_fmac_f32_e32 v183, v139, v115
	v_fmac_f32_e32 v137, v139, v123
	v_add_f32_e32 v136, v142, v159
	v_add_f32_e32 v138, v152, v178
	v_add_f32_e32 v139, v153, v179
	v_add_f32_e32 v142, v154, v180
	v_add_f32_e32 v152, v156, v181
	v_add_f32_e32 v153, v157, v182
	v_add_f32_e32 v154, v158, v183
	v_add_f32_e32 v137, v155, v137
	v_pk_mul_f32 v[128:129], v[132:133], v[128:129]
	v_pk_mul_f32 v[130:131], v[134:135], v[130:131]
	v_cvt_pk_bf16_f32 v132, v128, v129
	v_mul_f32_e32 v134, v129, v69
	v_mul_f32_e32 v135, v129, v77
	v_mul_f32_e32 v155, v129, v85
	v_mul_f32_e32 v156, v129, v93
	v_mul_f32_e32 v157, v129, v101
	v_mul_f32_e32 v158, v129, v109
	v_mul_f32_e32 v159, v129, v117
	v_mul_f32_e32 v129, v129, v125
	v_fmac_f32_e32 v134, v128, v68
	v_fmac_f32_e32 v135, v128, v76
	v_fmac_f32_e32 v155, v128, v84
	v_fmac_f32_e32 v156, v128, v92
	v_fmac_f32_e32 v157, v128, v100
	v_fmac_f32_e32 v158, v128, v108
	v_fmac_f32_e32 v159, v128, v116
	v_fmac_f32_e32 v129, v128, v124
	v_fmac_f32_e32 v134, v130, v70
	v_fmac_f32_e32 v135, v130, v78
	v_fmac_f32_e32 v155, v130, v86
	v_fmac_f32_e32 v156, v130, v94
	v_fmac_f32_e32 v157, v130, v102
	v_fmac_f32_e32 v158, v130, v110
	v_fmac_f32_e32 v159, v130, v118
	v_fmac_f32_e32 v129, v130, v126
	v_cvt_pk_bf16_f32 v133, v130, v131
	v_fmac_f32_e32 v134, v131, v71
	v_fmac_f32_e32 v135, v131, v79
	v_fmac_f32_e32 v155, v131, v87
	v_fmac_f32_e32 v156, v131, v95
	v_fmac_f32_e32 v157, v131, v103
	v_fmac_f32_e32 v158, v131, v111
	v_fmac_f32_e32 v159, v131, v119
	v_fmac_f32_e32 v129, v131, v127
	global_store_dwordx2 v[150:151], v[132:133], off offset:1536 sc1
	v_add_f32_e32 v128, v136, v134
	v_add_f32_e32 v130, v138, v135
	v_add_f32_e32 v131, v139, v155
	v_add_f32_e32 v132, v142, v156
	v_add_f32_e32 v133, v152, v157
	v_add_f32_e32 v134, v153, v158
	v_add_f32_e32 v135, v154, v159
	v_add_f32_e32 v129, v137, v129
	v_add_f32_dpp v128, v128, v128 quad_perm:[1,0,3,2] row_mask:0xf bank_mask:0xf bound_ctrl:1
	v_add_f32_dpp v130, v130, v130 quad_perm:[1,0,3,2] row_mask:0xf bank_mask:0xf bound_ctrl:1
	v_add_f32_dpp v131, v131, v131 quad_perm:[1,0,3,2] row_mask:0xf bank_mask:0xf bound_ctrl:1
	v_add_f32_dpp v132, v132, v132 quad_perm:[1,0,3,2] row_mask:0xf bank_mask:0xf bound_ctrl:1
	v_add_f32_dpp v133, v133, v133 quad_perm:[1,0,3,2] row_mask:0xf bank_mask:0xf bound_ctrl:1
	v_add_f32_dpp v134, v134, v134 quad_perm:[1,0,3,2] row_mask:0xf bank_mask:0xf bound_ctrl:1
	v_add_f32_dpp v135, v135, v135 quad_perm:[1,0,3,2] row_mask:0xf bank_mask:0xf bound_ctrl:1
	v_add_f32_dpp v129, v129, v129 quad_perm:[1,0,3,2] row_mask:0xf bank_mask:0xf bound_ctrl:1
; DI void phase_prep(const Params& p, char* smem) {
;     ...
; #pragma unroll
;       for (int c = 0; c < 8; ++c) part[c] = wave_sum(part[c]);
;       if (lane == 0) {
;         float4 a = {part[0], part[1], part[2], part[3]}, b = {part[4], part[5], part[6], part[7]};
;         ((float4*)(p.BGR + (size_t)row * 8))[0] = a;
;         ((float4*)(p.BGR + (size_t)row * 8))[1] = b;
;       }
	v_add_f32_dpp v128, v128, v128 quad_perm:[2,3,0,1] row_mask:0xf bank_mask:0xf bound_ctrl:1
	v_add_f32_dpp v130, v130, v130 quad_perm:[2,3,0,1] row_mask:0xf bank_mask:0xf bound_ctrl:1
	v_add_f32_dpp v131, v131, v131 quad_perm:[2,3,0,1] row_mask:0xf bank_mask:0xf bound_ctrl:1
	v_add_f32_dpp v132, v132, v132 quad_perm:[2,3,0,1] row_mask:0xf bank_mask:0xf bound_ctrl:1
	v_add_f32_dpp v133, v133, v133 quad_perm:[2,3,0,1] row_mask:0xf bank_mask:0xf bound_ctrl:1
	v_add_f32_dpp v134, v134, v134 quad_perm:[2,3,0,1] row_mask:0xf bank_mask:0xf bound_ctrl:1
	v_add_f32_dpp v135, v135, v135 quad_perm:[2,3,0,1] row_mask:0xf bank_mask:0xf bound_ctrl:1
	v_add_f32_dpp v129, v129, v129 quad_perm:[2,3,0,1] row_mask:0xf bank_mask:0xf bound_ctrl:1
	v_add_f32_dpp v128, v128, v128 row_half_mirror row_mask:0xf bank_mask:0xf bound_ctrl:1
	v_add_f32_dpp v130, v130, v130 row_half_mirror row_mask:0xf bank_mask:0xf bound_ctrl:1
	v_add_f32_dpp v131, v131, v131 row_half_mirror row_mask:0xf bank_mask:0xf bound_ctrl:1
	v_add_f32_dpp v132, v132, v132 row_half_mirror row_mask:0xf bank_mask:0xf bound_ctrl:1
	v_add_f32_dpp v133, v133, v133 row_half_mirror row_mask:0xf bank_mask:0xf bound_ctrl:1
	v_add_f32_dpp v134, v134, v134 row_half_mirror row_mask:0xf bank_mask:0xf bound_ctrl:1
	v_add_f32_dpp v135, v135, v135 row_half_mirror row_mask:0xf bank_mask:0xf bound_ctrl:1
	v_add_f32_dpp v129, v129, v129 row_half_mirror row_mask:0xf bank_mask:0xf bound_ctrl:1
	v_add_f32_dpp v128, v128, v128 row_mirror row_mask:0xf bank_mask:0xf bound_ctrl:1
	v_add_f32_dpp v130, v130, v130 row_mirror row_mask:0xf bank_mask:0xf bound_ctrl:1
	v_add_f32_dpp v131, v131, v131 row_mirror row_mask:0xf bank_mask:0xf bound_ctrl:1
	v_add_f32_dpp v132, v132, v132 row_mirror row_mask:0xf bank_mask:0xf bound_ctrl:1
	v_add_f32_dpp v133, v133, v133 row_mirror row_mask:0xf bank_mask:0xf bound_ctrl:1
	v_add_f32_dpp v134, v134, v134 row_mirror row_mask:0xf bank_mask:0xf bound_ctrl:1
	v_add_f32_dpp v135, v135, v135 row_mirror row_mask:0xf bank_mask:0xf bound_ctrl:1
	v_add_f32_dpp v129, v129, v129 row_mirror row_mask:0xf bank_mask:0xf bound_ctrl:1
	v_mov_b32_dpp v162, v128 row_bcast:15 row_mask:0xa bank_mask:0xf
	v_mov_b32_dpp v164, v130 row_bcast:15 row_mask:0xa bank_mask:0xf
	v_mov_b32_dpp v166, v131 row_bcast:15 row_mask:0xa bank_mask:0xf
	v_mov_b32_dpp v168, v132 row_bcast:15 row_mask:0xa bank_mask:0xf
	v_mov_b32_dpp v170, v133 row_bcast:15 row_mask:0xa bank_mask:0xf
	v_mov_b32_dpp v172, v134 row_bcast:15 row_mask:0xa bank_mask:0xf
	v_mov_b32_dpp v174, v135 row_bcast:15 row_mask:0xa bank_mask:0xf
	v_mov_b32_dpp v176, v129 row_bcast:15 row_mask:0xa bank_mask:0xf
	v_add_f32_e32 v128, v128, v162
	v_add_f32_e32 v130, v130, v164
	v_add_f32_e32 v131, v131, v166
	v_add_f32_e32 v132, v132, v168
	v_add_f32_e32 v133, v133, v170
	v_add_f32_e32 v134, v134, v172
	v_add_f32_e32 v135, v135, v174
	v_add_f32_e32 v129, v129, v176
	v_mov_b32_dpp v163, v128 row_bcast:31 row_mask:0xc bank_mask:0xf
	v_mov_b32_dpp v165, v130 row_bcast:31 row_mask:0xc bank_mask:0xf
	v_mov_b32_dpp v167, v131 row_bcast:31 row_mask:0xc bank_mask:0xf
	v_mov_b32_dpp v169, v132 row_bcast:31 row_mask:0xc bank_mask:0xf
	v_mov_b32_dpp v171, v133 row_bcast:31 row_mask:0xc bank_mask:0xf
	v_mov_b32_dpp v173, v134 row_bcast:31 row_mask:0xc bank_mask:0xf
	v_mov_b32_dpp v175, v135 row_bcast:31 row_mask:0xc bank_mask:0xf
	v_mov_b32_dpp v177, v129 row_bcast:31 row_mask:0xc bank_mask:0xf
	v_add_f32_e32 v128, v128, v163
	v_add_f32_e32 v130, v130, v165
	v_add_f32_e32 v131, v131, v167
	v_add_f32_e32 v132, v132, v169
	v_add_f32_e32 v133, v133, v171
	v_add_f32_e32 v134, v134, v173
	v_add_f32_e32 v135, v135, v175
	v_add_f32_e32 v129, v129, v177
	v_readlane_b32 s20, v128, 63
	v_readlane_b32 s21, v130, 63
	v_readlane_b32 s22, v131, 63
	v_readlane_b32 s23, v132, 63
	v_readlane_b32 s16, v133, 63
	v_readlane_b32 s17, v134, 63
	v_readlane_b32 s18, v135, 63
	v_readlane_b32 s19, v129, 63
	s_and_saveexec_b64 s[0:1], vcc
	s_cbranch_execz .LBB0_50
	v_lshlrev_b64 v[128:129], 5, v[140:141]
	v_lshl_add_u64 v[132:133], s[8:9], 0, v[128:129]
	v_mov_b32_e32 v128, s20
	v_mov_b32_e32 v129, s21
	v_mov_b32_e32 v130, s22
	v_mov_b32_e32 v131, s23
	global_store_dwordx4 v[132:133], v[128:131], off sc1
	s_nop 1
	v_mov_b32_e32 v128, s16
	v_mov_b32_e32 v129, s17
	v_mov_b32_e32 v130, s18
	v_mov_b32_e32 v131, s19
	global_store_dwordx4 v[132:133], v[128:131], off offset:16 sc1
	s_branch .LBB0_50

; #define MFMA32(a, b, c) __builtin_amdgcn_mfma_f32_32x32x16_bf16((a), (b), (c), 0, 0, 0)
; #define GA_LOAD(pr_) do { _Pragma("unroll") for (int i = 0; i < 4; ++i) ra[i] = *(const u32x4*)(Ab + (i * 32) * lda + (pr_) * 64); } while (0)
; #define GB_LOAD(kt_) do { const bfr* bk_ = Bb + (kt_) * NB * 32; \
;     _Pragma("unroll") for (int i = 0; i < 4; ++i) rb[i] = *(const u32x4*)(bk_ + (i * 64) * 32); } while (0)
; #define G_STORE(kt_) do { bfr* as_ = S0 + ((kt_) & 1) * GSTAGE; bfr* bs_ = as_ + 128 * 40; \
;     if (apar == ((kt_) & 1)) { _Pragma("unroll") for (int i = 0; i < 4; ++i) *(u32x4*)(as_ + asoff + i * 32 * 40) = ra[i]; } \
;     _Pragma("unroll") for (int i = 0; i < 4; ++i) *(u32x4*)(bs_ + bsoff + i * 64 * 40) = rb[i]; } while (0)
; template <int lda>
; DI void gemm_mainloop(const bfr* __restrict__ A, const bfr* __restrict__ Bt, int NB, int K, int m0, int n0, char* smem, f32x16 (&acc)[2][4]) {
;     ...
;   for (int kt = 0; kt < nk; ++kt) {
;     if (kt + 1 < nk) G_STORE(kt + 1);
;     if (kt + 2 < nk) {
;       GB_LOAD(kt + 2);
;       if ((kt & 1) == 0) GA_LOAD((kt >> 1) + 1);
;     }
;     const bfr* As = S0 + (kt & 1) * GSTAGE;
;     const bfr* Bs = As + 128 * 40;
; #pragma unroll
;     for (int ks = 0; ks < 2; ++ks) {
;       bf16x8 af[2], bfg[4];
; #pragma unroll
;       for (int i = 0; i < 2; ++i) af[i] = *(const bf16x8*)(As + (wr * 64 + i * 32 + r) * 40 + ks * 16 + hl * 8);
; #pragma unroll
;       for (int j = 0; j < 4; ++j) bfg[j] = *(const bf16x8*)(Bs + (wc * 128 + j * 32 + r) * 40 + ks * 16 + hl * 8);
; #pragma unroll
;       for (int i = 0; i < 2; ++i)
; #pragma unroll
;         for (int j = 0; j < 4; ++j) acc[i][j] = MFMA32(af[i], bfg[j], acc[i][j]);
;     }
;     __syncthreads();
;   }
.Lp1v_loop:
	s_waitcnt vmcnt(6) lgkmcnt(0)
	s_barrier
	s_mul_i32 s74, s71, 0x6000
	s_add_u32 s75, s74, 0x2000
	s_cmp_eq_u32 s71, 2
	s_cselect_b32 s75, 0x10000, s75
	v_add_u32_e32 v184, s74, v180
	v_add_u32_e32 v186, s75, v182
	v_add_u32_e32 v185, s74, v181
	v_add_u32_e32 v187, s75, v183
	s_add_u32 s71, s71, 1
	s_cmp_eq_u32 s71, 3
	s_cselect_b32 s71, 0, s71
	ds_read_b128 v[128:131], v184
	ds_read_b128 v[144:147], v186
	ds_read_b128 v[148:151], v186 offset:2048
	ds_read_b128 v[152:155], v186 offset:4096
	ds_read_b128 v[156:159], v186 offset:6144
	ds_read_b128 v[132:135], v184 offset:2048
	v_mfma_f32_32x32x16_bf16 v[112:127], v[136:139], v[164:167], v[112:127]
	s_mul_i32 s74, s70, 0x6000
	s_add_u32 s75, s74, s68
	s_mov_b32 m0, s75
	s_add_u32 s76, s74, 0x2000
	s_cmp_eq_u32 s70, 2
	s_cselect_b32 s76, 0x10000, s76
	global_load_lds_dwordx4 v160, s[64:65]
	v_mfma_f32_32x32x16_bf16 v[96:111], v[136:139], v[168:171], v[96:111]
	s_add_u32 m0, s75, 0x400
	s_add_u32 s76, s76, s69
	global_load_lds_dwordx4 v162, s[64:65]
	v_mfma_f32_32x32x16_bf16 v[80:95], v[136:139], v[172:175], v[80:95]
	s_mov_b32 m0, s76
	s_add_u32 s64, s64, 64
	s_addc_u32 s65, s65, 0
	global_load_lds_dwordx4 v163, s[66:67]
	v_mfma_f32_32x32x16_bf16 v[64:79], v[136:139], v[176:179], v[64:79]
	global_load_lds_dwordx4 v163, s[66:67] offset:1024
	v_mfma_f32_32x32x16_bf16 v[48:63], v[140:143], v[164:167], v[48:63]
	global_load_lds_dwordx4 v163, s[66:67] offset:2048
	v_mfma_f32_32x32x16_bf16 v[32:47], v[140:143], v[168:171], v[32:47]
	global_load_lds_dwordx4 v163, s[66:67] offset:3072
	s_add_u32 s66, s66, 0x10000
	s_addc_u32 s67, s67, 0
	v_mfma_f32_32x32x16_bf16 v[16:31], v[140:143], v[172:175], v[16:31]
	s_add_u32 s70, s70, 1
	s_cmp_eq_u32 s70, 3
	s_cselect_b32 s70, 0, s70
	v_mfma_f32_32x32x16_bf16 v[0:15], v[140:143], v[176:179], v[0:15]
	ds_read_b128 v[136:139], v185
	ds_read_b128 v[164:167], v187
	ds_read_b128 v[168:171], v187 offset:2048
	ds_read_b128 v[172:175], v187 offset:4096
	ds_read_b128 v[176:179], v187 offset:6144
	ds_read_b128 v[140:143], v185 offset:2048
	s_waitcnt lgkmcnt(10)
	v_mfma_f32_32x32x16_bf16 v[112:127], v[128:131], v[144:147], v[112:127]
	s_waitcnt lgkmcnt(9)
	v_mfma_f32_32x32x16_bf16 v[96:111], v[128:131], v[148:151], v[96:111]
	s_waitcnt lgkmcnt(8)
	v_mfma_f32_32x32x16_bf16 v[80:95], v[128:131], v[152:155], v[80:95]
	s_waitcnt lgkmcnt(7)
	v_mfma_f32_32x32x16_bf16 v[64:79], v[128:131], v[156:159], v[64:79]
	s_waitcnt lgkmcnt(6)
	v_mfma_f32_32x32x16_bf16 v[48:63], v[132:135], v[144:147], v[48:63]
	v_mfma_f32_32x32x16_bf16 v[32:47], v[132:135], v[148:151], v[32:47]
	v_mfma_f32_32x32x16_bf16 v[16:31], v[132:135], v[152:155], v[16:31]
	v_mfma_f32_32x32x16_bf16 v[0:15], v[132:135], v[156:159], v[0:15]
	s_add_u32 s72, s72, 1
	s_cmp_lt_u32 s72, 29
	s_cbranch_scc1 .Lp1v_loop
	s_waitcnt vmcnt(6) lgkmcnt(0)
	s_barrier
	s_mul_i32 s74, s71, 0x6000
	s_add_u32 s75, s74, 0x2000
	s_cmp_eq_u32 s71, 2
	s_cselect_b32 s75, 0x10000, s75
	v_add_u32_e32 v184, s74, v180
	v_add_u32_e32 v186, s75, v182
	v_add_u32_e32 v185, s74, v181
	v_add_u32_e32 v187, s75, v183
	s_add_u32 s71, s71, 1
	s_cmp_eq_u32 s71, 3
	s_cselect_b32 s71, 0, s71
	ds_read_b128 v[128:131], v184
	ds_read_b128 v[144:147], v186
	ds_read_b128 v[148:151], v186 offset:2048
	ds_read_b128 v[152:155], v186 offset:4096
	ds_read_b128 v[156:159], v186 offset:6144
	ds_read_b128 v[132:135], v184 offset:2048
	v_mfma_f32_32x32x16_bf16 v[112:127], v[136:139], v[164:167], v[112:127]
	v_mfma_f32_32x32x16_bf16 v[96:111], v[136:139], v[168:171], v[96:111]
	v_mfma_f32_32x32x16_bf16 v[80:95], v[136:139], v[172:175], v[80:95]
	v_mfma_f32_32x32x16_bf16 v[64:79], v[136:139], v[176:179], v[64:79]
	v_mfma_f32_32x32x16_bf16 v[48:63], v[140:143], v[164:167], v[48:63]
	v_mfma_f32_32x32x16_bf16 v[32:47], v[140:143], v[168:171], v[32:47]
	v_mfma_f32_32x32x16_bf16 v[16:31], v[140:143], v[172:175], v[16:31]
	v_mfma_f32_32x32x16_bf16 v[0:15], v[140:143], v[176:179], v[0:15]
	ds_read_b128 v[136:139], v185
	ds_read_b128 v[164:167], v187
	ds_read_b128 v[168:171], v187 offset:2048
	ds_read_b128 v[172:175], v187 offset:4096
	ds_read_b128 v[176:179], v187 offset:6144
	ds_read_b128 v[140:143], v185 offset:2048
	s_waitcnt lgkmcnt(10)
	v_mfma_f32_32x32x16_bf16 v[112:127], v[128:131], v[144:147], v[112:127]
	s_waitcnt lgkmcnt(9)
	v_mfma_f32_32x32x16_bf16 v[96:111], v[128:131], v[148:151], v[96:111]
	s_waitcnt lgkmcnt(8)
	v_mfma_f32_32x32x16_bf16 v[80:95], v[128:131], v[152:155], v[80:95]
	s_waitcnt lgkmcnt(7)
	v_mfma_f32_32x32x16_bf16 v[64:79], v[128:131], v[156:159], v[64:79]
	s_waitcnt lgkmcnt(6)
	v_mfma_f32_32x32x16_bf16 v[48:63], v[132:135], v[144:147], v[48:63]
	v_mfma_f32_32x32x16_bf16 v[32:47], v[132:135], v[148:151], v[32:47]
	v_mfma_f32_32x32x16_bf16 v[16:31], v[132:135], v[152:155], v[16:31]
	v_mfma_f32_32x32x16_bf16 v[0:15], v[132:135], v[156:159], v[0:15]
	s_waitcnt vmcnt(0) lgkmcnt(0)
	s_barrier
; #define MFMA32(a, b, c) __builtin_amdgcn_mfma_f32_32x32x16_bf16((a), (b), (c), 0, 0, 0)
; DI bfr f2bf(float a) { return (bfr)(pack2(a, 0.f) & 0xffffu); }
; template <int lda>
; DI void gemm_mainloop(const bfr* __restrict__ A, const bfr* __restrict__ Bt, int NB, int K, int m0, int n0, char* smem, f32x16 (&acc)[2][4]) {
;     ...
; #pragma unroll
;     for (int ks = 0; ks < 2; ++ks) {
;       bf16x8 af[2], bfg[4];
; #pragma unroll
;       for (int i = 0; i < 2; ++i) af[i] = *(const bf16x8*)(As + (wr * 64 + i * 32 + r) * 40 + ks * 16 + hl * 8);
; #pragma unroll
;       for (int j = 0; j < 4; ++j) bfg[j] = *(const bf16x8*)(Bs + (wc * 128 + j * 32 + r) * 40 + ks * 16 + hl * 8);
; #pragma unroll
;       for (int i = 0; i < 2; ++i)
; #pragma unroll
;         for (int j = 0; j < 4; ++j) acc[i][j] = MFMA32(af[i], bfg[j], acc[i][j]);
; DI void phase_gemm_in_even(const Params& p, char* smem) {
;     ...
;         float* o = p.out + O_MEMV + (size_t)l * 2097152;
;         bfr* vt = p.VT + (size_t)l * 2097152;
;         gemm_tile<1024>(p.MPB, p.WtXv + (size_t)l * 1048576, 1024, 1024, mt * 128, nt * 256, smem,
;                   [=](int row, int col, float v) {
;                     o[(size_t)row * 1024 + col] = v;
;                     const int ml = row & 15;
;                     const int rowpart = (row >> 8) * 262144 + ((row & 255) >> 4) * 512 + ((ml >> 2) & 1) * 256 + (((ml >> 3) << 2) | (ml & 3));
;                     const int colpart = (col >> 8) * 65536 + ((col & 255) >> 5) * 8192 + (col & 31) * 8;
;                     vt[rowpart + colpart] = f2bf(v);
;                   });
	s_mul_i32 s74, s71, 0x6000
	s_add_u32 s75, s74, 0x2000
	s_cmp_eq_u32 s71, 2
	s_cselect_b32 s75, 0x10000, s75
	v_add_u32_e32 v184, s74, v180
	v_add_u32_e32 v186, s75, v182
	v_add_u32_e32 v185, s74, v181
	v_add_u32_e32 v187, s75, v183
	s_add_u32 s71, s71, 1
	s_cmp_eq_u32 s71, 3
	s_cselect_b32 s71, 0, s71
	ds_read_b128 v[128:131], v184
	ds_read_b128 v[144:147], v186
	ds_read_b128 v[148:151], v186 offset:2048
	ds_read_b128 v[152:155], v186 offset:4096
	ds_read_b128 v[156:159], v186 offset:6144
	ds_read_b128 v[132:135], v184 offset:2048
	v_mfma_f32_32x32x16_bf16 v[112:127], v[136:139], v[164:167], v[112:127]
	v_mfma_f32_32x32x16_bf16 v[96:111], v[136:139], v[168:171], v[96:111]
	v_mfma_f32_32x32x16_bf16 v[80:95], v[136:139], v[172:175], v[80:95]
	v_mfma_f32_32x32x16_bf16 v[64:79], v[136:139], v[176:179], v[64:79]
	v_mfma_f32_32x32x16_bf16 v[48:63], v[140:143], v[164:167], v[48:63]
	v_mfma_f32_32x32x16_bf16 v[32:47], v[140:143], v[168:171], v[32:47]
	v_mfma_f32_32x32x16_bf16 v[16:31], v[140:143], v[172:175], v[16:31]
	v_mfma_f32_32x32x16_bf16 v[0:15], v[140:143], v[176:179], v[0:15]
	ds_read_b128 v[136:139], v185
	ds_read_b128 v[164:167], v187
	ds_read_b128 v[168:171], v187 offset:2048
	ds_read_b128 v[172:175], v187 offset:4096
	ds_read_b128 v[176:179], v187 offset:6144
	ds_read_b128 v[140:143], v185 offset:2048
	s_waitcnt lgkmcnt(10)
	v_mfma_f32_32x32x16_bf16 v[112:127], v[128:131], v[144:147], v[112:127]
	s_waitcnt lgkmcnt(9)
	v_mfma_f32_32x32x16_bf16 v[96:111], v[128:131], v[148:151], v[96:111]
	s_waitcnt lgkmcnt(8)
	v_mfma_f32_32x32x16_bf16 v[80:95], v[128:131], v[152:155], v[80:95]
	s_waitcnt lgkmcnt(7)
	v_mfma_f32_32x32x16_bf16 v[64:79], v[128:131], v[156:159], v[64:79]
	s_waitcnt lgkmcnt(6)
	v_mfma_f32_32x32x16_bf16 v[48:63], v[132:135], v[144:147], v[48:63]
	v_mfma_f32_32x32x16_bf16 v[32:47], v[132:135], v[148:151], v[32:47]
	v_mfma_f32_32x32x16_bf16 v[16:31], v[132:135], v[152:155], v[16:31]
	v_mfma_f32_32x32x16_bf16 v[0:15], v[132:135], v[156:159], v[0:15]
	s_waitcnt lgkmcnt(0)
	v_mfma_f32_32x32x16_bf16 v[112:127], v[136:139], v[164:167], v[112:127]
	v_mfma_f32_32x32x16_bf16 v[96:111], v[136:139], v[168:171], v[96:111]
	v_mfma_f32_32x32x16_bf16 v[80:95], v[136:139], v[172:175], v[80:95]
	v_mfma_f32_32x32x16_bf16 v[64:79], v[136:139], v[176:179], v[64:79]
	v_mfma_f32_32x32x16_bf16 v[48:63], v[140:143], v[164:167], v[48:63]
	v_mfma_f32_32x32x16_bf16 v[32:47], v[140:143], v[168:171], v[32:47]
	v_mfma_f32_32x32x16_bf16 v[16:31], v[140:143], v[172:175], v[16:31]
	v_mfma_f32_32x32x16_bf16 v[0:15], v[140:143], v[176:179], v[0:15]
	s_nop 7
	v_readlane_b32 s64, v188, 0
	v_readlane_b32 s65, v188, 1
	v_readlane_b32 s66, v188, 2
	v_readlane_b32 s67, v188, 3
	v_readlane_b32 s68, v188, 4
	v_readlane_b32 s69, v188, 5
	v_readlane_b32 s70, v188, 6
	v_readlane_b32 s71, v188, 7
	v_readlane_b32 s72, v188, 8
	v_readlane_b32 s73, v188, 9
	v_readlane_b32 s74, v188, 10
	v_readlane_b32 s75, v188, 11
	v_readlane_b32 s76, v188, 12
	v_readlane_b32 s77, v188, 13
	v_readlane_b32 s78, v188, 14
	v_readlane_b32 s79, v188, 15
	s_nop 7
	s_waitcnt vmcnt(1)
	s_nop 0
	s_nop 0
	s_nop 0
	s_waitcnt vmcnt(0)
	s_nop 0
	v_add_u32_e32 v140, v171, v173
	s_nop 0
	v_add_u32_e32 v160, v171, v172
	s_nop 0
	s_nop 0
	s_nop 0
	s_nop 0
	s_nop 0
	s_nop 0
	s_nop 0
	s_nop 0
	s_nop 0
	s_nop 0
	s_nop 0
	s_waitcnt lgkmcnt(0)
	s_nop 0
	s_nop 0
	s_lshl_b32 s0, s2, 2
	s_add_u32 s30, s33, s0
	s_addc_u32 s31, s38, 0
	s_lshl_b32 s0, s2, 1
	s_add_u32 s0, s6, s0
	s_nop 0
	s_addc_u32 s1, s7, 0
	s_nop 0
	s_nop 0
	s_nop 0
	s_nop 0
	s_nop 0
	s_nop 0
	s_nop 0
	s_nop 0
	s_nop 0
	s_waitcnt lgkmcnt(3)
	s_nop 0
	s_nop 0
	v_mov_b32_e32 v152, v196
	s_nop 0
	s_nop 0
	s_nop 0
	s_nop 0
	s_nop 0
	s_nop 0
	s_nop 0
	s_waitcnt lgkmcnt(0)
	s_nop 0
	s_nop 0
	v_ashrrev_i32_e32 v153, 1, v152
	v_and_b32_e32 v153, 0xffffffc0, v153
	v_and_b32_e32 v155, 31, v152
	v_add_u32_e32 v173, s58, v153
	v_lshrrev_b32_e32 v153, 3, v152
	v_lshlrev_b32_e32 v152, 1, v152
	v_and_b32_e32 v152, 0x80, v152
	v_or_b32_e32 v170, s57, v152
	v_or_b32_e32 v152, v170, v155
	v_lshlrev_b32_e32 v175, 8, v170
	s_nop 0
	v_lshlrev_b32_e32 v170, 10, v173
	v_and_b32_e32 v174, 4, v153
	v_and_b32_e32 v172, 0xfffc0000, v170
	v_lshlrev_b32_e32 v170, 5, v173
	v_lshlrev_b32_e32 v160, 2, v152
	v_lshlrev_b32_e32 v197, 3, v155
	v_and_b32_e32 v170, 0x1800, v170
	v_lshlrev_b32_e32 v228, 6, v174
	v_lshl_add_u64 v[152:153], s[30:31], 0, v[160:161]
	v_or_b32_e32 v160, v175, v197
	s_nop 0
	v_or3_b32 v229, v228, v170, v172
	v_or_b32_e32 v231, 10, v174
	v_or_b32_e32 v156, v229, v160
	v_ashrrev_i32_e32 v157, 31, v156
	v_or_b32_e32 v230, 1, v174
	v_or_b32_e32 v154, v173, v174
	v_lshl_add_u64 v[226:227], v[156:157], 1, s[0:1]
	s_nop 0
	v_or_b32_e32 v188, 2, v174
	v_or_b32_e32 v191, 9, v174
	v_or_b32_e32 v158, v173, v188
	v_or_b32_e32 v189, 3, v174
	v_ashrrev_i32_e32 v159, 31, v158
	v_or_b32_e32 v162, v173, v189
	v_or_b32_e32 v190, 8, v174
	s_nop 0
	v_or_b32_e32 v178, 11, v174
	v_or_b32_e32 v170, v173, v178
	v_ashrrev_i32_e32 v171, 31, v170
	v_or_b32_e32 v156, v173, v230
	v_lshlrev_b64 v[158:159], 12, v[158:159]
	v_ashrrev_i32_e32 v163, 31, v162
	v_or_b32_e32 v164, v173, v190
	s_nop 0
	v_lshlrev_b64 v[170:171], 12, v[170:171]
	v_ashrrev_i32_e32 v155, 31, v154
	v_ashrrev_i32_e32 v157, 31, v156
	v_lshl_add_u64 v[158:159], v[152:153], 0, v[158:159]
	v_lshlrev_b64 v[162:163], 12, v[162:163]
	v_ashrrev_i32_e32 v165, 31, v164
	v_lshl_add_u64 v[170:171], v[152:153], 0, v[170:171]
	s_nop 0
	v_or_b32_e32 v179, 16, v174
	v_lshlrev_b64 v[154:155], 12, v[154:155]
	v_lshlrev_b64 v[156:157], 12, v[156:157]
	global_store_dword v[158:159], v114, off
	v_lshl_add_u64 v[162:163], v[152:153], 0, v[162:163]
; DI bfr f2bf(float a) { return (bfr)(pack2(a, 0.f) & 0xffffu); }
; DI int crow(int reg, int h) { return (reg & 3) + 8 * (reg >> 2) + 4 * h; }
; template <int lda, class Epi>
; DI void gemm_tile(const bfr* __restrict__ A, const bfr* __restrict__ Bt, int NB, int K, int m0, int n0, char* smem, Epi epi) {
;     ...
; #pragma unroll
;   for (int i = 0; i < 2; ++i)
; #pragma unroll
;     for (int j = 0; j < 4; ++j)
; #pragma unroll
;       for (int q = 0; q < 16; ++q) {
;         int row = m0 + wr * 64 + i * 32 + crow(q, hl);
;         int col = n0 + wc * 128 + j * 32 + r;
;         epi(row, col, acc[i][j][q]);
;       }
; DI void phase_gemm_in_even(const Params& p, char* smem) {
;     ...
;         float* o = p.out + O_MEMV + (size_t)l * 2097152;
;         bfr* vt = p.VT + (size_t)l * 2097152;
;         gemm_tile<1024>(p.MPB, p.WtXv + (size_t)l * 1048576, 1024, 1024, mt * 128, nt * 256, smem,
;                   [=](int row, int col, float v) {
;                     o[(size_t)row * 1024 + col] = v;
;                     const int ml = row & 15;
;                     const int rowpart = (row >> 8) * 262144 + ((row & 255) >> 4) * 512 + ((ml >> 2) & 1) * 256 + (((ml >> 3) << 2) | (ml & 3));
;                     const int colpart = (col >> 8) * 65536 + ((col & 255) >> 5) * 8192 + (col & 31) * 8;
;                     vt[rowpart + colpart] = f2bf(v);
;                   });
	v_lshlrev_b64 v[164:165], 12, v[164:165]
	global_store_dword v[170:171], v119, off
	s_nop 0
	v_or_b32_e32 v166, v173, v191
	v_or_b32_e32 v168, v173, v231
	v_ashrrev_i32_e32 v167, 31, v166
	v_ashrrev_i32_e32 v169, 31, v168
	v_lshlrev_b64 v[166:167], 12, v[166:167]
	v_lshlrev_b64 v[168:169], 12, v[168:169]
	v_lshl_add_u64 v[166:167], v[152:153], 0, v[166:167]
	v_lshl_add_u64 v[168:169], v[152:153], 0, v[168:169]
	global_store_dword v[166:167], v117, off
	global_store_dword v[168:169], v118, off
	v_cvt_pk_bf16_f32 v119, v118, v119
	v_cvt_pk_bf16_f32 v118, v116, v117
	v_cvt_pk_bf16_f32 v117, v114, v115
	v_or_b32_e32 v114, v173, v179
	v_lshl_add_u64 v[154:155], v[152:153], 0, v[154:155]
	v_lshl_add_u64 v[156:157], v[152:153], 0, v[156:157]
	global_store_dword v[162:163], v115, off
	v_lshl_add_u64 v[164:165], v[152:153], 0, v[164:165]
	v_ashrrev_i32_e32 v115, 31, v114
	global_store_dword v[154:155], v112, off
	global_store_dword v[156:157], v113, off
	global_store_dword v[164:165], v116, off
	v_cvt_pk_bf16_f32 v116, v112, v113
	v_lshlrev_b64 v[112:113], 12, v[114:115]
	v_lshlrev_b32_e32 v114, 5, v114
	v_or_b32_e32 v172, v172, v228
	s_nop 0
	v_and_or_b32 v180, v114, s49, v172
	v_or_b32_e32 v114, v180, v160
	v_ashrrev_i32_e32 v115, 31, v114
	global_store_dwordx4 v[226:227], v[116:119], off sc1
	v_lshl_add_u64 v[114:115], v[114:115], 1, s[0:1]
	v_or_b32_e32 v181, 17, v174
	v_cvt_pk_bf16_f32 v116, v120, s0
	global_store_short v[114:115], v116, off
	v_or_b32_e32 v116, v173, v181
	v_ashrrev_i32_e32 v117, 31, v116
	v_lshlrev_b64 v[114:115], 12, v[116:117]
	v_lshlrev_b32_e32 v116, 5, v116
	v_and_or_b32 v182, v116, s49, v172
	v_or_b32_e32 v116, v182, v160
	v_ashrrev_i32_e32 v117, 31, v116
	v_cvt_pk_bf16_f32 v118, v121, s0
	v_lshl_add_u64 v[116:117], v[116:117], 1, s[0:1]
	v_or_b32_e32 v183, 18, v174
	global_store_short v[116:117], v118, off offset:2
	v_or_b32_e32 v118, v173, v183
	v_ashrrev_i32_e32 v119, 31, v118
	v_lshlrev_b64 v[116:117], 12, v[118:119]
	v_lshlrev_b32_e32 v118, 5, v118
	s_nop 0
	v_and_or_b32 v184, v118, s49, v172
	v_or_b32_e32 v118, v184, v160
	v_lshl_add_u64 v[112:113], v[152:153], 0, v[112:113]
	v_ashrrev_i32_e32 v119, 31, v118
	global_store_dword v[112:113], v120, off
	v_cvt_pk_bf16_f32 v120, v122, s0
	v_lshl_add_u64 v[118:119], v[118:119], 1, s[0:1]
	v_or_b32_e32 v185, 19, v174
	v_lshl_add_u64 v[114:115], v[152:153], 0, v[114:115]
	global_store_short v[118:119], v120, off offset:4
	v_or_b32_e32 v120, v173, v185
	global_store_dword v[114:115], v121, off
	v_ashrrev_i32_e32 v121, 31, v120
	v_lshlrev_b64 v[118:119], 12, v[120:121]
	v_lshlrev_b32_e32 v120, 5, v120
	v_and_or_b32 v186, v120, s49, v172
	v_or_b32_e32 v120, v186, v160
	v_lshl_add_u64 v[116:117], v[152:153], 0, v[116:117]
	v_ashrrev_i32_e32 v121, 31, v120
	global_store_dword v[116:117], v122, off
	v_cvt_pk_bf16_f32 v122, v123, s0
	v_lshl_add_u64 v[120:121], v[120:121], 1, s[0:1]
	v_or_b32_e32 v187, 24, v174
	v_lshl_add_u64 v[118:119], v[152:153], 0, v[118:119]
	global_store_short v[120:121], v122, off offset:6
	v_or_b32_e32 v122, v173, v187
	s_nop 0
	global_store_dword v[118:119], v123, off
	v_ashrrev_i32_e32 v123, 31, v122
	v_lshlrev_b64 v[120:121], 12, v[122:123]
	v_lshlrev_b32_e32 v122, 5, v122
	v_lshl_add_u64 v[120:121], v[152:153], 0, v[120:121]
	global_store_dword v[120:121], v124, off
	v_cvt_pk_bf16_f32 v124, v124, s0
	s_nop 0
	s_nop 0
	s_nop 0
	v_and_or_b32 v192, v122, s49, v172
	v_or_b32_e32 v122, v192, v160
	v_ashrrev_i32_e32 v123, 31, v122
	v_or_b32_e32 v193, 25, v174
	v_lshl_add_u64 v[122:123], v[122:123], 1, s[0:1]
	v_or_b32_e32 v176, v173, v193
	global_store_short v[122:123], v124, off offset:8
	s_nop 0
	v_ashrrev_i32_e32 v177, 31, v176
	v_lshlrev_b32_e32 v124, 5, v176
	v_lshlrev_b64 v[122:123], 12, v[176:177]
	v_and_or_b32 v177, v124, s49, v172
	v_lshl_add_u64 v[122:123], v[152:153], 0, v[122:123]
	v_or_b32_e32 v124, v177, v160
	global_store_dword v[122:123], v125, off
	s_nop 0
	v_cvt_pk_bf16_f32 v176, v125, s0
	v_ashrrev_i32_e32 v125, 31, v124
	v_lshl_add_u64 v[124:125], v[124:125], 1, s[0:1]
	global_store_short v[124:125], v176, off offset:10
	s_nop 0
	s_nop 6
	global_store_dword v[154:155], v96, off offset:128
	s_nop 0
	v_or_b32_e32 v146, 26, v174
	v_or_b32_e32 v144, v173, v146
	v_ashrrev_i32_e32 v145, 31, v144
	v_lshlrev_b64 v[124:125], 12, v[144:145]
	v_lshl_add_u64 v[124:125], v[152:153], 0, v[124:125]
	v_or_b32_e32 v145, 27, v174
	global_store_dword v[124:125], v126, off
	s_nop 0
	v_lshlrev_b32_e32 v136, 5, v144
	v_and_or_b32 v144, v136, s49, v172
	v_or_b32_e32 v136, v144, v160
	v_ashrrev_i32_e32 v137, 31, v136
	v_cvt_pk_bf16_f32 v126, v126, s0
	v_lshl_add_u64 v[136:137], v[136:137], 1, s[0:1]
	v_or_b32_e32 v138, v173, v145
	s_nop 0
	global_store_short v[136:137], v126, off offset:12
	v_ashrrev_i32_e32 v139, 31, v138
	v_lshlrev_b32_e32 v126, 5, v138
	v_lshlrev_b64 v[136:137], 12, v[138:139]
	v_and_or_b32 v139, v126, s49, v172
	v_lshl_add_u64 v[136:137], v[152:153], 0, v[136:137]
	v_or_b32_e32 v126, v139, v160
	s_nop 0
	global_store_dword v[136:137], v127, off
	v_cvt_pk_bf16_f32 v138, v127, s0
	v_ashrrev_i32_e32 v127, 31, v126
	v_lshl_add_u64 v[126:127], v[126:127], 1, s[0:1]
	global_store_short v[126:127], v138, off offset:14
	v_or_b32_e32 v126, 0x2000, v175
	v_and_or_b32 v126, v126, s50, v197
	s_nop 0
	global_store_dword v[156:157], v97, off offset:128
	global_store_dword v[158:159], v98, off offset:128
	global_store_dword v[162:163], v99, off offset:128
	global_store_dword v[164:165], v100, off offset:128
	global_store_dword v[166:167], v101, off offset:128
	global_store_dword v[168:169], v102, off offset:128
	global_store_dword v[170:171], v103, off offset:128
; DI bfr f2bf(float a) { return (bfr)(pack2(a, 0.f) & 0xffffu); }
; DI int crow(int reg, int h) { return (reg & 3) + 8 * (reg >> 2) + 4 * h; }
; template <int lda, class Epi>
; DI void gemm_tile(const bfr* __restrict__ A, const bfr* __restrict__ Bt, int NB, int K, int m0, int n0, char* smem, Epi epi) {
;     ...
; #pragma unroll
;   for (int i = 0; i < 2; ++i)
; #pragma unroll
;     for (int j = 0; j < 4; ++j)
; #pragma unroll
;       for (int q = 0; q < 16; ++q) {
;         int row = m0 + wr * 64 + i * 32 + crow(q, hl);
;         int col = n0 + wc * 128 + j * 32 + r;
;         epi(row, col, acc[i][j][q]);
;       }
; DI void phase_gemm_in_even(const Params& p, char* smem) {
;     ...
;         float* o = p.out + O_MEMV + (size_t)l * 2097152;
;         bfr* vt = p.VT + (size_t)l * 2097152;
;         gemm_tile<1024>(p.MPB, p.WtXv + (size_t)l * 1048576, 1024, 1024, mt * 128, nt * 256, smem,
;                   [=](int row, int col, float v) {
;                     o[(size_t)row * 1024 + col] = v;
;                     const int ml = row & 15;
;                     const int rowpart = (row >> 8) * 262144 + ((row & 255) >> 4) * 512 + ((ml >> 2) & 1) * 256 + (((ml >> 3) << 2) | (ml & 3));
;                     const int colpart = (col >> 8) * 65536 + ((col & 255) >> 5) * 8192 + (col & 31) * 8;
;                     vt[rowpart + colpart] = f2bf(v);
;                   });
	v_cvt_pk_bf16_f32 v103, v102, v103
	v_cvt_pk_bf16_f32 v102, v100, v101
	v_cvt_pk_bf16_f32 v100, v96, v97
	v_or_b32_e32 v96, v126, v180
	v_ashrrev_i32_e32 v97, 31, v96
	v_cvt_pk_bf16_f32 v101, v98, v99
	s_nop 0
	v_cvt_pk_bf16_f32 v98, v104, s0
	v_lshl_add_u64 v[96:97], v[96:97], 1, s[0:1]
	s_nop 0
	s_nop 0
	v_or_b32_e32 v128, v126, v229
	v_ashrrev_i32_e32 v129, 31, v128
	v_lshl_add_u64 v[128:129], v[128:129], 1, s[0:1]
	global_store_dwordx4 v[128:129], v[100:103], off sc1
	global_store_dword v[112:113], v104, off offset:128
	global_store_short v[96:97], v98, off
	global_store_dword v[114:115], v105, off offset:128
	v_or_b32_e32 v96, v126, v182
	v_ashrrev_i32_e32 v97, 31, v96
	v_cvt_pk_bf16_f32 v98, v105, s0
	v_lshl_add_u64 v[96:97], v[96:97], 1, s[0:1]
	global_store_short v[96:97], v98, off offset:2
	global_store_dword v[116:117], v106, off offset:128
	v_or_b32_e32 v96, v126, v184
	v_ashrrev_i32_e32 v97, 31, v96
	v_cvt_pk_bf16_f32 v98, v106, s0
	v_lshl_add_u64 v[96:97], v[96:97], 1, s[0:1]
	global_store_short v[96:97], v98, off offset:4
	global_store_dword v[118:119], v107, off offset:128
	v_or_b32_e32 v96, v126, v186
	v_ashrrev_i32_e32 v97, 31, v96
	v_cvt_pk_bf16_f32 v98, v107, s0
	v_lshl_add_u64 v[96:97], v[96:97], 1, s[0:1]
	global_store_short v[96:97], v98, off offset:6
	global_store_dword v[120:121], v108, off offset:128
	v_or_b32_e32 v96, v126, v192
	v_ashrrev_i32_e32 v97, 31, v96
	v_cvt_pk_bf16_f32 v98, v108, s0
	v_lshl_add_u64 v[96:97], v[96:97], 1, s[0:1]
	global_store_short v[96:97], v98, off offset:8
	global_store_dword v[122:123], v109, off offset:128
	v_or_b32_e32 v96, v126, v177
	v_ashrrev_i32_e32 v97, 31, v96
	v_cvt_pk_bf16_f32 v98, v109, s0
	v_lshl_add_u64 v[96:97], v[96:97], 1, s[0:1]
	global_store_short v[96:97], v98, off offset:10
	global_store_dword v[124:125], v110, off offset:128
	v_or_b32_e32 v96, v126, v144
	v_ashrrev_i32_e32 v97, 31, v96
	v_cvt_pk_bf16_f32 v98, v110, s0
	v_lshl_add_u64 v[96:97], v[96:97], 1, s[0:1]
	global_store_short v[96:97], v98, off offset:12
	global_store_dword v[136:137], v111, off offset:128
	v_or_b32_e32 v96, v126, v139
	v_ashrrev_i32_e32 v97, 31, v96
	v_cvt_pk_bf16_f32 v98, v111, s0
	v_lshl_add_u64 v[96:97], v[96:97], 1, s[0:1]
	global_store_short v[96:97], v98, off offset:14
	v_or_b32_e32 v96, 0x4000, v175
	v_and_or_b32 v96, v96, s51, v197
	global_store_dword v[154:155], v80, off offset:256
	v_or_b32_e32 v98, v96, v229
	global_store_dword v[156:157], v81, off offset:256
	global_store_dword v[158:159], v82, off offset:256
	global_store_dword v[162:163], v83, off offset:256
	global_store_dword v[164:165], v84, off offset:256
	global_store_dword v[166:167], v85, off offset:256
	global_store_dword v[168:169], v86, off offset:256
	global_store_dword v[170:171], v87, off offset:256
	v_cvt_pk_bf16_f32 v87, v86, v87
	v_cvt_pk_bf16_f32 v86, v84, v85
	v_cvt_pk_bf16_f32 v84, v80, v81
	v_or_b32_e32 v80, v96, v180
	v_ashrrev_i32_e32 v99, 31, v98
	v_ashrrev_i32_e32 v81, 31, v80
	v_lshl_add_u64 v[98:99], v[98:99], 1, s[0:1]
	v_cvt_pk_bf16_f32 v85, v82, v83
	v_cvt_pk_bf16_f32 v82, v88, s0
	v_lshl_add_u64 v[80:81], v[80:81], 1, s[0:1]
	global_store_dwordx4 v[98:99], v[84:87], off sc1
	global_store_dword v[112:113], v88, off offset:256
	global_store_short v[80:81], v82, off
	global_store_dword v[114:115], v89, off offset:256
	v_or_b32_e32 v80, v96, v182
	v_ashrrev_i32_e32 v81, 31, v80
	v_cvt_pk_bf16_f32 v82, v89, s0
	v_lshl_add_u64 v[80:81], v[80:81], 1, s[0:1]
	global_store_short v[80:81], v82, off offset:2
	global_store_dword v[116:117], v90, off offset:256
	v_or_b32_e32 v80, v96, v184
	v_ashrrev_i32_e32 v81, 31, v80
	v_cvt_pk_bf16_f32 v82, v90, s0
	v_lshl_add_u64 v[80:81], v[80:81], 1, s[0:1]
	global_store_short v[80:81], v82, off offset:4
	global_store_dword v[118:119], v91, off offset:256
	v_or_b32_e32 v80, v96, v186
	v_ashrrev_i32_e32 v81, 31, v80
	v_cvt_pk_bf16_f32 v82, v91, s0
	v_lshl_add_u64 v[80:81], v[80:81], 1, s[0:1]
	global_store_short v[80:81], v82, off offset:6
	global_store_dword v[120:121], v92, off offset:256
	v_or_b32_e32 v80, v96, v192
	v_ashrrev_i32_e32 v81, 31, v80
	v_cvt_pk_bf16_f32 v82, v92, s0
	v_lshl_add_u64 v[80:81], v[80:81], 1, s[0:1]
	global_store_short v[80:81], v82, off offset:8
	global_store_dword v[122:123], v93, off offset:256
	v_or_b32_e32 v80, v96, v177
	v_ashrrev_i32_e32 v81, 31, v80
	v_cvt_pk_bf16_f32 v82, v93, s0
	v_lshl_add_u64 v[80:81], v[80:81], 1, s[0:1]
	global_store_short v[80:81], v82, off offset:10
	global_store_dword v[124:125], v94, off offset:256
	v_or_b32_e32 v80, v96, v144
	v_ashrrev_i32_e32 v81, 31, v80
	v_cvt_pk_bf16_f32 v82, v94, s0
	v_lshl_add_u64 v[80:81], v[80:81], 1, s[0:1]
	global_store_short v[80:81], v82, off offset:12
	global_store_dword v[136:137], v95, off offset:256
	v_or_b32_e32 v80, v96, v139
	v_ashrrev_i32_e32 v81, 31, v80
	v_cvt_pk_bf16_f32 v82, v95, s0
	v_lshl_add_u64 v[80:81], v[80:81], 1, s[0:1]
	global_store_short v[80:81], v82, off offset:14
	v_or_b32_e32 v80, 0x6000, v175
	v_and_or_b32 v82, v80, s52, v197
	global_store_dword v[154:155], v64, off offset:384
	v_or_b32_e32 v80, v82, v229
	global_store_dword v[156:157], v65, off offset:384
	global_store_dword v[158:159], v66, off offset:384
	global_store_dword v[162:163], v67, off offset:384
	global_store_dword v[164:165], v68, off offset:384
	global_store_dword v[166:167], v69, off offset:384
	global_store_dword v[168:169], v70, off offset:384
	global_store_dword v[170:171], v71, off offset:384
	v_cvt_pk_bf16_f32 v71, v70, v71
	v_cvt_pk_bf16_f32 v70, v68, v69
	v_cvt_pk_bf16_f32 v68, v64, v65
	v_or_b32_e32 v64, v82, v180
	v_ashrrev_i32_e32 v81, 31, v80
	v_ashrrev_i32_e32 v65, 31, v64
; DI bfr f2bf(float a) { return (bfr)(pack2(a, 0.f) & 0xffffu); }
; DI int crow(int reg, int h) { return (reg & 3) + 8 * (reg >> 2) + 4 * h; }
; template <int lda, class Epi>
; DI void gemm_tile(const bfr* __restrict__ A, const bfr* __restrict__ Bt, int NB, int K, int m0, int n0, char* smem, Epi epi) {
;     ...
; #pragma unroll
;   for (int i = 0; i < 2; ++i)
; #pragma unroll
;     for (int j = 0; j < 4; ++j)
; #pragma unroll
;       for (int q = 0; q < 16; ++q) {
;         int row = m0 + wr * 64 + i * 32 + crow(q, hl);
;         int col = n0 + wc * 128 + j * 32 + r;
;         epi(row, col, acc[i][j][q]);
;       }
; DI void phase_gemm_in_even(const Params& p, char* smem) {
;     ...
;         float* o = p.out + O_MEMV + (size_t)l * 2097152;
;         bfr* vt = p.VT + (size_t)l * 2097152;
;         gemm_tile<1024>(p.MPB, p.WtXv + (size_t)l * 1048576, 1024, 1024, mt * 128, nt * 256, smem,
;                   [=](int row, int col, float v) {
;                     o[(size_t)row * 1024 + col] = v;
;                     const int ml = row & 15;
;                     const int rowpart = (row >> 8) * 262144 + ((row & 255) >> 4) * 512 + ((ml >> 2) & 1) * 256 + (((ml >> 3) << 2) | (ml & 3));
;                     const int colpart = (col >> 8) * 65536 + ((col & 255) >> 5) * 8192 + (col & 31) * 8;
;                     vt[rowpart + colpart] = f2bf(v);
;                   });
	v_lshl_add_u64 v[80:81], v[80:81], 1, s[0:1]
	v_cvt_pk_bf16_f32 v69, v66, v67
	v_cvt_pk_bf16_f32 v66, v72, s0
	v_lshl_add_u64 v[64:65], v[64:65], 1, s[0:1]
	global_store_dwordx4 v[80:81], v[68:71], off sc1
	global_store_dword v[112:113], v72, off offset:384
	global_store_short v[64:65], v66, off
	global_store_dword v[114:115], v73, off offset:384
	v_or_b32_e32 v64, v82, v182
	v_ashrrev_i32_e32 v65, 31, v64
	v_cvt_pk_bf16_f32 v66, v73, s0
	v_lshl_add_u64 v[64:65], v[64:65], 1, s[0:1]
	global_store_short v[64:65], v66, off offset:2
	global_store_dword v[116:117], v74, off offset:384
	v_or_b32_e32 v64, v82, v184
	v_ashrrev_i32_e32 v65, 31, v64
	v_cvt_pk_bf16_f32 v66, v74, s0
	v_lshl_add_u64 v[64:65], v[64:65], 1, s[0:1]
	global_store_short v[64:65], v66, off offset:4
	global_store_dword v[118:119], v75, off offset:384
	v_or_b32_e32 v64, v82, v186
	v_ashrrev_i32_e32 v65, 31, v64
	v_cvt_pk_bf16_f32 v66, v75, s0
	v_lshl_add_u64 v[64:65], v[64:65], 1, s[0:1]
	global_store_short v[64:65], v66, off offset:6
	global_store_dword v[120:121], v76, off offset:384
	v_or_b32_e32 v64, v82, v192
	v_ashrrev_i32_e32 v65, 31, v64
	v_cvt_pk_bf16_f32 v66, v76, s0
	v_lshl_add_u64 v[64:65], v[64:65], 1, s[0:1]
	global_store_short v[64:65], v66, off offset:8
	global_store_dword v[122:123], v77, off offset:384
	v_or_b32_e32 v64, v82, v177
	v_ashrrev_i32_e32 v65, 31, v64
	v_cvt_pk_bf16_f32 v66, v77, s0
	v_lshl_add_u64 v[64:65], v[64:65], 1, s[0:1]
	global_store_short v[64:65], v66, off offset:10
	global_store_dword v[124:125], v78, off offset:384
	v_or_b32_e32 v64, v82, v144
	v_ashrrev_i32_e32 v65, 31, v64
	v_cvt_pk_bf16_f32 v66, v78, s0
	v_lshl_add_u64 v[64:65], v[64:65], 1, s[0:1]
	global_store_short v[64:65], v66, off offset:12
	global_store_dword v[136:137], v79, off offset:384
	v_or_b32_e32 v64, v82, v139
	v_ashrrev_i32_e32 v65, 31, v64
	v_cvt_pk_bf16_f32 v66, v79, s0
	v_lshl_add_u64 v[64:65], v[64:65], 1, s[0:1]
	v_or_b32_e32 v83, 32, v173
	global_store_short v[64:65], v66, off offset:14
	v_lshlrev_b32_e32 v66, 5, v83
	v_and_or_b32 v86, v66, s53, v172
	v_or_b32_e32 v66, v86, v160
	v_or_b32_e32 v68, v83, v188
	v_or_b32_e32 v74, v83, v191
	v_or_b32_e32 v76, v83, v231
	v_or_b32_e32 v78, v83, v178
	v_ashrrev_i32_e32 v67, 31, v66
	v_ashrrev_i32_e32 v69, 31, v68
	v_or_b32_e32 v70, v83, v189
	v_ashrrev_i32_e32 v75, 31, v74
	v_ashrrev_i32_e32 v77, 31, v76
	v_ashrrev_i32_e32 v79, 31, v78
	v_or_b32_e32 v64, v83, v174
	v_lshl_add_u64 v[80:81], v[66:67], 1, s[0:1]
	v_or_b32_e32 v66, v83, v230
	v_lshlrev_b64 v[68:69], 12, v[68:69]
	v_ashrrev_i32_e32 v71, 31, v70
	v_or_b32_e32 v72, v83, v190
	v_lshlrev_b64 v[74:75], 12, v[74:75]
	v_lshlrev_b64 v[76:77], 12, v[76:77]
	v_lshlrev_b64 v[78:79], 12, v[78:79]
	v_ashrrev_i32_e32 v65, 31, v64
	v_ashrrev_i32_e32 v67, 31, v66
	v_lshl_add_u64 v[68:69], v[152:153], 0, v[68:69]
	v_lshlrev_b64 v[70:71], 12, v[70:71]
	v_ashrrev_i32_e32 v73, 31, v72
	v_lshl_add_u64 v[74:75], v[152:153], 0, v[74:75]
	v_lshl_add_u64 v[76:77], v[152:153], 0, v[76:77]
	v_lshl_add_u64 v[78:79], v[152:153], 0, v[78:79]
	v_lshlrev_b64 v[64:65], 12, v[64:65]
	v_lshlrev_b64 v[66:67], 12, v[66:67]
	global_store_dword v[68:69], v50, off
	v_lshl_add_u64 v[70:71], v[152:153], 0, v[70:71]
	v_lshlrev_b64 v[72:73], 12, v[72:73]
	global_store_dword v[74:75], v53, off
	global_store_dword v[76:77], v54, off
	global_store_dword v[78:79], v55, off
	v_cvt_pk_bf16_f32 v55, v54, v55
	v_cvt_pk_bf16_f32 v54, v52, v53
	v_cvt_pk_bf16_f32 v53, v50, v51
	v_or_b32_e32 v50, v83, v179
	v_lshl_add_u64 v[64:65], v[152:153], 0, v[64:65]
	v_lshl_add_u64 v[66:67], v[152:153], 0, v[66:67]
	global_store_dword v[70:71], v51, off
	v_lshl_add_u64 v[72:73], v[152:153], 0, v[72:73]
	v_ashrrev_i32_e32 v51, 31, v50
	global_store_dword v[64:65], v48, off
	global_store_dword v[66:67], v49, off
	global_store_dword v[72:73], v52, off
	v_cvt_pk_bf16_f32 v52, v48, v49
	v_lshlrev_b64 v[48:49], 12, v[50:51]
	v_lshlrev_b32_e32 v50, 5, v50
	v_and_or_b32 v87, v50, s54, v172
	v_or_b32_e32 v50, v87, v160
	v_ashrrev_i32_e32 v51, 31, v50
	global_store_dwordx4 v[80:81], v[52:55], off sc1
	v_lshl_add_u64 v[50:51], v[50:51], 1, s[0:1]
	v_lshl_add_u64 v[48:49], v[152:153], 0, v[48:49]
	v_cvt_pk_bf16_f32 v52, v56, s0
	global_store_short v[50:51], v52, off
	v_or_b32_e32 v52, v83, v181
	v_ashrrev_i32_e32 v53, 31, v52
	v_lshlrev_b64 v[50:51], 12, v[52:53]
	v_lshlrev_b32_e32 v52, 5, v52
	v_and_or_b32 v88, v52, s54, v172
	v_or_b32_e32 v52, v88, v160
	v_ashrrev_i32_e32 v53, 31, v52
	v_cvt_pk_bf16_f32 v54, v57, s0
	v_lshl_add_u64 v[52:53], v[52:53], 1, s[0:1]
	global_store_short v[52:53], v54, off offset:2
	v_or_b32_e32 v54, v83, v183
	v_ashrrev_i32_e32 v55, 31, v54
	v_lshlrev_b64 v[52:53], 12, v[54:55]
	v_lshlrev_b32_e32 v54, 5, v54
	v_and_or_b32 v89, v54, s54, v172
	v_or_b32_e32 v54, v89, v160
	v_ashrrev_i32_e32 v55, 31, v54
	global_store_dword v[48:49], v56, off
	v_cvt_pk_bf16_f32 v56, v58, s0
	v_lshl_add_u64 v[54:55], v[54:55], 1, s[0:1]
	v_lshl_add_u64 v[50:51], v[152:153], 0, v[50:51]
	global_store_short v[54:55], v56, off offset:4
	v_or_b32_e32 v56, v83, v185
	global_store_dword v[50:51], v57, off
	v_ashrrev_i32_e32 v57, 31, v56
	v_lshlrev_b64 v[54:55], 12, v[56:57]
	v_lshlrev_b32_e32 v56, 5, v56
	v_and_or_b32 v90, v56, s54, v172
	v_or_b32_e32 v56, v90, v160
	v_lshl_add_u64 v[52:53], v[152:153], 0, v[52:53]
	v_ashrrev_i32_e32 v57, 31, v56
	global_store_dword v[52:53], v58, off
	v_cvt_pk_bf16_f32 v58, v59, s0
	v_lshl_add_u64 v[56:57], v[56:57], 1, s[0:1]
	v_lshl_add_u64 v[54:55], v[152:153], 0, v[54:55]
	global_store_short v[56:57], v58, off offset:6
	v_or_b32_e32 v58, v83, v187
	global_store_dword v[54:55], v59, off
; DI bfr f2bf(float a) { return (bfr)(pack2(a, 0.f) & 0xffffu); }
; DI int crow(int reg, int h) { return (reg & 3) + 8 * (reg >> 2) + 4 * h; }
; template <int lda, class Epi>
; DI void gemm_tile(const bfr* __restrict__ A, const bfr* __restrict__ Bt, int NB, int K, int m0, int n0, char* smem, Epi epi) {
;     ...
; #pragma unroll
;   for (int i = 0; i < 2; ++i)
; #pragma unroll
;     for (int j = 0; j < 4; ++j)
; #pragma unroll
;       for (int q = 0; q < 16; ++q) {
;         int row = m0 + wr * 64 + i * 32 + crow(q, hl);
;         int col = n0 + wc * 128 + j * 32 + r;
;         epi(row, col, acc[i][j][q]);
;       }
; DI void phase_gemm_in_even(const Params& p, char* smem) {
;     ...
;         float* o = p.out + O_MEMV + (size_t)l * 2097152;
;         bfr* vt = p.VT + (size_t)l * 2097152;
;         gemm_tile<1024>(p.MPB, p.WtXv + (size_t)l * 1048576, 1024, 1024, mt * 128, nt * 256, smem,
;                   [=](int row, int col, float v) {
;                     o[(size_t)row * 1024 + col] = v;
;                     const int ml = row & 15;
;                     const int rowpart = (row >> 8) * 262144 + ((row & 255) >> 4) * 512 + ((ml >> 2) & 1) * 256 + (((ml >> 3) << 2) | (ml & 3));
;                     const int colpart = (col >> 8) * 65536 + ((col & 255) >> 5) * 8192 + (col & 31) * 8;
;                     vt[rowpart + colpart] = f2bf(v);
;                   });
	v_ashrrev_i32_e32 v59, 31, v58
	v_lshlrev_b64 v[56:57], 12, v[58:59]
	v_lshlrev_b32_e32 v58, 5, v58
	v_and_or_b32 v91, v58, s54, v172
	v_or_b32_e32 v58, v91, v160
	v_lshl_add_u64 v[56:57], v[152:153], 0, v[56:57]
	v_ashrrev_i32_e32 v59, 31, v58
	global_store_dword v[56:57], v60, off
	v_cvt_pk_bf16_f32 v60, v60, s0
	v_lshl_add_u64 v[58:59], v[58:59], 1, s[0:1]
	v_or_b32_e32 v80, v83, v193
	global_store_short v[58:59], v60, off offset:8
	v_ashrrev_i32_e32 v81, 31, v80
	v_lshlrev_b32_e32 v60, 5, v80
	v_lshlrev_b64 v[58:59], 12, v[80:81]
	v_and_or_b32 v92, v60, s54, v172
	v_lshl_add_u64 v[58:59], v[152:153], 0, v[58:59]
	v_or_b32_e32 v60, v92, v160
	global_store_dword v[58:59], v61, off
	v_cvt_pk_bf16_f32 v80, v61, s0
	v_ashrrev_i32_e32 v61, 31, v60
	v_lshl_add_u64 v[60:61], v[60:61], 1, s[0:1]
	global_store_short v[60:61], v80, off offset:10
	v_or_b32_e32 v80, v83, v146
	v_ashrrev_i32_e32 v81, 31, v80
	v_lshlrev_b64 v[60:61], 12, v[80:81]
	v_lshlrev_b32_e32 v80, 5, v80
	v_and_or_b32 v93, v80, s54, v172
	v_or_b32_e32 v80, v93, v160
	v_lshl_add_u64 v[60:61], v[152:153], 0, v[60:61]
	v_ashrrev_i32_e32 v81, 31, v80
	global_store_dword v[60:61], v62, off
	v_cvt_pk_bf16_f32 v62, v62, s0
	v_lshl_add_u64 v[80:81], v[80:81], 1, s[0:1]
	v_or_b32_e32 v84, v83, v145
	global_store_short v[80:81], v62, off offset:12
	v_ashrrev_i32_e32 v85, 31, v84
	v_lshlrev_b32_e32 v62, 5, v84
	v_lshlrev_b64 v[80:81], 12, v[84:85]
	v_and_or_b32 v84, v62, s54, v172
	v_lshl_add_u64 v[80:81], v[152:153], 0, v[80:81]
	v_or_b32_e32 v62, v84, v160
	global_store_dword v[80:81], v63, off
	v_cvt_pk_bf16_f32 v83, v63, s0
	v_ashrrev_i32_e32 v63, 31, v62
	v_lshl_add_u64 v[62:63], v[62:63], 1, s[0:1]
	global_store_short v[62:63], v83, off offset:14
	global_store_dword v[64:65], v32, off offset:128
	v_or_b32_e32 v62, v126, v86
	global_store_dword v[66:67], v33, off offset:128
	global_store_dword v[68:69], v34, off offset:128
	global_store_dword v[70:71], v35, off offset:128
	global_store_dword v[72:73], v36, off offset:128
	global_store_dword v[74:75], v37, off offset:128
	global_store_dword v[76:77], v38, off offset:128
	global_store_dword v[78:79], v39, off offset:128
	v_cvt_pk_bf16_f32 v39, v38, v39
	v_cvt_pk_bf16_f32 v38, v36, v37
	v_cvt_pk_bf16_f32 v36, v32, v33
	v_or_b32_e32 v32, v87, v126
	v_ashrrev_i32_e32 v63, 31, v62
	v_ashrrev_i32_e32 v33, 31, v32
	v_lshl_add_u64 v[62:63], v[62:63], 1, s[0:1]
	v_cvt_pk_bf16_f32 v37, v34, v35
	v_cvt_pk_bf16_f32 v34, v40, s0
	v_lshl_add_u64 v[32:33], v[32:33], 1, s[0:1]
	global_store_dwordx4 v[62:63], v[36:39], off sc1
	global_store_dword v[48:49], v40, off offset:128
	global_store_short v[32:33], v34, off
	global_store_dword v[50:51], v41, off offset:128
	v_or_b32_e32 v32, v88, v126
	v_ashrrev_i32_e32 v33, 31, v32
	v_cvt_pk_bf16_f32 v34, v41, s0
	v_lshl_add_u64 v[32:33], v[32:33], 1, s[0:1]
	global_store_short v[32:33], v34, off offset:2
	global_store_dword v[52:53], v42, off offset:128
	v_or_b32_e32 v32, v89, v126
	v_ashrrev_i32_e32 v33, 31, v32
	v_cvt_pk_bf16_f32 v34, v42, s0
	v_lshl_add_u64 v[32:33], v[32:33], 1, s[0:1]
	global_store_short v[32:33], v34, off offset:4
	global_store_dword v[54:55], v43, off offset:128
	v_or_b32_e32 v32, v90, v126
	v_ashrrev_i32_e32 v33, 31, v32
	v_cvt_pk_bf16_f32 v34, v43, s0
	v_lshl_add_u64 v[32:33], v[32:33], 1, s[0:1]
	global_store_short v[32:33], v34, off offset:6
	global_store_dword v[56:57], v44, off offset:128
	v_or_b32_e32 v32, v91, v126
	v_ashrrev_i32_e32 v33, 31, v32
	v_cvt_pk_bf16_f32 v34, v44, s0
	v_lshl_add_u64 v[32:33], v[32:33], 1, s[0:1]
	global_store_short v[32:33], v34, off offset:8
	global_store_dword v[58:59], v45, off offset:128
	v_or_b32_e32 v32, v92, v126
	v_ashrrev_i32_e32 v33, 31, v32
	v_cvt_pk_bf16_f32 v34, v45, s0
	v_lshl_add_u64 v[32:33], v[32:33], 1, s[0:1]
	global_store_short v[32:33], v34, off offset:10
	global_store_dword v[60:61], v46, off offset:128
	v_or_b32_e32 v32, v93, v126
	v_ashrrev_i32_e32 v33, 31, v32
	v_cvt_pk_bf16_f32 v34, v46, s0
	v_lshl_add_u64 v[32:33], v[32:33], 1, s[0:1]
	global_store_short v[32:33], v34, off offset:12
	global_store_dword v[80:81], v47, off offset:128
	v_or_b32_e32 v32, v84, v126
	v_ashrrev_i32_e32 v33, 31, v32
	v_cvt_pk_bf16_f32 v34, v47, s0
	v_lshl_add_u64 v[32:33], v[32:33], 1, s[0:1]
	global_store_short v[32:33], v34, off offset:14
	global_store_dword v[64:65], v16, off offset:256
	v_or_b32_e32 v32, v96, v86
	global_store_dword v[66:67], v17, off offset:256
	global_store_dword v[68:69], v18, off offset:256
	global_store_dword v[70:71], v19, off offset:256
	global_store_dword v[72:73], v20, off offset:256
	global_store_dword v[74:75], v21, off offset:256
	global_store_dword v[76:77], v22, off offset:256
; DI bfr f2bf(float a) { return (bfr)(pack2(a, 0.f) & 0xffffu); }
; DI int crow(int reg, int h) { return (reg & 3) + 8 * (reg >> 2) + 4 * h; }
; template <int lda, class Epi>
; DI void gemm_tile(const bfr* __restrict__ A, const bfr* __restrict__ Bt, int NB, int K, int m0, int n0, char* smem, Epi epi) {
;     ...
; #pragma unroll
;   for (int i = 0; i < 2; ++i)
; #pragma unroll
;     for (int j = 0; j < 4; ++j)
; #pragma unroll
;       for (int q = 0; q < 16; ++q) {
;         int row = m0 + wr * 64 + i * 32 + crow(q, hl);
;         int col = n0 + wc * 128 + j * 32 + r;
;         epi(row, col, acc[i][j][q]);
;       }
; DI void phase_gemm_in_even(const Params& p, char* smem) {
;     ...
;         float* o = p.out + O_MEMV + (size_t)l * 2097152;
;         bfr* vt = p.VT + (size_t)l * 2097152;
;         gemm_tile<1024>(p.MPB, p.WtXv + (size_t)l * 1048576, 1024, 1024, mt * 128, nt * 256, smem,
;                   [=](int row, int col, float v) {
;                     o[(size_t)row * 1024 + col] = v;
;                     const int ml = row & 15;
;                     const int rowpart = (row >> 8) * 262144 + ((row & 255) >> 4) * 512 + ((ml >> 2) & 1) * 256 + (((ml >> 3) << 2) | (ml & 3));
;                     const int colpart = (col >> 8) * 65536 + ((col & 255) >> 5) * 8192 + (col & 31) * 8;
;                     vt[rowpart + colpart] = f2bf(v);
;                   });
	global_store_dword v[78:79], v23, off offset:256
	v_cvt_pk_bf16_f32 v23, v22, v23
	v_cvt_pk_bf16_f32 v22, v20, v21
	v_cvt_pk_bf16_f32 v20, v16, v17
	v_or_b32_e32 v16, v87, v96
	v_ashrrev_i32_e32 v33, 31, v32
	v_ashrrev_i32_e32 v17, 31, v16
	v_lshl_add_u64 v[32:33], v[32:33], 1, s[0:1]
	v_cvt_pk_bf16_f32 v21, v18, v19
	v_cvt_pk_bf16_f32 v18, v24, s0
	v_lshl_add_u64 v[16:17], v[16:17], 1, s[0:1]
	global_store_dwordx4 v[32:33], v[20:23], off sc1
	global_store_dword v[48:49], v24, off offset:256
	global_store_short v[16:17], v18, off
	global_store_dword v[50:51], v25, off offset:256
	v_or_b32_e32 v16, v88, v96
	v_ashrrev_i32_e32 v17, 31, v16
	v_cvt_pk_bf16_f32 v18, v25, s0
	v_lshl_add_u64 v[16:17], v[16:17], 1, s[0:1]
	global_store_short v[16:17], v18, off offset:2
	global_store_dword v[52:53], v26, off offset:256
	v_or_b32_e32 v16, v89, v96
	v_ashrrev_i32_e32 v17, 31, v16
	v_cvt_pk_bf16_f32 v18, v26, s0
	v_lshl_add_u64 v[16:17], v[16:17], 1, s[0:1]
	global_store_short v[16:17], v18, off offset:4
	global_store_dword v[54:55], v27, off offset:256
	v_or_b32_e32 v16, v90, v96
	v_ashrrev_i32_e32 v17, 31, v16
	v_cvt_pk_bf16_f32 v18, v27, s0
	v_lshl_add_u64 v[16:17], v[16:17], 1, s[0:1]
	global_store_short v[16:17], v18, off offset:6
	global_store_dword v[56:57], v28, off offset:256
	v_or_b32_e32 v16, v91, v96
	v_ashrrev_i32_e32 v17, 31, v16
	v_cvt_pk_bf16_f32 v18, v28, s0
	v_lshl_add_u64 v[16:17], v[16:17], 1, s[0:1]
	global_store_short v[16:17], v18, off offset:8
	global_store_dword v[58:59], v29, off offset:256
	v_or_b32_e32 v16, v92, v96
	v_ashrrev_i32_e32 v17, 31, v16
	v_cvt_pk_bf16_f32 v18, v29, s0
	v_lshl_add_u64 v[16:17], v[16:17], 1, s[0:1]
	global_store_short v[16:17], v18, off offset:10
	global_store_dword v[60:61], v30, off offset:256
	v_or_b32_e32 v16, v93, v96
	v_ashrrev_i32_e32 v17, 31, v16
	v_cvt_pk_bf16_f32 v18, v30, s0
	v_lshl_add_u64 v[16:17], v[16:17], 1, s[0:1]
	global_store_short v[16:17], v18, off offset:12
	global_store_dword v[80:81], v31, off offset:256
	v_or_b32_e32 v16, v84, v96
	v_ashrrev_i32_e32 v17, 31, v16
	v_cvt_pk_bf16_f32 v18, v31, s0
	v_lshl_add_u64 v[16:17], v[16:17], 1, s[0:1]
	global_store_short v[16:17], v18, off offset:14
	global_store_dword v[64:65], v0, off offset:384
	v_or_b32_e32 v16, v82, v86
	global_store_dword v[66:67], v1, off offset:384
	global_store_dword v[68:69], v2, off offset:384
	global_store_dword v[70:71], v3, off offset:384
	global_store_dword v[72:73], v4, off offset:384
	global_store_dword v[74:75], v5, off offset:384
	global_store_dword v[76:77], v6, off offset:384
	global_store_dword v[78:79], v7, off offset:384
	v_cvt_pk_bf16_f32 v7, v6, v7
	v_cvt_pk_bf16_f32 v6, v4, v5
	v_cvt_pk_bf16_f32 v4, v0, v1
	v_or_b32_e32 v0, v87, v82
	v_ashrrev_i32_e32 v17, 31, v16
	v_ashrrev_i32_e32 v1, 31, v0
	v_lshl_add_u64 v[16:17], v[16:17], 1, s[0:1]
	v_cvt_pk_bf16_f32 v5, v2, v3
	v_cvt_pk_bf16_f32 v2, v8, s0
	v_lshl_add_u64 v[0:1], v[0:1], 1, s[0:1]
	global_store_dwordx4 v[16:17], v[4:7], off sc1
	global_store_dword v[48:49], v8, off offset:384
	global_store_short v[0:1], v2, off
	global_store_dword v[50:51], v9, off offset:384
	v_or_b32_e32 v0, v88, v82
	v_ashrrev_i32_e32 v1, 31, v0
	v_cvt_pk_bf16_f32 v2, v9, s0
	v_lshl_add_u64 v[0:1], v[0:1], 1, s[0:1]
	global_store_short v[0:1], v2, off offset:2
	global_store_dword v[52:53], v10, off offset:384
	v_or_b32_e32 v0, v89, v82
	v_ashrrev_i32_e32 v1, 31, v0
	v_cvt_pk_bf16_f32 v2, v10, s0
	v_lshl_add_u64 v[0:1], v[0:1], 1, s[0:1]
	global_store_short v[0:1], v2, off offset:4
	global_store_dword v[54:55], v11, off offset:384
	v_or_b32_e32 v0, v90, v82
	v_ashrrev_i32_e32 v1, 31, v0
	v_cvt_pk_bf16_f32 v2, v11, s0
	v_lshl_add_u64 v[0:1], v[0:1], 1, s[0:1]
	global_store_short v[0:1], v2, off offset:6
	global_store_dword v[56:57], v12, off offset:384
	v_or_b32_e32 v0, v91, v82
	v_ashrrev_i32_e32 v1, 31, v0
	v_cvt_pk_bf16_f32 v2, v12, s0
	v_lshl_add_u64 v[0:1], v[0:1], 1, s[0:1]
	global_store_short v[0:1], v2, off offset:8
	global_store_dword v[58:59], v13, off offset:384
	v_or_b32_e32 v0, v92, v82
	v_ashrrev_i32_e32 v1, 31, v0
	v_cvt_pk_bf16_f32 v2, v13, s0
	v_lshl_add_u64 v[0:1], v[0:1], 1, s[0:1]
	global_store_short v[0:1], v2, off offset:10
	global_store_dword v[60:61], v14, off offset:384
	v_or_b32_e32 v0, v93, v82
	v_ashrrev_i32_e32 v1, 31, v0
	v_cvt_pk_bf16_f32 v2, v14, s0
	v_lshl_add_u64 v[0:1], v[0:1], 1, s[0:1]
	global_store_short v[0:1], v2, off offset:12
	global_store_dword v[80:81], v15, off offset:384
	v_or_b32_e32 v0, v84, v82
	v_ashrrev_i32_e32 v1, 31, v0
	v_cvt_pk_bf16_f32 v2, v15, s0
	v_lshl_add_u64 v[0:1], v[0:1], 1, s[0:1]
	global_store_short v[0:1], v2, off offset:14
	s_mov_b64 s[0:1], 0

; DI float bflo(unsigned u) { return __uint_as_float(u << 16); }
; DI float bfhi(unsigned u) { return __uint_as_float(u & 0xffff0000u); }
; template <int G0>
; DI void qkv_run4_half(const Params& p, int row0, int lane) {
;     ...
;   for (int i = 0; i < 7; ++i) {
;     const int rr = (i >= 3 || t0 > 0) ? (row0 - 3 + i) : row0;
;     const bfr* rp = p.PB + (size_t)rr * EINP + 1536 + G0 * 128 + lane * 2;
; #pragma unroll
;     for (int g = 0; g < 4; ++g) u[g][i] = *(const unsigned*)(rp + g * 128);
;   }
; #pragma unroll
;   for (int j = 0; j < 4; ++j) {
;     const float* wp = p.sc_w + (size_t)j * 1536 + G0 * 128 + lane * 2;
; #pragma unroll
;     for (int g = 0; g < 4; ++g) w[g][j] = *(const float2*)(wp + g * 128);
;   }
;   const float hm = (t0 > 0) ? 1.f : 0.f;
; #pragma unroll
;   for (int k = 0; k < 4; ++k) {
;     const int row = row0 + k;
; #pragma unroll
;     for (int g = 0; g < 4; ++g) {
;       const int grp = G0 + g;
;       const int ch = grp * 128 + lane * 2;
;       float a0 = 0.f, a1 = 0.f;
; #pragma unroll
;       for (int j = 0; j < 4; ++j) {
;         const int i = k + j;
;         const float m = (i >= 3) ? 1.f : hm;
;         a0 += w[g][j].x * (bflo(u[g][i]) * m);
;         a1 += w[g][j].y * (bfhi(u[g][i]) * m);
.LBB0_223:
	v_add_u32_e32 v185, -3, v178
	v_and_b32_e32 v112, 0x7fc, v185
	v_add_u32_e32 v87, -6, v178
	v_cmp_ne_u32_e32 vcc, 0, v112
	v_mad_i64_i32 v[96:97], s[4:5], v185, s25, v[84:85]
	s_nop 0
	v_cndmask_b32_e32 v87, v185, v87, vcc
	v_mad_i64_i32 v[102:103], s[4:5], v87, s25, v[84:85]
	v_add_u32_e32 v87, -5, v178
	v_cndmask_b32_e32 v87, v185, v87, vcc
	v_mad_i64_i32 v[100:101], s[4:5], v87, s25, v[84:85]
	v_subbrev_co_u32_e32 v87, vcc, 0, v185, vcc
	v_mad_i64_i32 v[98:99], s[4:5], v87, s25, v[84:85]
	v_add_u32_e32 v186, -2, v178
	v_lshl_add_u64 v[88:89], v[102:103], 0, v[2:3]
	v_lshl_add_u64 v[92:93], v[98:99], 0, v[2:3]
	v_lshl_add_u64 v[94:95], v[96:97], 0, v[2:3]
	v_mad_i64_i32 v[106:107], s[4:5], v186, s25, v[84:85]
	v_lshl_add_u64 v[90:91], v[100:101], 0, v[2:3]
	global_load_dword v113, v[88:89], off offset:3072
	global_load_dword v114, v[88:89], off offset:3328
	global_load_dword v115, v[90:91], off offset:3072
	global_load_dword v116, v[92:93], off offset:3072
	global_load_dword v117, v[94:95], off offset:3072
	global_load_dword v118, v[90:91], off offset:3328
	global_load_dword v119, v[92:93], off offset:3328
	global_load_dword v120, v[94:95], off offset:3328
	global_load_dword v121, v[88:89], off offset:3584
	global_load_dword v122, v[90:91], off offset:3584
	global_load_dword v123, v[92:93], off offset:3584
	global_load_dword v124, v[94:95], off offset:3584
	global_load_dword v125, v[88:89], off offset:3840
	global_load_dword v126, v[90:91], off offset:3840
	global_load_dword v127, v[92:93], off offset:3840
	v_mad_i64_i32 v[92:93], s[4:5], v178, s25, v[84:85]
	global_load_dwordx2 v[140:141], v[6:7], off offset:512
	global_load_dwordx2 v[142:143], v[10:11], off
	global_load_dwordx2 v[144:145], v[18:19], off
	global_load_dwordx2 v[138:139], v[26:27], off
	global_load_dword v154, v[94:95], off offset:3840
	v_lshl_add_u64 v[94:95], v[106:107], 0, v[2:3]
	v_lshl_add_u64 v[88:89], v[92:93], 0, v[2:3]
	global_load_dword v187, v[94:95], off offset:3072
	global_load_dword v174, v[88:89], off offset:3072
	global_load_dword v173, v[88:89], off offset:3328
	global_load_dword v172, v[88:89], off offset:3584
	global_load_dword v91, v[88:89], off offset:3840
	v_add_u32_e32 v87, -1, v178
	v_mad_i64_i32 v[104:105], s[4:5], v87, s25, v[84:85]
	v_lshl_add_u64 v[108:109], v[104:105], 0, v[2:3]
	global_load_dword v177, v[94:95], off offset:3328
	global_load_dword v170, v[94:95], off offset:3584
	global_load_dword v168, v[94:95], off offset:3840
	global_load_dword v169, v[108:109], off offset:3072
	global_load_dword v171, v[108:109], off offset:3328
	global_load_dword v176, v[108:109], off offset:3584
	global_load_dword v175, v[108:109], off offset:3840
	global_load_dwordx2 v[132:133], v[6:7], off offset:1024
	global_load_dwordx2 v[134:135], v[12:13], off
	global_load_dwordx2 v[136:137], v[20:21], off
	global_load_dwordx2 v[128:129], v[28:29], off
	v_ashrrev_i32_e32 v90, 9, v184
	v_cmp_eq_u32_e32 vcc, 0, v112
	v_mul_i32_i24_e32 v155, 3, v90
	v_mad_i64_i32 v[110:111], s[4:5], v185, s26, v[32:33]
	v_cndmask_b32_e64 v90, 1.0, 0, vcc
	v_cmp_eq_u32_e64 s[4:5], s24, v112
	s_waitcnt vmcnt(31)
	v_lshlrev_b32_e32 v108, 16, v117
	v_and_b32_e32 v109, 0xffff0000, v117
	s_waitcnt vmcnt(29)
	v_and_b32_e32 v117, 0xffff0000, v119
	s_waitcnt vmcnt(28)
	v_lshlrev_b32_e32 v146, 16, v120
	v_and_b32_e32 v147, 0xffff0000, v120
	s_waitcnt vmcnt(27)
	v_lshlrev_b32_e32 v188, 16, v121
	v_and_b32_e32 v189, 0xffff0000, v121
	v_lshlrev_b32_e32 v88, 16, v114
	v_and_b32_e32 v89, 0xffff0000, v114
	v_lshlrev_b32_e32 v166, 16, v115
	v_and_b32_e32 v167, 0xffff0000, v115
	v_lshlrev_b32_e32 v114, 16, v118
	v_and_b32_e32 v115, 0xffff0000, v118
	v_lshlrev_b32_e32 v94, 16, v116
	v_and_b32_e32 v95, 0xffff0000, v116
	v_lshlrev_b32_e32 v116, 16, v119
	s_waitcnt vmcnt(24)
	v_lshlrev_b32_e32 v130, 16, v124
	s_waitcnt vmcnt(11)
	v_pk_mul_f32 v[88:89], v[90:91], v[88:89] op_sel_hi:[0,1]
	v_pk_mul_f32 v[164:165], v[90:91], v[114:115] op_sel_hi:[0,1]
	v_pk_fma_f32 v[88:89], v[88:89], v[140:141], 0 op_sel_hi:[1,1,0]
	v_pk_mul_f32 v[160:161], v[90:91], v[116:117] op_sel_hi:[0,1]
	v_pk_fma_f32 v[88:89], v[164:165], v[142:143], v[88:89]
	v_lshlrev_b32_e32 v114, 16, v122
	v_pk_fma_f32 v[88:89], v[160:161], v[144:145], v[88:89]
	v_and_b32_e32 v115, 0xffff0000, v122
	v_pk_fma_f32 v[192:193], v[138:139], v[146:147], v[88:89]
	v_pk_mul_f32 v[162:163], v[90:91], v[114:115] op_sel_hi:[0,1]
	v_lshlrev_b32_e32 v114, 16, v123
	v_and_b32_e32 v115, 0xffff0000, v123
	v_and_b32_e32 v131, 0xffff0000, v124
	v_lshlrev_b32_e32 v190, 16, v125
	v_and_b32_e32 v191, 0xffff0000, v125
	global_load_dwordx2 v[118:119], v[6:7], off offset:1536
	global_load_dwordx2 v[116:117], v[6:7], off
	global_load_dwordx2 v[120:121], v[14:15], off
	global_load_dwordx2 v[148:149], v[8:9], off
	global_load_dwordx2 v[124:125], v[22:23], off
	global_load_dwordx2 v[152:153], v[16:17], off
	global_load_dwordx2 v[122:123], v[30:31], off
	global_load_dwordx2 v[150:151], v[24:25], off
	v_mul_f32_e32 v88, 0xbfb8aa3b, v192
	v_mul_f32_e32 v89, 0xbfb8aa3b, v193
	v_exp_f32_e32 v88, v88
	v_exp_f32_e32 v89, v89
	v_pk_mul_f32 v[158:159], v[90:91], v[114:115] op_sel_hi:[0,1]
	v_lshlrev_b32_e32 v114, 16, v126
	v_and_b32_e32 v115, 0xffff0000, v126
	v_pk_add_f32 v[194:195], v[88:89], 1.0 op_sel_hi:[1,0]
	v_lshlrev_b32_e32 v126, 16, v127
	v_div_scale_f32 v197, s[6:7], v195, v195, v193
	v_rcp_f32_e32 v198, v197
	v_and_b32_e32 v127, 0xffff0000, v127
	v_pk_mul_f32 v[156:157], v[90:91], v[126:127] op_sel_hi:[0,1]
	v_lshlrev_b32_e32 v126, 16, v154
	v_and_b32_e32 v127, 0xffff0000, v154
	v_mad_i64_i32 v[88:89], s[6:7], v155, s26, 0
	v_lshlrev_b32_e32 v154, 16, v187
	v_and_b32_e32 v155, 0xffff0000, v187
	v_fma_f32 v187, -v197, v198, 1.0
	v_fmac_f32_e32 v198, v187, v198
	v_div_scale_f32 v187, vcc, v193, v195, v193
	v_mul_f32_e32 v199, v187, v198
	v_fma_f32 v200, -v197, v199, v187
	v_fmac_f32_e32 v199, v200, v198
	v_fma_f32 v187, -v197, v199, v187
	v_div_scale_f32 v197, s[6:7], v194, v194, v192
	v_rcp_f32_e32 v200, v197
	v_div_fmas_f32 v187, v187, v198, v199
	v_div_fixup_f32 v193, v187, v195, v193
	v_pk_mul_f32 v[188:189], v[90:91], v[188:189] op_sel_hi:[0,1]
	v_fma_f32 v187, -v197, v200, 1.0
	v_fmac_f32_e32 v200, v187, v200
	v_div_scale_f32 v187, vcc, v192, v194, v192
	v_mul_f32_e32 v195, v187, v200
	v_fma_f32 v198, -v197, v195, v187
	v_fmac_f32_e32 v195, v198, v200
	v_fma_f32 v187, -v197, v195, v187
	v_div_fmas_f32 v187, v187, v200, v195
	v_div_fixup_f32 v192, v187, v194, v192
	v_pk_mul_f32 v[194:195], v[192:193], v[192:193]
	s_waitcnt vmcnt(11)
; DI float bflo(unsigned u) { return __uint_as_float(u << 16); }
; DI float bfhi(unsigned u) { return __uint_as_float(u & 0xffff0000u); }
; DI float siluf_(float x) { return x / (1.0f + __expf(-x)); }
; template <int G0>
; DI void qkv_run4_half(const Params& p, int row0, int lane) {
;     ...
;     for (int g = 0; g < 4; ++g) {
;       const int grp = G0 + g;
;       const int ch = grp * 128 + lane * 2;
;       float a0 = 0.f, a1 = 0.f;
; #pragma unroll
;       for (int j = 0; j < 4; ++j) {
;         const int i = k + j;
;         const float m = (i >= 3) ? 1.f : hm;
;         a0 += w[g][j].x * (bflo(u[g][i]) * m);
;         a1 += w[g][j].y * (bfhi(u[g][i]) * m);
;       }
;       float y0 = siluf_(a0), y1 = siluf_(a1);
;       if (grp < 8) {
;         float ss = wave_sum(y0 * y0 + y1 * y1);
;         float inv = rsqrtf(ss + EPSF);
;         if (grp < 4) inv *= 0.08838834764831845f;
;         y0 *= inv; y1 *= inv;
;       }
;       float2 o = {y0, y1};
;       *(float2*)(p.QKV + (size_t)row * 1536 + ch) = o;
	v_pk_fma_f32 v[188:189], v[188:189], v[132:133], 0 op_sel_hi:[1,1,0]
	v_add_f32_e32 v187, v194, v195
	v_mov_b32_e32 v194, 0
	s_waitcnt vmcnt(10)
	v_pk_fma_f32 v[188:189], v[162:163], v[134:135], v[188:189]
	v_add_f32_dpp v187, v187, v187 quad_perm:[1,0,3,2] row_mask:0xf bank_mask:0xf bound_ctrl:1
	s_waitcnt vmcnt(9)
	v_pk_fma_f32 v[188:189], v[158:159], v[136:137], v[188:189]
	v_pk_mul_f32 v[190:191], v[90:91], v[190:191] op_sel_hi:[0,1]
	v_add_f32_dpp v187, v187, v187 quad_perm:[2,3,0,1] row_mask:0xf bank_mask:0xf bound_ctrl:1
	s_waitcnt vmcnt(8)
	v_pk_fma_f32 v[188:189], v[128:129], v[130:131], v[188:189]
	v_pk_mul_f32 v[114:115], v[90:91], v[114:115] op_sel_hi:[0,1]
	v_add_f32_dpp v187, v187, v187 row_half_mirror row_mask:0xf bank_mask:0xf bound_ctrl:1
	v_mul_f32_e32 v195, 0xbfb8aa3b, v189
	v_exp_f32_e32 v195, v195
	v_add_f32_dpp v187, v187, v187 row_mirror row_mask:0xf bank_mask:0xf bound_ctrl:1
	v_lshlrev_b32_e32 v112, 16, v113
	v_and_b32_e32 v113, 0xffff0000, v113
	v_mov_b32_dpp v194, v187 row_bcast:15 row_mask:0xa bank_mask:0xf
	v_add_f32_e32 v187, v187, v194
	v_mov_b32_e32 v194, 0
	v_pk_mul_f32 v[112:113], v[90:91], v[112:113] op_sel_hi:[0,1]
	v_pk_mul_f32 v[166:167], v[90:91], v[166:167] op_sel_hi:[0,1]
	v_mov_b32_dpp v194, v187 row_bcast:31 row_mask:0xc bank_mask:0xf
	v_add_f32_e32 v187, v187, v194
	v_mul_f32_e32 v194, 0xbfb8aa3b, v188
	v_readlane_b32 s6, v187, 63
	v_exp_f32_e32 v194, v194
	v_pk_mul_f32 v[94:95], v[90:91], v[94:95] op_sel_hi:[0,1]
	v_add_f32_e32 v187, s6, v179
	v_mul_f32_e32 v197, 0x4b800000, v187
	v_cmp_gt_f32_e32 vcc, s27, v187
	v_pk_add_f32 v[194:195], v[194:195], 1.0 op_sel_hi:[1,0]
	s_waitcnt vmcnt(7)
	v_pk_fma_f32 v[190:191], v[190:191], v[118:119], 0 op_sel_hi:[1,1,0]
	v_cndmask_b32_e32 v187, v187, v197, vcc
	v_rsq_f32_e32 v187, v187
	v_div_scale_f32 v197, s[6:7], v195, v195, v189
	v_rcp_f32_e32 v199, v197
	v_mul_f32_e32 v198, 0x45800000, v187
	v_cndmask_b32_e32 v187, v187, v198, vcc
	v_mul_f32_e32 v198, 0x3db504f3, v187
	v_fma_f32 v187, -v197, v199, 1.0
	v_fmac_f32_e32 v199, v187, v199
	v_div_scale_f32 v187, vcc, v189, v195, v189
	v_mul_f32_e32 v200, v187, v199
	v_fma_f32 v201, -v197, v200, v187
	v_fmac_f32_e32 v200, v201, v199
	v_fma_f32 v187, -v197, v200, v187
	v_div_scale_f32 v197, s[6:7], v194, v194, v188
	v_rcp_f32_e32 v201, v197
	v_div_fmas_f32 v187, v187, v199, v200
	v_div_fixup_f32 v189, v187, v195, v189
	s_waitcnt vmcnt(5)
	v_pk_fma_f32 v[190:191], v[114:115], v[120:121], v[190:191]
	v_fma_f32 v187, -v197, v201, 1.0
	v_fmac_f32_e32 v201, v187, v201
	v_div_scale_f32 v187, vcc, v188, v194, v188
	v_mul_f32_e32 v195, v187, v201
	v_fma_f32 v199, -v197, v195, v187
	v_fmac_f32_e32 v195, v199, v201
	v_fma_f32 v187, -v197, v195, v187
	v_div_fmas_f32 v187, v187, v201, v195
	v_div_fixup_f32 v188, v187, v194, v188
	v_pk_mul_f32 v[194:195], v[188:189], v[188:189]
	s_waitcnt vmcnt(3)
	v_pk_fma_f32 v[190:191], v[156:157], v[124:125], v[190:191]
	v_add_f32_e32 v187, v194, v195
	v_mov_b32_e32 v194, 0
	s_waitcnt vmcnt(1)
	v_pk_fma_f32 v[190:191], v[122:123], v[126:127], v[190:191]
	v_add_f32_dpp v187, v187, v187 quad_perm:[1,0,3,2] row_mask:0xf bank_mask:0xf bound_ctrl:1
	v_mul_f32_e32 v195, 0xbfb8aa3b, v191
	v_exp_f32_e32 v195, v195
	v_add_f32_dpp v187, v187, v187 quad_perm:[2,3,0,1] row_mask:0xf bank_mask:0xf bound_ctrl:1
	v_pk_mul_f32 v[192:193], v[192:193], v[198:199] op_sel_hi:[1,0]
	global_store_dwordx2 v[110:111], v[192:193], off offset:512 sc1
	v_add_f32_dpp v187, v187, v187 row_half_mirror row_mask:0xf bank_mask:0xf bound_ctrl:1
	v_pk_fma_f32 v[112:113], v[112:113], v[116:117], 0 op_sel_hi:[1,1,0]
	s_nop 0
	v_add_f32_dpp v187, v187, v187 row_mirror row_mask:0xf bank_mask:0xf bound_ctrl:1
	v_pk_fma_f32 v[112:113], v[166:167], v[148:149], v[112:113]
	s_nop 0
	v_mov_b32_dpp v194, v187 row_bcast:15 row_mask:0xa bank_mask:0xf
	v_add_f32_e32 v187, v187, v194
	v_mov_b32_e32 v194, 0
	v_pk_fma_f32 v[112:113], v[94:95], v[152:153], v[112:113]
	s_nop 0
	v_mov_b32_dpp v194, v187 row_bcast:31 row_mask:0xc bank_mask:0xf
	v_add_f32_e32 v187, v187, v194
	s_waitcnt vmcnt(1)
	v_pk_fma_f32 v[112:113], v[150:151], v[108:109], v[112:113]
	v_readlane_b32 s6, v187, 63
	s_nop 1
	v_add_f32_e32 v187, s6, v179
	v_mul_f32_e32 v194, 0x4b800000, v187
	v_cmp_gt_f32_e32 vcc, s27, v187
	s_nop 1
	v_cndmask_b32_e32 v187, v187, v194, vcc
	v_mul_f32_e32 v194, 0xbfb8aa3b, v190
	v_exp_f32_e32 v194, v194
	v_rsq_f32_e32 v187, v187
	v_pk_add_f32 v[192:193], v[194:195], 1.0 op_sel_hi:[1,0]
	s_nop 0
	v_div_scale_f32 v195, s[6:7], v193, v193, v191
	v_rcp_f32_e32 v198, v195
	v_mul_f32_e32 v197, 0x45800000, v187
	v_cndmask_b32_e32 v187, v187, v197, vcc
	v_mul_f32_e32 v194, 0x3db504f3, v187
	v_fma_f32 v187, -v195, v198, 1.0
	v_fmac_f32_e32 v198, v187, v198
	v_div_scale_f32 v187, vcc, v191, v193, v191
	v_pk_mul_f32 v[188:189], v[188:189], v[194:195] op_sel_hi:[1,0]
	v_mul_f32_e32 v194, v187, v198
	v_fma_f32 v197, -v195, v194, v187
	v_fmac_f32_e32 v194, v197, v198
	v_fma_f32 v187, -v195, v194, v187
	v_div_scale_f32 v195, s[6:7], v192, v192, v190
	v_rcp_f32_e32 v197, v195
	v_div_fmas_f32 v187, v187, v198, v194
	v_div_fixup_f32 v191, v187, v193, v191
	global_store_dwordx2 v[110:111], v[188:189], off offset:1024 sc1
	v_fma_f32 v187, -v195, v197, 1.0
	v_fmac_f32_e32 v197, v187, v197
	v_div_scale_f32 v187, vcc, v190, v192, v190
	v_mul_f32_e32 v193, v187, v197
	v_fma_f32 v194, -v195, v193, v187
	v_fmac_f32_e32 v193, v194, v197
	v_fma_f32 v187, -v195, v193, v187
	v_div_fmas_f32 v187, v187, v197, v193
	v_div_fixup_f32 v190, v187, v192, v190
	v_pk_mul_f32 v[192:193], v[190:191], v[190:191]
	s_nop 0
	v_add_f32_e32 v187, v192, v193
	v_mov_b32_e32 v192, 0
; DI float bflo(unsigned u) { return __uint_as_float(u << 16); }
; DI float bfhi(unsigned u) { return __uint_as_float(u & 0xffff0000u); }
; DI float siluf_(float x) { return x / (1.0f + __expf(-x)); }
; template <int G0>
; DI void qkv_run4_half(const Params& p, int row0, int lane) {
;     ...
;     for (int g = 0; g < 4; ++g) {
;       const int grp = G0 + g;
;       const int ch = grp * 128 + lane * 2;
;       float a0 = 0.f, a1 = 0.f;
; #pragma unroll
;       for (int j = 0; j < 4; ++j) {
;         const int i = k + j;
;         const float m = (i >= 3) ? 1.f : hm;
;         a0 += w[g][j].x * (bflo(u[g][i]) * m);
;         a1 += w[g][j].y * (bfhi(u[g][i]) * m);
;       }
;       float y0 = siluf_(a0), y1 = siluf_(a1);
;       if (grp < 8) {
;         float ss = wave_sum(y0 * y0 + y1 * y1);
;         float inv = rsqrtf(ss + EPSF);
;         if (grp < 4) inv *= 0.08838834764831845f;
;         y0 *= inv; y1 *= inv;
;       }
;       float2 o = {y0, y1};
;       *(float2*)(p.QKV + (size_t)row * 1536 + ch) = o;
;       if (t0 == 2044 && k >= 1) {
;         float2 c = {bflo(u[g][k + 3]), bfhi(u[g][k + 3])};
;         *(float2*)(p.out + O_QKVP + ((size_t)b * 3 + (k - 1)) * 1536 + ch) = c;
;       }
	v_mul_f32_e32 v193, 0xbfb8aa3b, v113
	v_add_f32_dpp v187, v187, v187 quad_perm:[1,0,3,2] row_mask:0xf bank_mask:0xf bound_ctrl:1
	v_exp_f32_e32 v193, v193
	s_nop 0
	v_add_f32_dpp v187, v187, v187 quad_perm:[2,3,0,1] row_mask:0xf bank_mask:0xf bound_ctrl:1
	s_nop 1
	v_add_f32_dpp v187, v187, v187 row_half_mirror row_mask:0xf bank_mask:0xf bound_ctrl:1
	s_nop 1
	v_add_f32_dpp v187, v187, v187 row_mirror row_mask:0xf bank_mask:0xf bound_ctrl:1
	s_nop 1
	v_mov_b32_dpp v192, v187 row_bcast:15 row_mask:0xa bank_mask:0xf
	v_add_f32_e32 v187, v187, v192
	v_mov_b32_e32 v192, 0
	s_nop 1
	v_mov_b32_dpp v192, v187 row_bcast:31 row_mask:0xc bank_mask:0xf
	v_add_f32_e32 v187, v187, v192
	s_nop 0
	v_readlane_b32 s6, v187, 63
	s_nop 1
	v_add_f32_e32 v187, s6, v179
	v_mul_f32_e32 v192, 0x4b800000, v187
	v_cmp_gt_f32_e32 vcc, s27, v187
	s_nop 1
	v_cndmask_b32_e32 v187, v187, v192, vcc
	v_rsq_f32_e32 v187, v187
	v_mul_f32_e32 v192, 0xbfb8aa3b, v112
	v_exp_f32_e32 v192, v192
	v_mul_f32_e32 v188, 0x45800000, v187
	v_cndmask_b32_e32 v187, v187, v188, vcc
	v_pk_add_f32 v[188:189], v[192:193], 1.0 op_sel_hi:[1,0]
	v_mul_f32_e32 v192, 0x3db504f3, v187
	v_div_scale_f32 v193, s[6:7], v189, v189, v113
	v_rcp_f32_e32 v194, v193
	v_pk_mul_f32 v[190:191], v[190:191], v[192:193] op_sel_hi:[1,0]
	global_store_dwordx2 v[110:111], v[190:191], off offset:1536 sc1
	v_fma_f32 v187, -v193, v194, 1.0
	v_fmac_f32_e32 v194, v187, v194
	v_div_scale_f32 v187, vcc, v113, v189, v113
	v_mul_f32_e32 v190, v187, v194
	v_fma_f32 v191, -v193, v190, v187
	v_fmac_f32_e32 v190, v191, v194
	v_div_scale_f32 v191, s[6:7], v188, v188, v112
	v_rcp_f32_e32 v192, v191
	v_fma_f32 v187, -v193, v190, v187
	v_div_fmas_f32 v187, v187, v194, v190
	v_div_fixup_f32 v189, v187, v189, v113
	v_fma_f32 v113, -v191, v192, 1.0
	v_fmac_f32_e32 v192, v113, v192
	v_div_scale_f32 v113, vcc, v112, v188, v112
	v_mul_f32_e32 v187, v113, v192
	v_fma_f32 v190, -v191, v187, v113
	v_fmac_f32_e32 v187, v190, v192
	v_fma_f32 v113, -v191, v187, v113
	v_div_fmas_f32 v113, v113, v192, v187
	v_div_fixup_f32 v188, v113, v188, v112
	v_pk_mul_f32 v[112:113], v[188:189], v[188:189]
	s_nop 0
	v_add_f32_e32 v112, v112, v113
	v_mov_b32_e32 v113, 0
	s_nop 0
	v_add_f32_dpp v112, v112, v112 quad_perm:[1,0,3,2] row_mask:0xf bank_mask:0xf bound_ctrl:1
	s_nop 1
	v_add_f32_dpp v112, v112, v112 quad_perm:[2,3,0,1] row_mask:0xf bank_mask:0xf bound_ctrl:1
	s_nop 1
	v_add_f32_dpp v112, v112, v112 row_half_mirror row_mask:0xf bank_mask:0xf bound_ctrl:1
	s_nop 1
	v_add_f32_dpp v112, v112, v112 row_mirror row_mask:0xf bank_mask:0xf bound_ctrl:1
	s_nop 1
	v_mov_b32_dpp v113, v112 row_bcast:15 row_mask:0xa bank_mask:0xf
	v_add_f32_e32 v112, v112, v113
	v_mov_b32_e32 v113, 0
	s_nop 1
	v_mov_b32_dpp v113, v112 row_bcast:31 row_mask:0xc bank_mask:0xf
	v_add_f32_e32 v112, v112, v113
	s_nop 0
	v_readlane_b32 s6, v112, 63
	v_pk_fma_f32 v[112:113], v[166:167], v[116:117], 0 op_sel_hi:[1,1,0]
	s_nop 0
	v_pk_fma_f32 v[112:113], v[94:95], v[148:149], v[112:113]
	v_add_f32_e32 v187, s6, v179
	v_pk_fma_f32 v[112:113], v[152:153], v[108:109], v[112:113]
	v_mul_f32_e32 v190, 0x4b800000, v187
	v_pk_fma_f32 v[166:167], v[150:151], v[154:155], v[112:113]
	v_cmp_gt_f32_e32 vcc, s27, v187
	v_mul_f32_e32 v112, 0xbfb8aa3b, v166
	v_mul_f32_e32 v113, 0xbfb8aa3b, v167
	v_exp_f32_e32 v112, v112
	v_exp_f32_e32 v113, v113
	v_cndmask_b32_e32 v187, v187, v190, vcc
	v_rsq_f32_e32 v187, v187
	v_pk_add_f32 v[190:191], v[112:113], 1.0 op_sel_hi:[1,0]
	s_nop 0
	v_div_scale_f32 v192, s[6:7], v191, v191, v167
	v_rcp_f32_e32 v193, v192
	v_mul_f32_e32 v194, 0x45800000, v187
	v_cndmask_b32_e32 v187, v187, v194, vcc
	v_mad_i64_i32 v[112:113], s[6:7], v186, s26, v[32:33]
	v_fma_f32 v194, -v192, v193, 1.0
	v_fmac_f32_e32 v193, v194, v193
	v_div_scale_f32 v194, vcc, v167, v191, v167
	v_mul_f32_e32 v195, v194, v193
	v_fma_f32 v197, -v192, v195, v194
	v_fmac_f32_e32 v195, v197, v193
	v_fma_f32 v192, -v192, v195, v194
	v_div_scale_f32 v194, s[6:7], v190, v190, v166
	v_rcp_f32_e32 v197, v194
	v_div_fmas_f32 v192, v192, v193, v195
	v_div_fixup_f32 v167, v192, v191, v167
	v_fma_f32 v191, -v194, v197, 1.0
	v_fmac_f32_e32 v197, v191, v197
	v_div_scale_f32 v191, vcc, v166, v190, v166
	v_mul_f32_e32 v192, v191, v197
	v_fma_f32 v193, -v194, v192, v191
	v_fmac_f32_e32 v192, v193, v197
	v_fma_f32 v191, -v194, v192, v191
	v_div_fmas_f32 v191, v191, v197, v192
	v_div_fixup_f32 v166, v191, v190, v166
	v_pk_mul_f32 v[190:191], v[166:167], v[166:167]
	s_nop 0
	v_add_f32_e32 v190, v190, v191
	v_mov_b32_e32 v191, 0
	s_nop 0
	v_add_f32_dpp v190, v190, v190 quad_perm:[1,0,3,2] row_mask:0xf bank_mask:0xf bound_ctrl:1
	s_nop 1
	v_add_f32_dpp v190, v190, v190 quad_perm:[2,3,0,1] row_mask:0xf bank_mask:0xf bound_ctrl:1
	s_nop 1
	v_add_f32_dpp v190, v190, v190 row_half_mirror row_mask:0xf bank_mask:0xf bound_ctrl:1
	s_nop 1
	v_add_f32_dpp v190, v190, v190 row_mirror row_mask:0xf bank_mask:0xf bound_ctrl:1
	s_nop 1
	v_mov_b32_dpp v191, v190 row_bcast:15 row_mask:0xa bank_mask:0xf
	v_add_f32_e32 v190, v190, v191
	v_mov_b32_e32 v191, 0
	s_nop 1
	v_mov_b32_dpp v191, v190 row_bcast:31 row_mask:0xc bank_mask:0xf
	v_add_f32_e32 v190, v190, v191
	s_nop 0
	v_readlane_b32 s6, v190, 63
	s_nop 1
	v_add_f32_e32 v190, s6, v179
	v_mul_f32_e32 v191, 0x4b800000, v190
	v_cmp_gt_f32_e32 vcc, s27, v190
	s_nop 1
	v_cndmask_b32_e32 v190, v190, v191, vcc
	v_rsq_f32_e32 v191, v190
	v_mul_f32_e32 v190, 0x3db504f3, v187
	v_mul_f32_e32 v187, 0x45800000, v191
	v_pk_mul_f32 v[188:189], v[188:189], v[190:191] op_sel_hi:[1,0]
	v_cndmask_b32_e32 v187, v191, v187, vcc
	global_store_dwordx2 v[110:111], v[188:189], off sc1
	v_mul_f32_e32 v188, 0x3db504f3, v187
	v_pk_mul_f32 v[166:167], v[166:167], v[188:189] op_sel_hi:[1,0]
	global_store_dwordx2 v[112:113], v[166:167], off sc1
	s_and_saveexec_b64 s[6:7], s[4:5]
	s_cbranch_execz .LBB0_225
	v_lshl_add_u64 v[166:167], v[56:57], 0, v[88:89]
	global_store_dwordx2 v[166:167], v[154:155], off sc1
; DI float bflo(unsigned u) { return __uint_as_float(u << 16); }
; DI float bfhi(unsigned u) { return __uint_as_float(u & 0xffff0000u); }
; DI float siluf_(float x) { return x / (1.0f + __expf(-x)); }
; template <int G0>
; DI void qkv_run4_half(const Params& p, int row0, int lane) {
;     ...
;     for (int g = 0; g < 4; ++g) {
;       const int grp = G0 + g;
;       const int ch = grp * 128 + lane * 2;
;       float a0 = 0.f, a1 = 0.f;
; #pragma unroll
;       for (int j = 0; j < 4; ++j) {
;         const int i = k + j;
;         const float m = (i >= 3) ? 1.f : hm;
;         a0 += w[g][j].x * (bflo(u[g][i]) * m);
;         a1 += w[g][j].y * (bfhi(u[g][i]) * m);
;       }
;       float y0 = siluf_(a0), y1 = siluf_(a1);
;       if (grp < 8) {
;         float ss = wave_sum(y0 * y0 + y1 * y1);
;         float inv = rsqrtf(ss + EPSF);
;         if (grp < 4) inv *= 0.08838834764831845f;
;         y0 *= inv; y1 *= inv;
;       }
;       float2 o = {y0, y1};
;       *(float2*)(p.QKV + (size_t)row * 1536 + ch) = o;
;       if (t0 == 2044 && k >= 1) {
;         float2 c = {bflo(u[g][k + 3]), bfhi(u[g][k + 3])};
;         *(float2*)(p.out + O_QKVP + ((size_t)b * 3 + (k - 1)) * 1536 + ch) = c;
;       }
.LBB0_225:
	s_or_b64 exec, exec, s[6:7]
	v_pk_fma_f32 v[164:165], v[164:165], v[140:141], 0 op_sel_hi:[1,1,0]
	v_lshlrev_b32_e32 v166, 16, v177
	v_pk_fma_f32 v[164:165], v[160:161], v[142:143], v[164:165]
	v_and_b32_e32 v167, 0xffff0000, v177
	v_pk_fma_f32 v[164:165], v[144:145], v[146:147], v[164:165]
	s_nop 0
	v_pk_fma_f32 v[164:165], v[138:139], v[166:167], v[164:165]
	s_nop 0
	v_mul_f32_e32 v177, 0xbfb8aa3b, v164
	v_exp_f32_e32 v188, v177
	v_mul_f32_e32 v177, 0xbfb8aa3b, v165
	v_exp_f32_e32 v189, v177
	s_nop 0
	v_pk_add_f32 v[188:189], v[188:189], 1.0 op_sel_hi:[1,0]
	s_nop 0
	v_div_scale_f32 v177, s[6:7], v189, v189, v165
	v_rcp_f32_e32 v187, v177
	s_nop 0
	v_fma_f32 v190, -v177, v187, 1.0
	v_fmac_f32_e32 v187, v190, v187
	v_div_scale_f32 v190, vcc, v165, v189, v165
	v_mul_f32_e32 v191, v190, v187
	v_fma_f32 v192, -v177, v191, v190
	v_fmac_f32_e32 v191, v192, v187
	v_fma_f32 v177, -v177, v191, v190
	v_div_scale_f32 v190, s[6:7], v188, v188, v164
	v_rcp_f32_e32 v192, v190
	v_div_fmas_f32 v177, v177, v187, v191
	v_div_fixup_f32 v165, v177, v189, v165
	v_fma_f32 v177, -v190, v192, 1.0
	v_fmac_f32_e32 v192, v177, v192
	v_div_scale_f32 v177, vcc, v164, v188, v164
	v_mul_f32_e32 v187, v177, v192
	v_fma_f32 v189, -v190, v187, v177
	v_fmac_f32_e32 v187, v189, v192
	v_fma_f32 v177, -v190, v187, v177
	v_div_fmas_f32 v177, v177, v192, v187
	v_div_fixup_f32 v164, v177, v188, v164
	v_pk_mul_f32 v[188:189], v[164:165], v[164:165]
	v_mov_b32_e32 v187, 0
	v_add_f32_e32 v177, v188, v189
	s_nop 1
	v_add_f32_dpp v177, v177, v177 quad_perm:[1,0,3,2] row_mask:0xf bank_mask:0xf bound_ctrl:1
	s_nop 1
	v_add_f32_dpp v177, v177, v177 quad_perm:[2,3,0,1] row_mask:0xf bank_mask:0xf bound_ctrl:1
	s_nop 1
	v_add_f32_dpp v177, v177, v177 row_half_mirror row_mask:0xf bank_mask:0xf bound_ctrl:1
	s_nop 1
	v_add_f32_dpp v177, v177, v177 row_mirror row_mask:0xf bank_mask:0xf bound_ctrl:1
	s_nop 1
	v_mov_b32_dpp v187, v177 row_bcast:15 row_mask:0xa bank_mask:0xf
	v_add_f32_e32 v177, v177, v187
	v_mov_b32_e32 v187, 0
	s_nop 1
	v_mov_b32_dpp v187, v177 row_bcast:31 row_mask:0xc bank_mask:0xf
	v_add_f32_e32 v177, v177, v187
	s_nop 0
	v_readlane_b32 s6, v177, 63
	s_nop 1
	v_add_f32_e32 v177, s6, v179
	v_mul_f32_e32 v187, 0x4b800000, v177
	v_cmp_gt_f32_e32 vcc, s27, v177
	s_nop 1
	v_cndmask_b32_e32 v177, v177, v187, vcc
	v_rsq_f32_e32 v177, v177
	s_nop 0
	v_mul_f32_e32 v187, 0x45800000, v177
	v_cndmask_b32_e32 v177, v177, v187, vcc
	v_mul_f32_e32 v188, 0x3db504f3, v177
	v_pk_mul_f32 v[164:165], v[164:165], v[188:189] op_sel_hi:[1,0]
	global_store_dwordx2 v[112:113], v[164:165], off offset:512 sc1
	s_and_saveexec_b64 s[6:7], s[4:5]
	s_cbranch_execz .LBB0_227
	v_lshl_add_u64 v[164:165], v[58:59], 0, v[88:89]
	global_store_dwordx2 v[164:165], v[166:167], off sc1
.LBB0_227:
	s_or_b64 exec, exec, s[6:7]
	v_pk_fma_f32 v[162:163], v[162:163], v[132:133], 0 op_sel_hi:[1,1,0]
	v_lshlrev_b32_e32 v164, 16, v170
	v_pk_fma_f32 v[162:163], v[158:159], v[134:135], v[162:163]
	v_and_b32_e32 v165, 0xffff0000, v170
	v_pk_fma_f32 v[162:163], v[136:137], v[130:131], v[162:163]
	s_nop 0
	v_pk_fma_f32 v[162:163], v[128:129], v[164:165], v[162:163]
	s_nop 0
	v_mul_f32_e32 v170, 0xbfb8aa3b, v162
	v_exp_f32_e32 v188, v170
	v_mul_f32_e32 v170, 0xbfb8aa3b, v163
	v_exp_f32_e32 v189, v170
	s_nop 0
	v_pk_add_f32 v[188:189], v[188:189], 1.0 op_sel_hi:[1,0]
	s_nop 0
	v_div_scale_f32 v170, s[6:7], v189, v189, v163
	v_rcp_f32_e32 v177, v170
	s_nop 0
	v_fma_f32 v187, -v170, v177, 1.0
	v_fmac_f32_e32 v177, v187, v177
	v_div_scale_f32 v187, vcc, v163, v189, v163
	v_mul_f32_e32 v190, v187, v177
	v_fma_f32 v191, -v170, v190, v187
	v_fmac_f32_e32 v190, v191, v177
	v_fma_f32 v170, -v170, v190, v187
	v_div_scale_f32 v187, s[6:7], v188, v188, v162
	v_rcp_f32_e32 v191, v187
	v_div_fmas_f32 v170, v170, v177, v190
	v_div_fixup_f32 v163, v170, v189, v163
	v_fma_f32 v170, -v187, v191, 1.0
	v_fmac_f32_e32 v191, v170, v191
	v_div_scale_f32 v170, vcc, v162, v188, v162
	v_mul_f32_e32 v177, v170, v191
	v_fma_f32 v189, -v187, v177, v170
	v_fmac_f32_e32 v177, v189, v191
	v_fma_f32 v170, -v187, v177, v170
	v_div_fmas_f32 v170, v170, v191, v177
	v_div_fixup_f32 v162, v170, v188, v162
	v_pk_mul_f32 v[188:189], v[162:163], v[162:163]
	v_mov_b32_e32 v177, 0
	v_add_f32_e32 v170, v188, v189
	s_nop 1
	v_add_f32_dpp v170, v170, v170 quad_perm:[1,0,3,2] row_mask:0xf bank_mask:0xf bound_ctrl:1
	s_nop 1
	v_add_f32_dpp v170, v170, v170 quad_perm:[2,3,0,1] row_mask:0xf bank_mask:0xf bound_ctrl:1
	s_nop 1
	v_add_f32_dpp v170, v170, v170 row_half_mirror row_mask:0xf bank_mask:0xf bound_ctrl:1
	s_nop 1
	v_add_f32_dpp v170, v170, v170 row_mirror row_mask:0xf bank_mask:0xf bound_ctrl:1
	s_nop 1
	v_mov_b32_dpp v177, v170 row_bcast:15 row_mask:0xa bank_mask:0xf
	v_add_f32_e32 v170, v170, v177
	v_mov_b32_e32 v177, 0
	s_nop 1
	v_mov_b32_dpp v177, v170 row_bcast:31 row_mask:0xc bank_mask:0xf
	v_add_f32_e32 v170, v170, v177
	s_nop 0
	v_readlane_b32 s6, v170, 63
	s_nop 1
	v_add_f32_e32 v170, s6, v179
	v_mul_f32_e32 v177, 0x4b800000, v170
	v_cmp_gt_f32_e32 vcc, s27, v170
	s_nop 1
	v_cndmask_b32_e32 v170, v170, v177, vcc
	v_rsq_f32_e32 v170, v170
	s_nop 0
	v_mul_f32_e32 v177, 0x45800000, v170
	v_cndmask_b32_e32 v170, v170, v177, vcc
	v_mul_f32_e32 v170, 0x3db504f3, v170
	v_pk_mul_f32 v[162:163], v[162:163], v[170:171] op_sel_hi:[1,0]
	global_store_dwordx2 v[112:113], v[162:163], off offset:1024 sc1
	s_and_saveexec_b64 s[6:7], s[4:5]
	s_cbranch_execz .LBB0_229
	v_lshl_add_u64 v[162:163], v[60:61], 0, v[88:89]
	global_store_dwordx2 v[162:163], v[164:165], off sc1
; DI float bflo(unsigned u) { return __uint_as_float(u << 16); }
; DI float bfhi(unsigned u) { return __uint_as_float(u & 0xffff0000u); }
; DI float siluf_(float x) { return x / (1.0f + __expf(-x)); }
; template <int G0>
; DI void qkv_run4_half(const Params& p, int row0, int lane) {
;     ...
;     for (int g = 0; g < 4; ++g) {
;       const int grp = G0 + g;
;       const int ch = grp * 128 + lane * 2;
;       float a0 = 0.f, a1 = 0.f;
; #pragma unroll
;       for (int j = 0; j < 4; ++j) {
;         const int i = k + j;
;         const float m = (i >= 3) ? 1.f : hm;
;         a0 += w[g][j].x * (bflo(u[g][i]) * m);
;         a1 += w[g][j].y * (bfhi(u[g][i]) * m);
;       }
;       float y0 = siluf_(a0), y1 = siluf_(a1);
;       if (grp < 8) {
;         float ss = wave_sum(y0 * y0 + y1 * y1);
;         float inv = rsqrtf(ss + EPSF);
;         if (grp < 4) inv *= 0.08838834764831845f;
;         y0 *= inv; y1 *= inv;
;       }
;       float2 o = {y0, y1};
;       *(float2*)(p.QKV + (size_t)row * 1536 + ch) = o;
;       if (t0 == 2044 && k >= 1) {
;         float2 c = {bflo(u[g][k + 3]), bfhi(u[g][k + 3])};
;         *(float2*)(p.out + O_QKVP + ((size_t)b * 3 + (k - 1)) * 1536 + ch) = c;
;       }
.LBB0_229:
	s_or_b64 exec, exec, s[6:7]
	v_pk_fma_f32 v[114:115], v[114:115], v[118:119], 0 op_sel_hi:[1,1,0]
	v_lshlrev_b32_e32 v162, 16, v168
	v_pk_fma_f32 v[114:115], v[156:157], v[120:121], v[114:115]
	v_and_b32_e32 v163, 0xffff0000, v168
	v_pk_fma_f32 v[114:115], v[124:125], v[126:127], v[114:115]
	s_nop 0
	v_pk_fma_f32 v[114:115], v[122:123], v[162:163], v[114:115]
	s_nop 0
	v_mul_f32_e32 v168, 0xbfb8aa3b, v114
	v_exp_f32_e32 v188, v168
	v_mul_f32_e32 v168, 0xbfb8aa3b, v115
	v_exp_f32_e32 v189, v168
	s_nop 0
	v_pk_add_f32 v[188:189], v[188:189], 1.0 op_sel_hi:[1,0]
	s_nop 0
	v_div_scale_f32 v168, s[6:7], v189, v189, v115
	v_rcp_f32_e32 v170, v168
	s_nop 0
	v_fma_f32 v177, -v168, v170, 1.0
	v_fmac_f32_e32 v170, v177, v170
	v_div_scale_f32 v177, vcc, v115, v189, v115
	v_mul_f32_e32 v187, v177, v170
	v_fma_f32 v190, -v168, v187, v177
	v_fmac_f32_e32 v187, v190, v170
	v_fma_f32 v168, -v168, v187, v177
	v_div_scale_f32 v177, s[6:7], v188, v188, v114
	v_rcp_f32_e32 v190, v177
	v_div_fmas_f32 v168, v168, v170, v187
	v_div_fixup_f32 v115, v168, v189, v115
	v_fma_f32 v168, -v177, v190, 1.0
	v_fmac_f32_e32 v190, v168, v190
	v_div_scale_f32 v168, vcc, v114, v188, v114
	v_mul_f32_e32 v170, v168, v190
	v_fma_f32 v187, -v177, v170, v168
	v_fmac_f32_e32 v170, v187, v190
	v_fma_f32 v168, -v177, v170, v168
	v_div_fmas_f32 v168, v168, v190, v170
	v_div_fixup_f32 v114, v168, v188, v114
	v_pk_mul_f32 v[188:189], v[114:115], v[114:115]
	v_mov_b32_e32 v170, 0
	v_add_f32_e32 v168, v188, v189
	s_nop 1
	v_add_f32_dpp v168, v168, v168 quad_perm:[1,0,3,2] row_mask:0xf bank_mask:0xf bound_ctrl:1
	s_nop 1
	v_add_f32_dpp v168, v168, v168 quad_perm:[2,3,0,1] row_mask:0xf bank_mask:0xf bound_ctrl:1
	s_nop 1
	v_add_f32_dpp v168, v168, v168 row_half_mirror row_mask:0xf bank_mask:0xf bound_ctrl:1
	s_nop 1
	v_add_f32_dpp v168, v168, v168 row_mirror row_mask:0xf bank_mask:0xf bound_ctrl:1
	s_nop 1
	v_mov_b32_dpp v170, v168 row_bcast:15 row_mask:0xa bank_mask:0xf
	v_add_f32_e32 v168, v168, v170
	v_mov_b32_e32 v170, 0
	s_nop 1
	v_mov_b32_dpp v170, v168 row_bcast:31 row_mask:0xc bank_mask:0xf
	v_add_f32_e32 v168, v168, v170
	s_nop 0
	v_readlane_b32 s6, v168, 63
	s_nop 1
	v_add_f32_e32 v168, s6, v179
	v_mul_f32_e32 v170, 0x4b800000, v168
	v_cmp_gt_f32_e32 vcc, s27, v168
	s_nop 1
	v_cndmask_b32_e32 v168, v168, v170, vcc
	v_rsq_f32_e32 v168, v168
	s_nop 0
	v_mul_f32_e32 v170, 0x45800000, v168
	v_cndmask_b32_e32 v168, v168, v170, vcc
	v_mul_f32_e32 v168, 0x3db504f3, v168
	v_pk_mul_f32 v[114:115], v[114:115], v[168:169] op_sel_hi:[1,0]
	global_store_dwordx2 v[112:113], v[114:115], off offset:1536 sc1
	s_and_saveexec_b64 s[6:7], s[4:5]
	s_cbranch_execz .LBB0_231
	v_lshl_add_u64 v[114:115], v[62:63], 0, v[88:89]
	global_store_dwordx2 v[114:115], v[162:163], off sc1
.LBB0_231:
	s_or_b64 exec, exec, s[6:7]
	v_pk_fma_f32 v[94:95], v[94:95], v[116:117], 0 op_sel_hi:[1,1,0]
	v_lshlrev_b32_e32 v168, 16, v169
	v_pk_fma_f32 v[94:95], v[148:149], v[108:109], v[94:95]
	v_and_b32_e32 v169, 0xffff0000, v169
	v_pk_fma_f32 v[94:95], v[152:153], v[154:155], v[94:95]
	s_nop 0
	v_pk_fma_f32 v[94:95], v[150:151], v[168:169], v[94:95]
	s_nop 0
	v_mul_f32_e32 v114, 0xbfb8aa3b, v94
	v_mul_f32_e32 v115, 0xbfb8aa3b, v95
	v_exp_f32_e32 v114, v114
	v_exp_f32_e32 v115, v115
	s_nop 0
	v_pk_add_f32 v[114:115], v[114:115], 1.0 op_sel_hi:[1,0]
	s_nop 0
	v_div_scale_f32 v170, s[6:7], v115, v115, v95
	v_rcp_f32_e32 v177, v170
	s_nop 0
	v_fma_f32 v187, -v170, v177, 1.0
	v_fmac_f32_e32 v177, v187, v177
	v_div_scale_f32 v187, vcc, v95, v115, v95
	v_mul_f32_e32 v188, v187, v177
	v_fma_f32 v189, -v170, v188, v187
	v_fmac_f32_e32 v188, v189, v177
	v_fma_f32 v170, -v170, v188, v187
	v_div_scale_f32 v187, s[6:7], v114, v114, v94
	v_rcp_f32_e32 v190, v187
	v_div_fmas_f32 v170, v170, v177, v188
	v_div_fixup_f32 v189, v170, v115, v95
	v_fma_f32 v95, -v187, v190, 1.0
	v_fmac_f32_e32 v190, v95, v190
	v_div_scale_f32 v95, vcc, v94, v114, v94
	v_mul_f32_e32 v115, v95, v190
	v_fma_f32 v170, -v187, v115, v95
	v_fmac_f32_e32 v115, v170, v190
	v_fma_f32 v95, -v187, v115, v95
	v_div_fmas_f32 v95, v95, v190, v115
	v_div_fixup_f32 v188, v95, v114, v94
	v_pk_mul_f32 v[94:95], v[188:189], v[188:189]
	s_nop 0
	v_add_f32_e32 v94, v94, v95
	v_mov_b32_e32 v95, 0
	s_nop 0
	v_add_f32_dpp v94, v94, v94 quad_perm:[1,0,3,2] row_mask:0xf bank_mask:0xf bound_ctrl:1
	s_nop 1
	v_add_f32_dpp v94, v94, v94 quad_perm:[2,3,0,1] row_mask:0xf bank_mask:0xf bound_ctrl:1
	s_nop 1
	v_add_f32_dpp v94, v94, v94 row_half_mirror row_mask:0xf bank_mask:0xf bound_ctrl:1
	s_nop 1
	v_add_f32_dpp v94, v94, v94 row_mirror row_mask:0xf bank_mask:0xf bound_ctrl:1
	s_nop 1
	v_mov_b32_dpp v95, v94 row_bcast:15 row_mask:0xa bank_mask:0xf
	v_add_f32_e32 v94, v94, v95
	v_mov_b32_e32 v95, 0
	s_nop 1
	v_mov_b32_dpp v95, v94 row_bcast:31 row_mask:0xc bank_mask:0xf
	v_add_f32_e32 v94, v94, v95
	s_nop 0
	v_readlane_b32 s6, v94, 63
	s_nop 1
	v_add_f32_e32 v94, s6, v179
	v_mul_f32_e32 v95, 0x4b800000, v94
	v_cmp_gt_f32_e32 vcc, s27, v94
	v_mad_i64_i32 v[114:115], s[6:7], v87, s26, v[32:33]
	s_nop 0
	v_cndmask_b32_e32 v94, v94, v95, vcc
	v_rsq_f32_e32 v170, v94
	v_lshl_add_u64 v[94:95], v[88:89], 0, s[12:13]
	v_mul_f32_e32 v177, 0x45800000, v170
	v_cndmask_b32_e32 v170, v170, v177, vcc
	v_mul_f32_e32 v170, 0x3db504f3, v170
	v_pk_mul_f32 v[188:189], v[188:189], v[170:171] op_sel_hi:[1,0]
	global_store_dwordx2 v[114:115], v[188:189], off sc1
	s_and_saveexec_b64 s[6:7], s[4:5]
	s_cbranch_execz .LBB0_233
	v_lshl_add_u64 v[188:189], v[56:57], 0, v[94:95]
	global_store_dwordx2 v[188:189], v[168:169], off sc1
; DI float bflo(unsigned u) { return __uint_as_float(u << 16); }
; DI float bfhi(unsigned u) { return __uint_as_float(u & 0xffff0000u); }
; DI float siluf_(float x) { return x / (1.0f + __expf(-x)); }
; template <int G0>
; DI void qkv_run4_half(const Params& p, int row0, int lane) {
;     ...
;     for (int g = 0; g < 4; ++g) {
;       const int grp = G0 + g;
;       const int ch = grp * 128 + lane * 2;
;       float a0 = 0.f, a1 = 0.f;
; #pragma unroll
;       for (int j = 0; j < 4; ++j) {
;         const int i = k + j;
;         const float m = (i >= 3) ? 1.f : hm;
;         a0 += w[g][j].x * (bflo(u[g][i]) * m);
;         a1 += w[g][j].y * (bfhi(u[g][i]) * m);
;       }
;       float y0 = siluf_(a0), y1 = siluf_(a1);
;       if (grp < 8) {
;         float ss = wave_sum(y0 * y0 + y1 * y1);
;         float inv = rsqrtf(ss + EPSF);
;         if (grp < 4) inv *= 0.08838834764831845f;
;         y0 *= inv; y1 *= inv;
;       }
;       float2 o = {y0, y1};
;       *(float2*)(p.QKV + (size_t)row * 1536 + ch) = o;
;       if (t0 == 2044 && k >= 1) {
;         float2 c = {bflo(u[g][k + 3]), bfhi(u[g][k + 3])};
;         *(float2*)(p.out + O_QKVP + ((size_t)b * 3 + (k - 1)) * 1536 + ch) = c;
;       }
.LBB0_233:
	s_or_b64 exec, exec, s[6:7]
	v_pk_fma_f32 v[160:161], v[160:161], v[140:141], 0 op_sel_hi:[1,1,0]
	v_lshlrev_b32_e32 v170, 16, v171
	v_pk_fma_f32 v[160:161], v[142:143], v[146:147], v[160:161]
	v_and_b32_e32 v171, 0xffff0000, v171
	v_pk_fma_f32 v[160:161], v[144:145], v[166:167], v[160:161]
	s_nop 0
	v_pk_fma_f32 v[160:161], v[138:139], v[170:171], v[160:161]
	s_nop 0
	v_mul_f32_e32 v177, 0xbfb8aa3b, v160
	v_exp_f32_e32 v188, v177
	v_mul_f32_e32 v177, 0xbfb8aa3b, v161
	v_exp_f32_e32 v189, v177
	s_nop 0
	v_pk_add_f32 v[188:189], v[188:189], 1.0 op_sel_hi:[1,0]
	s_nop 0
	v_div_scale_f32 v177, s[6:7], v189, v189, v161
	v_rcp_f32_e32 v187, v177
	s_nop 0
	v_fma_f32 v190, -v177, v187, 1.0
	v_fmac_f32_e32 v187, v190, v187
	v_div_scale_f32 v190, vcc, v161, v189, v161
	v_mul_f32_e32 v191, v190, v187
	v_fma_f32 v192, -v177, v191, v190
	v_fmac_f32_e32 v191, v192, v187
	v_fma_f32 v177, -v177, v191, v190
	v_div_scale_f32 v190, s[6:7], v188, v188, v160
	v_rcp_f32_e32 v192, v190
	v_div_fmas_f32 v177, v177, v187, v191
	v_div_fixup_f32 v161, v177, v189, v161
	v_fma_f32 v177, -v190, v192, 1.0
	v_fmac_f32_e32 v192, v177, v192
	v_div_scale_f32 v177, vcc, v160, v188, v160
	v_mul_f32_e32 v187, v177, v192
	v_fma_f32 v189, -v190, v187, v177
	v_fmac_f32_e32 v187, v189, v192
	v_fma_f32 v177, -v190, v187, v177
	v_div_fmas_f32 v177, v177, v192, v187
	v_div_fixup_f32 v160, v177, v188, v160
	v_pk_mul_f32 v[188:189], v[160:161], v[160:161]
	v_mov_b32_e32 v187, 0
	v_add_f32_e32 v177, v188, v189
	s_nop 1
	v_add_f32_dpp v177, v177, v177 quad_perm:[1,0,3,2] row_mask:0xf bank_mask:0xf bound_ctrl:1
	s_nop 1
	v_add_f32_dpp v177, v177, v177 quad_perm:[2,3,0,1] row_mask:0xf bank_mask:0xf bound_ctrl:1
	s_nop 1
	v_add_f32_dpp v177, v177, v177 row_half_mirror row_mask:0xf bank_mask:0xf bound_ctrl:1
	s_nop 1
	v_add_f32_dpp v177, v177, v177 row_mirror row_mask:0xf bank_mask:0xf bound_ctrl:1
	s_nop 1
	v_mov_b32_dpp v187, v177 row_bcast:15 row_mask:0xa bank_mask:0xf
	v_add_f32_e32 v177, v177, v187
	v_mov_b32_e32 v187, 0
	s_nop 1
	v_mov_b32_dpp v187, v177 row_bcast:31 row_mask:0xc bank_mask:0xf
	v_add_f32_e32 v177, v177, v187
	s_nop 0
	v_readlane_b32 s6, v177, 63
	s_nop 1
	v_add_f32_e32 v177, s6, v179
	v_mul_f32_e32 v187, 0x4b800000, v177
	v_cmp_gt_f32_e32 vcc, s27, v177
	s_nop 1
	v_cndmask_b32_e32 v177, v177, v187, vcc
	v_rsq_f32_e32 v177, v177
	s_nop 0
	v_mul_f32_e32 v187, 0x45800000, v177
	v_cndmask_b32_e32 v177, v177, v187, vcc
	v_mul_f32_e32 v188, 0x3db504f3, v177
	v_pk_mul_f32 v[160:161], v[160:161], v[188:189] op_sel_hi:[1,0]
	global_store_dwordx2 v[114:115], v[160:161], off offset:512 sc1
	s_and_saveexec_b64 s[6:7], s[4:5]
	s_cbranch_execz .LBB0_235
	v_lshl_add_u64 v[160:161], v[58:59], 0, v[94:95]
	global_store_dwordx2 v[160:161], v[170:171], off sc1
.LBB0_235:
	s_or_b64 exec, exec, s[6:7]
	v_pk_fma_f32 v[158:159], v[158:159], v[132:133], 0 op_sel_hi:[1,1,0]
	v_lshlrev_b32_e32 v160, 16, v176
	v_pk_fma_f32 v[158:159], v[134:135], v[130:131], v[158:159]
	v_and_b32_e32 v161, 0xffff0000, v176
	v_pk_fma_f32 v[158:159], v[136:137], v[164:165], v[158:159]
	s_nop 0
	v_pk_fma_f32 v[158:159], v[128:129], v[160:161], v[158:159]
	s_nop 0
	v_mul_f32_e32 v176, 0xbfb8aa3b, v158
	v_mul_f32_e32 v177, 0xbfb8aa3b, v159
	v_exp_f32_e32 v176, v176
	v_exp_f32_e32 v177, v177
	s_nop 0
	v_pk_add_f32 v[176:177], v[176:177], 1.0 op_sel_hi:[1,0]
	s_nop 0
	v_div_scale_f32 v187, s[6:7], v177, v177, v159
	v_rcp_f32_e32 v188, v187
	s_nop 0
	v_fma_f32 v189, -v187, v188, 1.0
	v_fmac_f32_e32 v188, v189, v188
	v_div_scale_f32 v189, vcc, v159, v177, v159
	v_mul_f32_e32 v190, v189, v188
	v_fma_f32 v191, -v187, v190, v189
	v_fmac_f32_e32 v190, v191, v188
	v_fma_f32 v187, -v187, v190, v189
	v_div_scale_f32 v189, s[6:7], v176, v176, v158
	v_rcp_f32_e32 v191, v189
	v_div_fmas_f32 v187, v187, v188, v190
	v_div_fixup_f32 v159, v187, v177, v159
	v_fma_f32 v177, -v189, v191, 1.0
	v_fmac_f32_e32 v191, v177, v191
	v_div_scale_f32 v177, vcc, v158, v176, v158
	v_mul_f32_e32 v187, v177, v191
	v_fma_f32 v188, -v189, v187, v177
	v_fmac_f32_e32 v187, v188, v191
	v_fma_f32 v177, -v189, v187, v177
	v_div_fmas_f32 v177, v177, v191, v187
	v_div_fixup_f32 v158, v177, v176, v158
	v_pk_mul_f32 v[176:177], v[158:159], v[158:159]
	s_nop 0
	v_add_f32_e32 v176, v176, v177
	v_mov_b32_e32 v177, 0
	s_nop 0
	v_add_f32_dpp v176, v176, v176 quad_perm:[1,0,3,2] row_mask:0xf bank_mask:0xf bound_ctrl:1
	s_nop 1
	v_add_f32_dpp v176, v176, v176 quad_perm:[2,3,0,1] row_mask:0xf bank_mask:0xf bound_ctrl:1
	s_nop 1
	v_add_f32_dpp v176, v176, v176 row_half_mirror row_mask:0xf bank_mask:0xf bound_ctrl:1
	s_nop 1
	v_add_f32_dpp v176, v176, v176 row_mirror row_mask:0xf bank_mask:0xf bound_ctrl:1
	s_nop 1
	v_mov_b32_dpp v177, v176 row_bcast:15 row_mask:0xa bank_mask:0xf
	v_add_f32_e32 v176, v176, v177
	v_mov_b32_e32 v177, 0
	s_nop 1
	v_mov_b32_dpp v177, v176 row_bcast:31 row_mask:0xc bank_mask:0xf
	v_add_f32_e32 v176, v176, v177
	s_nop 0
	v_readlane_b32 s6, v176, 63
	s_nop 1
	v_add_f32_e32 v176, s6, v179
	v_mul_f32_e32 v177, 0x4b800000, v176
	v_cmp_gt_f32_e32 vcc, s27, v176
	s_nop 1
	v_cndmask_b32_e32 v176, v176, v177, vcc
	v_rsq_f32_e32 v176, v176
	s_nop 0
	v_mul_f32_e32 v177, 0x45800000, v176
	v_cndmask_b32_e32 v176, v176, v177, vcc
	v_mul_f32_e32 v176, 0x3db504f3, v176
	v_pk_mul_f32 v[158:159], v[158:159], v[176:177] op_sel_hi:[1,0]
	global_store_dwordx2 v[114:115], v[158:159], off offset:1024 sc1
	s_and_saveexec_b64 s[6:7], s[4:5]
	s_cbranch_execz .LBB0_237
	v_lshl_add_u64 v[158:159], v[60:61], 0, v[94:95]
	global_store_dwordx2 v[158:159], v[160:161], off sc1
; DI float bflo(unsigned u) { return __uint_as_float(u << 16); }
; DI float bfhi(unsigned u) { return __uint_as_float(u & 0xffff0000u); }
; DI float siluf_(float x) { return x / (1.0f + __expf(-x)); }
; template <int G0>
; DI void qkv_run4_half(const Params& p, int row0, int lane) {
;     ...
;     for (int g = 0; g < 4; ++g) {
;       const int grp = G0 + g;
;       const int ch = grp * 128 + lane * 2;
;       float a0 = 0.f, a1 = 0.f;
; #pragma unroll
;       for (int j = 0; j < 4; ++j) {
;         const int i = k + j;
;         const float m = (i >= 3) ? 1.f : hm;
;         a0 += w[g][j].x * (bflo(u[g][i]) * m);
;         a1 += w[g][j].y * (bfhi(u[g][i]) * m);
;       }
;       float y0 = siluf_(a0), y1 = siluf_(a1);
;       if (grp < 8) {
;         float ss = wave_sum(y0 * y0 + y1 * y1);
;         float inv = rsqrtf(ss + EPSF);
;         if (grp < 4) inv *= 0.08838834764831845f;
;         y0 *= inv; y1 *= inv;
;       }
;       float2 o = {y0, y1};
;       *(float2*)(p.QKV + (size_t)row * 1536 + ch) = o;
;       if (t0 == 2044 && k >= 1) {
;         float2 c = {bflo(u[g][k + 3]), bfhi(u[g][k + 3])};
;         *(float2*)(p.out + O_QKVP + ((size_t)b * 3 + (k - 1)) * 1536 + ch) = c;
;       }
.LBB0_237:
	s_or_b64 exec, exec, s[6:7]
	v_pk_fma_f32 v[156:157], v[156:157], v[118:119], 0 op_sel_hi:[1,1,0]
	v_lshlrev_b32_e32 v158, 16, v175
	v_pk_fma_f32 v[156:157], v[120:121], v[126:127], v[156:157]
	v_and_b32_e32 v159, 0xffff0000, v175
	v_pk_fma_f32 v[156:157], v[124:125], v[162:163], v[156:157]
	s_nop 0
	v_pk_fma_f32 v[156:157], v[122:123], v[158:159], v[156:157]
	s_nop 0
	v_mul_f32_e32 v175, 0xbfb8aa3b, v156
	v_exp_f32_e32 v176, v175
	v_mul_f32_e32 v175, 0xbfb8aa3b, v157
	v_exp_f32_e32 v177, v175
	s_nop 0
	v_pk_add_f32 v[176:177], v[176:177], 1.0 op_sel_hi:[1,0]
	s_nop 0
	v_div_scale_f32 v175, s[6:7], v177, v177, v157
	v_rcp_f32_e32 v187, v175
	s_nop 0
	v_fma_f32 v188, -v175, v187, 1.0
	v_fmac_f32_e32 v187, v188, v187
	v_div_scale_f32 v188, vcc, v157, v177, v157
	v_mul_f32_e32 v189, v188, v187
	v_fma_f32 v190, -v175, v189, v188
	v_fmac_f32_e32 v189, v190, v187
	v_fma_f32 v175, -v175, v189, v188
	v_div_scale_f32 v188, s[6:7], v176, v176, v156
	v_rcp_f32_e32 v190, v188
	v_div_fmas_f32 v175, v175, v187, v189
	v_div_fixup_f32 v157, v175, v177, v157
	v_fma_f32 v175, -v188, v190, 1.0
	v_fmac_f32_e32 v190, v175, v190
	v_div_scale_f32 v175, vcc, v156, v176, v156
	v_mul_f32_e32 v177, v175, v190
	v_fma_f32 v187, -v188, v177, v175
	v_fmac_f32_e32 v177, v187, v190
	v_fma_f32 v175, -v188, v177, v175
	v_div_fmas_f32 v175, v175, v190, v177
	v_div_fixup_f32 v156, v175, v176, v156
	v_pk_mul_f32 v[176:177], v[156:157], v[156:157]
	s_nop 0
	v_add_f32_e32 v175, v176, v177
	v_mov_b32_e32 v176, 0
	s_nop 0
	v_add_f32_dpp v175, v175, v175 quad_perm:[1,0,3,2] row_mask:0xf bank_mask:0xf bound_ctrl:1
	s_nop 1
	v_add_f32_dpp v175, v175, v175 quad_perm:[2,3,0,1] row_mask:0xf bank_mask:0xf bound_ctrl:1
	s_nop 1
	v_add_f32_dpp v175, v175, v175 row_half_mirror row_mask:0xf bank_mask:0xf bound_ctrl:1
	s_nop 1
	v_add_f32_dpp v175, v175, v175 row_mirror row_mask:0xf bank_mask:0xf bound_ctrl:1
	s_nop 1
	v_mov_b32_dpp v176, v175 row_bcast:15 row_mask:0xa bank_mask:0xf
	v_add_f32_e32 v175, v175, v176
	v_mov_b32_e32 v176, 0
	s_nop 1
	v_mov_b32_dpp v176, v175 row_bcast:31 row_mask:0xc bank_mask:0xf
	v_add_f32_e32 v175, v175, v176
	s_nop 0
	v_readlane_b32 s6, v175, 63
	s_nop 1
	v_add_f32_e32 v175, s6, v179
	v_mul_f32_e32 v176, 0x4b800000, v175
	v_cmp_gt_f32_e32 vcc, s27, v175
	s_nop 1
	v_cndmask_b32_e32 v175, v175, v176, vcc
	v_rsq_f32_e32 v175, v175
	s_nop 0
	v_mul_f32_e32 v176, 0x45800000, v175
	v_cndmask_b32_e32 v175, v175, v176, vcc
	v_mul_f32_e32 v176, 0x3db504f3, v175
	v_pk_mul_f32 v[156:157], v[156:157], v[176:177] op_sel_hi:[1,0]
	global_store_dwordx2 v[114:115], v[156:157], off offset:1536 sc1
	s_and_saveexec_b64 s[6:7], s[4:5]
	s_cbranch_execz .LBB0_239
	v_lshl_add_u64 v[156:157], v[62:63], 0, v[94:95]
	global_store_dwordx2 v[156:157], v[158:159], off sc1
.LBB0_239:
	s_or_b64 exec, exec, s[6:7]
	v_pk_fma_f32 v[108:109], v[116:117], v[108:109], 0 op_sel_hi:[1,1,0]
	v_lshlrev_b32_e32 v156, 16, v174
	v_pk_fma_f32 v[108:109], v[148:149], v[154:155], v[108:109]
	v_and_b32_e32 v157, 0xffff0000, v174
	v_pk_fma_f32 v[108:109], v[152:153], v[168:169], v[108:109]
	s_nop 0
	v_pk_fma_f32 v[108:109], v[150:151], v[156:157], v[108:109]
	s_nop 0
	v_mul_f32_e32 v116, 0xbfb8aa3b, v108
	v_mul_f32_e32 v117, 0xbfb8aa3b, v109
	v_exp_f32_e32 v116, v116
	v_exp_f32_e32 v117, v117
	s_nop 0
	v_pk_add_f32 v[116:117], v[116:117], 1.0 op_sel_hi:[1,0]
	s_nop 0
	v_div_scale_f32 v148, s[6:7], v117, v117, v109
	v_rcp_f32_e32 v149, v148
	s_nop 0
	v_fma_f32 v150, -v148, v149, 1.0
	v_fmac_f32_e32 v149, v150, v149
	v_div_scale_f32 v150, vcc, v109, v117, v109
	v_mul_f32_e32 v151, v150, v149
	v_fma_f32 v152, -v148, v151, v150
	v_fmac_f32_e32 v151, v152, v149
	v_fma_f32 v148, -v148, v151, v150
	v_div_scale_f32 v150, s[6:7], v116, v116, v108
	v_rcp_f32_e32 v152, v150
	v_div_fmas_f32 v148, v148, v149, v151
	v_div_fixup_f32 v149, v148, v117, v109
	v_fma_f32 v109, -v150, v152, 1.0
	v_fmac_f32_e32 v152, v109, v152
	v_div_scale_f32 v109, vcc, v108, v116, v108
	v_mul_f32_e32 v117, v109, v152
	v_fma_f32 v148, -v150, v117, v109
	v_fmac_f32_e32 v117, v148, v152
	v_fma_f32 v109, -v150, v117, v109
	v_div_fmas_f32 v109, v109, v152, v117
	v_div_fixup_f32 v148, v109, v116, v108
	v_pk_mul_f32 v[108:109], v[148:149], v[148:149]
	s_nop 0
	v_add_f32_e32 v108, v108, v109
	v_mov_b32_e32 v109, 0
	s_nop 0
	v_add_f32_dpp v108, v108, v108 quad_perm:[1,0,3,2] row_mask:0xf bank_mask:0xf bound_ctrl:1
	s_nop 1
	v_add_f32_dpp v108, v108, v108 quad_perm:[2,3,0,1] row_mask:0xf bank_mask:0xf bound_ctrl:1
	s_nop 1
	v_add_f32_dpp v108, v108, v108 row_half_mirror row_mask:0xf bank_mask:0xf bound_ctrl:1
	s_nop 1
	v_add_f32_dpp v108, v108, v108 row_mirror row_mask:0xf bank_mask:0xf bound_ctrl:1
	s_nop 1
	v_mov_b32_dpp v109, v108 row_bcast:15 row_mask:0xa bank_mask:0xf
	v_add_f32_e32 v108, v108, v109
	v_mov_b32_e32 v109, 0
	s_nop 1
	v_mov_b32_dpp v109, v108 row_bcast:31 row_mask:0xc bank_mask:0xf
	v_add_f32_e32 v108, v108, v109
	s_nop 0
	v_readlane_b32 s6, v108, 63
	s_nop 1
	v_add_f32_e32 v108, s6, v179
	v_mul_f32_e32 v109, 0x4b800000, v108
	v_cmp_gt_f32_e32 vcc, s27, v108
	v_mad_i64_i32 v[116:117], s[6:7], v178, s26, v[32:33]
	s_nop 0
	v_cndmask_b32_e32 v108, v108, v109, vcc
	v_rsq_f32_e32 v150, v108
	v_lshl_add_u64 v[108:109], v[88:89], 0, s[14:15]
	v_mul_f32_e32 v151, 0x45800000, v150
	v_cndmask_b32_e32 v150, v150, v151, vcc
	v_mul_f32_e32 v150, 0x3db504f3, v150
	v_pk_mul_f32 v[148:149], v[148:149], v[150:151] op_sel_hi:[1,0]
	global_store_dwordx2 v[116:117], v[148:149], off sc1
	s_and_saveexec_b64 s[6:7], s[4:5]
	s_cbranch_execz .LBB0_241
	v_lshl_add_u64 v[148:149], v[56:57], 0, v[108:109]
	global_store_dwordx2 v[148:149], v[156:157], off sc1
; DI float bflo(unsigned u) { return __uint_as_float(u << 16); }
; DI float bfhi(unsigned u) { return __uint_as_float(u & 0xffff0000u); }
; DI float siluf_(float x) { return x / (1.0f + __expf(-x)); }
; template <int G0>
; DI void qkv_run4_half(const Params& p, int row0, int lane) {
;     ...
;     for (int g = 0; g < 4; ++g) {
;       const int grp = G0 + g;
;       const int ch = grp * 128 + lane * 2;
;       float a0 = 0.f, a1 = 0.f;
; #pragma unroll
;       for (int j = 0; j < 4; ++j) {
;         const int i = k + j;
;         const float m = (i >= 3) ? 1.f : hm;
;         a0 += w[g][j].x * (bflo(u[g][i]) * m);
;         a1 += w[g][j].y * (bfhi(u[g][i]) * m);
;       }
;       float y0 = siluf_(a0), y1 = siluf_(a1);
;       if (grp < 8) {
;         float ss = wave_sum(y0 * y0 + y1 * y1);
;         float inv = rsqrtf(ss + EPSF);
;         if (grp < 4) inv *= 0.08838834764831845f;
;         y0 *= inv; y1 *= inv;
;       }
;       float2 o = {y0, y1};
;       *(float2*)(p.QKV + (size_t)row * 1536 + ch) = o;
;       if (t0 == 2044 && k >= 1) {
;         float2 c = {bflo(u[g][k + 3]), bfhi(u[g][k + 3])};
;         *(float2*)(p.out + O_QKVP + ((size_t)b * 3 + (k - 1)) * 1536 + ch) = c;
;       }
.LBB0_241:
	s_or_b64 exec, exec, s[6:7]
	v_pk_fma_f32 v[140:141], v[140:141], v[146:147], 0 op_sel_hi:[1,1,0]
	v_lshlrev_b32_e32 v148, 16, v173
	v_pk_fma_f32 v[140:141], v[142:143], v[166:167], v[140:141]
	v_and_b32_e32 v149, 0xffff0000, v173
	v_pk_fma_f32 v[140:141], v[144:145], v[170:171], v[140:141]
	s_nop 0
	v_pk_fma_f32 v[138:139], v[138:139], v[148:149], v[140:141]
	s_nop 0
	v_mul_f32_e32 v140, 0xbfb8aa3b, v138
	v_mul_f32_e32 v141, 0xbfb8aa3b, v139
	v_exp_f32_e32 v140, v140
	v_exp_f32_e32 v141, v141
	s_nop 0
	v_pk_add_f32 v[140:141], v[140:141], 1.0 op_sel_hi:[1,0]
	s_nop 0
	v_div_scale_f32 v142, s[6:7], v141, v141, v139
	v_rcp_f32_e32 v143, v142
	s_nop 0
	v_fma_f32 v144, -v142, v143, 1.0
	v_fmac_f32_e32 v143, v144, v143
	v_div_scale_f32 v144, vcc, v139, v141, v139
	v_mul_f32_e32 v145, v144, v143
	v_fma_f32 v146, -v142, v145, v144
	v_fmac_f32_e32 v145, v146, v143
	v_fma_f32 v142, -v142, v145, v144
	v_div_scale_f32 v144, s[6:7], v140, v140, v138
	v_rcp_f32_e32 v146, v144
	v_div_fmas_f32 v142, v142, v143, v145
	v_div_fixup_f32 v139, v142, v141, v139
	v_fma_f32 v141, -v144, v146, 1.0
	v_fmac_f32_e32 v146, v141, v146
	v_div_scale_f32 v141, vcc, v138, v140, v138
	v_mul_f32_e32 v142, v141, v146
	v_fma_f32 v143, -v144, v142, v141
	v_fmac_f32_e32 v142, v143, v146
	v_fma_f32 v141, -v144, v142, v141
	v_div_fmas_f32 v141, v141, v146, v142
	v_div_fixup_f32 v138, v141, v140, v138
	v_pk_mul_f32 v[140:141], v[138:139], v[138:139]
	s_nop 0
	v_add_f32_e32 v140, v140, v141
	v_mov_b32_e32 v141, 0
	s_nop 0
	v_add_f32_dpp v140, v140, v140 quad_perm:[1,0,3,2] row_mask:0xf bank_mask:0xf bound_ctrl:1
	s_nop 1
	v_add_f32_dpp v140, v140, v140 quad_perm:[2,3,0,1] row_mask:0xf bank_mask:0xf bound_ctrl:1
	s_nop 1
	v_add_f32_dpp v140, v140, v140 row_half_mirror row_mask:0xf bank_mask:0xf bound_ctrl:1
	s_nop 1
	v_add_f32_dpp v140, v140, v140 row_mirror row_mask:0xf bank_mask:0xf bound_ctrl:1
	s_nop 1
	v_mov_b32_dpp v141, v140 row_bcast:15 row_mask:0xa bank_mask:0xf
	v_add_f32_e32 v140, v140, v141
	v_mov_b32_e32 v141, 0
	s_nop 1
	v_mov_b32_dpp v141, v140 row_bcast:31 row_mask:0xc bank_mask:0xf
	v_add_f32_e32 v140, v140, v141
	s_nop 0
	v_readlane_b32 s6, v140, 63
	s_nop 1
	v_add_f32_e32 v140, s6, v179
	v_mul_f32_e32 v141, 0x4b800000, v140
	v_cmp_gt_f32_e32 vcc, s27, v140
	s_nop 1
	v_cndmask_b32_e32 v140, v140, v141, vcc
	v_rsq_f32_e32 v140, v140
	s_nop 0
	v_mul_f32_e32 v141, 0x45800000, v140
	v_cndmask_b32_e32 v140, v140, v141, vcc
	v_mul_f32_e32 v140, 0x3db504f3, v140
	v_pk_mul_f32 v[138:139], v[138:139], v[140:141] op_sel_hi:[1,0]
	global_store_dwordx2 v[116:117], v[138:139], off offset:512 sc1
	s_and_saveexec_b64 s[6:7], s[4:5]
	s_cbranch_execz .LBB0_243
	v_lshl_add_u64 v[138:139], v[58:59], 0, v[108:109]
	global_store_dwordx2 v[138:139], v[148:149], off sc1
.LBB0_243:
	s_or_b64 exec, exec, s[6:7]
	v_pk_fma_f32 v[130:131], v[132:133], v[130:131], 0 op_sel_hi:[1,1,0]
	v_lshlrev_b32_e32 v138, 16, v172
	v_pk_fma_f32 v[130:131], v[134:135], v[164:165], v[130:131]
	v_and_b32_e32 v139, 0xffff0000, v172
	v_pk_fma_f32 v[130:131], v[136:137], v[160:161], v[130:131]
	s_nop 0
	v_pk_fma_f32 v[128:129], v[128:129], v[138:139], v[130:131]
	s_nop 0
	v_mul_f32_e32 v130, 0xbfb8aa3b, v128
	v_mul_f32_e32 v131, 0xbfb8aa3b, v129
	v_exp_f32_e32 v130, v130
	v_exp_f32_e32 v131, v131
	s_nop 0
	v_pk_add_f32 v[130:131], v[130:131], 1.0 op_sel_hi:[1,0]
	s_nop 0
	v_div_scale_f32 v132, s[6:7], v131, v131, v129
	v_rcp_f32_e32 v133, v132
	s_nop 0
	v_fma_f32 v134, -v132, v133, 1.0
	v_fmac_f32_e32 v133, v134, v133
	v_div_scale_f32 v134, vcc, v129, v131, v129
	v_mul_f32_e32 v135, v134, v133
	v_fma_f32 v136, -v132, v135, v134
	v_fmac_f32_e32 v135, v136, v133
	v_fma_f32 v132, -v132, v135, v134
	v_div_scale_f32 v134, s[6:7], v130, v130, v128
	v_rcp_f32_e32 v136, v134
	v_div_fmas_f32 v132, v132, v133, v135
	v_div_fixup_f32 v129, v132, v131, v129
	v_fma_f32 v131, -v134, v136, 1.0
	v_fmac_f32_e32 v136, v131, v136
	v_div_scale_f32 v131, vcc, v128, v130, v128
	v_mul_f32_e32 v132, v131, v136
	v_fma_f32 v133, -v134, v132, v131
	v_fmac_f32_e32 v132, v133, v136
	v_fma_f32 v131, -v134, v132, v131
	v_div_fmas_f32 v131, v131, v136, v132
	v_div_fixup_f32 v128, v131, v130, v128
	v_pk_mul_f32 v[130:131], v[128:129], v[128:129]
	s_nop 0
	v_add_f32_e32 v130, v130, v131
	v_mov_b32_e32 v131, 0
	s_nop 0
	v_add_f32_dpp v130, v130, v130 quad_perm:[1,0,3,2] row_mask:0xf bank_mask:0xf bound_ctrl:1
	s_nop 1
	v_add_f32_dpp v130, v130, v130 quad_perm:[2,3,0,1] row_mask:0xf bank_mask:0xf bound_ctrl:1
	s_nop 1
	v_add_f32_dpp v130, v130, v130 row_half_mirror row_mask:0xf bank_mask:0xf bound_ctrl:1
	s_nop 1
	v_add_f32_dpp v130, v130, v130 row_mirror row_mask:0xf bank_mask:0xf bound_ctrl:1
	s_nop 1
	v_mov_b32_dpp v131, v130 row_bcast:15 row_mask:0xa bank_mask:0xf
	v_add_f32_e32 v130, v130, v131
	v_mov_b32_e32 v131, 0
	s_nop 1
	v_mov_b32_dpp v131, v130 row_bcast:31 row_mask:0xc bank_mask:0xf
	v_add_f32_e32 v130, v130, v131
	s_nop 0
	v_readlane_b32 s6, v130, 63
	s_nop 1
	v_add_f32_e32 v130, s6, v179
	v_mul_f32_e32 v131, 0x4b800000, v130
	v_cmp_gt_f32_e32 vcc, s27, v130
	s_nop 1
	v_cndmask_b32_e32 v130, v130, v131, vcc
	v_rsq_f32_e32 v130, v130
	s_nop 0
	v_mul_f32_e32 v131, 0x45800000, v130
	v_cndmask_b32_e32 v130, v130, v131, vcc
	v_mul_f32_e32 v130, 0x3db504f3, v130
	v_pk_mul_f32 v[128:129], v[128:129], v[130:131] op_sel_hi:[1,0]
	global_store_dwordx2 v[116:117], v[128:129], off offset:1024 sc1
	s_and_saveexec_b64 s[6:7], s[4:5]
	s_cbranch_execz .LBB0_245
	v_lshl_add_u64 v[128:129], v[60:61], 0, v[108:109]
	global_store_dwordx2 v[128:129], v[138:139], off sc1
; DI float bflo(unsigned u) { return __uint_as_float(u << 16); }
; DI float bfhi(unsigned u) { return __uint_as_float(u & 0xffff0000u); }
; DI float siluf_(float x) { return x / (1.0f + __expf(-x)); }
; template <int G0>
; DI void qkv_run4_half(const Params& p, int row0, int lane) {
;     ...
;   for (int i = 0; i < 7; ++i) {
;     const int rr = (i >= 3 || t0 > 0) ? (row0 - 3 + i) : row0;
;     const bfr* rp = p.PB + (size_t)rr * EINP + 1536 + G0 * 128 + lane * 2;
; #pragma unroll
;     for (int g = 0; g < 4; ++g) u[g][i] = *(const unsigned*)(rp + g * 128);
;   }
; #pragma unroll
;   for (int j = 0; j < 4; ++j) {
;     const float* wp = p.sc_w + (size_t)j * 1536 + G0 * 128 + lane * 2;
; #pragma unroll
;     for (int g = 0; g < 4; ++g) w[g][j] = *(const float2*)(wp + g * 128);
;   }
;     ...
;     for (int g = 0; g < 4; ++g) {
;       const int grp = G0 + g;
;       const int ch = grp * 128 + lane * 2;
;       float a0 = 0.f, a1 = 0.f;
; #pragma unroll
;       for (int j = 0; j < 4; ++j) {
;         const int i = k + j;
;         const float m = (i >= 3) ? 1.f : hm;
;         a0 += w[g][j].x * (bflo(u[g][i]) * m);
;         a1 += w[g][j].y * (bfhi(u[g][i]) * m);
;       }
;       float y0 = siluf_(a0), y1 = siluf_(a1);
;       if (grp < 8) {
;         float ss = wave_sum(y0 * y0 + y1 * y1);
;         float inv = rsqrtf(ss + EPSF);
;         if (grp < 4) inv *= 0.08838834764831845f;
;         y0 *= inv; y1 *= inv;
;       }
;       float2 o = {y0, y1};
;       *(float2*)(p.QKV + (size_t)row * 1536 + ch) = o;
;       if (t0 == 2044 && k >= 1) {
;         float2 c = {bflo(u[g][k + 3]), bfhi(u[g][k + 3])};
;         *(float2*)(p.out + O_QKVP + ((size_t)b * 3 + (k - 1)) * 1536 + ch) = c;
;       }
.LBB0_245:
	s_or_b64 exec, exec, s[6:7]
	v_pk_fma_f32 v[118:119], v[118:119], v[126:127], 0 op_sel_hi:[1,1,0]
	v_lshlrev_b32_e32 v128, 16, v91
	v_pk_fma_f32 v[118:119], v[120:121], v[162:163], v[118:119]
	v_and_b32_e32 v129, 0xffff0000, v91
	v_pk_fma_f32 v[118:119], v[124:125], v[158:159], v[118:119]
	s_nop 0
	v_pk_fma_f32 v[118:119], v[122:123], v[128:129], v[118:119]
	s_nop 0
	v_mul_f32_e32 v91, 0xbfb8aa3b, v118
	v_exp_f32_e32 v120, v91
	v_mul_f32_e32 v91, 0xbfb8aa3b, v119
	v_exp_f32_e32 v121, v91
	s_nop 0
	v_pk_add_f32 v[120:121], v[120:121], 1.0 op_sel_hi:[1,0]
	s_nop 0
	v_div_scale_f32 v91, s[6:7], v121, v121, v119
	v_rcp_f32_e32 v122, v91
	s_nop 0
	v_fma_f32 v123, -v91, v122, 1.0
	v_fmac_f32_e32 v122, v123, v122
	v_div_scale_f32 v123, vcc, v119, v121, v119
	v_mul_f32_e32 v124, v123, v122
	v_fma_f32 v125, -v91, v124, v123
	v_fmac_f32_e32 v124, v125, v122
	v_fma_f32 v91, -v91, v124, v123
	v_div_scale_f32 v123, s[6:7], v120, v120, v118
	v_rcp_f32_e32 v125, v123
	v_div_fmas_f32 v91, v91, v122, v124
	v_div_fixup_f32 v119, v91, v121, v119
	v_fma_f32 v91, -v123, v125, 1.0
	v_fmac_f32_e32 v125, v91, v125
	v_div_scale_f32 v91, vcc, v118, v120, v118
	v_mul_f32_e32 v121, v91, v125
	v_fma_f32 v122, -v123, v121, v91
	v_fmac_f32_e32 v121, v122, v125
	v_fma_f32 v91, -v123, v121, v91
	v_div_fmas_f32 v91, v91, v125, v121
	v_div_fixup_f32 v118, v91, v120, v118
	v_pk_mul_f32 v[120:121], v[118:119], v[118:119]
	s_nop 0
	v_add_f32_e32 v91, v120, v121
	v_mov_b32_e32 v120, 0
	s_nop 0
	v_add_f32_dpp v91, v91, v91 quad_perm:[1,0,3,2] row_mask:0xf bank_mask:0xf bound_ctrl:1
	s_nop 1
	v_add_f32_dpp v91, v91, v91 quad_perm:[2,3,0,1] row_mask:0xf bank_mask:0xf bound_ctrl:1
	s_nop 1
	v_add_f32_dpp v91, v91, v91 row_half_mirror row_mask:0xf bank_mask:0xf bound_ctrl:1
	s_nop 1
	v_add_f32_dpp v91, v91, v91 row_mirror row_mask:0xf bank_mask:0xf bound_ctrl:1
	s_nop 1
	v_mov_b32_dpp v120, v91 row_bcast:15 row_mask:0xa bank_mask:0xf
	v_add_f32_e32 v91, v91, v120
	v_mov_b32_e32 v120, 0
	s_nop 1
	v_mov_b32_dpp v120, v91 row_bcast:31 row_mask:0xc bank_mask:0xf
	v_add_f32_e32 v91, v91, v120
	s_nop 0
	v_readlane_b32 s6, v91, 63
	s_nop 1
	v_add_f32_e32 v91, s6, v179
	v_mul_f32_e32 v120, 0x4b800000, v91
	v_cmp_gt_f32_e32 vcc, s27, v91
	s_nop 1
	v_cndmask_b32_e32 v91, v91, v120, vcc
	v_rsq_f32_e32 v91, v91
	s_nop 0
	v_mul_f32_e32 v120, 0x45800000, v91
	v_cndmask_b32_e32 v91, v91, v120, vcc
	v_mul_f32_e32 v120, 0x3db504f3, v91
	v_pk_mul_f32 v[118:119], v[118:119], v[120:121] op_sel_hi:[1,0]
	global_store_dwordx2 v[116:117], v[118:119], off offset:1536 sc1
	s_and_saveexec_b64 s[6:7], s[4:5]
	s_cbranch_execz .LBB0_247
	v_lshl_add_u64 v[118:119], v[62:63], 0, v[108:109]
	global_store_dwordx2 v[118:119], v[128:129], off sc1
.LBB0_247:
	s_or_b64 exec, exec, s[6:7]
	v_lshl_add_u64 v[118:119], v[102:103], 0, v[2:3]
	v_add_co_u32_e32 v120, vcc, 0x1000, v118
	v_lshl_add_u64 v[122:123], v[100:101], 0, v[2:3]
	s_nop 0
	v_addc_co_u32_e32 v121, vcc, 0, v119, vcc
	v_add_co_u32_e32 v124, vcc, 0x1000, v122
	v_lshl_add_u64 v[118:119], v[118:119], 0, s[18:19]
	s_nop 0
	v_addc_co_u32_e32 v125, vcc, 0, v123, vcc
	global_load_dword v134, v[120:121], off
	global_load_dword v135, v[124:125], off
	v_lshl_add_u64 v[120:121], v[98:99], 0, v[2:3]
	v_add_co_u32_e32 v124, vcc, 0x1000, v120
	v_lshl_add_u64 v[122:123], v[122:123], 0, s[18:19]
	s_nop 0
	v_addc_co_u32_e32 v125, vcc, 0, v121, vcc
	global_load_dword v136, v[124:125], off
	global_load_dword v147, v[122:123], off offset:256
	global_load_dword v146, v[118:119], off offset:256
	v_lshl_add_u64 v[124:125], v[96:97], 0, v[2:3]
	v_add_co_u32_e32 v126, vcc, 0x1000, v124
	v_lshl_add_u64 v[120:121], v[120:121], 0, s[18:19]
	s_nop 0
	v_addc_co_u32_e32 v127, vcc, 0, v125, vcc
	global_load_dword v137, v[126:127], off
	global_load_dword v150, v[120:121], off offset:256
	v_lshl_add_u64 v[124:125], v[124:125], 0, s[18:19]
	global_load_dword v151, v[124:125], off offset:256
	global_load_dword v152, v[118:119], off offset:512
	global_load_dword v153, v[122:123], off offset:512
	global_load_dword v154, v[120:121], off offset:512
	global_load_dword v155, v[124:125], off offset:512
	global_load_dword v156, v[122:123], off offset:768
	global_load_dword v157, v[118:119], off offset:768
	global_load_dwordx2 v[140:141], v[6:7], off offset:2560
	global_load_dwordx2 v[142:143], v[34:35], off offset:512
	global_load_dwordx2 v[144:145], v[36:37], off offset:512
	global_load_dwordx2 v[138:139], v[38:39], off offset:512
	global_load_dword v199, v[124:125], off offset:768
	global_load_dword v204, v[120:121], off offset:768
	v_lshl_add_u64 v[118:119], v[106:107], 0, v[2:3]
	v_lshl_add_u64 v[128:129], v[118:119], 0, s[18:19]
	v_add_co_u32_e32 v118, vcc, 0x1000, v118
	v_lshl_add_u64 v[122:123], v[104:105], 0, v[2:3]
	s_nop 0
	v_addc_co_u32_e32 v119, vcc, 0, v119, vcc
	v_add_co_u32_e32 v120, vcc, 0x1000, v122
	v_lshl_add_u64 v[126:127], v[92:93], 0, v[2:3]
	s_nop 0
	v_addc_co_u32_e32 v121, vcc, 0, v123, vcc
	v_lshl_add_u64 v[130:131], v[122:123], 0, s[18:19]
	v_lshl_add_u64 v[132:133], v[126:127], 0, s[18:19]
	v_add_co_u32_e32 v122, vcc, 0x1000, v126
	global_load_dword v198, v[128:129], off offset:256
	global_load_dword v197, v[128:129], off offset:512
	global_load_dword v208, v[118:119], off
	global_load_dword v193, v[130:131], off offset:256
	global_load_dword v192, v[130:131], off offset:512
	global_load_dword v194, v[120:121], off
	global_load_dword v191, v[130:131], off offset:768
	global_load_dword v195, v[128:129], off offset:768
	v_addc_co_u32_e32 v123, vcc, 0, v127, vcc
	global_load_dword v189, v[132:133], off offset:256
	global_load_dword v188, v[132:133], off offset:512
	global_load_dword v190, v[122:123], off
	global_load_dword v187, v[132:133], off offset:768
	v_mov_b32_e32 v91, v90
	s_waitcnt vmcnt(31)
; DI float bflo(unsigned u) { return __uint_as_float(u << 16); }
; DI float bfhi(unsigned u) { return __uint_as_float(u & 0xffff0000u); }
; DI float siluf_(float x) { return x / (1.0f + __expf(-x)); }
; template <int G0>
; DI void qkv_run4_half(const Params& p, int row0, int lane) {
;     ...
;   for (int k = 0; k < 4; ++k) {
;     const int row = row0 + k;
; #pragma unroll
;     for (int g = 0; g < 4; ++g) {
;       const int grp = G0 + g;
;       const int ch = grp * 128 + lane * 2;
;       float a0 = 0.f, a1 = 0.f;
; #pragma unroll
;       for (int j = 0; j < 4; ++j) {
;         const int i = k + j;
;         const float m = (i >= 3) ? 1.f : hm;
;         a0 += w[g][j].x * (bflo(u[g][i]) * m);
;         a1 += w[g][j].y * (bfhi(u[g][i]) * m);
;       }
;       float y0 = siluf_(a0), y1 = siluf_(a1);
;       if (grp < 8) {
;         float ss = wave_sum(y0 * y0 + y1 * y1);
;         float inv = rsqrtf(ss + EPSF);
;         if (grp < 4) inv *= 0.08838834764831845f;
;         y0 *= inv; y1 *= inv;
;       }
	v_lshlrev_b32_e32 v170, 16, v134
	v_and_b32_e32 v171, 0xffff0000, v134
	s_waitcnt vmcnt(30)
	v_lshlrev_b32_e32 v176, 16, v135
	v_and_b32_e32 v177, 0xffff0000, v135
	v_pk_mul_f32 v[170:171], v[90:91], v[170:171]
	v_pk_mul_f32 v[176:177], v[90:91], v[176:177]
	s_waitcnt vmcnt(29)
	v_lshlrev_b32_e32 v118, 16, v136
	v_and_b32_e32 v119, 0xffff0000, v136
	s_waitcnt vmcnt(27)
	v_lshlrev_b32_e32 v126, 16, v146
	v_and_b32_e32 v127, 0xffff0000, v146
	v_pk_mul_f32 v[166:167], v[90:91], v[118:119]
	v_lshlrev_b32_e32 v118, 16, v147
	v_and_b32_e32 v119, 0xffff0000, v147
	v_pk_mul_f32 v[126:127], v[90:91], v[126:127]
	v_pk_mul_f32 v[168:169], v[90:91], v[118:119]
	s_waitcnt vmcnt(26)
	v_lshlrev_b32_e32 v148, 16, v137
	v_and_b32_e32 v149, 0xffff0000, v137
	global_load_dwordx2 v[132:133], v[6:7], off offset:3072
	global_load_dwordx2 v[134:135], v[34:35], off offset:1024
	global_load_dwordx2 v[136:137], v[36:37], off offset:1024
	global_load_dwordx2 v[128:129], v[38:39], off offset:1024
	s_waitcnt vmcnt(29)
	v_lshlrev_b32_e32 v118, 16, v150
	v_and_b32_e32 v119, 0xffff0000, v150
	s_waitcnt vmcnt(21)
	v_pk_fma_f32 v[126:127], v[126:127], v[140:141], 0 op_sel_hi:[1,1,0]
	v_pk_mul_f32 v[164:165], v[90:91], v[118:119]
	s_waitcnt vmcnt(20)
	v_pk_fma_f32 v[126:127], v[168:169], v[142:143], v[126:127]
	v_lshlrev_b32_e32 v146, 16, v151
	v_and_b32_e32 v147, 0xffff0000, v151
	s_waitcnt vmcnt(19)
	v_pk_fma_f32 v[126:127], v[164:165], v[144:145], v[126:127]
	v_lshlrev_b32_e32 v118, 16, v153
	v_and_b32_e32 v119, 0xffff0000, v153
	s_waitcnt vmcnt(18)
	v_pk_fma_f32 v[202:203], v[138:139], v[146:147], v[126:127]
	v_pk_mul_f32 v[174:175], v[90:91], v[118:119]
	v_lshlrev_b32_e32 v118, 16, v154
	v_and_b32_e32 v119, 0xffff0000, v154
	v_mul_f32_e32 v126, 0xbfb8aa3b, v202
	v_mul_f32_e32 v127, 0xbfb8aa3b, v203
	v_lshlrev_b32_e32 v158, 16, v152
	v_and_b32_e32 v159, 0xffff0000, v152
	v_pk_mul_f32 v[162:163], v[90:91], v[118:119]
	v_lshlrev_b32_e32 v130, 16, v155
	v_and_b32_e32 v131, 0xffff0000, v155
	v_lshlrev_b32_e32 v200, 16, v157
	v_and_b32_e32 v201, 0xffff0000, v157
	v_lshlrev_b32_e32 v160, 16, v156
	v_and_b32_e32 v161, 0xffff0000, v156
	global_load_dwordx2 v[118:119], v[6:7], off offset:3584
	global_load_dwordx2 v[150:151], v[6:7], off offset:2048
	global_load_dwordx2 v[120:121], v[34:35], off offset:1536
	global_load_dwordx2 v[152:153], v[34:35], off
	global_load_dwordx2 v[124:125], v[36:37], off offset:1536
	global_load_dwordx2 v[156:157], v[36:37], off
	global_load_dwordx2 v[122:123], v[38:39], off offset:1536
	global_load_dwordx2 v[154:155], v[38:39], off
	v_exp_f32_e32 v126, v126
	v_exp_f32_e32 v127, v127
	v_pk_mul_f32 v[172:173], v[90:91], v[160:161]
	s_waitcnt vmcnt(24)
	v_lshlrev_b32_e32 v160, 16, v204
	v_and_b32_e32 v161, 0xffff0000, v204
	v_pk_add_f32 v[204:205], v[126:127], 1.0 op_sel_hi:[1,0]
	v_lshlrev_b32_e32 v126, 16, v199
	v_div_scale_f32 v206, s[6:7], v205, v205, v203
	v_rcp_f32_e32 v207, v206
	v_and_b32_e32 v127, 0xffff0000, v199
	v_pk_mul_f32 v[158:159], v[90:91], v[158:159]
	v_pk_mul_f32 v[200:201], v[90:91], v[200:201]
	v_fma_f32 v199, -v206, v207, 1.0
	v_fmac_f32_e32 v207, v199, v207
	v_div_scale_f32 v199, vcc, v203, v205, v203
	v_mul_f32_e32 v209, v199, v207
	v_fma_f32 v210, -v206, v209, v199
	v_fmac_f32_e32 v209, v210, v207
	v_fma_f32 v199, -v206, v209, v199
	v_div_scale_f32 v206, s[6:7], v204, v204, v202
	v_rcp_f32_e32 v210, v206
	v_div_fmas_f32 v199, v199, v207, v209
	v_div_fixup_f32 v203, v199, v205, v203
	v_pk_mul_f32 v[160:161], v[90:91], v[160:161]
	v_fma_f32 v199, -v206, v210, 1.0
	v_fmac_f32_e32 v210, v199, v210
	v_div_scale_f32 v199, vcc, v202, v204, v202
	v_mul_f32_e32 v205, v199, v210
	v_fma_f32 v207, -v206, v205, v199
	v_fmac_f32_e32 v205, v207, v210
	v_fma_f32 v199, -v206, v205, v199
	v_div_fmas_f32 v199, v199, v210, v205
	v_div_fixup_f32 v202, v199, v204, v202
	v_pk_mul_f32 v[204:205], v[202:203], v[202:203]
	s_waitcnt vmcnt(11)
	v_pk_fma_f32 v[158:159], v[158:159], v[132:133], 0 op_sel_hi:[1,1,0]
	v_add_f32_e32 v199, v204, v205
	v_mov_b32_e32 v204, v3
	s_waitcnt vmcnt(10)
	v_pk_fma_f32 v[158:159], v[174:175], v[134:135], v[158:159]
	v_add_f32_dpp v199, v199, v199 quad_perm:[1,0,3,2] row_mask:0xf bank_mask:0xf bound_ctrl:1
	s_waitcnt vmcnt(9)
	v_pk_fma_f32 v[158:159], v[162:163], v[136:137], v[158:159]
	s_waitcnt vmcnt(7)
	v_pk_fma_f32 v[200:201], v[200:201], v[118:119], 0 op_sel_hi:[1,1,0]
	v_add_f32_dpp v199, v199, v199 quad_perm:[2,3,0,1] row_mask:0xf bank_mask:0xf bound_ctrl:1
	s_waitcnt vmcnt(5)
	v_pk_fma_f32 v[200:201], v[172:173], v[120:121], v[200:201]
	v_pk_fma_f32 v[170:171], v[170:171], v[150:151], 0 op_sel_hi:[1,1,0]
	v_add_f32_dpp v199, v199, v199 row_half_mirror row_mask:0xf bank_mask:0xf bound_ctrl:1
	s_waitcnt vmcnt(3)
	v_pk_fma_f32 v[200:201], v[160:161], v[124:125], v[200:201]
	v_pk_fma_f32 v[170:171], v[176:177], v[152:153], v[170:171]
	v_add_f32_dpp v199, v199, v199 row_mirror row_mask:0xf bank_mask:0xf bound_ctrl:1
	s_waitcnt vmcnt(1)
	v_pk_fma_f32 v[200:201], v[122:123], v[126:127], v[200:201]
	v_pk_fma_f32 v[170:171], v[166:167], v[156:157], v[170:171]
	v_mov_b32_dpp v204, v199 row_bcast:15 row_mask:0xa bank_mask:0xf
	v_add_f32_e32 v199, v199, v204
	v_mov_b32_e32 v204, v3
	s_waitcnt vmcnt(0)
; DI float bflo(unsigned u) { return __uint_as_float(u << 16); }
; DI float bfhi(unsigned u) { return __uint_as_float(u & 0xffff0000u); }
; DI float siluf_(float x) { return x / (1.0f + __expf(-x)); }
; template <int G0>
; DI void qkv_run4_half(const Params& p, int row0, int lane) {
;     ...
;     for (int g = 0; g < 4; ++g) {
;       const int grp = G0 + g;
;       const int ch = grp * 128 + lane * 2;
;       float a0 = 0.f, a1 = 0.f;
; #pragma unroll
;       for (int j = 0; j < 4; ++j) {
;         const int i = k + j;
;         const float m = (i >= 3) ? 1.f : hm;
;         a0 += w[g][j].x * (bflo(u[g][i]) * m);
;         a1 += w[g][j].y * (bfhi(u[g][i]) * m);
;       }
;       float y0 = siluf_(a0), y1 = siluf_(a1);
;       if (grp < 8) {
;         float ss = wave_sum(y0 * y0 + y1 * y1);
;         float inv = rsqrtf(ss + EPSF);
;         if (grp < 4) inv *= 0.08838834764831845f;
;         y0 *= inv; y1 *= inv;
;       }
;       float2 o = {y0, y1};
;       *(float2*)(p.QKV + (size_t)row * 1536 + ch) = o;
	v_pk_fma_f32 v[170:171], v[154:155], v[148:149], v[170:171]
	v_pk_fma_f32 v[176:177], v[176:177], v[150:151], 0 op_sel_hi:[1,1,0]
	v_mov_b32_dpp v204, v199 row_bcast:31 row_mask:0xc bank_mask:0xf
	v_add_f32_e32 v199, v199, v204
	v_pk_fma_f32 v[176:177], v[166:167], v[152:153], v[176:177]
	v_readlane_b32 s6, v199, 63
	v_pk_fma_f32 v[176:177], v[156:157], v[148:149], v[176:177]
	s_nop 0
	v_add_f32_e32 v199, s6, v179
	v_mul_f32_e32 v204, 0x4b800000, v199
	v_cmp_gt_f32_e32 vcc, s27, v199
	s_nop 1
	v_cndmask_b32_e32 v199, v199, v204, vcc
	v_pk_fma_f32 v[204:205], v[128:129], v[130:131], v[158:159]
	v_rsq_f32_e32 v199, v199
	v_mul_f32_e32 v158, 0xbfb8aa3b, v204
	v_exp_f32_e32 v206, v158
	v_mul_f32_e32 v158, 0xbfb8aa3b, v205
	v_exp_f32_e32 v207, v158
	v_lshlrev_b32_e32 v158, 16, v208
	v_and_b32_e32 v159, 0xffff0000, v208
	v_mul_f32_e32 v208, 0x45800000, v199
	v_pk_add_f32 v[206:207], v[206:207], 1.0 op_sel_hi:[1,0]
	v_cndmask_b32_e32 v208, v199, v208, vcc
	v_div_scale_f32 v209, s[6:7], v207, v207, v205
	v_rcp_f32_e32 v210, v209
	v_pk_mul_f32 v[202:203], v[202:203], v[208:209] op_sel_hi:[1,0]
	global_store_dwordx2 v[110:111], v[202:203], off offset:2560 sc1
	v_div_scale_f32 v208, s[6:7], v206, v206, v204
	v_fma_f32 v199, -v209, v210, 1.0
	v_fmac_f32_e32 v210, v199, v210
	v_div_scale_f32 v199, vcc, v205, v207, v205
	v_mul_f32_e32 v202, v199, v210
	v_fma_f32 v203, -v209, v202, v199
	v_fmac_f32_e32 v202, v203, v210
	v_fma_f32 v199, -v209, v202, v199
	v_rcp_f32_e32 v209, v208
	v_div_fmas_f32 v199, v199, v210, v202
	v_div_fixup_f32 v203, v199, v207, v205
	v_pk_fma_f32 v[176:177], v[154:155], v[158:159], v[176:177]
	v_fma_f32 v199, -v208, v209, 1.0
	v_fmac_f32_e32 v209, v199, v209
	v_div_scale_f32 v199, vcc, v204, v206, v204
	v_mul_f32_e32 v202, v199, v209
	v_fma_f32 v205, -v208, v202, v199
	v_fmac_f32_e32 v202, v205, v209
	v_fma_f32 v199, -v208, v202, v199
	v_div_fmas_f32 v199, v199, v209, v202
	v_div_fixup_f32 v202, v199, v206, v204
	v_pk_mul_f32 v[204:205], v[202:203], v[202:203]
	s_nop 0
	v_add_f32_e32 v199, v204, v205
	v_mov_b32_e32 v204, v3
	v_mul_f32_e32 v205, 0xbfb8aa3b, v201
	v_add_f32_dpp v199, v199, v199 quad_perm:[1,0,3,2] row_mask:0xf bank_mask:0xf bound_ctrl:1
	v_exp_f32_e32 v205, v205
	s_nop 0
	v_add_f32_dpp v199, v199, v199 quad_perm:[2,3,0,1] row_mask:0xf bank_mask:0xf bound_ctrl:1
	s_nop 1
	v_add_f32_dpp v199, v199, v199 row_half_mirror row_mask:0xf bank_mask:0xf bound_ctrl:1
	s_nop 1
	v_add_f32_dpp v199, v199, v199 row_mirror row_mask:0xf bank_mask:0xf bound_ctrl:1
	s_nop 1
	v_mov_b32_dpp v204, v199 row_bcast:15 row_mask:0xa bank_mask:0xf
	v_add_f32_e32 v199, v199, v204
	v_mov_b32_e32 v204, v3
	s_nop 1
	v_mov_b32_dpp v204, v199 row_bcast:31 row_mask:0xc bank_mask:0xf
	v_add_f32_e32 v199, v199, v204
	v_mul_f32_e32 v204, 0xbfb8aa3b, v200
	v_exp_f32_e32 v204, v204
	v_readlane_b32 s6, v199, 63
	v_pk_add_f32 v[204:205], v[204:205], 1.0 op_sel_hi:[1,0]
	s_nop 0
	v_add_f32_e32 v199, s6, v179
	v_mul_f32_e32 v206, 0x4b800000, v199
	v_cmp_gt_f32_e32 vcc, s27, v199
	v_div_scale_f32 v207, s[6:7], v205, v205, v201
	s_nop 0
	v_cndmask_b32_e32 v199, v199, v206, vcc
	v_rsq_f32_e32 v199, v199
	v_rcp_f32_e32 v208, v207
	v_mul_f32_e32 v206, 0x45800000, v199
	v_cndmask_b32_e32 v206, v199, v206, vcc
	v_fma_f32 v199, -v207, v208, 1.0
	v_fmac_f32_e32 v208, v199, v208
	v_div_scale_f32 v199, vcc, v201, v205, v201
	v_pk_mul_f32 v[202:203], v[202:203], v[206:207] op_sel_hi:[1,0]
	v_mul_f32_e32 v206, v199, v208
	v_fma_f32 v209, -v207, v206, v199
	v_fmac_f32_e32 v206, v209, v208
	v_fma_f32 v199, -v207, v206, v199
	v_div_scale_f32 v207, s[6:7], v204, v204, v200
	v_rcp_f32_e32 v209, v207
	v_div_fmas_f32 v199, v199, v208, v206
	v_div_fixup_f32 v201, v199, v205, v201
	global_store_dwordx2 v[110:111], v[202:203], off offset:3072 sc1
	v_fma_f32 v199, -v207, v209, 1.0
	v_fmac_f32_e32 v209, v199, v209
	v_div_scale_f32 v199, vcc, v200, v204, v200
	v_mul_f32_e32 v205, v199, v209
	v_fma_f32 v206, -v207, v205, v199
	v_fmac_f32_e32 v205, v206, v209
	v_fma_f32 v199, -v207, v205, v199
	v_div_fmas_f32 v199, v199, v209, v205
	v_div_fixup_f32 v200, v199, v204, v200
	v_pk_mul_f32 v[204:205], v[200:201], v[200:201]
	s_nop 0
	v_add_f32_e32 v199, v204, v205
	v_mov_b32_e32 v204, v3
	v_mul_f32_e32 v205, 0xbfb8aa3b, v171
	v_add_f32_dpp v199, v199, v199 quad_perm:[1,0,3,2] row_mask:0xf bank_mask:0xf bound_ctrl:1
	v_exp_f32_e32 v205, v205
	s_nop 0
	v_add_f32_dpp v199, v199, v199 quad_perm:[2,3,0,1] row_mask:0xf bank_mask:0xf bound_ctrl:1
	s_nop 1
	v_add_f32_dpp v199, v199, v199 row_half_mirror row_mask:0xf bank_mask:0xf bound_ctrl:1
	s_nop 1
	v_add_f32_dpp v199, v199, v199 row_mirror row_mask:0xf bank_mask:0xf bound_ctrl:1
	s_nop 1
	v_mov_b32_dpp v204, v199 row_bcast:15 row_mask:0xa bank_mask:0xf
	v_add_f32_e32 v199, v199, v204
	v_mov_b32_e32 v204, v3
	s_nop 1
	v_mov_b32_dpp v204, v199 row_bcast:31 row_mask:0xc bank_mask:0xf
	v_add_f32_e32 v199, v199, v204
	v_mul_f32_e32 v204, 0xbfb8aa3b, v170
	v_exp_f32_e32 v204, v204
	v_readlane_b32 s6, v199, 63
	v_pk_add_f32 v[204:205], v[204:205], 1.0 op_sel_hi:[1,0]
	s_nop 0
	v_add_f32_e32 v199, s6, v179
	v_mul_f32_e32 v206, 0x4b800000, v199
	v_cmp_gt_f32_e32 vcc, s27, v199
	s_nop 1
	v_cndmask_b32_e32 v199, v199, v206, vcc
	v_rsq_f32_e32 v199, v199
	v_div_scale_f32 v206, s[6:7], v205, v205, v171
	v_rcp_f32_e32 v207, v206
	v_mul_f32_e32 v202, 0x45800000, v199
	v_cndmask_b32_e32 v202, v199, v202, vcc
	v_fma_f32 v199, -v206, v207, 1.0
	v_fmac_f32_e32 v207, v199, v207
	v_div_scale_f32 v199, vcc, v171, v205, v171
	v_mul_f32_e32 v203, v199, v207
	v_fma_f32 v208, -v206, v203, v199
	v_fmac_f32_e32 v203, v208, v207
	v_fma_f32 v199, -v206, v203, v199
; DI float bflo(unsigned u) { return __uint_as_float(u << 16); }
; DI float bfhi(unsigned u) { return __uint_as_float(u & 0xffff0000u); }
; DI float siluf_(float x) { return x / (1.0f + __expf(-x)); }
; template <int G0>
; DI void qkv_run4_half(const Params& p, int row0, int lane) {
;     ...
;     for (int g = 0; g < 4; ++g) {
;       const int grp = G0 + g;
;       const int ch = grp * 128 + lane * 2;
;       float a0 = 0.f, a1 = 0.f;
; #pragma unroll
;       for (int j = 0; j < 4; ++j) {
;         const int i = k + j;
;         const float m = (i >= 3) ? 1.f : hm;
;         a0 += w[g][j].x * (bflo(u[g][i]) * m);
;         a1 += w[g][j].y * (bfhi(u[g][i]) * m);
;       }
;       float y0 = siluf_(a0), y1 = siluf_(a1);
;       if (grp < 8) {
;         float ss = wave_sum(y0 * y0 + y1 * y1);
;         float inv = rsqrtf(ss + EPSF);
;         if (grp < 4) inv *= 0.08838834764831845f;
;         y0 *= inv; y1 *= inv;
;       }
;       float2 o = {y0, y1};
;       *(float2*)(p.QKV + (size_t)row * 1536 + ch) = o;
;       if (t0 == 2044 && k >= 1) {
;         float2 c = {bflo(u[g][k + 3]), bfhi(u[g][k + 3])};
;         *(float2*)(p.out + O_QKVP + ((size_t)b * 3 + (k - 1)) * 1536 + ch) = c;
;       }
	v_div_scale_f32 v206, s[6:7], v204, v204, v170
	v_rcp_f32_e32 v208, v206
	v_div_fmas_f32 v199, v199, v207, v203
	v_div_fixup_f32 v171, v199, v205, v171
	v_fma_f32 v199, -v206, v208, 1.0
	v_fmac_f32_e32 v208, v199, v208
	v_div_scale_f32 v199, vcc, v170, v204, v170
	v_mul_f32_e32 v203, v199, v208
	v_fma_f32 v205, -v206, v203, v199
	v_fmac_f32_e32 v203, v205, v208
	v_fma_f32 v199, -v206, v203, v199
	v_div_fmas_f32 v199, v199, v208, v203
	v_div_fixup_f32 v170, v199, v204, v170
	v_pk_mul_f32 v[204:205], v[170:171], v[170:171]
	v_mov_b32_e32 v203, v3
	v_add_f32_e32 v199, v204, v205
	v_mul_f32_e32 v204, 0xbfb8aa3b, v176
	v_mul_f32_e32 v205, 0xbfb8aa3b, v177
	v_add_f32_dpp v199, v199, v199 quad_perm:[1,0,3,2] row_mask:0xf bank_mask:0xf bound_ctrl:1
	v_exp_f32_e32 v204, v204
	v_exp_f32_e32 v205, v205
	v_add_f32_dpp v199, v199, v199 quad_perm:[2,3,0,1] row_mask:0xf bank_mask:0xf bound_ctrl:1
	v_pk_add_f32 v[204:205], v[204:205], 1.0 op_sel_hi:[1,0]
	s_nop 0
	v_add_f32_dpp v199, v199, v199 row_half_mirror row_mask:0xf bank_mask:0xf bound_ctrl:1
	s_nop 1
	v_add_f32_dpp v199, v199, v199 row_mirror row_mask:0xf bank_mask:0xf bound_ctrl:1
	s_nop 1
	v_mov_b32_dpp v203, v199 row_bcast:15 row_mask:0xa bank_mask:0xf
	v_add_f32_e32 v199, v199, v203
	v_mov_b32_e32 v203, v3
	s_nop 1
	v_mov_b32_dpp v203, v199 row_bcast:31 row_mask:0xc bank_mask:0xf
	v_add_f32_e32 v199, v199, v203
	s_nop 0
	v_readlane_b32 s6, v199, 63
	s_nop 1
	v_add_f32_e32 v199, s6, v179
	v_mul_f32_e32 v203, 0x4b800000, v199
	v_cmp_gt_f32_e64 s[6:7], s27, v199
	s_nop 1
	v_cndmask_b32_e64 v199, v199, v203, s[6:7]
	v_div_scale_f32 v203, s[38:39], v205, v205, v177
	v_rcp_f32_e32 v206, v203
	v_pk_mul_f32 v[200:201], v[200:201], v[202:203] op_sel_hi:[1,0]
	global_store_dwordx2 v[110:111], v[200:201], off offset:3584 sc1
	v_rsq_f32_e32 v199, v199
	v_fma_f32 v200, -v203, v206, 1.0
	v_fmac_f32_e32 v206, v200, v206
	v_div_scale_f32 v200, vcc, v177, v205, v177
	v_mul_f32_e32 v201, v200, v206
	v_fma_f32 v207, -v203, v201, v200
	v_fmac_f32_e32 v201, v207, v206
	v_fma_f32 v200, -v203, v201, v200
	v_div_scale_f32 v203, s[38:39], v204, v204, v176
	v_rcp_f32_e32 v207, v203
	v_div_fmas_f32 v200, v200, v206, v201
	v_div_fixup_f32 v177, v200, v205, v177
	v_mul_f32_e32 v202, 0x45800000, v199
	v_fma_f32 v200, -v203, v207, 1.0
	v_fmac_f32_e32 v207, v200, v207
	v_div_scale_f32 v200, vcc, v176, v204, v176
	v_mul_f32_e32 v201, v200, v207
	v_fma_f32 v205, -v203, v201, v200
	v_fmac_f32_e32 v201, v205, v207
	v_fma_f32 v200, -v203, v201, v200
	v_div_fmas_f32 v200, v200, v207, v201
	v_div_fixup_f32 v176, v200, v204, v176
	v_pk_mul_f32 v[200:201], v[176:177], v[176:177]
	s_nop 0
	v_add_f32_e32 v200, v200, v201
	v_mov_b32_e32 v201, v3
	s_nop 0
	v_add_f32_dpp v200, v200, v200 quad_perm:[1,0,3,2] row_mask:0xf bank_mask:0xf bound_ctrl:1
	s_nop 1
	v_add_f32_dpp v200, v200, v200 quad_perm:[2,3,0,1] row_mask:0xf bank_mask:0xf bound_ctrl:1
	s_nop 1
	v_add_f32_dpp v200, v200, v200 row_half_mirror row_mask:0xf bank_mask:0xf bound_ctrl:1
	s_nop 1
	v_add_f32_dpp v200, v200, v200 row_mirror row_mask:0xf bank_mask:0xf bound_ctrl:1
	s_nop 1
	v_mov_b32_dpp v201, v200 row_bcast:15 row_mask:0xa bank_mask:0xf
	v_add_f32_e32 v200, v200, v201
	v_mov_b32_e32 v201, v3
	s_nop 1
	v_mov_b32_dpp v201, v200 row_bcast:31 row_mask:0xc bank_mask:0xf
	v_add_f32_e32 v200, v200, v201
	s_nop 0
	v_readlane_b32 s37, v200, 63
	s_nop 1
	v_add_f32_e32 v200, s37, v179
	v_mul_f32_e32 v201, 0x4b800000, v200
	v_cmp_gt_f32_e32 vcc, s27, v200
	s_nop 1
	v_cndmask_b32_e32 v200, v200, v201, vcc
	v_rsq_f32_e32 v201, v200
	v_cndmask_b32_e64 v200, v199, v202, s[6:7]
	v_pk_mul_f32 v[170:171], v[170:171], v[200:201] op_sel_hi:[1,0]
	global_store_dwordx2 v[110:111], v[170:171], off offset:2048 sc1
	v_mul_f32_e32 v110, 0x45800000, v201
	v_cndmask_b32_e32 v110, v201, v110, vcc
	v_pk_mul_f32 v[110:111], v[176:177], v[110:111] op_sel_hi:[1,0]
	global_store_dwordx2 v[112:113], v[110:111], off offset:2048 sc1
	s_and_saveexec_b64 s[6:7], s[4:5]
	s_cbranch_execz .LBB0_249
	v_lshl_add_u64 v[110:111], v[64:65], 0, v[88:89]
	global_store_dwordx2 v[110:111], v[158:159], off sc1
.LBB0_249:
	s_or_b64 exec, exec, s[6:7]
	v_pk_fma_f32 v[110:111], v[168:169], v[140:141], 0 op_sel_hi:[1,1,0]
	v_lshlrev_b32_e32 v170, 16, v198
	v_pk_fma_f32 v[110:111], v[164:165], v[142:143], v[110:111]
	v_and_b32_e32 v171, 0xffff0000, v198
	v_pk_fma_f32 v[110:111], v[144:145], v[146:147], v[110:111]
	s_nop 0
	v_pk_fma_f32 v[110:111], v[138:139], v[170:171], v[110:111]
	s_nop 0
	v_mul_f32_e32 v168, 0xbfb8aa3b, v110
	v_mul_f32_e32 v169, 0xbfb8aa3b, v111
	v_exp_f32_e32 v168, v168
	v_exp_f32_e32 v169, v169
	s_nop 0
	v_pk_add_f32 v[168:169], v[168:169], 1.0 op_sel_hi:[1,0]
	s_nop 0
	v_div_scale_f32 v176, s[6:7], v169, v169, v111
	v_rcp_f32_e32 v177, v176
	s_nop 0
	v_fma_f32 v198, -v176, v177, 1.0
	v_fmac_f32_e32 v177, v198, v177
	v_div_scale_f32 v198, vcc, v111, v169, v111
	v_mul_f32_e32 v199, v198, v177
	v_fma_f32 v200, -v176, v199, v198
	v_fmac_f32_e32 v199, v200, v177
	v_fma_f32 v176, -v176, v199, v198
	v_div_scale_f32 v198, s[6:7], v168, v168, v110
	v_rcp_f32_e32 v200, v198
	v_div_fmas_f32 v176, v176, v177, v199
	v_div_fixup_f32 v111, v176, v169, v111
	v_fma_f32 v169, -v198, v200, 1.0
	v_fmac_f32_e32 v200, v169, v200
	v_div_scale_f32 v169, vcc, v110, v168, v110
	v_mul_f32_e32 v176, v169, v200
	v_fma_f32 v177, -v198, v176, v169
	v_fmac_f32_e32 v176, v177, v200
	v_fma_f32 v169, -v198, v176, v169
	v_div_fmas_f32 v169, v169, v200, v176
	v_div_fixup_f32 v110, v169, v168, v110
	v_pk_mul_f32 v[168:169], v[110:111], v[110:111]
	s_nop 0
	v_add_f32_e32 v168, v168, v169
	v_mov_b32_e32 v169, v3
	s_nop 0
	v_add_f32_dpp v168, v168, v168 quad_perm:[1,0,3,2] row_mask:0xf bank_mask:0xf bound_ctrl:1
	s_nop 1
	v_add_f32_dpp v168, v168, v168 quad_perm:[2,3,0,1] row_mask:0xf bank_mask:0xf bound_ctrl:1
	s_nop 1
	v_add_f32_dpp v168, v168, v168 row_half_mirror row_mask:0xf bank_mask:0xf bound_ctrl:1
	s_nop 1
	v_add_f32_dpp v168, v168, v168 row_mirror row_mask:0xf bank_mask:0xf bound_ctrl:1
	s_nop 1
	v_mov_b32_dpp v169, v168 row_bcast:15 row_mask:0xa bank_mask:0xf
	v_add_f32_e32 v168, v168, v169
	v_mov_b32_e32 v169, v3
	s_nop 1
	v_mov_b32_dpp v169, v168 row_bcast:31 row_mask:0xc bank_mask:0xf
	v_add_f32_e32 v168, v168, v169
	s_nop 0
	v_readlane_b32 s6, v168, 63
	s_nop 1
	v_add_f32_e32 v168, s6, v179
	v_mul_f32_e32 v169, 0x4b800000, v168
	v_cmp_gt_f32_e32 vcc, s27, v168
	s_nop 1
	v_cndmask_b32_e32 v168, v168, v169, vcc
	v_rsq_f32_e32 v168, v168
	s_nop 0
	v_mul_f32_e32 v169, 0x45800000, v168
	v_cndmask_b32_e32 v168, v168, v169, vcc
	v_pk_mul_f32 v[110:111], v[110:111], v[168:169] op_sel_hi:[1,0]
	global_store_dwordx2 v[112:113], v[110:111], off offset:2560 sc1
	s_and_saveexec_b64 s[6:7], s[4:5]
	s_cbranch_execz .LBB0_251
	v_lshl_add_u64 v[110:111], v[66:67], 0, v[88:89]
	global_store_dwordx2 v[110:111], v[170:171], off sc1
; DI float bflo(unsigned u) { return __uint_as_float(u << 16); }
; DI float bfhi(unsigned u) { return __uint_as_float(u & 0xffff0000u); }
; DI float siluf_(float x) { return x / (1.0f + __expf(-x)); }
; template <int G0>
; DI void qkv_run4_half(const Params& p, int row0, int lane) {
;     ...
;     for (int g = 0; g < 4; ++g) {
;       const int grp = G0 + g;
;       const int ch = grp * 128 + lane * 2;
;       float a0 = 0.f, a1 = 0.f;
; #pragma unroll
;       for (int j = 0; j < 4; ++j) {
;         const int i = k + j;
;         const float m = (i >= 3) ? 1.f : hm;
;         a0 += w[g][j].x * (bflo(u[g][i]) * m);
;         a1 += w[g][j].y * (bfhi(u[g][i]) * m);
;       }
;       float y0 = siluf_(a0), y1 = siluf_(a1);
;       if (grp < 8) {
;         float ss = wave_sum(y0 * y0 + y1 * y1);
;         float inv = rsqrtf(ss + EPSF);
;         if (grp < 4) inv *= 0.08838834764831845f;
;         y0 *= inv; y1 *= inv;
;       }
;       float2 o = {y0, y1};
;       *(float2*)(p.QKV + (size_t)row * 1536 + ch) = o;
;       if (t0 == 2044 && k >= 1) {
;         float2 c = {bflo(u[g][k + 3]), bfhi(u[g][k + 3])};
;         *(float2*)(p.out + O_QKVP + ((size_t)b * 3 + (k - 1)) * 1536 + ch) = c;
;       }
.LBB0_251:
	s_or_b64 exec, exec, s[6:7]
	v_pk_fma_f32 v[110:111], v[174:175], v[132:133], 0 op_sel_hi:[1,1,0]
	v_lshlrev_b32_e32 v168, 16, v197
	v_pk_fma_f32 v[110:111], v[162:163], v[134:135], v[110:111]
	v_and_b32_e32 v169, 0xffff0000, v197
	v_pk_fma_f32 v[110:111], v[136:137], v[130:131], v[110:111]
	s_nop 0
	v_pk_fma_f32 v[110:111], v[128:129], v[168:169], v[110:111]
	s_nop 0
	v_mul_f32_e32 v174, 0xbfb8aa3b, v110
	v_mul_f32_e32 v175, 0xbfb8aa3b, v111
	v_exp_f32_e32 v174, v174
	v_exp_f32_e32 v175, v175
	s_nop 0
	v_pk_add_f32 v[174:175], v[174:175], 1.0 op_sel_hi:[1,0]
	s_nop 0
	v_div_scale_f32 v176, s[6:7], v175, v175, v111
	v_rcp_f32_e32 v177, v176
	s_nop 0
	v_fma_f32 v197, -v176, v177, 1.0
	v_fmac_f32_e32 v177, v197, v177
	v_div_scale_f32 v197, vcc, v111, v175, v111
	v_mul_f32_e32 v198, v197, v177
	v_fma_f32 v199, -v176, v198, v197
	v_fmac_f32_e32 v198, v199, v177
	v_fma_f32 v176, -v176, v198, v197
	v_div_scale_f32 v197, s[6:7], v174, v174, v110
	v_rcp_f32_e32 v199, v197
	v_div_fmas_f32 v176, v176, v177, v198
	v_div_fixup_f32 v111, v176, v175, v111
	v_fma_f32 v175, -v197, v199, 1.0
	v_fmac_f32_e32 v199, v175, v199
	v_div_scale_f32 v175, vcc, v110, v174, v110
	v_mul_f32_e32 v176, v175, v199
	v_fma_f32 v177, -v197, v176, v175
	v_fmac_f32_e32 v176, v177, v199
	v_fma_f32 v175, -v197, v176, v175
	v_div_fmas_f32 v175, v175, v199, v176
	v_div_fixup_f32 v110, v175, v174, v110
	v_pk_mul_f32 v[174:175], v[110:111], v[110:111]
	s_nop 0
	v_add_f32_e32 v174, v174, v175
	v_mov_b32_e32 v175, v3
	s_nop 0
	v_add_f32_dpp v174, v174, v174 quad_perm:[1,0,3,2] row_mask:0xf bank_mask:0xf bound_ctrl:1
	s_nop 1
	v_add_f32_dpp v174, v174, v174 quad_perm:[2,3,0,1] row_mask:0xf bank_mask:0xf bound_ctrl:1
	s_nop 1
	v_add_f32_dpp v174, v174, v174 row_half_mirror row_mask:0xf bank_mask:0xf bound_ctrl:1
	s_nop 1
	v_add_f32_dpp v174, v174, v174 row_mirror row_mask:0xf bank_mask:0xf bound_ctrl:1
	s_nop 1
	v_mov_b32_dpp v175, v174 row_bcast:15 row_mask:0xa bank_mask:0xf
	v_add_f32_e32 v174, v174, v175
	v_mov_b32_e32 v175, v3
	s_nop 1
	v_mov_b32_dpp v175, v174 row_bcast:31 row_mask:0xc bank_mask:0xf
	v_add_f32_e32 v174, v174, v175
	s_nop 0
	v_readlane_b32 s6, v174, 63
	s_nop 1
	v_add_f32_e32 v174, s6, v179
	v_mul_f32_e32 v175, 0x4b800000, v174
	v_cmp_gt_f32_e32 vcc, s27, v174
	s_nop 1
	v_cndmask_b32_e32 v174, v174, v175, vcc
	v_rsq_f32_e32 v174, v174
	s_nop 0
	v_mul_f32_e32 v175, 0x45800000, v174
	v_cndmask_b32_e32 v174, v174, v175, vcc
	v_pk_mul_f32 v[110:111], v[110:111], v[174:175] op_sel_hi:[1,0]
	global_store_dwordx2 v[112:113], v[110:111], off offset:3072 sc1
	s_and_saveexec_b64 s[6:7], s[4:5]
	s_cbranch_execz .LBB0_253
	v_lshl_add_u64 v[110:111], v[68:69], 0, v[88:89]
	global_store_dwordx2 v[110:111], v[168:169], off sc1
.LBB0_253:
	s_or_b64 exec, exec, s[6:7]
	v_pk_fma_f32 v[172:173], v[172:173], v[118:119], 0 op_sel_hi:[1,1,0]
	v_lshlrev_b32_e32 v110, 16, v195
	v_pk_fma_f32 v[172:173], v[160:161], v[120:121], v[172:173]
	v_and_b32_e32 v111, 0xffff0000, v195
	v_pk_fma_f32 v[172:173], v[124:125], v[126:127], v[172:173]
	s_nop 0
	v_pk_fma_f32 v[172:173], v[122:123], v[110:111], v[172:173]
	s_nop 0
	v_mul_f32_e32 v174, 0xbfb8aa3b, v172
	v_mul_f32_e32 v175, 0xbfb8aa3b, v173
	v_exp_f32_e32 v174, v174
	v_exp_f32_e32 v175, v175
	s_nop 0
	v_pk_add_f32 v[174:175], v[174:175], 1.0 op_sel_hi:[1,0]
	s_nop 0
	v_div_scale_f32 v176, s[6:7], v175, v175, v173
	v_rcp_f32_e32 v177, v176
	s_nop 0
	v_fma_f32 v195, -v176, v177, 1.0
	v_fmac_f32_e32 v177, v195, v177
	v_div_scale_f32 v195, vcc, v173, v175, v173
	v_mul_f32_e32 v197, v195, v177
	v_fma_f32 v198, -v176, v197, v195
	v_fmac_f32_e32 v197, v198, v177
	v_fma_f32 v176, -v176, v197, v195
	v_div_scale_f32 v195, s[6:7], v174, v174, v172
	v_rcp_f32_e32 v198, v195
	v_div_fmas_f32 v176, v176, v177, v197
	v_div_fixup_f32 v173, v176, v175, v173
	v_fma_f32 v175, -v195, v198, 1.0
	v_fmac_f32_e32 v198, v175, v198
	v_div_scale_f32 v175, vcc, v172, v174, v172
	v_mul_f32_e32 v176, v175, v198
	v_fma_f32 v177, -v195, v176, v175
	v_fmac_f32_e32 v176, v177, v198
	v_fma_f32 v175, -v195, v176, v175
	v_div_fmas_f32 v175, v175, v198, v176
	v_div_fixup_f32 v172, v175, v174, v172
	v_pk_mul_f32 v[174:175], v[172:173], v[172:173]
	s_nop 0
	v_add_f32_e32 v174, v174, v175
	v_mov_b32_e32 v175, v3
	s_nop 0
	v_add_f32_dpp v174, v174, v174 quad_perm:[1,0,3,2] row_mask:0xf bank_mask:0xf bound_ctrl:1
	s_nop 1
	v_add_f32_dpp v174, v174, v174 quad_perm:[2,3,0,1] row_mask:0xf bank_mask:0xf bound_ctrl:1
	s_nop 1
	v_add_f32_dpp v174, v174, v174 row_half_mirror row_mask:0xf bank_mask:0xf bound_ctrl:1
	s_nop 1
	v_add_f32_dpp v174, v174, v174 row_mirror row_mask:0xf bank_mask:0xf bound_ctrl:1
	s_nop 1
	v_mov_b32_dpp v175, v174 row_bcast:15 row_mask:0xa bank_mask:0xf
	v_add_f32_e32 v174, v174, v175
	v_mov_b32_e32 v175, v3
	s_nop 1
	v_mov_b32_dpp v175, v174 row_bcast:31 row_mask:0xc bank_mask:0xf
	v_add_f32_e32 v174, v174, v175
	s_nop 0
	v_readlane_b32 s6, v174, 63
	s_nop 1
	v_add_f32_e32 v174, s6, v179
	v_mul_f32_e32 v175, 0x4b800000, v174
	v_cmp_gt_f32_e32 vcc, s27, v174
	s_nop 1
	v_cndmask_b32_e32 v174, v174, v175, vcc
	v_rsq_f32_e32 v174, v174
	s_nop 0
	v_mul_f32_e32 v175, 0x45800000, v174
	v_cndmask_b32_e32 v174, v174, v175, vcc
	v_pk_mul_f32 v[172:173], v[172:173], v[174:175] op_sel_hi:[1,0]
	global_store_dwordx2 v[112:113], v[172:173], off offset:3584 sc1
	s_and_saveexec_b64 s[6:7], s[4:5]
	s_cbranch_execz .LBB0_255
	v_lshl_add_u64 v[112:113], v[70:71], 0, v[88:89]
	global_store_dwordx2 v[112:113], v[110:111], off sc1
; DI float bflo(unsigned u) { return __uint_as_float(u << 16); }
; DI float bfhi(unsigned u) { return __uint_as_float(u & 0xffff0000u); }
; DI float siluf_(float x) { return x / (1.0f + __expf(-x)); }
; template <int G0>
; DI void qkv_run4_half(const Params& p, int row0, int lane) {
;     ...
;     for (int g = 0; g < 4; ++g) {
;       const int grp = G0 + g;
;       const int ch = grp * 128 + lane * 2;
;       float a0 = 0.f, a1 = 0.f;
; #pragma unroll
;       for (int j = 0; j < 4; ++j) {
;         const int i = k + j;
;         const float m = (i >= 3) ? 1.f : hm;
;         a0 += w[g][j].x * (bflo(u[g][i]) * m);
;         a1 += w[g][j].y * (bfhi(u[g][i]) * m);
;       }
;       float y0 = siluf_(a0), y1 = siluf_(a1);
;       if (grp < 8) {
;         float ss = wave_sum(y0 * y0 + y1 * y1);
;         float inv = rsqrtf(ss + EPSF);
;         if (grp < 4) inv *= 0.08838834764831845f;
;         y0 *= inv; y1 *= inv;
;       }
;       float2 o = {y0, y1};
;       *(float2*)(p.QKV + (size_t)row * 1536 + ch) = o;
;       if (t0 == 2044 && k >= 1) {
;         float2 c = {bflo(u[g][k + 3]), bfhi(u[g][k + 3])};
;         *(float2*)(p.out + O_QKVP + ((size_t)b * 3 + (k - 1)) * 1536 + ch) = c;
;       }
.LBB0_255:
	s_or_b64 exec, exec, s[6:7]
	v_pk_fma_f32 v[112:113], v[166:167], v[150:151], 0 op_sel_hi:[1,1,0]
	v_lshlrev_b32_e32 v172, 16, v194
	v_pk_fma_f32 v[112:113], v[152:153], v[148:149], v[112:113]
	v_and_b32_e32 v173, 0xffff0000, v194
	v_pk_fma_f32 v[112:113], v[156:157], v[158:159], v[112:113]
	s_nop 0
	v_pk_fma_f32 v[112:113], v[154:155], v[172:173], v[112:113]
	s_nop 0
	v_mul_f32_e32 v166, 0xbfb8aa3b, v112
	v_mul_f32_e32 v167, 0xbfb8aa3b, v113
	v_exp_f32_e32 v166, v166
	v_exp_f32_e32 v167, v167
	s_nop 0
	v_pk_add_f32 v[166:167], v[166:167], 1.0 op_sel_hi:[1,0]
	s_nop 0
	v_div_scale_f32 v174, s[6:7], v167, v167, v113
	v_rcp_f32_e32 v175, v174
	s_nop 0
	v_fma_f32 v176, -v174, v175, 1.0
	v_fmac_f32_e32 v175, v176, v175
	v_div_scale_f32 v176, vcc, v113, v167, v113
	v_mul_f32_e32 v177, v176, v175
	v_fma_f32 v194, -v174, v177, v176
	v_fmac_f32_e32 v177, v194, v175
	v_fma_f32 v174, -v174, v177, v176
	v_div_scale_f32 v176, s[6:7], v166, v166, v112
	v_rcp_f32_e32 v194, v176
	v_div_fmas_f32 v174, v174, v175, v177
	v_div_fixup_f32 v113, v174, v167, v113
	v_fma_f32 v167, -v176, v194, 1.0
	v_fmac_f32_e32 v194, v167, v194
	v_div_scale_f32 v167, vcc, v112, v166, v112
	v_mul_f32_e32 v174, v167, v194
	v_fma_f32 v175, -v176, v174, v167
	v_fmac_f32_e32 v174, v175, v194
	v_fma_f32 v167, -v176, v174, v167
	v_div_fmas_f32 v167, v167, v194, v174
	v_div_fixup_f32 v112, v167, v166, v112
	v_pk_mul_f32 v[166:167], v[112:113], v[112:113]
	s_nop 0
	v_add_f32_e32 v166, v166, v167
	v_mov_b32_e32 v167, v3
	s_nop 0
	v_add_f32_dpp v166, v166, v166 quad_perm:[1,0,3,2] row_mask:0xf bank_mask:0xf bound_ctrl:1
	s_nop 1
	v_add_f32_dpp v166, v166, v166 quad_perm:[2,3,0,1] row_mask:0xf bank_mask:0xf bound_ctrl:1
	s_nop 1
	v_add_f32_dpp v166, v166, v166 row_half_mirror row_mask:0xf bank_mask:0xf bound_ctrl:1
	s_nop 1
	v_add_f32_dpp v166, v166, v166 row_mirror row_mask:0xf bank_mask:0xf bound_ctrl:1
	s_nop 1
	v_mov_b32_dpp v167, v166 row_bcast:15 row_mask:0xa bank_mask:0xf
	v_add_f32_e32 v166, v166, v167
	v_mov_b32_e32 v167, v3
	s_nop 1
	v_mov_b32_dpp v167, v166 row_bcast:31 row_mask:0xc bank_mask:0xf
	v_add_f32_e32 v166, v166, v167
	s_nop 0
	v_readlane_b32 s6, v166, 63
	s_nop 1
	v_add_f32_e32 v166, s6, v179
	v_mul_f32_e32 v167, 0x4b800000, v166
	v_cmp_gt_f32_e32 vcc, s27, v166
	s_nop 1
	v_cndmask_b32_e32 v166, v166, v167, vcc
	v_rsq_f32_e32 v166, v166
	s_nop 0
	v_mul_f32_e32 v167, 0x45800000, v166
	v_cndmask_b32_e32 v166, v166, v167, vcc
	v_pk_mul_f32 v[112:113], v[112:113], v[166:167] op_sel_hi:[1,0]
	global_store_dwordx2 v[114:115], v[112:113], off offset:2048 sc1
	s_and_saveexec_b64 s[6:7], s[4:5]
	s_cbranch_execz .LBB0_257
	v_lshl_add_u64 v[112:113], v[64:65], 0, v[94:95]
	global_store_dwordx2 v[112:113], v[172:173], off sc1
.LBB0_257:
	s_or_b64 exec, exec, s[6:7]
	v_pk_fma_f32 v[112:113], v[164:165], v[140:141], 0 op_sel_hi:[1,1,0]
	v_lshlrev_b32_e32 v166, 16, v193
	v_pk_fma_f32 v[112:113], v[142:143], v[146:147], v[112:113]
	v_and_b32_e32 v167, 0xffff0000, v193
	v_pk_fma_f32 v[112:113], v[144:145], v[170:171], v[112:113]
	s_nop 0
	v_pk_fma_f32 v[112:113], v[138:139], v[166:167], v[112:113]
	s_nop 0
	v_mul_f32_e32 v164, 0xbfb8aa3b, v112
	v_mul_f32_e32 v165, 0xbfb8aa3b, v113
	v_exp_f32_e32 v164, v164
	v_exp_f32_e32 v165, v165
	s_nop 0
	v_pk_add_f32 v[164:165], v[164:165], 1.0 op_sel_hi:[1,0]
	s_nop 0
	v_div_scale_f32 v174, s[6:7], v165, v165, v113
	v_rcp_f32_e32 v175, v174
	s_nop 0
	v_fma_f32 v176, -v174, v175, 1.0
	v_fmac_f32_e32 v175, v176, v175
	v_div_scale_f32 v176, vcc, v113, v165, v113
	v_mul_f32_e32 v177, v176, v175
	v_fma_f32 v193, -v174, v177, v176
	v_fmac_f32_e32 v177, v193, v175
	v_fma_f32 v174, -v174, v177, v176
	v_div_scale_f32 v176, s[6:7], v164, v164, v112
	v_rcp_f32_e32 v193, v176
	v_div_fmas_f32 v174, v174, v175, v177
	v_div_fixup_f32 v113, v174, v165, v113
	v_fma_f32 v165, -v176, v193, 1.0
	v_fmac_f32_e32 v193, v165, v193
	v_div_scale_f32 v165, vcc, v112, v164, v112
	v_mul_f32_e32 v174, v165, v193
	v_fma_f32 v175, -v176, v174, v165
	v_fmac_f32_e32 v174, v175, v193
	v_fma_f32 v165, -v176, v174, v165
	v_div_fmas_f32 v165, v165, v193, v174
	v_div_fixup_f32 v112, v165, v164, v112
	v_pk_mul_f32 v[164:165], v[112:113], v[112:113]
	s_nop 0
	v_add_f32_e32 v164, v164, v165
	v_mov_b32_e32 v165, v3
	s_nop 0
	v_add_f32_dpp v164, v164, v164 quad_perm:[1,0,3,2] row_mask:0xf bank_mask:0xf bound_ctrl:1
	s_nop 1
	v_add_f32_dpp v164, v164, v164 quad_perm:[2,3,0,1] row_mask:0xf bank_mask:0xf bound_ctrl:1
	s_nop 1
	v_add_f32_dpp v164, v164, v164 row_half_mirror row_mask:0xf bank_mask:0xf bound_ctrl:1
	s_nop 1
	v_add_f32_dpp v164, v164, v164 row_mirror row_mask:0xf bank_mask:0xf bound_ctrl:1
	s_nop 1
	v_mov_b32_dpp v165, v164 row_bcast:15 row_mask:0xa bank_mask:0xf
	v_add_f32_e32 v164, v164, v165
	v_mov_b32_e32 v165, v3
	s_nop 1
	v_mov_b32_dpp v165, v164 row_bcast:31 row_mask:0xc bank_mask:0xf
	v_add_f32_e32 v164, v164, v165
	s_nop 0
	v_readlane_b32 s6, v164, 63
	s_nop 1
	v_add_f32_e32 v164, s6, v179
	v_mul_f32_e32 v165, 0x4b800000, v164
	v_cmp_gt_f32_e32 vcc, s27, v164
	s_nop 1
	v_cndmask_b32_e32 v164, v164, v165, vcc
	v_rsq_f32_e32 v164, v164
	s_nop 0
	v_mul_f32_e32 v165, 0x45800000, v164
	v_cndmask_b32_e32 v164, v164, v165, vcc
	v_pk_mul_f32 v[112:113], v[112:113], v[164:165] op_sel_hi:[1,0]
	global_store_dwordx2 v[114:115], v[112:113], off offset:2560 sc1
	s_and_saveexec_b64 s[6:7], s[4:5]
	s_cbranch_execz .LBB0_259
	v_lshl_add_u64 v[112:113], v[66:67], 0, v[94:95]
	global_store_dwordx2 v[112:113], v[166:167], off sc1
; DI float bflo(unsigned u) { return __uint_as_float(u << 16); }
; DI float bfhi(unsigned u) { return __uint_as_float(u & 0xffff0000u); }
; DI float siluf_(float x) { return x / (1.0f + __expf(-x)); }
; template <int G0>
; DI void qkv_run4_half(const Params& p, int row0, int lane) {
;     ...
;     for (int g = 0; g < 4; ++g) {
;       const int grp = G0 + g;
;       const int ch = grp * 128 + lane * 2;
;       float a0 = 0.f, a1 = 0.f;
; #pragma unroll
;       for (int j = 0; j < 4; ++j) {
;         const int i = k + j;
;         const float m = (i >= 3) ? 1.f : hm;
;         a0 += w[g][j].x * (bflo(u[g][i]) * m);
;         a1 += w[g][j].y * (bfhi(u[g][i]) * m);
;       }
;       float y0 = siluf_(a0), y1 = siluf_(a1);
;       if (grp < 8) {
;         float ss = wave_sum(y0 * y0 + y1 * y1);
;         float inv = rsqrtf(ss + EPSF);
;         if (grp < 4) inv *= 0.08838834764831845f;
;         y0 *= inv; y1 *= inv;
;       }
;       float2 o = {y0, y1};
;       *(float2*)(p.QKV + (size_t)row * 1536 + ch) = o;
;       if (t0 == 2044 && k >= 1) {
;         float2 c = {bflo(u[g][k + 3]), bfhi(u[g][k + 3])};
;         *(float2*)(p.out + O_QKVP + ((size_t)b * 3 + (k - 1)) * 1536 + ch) = c;
;       }
.LBB0_259:
	s_or_b64 exec, exec, s[6:7]
	v_pk_fma_f32 v[112:113], v[162:163], v[132:133], 0 op_sel_hi:[1,1,0]
	v_lshlrev_b32_e32 v164, 16, v192
	v_pk_fma_f32 v[112:113], v[134:135], v[130:131], v[112:113]
	v_and_b32_e32 v165, 0xffff0000, v192
	v_pk_fma_f32 v[112:113], v[136:137], v[168:169], v[112:113]
	s_nop 0
	v_pk_fma_f32 v[112:113], v[128:129], v[164:165], v[112:113]
	s_nop 0
	v_mul_f32_e32 v162, 0xbfb8aa3b, v112
	v_mul_f32_e32 v163, 0xbfb8aa3b, v113
	v_exp_f32_e32 v162, v162
	v_exp_f32_e32 v163, v163
	s_nop 0
	v_pk_add_f32 v[162:163], v[162:163], 1.0 op_sel_hi:[1,0]
	s_nop 0
	v_div_scale_f32 v174, s[6:7], v163, v163, v113
	v_rcp_f32_e32 v175, v174
	s_nop 0
	v_fma_f32 v176, -v174, v175, 1.0
	v_fmac_f32_e32 v175, v176, v175
	v_div_scale_f32 v176, vcc, v113, v163, v113
	v_mul_f32_e32 v177, v176, v175
	v_fma_f32 v192, -v174, v177, v176
	v_fmac_f32_e32 v177, v192, v175
	v_fma_f32 v174, -v174, v177, v176
	v_div_scale_f32 v176, s[6:7], v162, v162, v112
	v_rcp_f32_e32 v192, v176
	v_div_fmas_f32 v174, v174, v175, v177
	v_div_fixup_f32 v113, v174, v163, v113
	v_fma_f32 v163, -v176, v192, 1.0
	v_fmac_f32_e32 v192, v163, v192
	v_div_scale_f32 v163, vcc, v112, v162, v112
	v_mul_f32_e32 v174, v163, v192
	v_fma_f32 v175, -v176, v174, v163
	v_fmac_f32_e32 v174, v175, v192
	v_fma_f32 v163, -v176, v174, v163
	v_div_fmas_f32 v163, v163, v192, v174
	v_div_fixup_f32 v112, v163, v162, v112
	v_pk_mul_f32 v[162:163], v[112:113], v[112:113]
	s_nop 0
	v_add_f32_e32 v162, v162, v163
	v_mov_b32_e32 v163, v3
	s_nop 0
	v_add_f32_dpp v162, v162, v162 quad_perm:[1,0,3,2] row_mask:0xf bank_mask:0xf bound_ctrl:1
	s_nop 1
	v_add_f32_dpp v162, v162, v162 quad_perm:[2,3,0,1] row_mask:0xf bank_mask:0xf bound_ctrl:1
	s_nop 1
	v_add_f32_dpp v162, v162, v162 row_half_mirror row_mask:0xf bank_mask:0xf bound_ctrl:1
	s_nop 1
	v_add_f32_dpp v162, v162, v162 row_mirror row_mask:0xf bank_mask:0xf bound_ctrl:1
	s_nop 1
	v_mov_b32_dpp v163, v162 row_bcast:15 row_mask:0xa bank_mask:0xf
	v_add_f32_e32 v162, v162, v163
	v_mov_b32_e32 v163, v3
	s_nop 1
	v_mov_b32_dpp v163, v162 row_bcast:31 row_mask:0xc bank_mask:0xf
	v_add_f32_e32 v162, v162, v163
	s_nop 0
	v_readlane_b32 s6, v162, 63
	s_nop 1
	v_add_f32_e32 v162, s6, v179
	v_mul_f32_e32 v163, 0x4b800000, v162
	v_cmp_gt_f32_e32 vcc, s27, v162
	s_nop 1
	v_cndmask_b32_e32 v162, v162, v163, vcc
	v_rsq_f32_e32 v162, v162
	s_nop 0
	v_mul_f32_e32 v163, 0x45800000, v162
	v_cndmask_b32_e32 v162, v162, v163, vcc
	v_pk_mul_f32 v[112:113], v[112:113], v[162:163] op_sel_hi:[1,0]
	global_store_dwordx2 v[114:115], v[112:113], off offset:3072 sc1
	s_and_saveexec_b64 s[6:7], s[4:5]
	s_cbranch_execz .LBB0_261
	v_lshl_add_u64 v[112:113], v[68:69], 0, v[94:95]
	global_store_dwordx2 v[112:113], v[164:165], off sc1
.LBB0_261:
	s_or_b64 exec, exec, s[6:7]
	v_pk_fma_f32 v[160:161], v[160:161], v[118:119], 0 op_sel_hi:[1,1,0]
	v_lshlrev_b32_e32 v112, 16, v191
	v_pk_fma_f32 v[160:161], v[120:121], v[126:127], v[160:161]
	v_and_b32_e32 v113, 0xffff0000, v191
	v_pk_fma_f32 v[160:161], v[124:125], v[110:111], v[160:161]
	s_nop 0
	v_pk_fma_f32 v[160:161], v[122:123], v[112:113], v[160:161]
	s_nop 0
	v_mul_f32_e32 v162, 0xbfb8aa3b, v160
	v_mul_f32_e32 v163, 0xbfb8aa3b, v161
	v_exp_f32_e32 v162, v162
	v_exp_f32_e32 v163, v163
	s_nop 0
	v_pk_add_f32 v[162:163], v[162:163], 1.0 op_sel_hi:[1,0]
	s_nop 0
	v_div_scale_f32 v174, s[6:7], v163, v163, v161
	v_rcp_f32_e32 v175, v174
	s_nop 0
	v_fma_f32 v176, -v174, v175, 1.0
	v_fmac_f32_e32 v175, v176, v175
	v_div_scale_f32 v176, vcc, v161, v163, v161
	v_mul_f32_e32 v177, v176, v175
	v_fma_f32 v191, -v174, v177, v176
	v_fmac_f32_e32 v177, v191, v175
	v_fma_f32 v174, -v174, v177, v176
	v_div_scale_f32 v176, s[6:7], v162, v162, v160
	v_rcp_f32_e32 v191, v176
	v_div_fmas_f32 v174, v174, v175, v177
	v_div_fixup_f32 v161, v174, v163, v161
	v_fma_f32 v163, -v176, v191, 1.0
	v_fmac_f32_e32 v191, v163, v191
	v_div_scale_f32 v163, vcc, v160, v162, v160
	v_mul_f32_e32 v174, v163, v191
	v_fma_f32 v175, -v176, v174, v163
	v_fmac_f32_e32 v174, v175, v191
	v_fma_f32 v163, -v176, v174, v163
	v_div_fmas_f32 v163, v163, v191, v174
	v_div_fixup_f32 v160, v163, v162, v160
	v_pk_mul_f32 v[162:163], v[160:161], v[160:161]
	s_nop 0
	v_add_f32_e32 v162, v162, v163
	v_mov_b32_e32 v163, v3
	s_nop 0
	v_add_f32_dpp v162, v162, v162 quad_perm:[1,0,3,2] row_mask:0xf bank_mask:0xf bound_ctrl:1
	s_nop 1
	v_add_f32_dpp v162, v162, v162 quad_perm:[2,3,0,1] row_mask:0xf bank_mask:0xf bound_ctrl:1
	s_nop 1
	v_add_f32_dpp v162, v162, v162 row_half_mirror row_mask:0xf bank_mask:0xf bound_ctrl:1
	s_nop 1
	v_add_f32_dpp v162, v162, v162 row_mirror row_mask:0xf bank_mask:0xf bound_ctrl:1
	s_nop 1
	v_mov_b32_dpp v163, v162 row_bcast:15 row_mask:0xa bank_mask:0xf
	v_add_f32_e32 v162, v162, v163
	v_mov_b32_e32 v163, v3
	s_nop 1
	v_mov_b32_dpp v163, v162 row_bcast:31 row_mask:0xc bank_mask:0xf
	v_add_f32_e32 v162, v162, v163
	s_nop 0
	v_readlane_b32 s6, v162, 63
	s_nop 1
	v_add_f32_e32 v162, s6, v179
	v_mul_f32_e32 v163, 0x4b800000, v162
	v_cmp_gt_f32_e32 vcc, s27, v162
	s_nop 1
	v_cndmask_b32_e32 v162, v162, v163, vcc
	v_rsq_f32_e32 v162, v162
	s_nop 0
	v_mul_f32_e32 v163, 0x45800000, v162
	v_cndmask_b32_e32 v162, v162, v163, vcc
	v_pk_mul_f32 v[160:161], v[160:161], v[162:163] op_sel_hi:[1,0]
	global_store_dwordx2 v[114:115], v[160:161], off offset:3584 sc1
	s_and_saveexec_b64 s[6:7], s[4:5]
	s_cbranch_execz .LBB0_263
	v_lshl_add_u64 v[114:115], v[70:71], 0, v[94:95]
	global_store_dwordx2 v[114:115], v[112:113], off sc1
; DI float bflo(unsigned u) { return __uint_as_float(u << 16); }
; DI float bfhi(unsigned u) { return __uint_as_float(u & 0xffff0000u); }
; DI float siluf_(float x) { return x / (1.0f + __expf(-x)); }
; template <int G0>
; DI void qkv_run4_half(const Params& p, int row0, int lane) {
;     ...
;     for (int g = 0; g < 4; ++g) {
;       const int grp = G0 + g;
;       const int ch = grp * 128 + lane * 2;
;       float a0 = 0.f, a1 = 0.f;
; #pragma unroll
;       for (int j = 0; j < 4; ++j) {
;         const int i = k + j;
;         const float m = (i >= 3) ? 1.f : hm;
;         a0 += w[g][j].x * (bflo(u[g][i]) * m);
;         a1 += w[g][j].y * (bfhi(u[g][i]) * m);
;       }
;       float y0 = siluf_(a0), y1 = siluf_(a1);
;       if (grp < 8) {
;         float ss = wave_sum(y0 * y0 + y1 * y1);
;         float inv = rsqrtf(ss + EPSF);
;         if (grp < 4) inv *= 0.08838834764831845f;
;         y0 *= inv; y1 *= inv;
;       }
;       float2 o = {y0, y1};
;       *(float2*)(p.QKV + (size_t)row * 1536 + ch) = o;
;       if (t0 == 2044 && k >= 1) {
;         float2 c = {bflo(u[g][k + 3]), bfhi(u[g][k + 3])};
;         *(float2*)(p.out + O_QKVP + ((size_t)b * 3 + (k - 1)) * 1536 + ch) = c;
;       }
.LBB0_263:
	s_or_b64 exec, exec, s[6:7]
	v_pk_fma_f32 v[148:149], v[150:151], v[148:149], 0 op_sel_hi:[1,1,0]
	v_lshlrev_b32_e32 v114, 16, v190
	v_pk_fma_f32 v[148:149], v[152:153], v[158:159], v[148:149]
	v_and_b32_e32 v115, 0xffff0000, v190
	v_pk_fma_f32 v[148:149], v[156:157], v[172:173], v[148:149]
	s_nop 0
	v_pk_fma_f32 v[148:149], v[154:155], v[114:115], v[148:149]
	s_nop 0
	v_mul_f32_e32 v150, 0xbfb8aa3b, v148
	v_mul_f32_e32 v151, 0xbfb8aa3b, v149
	v_exp_f32_e32 v150, v150
	v_exp_f32_e32 v151, v151
	s_nop 0
	v_pk_add_f32 v[150:151], v[150:151], 1.0 op_sel_hi:[1,0]
	s_nop 0
	v_div_scale_f32 v152, s[6:7], v151, v151, v149
	v_rcp_f32_e32 v153, v152
	s_nop 0
	v_fma_f32 v154, -v152, v153, 1.0
	v_fmac_f32_e32 v153, v154, v153
	v_div_scale_f32 v154, vcc, v149, v151, v149
	v_mul_f32_e32 v155, v154, v153
	v_fma_f32 v156, -v152, v155, v154
	v_fmac_f32_e32 v155, v156, v153
	v_fma_f32 v152, -v152, v155, v154
	v_div_scale_f32 v154, s[6:7], v150, v150, v148
	v_rcp_f32_e32 v156, v154
	v_div_fmas_f32 v152, v152, v153, v155
	v_div_fixup_f32 v149, v152, v151, v149
	v_fma_f32 v151, -v154, v156, 1.0
	v_fmac_f32_e32 v156, v151, v156
	v_div_scale_f32 v151, vcc, v148, v150, v148
	v_mul_f32_e32 v152, v151, v156
	v_fma_f32 v153, -v154, v152, v151
	v_fmac_f32_e32 v152, v153, v156
	v_fma_f32 v151, -v154, v152, v151
	v_div_fmas_f32 v151, v151, v156, v152
	v_div_fixup_f32 v148, v151, v150, v148
	v_pk_mul_f32 v[150:151], v[148:149], v[148:149]
	s_nop 0
	v_add_f32_e32 v150, v150, v151
	v_mov_b32_e32 v151, v3
	s_nop 0
	v_add_f32_dpp v150, v150, v150 quad_perm:[1,0,3,2] row_mask:0xf bank_mask:0xf bound_ctrl:1
	s_nop 1
	v_add_f32_dpp v150, v150, v150 quad_perm:[2,3,0,1] row_mask:0xf bank_mask:0xf bound_ctrl:1
	s_nop 1
	v_add_f32_dpp v150, v150, v150 row_half_mirror row_mask:0xf bank_mask:0xf bound_ctrl:1
	s_nop 1
	v_add_f32_dpp v150, v150, v150 row_mirror row_mask:0xf bank_mask:0xf bound_ctrl:1
	s_nop 1
	v_mov_b32_dpp v151, v150 row_bcast:15 row_mask:0xa bank_mask:0xf
	v_add_f32_e32 v150, v150, v151
	v_mov_b32_e32 v151, v3
	s_nop 1
	v_mov_b32_dpp v151, v150 row_bcast:31 row_mask:0xc bank_mask:0xf
	v_add_f32_e32 v150, v150, v151
	s_nop 0
	v_readlane_b32 s6, v150, 63
	s_nop 1
	v_add_f32_e32 v150, s6, v179
	v_mul_f32_e32 v151, 0x4b800000, v150
	v_cmp_gt_f32_e32 vcc, s27, v150
	s_nop 1
	v_cndmask_b32_e32 v150, v150, v151, vcc
	v_rsq_f32_e32 v150, v150
	s_nop 0
	v_mul_f32_e32 v151, 0x45800000, v150
	v_cndmask_b32_e32 v150, v150, v151, vcc
	v_pk_mul_f32 v[148:149], v[148:149], v[150:151] op_sel_hi:[1,0]
	global_store_dwordx2 v[116:117], v[148:149], off offset:2048 sc1
	s_and_saveexec_b64 s[6:7], s[4:5]
	s_cbranch_execz .LBB0_265
	v_lshl_add_u64 v[148:149], v[64:65], 0, v[108:109]
	global_store_dwordx2 v[148:149], v[114:115], off sc1
.LBB0_265:
	s_or_b64 exec, exec, s[6:7]
	v_pk_fma_f32 v[140:141], v[140:141], v[146:147], 0 op_sel_hi:[1,1,0]
	v_lshlrev_b32_e32 v114, 16, v189
	v_pk_fma_f32 v[140:141], v[142:143], v[170:171], v[140:141]
	v_and_b32_e32 v115, 0xffff0000, v189
	v_pk_fma_f32 v[140:141], v[144:145], v[166:167], v[140:141]
	s_nop 0
	v_pk_fma_f32 v[138:139], v[138:139], v[114:115], v[140:141]
	s_nop 0
	v_mul_f32_e32 v140, 0xbfb8aa3b, v138
	v_mul_f32_e32 v141, 0xbfb8aa3b, v139
	v_exp_f32_e32 v140, v140
	v_exp_f32_e32 v141, v141
	s_nop 0
	v_pk_add_f32 v[140:141], v[140:141], 1.0 op_sel_hi:[1,0]
	s_nop 0
	v_div_scale_f32 v142, s[6:7], v141, v141, v139
	v_rcp_f32_e32 v143, v142
	s_nop 0
	v_fma_f32 v144, -v142, v143, 1.0
	v_fmac_f32_e32 v143, v144, v143
	v_div_scale_f32 v144, vcc, v139, v141, v139
	v_mul_f32_e32 v145, v144, v143
	v_fma_f32 v146, -v142, v145, v144
	v_fmac_f32_e32 v145, v146, v143
	v_fma_f32 v142, -v142, v145, v144
	v_div_scale_f32 v144, s[6:7], v140, v140, v138
	v_rcp_f32_e32 v146, v144
	v_div_fmas_f32 v142, v142, v143, v145
	v_div_fixup_f32 v139, v142, v141, v139
	v_fma_f32 v141, -v144, v146, 1.0
	v_fmac_f32_e32 v146, v141, v146
	v_div_scale_f32 v141, vcc, v138, v140, v138
	v_mul_f32_e32 v142, v141, v146
	v_fma_f32 v143, -v144, v142, v141
	v_fmac_f32_e32 v142, v143, v146
	v_fma_f32 v141, -v144, v142, v141
	v_div_fmas_f32 v141, v141, v146, v142
	v_div_fixup_f32 v138, v141, v140, v138
	v_pk_mul_f32 v[140:141], v[138:139], v[138:139]
	s_nop 0
	v_add_f32_e32 v140, v140, v141
	v_mov_b32_e32 v141, v3
	s_nop 0
	v_add_f32_dpp v140, v140, v140 quad_perm:[1,0,3,2] row_mask:0xf bank_mask:0xf bound_ctrl:1
	s_nop 1
	v_add_f32_dpp v140, v140, v140 quad_perm:[2,3,0,1] row_mask:0xf bank_mask:0xf bound_ctrl:1
	s_nop 1
	v_add_f32_dpp v140, v140, v140 row_half_mirror row_mask:0xf bank_mask:0xf bound_ctrl:1
	s_nop 1
	v_add_f32_dpp v140, v140, v140 row_mirror row_mask:0xf bank_mask:0xf bound_ctrl:1
	s_nop 1
	v_mov_b32_dpp v141, v140 row_bcast:15 row_mask:0xa bank_mask:0xf
	v_add_f32_e32 v140, v140, v141
	v_mov_b32_e32 v141, v3
	s_nop 1
	v_mov_b32_dpp v141, v140 row_bcast:31 row_mask:0xc bank_mask:0xf
	v_add_f32_e32 v140, v140, v141
	s_nop 0
	v_readlane_b32 s6, v140, 63
	s_nop 1
	v_add_f32_e32 v140, s6, v179
	v_mul_f32_e32 v141, 0x4b800000, v140
	v_cmp_gt_f32_e32 vcc, s27, v140
	s_nop 1
	v_cndmask_b32_e32 v140, v140, v141, vcc
	v_rsq_f32_e32 v140, v140
	s_nop 0
	v_mul_f32_e32 v141, 0x45800000, v140
	v_cndmask_b32_e32 v140, v140, v141, vcc
	v_pk_mul_f32 v[138:139], v[138:139], v[140:141] op_sel_hi:[1,0]
	global_store_dwordx2 v[116:117], v[138:139], off offset:2560 sc1
	s_and_saveexec_b64 s[6:7], s[4:5]
	s_cbranch_execz .LBB0_267
	v_lshl_add_u64 v[138:139], v[66:67], 0, v[108:109]
	global_store_dwordx2 v[138:139], v[114:115], off sc1
; DI float bflo(unsigned u) { return __uint_as_float(u << 16); }
; DI float bfhi(unsigned u) { return __uint_as_float(u & 0xffff0000u); }
; DI float siluf_(float x) { return x / (1.0f + __expf(-x)); }
; template <int G0>
; DI void qkv_run4_half(const Params& p, int row0, int lane) {
;     ...
;     for (int g = 0; g < 4; ++g) {
;       const int grp = G0 + g;
;       const int ch = grp * 128 + lane * 2;
;       float a0 = 0.f, a1 = 0.f;
; #pragma unroll
;       for (int j = 0; j < 4; ++j) {
;         const int i = k + j;
;         const float m = (i >= 3) ? 1.f : hm;
;         a0 += w[g][j].x * (bflo(u[g][i]) * m);
;         a1 += w[g][j].y * (bfhi(u[g][i]) * m);
;       }
;       float y0 = siluf_(a0), y1 = siluf_(a1);
;       if (grp < 8) {
;         float ss = wave_sum(y0 * y0 + y1 * y1);
;         float inv = rsqrtf(ss + EPSF);
;         if (grp < 4) inv *= 0.08838834764831845f;
;         y0 *= inv; y1 *= inv;
;       }
;       float2 o = {y0, y1};
;       *(float2*)(p.QKV + (size_t)row * 1536 + ch) = o;
;       if (t0 == 2044 && k >= 1) {
;         float2 c = {bflo(u[g][k + 3]), bfhi(u[g][k + 3])};
;         *(float2*)(p.out + O_QKVP + ((size_t)b * 3 + (k - 1)) * 1536 + ch) = c;
;       }
.LBB0_267:
	s_or_b64 exec, exec, s[6:7]
	v_pk_fma_f32 v[130:131], v[132:133], v[130:131], 0 op_sel_hi:[1,1,0]
	v_lshlrev_b32_e32 v114, 16, v188
	v_pk_fma_f32 v[130:131], v[134:135], v[168:169], v[130:131]
	v_and_b32_e32 v115, 0xffff0000, v188
	v_pk_fma_f32 v[130:131], v[136:137], v[164:165], v[130:131]
	s_nop 0
	v_pk_fma_f32 v[128:129], v[128:129], v[114:115], v[130:131]
	s_nop 0
	v_mul_f32_e32 v130, 0xbfb8aa3b, v128
	v_mul_f32_e32 v131, 0xbfb8aa3b, v129
	v_exp_f32_e32 v130, v130
	v_exp_f32_e32 v131, v131
	s_nop 0
	v_pk_add_f32 v[130:131], v[130:131], 1.0 op_sel_hi:[1,0]
	s_nop 0
	v_div_scale_f32 v132, s[6:7], v131, v131, v129
	v_rcp_f32_e32 v133, v132
	s_nop 0
	v_fma_f32 v134, -v132, v133, 1.0
	v_fmac_f32_e32 v133, v134, v133
	v_div_scale_f32 v134, vcc, v129, v131, v129
	v_mul_f32_e32 v135, v134, v133
	v_fma_f32 v136, -v132, v135, v134
	v_fmac_f32_e32 v135, v136, v133
	v_fma_f32 v132, -v132, v135, v134
	v_div_scale_f32 v134, s[6:7], v130, v130, v128
	v_rcp_f32_e32 v136, v134
	v_div_fmas_f32 v132, v132, v133, v135
	v_div_fixup_f32 v129, v132, v131, v129
	v_fma_f32 v131, -v134, v136, 1.0
	v_fmac_f32_e32 v136, v131, v136
	v_div_scale_f32 v131, vcc, v128, v130, v128
	v_mul_f32_e32 v132, v131, v136
	v_fma_f32 v133, -v134, v132, v131
	v_fmac_f32_e32 v132, v133, v136
	v_fma_f32 v131, -v134, v132, v131
	v_div_fmas_f32 v131, v131, v136, v132
	v_div_fixup_f32 v128, v131, v130, v128
	v_pk_mul_f32 v[130:131], v[128:129], v[128:129]
	s_nop 0
	v_add_f32_e32 v130, v130, v131
	v_mov_b32_e32 v131, v3
	s_nop 0
	v_add_f32_dpp v130, v130, v130 quad_perm:[1,0,3,2] row_mask:0xf bank_mask:0xf bound_ctrl:1
	s_nop 1
	v_add_f32_dpp v130, v130, v130 quad_perm:[2,3,0,1] row_mask:0xf bank_mask:0xf bound_ctrl:1
	s_nop 1
	v_add_f32_dpp v130, v130, v130 row_half_mirror row_mask:0xf bank_mask:0xf bound_ctrl:1
	s_nop 1
	v_add_f32_dpp v130, v130, v130 row_mirror row_mask:0xf bank_mask:0xf bound_ctrl:1
	s_nop 1
	v_mov_b32_dpp v131, v130 row_bcast:15 row_mask:0xa bank_mask:0xf
	v_add_f32_e32 v130, v130, v131
	v_mov_b32_e32 v131, v3
	s_nop 1
	v_mov_b32_dpp v131, v130 row_bcast:31 row_mask:0xc bank_mask:0xf
	v_add_f32_e32 v130, v130, v131
	s_nop 0
	v_readlane_b32 s6, v130, 63
	s_nop 1
	v_add_f32_e32 v130, s6, v179
	v_mul_f32_e32 v131, 0x4b800000, v130
	v_cmp_gt_f32_e32 vcc, s27, v130
	s_nop 1
	v_cndmask_b32_e32 v130, v130, v131, vcc
	v_rsq_f32_e32 v130, v130
	s_nop 0
	v_mul_f32_e32 v131, 0x45800000, v130
	v_cndmask_b32_e32 v130, v130, v131, vcc
	v_pk_mul_f32 v[128:129], v[128:129], v[130:131] op_sel_hi:[1,0]
	global_store_dwordx2 v[116:117], v[128:129], off offset:3072 sc1
	s_and_saveexec_b64 s[6:7], s[4:5]
	s_cbranch_execz .LBB0_269
	v_lshl_add_u64 v[128:129], v[68:69], 0, v[108:109]
	global_store_dwordx2 v[128:129], v[114:115], off sc1
.LBB0_269:
	s_or_b64 exec, exec, s[6:7]
	v_pk_fma_f32 v[118:119], v[118:119], v[126:127], 0 op_sel_hi:[1,1,0]
	v_lshlrev_b32_e32 v114, 16, v187
	v_pk_fma_f32 v[110:111], v[120:121], v[110:111], v[118:119]
	v_and_b32_e32 v115, 0xffff0000, v187
	v_pk_fma_f32 v[110:111], v[124:125], v[112:113], v[110:111]
	s_nop 0
	v_pk_fma_f32 v[110:111], v[122:123], v[114:115], v[110:111]
	s_nop 0
	v_mul_f32_e32 v112, 0xbfb8aa3b, v110
	v_mul_f32_e32 v113, 0xbfb8aa3b, v111
	v_exp_f32_e32 v112, v112
	v_exp_f32_e32 v113, v113
	s_nop 0
	v_pk_add_f32 v[112:113], v[112:113], 1.0 op_sel_hi:[1,0]
	s_nop 0
	v_div_scale_f32 v118, s[6:7], v113, v113, v111
	v_rcp_f32_e32 v119, v118
	s_nop 0
	v_fma_f32 v120, -v118, v119, 1.0
	v_fmac_f32_e32 v119, v120, v119
	v_div_scale_f32 v120, vcc, v111, v113, v111
	v_mul_f32_e32 v121, v120, v119
	v_fma_f32 v122, -v118, v121, v120
	v_fmac_f32_e32 v121, v122, v119
	v_fma_f32 v118, -v118, v121, v120
	v_div_scale_f32 v120, s[6:7], v112, v112, v110
	v_rcp_f32_e32 v122, v120
	v_div_fmas_f32 v118, v118, v119, v121
	v_div_fixup_f32 v111, v118, v113, v111
	v_fma_f32 v113, -v120, v122, 1.0
	v_fmac_f32_e32 v122, v113, v122
	v_div_scale_f32 v113, vcc, v110, v112, v110
	v_mul_f32_e32 v118, v113, v122
	v_fma_f32 v119, -v120, v118, v113
	v_fmac_f32_e32 v118, v119, v122
	v_fma_f32 v113, -v120, v118, v113
	v_div_fmas_f32 v113, v113, v122, v118
	v_div_fixup_f32 v110, v113, v112, v110
	v_pk_mul_f32 v[112:113], v[110:111], v[110:111]
	s_nop 0
	v_add_f32_e32 v112, v112, v113
	v_mov_b32_e32 v113, v3
	s_nop 0
	v_add_f32_dpp v112, v112, v112 quad_perm:[1,0,3,2] row_mask:0xf bank_mask:0xf bound_ctrl:1
	s_nop 1
	v_add_f32_dpp v112, v112, v112 quad_perm:[2,3,0,1] row_mask:0xf bank_mask:0xf bound_ctrl:1
	s_nop 1
	v_add_f32_dpp v112, v112, v112 row_half_mirror row_mask:0xf bank_mask:0xf bound_ctrl:1
	s_nop 1
	v_add_f32_dpp v112, v112, v112 row_mirror row_mask:0xf bank_mask:0xf bound_ctrl:1
	s_nop 1
	v_mov_b32_dpp v113, v112 row_bcast:15 row_mask:0xa bank_mask:0xf
	v_add_f32_e32 v112, v112, v113
	v_mov_b32_e32 v113, v3
	s_nop 1
	v_mov_b32_dpp v113, v112 row_bcast:31 row_mask:0xc bank_mask:0xf
	v_add_f32_e32 v112, v112, v113
	s_nop 0
	v_readlane_b32 s6, v112, 63
	s_nop 1
	v_add_f32_e32 v112, s6, v179
	v_mul_f32_e32 v113, 0x4b800000, v112
	v_cmp_gt_f32_e32 vcc, s27, v112
	s_nop 1
	v_cndmask_b32_e32 v112, v112, v113, vcc
	v_rsq_f32_e32 v112, v112
	s_nop 0
	v_mul_f32_e32 v113, 0x45800000, v112
	v_cndmask_b32_e32 v112, v112, v113, vcc
	v_pk_mul_f32 v[110:111], v[110:111], v[112:113] op_sel_hi:[1,0]
	global_store_dwordx2 v[116:117], v[110:111], off offset:3584 sc1
	s_and_saveexec_b64 s[6:7], s[4:5]
	s_cbranch_execz .LBB0_271
	v_lshl_add_u64 v[110:111], v[70:71], 0, v[108:109]
	global_store_dwordx2 v[110:111], v[114:115], off sc1
; DI float bflo(unsigned u) { return __uint_as_float(u << 16); }
; DI float bfhi(unsigned u) { return __uint_as_float(u & 0xffff0000u); }
; template <int G0>
; DI void qkv_run4_half(const Params& p, int row0, int lane) {
;     ...
;   for (int i = 0; i < 7; ++i) {
;     const int rr = (i >= 3 || t0 > 0) ? (row0 - 3 + i) : row0;
;     const bfr* rp = p.PB + (size_t)rr * EINP + 1536 + G0 * 128 + lane * 2;
; #pragma unroll
;     for (int g = 0; g < 4; ++g) u[g][i] = *(const unsigned*)(rp + g * 128);
;   }
; #pragma unroll
;   for (int j = 0; j < 4; ++j) {
;     const float* wp = p.sc_w + (size_t)j * 1536 + G0 * 128 + lane * 2;
; #pragma unroll
;     for (int g = 0; g < 4; ++g) w[g][j] = *(const float2*)(wp + g * 128);
;   }
;   const float hm = (t0 > 0) ? 1.f : 0.f;
; #pragma unroll
;   for (int k = 0; k < 4; ++k) {
;     const int row = row0 + k;
; #pragma unroll
;     for (int g = 0; g < 4; ++g) {
;       const int grp = G0 + g;
;       const int ch = grp * 128 + lane * 2;
;       float a0 = 0.f, a1 = 0.f;
; #pragma unroll
;       for (int j = 0; j < 4; ++j) {
;         const int i = k + j;
;         const float m = (i >= 3) ? 1.f : hm;
;         a0 += w[g][j].x * (bflo(u[g][i]) * m);
;         a1 += w[g][j].y * (bfhi(u[g][i]) * m);
.LBB0_271:
	s_or_b64 exec, exec, s[6:7]
	v_lshl_add_u64 v[102:103], v[102:103], 0, v[2:3]
	v_add_co_u32_e32 v110, vcc, 0x1000, v102
	v_lshl_add_u64 v[100:101], v[100:101], 0, v[2:3]
	s_nop 0
	v_addc_co_u32_e32 v111, vcc, 0, v103, vcc
	v_add_co_u32_e32 v112, vcc, 0x1000, v100
	v_lshl_add_u64 v[98:99], v[98:99], 0, v[2:3]
	s_nop 0
	v_addc_co_u32_e32 v113, vcc, 0, v101, vcc
	global_load_dword v120, v[110:111], off offset:1024
	global_load_dword v121, v[112:113], off offset:1024
	v_add_co_u32_e32 v110, vcc, 0x1000, v98
	v_lshl_add_u64 v[96:97], v[96:97], 0, v[2:3]
	s_nop 0
	v_addc_co_u32_e32 v111, vcc, 0, v99, vcc
	v_lshl_add_u64 v[102:103], v[102:103], 0, s[20:21]
	global_load_dword v122, v[110:111], off offset:1024
	global_load_dword v123, v[102:103], off offset:256
	v_add_co_u32_e32 v110, vcc, 0x1000, v96
	v_lshl_add_u64 v[100:101], v[100:101], 0, s[20:21]
	s_nop 0
	v_addc_co_u32_e32 v111, vcc, 0, v97, vcc
	global_load_dword v110, v[110:111], off offset:1024
	v_lshl_add_u64 v[98:99], v[98:99], 0, s[20:21]
	global_load_dword v124, v[100:101], off offset:256
	global_load_dword v125, v[98:99], off offset:256
	v_lshl_add_u64 v[96:97], v[96:97], 0, s[20:21]
	global_load_dword v128, v[96:97], off offset:256
	global_load_dword v129, v[102:103], off offset:512
	global_load_dword v130, v[100:101], off offset:512
	global_load_dword v131, v[98:99], off offset:512
	global_load_dword v132, v[96:97], off offset:512
	global_load_dword v133, v[100:101], off offset:768
	global_load_dword v134, v[102:103], off offset:768
	global_load_dword v169, v[96:97], off offset:768
	global_load_dword v135, v[98:99], off offset:768
	global_load_dwordx2 v[114:115], v[40:41], off offset:512
	global_load_dwordx2 v[116:117], v[42:43], off offset:512
	global_load_dwordx2 v[118:119], v[44:45], off offset:512
	global_load_dwordx2 v[112:113], v[46:47], off offset:512
	v_lshl_add_u64 v[96:97], v[106:107], 0, v[2:3]
	v_lshl_add_u64 v[98:99], v[96:97], 0, s[20:21]
	v_add_co_u32_e32 v96, vcc, 0x1000, v96
	v_lshl_add_u64 v[100:101], v[104:105], 0, v[2:3]
	s_nop 0
	v_addc_co_u32_e32 v97, vcc, 0, v97, vcc
	v_lshl_add_u64 v[102:103], v[100:101], 0, s[20:21]
	v_add_co_u32_e32 v100, vcc, 0x1000, v100
	v_lshl_add_u64 v[92:93], v[92:93], 0, v[2:3]
	s_nop 0
	v_addc_co_u32_e32 v101, vcc, 0, v101, vcc
	v_mad_i64_i32 v[136:137], s[6:7], v185, s26, 0
	global_load_dword v185, v[96:97], off offset:1024
	global_load_dword v168, v[98:99], off offset:256
	global_load_dword v167, v[98:99], off offset:512
	global_load_dword v165, v[100:101], off offset:1024
	global_load_dword v164, v[102:103], off offset:256
	global_load_dword v163, v[102:103], off offset:512
	global_load_dword v162, v[102:103], off offset:768
	global_load_dword v166, v[98:99], off offset:768
	v_lshl_add_u64 v[96:97], v[92:93], 0, s[20:21]
	v_add_co_u32_e32 v92, vcc, 0x1000, v92
	v_mad_i64_i32 v[142:143], s[6:7], v186, s26, 0
	s_nop 0
	v_addc_co_u32_e32 v93, vcc, 0, v93, vcc
	global_load_dword v161, v[92:93], off offset:1024
	global_load_dword v160, v[96:97], off offset:256
	global_load_dword v159, v[96:97], off offset:512
	global_load_dword v158, v[96:97], off offset:768
	v_lshl_add_u64 v[150:151], v[48:49], 0, v[136:137]
	v_lshl_add_u64 v[172:173], v[50:51], 0, v[136:137]
	v_lshl_add_u64 v[176:177], v[52:53], 0, v[136:137]
	v_lshl_add_u64 v[192:193], v[54:55], 0, v[136:137]
	s_waitcnt vmcnt(31)
	v_lshlrev_b32_e32 v156, 16, v120
	v_and_b32_e32 v157, 0xffff0000, v120
	s_waitcnt vmcnt(30)
	v_lshlrev_b32_e32 v170, 16, v121
	v_and_b32_e32 v171, 0xffff0000, v121
	v_pk_mul_f32 v[170:171], v[90:91], v[170:171]
	s_waitcnt vmcnt(29)
	v_lshlrev_b32_e32 v92, 16, v122
	v_and_b32_e32 v93, 0xffff0000, v122
	v_pk_mul_f32 v[146:147], v[90:91], v[92:93]
	s_waitcnt vmcnt(28)
	v_lshlrev_b32_e32 v120, 16, v123
	v_and_b32_e32 v121, 0xffff0000, v123
	v_pk_mul_f32 v[120:121], v[90:91], v[120:121]
	s_waitcnt vmcnt(27)
	v_lshlrev_b32_e32 v126, 16, v110
	v_and_b32_e32 v127, 0xffff0000, v110
	global_load_dwordx2 v[104:105], v[40:41], off offset:1024
	global_load_dwordx2 v[106:107], v[42:43], off offset:1024
	global_load_dwordx2 v[110:111], v[44:45], off offset:1024
	global_load_dwordx2 v[102:103], v[46:47], off offset:1024
	s_waitcnt vmcnt(30)
	v_lshlrev_b32_e32 v92, 16, v124
	v_and_b32_e32 v93, 0xffff0000, v124
	v_pk_mul_f32 v[148:149], v[90:91], v[92:93]
	s_waitcnt vmcnt(29)
	v_lshlrev_b32_e32 v92, 16, v125
	v_and_b32_e32 v93, 0xffff0000, v125
	v_pk_mul_f32 v[144:145], v[90:91], v[92:93]
	s_waitcnt vmcnt(26)
	v_lshlrev_b32_e32 v92, 16, v130
	v_and_b32_e32 v93, 0xffff0000, v130
	v_pk_mul_f32 v[154:155], v[90:91], v[92:93]
	s_waitcnt vmcnt(25)
	v_lshlrev_b32_e32 v92, 16, v131
	v_and_b32_e32 v93, 0xffff0000, v131
	v_pk_mul_f32 v[140:141], v[90:91], v[92:93]
	s_waitcnt vmcnt(23)
	v_lshlrev_b32_e32 v92, 16, v133
	v_and_b32_e32 v93, 0xffff0000, v133
	v_lshlrev_b32_e32 v124, 16, v128
	v_and_b32_e32 v125, 0xffff0000, v128
	v_lshlrev_b32_e32 v174, 16, v129
	v_and_b32_e32 v175, 0xffff0000, v129
	v_lshlrev_b32_e32 v122, 16, v132
	v_and_b32_e32 v123, 0xffff0000, v132
	s_waitcnt vmcnt(22)
	v_lshlrev_b32_e32 v186, 16, v134
	v_and_b32_e32 v187, 0xffff0000, v134
	v_pk_mul_f32 v[152:153], v[90:91], v[92:93]
	s_waitcnt vmcnt(20)
	v_lshlrev_b32_e32 v138, 16, v135
	v_and_b32_e32 v139, 0xffff0000, v135
	global_load_dwordx2 v[92:93], v[40:41], off offset:1536
	global_load_dwordx2 v[128:129], v[40:41], off
	global_load_dwordx2 v[96:97], v[42:43], off offset:1536
	global_load_dwordx2 v[130:131], v[42:43], off
	global_load_dwordx2 v[100:101], v[44:45], off offset:1536
	global_load_dwordx2 v[134:135], v[44:45], off
	global_load_dwordx2 v[98:99], v[46:47], off offset:1536
	global_load_dwordx2 v[132:133], v[46:47], off
	s_waitcnt vmcnt(27)
; DI float bflo(unsigned u) { return __uint_as_float(u << 16); }
; DI float bfhi(unsigned u) { return __uint_as_float(u & 0xffff0000u); }
; DI float siluf_(float x) { return x / (1.0f + __expf(-x)); }
; template <int G0>
; DI void qkv_run4_half(const Params& p, int row0, int lane) {
;     ...
;     for (int g = 0; g < 4; ++g) {
;       const int grp = G0 + g;
;       const int ch = grp * 128 + lane * 2;
;       float a0 = 0.f, a1 = 0.f;
; #pragma unroll
;       for (int j = 0; j < 4; ++j) {
;         const int i = k + j;
;         const float m = (i >= 3) ? 1.f : hm;
;         a0 += w[g][j].x * (bflo(u[g][i]) * m);
;         a1 += w[g][j].y * (bfhi(u[g][i]) * m);
;       }
;       float y0 = siluf_(a0), y1 = siluf_(a1);
;       if (grp < 8) {
;         float ss = wave_sum(y0 * y0 + y1 * y1);
;         float inv = rsqrtf(ss + EPSF);
;         if (grp < 4) inv *= 0.08838834764831845f;
;         y0 *= inv; y1 *= inv;
;       }
;       float2 o = {y0, y1};
;       *(float2*)(p.QKV + (size_t)row * 1536 + ch) = o;
;       if (t0 == 2044 && k >= 1) {
;         float2 c = {bflo(u[g][k + 3]), bfhi(u[g][k + 3])};
;         *(float2*)(p.out + O_QKVP + ((size_t)b * 3 + (k - 1)) * 1536 + ch) = c;
;       }
	v_pk_fma_f32 v[120:121], v[120:121], v[114:115], 0 op_sel_hi:[1,1,0]
	s_waitcnt vmcnt(23)
	v_lshlrev_b32_e32 v136, 16, v185
	v_pk_fma_f32 v[120:121], v[148:149], v[116:117], v[120:121]
	v_and_b32_e32 v137, 0xffff0000, v185
	v_pk_fma_f32 v[120:121], v[144:145], v[118:119], v[120:121]
	v_pk_mul_f32 v[174:175], v[90:91], v[174:175]
	v_pk_fma_f32 v[188:189], v[112:113], v[124:125], v[120:121]
	v_and_b32_e32 v121, 0xffff0000, v169
	v_mul_f32_e32 v120, 0xbfb8aa3b, v188
	v_exp_f32_e32 v190, v120
	v_mul_f32_e32 v120, 0xbfb8aa3b, v189
	v_exp_f32_e32 v191, v120
	v_lshlrev_b32_e32 v120, 16, v169
	v_pk_mul_f32 v[186:187], v[90:91], v[186:187]
	v_pk_mul_f32 v[138:139], v[90:91], v[138:139]
	v_pk_add_f32 v[190:191], v[190:191], 1.0 op_sel_hi:[1,0]
	v_pk_mul_f32 v[90:91], v[90:91], v[156:157]
	v_div_scale_f32 v169, s[6:7], v191, v191, v189
	v_rcp_f32_e32 v194, v169
	s_waitcnt vmcnt(11)
	v_pk_fma_f32 v[174:175], v[174:175], v[104:105], 0 op_sel_hi:[1,1,0]
	v_fma_f32 v185, -v169, v194, 1.0
	v_fmac_f32_e32 v194, v185, v194
	v_div_scale_f32 v185, vcc, v189, v191, v189
	v_mul_f32_e32 v195, v185, v194
	v_fma_f32 v197, -v169, v195, v185
	v_fmac_f32_e32 v195, v197, v194
	v_fma_f32 v169, -v169, v195, v185
	v_div_scale_f32 v185, s[6:7], v190, v190, v188
	v_rcp_f32_e32 v197, v185
	s_waitcnt vmcnt(10)
	v_pk_fma_f32 v[174:175], v[154:155], v[106:107], v[174:175]
	v_div_fmas_f32 v169, v169, v194, v195
	s_waitcnt vmcnt(9)
	v_pk_fma_f32 v[174:175], v[140:141], v[110:111], v[174:175]
	v_div_fixup_f32 v189, v169, v191, v189
	s_waitcnt vmcnt(8)
	v_pk_fma_f32 v[174:175], v[102:103], v[122:123], v[174:175]
	v_fma_f32 v169, -v185, v197, 1.0
	v_mul_f32_e32 v194, 0xbfb8aa3b, v174
	v_mul_f32_e32 v195, 0xbfb8aa3b, v175
	v_exp_f32_e32 v194, v194
	v_exp_f32_e32 v195, v195
	v_fmac_f32_e32 v197, v169, v197
	v_div_scale_f32 v169, vcc, v188, v190, v188
	v_mul_f32_e32 v191, v169, v197
	v_fma_f32 v198, -v185, v191, v169
	v_fmac_f32_e32 v191, v198, v197
	v_pk_add_f32 v[194:195], v[194:195], 1.0 op_sel_hi:[1,0]
	v_fma_f32 v169, -v185, v191, v169
	v_div_scale_f32 v185, s[6:7], v195, v195, v175
	v_rcp_f32_e32 v198, v185
	v_div_fmas_f32 v169, v169, v197, v191
	v_div_fixup_f32 v188, v169, v190, v188
	global_store_dwordx2 v[172:173], v[188:189], off sc1
	v_fma_f32 v169, -v185, v198, 1.0
	v_fmac_f32_e32 v198, v169, v198
	v_div_scale_f32 v169, vcc, v175, v195, v175
	v_mul_f32_e32 v172, v169, v198
	v_fma_f32 v173, -v185, v172, v169
	s_waitcnt vmcnt(8)
	v_pk_fma_f32 v[186:187], v[186:187], v[92:93], 0 op_sel_hi:[1,1,0]
	v_fmac_f32_e32 v172, v173, v198
	s_waitcnt vmcnt(6)
	v_pk_fma_f32 v[186:187], v[152:153], v[96:97], v[186:187]
	v_fma_f32 v169, -v185, v172, v169
	v_div_scale_f32 v185, s[6:7], v194, v194, v174
	s_waitcnt vmcnt(4)
	v_pk_fma_f32 v[186:187], v[138:139], v[100:101], v[186:187]
	v_rcp_f32_e32 v190, v185
	v_div_fmas_f32 v169, v169, v198, v172
	s_waitcnt vmcnt(2)
	v_pk_fma_f32 v[186:187], v[98:99], v[120:121], v[186:187]
	v_div_fixup_f32 v173, v169, v195, v175
	v_mul_f32_e32 v175, 0xbfb8aa3b, v186
	v_exp_f32_e32 v188, v175
	v_mul_f32_e32 v175, 0xbfb8aa3b, v187
	v_exp_f32_e32 v189, v175
	v_fma_f32 v169, -v185, v190, 1.0
	v_fmac_f32_e32 v190, v169, v190
	v_div_scale_f32 v169, vcc, v174, v194, v174
	v_mul_f32_e32 v172, v169, v190
	v_fma_f32 v175, -v185, v172, v169
	v_pk_add_f32 v[188:189], v[188:189], 1.0 op_sel_hi:[1,0]
	v_fmac_f32_e32 v172, v175, v190
	v_div_scale_f32 v175, s[6:7], v189, v189, v187
	v_fma_f32 v169, -v185, v172, v169
	v_rcp_f32_e32 v185, v175
	v_div_fmas_f32 v169, v169, v190, v172
	v_div_fixup_f32 v172, v169, v194, v174
	global_store_dwordx2 v[176:177], v[172:173], off sc1
	v_fma_f32 v169, -v175, v185, 1.0
	v_fmac_f32_e32 v185, v169, v185
	v_div_scale_f32 v169, vcc, v187, v189, v187
	v_mul_f32_e32 v172, v169, v185
	v_fma_f32 v173, -v175, v172, v169
	v_fmac_f32_e32 v172, v173, v185
	v_div_scale_f32 v174, s[6:7], v188, v188, v186
	v_pk_fma_f32 v[90:91], v[90:91], v[128:129], 0 op_sel_hi:[1,1,0]
	v_fma_f32 v169, -v175, v172, v169
	v_rcp_f32_e32 v175, v174
	v_pk_fma_f32 v[90:91], v[170:171], v[130:131], v[90:91]
	v_div_fmas_f32 v169, v169, v185, v172
	v_pk_fma_f32 v[90:91], v[146:147], v[134:135], v[90:91]
	v_div_fixup_f32 v173, v169, v189, v187
	s_waitcnt vmcnt(2)
	v_pk_fma_f32 v[90:91], v[132:133], v[126:127], v[90:91]
	v_fma_f32 v169, -v174, v175, 1.0
	v_mul_f32_e32 v156, 0xbfb8aa3b, v90
	v_mul_f32_e32 v157, 0xbfb8aa3b, v91
	v_exp_f32_e32 v156, v156
	v_exp_f32_e32 v157, v157
	v_fmac_f32_e32 v175, v169, v175
	v_div_scale_f32 v169, vcc, v186, v188, v186
	v_mul_f32_e32 v172, v169, v175
	v_fma_f32 v176, -v174, v172, v169
	v_fmac_f32_e32 v172, v176, v175
	v_pk_add_f32 v[156:157], v[156:157], 1.0 op_sel_hi:[1,0]
	v_fma_f32 v169, -v174, v172, v169
	v_div_scale_f32 v174, s[6:7], v157, v157, v91
	v_div_fmas_f32 v169, v169, v175, v172
	v_rcp_f32_e32 v175, v174
	v_div_fixup_f32 v172, v169, v188, v186
	v_pk_fma_f32 v[170:171], v[170:171], v[128:129], 0 op_sel_hi:[1,1,0]
	global_store_dwordx2 v[192:193], v[172:173], off sc1
	v_fma_f32 v169, -v174, v175, 1.0
	v_fmac_f32_e32 v175, v169, v175
	v_div_scale_f32 v169, vcc, v91, v157, v91
	v_mul_f32_e32 v176, v169, v175
	v_fma_f32 v177, -v174, v176, v169
	v_fmac_f32_e32 v176, v177, v175
	v_div_scale_f32 v177, s[6:7], v156, v156, v90
	v_pk_fma_f32 v[170:171], v[146:147], v[130:131], v[170:171]
	v_rcp_f32_e32 v185, v177
	v_pk_fma_f32 v[170:171], v[134:135], v[126:127], v[170:171]
	v_fma_f32 v169, -v174, v176, v169
	v_pk_fma_f32 v[170:171], v[132:133], v[136:137], v[170:171]
	v_div_fmas_f32 v169, v169, v175, v176
	v_mul_f32_e32 v174, 0xbfb8aa3b, v170
	v_mul_f32_e32 v175, 0xbfb8aa3b, v171
	v_exp_f32_e32 v174, v174
	v_exp_f32_e32 v175, v175
	v_div_fixup_f32 v91, v169, v157, v91
	v_fma_f32 v157, -v177, v185, 1.0
	v_fmac_f32_e32 v185, v157, v185
	v_div_scale_f32 v157, vcc, v90, v156, v90
	v_mul_f32_e32 v169, v157, v185
	v_fma_f32 v176, -v177, v169, v157
	v_pk_add_f32 v[174:175], v[174:175], 1.0 op_sel_hi:[1,0]
	v_fmac_f32_e32 v169, v176, v185
	v_div_scale_f32 v176, s[6:7], v175, v175, v171
	v_fma_f32 v157, -v177, v169, v157
	v_rcp_f32_e32 v177, v176
	v_div_fmas_f32 v157, v157, v185, v169
	v_div_fixup_f32 v90, v157, v156, v90
	global_store_dwordx2 v[150:151], v[90:91], off sc1
	v_fma_f32 v90, -v176, v177, 1.0
	v_fmac_f32_e32 v177, v90, v177
	v_div_scale_f32 v90, vcc, v171, v175, v171
	v_mul_f32_e32 v91, v90, v177
	v_fma_f32 v150, -v176, v91, v90
	v_fmac_f32_e32 v91, v150, v177
	v_div_scale_f32 v150, s[6:7], v174, v174, v170
	v_rcp_f32_e32 v151, v150
	v_fma_f32 v90, -v176, v91, v90
	v_div_fmas_f32 v90, v90, v177, v91
	v_div_fixup_f32 v91, v90, v175, v171
	v_fma_f32 v90, -v150, v151, 1.0
	v_fmac_f32_e32 v151, v90, v151
	v_div_scale_f32 v90, vcc, v170, v174, v170
	v_mul_f32_e32 v156, v90, v151
	v_fma_f32 v157, -v150, v156, v90
	v_fmac_f32_e32 v156, v157, v151
	v_fma_f32 v90, -v150, v156, v90
	v_div_fmas_f32 v90, v90, v151, v156
	v_lshl_add_u64 v[172:173], v[48:49], 0, v[142:143]
	v_div_fixup_f32 v90, v90, v174, v170
	global_store_dwordx2 v[172:173], v[90:91], off sc1
	s_and_saveexec_b64 s[6:7], s[4:5]
	s_cbranch_execz .LBB0_273
; DI float bflo(unsigned u) { return __uint_as_float(u << 16); }
; DI float bfhi(unsigned u) { return __uint_as_float(u & 0xffff0000u); }
; DI float siluf_(float x) { return x / (1.0f + __expf(-x)); }
; template <int G0>
; DI void qkv_run4_half(const Params& p, int row0, int lane) {
;     ...
;     for (int g = 0; g < 4; ++g) {
;       const int grp = G0 + g;
;       const int ch = grp * 128 + lane * 2;
;       float a0 = 0.f, a1 = 0.f;
; #pragma unroll
;       for (int j = 0; j < 4; ++j) {
;         const int i = k + j;
;         const float m = (i >= 3) ? 1.f : hm;
;         a0 += w[g][j].x * (bflo(u[g][i]) * m);
;         a1 += w[g][j].y * (bfhi(u[g][i]) * m);
;       }
;       float y0 = siluf_(a0), y1 = siluf_(a1);
;       if (grp < 8) {
;         float ss = wave_sum(y0 * y0 + y1 * y1);
;         float inv = rsqrtf(ss + EPSF);
;         if (grp < 4) inv *= 0.08838834764831845f;
;         y0 *= inv; y1 *= inv;
;       }
;       float2 o = {y0, y1};
;       *(float2*)(p.QKV + (size_t)row * 1536 + ch) = o;
;       if (t0 == 2044 && k >= 1) {
;         float2 c = {bflo(u[g][k + 3]), bfhi(u[g][k + 3])};
;         *(float2*)(p.out + O_QKVP + ((size_t)b * 3 + (k - 1)) * 1536 + ch) = c;
;       }
	v_lshl_add_u64 v[90:91], v[72:73], 0, v[88:89]
	global_store_dwordx2 v[90:91], v[136:137], off sc1
.LBB0_273:
	s_or_b64 exec, exec, s[6:7]
	v_pk_fma_f32 v[90:91], v[148:149], v[114:115], 0 op_sel_hi:[1,1,0]
	v_lshlrev_b32_e32 v150, 16, v168
	v_pk_fma_f32 v[90:91], v[144:145], v[116:117], v[90:91]
	v_and_b32_e32 v151, 0xffff0000, v168
	v_pk_fma_f32 v[90:91], v[118:119], v[124:125], v[90:91]
	v_lshl_add_u64 v[156:157], v[50:51], 0, v[142:143]
	v_pk_fma_f32 v[90:91], v[112:113], v[150:151], v[90:91]
	s_nop 0
	v_mul_f32_e32 v148, 0xbfb8aa3b, v90
	v_mul_f32_e32 v149, 0xbfb8aa3b, v91
	v_exp_f32_e32 v148, v148
	v_exp_f32_e32 v149, v149
	s_nop 0
	v_pk_add_f32 v[148:149], v[148:149], 1.0 op_sel_hi:[1,0]
	s_nop 0
	v_div_scale_f32 v168, s[6:7], v149, v149, v91
	v_rcp_f32_e32 v169, v168
	s_nop 0
	v_fma_f32 v170, -v168, v169, 1.0
	v_fmac_f32_e32 v169, v170, v169
	v_div_scale_f32 v170, vcc, v91, v149, v91
	v_mul_f32_e32 v171, v170, v169
	v_fma_f32 v172, -v168, v171, v170
	v_fmac_f32_e32 v171, v172, v169
	v_fma_f32 v168, -v168, v171, v170
	v_div_scale_f32 v170, s[6:7], v148, v148, v90
	v_rcp_f32_e32 v172, v170
	v_div_fmas_f32 v168, v168, v169, v171
	v_div_fixup_f32 v91, v168, v149, v91
	v_fma_f32 v149, -v170, v172, 1.0
	v_fmac_f32_e32 v172, v149, v172
	v_div_scale_f32 v149, vcc, v90, v148, v90
	v_mul_f32_e32 v168, v149, v172
	v_fma_f32 v169, -v170, v168, v149
	v_fmac_f32_e32 v168, v169, v172
	v_fma_f32 v149, -v170, v168, v149
	v_div_fmas_f32 v149, v149, v172, v168
	v_div_fixup_f32 v90, v149, v148, v90
	global_store_dwordx2 v[156:157], v[90:91], off sc1
	s_and_saveexec_b64 s[6:7], s[4:5]
	s_cbranch_execz .LBB0_275
	v_lshl_add_u64 v[90:91], v[74:75], 0, v[88:89]
	global_store_dwordx2 v[90:91], v[150:151], off sc1
.LBB0_275:
	s_or_b64 exec, exec, s[6:7]
	v_pk_fma_f32 v[90:91], v[154:155], v[104:105], 0 op_sel_hi:[1,1,0]
	v_lshlrev_b32_e32 v148, 16, v167
	v_pk_fma_f32 v[90:91], v[140:141], v[106:107], v[90:91]
	v_and_b32_e32 v149, 0xffff0000, v167
	v_pk_fma_f32 v[90:91], v[110:111], v[122:123], v[90:91]
	v_lshl_add_u64 v[156:157], v[52:53], 0, v[142:143]
	v_pk_fma_f32 v[90:91], v[102:103], v[148:149], v[90:91]
	s_nop 0
	v_mul_f32_e32 v154, 0xbfb8aa3b, v90
	v_mul_f32_e32 v155, 0xbfb8aa3b, v91
	v_exp_f32_e32 v154, v154
	v_exp_f32_e32 v155, v155
	s_nop 0
	v_pk_add_f32 v[154:155], v[154:155], 1.0 op_sel_hi:[1,0]
	s_nop 0
	v_div_scale_f32 v167, s[6:7], v155, v155, v91
	v_rcp_f32_e32 v168, v167
	s_nop 0
	v_fma_f32 v169, -v167, v168, 1.0
	v_fmac_f32_e32 v168, v169, v168
	v_div_scale_f32 v169, vcc, v91, v155, v91
	v_mul_f32_e32 v170, v169, v168
	v_fma_f32 v171, -v167, v170, v169
	v_fmac_f32_e32 v170, v171, v168
	v_fma_f32 v167, -v167, v170, v169
	v_div_scale_f32 v169, s[6:7], v154, v154, v90
	v_rcp_f32_e32 v171, v169
	v_div_fmas_f32 v167, v167, v168, v170
	v_div_fixup_f32 v91, v167, v155, v91
	v_fma_f32 v155, -v169, v171, 1.0
	v_fmac_f32_e32 v171, v155, v171
	v_div_scale_f32 v155, vcc, v90, v154, v90
	v_mul_f32_e32 v167, v155, v171
	v_fma_f32 v168, -v169, v167, v155
	v_fmac_f32_e32 v167, v168, v171
	v_fma_f32 v155, -v169, v167, v155
	v_div_fmas_f32 v155, v155, v171, v167
	v_div_fixup_f32 v90, v155, v154, v90
	global_store_dwordx2 v[156:157], v[90:91], off sc1
	s_and_saveexec_b64 s[6:7], s[4:5]
	s_cbranch_execz .LBB0_277
	v_lshl_add_u64 v[90:91], v[76:77], 0, v[88:89]
	global_store_dwordx2 v[90:91], v[148:149], off sc1
.LBB0_277:
	s_or_b64 exec, exec, s[6:7]
	v_pk_fma_f32 v[152:153], v[152:153], v[92:93], 0 op_sel_hi:[1,1,0]
	v_lshlrev_b32_e32 v90, 16, v166
	v_pk_fma_f32 v[152:153], v[138:139], v[96:97], v[152:153]
	v_and_b32_e32 v91, 0xffff0000, v166
	v_pk_fma_f32 v[152:153], v[100:101], v[120:121], v[152:153]
	v_lshl_add_u64 v[142:143], v[54:55], 0, v[142:143]
	v_pk_fma_f32 v[152:153], v[98:99], v[90:91], v[152:153]
	s_nop 0
	v_mul_f32_e32 v154, 0xbfb8aa3b, v152
	v_mul_f32_e32 v155, 0xbfb8aa3b, v153
	v_exp_f32_e32 v154, v154
	v_exp_f32_e32 v155, v155
	s_nop 0
	v_pk_add_f32 v[154:155], v[154:155], 1.0 op_sel_hi:[1,0]
	s_nop 0
	v_div_scale_f32 v156, s[6:7], v155, v155, v153
	v_rcp_f32_e32 v157, v156
	s_nop 0
	v_fma_f32 v166, -v156, v157, 1.0
	v_fmac_f32_e32 v157, v166, v157
	v_div_scale_f32 v166, vcc, v153, v155, v153
	v_mul_f32_e32 v167, v166, v157
	v_fma_f32 v168, -v156, v167, v166
	v_fmac_f32_e32 v167, v168, v157
	v_fma_f32 v156, -v156, v167, v166
	v_div_scale_f32 v166, s[6:7], v154, v154, v152
	v_rcp_f32_e32 v168, v166
	v_div_fmas_f32 v156, v156, v157, v167
	v_div_fixup_f32 v153, v156, v155, v153
	v_fma_f32 v155, -v166, v168, 1.0
	v_fmac_f32_e32 v168, v155, v168
	v_div_scale_f32 v155, vcc, v152, v154, v152
	v_mul_f32_e32 v156, v155, v168
	v_fma_f32 v157, -v166, v156, v155
	v_fmac_f32_e32 v156, v157, v168
	v_fma_f32 v155, -v166, v156, v155
	v_div_fmas_f32 v155, v155, v168, v156
	v_div_fixup_f32 v152, v155, v154, v152
	global_store_dwordx2 v[142:143], v[152:153], off sc1
	s_and_saveexec_b64 s[6:7], s[4:5]
	s_cbranch_execz .LBB0_279
	v_lshl_add_u64 v[88:89], v[78:79], 0, v[88:89]
	global_store_dwordx2 v[88:89], v[90:91], off sc1
; DI float bflo(unsigned u) { return __uint_as_float(u << 16); }
; DI float bfhi(unsigned u) { return __uint_as_float(u & 0xffff0000u); }
; DI float siluf_(float x) { return x / (1.0f + __expf(-x)); }
; template <int G0>
; DI void qkv_run4_half(const Params& p, int row0, int lane) {
;     ...
;     for (int g = 0; g < 4; ++g) {
;       const int grp = G0 + g;
;       const int ch = grp * 128 + lane * 2;
;       float a0 = 0.f, a1 = 0.f;
; #pragma unroll
;       for (int j = 0; j < 4; ++j) {
;         const int i = k + j;
;         const float m = (i >= 3) ? 1.f : hm;
;         a0 += w[g][j].x * (bflo(u[g][i]) * m);
;         a1 += w[g][j].y * (bfhi(u[g][i]) * m);
;       }
;       float y0 = siluf_(a0), y1 = siluf_(a1);
;       if (grp < 8) {
;         float ss = wave_sum(y0 * y0 + y1 * y1);
;         float inv = rsqrtf(ss + EPSF);
;         if (grp < 4) inv *= 0.08838834764831845f;
;         y0 *= inv; y1 *= inv;
;       }
;       float2 o = {y0, y1};
;       *(float2*)(p.QKV + (size_t)row * 1536 + ch) = o;
;       if (t0 == 2044 && k >= 1) {
;         float2 c = {bflo(u[g][k + 3]), bfhi(u[g][k + 3])};
;         *(float2*)(p.out + O_QKVP + ((size_t)b * 3 + (k - 1)) * 1536 + ch) = c;
;       }
.LBB0_279:
	s_or_b64 exec, exec, s[6:7]
	v_pk_fma_f32 v[88:89], v[146:147], v[128:129], 0 op_sel_hi:[1,1,0]
	v_lshlrev_b32_e32 v152, 16, v165
	v_pk_fma_f32 v[88:89], v[130:131], v[126:127], v[88:89]
	v_and_b32_e32 v153, 0xffff0000, v165
	v_pk_fma_f32 v[88:89], v[134:135], v[136:137], v[88:89]
	v_mad_i64_i32 v[154:155], s[6:7], v87, s26, 0
	v_pk_fma_f32 v[88:89], v[132:133], v[152:153], v[88:89]
	v_lshl_add_u64 v[146:147], v[48:49], 0, v[154:155]
	v_mul_f32_e32 v142, 0xbfb8aa3b, v88
	v_mul_f32_e32 v143, 0xbfb8aa3b, v89
	v_exp_f32_e32 v142, v142
	v_exp_f32_e32 v143, v143
	s_nop 0
	v_pk_add_f32 v[142:143], v[142:143], 1.0 op_sel_hi:[1,0]
	s_nop 0
	v_div_scale_f32 v156, s[6:7], v143, v143, v89
	v_rcp_f32_e32 v157, v156
	s_nop 0
	v_fma_f32 v87, -v156, v157, 1.0
	v_fmac_f32_e32 v157, v87, v157
	v_div_scale_f32 v87, vcc, v89, v143, v89
	v_mul_f32_e32 v165, v87, v157
	v_fma_f32 v166, -v156, v165, v87
	v_fmac_f32_e32 v165, v166, v157
	v_fma_f32 v87, -v156, v165, v87
	v_div_scale_f32 v156, s[6:7], v142, v142, v88
	v_rcp_f32_e32 v166, v156
	v_div_fmas_f32 v87, v87, v157, v165
	v_div_fixup_f32 v89, v87, v143, v89
	v_fma_f32 v87, -v156, v166, 1.0
	v_fmac_f32_e32 v166, v87, v166
	v_div_scale_f32 v87, vcc, v88, v142, v88
	v_mul_f32_e32 v143, v87, v166
	v_fma_f32 v157, -v156, v143, v87
	v_fmac_f32_e32 v143, v157, v166
	v_fma_f32 v87, -v156, v143, v87
	v_div_fmas_f32 v87, v87, v166, v143
	v_div_fixup_f32 v88, v87, v142, v88
	global_store_dwordx2 v[146:147], v[88:89], off sc1
	s_and_saveexec_b64 s[6:7], s[4:5]
	s_cbranch_execz .LBB0_281
	v_lshl_add_u64 v[88:89], v[72:73], 0, v[94:95]
	global_store_dwordx2 v[88:89], v[152:153], off sc1
.LBB0_281:
	s_or_b64 exec, exec, s[6:7]
	v_pk_fma_f32 v[88:89], v[144:145], v[114:115], 0 op_sel_hi:[1,1,0]
	v_lshlrev_b32_e32 v146, 16, v164
	v_pk_fma_f32 v[88:89], v[116:117], v[124:125], v[88:89]
	v_and_b32_e32 v147, 0xffff0000, v164
	v_pk_fma_f32 v[88:89], v[118:119], v[150:151], v[88:89]
	v_lshl_add_u64 v[144:145], v[50:51], 0, v[154:155]
	v_pk_fma_f32 v[88:89], v[112:113], v[146:147], v[88:89]
	s_nop 0
	v_mul_f32_e32 v87, 0xbfb8aa3b, v88
	v_exp_f32_e32 v142, v87
	v_mul_f32_e32 v87, 0xbfb8aa3b, v89
	v_exp_f32_e32 v143, v87
	s_nop 0
	v_pk_add_f32 v[142:143], v[142:143], 1.0 op_sel_hi:[1,0]
	s_nop 0
	v_div_scale_f32 v87, s[6:7], v143, v143, v89
	v_rcp_f32_e32 v156, v87
	s_nop 0
	v_fma_f32 v157, -v87, v156, 1.0
	v_fmac_f32_e32 v156, v157, v156
	v_div_scale_f32 v157, vcc, v89, v143, v89
	v_mul_f32_e32 v164, v157, v156
	v_fma_f32 v165, -v87, v164, v157
	v_fmac_f32_e32 v164, v165, v156
	v_fma_f32 v87, -v87, v164, v157
	v_div_scale_f32 v157, s[6:7], v142, v142, v88
	v_rcp_f32_e32 v165, v157
	v_div_fmas_f32 v87, v87, v156, v164
	v_div_fixup_f32 v89, v87, v143, v89
	v_fma_f32 v87, -v157, v165, 1.0
	v_fmac_f32_e32 v165, v87, v165
	v_div_scale_f32 v87, vcc, v88, v142, v88
	v_mul_f32_e32 v143, v87, v165
	v_fma_f32 v156, -v157, v143, v87
	v_fmac_f32_e32 v143, v156, v165
	v_fma_f32 v87, -v157, v143, v87
	v_div_fmas_f32 v87, v87, v165, v143
	v_div_fixup_f32 v88, v87, v142, v88
	global_store_dwordx2 v[144:145], v[88:89], off sc1
	s_and_saveexec_b64 s[6:7], s[4:5]
	s_cbranch_execz .LBB0_283
	v_lshl_add_u64 v[88:89], v[74:75], 0, v[94:95]
	global_store_dwordx2 v[88:89], v[146:147], off sc1
.LBB0_283:
	s_or_b64 exec, exec, s[6:7]
	v_pk_fma_f32 v[88:89], v[140:141], v[104:105], 0 op_sel_hi:[1,1,0]
	v_lshlrev_b32_e32 v142, 16, v163
	v_pk_fma_f32 v[88:89], v[106:107], v[122:123], v[88:89]
	v_and_b32_e32 v143, 0xffff0000, v163
	v_pk_fma_f32 v[88:89], v[110:111], v[148:149], v[88:89]
	v_lshl_add_u64 v[144:145], v[52:53], 0, v[154:155]
	v_pk_fma_f32 v[88:89], v[102:103], v[142:143], v[88:89]
	s_nop 0
	v_mul_f32_e32 v87, 0xbfb8aa3b, v88
	v_exp_f32_e32 v140, v87
	v_mul_f32_e32 v87, 0xbfb8aa3b, v89
	v_exp_f32_e32 v141, v87
	s_nop 0
	v_pk_add_f32 v[140:141], v[140:141], 1.0 op_sel_hi:[1,0]
	s_nop 0
	v_div_scale_f32 v87, s[6:7], v141, v141, v89
	v_rcp_f32_e32 v156, v87
	s_nop 0
	v_fma_f32 v157, -v87, v156, 1.0
	v_fmac_f32_e32 v156, v157, v156
	v_div_scale_f32 v157, vcc, v89, v141, v89
	v_mul_f32_e32 v163, v157, v156
	v_fma_f32 v164, -v87, v163, v157
	v_fmac_f32_e32 v163, v164, v156
	v_fma_f32 v87, -v87, v163, v157
	v_div_scale_f32 v157, s[6:7], v140, v140, v88
	v_rcp_f32_e32 v164, v157
	v_div_fmas_f32 v87, v87, v156, v163
	v_div_fixup_f32 v89, v87, v141, v89
	v_fma_f32 v87, -v157, v164, 1.0
	v_fmac_f32_e32 v164, v87, v164
	v_div_scale_f32 v87, vcc, v88, v140, v88
	v_mul_f32_e32 v141, v87, v164
	v_fma_f32 v156, -v157, v141, v87
	v_fmac_f32_e32 v141, v156, v164
	v_fma_f32 v87, -v157, v141, v87
	v_div_fmas_f32 v87, v87, v164, v141
	v_div_fixup_f32 v88, v87, v140, v88
	global_store_dwordx2 v[144:145], v[88:89], off sc1
	s_and_saveexec_b64 s[6:7], s[4:5]
	s_cbranch_execz .LBB0_285
	v_lshl_add_u64 v[88:89], v[76:77], 0, v[94:95]
	global_store_dwordx2 v[88:89], v[142:143], off sc1
; DI float bflo(unsigned u) { return __uint_as_float(u << 16); }
; DI float bfhi(unsigned u) { return __uint_as_float(u & 0xffff0000u); }
; DI float siluf_(float x) { return x / (1.0f + __expf(-x)); }
; template <int G0>
; DI void qkv_run4_half(const Params& p, int row0, int lane) {
;     ...
;   for (int k = 0; k < 4; ++k) {
;     const int row = row0 + k;
; #pragma unroll
;     for (int g = 0; g < 4; ++g) {
;       const int grp = G0 + g;
;       const int ch = grp * 128 + lane * 2;
;       float a0 = 0.f, a1 = 0.f;
; #pragma unroll
;       for (int j = 0; j < 4; ++j) {
;         const int i = k + j;
;         const float m = (i >= 3) ? 1.f : hm;
;         a0 += w[g][j].x * (bflo(u[g][i]) * m);
;         a1 += w[g][j].y * (bfhi(u[g][i]) * m);
;       }
;       float y0 = siluf_(a0), y1 = siluf_(a1);
;       if (grp < 8) {
;         float ss = wave_sum(y0 * y0 + y1 * y1);
;         float inv = rsqrtf(ss + EPSF);
;         if (grp < 4) inv *= 0.08838834764831845f;
;         y0 *= inv; y1 *= inv;
;       }
;       float2 o = {y0, y1};
;       *(float2*)(p.QKV + (size_t)row * 1536 + ch) = o;
;       if (t0 == 2044 && k >= 1) {
;         float2 c = {bflo(u[g][k + 3]), bfhi(u[g][k + 3])};
;         *(float2*)(p.out + O_QKVP + ((size_t)b * 3 + (k - 1)) * 1536 + ch) = c;
;       }
;     }
.LBB0_285:
	s_or_b64 exec, exec, s[6:7]
	v_pk_fma_f32 v[138:139], v[138:139], v[92:93], 0 op_sel_hi:[1,1,0]
	v_lshlrev_b32_e32 v88, 16, v162
	v_pk_fma_f32 v[138:139], v[96:97], v[120:121], v[138:139]
	v_and_b32_e32 v89, 0xffff0000, v162
	v_pk_fma_f32 v[138:139], v[100:101], v[90:91], v[138:139]
	v_lshl_add_u64 v[144:145], v[54:55], 0, v[154:155]
	v_pk_fma_f32 v[138:139], v[98:99], v[88:89], v[138:139]
	s_nop 0
	v_mul_f32_e32 v87, 0xbfb8aa3b, v138
	v_exp_f32_e32 v140, v87
	v_mul_f32_e32 v87, 0xbfb8aa3b, v139
	v_exp_f32_e32 v141, v87
	s_nop 0
	v_pk_add_f32 v[140:141], v[140:141], 1.0 op_sel_hi:[1,0]
	s_nop 0
	v_div_scale_f32 v87, s[6:7], v141, v141, v139
	v_rcp_f32_e32 v156, v87
	s_nop 0
	v_fma_f32 v154, -v87, v156, 1.0
	v_fmac_f32_e32 v156, v154, v156
	v_div_scale_f32 v154, vcc, v139, v141, v139
	v_mul_f32_e32 v155, v154, v156
	v_fma_f32 v157, -v87, v155, v154
	v_fmac_f32_e32 v155, v157, v156
	v_fma_f32 v87, -v87, v155, v154
	v_div_scale_f32 v154, s[6:7], v140, v140, v138
	v_rcp_f32_e32 v157, v154
	v_div_fmas_f32 v87, v87, v156, v155
	v_div_fixup_f32 v139, v87, v141, v139
	v_fma_f32 v87, -v154, v157, 1.0
	v_fmac_f32_e32 v157, v87, v157
	v_div_scale_f32 v87, vcc, v138, v140, v138
	v_mul_f32_e32 v141, v87, v157
	v_fma_f32 v155, -v154, v141, v87
	v_fmac_f32_e32 v141, v155, v157
	v_fma_f32 v87, -v154, v141, v87
	v_div_fmas_f32 v87, v87, v157, v141
	v_div_fixup_f32 v138, v87, v140, v138
	global_store_dwordx2 v[144:145], v[138:139], off sc1
	s_and_saveexec_b64 s[6:7], s[4:5]
	s_cbranch_execz .LBB0_287
	v_lshl_add_u64 v[94:95], v[78:79], 0, v[94:95]
	global_store_dwordx2 v[94:95], v[88:89], off sc1
.LBB0_287:
	s_or_b64 exec, exec, s[6:7]
	v_pk_fma_f32 v[94:95], v[128:129], v[126:127], 0 op_sel_hi:[1,1,0]
	v_lshlrev_b32_e32 v138, 16, v161
	v_pk_fma_f32 v[94:95], v[130:131], v[136:137], v[94:95]
	v_and_b32_e32 v139, 0xffff0000, v161
	v_pk_fma_f32 v[94:95], v[134:135], v[152:153], v[94:95]
	s_nop 0
	v_pk_fma_f32 v[126:127], v[132:133], v[138:139], v[94:95]
	s_nop 0
	v_mul_f32_e32 v87, 0xbfb8aa3b, v126
	v_exp_f32_e32 v94, v87
	v_mul_f32_e32 v87, 0xbfb8aa3b, v127
	v_exp_f32_e32 v95, v87
	s_nop 0
	v_pk_add_f32 v[128:129], v[94:95], 1.0 op_sel_hi:[1,0]
	s_nop 0
	v_div_scale_f32 v87, s[6:7], v129, v129, v127
	v_rcp_f32_e32 v132, v87
	v_mad_i64_i32 v[94:95], s[6:7], v178, s26, 0
	v_lshl_add_u64 v[130:131], v[48:49], 0, v[94:95]
	v_fma_f32 v133, -v87, v132, 1.0
	v_fmac_f32_e32 v132, v133, v132
	v_div_scale_f32 v133, vcc, v127, v129, v127
	v_mul_f32_e32 v134, v133, v132
	v_fma_f32 v135, -v87, v134, v133
	v_fmac_f32_e32 v134, v135, v132
	v_fma_f32 v87, -v87, v134, v133
	v_div_scale_f32 v133, s[6:7], v128, v128, v126
	v_rcp_f32_e32 v135, v133
	v_div_fmas_f32 v87, v87, v132, v134
	v_div_fixup_f32 v127, v87, v129, v127
	v_fma_f32 v87, -v133, v135, 1.0
	v_fmac_f32_e32 v135, v87, v135
	v_div_scale_f32 v87, vcc, v126, v128, v126
	v_mul_f32_e32 v129, v87, v135
	v_fma_f32 v132, -v133, v129, v87
	v_fmac_f32_e32 v129, v132, v135
	v_fma_f32 v87, -v133, v129, v87
	v_div_fmas_f32 v87, v87, v135, v129
	v_div_fixup_f32 v126, v87, v128, v126
	global_store_dwordx2 v[130:131], v[126:127], off sc1
	s_and_saveexec_b64 s[6:7], s[4:5]
	s_cbranch_execz .LBB0_289
	v_lshl_add_u64 v[126:127], v[72:73], 0, v[108:109]
	global_store_dwordx2 v[126:127], v[138:139], off sc1
; DI float bflo(unsigned u) { return __uint_as_float(u << 16); }
; DI float bfhi(unsigned u) { return __uint_as_float(u & 0xffff0000u); }
; DI float siluf_(float x) { return x / (1.0f + __expf(-x)); }
; template <int G0>
; DI void qkv_run4_half(const Params& p, int row0, int lane) {
;     ...
;   for (int k = 0; k < 4; ++k) {
;     const int row = row0 + k;
; #pragma unroll
;     for (int g = 0; g < 4; ++g) {
;       const int grp = G0 + g;
;       const int ch = grp * 128 + lane * 2;
;       float a0 = 0.f, a1 = 0.f;
; #pragma unroll
;       for (int j = 0; j < 4; ++j) {
;         const int i = k + j;
;         const float m = (i >= 3) ? 1.f : hm;
;         a0 += w[g][j].x * (bflo(u[g][i]) * m);
;         a1 += w[g][j].y * (bfhi(u[g][i]) * m);
;       }
;       float y0 = siluf_(a0), y1 = siluf_(a1);
;       if (grp < 8) {
;         float ss = wave_sum(y0 * y0 + y1 * y1);
;         float inv = rsqrtf(ss + EPSF);
;         if (grp < 4) inv *= 0.08838834764831845f;
;         y0 *= inv; y1 *= inv;
;       }
;       float2 o = {y0, y1};
;       *(float2*)(p.QKV + (size_t)row * 1536 + ch) = o;
;       if (t0 == 2044 && k >= 1) {
;         float2 c = {bflo(u[g][k + 3]), bfhi(u[g][k + 3])};
;         *(float2*)(p.out + O_QKVP + ((size_t)b * 3 + (k - 1)) * 1536 + ch) = c;
;       }
;     }
.LBB0_289:
	s_or_b64 exec, exec, s[6:7]
	v_pk_fma_f32 v[114:115], v[114:115], v[124:125], 0 op_sel_hi:[1,1,0]
	v_lshlrev_b32_e32 v126, 16, v160
	v_pk_fma_f32 v[114:115], v[116:117], v[150:151], v[114:115]
	v_and_b32_e32 v127, 0xffff0000, v160
	v_pk_fma_f32 v[114:115], v[118:119], v[146:147], v[114:115]
	v_lshl_add_u64 v[116:117], v[50:51], 0, v[94:95]
	v_pk_fma_f32 v[112:113], v[112:113], v[126:127], v[114:115]
	s_nop 0
	v_mul_f32_e32 v87, 0xbfb8aa3b, v112
	v_exp_f32_e32 v114, v87
	v_mul_f32_e32 v87, 0xbfb8aa3b, v113
	v_exp_f32_e32 v115, v87
	s_nop 0
	v_pk_add_f32 v[114:115], v[114:115], 1.0 op_sel_hi:[1,0]
	s_nop 0
	v_div_scale_f32 v87, s[6:7], v115, v115, v113
	v_rcp_f32_e32 v118, v87
	s_nop 0
	v_fma_f32 v119, -v87, v118, 1.0
	v_fmac_f32_e32 v118, v119, v118
	v_div_scale_f32 v119, vcc, v113, v115, v113
	v_mul_f32_e32 v124, v119, v118
	v_fma_f32 v125, -v87, v124, v119
	v_fmac_f32_e32 v124, v125, v118
	v_fma_f32 v87, -v87, v124, v119
	v_div_scale_f32 v119, s[6:7], v114, v114, v112
	v_rcp_f32_e32 v125, v119
	v_div_fmas_f32 v87, v87, v118, v124
	v_div_fixup_f32 v113, v87, v115, v113
	v_fma_f32 v87, -v119, v125, 1.0
	v_fmac_f32_e32 v125, v87, v125
	v_div_scale_f32 v87, vcc, v112, v114, v112
	v_mul_f32_e32 v115, v87, v125
	v_fma_f32 v118, -v119, v115, v87
	v_fmac_f32_e32 v115, v118, v125
	v_fma_f32 v87, -v119, v115, v87
	v_div_fmas_f32 v87, v87, v125, v115
	v_div_fixup_f32 v112, v87, v114, v112
	global_store_dwordx2 v[116:117], v[112:113], off sc1
	s_and_saveexec_b64 s[6:7], s[4:5]
	s_cbranch_execz .LBB0_291
	v_lshl_add_u64 v[112:113], v[74:75], 0, v[108:109]
	global_store_dwordx2 v[112:113], v[126:127], off sc1
.LBB0_291:
	s_or_b64 exec, exec, s[6:7]
	v_pk_fma_f32 v[104:105], v[104:105], v[122:123], 0 op_sel_hi:[1,1,0]
	v_lshlrev_b32_e32 v112, 16, v159
	v_pk_fma_f32 v[104:105], v[106:107], v[148:149], v[104:105]
	v_and_b32_e32 v113, 0xffff0000, v159
	v_pk_fma_f32 v[104:105], v[110:111], v[142:143], v[104:105]
	v_lshl_add_u64 v[106:107], v[52:53], 0, v[94:95]
	v_pk_fma_f32 v[102:103], v[102:103], v[112:113], v[104:105]
	s_nop 0
	v_mul_f32_e32 v87, 0xbfb8aa3b, v102
	v_exp_f32_e32 v104, v87
	v_mul_f32_e32 v87, 0xbfb8aa3b, v103
	v_exp_f32_e32 v105, v87
	s_nop 0
	v_pk_add_f32 v[104:105], v[104:105], 1.0 op_sel_hi:[1,0]
	s_nop 0
	v_div_scale_f32 v87, s[6:7], v105, v105, v103
	v_rcp_f32_e32 v110, v87
	s_nop 0
	v_fma_f32 v111, -v87, v110, 1.0
	v_fmac_f32_e32 v110, v111, v110
	v_div_scale_f32 v111, vcc, v103, v105, v103
	v_mul_f32_e32 v114, v111, v110
	v_fma_f32 v115, -v87, v114, v111
	v_fmac_f32_e32 v114, v115, v110
	v_fma_f32 v87, -v87, v114, v111
	v_div_scale_f32 v111, s[6:7], v104, v104, v102
	v_rcp_f32_e32 v115, v111
	v_div_fmas_f32 v87, v87, v110, v114
	v_div_fixup_f32 v103, v87, v105, v103
	v_fma_f32 v87, -v111, v115, 1.0
	v_fmac_f32_e32 v115, v87, v115
	v_div_scale_f32 v87, vcc, v102, v104, v102
	v_mul_f32_e32 v105, v87, v115
	v_fma_f32 v110, -v111, v105, v87
	v_fmac_f32_e32 v105, v110, v115
	v_fma_f32 v87, -v111, v105, v87
	v_div_fmas_f32 v87, v87, v115, v105
	v_div_fixup_f32 v102, v87, v104, v102
	global_store_dwordx2 v[106:107], v[102:103], off sc1
	s_and_saveexec_b64 s[6:7], s[4:5]
	s_cbranch_execz .LBB0_293
	v_lshl_add_u64 v[102:103], v[76:77], 0, v[108:109]
	global_store_dwordx2 v[102:103], v[112:113], off sc1
.LBB0_293:
	s_or_b64 exec, exec, s[6:7]
	v_pk_fma_f32 v[92:93], v[92:93], v[120:121], 0 op_sel_hi:[1,1,0]
	v_lshlrev_b32_e32 v102, 16, v158
	v_pk_fma_f32 v[90:91], v[96:97], v[90:91], v[92:93]
	v_and_b32_e32 v103, 0xffff0000, v158
	v_pk_fma_f32 v[88:89], v[100:101], v[88:89], v[90:91]
	v_lshl_add_u64 v[92:93], v[54:55], 0, v[94:95]
	v_pk_fma_f32 v[88:89], v[98:99], v[102:103], v[88:89]
	s_nop 0
	v_mul_f32_e32 v87, 0xbfb8aa3b, v88
	v_exp_f32_e32 v90, v87
	v_mul_f32_e32 v87, 0xbfb8aa3b, v89
	v_exp_f32_e32 v91, v87
	s_nop 0
	v_pk_add_f32 v[90:91], v[90:91], 1.0 op_sel_hi:[1,0]
	s_nop 0
	v_div_scale_f32 v87, s[6:7], v91, v91, v89
	v_rcp_f32_e32 v96, v87
	s_nop 0
	v_fma_f32 v94, -v87, v96, 1.0
	v_fmac_f32_e32 v96, v94, v96
	v_div_scale_f32 v94, vcc, v89, v91, v89
	v_mul_f32_e32 v95, v94, v96
	v_fma_f32 v97, -v87, v95, v94
	v_fmac_f32_e32 v95, v97, v96
	v_fma_f32 v87, -v87, v95, v94
	v_div_scale_f32 v94, s[6:7], v90, v90, v88
	v_rcp_f32_e32 v97, v94
	v_div_fmas_f32 v87, v87, v96, v95
	v_div_fixup_f32 v89, v87, v91, v89
	v_fma_f32 v87, -v94, v97, 1.0
	v_fmac_f32_e32 v97, v87, v97
	v_div_scale_f32 v87, vcc, v88, v90, v88
	v_mul_f32_e32 v91, v87, v97
	v_fma_f32 v95, -v94, v91, v87
	v_fmac_f32_e32 v91, v95, v97
	v_fma_f32 v87, -v94, v91, v87
	v_div_fmas_f32 v87, v87, v97, v91
	v_div_fixup_f32 v88, v87, v90, v88
	global_store_dwordx2 v[92:93], v[88:89], off sc1
	s_and_saveexec_b64 s[6:7], s[4:5]
	s_cbranch_execz .LBB0_295
	v_lshl_add_u64 v[88:89], v[78:79], 0, v[108:109]
	global_store_dwordx2 v[88:89], v[102:103], off sc1

; DI float bflo(unsigned u) { return __uint_as_float(u << 16); }
; DI float bfhi(unsigned u) { return __uint_as_float(u & 0xffff0000u); }
; DI float siluf_(float x) { return x / (1.0f + __expf(-x)); }
; template <bool IS_P, bool EDGE>
; DI void qkv_token(const Params& p, int row, int lane) {
;     ...
;   for (int grp = 0; grp < 12; ++grp) {
;     const int ch = grp * 128 + lane * 2;
;     float x0[4], x1[4];
;     if (IS_P) {
;       unsigned u[4];
; #pragma unroll
;       for (int j = 0; j < 4; ++j) {
;         const int rc = (!EDGE || t - 3 + j >= 0) ? (row - 3 + j) : row;
;         u[j] = *(const unsigned*)(p.PB + (size_t)rc * EINP + 1536 + ch);
;       }
; #pragma unroll
;       for (int j = 0; j < 4; ++j) {
;         const bool ok = (!EDGE || t - 3 + j >= 0);
;         x0[j] = ok ? bflo(u[j]) : 0.f;
;         x1[j] = ok ? bfhi(u[j]) : 0.f;
;       }
;     } else {
; #pragma unroll
;       for (int j = 0; j < 3; ++j) {
;         float2 f = *(const float2*)(p.state_qkv_conv + ((size_t)s * 3 + j) * 1536 + ch);
;         x0[j] = f.x; x1[j] = f.y;
;       }
;       unsigned u = *(const unsigned*)(p.PB + (size_t)row * EINP + 1536 + ch);
;       x0[3] = bflo(u); x1[3] = bfhi(u);
;     }
;     float a0 = 0.f, a1 = 0.f;
; #pragma unroll
;     for (int j = 0; j < 4; ++j) {
;       float2 w = *(const float2*)(p.sc_w + (size_t)j * 1536 + ch);
;       a0 += w.x * x0[j]; a1 += w.y * x1[j];
;     }
;     float y0 = siluf_(a0), y1 = siluf_(a1);
;     if (grp < 8) {
;       float ss = wave_sum(y0 * y0 + y1 * y1);
;       float inv = rsqrtf(ss + EPSF);
;       if (grp < 4) inv *= 0.08838834764831845f;
;       y0 *= inv; y1 *= inv;
;     }
;     float2 o = {y0, y1};
;     *(float2*)(p.QKV + (size_t)row * 1536 + ch) = o;
;     if (IS_P) {
;       if (t >= 2045) {
;         float2 c = {x0[3], x1[3]};
;         *(float2*)(p.out + O_QKVP + ((size_t)b * 3 + (t - 2045)) * 1536 + ch) = c;
;       }
;     } else {
;       float2 c0 = {x0[1], x1[1]}, c1 = {x0[2], x1[2]}, c2 = {x0[3], x1[3]};
;       *(float2*)(p.out + O_QKVS + ((size_t)s * 3 + 0) * 1536 + ch) = c0;
;       *(float2*)(p.out + O_QKVS + ((size_t)s * 3 + 1) * 1536 + ch) = c1;
;       *(float2*)(p.out + O_QKVS + ((size_t)s * 3 + 2) * 1536 + ch) = c2;
;     }
;   }
.LBB0_303:
	global_store_dwordx2 v[30:31], v[38:39], off offset:2560 sc1
	v_add_co_u32_e32 v30, vcc, 0x6b14000, v28
	s_add_i32 s38, s38, 6
	s_nop 0
	v_addc_co_u32_e32 v31, vcc, 0, v29, vcc
	global_store_dwordx2 v[30:31], v[36:37], off offset:2560 sc1
	v_add_co_u32_e32 v30, vcc, 0x6b16000, v28
	s_add_u32 s16, s16, 0xc00
	s_nop 0
	v_addc_co_u32_e32 v31, vcc, 0, v29, vcc
	v_add_co_u32_e32 v28, vcc, 0x6b17000, v28
	s_addc_u32 s17, s17, 0
	s_nop 0
	v_addc_co_u32_e32 v29, vcc, 0, v29, vcc
	s_cmpk_eq_i32 s16, 0x1800
	v_lshl_add_u64 v[20:21], v[20:21], 0, s[14:15]
	global_store_dwordx2 v[30:31], v[34:35], off offset:512 sc1
	global_store_dwordx2 v[28:29], v[32:33], off offset:2560 sc1
	s_cbranch_scc1 .LBB0_312
.LBB0_304:
	v_lshl_add_u64 v[34:35], v[24:25], 0, s[16:17]
	v_add_co_u32_e32 v38, vcc, 0x1000, v34
	v_lshl_add_u64 v[32:33], v[12:13], 0, s[16:17]
	s_nop 0
	v_addc_co_u32_e32 v39, vcc, 0, v35, vcc
	v_add_co_u32_e32 v40, vcc, 0x3000, v34
	global_load_dword v19, v[20:21], off offset:-1280
	s_nop 0
	v_addc_co_u32_e32 v41, vcc, 0, v35, vcc
	v_add_co_u32_e32 v42, vcc, 0x1000, v32
	global_load_dwordx2 v[46:47], v[38:39], off offset:2048
	global_load_dwordx2 v[48:49], v[40:41], off
	global_load_dwordx2 v[56:57], v[34:35], off
	v_addc_co_u32_e32 v43, vcc, 0, v33, vcc
	global_load_dwordx2 v[58:59], v[32:33], off
	v_add_co_u32_e32 v44, vcc, 0x3000, v32
	v_lshl_add_u64 v[28:29], v[22:23], 0, s[16:17]
	s_nop 0
	v_addc_co_u32_e32 v45, vcc, 0, v33, vcc
	v_add_co_u32_e32 v36, vcc, s18, v32
	v_mov_b32_e32 v55, 0
	s_nop 0
	v_addc_co_u32_e32 v37, vcc, 0, v33, vcc
	global_load_dwordx2 v[60:61], v[42:43], off offset:2048
	global_load_dwordx2 v[62:63], v[44:45], off
	global_load_dwordx2 v[64:65], v[36:37], off offset:2048
	v_add_co_u32_e32 v66, vcc, s26, v28
	v_mov_b32_e32 v70, 0
	s_nop 0
	v_addc_co_u32_e32 v67, vcc, 0, v29, vcc
	s_cmp_lt_u32 s38, 4
	v_lshl_add_u64 v[30:31], v[26:27], 0, s[16:17]
	s_waitcnt vmcnt(7)
	v_lshlrev_b32_e32 v68, 16, v19
	v_and_b32_e32 v69, 0xffff0000, v19
	s_waitcnt vmcnt(3)
	v_pk_fma_f32 v[56:57], v[56:57], v[58:59], 0 op_sel_hi:[1,1,0]
	s_waitcnt vmcnt(2)
	v_pk_fma_f32 v[56:57], v[46:47], v[60:61], v[56:57]
	s_waitcnt vmcnt(1)
	v_pk_fma_f32 v[56:57], v[48:49], v[62:63], v[56:57]
	v_add_co_u32_e32 v60, vcc, s27, v28
	s_waitcnt vmcnt(0)
	v_pk_fma_f32 v[56:57], v[64:65], v[68:69], v[56:57]
	v_addc_co_u32_e32 v61, vcc, 0, v29, vcc
	v_mul_f32_e32 v19, 0xbfb8aa3b, v56
	v_mul_f32_e32 v59, 0xbfb8aa3b, v57
	v_exp_f32_e32 v58, v19
	v_exp_f32_e32 v59, v59
	s_nop 0
	v_pk_add_f32 v[58:59], v[58:59], 1.0 op_sel_hi:[1,0]
	s_nop 0
	v_div_scale_f32 v19, s[4:5], v59, v59, v57
	v_div_scale_f32 v63, s[4:5], v58, v58, v56
	v_rcp_f32_e32 v64, v19
	v_rcp_f32_e32 v65, v63
	v_div_scale_f32 v62, vcc, v57, v59, v57
	v_fma_f32 v72, -v19, v64, 1.0
	v_fma_f32 v73, -v63, v65, 1.0
	v_fmac_f32_e32 v64, v72, v64
	v_div_scale_f32 v71, s[4:5], v56, v58, v56
	v_fmac_f32_e32 v65, v73, v65
	v_mul_f32_e32 v72, v62, v64
	v_mul_f32_e32 v73, v71, v65
	v_fma_f32 v74, -v19, v72, v62
	v_fma_f32 v75, -v63, v73, v71
	v_fmac_f32_e32 v72, v74, v64
	v_fmac_f32_e32 v73, v75, v65
	v_fma_f32 v19, -v19, v72, v62
	v_fma_f32 v62, -v63, v73, v71
	v_div_fmas_f32 v19, v19, v64, v72
	s_mov_b64 vcc, s[4:5]
	v_div_fixup_f32 v57, v19, v59, v57
	v_div_fmas_f32 v19, v62, v65, v73
	v_div_fixup_f32 v56, v19, v58, v56
	v_pk_mul_f32 v[58:59], v[56:57], v[56:57]
	s_nop 0
	v_add_f32_e32 v19, v58, v59
	s_nop 1
	v_add_f32_dpp v19, v19, v19 quad_perm:[1,0,3,2] row_mask:0xf bank_mask:0xf bound_ctrl:1
	s_nop 1
	v_add_f32_dpp v19, v19, v19 quad_perm:[2,3,0,1] row_mask:0xf bank_mask:0xf bound_ctrl:1
	s_nop 1
	v_add_f32_dpp v19, v19, v19 row_half_mirror row_mask:0xf bank_mask:0xf bound_ctrl:1
	s_nop 1
	v_add_f32_dpp v19, v19, v19 row_mirror row_mask:0xf bank_mask:0xf bound_ctrl:1
	s_nop 1
	v_mov_b32_dpp v55, v19 row_bcast:15 row_mask:0xa bank_mask:0xf
	v_add_f32_e32 v19, v19, v55
	s_nop 1
	v_mov_b32_dpp v70, v19 row_bcast:31 row_mask:0xc bank_mask:0xf
	v_add_f32_e32 v19, v19, v70
	s_nop 0
	v_readlane_b32 s4, v19, 63
	s_nop 1
	v_add_f32_e32 v19, s4, v50
	v_mul_f32_e32 v55, 0x4b800000, v19
	v_cmp_gt_f32_e32 vcc, s25, v19
	v_add_co_u32_e64 v58, s[4:5], s28, v28
	s_nop 0
	v_cndmask_b32_e32 v19, v19, v55, vcc
	v_rsq_f32_e32 v19, v19
	v_addc_co_u32_e64 v59, s[4:5], 0, v29, s[4:5]
	s_cselect_b64 s[4:5], -1, 0
	v_mul_f32_e32 v55, 0x45800000, v19
	v_cndmask_b32_e32 v19, v19, v55, vcc
	v_mul_f32_e32 v55, 0x3db504f3, v19
	v_cndmask_b32_e64 v62, v19, v55, s[4:5]
	v_pk_mul_f32 v[56:57], v[56:57], v[62:63] op_sel_hi:[1,0]
	global_store_dwordx2 v[30:31], v[56:57], off sc1
	global_store_dwordx2 v[66:67], v[46:47], off sc1
	global_store_dwordx2 v[60:61], v[48:49], off offset:2048 sc1
	global_store_dwordx2 v[58:59], v[68:69], off sc1
	global_load_dword v19, v[20:21], off offset:-1024
	s_nop 0
	global_load_dwordx2 v[46:47], v[38:39], off offset:2560
	global_load_dwordx2 v[48:49], v[40:41], off offset:512
	global_load_dwordx2 v[56:57], v[34:35], off offset:512
	global_load_dwordx2 v[62:63], v[32:33], off offset:512
	global_load_dwordx2 v[64:65], v[42:43], off offset:2560
	global_load_dwordx2 v[68:69], v[44:45], off offset:512
	global_load_dwordx2 v[70:71], v[36:37], off offset:2560
	s_cmp_gt_u32 s38, 5
	s_waitcnt vmcnt(7)
	v_lshlrev_b32_e32 v72, 16, v19
	v_and_b32_e32 v73, 0xffff0000, v19
	s_waitcnt vmcnt(3)
	v_pk_fma_f32 v[56:57], v[56:57], v[62:63], 0 op_sel_hi:[1,1,0]
	s_waitcnt vmcnt(2)
	v_pk_fma_f32 v[56:57], v[46:47], v[64:65], v[56:57]
	s_waitcnt vmcnt(1)
	v_pk_fma_f32 v[56:57], v[48:49], v[68:69], v[56:57]
	s_waitcnt vmcnt(0)
; DI float bflo(unsigned u) { return __uint_as_float(u << 16); }
; DI float bfhi(unsigned u) { return __uint_as_float(u & 0xffff0000u); }
; DI float siluf_(float x) { return x / (1.0f + __expf(-x)); }
; template <bool IS_P, bool EDGE>
; DI void qkv_token(const Params& p, int row, int lane) {
;     ...
;   for (int grp = 0; grp < 12; ++grp) {
;     const int ch = grp * 128 + lane * 2;
;     float x0[4], x1[4];
;     if (IS_P) {
;       unsigned u[4];
; #pragma unroll
;       for (int j = 0; j < 4; ++j) {
;         const int rc = (!EDGE || t - 3 + j >= 0) ? (row - 3 + j) : row;
;         u[j] = *(const unsigned*)(p.PB + (size_t)rc * EINP + 1536 + ch);
;       }
; #pragma unroll
;       for (int j = 0; j < 4; ++j) {
;         const bool ok = (!EDGE || t - 3 + j >= 0);
;         x0[j] = ok ? bflo(u[j]) : 0.f;
;         x1[j] = ok ? bfhi(u[j]) : 0.f;
;       }
;     } else {
; #pragma unroll
;       for (int j = 0; j < 3; ++j) {
;         float2 f = *(const float2*)(p.state_qkv_conv + ((size_t)s * 3 + j) * 1536 + ch);
;         x0[j] = f.x; x1[j] = f.y;
;       }
;       unsigned u = *(const unsigned*)(p.PB + (size_t)row * EINP + 1536 + ch);
;       x0[3] = bflo(u); x1[3] = bfhi(u);
;     }
;     float a0 = 0.f, a1 = 0.f;
; #pragma unroll
;     for (int j = 0; j < 4; ++j) {
;       float2 w = *(const float2*)(p.sc_w + (size_t)j * 1536 + ch);
;       a0 += w.x * x0[j]; a1 += w.y * x1[j];
;     }
;     float y0 = siluf_(a0), y1 = siluf_(a1);
;     if (grp < 8) {
;       float ss = wave_sum(y0 * y0 + y1 * y1);
;       float inv = rsqrtf(ss + EPSF);
;       if (grp < 4) inv *= 0.08838834764831845f;
;       y0 *= inv; y1 *= inv;
;     }
;     float2 o = {y0, y1};
;     *(float2*)(p.QKV + (size_t)row * 1536 + ch) = o;
;     if (IS_P) {
;       if (t >= 2045) {
;         float2 c = {x0[3], x1[3]};
;         *(float2*)(p.out + O_QKVP + ((size_t)b * 3 + (t - 2045)) * 1536 + ch) = c;
;       }
;     } else {
;       float2 c0 = {x0[1], x1[1]}, c1 = {x0[2], x1[2]}, c2 = {x0[3], x1[3]};
;       *(float2*)(p.out + O_QKVS + ((size_t)s * 3 + 0) * 1536 + ch) = c0;
;       *(float2*)(p.out + O_QKVS + ((size_t)s * 3 + 1) * 1536 + ch) = c1;
;       *(float2*)(p.out + O_QKVS + ((size_t)s * 3 + 2) * 1536 + ch) = c2;
;     }
;   }
	v_pk_fma_f32 v[56:57], v[70:71], v[72:73], v[56:57]
	s_nop 0
	v_mul_f32_e32 v19, 0xbfb8aa3b, v56
	v_mul_f32_e32 v55, 0xbfb8aa3b, v57
	v_exp_f32_e32 v62, v19
	v_exp_f32_e32 v63, v55
	v_mov_b32_e32 v19, 0
	v_mov_b32_e32 v55, 0
	v_pk_add_f32 v[62:63], v[62:63], 1.0 op_sel_hi:[1,0]
	s_nop 0
	v_div_scale_f32 v64, s[6:7], v63, v63, v57
	v_div_scale_f32 v68, s[6:7], v62, v62, v56
	v_rcp_f32_e32 v69, v64
	v_rcp_f32_e32 v70, v68
	v_div_scale_f32 v65, vcc, v57, v63, v57
	v_fma_f32 v74, -v64, v69, 1.0
	v_fma_f32 v75, -v68, v70, 1.0
	v_fmac_f32_e32 v69, v74, v69
	v_div_scale_f32 v71, s[6:7], v56, v62, v56
	v_fmac_f32_e32 v70, v75, v70
	v_mul_f32_e32 v74, v65, v69
	v_mul_f32_e32 v75, v71, v70
	v_fma_f32 v76, -v64, v74, v65
	v_fma_f32 v77, -v68, v75, v71
	v_fmac_f32_e32 v74, v76, v69
	v_fmac_f32_e32 v75, v77, v70
	v_fma_f32 v64, -v64, v74, v65
	v_fma_f32 v65, -v68, v75, v71
	v_div_fmas_f32 v64, v64, v69, v74
	s_mov_b64 vcc, s[6:7]
	v_div_fixup_f32 v57, v64, v63, v57
	v_div_fmas_f32 v63, v65, v70, v75
	v_div_fixup_f32 v56, v63, v62, v56
	v_pk_mul_f32 v[62:63], v[56:57], v[56:57]
	s_nop 0
	v_add_f32_e32 v62, v62, v63
	s_nop 1
	v_add_f32_dpp v62, v62, v62 quad_perm:[1,0,3,2] row_mask:0xf bank_mask:0xf bound_ctrl:1
	s_nop 1
	v_add_f32_dpp v62, v62, v62 quad_perm:[2,3,0,1] row_mask:0xf bank_mask:0xf bound_ctrl:1
	s_nop 1
	v_add_f32_dpp v62, v62, v62 row_half_mirror row_mask:0xf bank_mask:0xf bound_ctrl:1
	s_nop 1
	v_add_f32_dpp v62, v62, v62 row_mirror row_mask:0xf bank_mask:0xf bound_ctrl:1
	s_nop 1
	v_mov_b32_dpp v19, v62 row_bcast:15 row_mask:0xa bank_mask:0xf
	v_add_f32_e32 v19, v62, v19
	s_nop 1
	v_mov_b32_dpp v55, v19 row_bcast:31 row_mask:0xc bank_mask:0xf
	v_add_f32_e32 v19, v19, v55
	s_nop 0
	v_readlane_b32 s6, v19, 63
	s_nop 1
	v_add_f32_e32 v19, s6, v50
	v_mul_f32_e32 v55, 0x4b800000, v19
	v_cmp_gt_f32_e32 vcc, s25, v19
	s_nop 1
	v_cndmask_b32_e32 v19, v19, v55, vcc
	v_rsq_f32_e32 v19, v19
	s_nop 0
	v_mul_f32_e32 v55, 0x45800000, v19
	v_cndmask_b32_e32 v19, v19, v55, vcc
	v_mul_f32_e32 v55, 0x3db504f3, v19
	v_cndmask_b32_e64 v62, v19, v55, s[4:5]
	v_pk_mul_f32 v[56:57], v[56:57], v[62:63] op_sel_hi:[1,0]
	global_store_dwordx2 v[30:31], v[56:57], off offset:512 sc1
	global_store_dwordx2 v[66:67], v[46:47], off offset:512 sc1
	global_store_dwordx2 v[60:61], v[48:49], off offset:2560 sc1
	global_store_dwordx2 v[58:59], v[72:73], off offset:512 sc1
	global_load_dword v19, v[20:21], off offset:-768
	s_nop 0
	global_load_dwordx2 v[56:57], v[34:35], off offset:1024
	global_load_dwordx2 v[48:49], v[38:39], off offset:3072
	global_load_dwordx2 v[46:47], v[40:41], off offset:1024
	global_load_dwordx2 v[58:59], v[32:33], off offset:1024
	global_load_dwordx2 v[60:61], v[42:43], off offset:3072
	global_load_dwordx2 v[62:63], v[44:45], off offset:1024
	global_load_dwordx2 v[64:65], v[36:37], off offset:3072
	s_waitcnt vmcnt(7)
	v_lshlrev_b32_e32 v38, 16, v19
	v_and_b32_e32 v39, 0xffff0000, v19
	s_waitcnt vmcnt(3)
	v_pk_fma_f32 v[40:41], v[56:57], v[58:59], 0 op_sel_hi:[1,1,0]
	s_waitcnt vmcnt(2)
	v_pk_fma_f32 v[40:41], v[48:49], v[60:61], v[40:41]
	s_waitcnt vmcnt(1)
	v_pk_fma_f32 v[40:41], v[46:47], v[62:63], v[40:41]
	s_waitcnt vmcnt(0)
	v_pk_fma_f32 v[40:41], v[64:65], v[38:39], v[40:41]
	s_nop 0
	v_mul_f32_e32 v19, 0xbfb8aa3b, v40
	v_mul_f32_e32 v43, 0xbfb8aa3b, v41
	v_exp_f32_e32 v42, v19
	v_exp_f32_e32 v43, v43
	s_nop 0
	v_pk_add_f32 v[42:43], v[42:43], 1.0 op_sel_hi:[1,0]
	s_nop 0
	v_div_scale_f32 v19, s[6:7], v43, v43, v41
	v_div_scale_f32 v45, s[6:7], v42, v42, v40
	v_rcp_f32_e32 v55, v19
	v_rcp_f32_e32 v56, v45
	v_div_scale_f32 v44, vcc, v41, v43, v41
	v_fma_f32 v58, -v19, v55, 1.0
	v_fma_f32 v59, -v45, v56, 1.0
	v_fmac_f32_e32 v55, v58, v55
	v_div_scale_f32 v57, s[6:7], v40, v42, v40
	v_fmac_f32_e32 v56, v59, v56
	v_mul_f32_e32 v58, v44, v55
	v_mul_f32_e32 v59, v57, v56
	v_fma_f32 v60, -v19, v58, v44
	v_fma_f32 v61, -v45, v59, v57
	v_fmac_f32_e32 v58, v60, v55
	v_fmac_f32_e32 v59, v61, v56
	v_fma_f32 v19, -v19, v58, v44
	v_fma_f32 v44, -v45, v59, v57
	v_div_fmas_f32 v19, v19, v55, v58
	s_mov_b64 vcc, s[6:7]
	v_div_fixup_f32 v41, v19, v43, v41
	v_div_fmas_f32 v19, v44, v56, v59
	v_div_fixup_f32 v40, v19, v42, v40
	s_cbranch_scc1 .LBB0_306
	v_pk_mul_f32 v[42:43], v[40:41], v[40:41]
	s_cmp_eq_u32 s16, 0
	v_add_f32_e32 v19, v42, v43
	v_mov_b32_e32 v42, 0
	s_nop 0
	v_add_f32_dpp v19, v19, v19 quad_perm:[1,0,3,2] row_mask:0xf bank_mask:0xf bound_ctrl:1
	s_nop 1
	v_add_f32_dpp v19, v19, v19 quad_perm:[2,3,0,1] row_mask:0xf bank_mask:0xf bound_ctrl:1
	s_nop 1
	v_add_f32_dpp v19, v19, v19 row_half_mirror row_mask:0xf bank_mask:0xf bound_ctrl:1
	s_nop 1
	v_add_f32_dpp v19, v19, v19 row_mirror row_mask:0xf bank_mask:0xf bound_ctrl:1
	s_nop 1
	v_mov_b32_dpp v42, v19 row_bcast:15 row_mask:0xa bank_mask:0xf
	v_add_f32_e32 v19, v19, v42
	v_mov_b32_e32 v42, 0
	s_nop 1
	v_mov_b32_dpp v42, v19 row_bcast:31 row_mask:0xc bank_mask:0xf
	v_add_f32_e32 v19, v19, v42
	s_nop 0
	v_readlane_b32 s6, v19, 63
	s_nop 1
	v_add_f32_e32 v19, s6, v50
	v_mul_f32_e32 v42, 0x4b800000, v19
	v_cmp_gt_f32_e32 vcc, s25, v19
	s_nop 1
	v_cndmask_b32_e32 v19, v19, v42, vcc
	v_rsq_f32_e32 v19, v19
	s_nop 0
	v_mul_f32_e32 v42, 0x45800000, v19
	v_cndmask_b32_e32 v19, v19, v42, vcc
	v_mul_f32_e32 v42, 0x3db504f3, v19
	s_cselect_b64 vcc, -1, 0
	v_cndmask_b32_e32 v42, v19, v42, vcc
	v_pk_mul_f32 v[40:41], v[40:41], v[42:43] op_sel_hi:[1,0]
; DI float bflo(unsigned u) { return __uint_as_float(u << 16); }
; DI float bfhi(unsigned u) { return __uint_as_float(u & 0xffff0000u); }
; DI float siluf_(float x) { return x / (1.0f + __expf(-x)); }
; template <bool IS_P, bool EDGE>
; DI void qkv_token(const Params& p, int row, int lane) {
;     ...
;   for (int grp = 0; grp < 12; ++grp) {
;     const int ch = grp * 128 + lane * 2;
;     float x0[4], x1[4];
;     if (IS_P) {
;       unsigned u[4];
; #pragma unroll
;       for (int j = 0; j < 4; ++j) {
;         const int rc = (!EDGE || t - 3 + j >= 0) ? (row - 3 + j) : row;
;         u[j] = *(const unsigned*)(p.PB + (size_t)rc * EINP + 1536 + ch);
;       }
; #pragma unroll
;       for (int j = 0; j < 4; ++j) {
;         const bool ok = (!EDGE || t - 3 + j >= 0);
;         x0[j] = ok ? bflo(u[j]) : 0.f;
;         x1[j] = ok ? bfhi(u[j]) : 0.f;
;       }
;     } else {
; #pragma unroll
;       for (int j = 0; j < 3; ++j) {
;         float2 f = *(const float2*)(p.state_qkv_conv + ((size_t)s * 3 + j) * 1536 + ch);
;         x0[j] = f.x; x1[j] = f.y;
;       }
;       unsigned u = *(const unsigned*)(p.PB + (size_t)row * EINP + 1536 + ch);
;       x0[3] = bflo(u); x1[3] = bfhi(u);
;     }
;     float a0 = 0.f, a1 = 0.f;
; #pragma unroll
;     for (int j = 0; j < 4; ++j) {
;       float2 w = *(const float2*)(p.sc_w + (size_t)j * 1536 + ch);
;       a0 += w.x * x0[j]; a1 += w.y * x1[j];
;     }
;     float y0 = siluf_(a0), y1 = siluf_(a1);
;     if (grp < 8) {
;       float ss = wave_sum(y0 * y0 + y1 * y1);
;       float inv = rsqrtf(ss + EPSF);
;       if (grp < 4) inv *= 0.08838834764831845f;
;       y0 *= inv; y1 *= inv;
;     }
;     float2 o = {y0, y1};
;     *(float2*)(p.QKV + (size_t)row * 1536 + ch) = o;
;     if (IS_P) {
;       if (t >= 2045) {
;         float2 c = {x0[3], x1[3]};
;         *(float2*)(p.out + O_QKVP + ((size_t)b * 3 + (t - 2045)) * 1536 + ch) = c;
;       }
;     } else {
;       float2 c0 = {x0[1], x1[1]}, c1 = {x0[2], x1[2]}, c2 = {x0[3], x1[3]};
;       *(float2*)(p.out + O_QKVS + ((size_t)s * 3 + 0) * 1536 + ch) = c0;
;       *(float2*)(p.out + O_QKVS + ((size_t)s * 3 + 1) * 1536 + ch) = c1;
;       *(float2*)(p.out + O_QKVS + ((size_t)s * 3 + 2) * 1536 + ch) = c2;
;     }
;   }
.LBB0_306:
	global_store_dwordx2 v[30:31], v[40:41], off offset:1024 sc1
	v_add_co_u32_e32 v40, vcc, 0x6b14000, v28
	s_cmp_gt_u32 s38, 4
	s_nop 0
	v_addc_co_u32_e32 v41, vcc, 0, v29, vcc
	global_store_dwordx2 v[40:41], v[48:49], off offset:1024 sc1
	v_add_co_u32_e32 v40, vcc, 0x6b15000, v28
	s_nop 1
	v_addc_co_u32_e32 v41, vcc, 0, v29, vcc
	global_store_dwordx2 v[40:41], v[46:47], off offset:3072 sc1
	v_add_co_u32_e32 v40, vcc, 0x6b17000, v28
	s_nop 1
	v_addc_co_u32_e32 v41, vcc, 0, v29, vcc
	global_store_dwordx2 v[40:41], v[38:39], off offset:1024 sc1
	v_add_co_u32_e32 v38, vcc, s23, v34
	global_load_dword v19, v[20:21], off offset:-512
	global_load_dwordx2 v[46:47], v[34:35], off offset:1536
	v_addc_co_u32_e32 v39, vcc, 0, v35, vcc
	v_add_co_u32_e32 v40, vcc, s24, v34
	global_load_dwordx2 v[42:43], v[38:39], off offset:3584
	s_nop 0
	v_addc_co_u32_e32 v41, vcc, 0, v35, vcc
	v_add_co_u32_e32 v38, vcc, s23, v32
	global_load_dwordx2 v[44:45], v[40:41], off offset:1536
	global_load_dwordx2 v[48:49], v[32:33], off offset:1536
	v_addc_co_u32_e32 v39, vcc, 0, v33, vcc
	global_load_dwordx2 v[56:57], v[38:39], off offset:3584
	v_add_co_u32_e32 v38, vcc, s24, v32
	s_waitcnt vmcnt(1)
	v_pk_fma_f32 v[46:47], v[46:47], v[48:49], 0 op_sel_hi:[1,1,0]
	v_addc_co_u32_e32 v39, vcc, 0, v33, vcc
	global_load_dwordx2 v[58:59], v[38:39], off offset:1536
	global_load_dwordx2 v[60:61], v[36:37], off offset:3584
	s_waitcnt vmcnt(2)
	v_pk_fma_f32 v[46:47], v[42:43], v[56:57], v[46:47]
	v_lshlrev_b32_e32 v36, 16, v19
	v_and_b32_e32 v37, 0xffff0000, v19
	s_waitcnt vmcnt(1)
	v_pk_fma_f32 v[46:47], v[44:45], v[58:59], v[46:47]
	s_waitcnt vmcnt(0)
	v_pk_fma_f32 v[46:47], v[60:61], v[36:37], v[46:47]
	s_nop 0
	v_mul_f32_e32 v19, 0xbfb8aa3b, v46
	v_mul_f32_e32 v49, 0xbfb8aa3b, v47
	v_exp_f32_e32 v48, v19
	v_exp_f32_e32 v49, v49
	s_nop 0
	v_pk_add_f32 v[48:49], v[48:49], 1.0 op_sel_hi:[1,0]
	s_nop 0
	v_div_scale_f32 v19, s[6:7], v49, v49, v47
	v_div_scale_f32 v56, s[6:7], v48, v48, v46
	v_rcp_f32_e32 v57, v19
	v_rcp_f32_e32 v58, v56
	v_div_scale_f32 v55, vcc, v47, v49, v47
	v_fma_f32 v60, -v19, v57, 1.0
	v_fma_f32 v61, -v56, v58, 1.0
	v_fmac_f32_e32 v57, v60, v57
	v_div_scale_f32 v59, s[6:7], v46, v48, v46
	v_fmac_f32_e32 v58, v61, v58
	v_mul_f32_e32 v60, v55, v57
	v_mul_f32_e32 v61, v59, v58
	v_fma_f32 v62, -v19, v60, v55
	v_fma_f32 v63, -v56, v61, v59
	v_fmac_f32_e32 v60, v62, v57
	v_fmac_f32_e32 v61, v63, v58
	v_fma_f32 v19, -v19, v60, v55
	v_fma_f32 v55, -v56, v61, v59
	v_div_fmas_f32 v19, v19, v57, v60
	s_mov_b64 vcc, s[6:7]
	v_div_fixup_f32 v47, v19, v49, v47
	v_div_fmas_f32 v19, v55, v58, v61
	v_div_fixup_f32 v46, v19, v48, v46
	s_cbranch_scc1 .LBB0_308
	v_pk_mul_f32 v[48:49], v[46:47], v[46:47]
	s_cmp_eq_u32 s16, 0
	v_add_f32_e32 v19, v48, v49
	v_mov_b32_e32 v48, 0
	s_nop 0
	v_add_f32_dpp v19, v19, v19 quad_perm:[1,0,3,2] row_mask:0xf bank_mask:0xf bound_ctrl:1
	s_nop 1
	v_add_f32_dpp v19, v19, v19 quad_perm:[2,3,0,1] row_mask:0xf bank_mask:0xf bound_ctrl:1
	s_nop 1
	v_add_f32_dpp v19, v19, v19 row_half_mirror row_mask:0xf bank_mask:0xf bound_ctrl:1
	s_nop 1
	v_add_f32_dpp v19, v19, v19 row_mirror row_mask:0xf bank_mask:0xf bound_ctrl:1
	s_nop 1
	v_mov_b32_dpp v48, v19 row_bcast:15 row_mask:0xa bank_mask:0xf
	v_add_f32_e32 v19, v19, v48
	v_mov_b32_e32 v48, 0
	s_nop 1
	v_mov_b32_dpp v48, v19 row_bcast:31 row_mask:0xc bank_mask:0xf
	v_add_f32_e32 v19, v19, v48
	s_nop 0
	v_readlane_b32 s6, v19, 63
	s_nop 1
	v_add_f32_e32 v19, s6, v50
	v_mul_f32_e32 v48, 0x4b800000, v19
	v_cmp_gt_f32_e32 vcc, s25, v19
	s_nop 1
	v_cndmask_b32_e32 v19, v19, v48, vcc
	v_rsq_f32_e32 v19, v19
	s_nop 0
	v_mul_f32_e32 v48, 0x45800000, v19
	v_cndmask_b32_e32 v19, v19, v48, vcc
	v_mul_f32_e32 v48, 0x3db504f3, v19
	s_cselect_b64 vcc, -1, 0
	v_cndmask_b32_e32 v48, v19, v48, vcc
	v_pk_mul_f32 v[46:47], v[46:47], v[48:49] op_sel_hi:[1,0]
.LBB0_308:
	global_store_dwordx2 v[30:31], v[46:47], off offset:1536 sc1
	v_add_co_u32_e32 v46, vcc, 0x6b14000, v28
	s_nop 1
	v_addc_co_u32_e32 v47, vcc, 0, v29, vcc
	global_store_dwordx2 v[46:47], v[42:43], off offset:1536 sc1
	v_add_co_u32_e32 v42, vcc, 0x6b15000, v28
	s_nop 1
	v_addc_co_u32_e32 v43, vcc, 0, v29, vcc
	global_store_dwordx2 v[42:43], v[44:45], off offset:3584 sc1
	v_add_co_u32_e32 v42, vcc, 0x6b17000, v28
	s_nop 1
	v_addc_co_u32_e32 v43, vcc, 0, v29, vcc
	global_store_dwordx2 v[42:43], v[36:37], off offset:1536 sc1
	v_add_co_u32_e32 v36, vcc, 0x2000, v34
	global_load_dword v19, v[20:21], off offset:-256
	global_load_dwordx2 v[46:47], v[34:35], off offset:2048
	v_addc_co_u32_e32 v37, vcc, 0, v35, vcc
	v_add_co_u32_e32 v44, vcc, 0x2000, v32
	global_load_dwordx2 v[42:43], v[36:37], off
	s_nop 0
	global_load_dwordx2 v[36:37], v[40:41], off offset:2048
	global_load_dwordx2 v[48:49], v[32:33], off offset:2048
	v_addc_co_u32_e32 v45, vcc, 0, v33, vcc
	global_load_dwordx2 v[56:57], v[44:45], off
	global_load_dwordx2 v[58:59], v[38:39], off offset:2048
	v_add_co_u32_e32 v44, vcc, 0x5000, v32
	s_waitcnt vmcnt(2)
	v_pk_fma_f32 v[46:47], v[46:47], v[48:49], 0 op_sel_hi:[1,1,0]
	v_addc_co_u32_e32 v45, vcc, 0, v33, vcc
	global_load_dwordx2 v[60:61], v[44:45], off
	s_waitcnt vmcnt(2)
	v_pk_fma_f32 v[46:47], v[42:43], v[56:57], v[46:47]
	v_lshlrev_b32_e32 v44, 16, v19
	v_and_b32_e32 v45, 0xffff0000, v19
	s_waitcnt vmcnt(1)
	v_pk_fma_f32 v[46:47], v[36:37], v[58:59], v[46:47]
	s_waitcnt vmcnt(0)
	v_pk_fma_f32 v[46:47], v[60:61], v[44:45], v[46:47]
	s_nop 0
	v_mul_f32_e32 v19, 0xbfb8aa3b, v46
	v_mul_f32_e32 v49, 0xbfb8aa3b, v47
	v_exp_f32_e32 v48, v19
	v_exp_f32_e32 v49, v49
	s_nop 0
	v_pk_add_f32 v[48:49], v[48:49], 1.0 op_sel_hi:[1,0]
	s_nop 0
	v_div_scale_f32 v19, s[6:7], v49, v49, v47
	v_div_scale_f32 v56, s[6:7], v48, v48, v46
	v_rcp_f32_e32 v57, v19
	v_rcp_f32_e32 v58, v56
	v_div_scale_f32 v55, vcc, v47, v49, v47
	v_fma_f32 v60, -v19, v57, 1.0
	v_fma_f32 v61, -v56, v58, 1.0
	v_fmac_f32_e32 v57, v60, v57
	v_div_scale_f32 v59, s[6:7], v46, v48, v46
	v_fmac_f32_e32 v58, v61, v58
	v_mul_f32_e32 v60, v55, v57
	v_mul_f32_e32 v61, v59, v58
	v_fma_f32 v62, -v19, v60, v55
	v_fma_f32 v63, -v56, v61, v59
	v_fmac_f32_e32 v60, v62, v57
	v_fmac_f32_e32 v61, v63, v58
	v_fma_f32 v19, -v19, v60, v55
	v_fma_f32 v55, -v56, v61, v59
	v_div_fmas_f32 v19, v19, v57, v60
	s_mov_b64 vcc, s[6:7]
	v_div_fixup_f32 v47, v19, v49, v47
	v_div_fmas_f32 v19, v55, v58, v61
	s_andn2_b64 vcc, exec, s[4:5]
	v_div_fixup_f32 v46, v19, v48, v46
	s_cbranch_vccnz .LBB0_310
; DI float bflo(unsigned u) { return __uint_as_float(u << 16); }
; DI float bfhi(unsigned u) { return __uint_as_float(u & 0xffff0000u); }
; DI float siluf_(float x) { return x / (1.0f + __expf(-x)); }
; template <bool IS_P, bool EDGE>
; DI void qkv_token(const Params& p, int row, int lane) {
;     ...
;   for (int grp = 0; grp < 12; ++grp) {
;     const int ch = grp * 128 + lane * 2;
;     float x0[4], x1[4];
;     if (IS_P) {
;       unsigned u[4];
; #pragma unroll
;       for (int j = 0; j < 4; ++j) {
;         const int rc = (!EDGE || t - 3 + j >= 0) ? (row - 3 + j) : row;
;         u[j] = *(const unsigned*)(p.PB + (size_t)rc * EINP + 1536 + ch);
;       }
; #pragma unroll
;       for (int j = 0; j < 4; ++j) {
;         const bool ok = (!EDGE || t - 3 + j >= 0);
;         x0[j] = ok ? bflo(u[j]) : 0.f;
;         x1[j] = ok ? bfhi(u[j]) : 0.f;
;       }
;     } else {
; #pragma unroll
;       for (int j = 0; j < 3; ++j) {
;         float2 f = *(const float2*)(p.state_qkv_conv + ((size_t)s * 3 + j) * 1536 + ch);
;         x0[j] = f.x; x1[j] = f.y;
;       }
;       unsigned u = *(const unsigned*)(p.PB + (size_t)row * EINP + 1536 + ch);
;       x0[3] = bflo(u); x1[3] = bfhi(u);
;     }
;     float a0 = 0.f, a1 = 0.f;
; #pragma unroll
;     for (int j = 0; j < 4; ++j) {
;       float2 w = *(const float2*)(p.sc_w + (size_t)j * 1536 + ch);
;       a0 += w.x * x0[j]; a1 += w.y * x1[j];
;     }
;     float y0 = siluf_(a0), y1 = siluf_(a1);
;     if (grp < 8) {
;       float ss = wave_sum(y0 * y0 + y1 * y1);
;       float inv = rsqrtf(ss + EPSF);
;       if (grp < 4) inv *= 0.08838834764831845f;
;       y0 *= inv; y1 *= inv;
;     }
;     float2 o = {y0, y1};
;     *(float2*)(p.QKV + (size_t)row * 1536 + ch) = o;
;     if (IS_P) {
;       if (t >= 2045) {
;         float2 c = {x0[3], x1[3]};
;         *(float2*)(p.out + O_QKVP + ((size_t)b * 3 + (t - 2045)) * 1536 + ch) = c;
;       }
;     } else {
;       float2 c0 = {x0[1], x1[1]}, c1 = {x0[2], x1[2]}, c2 = {x0[3], x1[3]};
;       *(float2*)(p.out + O_QKVS + ((size_t)s * 3 + 0) * 1536 + ch) = c0;
;       *(float2*)(p.out + O_QKVS + ((size_t)s * 3 + 1) * 1536 + ch) = c1;
;       *(float2*)(p.out + O_QKVS + ((size_t)s * 3 + 2) * 1536 + ch) = c2;
;     }
;   }
	v_pk_mul_f32 v[48:49], v[46:47], v[46:47]
	s_nop 0
	v_add_f32_e32 v19, v48, v49
	v_mov_b32_e32 v48, 0
	s_nop 0
	v_add_f32_dpp v19, v19, v19 quad_perm:[1,0,3,2] row_mask:0xf bank_mask:0xf bound_ctrl:1
	s_nop 1
	v_add_f32_dpp v19, v19, v19 quad_perm:[2,3,0,1] row_mask:0xf bank_mask:0xf bound_ctrl:1
	s_nop 1
	v_add_f32_dpp v19, v19, v19 row_half_mirror row_mask:0xf bank_mask:0xf bound_ctrl:1
	s_nop 1
	v_add_f32_dpp v19, v19, v19 row_mirror row_mask:0xf bank_mask:0xf bound_ctrl:1
	s_nop 1
	v_mov_b32_dpp v48, v19 row_bcast:15 row_mask:0xa bank_mask:0xf
	v_add_f32_e32 v19, v19, v48
	v_mov_b32_e32 v48, 0
	s_nop 1
	v_mov_b32_dpp v48, v19 row_bcast:31 row_mask:0xc bank_mask:0xf
	v_add_f32_e32 v19, v19, v48
	s_nop 0
	v_readlane_b32 s4, v19, 63
	s_nop 1
	v_add_f32_e32 v19, s4, v50
	v_mul_f32_e32 v48, 0x4b800000, v19
	v_cmp_gt_f32_e32 vcc, s25, v19
	s_nop 1
	v_cndmask_b32_e32 v19, v19, v48, vcc
	v_rsq_f32_e32 v19, v19
	s_nop 0
	v_mul_f32_e32 v48, 0x45800000, v19
	v_cndmask_b32_e32 v48, v19, v48, vcc
	v_pk_mul_f32 v[46:47], v[46:47], v[48:49] op_sel_hi:[1,0]
.LBB0_310:
	global_store_dwordx2 v[30:31], v[46:47], off offset:2048 sc1
	v_add_co_u32_e32 v46, vcc, 0x6b14000, v28
	s_cmp_gt_u32 s38, 2
	s_nop 0
	v_addc_co_u32_e32 v47, vcc, 0, v29, vcc
	global_store_dwordx2 v[46:47], v[42:43], off offset:2048 sc1
	v_add_co_u32_e32 v42, vcc, 0x6b16000, v28
	s_nop 1
	v_addc_co_u32_e32 v43, vcc, 0, v29, vcc
	global_store_dwordx2 v[42:43], v[36:37], off sc1
	v_add_co_u32_e32 v36, vcc, 0x6b17000, v28
	s_nop 1
	v_addc_co_u32_e32 v37, vcc, 0, v29, vcc
	global_store_dwordx2 v[36:37], v[44:45], off offset:2048 sc1
	v_add_co_u32_e32 v44, vcc, 0x2000, v34
	global_load_dword v19, v[20:21], off
	global_load_dwordx2 v[42:43], v[34:35], off offset:2560
	v_addc_co_u32_e32 v45, vcc, 0, v35, vcc
	global_load_dwordx2 v[36:37], v[44:45], off offset:512
	global_load_dwordx2 v[34:35], v[40:41], off offset:2560
	global_load_dwordx2 v[46:47], v[32:33], off offset:2560
	v_add_co_u32_e32 v40, vcc, 0x2000, v32
	s_nop 1
	v_addc_co_u32_e32 v41, vcc, 0, v33, vcc
	v_add_co_u32_e32 v32, vcc, 0x5000, v32
	s_nop 1
	v_addc_co_u32_e32 v33, vcc, 0, v33, vcc
	global_load_dwordx2 v[44:45], v[40:41], off offset:512
	global_load_dwordx2 v[48:49], v[38:39], off offset:2560
	global_load_dwordx2 v[56:57], v[32:33], off offset:512
	s_waitcnt vmcnt(7)
	v_lshlrev_b32_e32 v32, 16, v19
	v_and_b32_e32 v33, 0xffff0000, v19
	s_waitcnt vmcnt(3)
	v_pk_fma_f32 v[38:39], v[42:43], v[46:47], 0 op_sel_hi:[1,1,0]
	s_waitcnt vmcnt(2)
	v_pk_fma_f32 v[38:39], v[36:37], v[44:45], v[38:39]
	s_waitcnt vmcnt(1)
	v_pk_fma_f32 v[38:39], v[34:35], v[48:49], v[38:39]
	s_waitcnt vmcnt(0)
	v_pk_fma_f32 v[38:39], v[56:57], v[32:33], v[38:39]
	s_nop 0
	v_mul_f32_e32 v19, 0xbfb8aa3b, v38
	v_mul_f32_e32 v41, 0xbfb8aa3b, v39
	v_exp_f32_e32 v40, v19
	v_exp_f32_e32 v41, v41
	s_nop 0
	v_pk_add_f32 v[40:41], v[40:41], 1.0 op_sel_hi:[1,0]
	s_nop 0
	v_div_scale_f32 v19, s[4:5], v41, v41, v39
	v_div_scale_f32 v43, s[4:5], v40, v40, v38
	v_rcp_f32_e32 v44, v19
	v_rcp_f32_e32 v45, v43
	v_div_scale_f32 v42, vcc, v39, v41, v39
	v_fma_f32 v47, -v19, v44, 1.0
	v_fma_f32 v48, -v43, v45, 1.0
	v_fmac_f32_e32 v44, v47, v44
	v_div_scale_f32 v46, s[4:5], v38, v40, v38
	v_fmac_f32_e32 v45, v48, v45
	v_mul_f32_e32 v47, v42, v44
	v_mul_f32_e32 v48, v46, v45
	v_fma_f32 v49, -v19, v47, v42
	v_fma_f32 v55, -v43, v48, v46
	v_fmac_f32_e32 v47, v49, v44
	v_fmac_f32_e32 v48, v55, v45
	v_fma_f32 v19, -v19, v47, v42
	v_fma_f32 v42, -v43, v48, v46
	v_div_fmas_f32 v19, v19, v44, v47
	s_mov_b64 vcc, s[4:5]
	v_div_fixup_f32 v39, v19, v41, v39
	v_div_fmas_f32 v19, v42, v45, v48
	v_div_fixup_f32 v38, v19, v40, v38
	s_cbranch_scc1 .LBB0_303
	v_pk_mul_f32 v[40:41], v[38:39], v[38:39]
	s_nop 0
	v_add_f32_e32 v19, v40, v41
	v_mov_b32_e32 v40, 0
	s_nop 0
	v_add_f32_dpp v19, v19, v19 quad_perm:[1,0,3,2] row_mask:0xf bank_mask:0xf bound_ctrl:1
	s_nop 1
	v_add_f32_dpp v19, v19, v19 quad_perm:[2,3,0,1] row_mask:0xf bank_mask:0xf bound_ctrl:1
	s_nop 1
	v_add_f32_dpp v19, v19, v19 row_half_mirror row_mask:0xf bank_mask:0xf bound_ctrl:1
	s_nop 1
	v_add_f32_dpp v19, v19, v19 row_mirror row_mask:0xf bank_mask:0xf bound_ctrl:1
	s_nop 1
	v_mov_b32_dpp v40, v19 row_bcast:15 row_mask:0xa bank_mask:0xf
	v_add_f32_e32 v19, v19, v40
	v_mov_b32_e32 v40, 0
	s_nop 1
	v_mov_b32_dpp v40, v19 row_bcast:31 row_mask:0xc bank_mask:0xf
	v_add_f32_e32 v19, v19, v40
	s_nop 0
	v_readlane_b32 s4, v19, 63
	s_nop 1
	v_add_f32_e32 v19, s4, v50
	v_mul_f32_e32 v40, 0x4b800000, v19
	v_cmp_gt_f32_e32 vcc, s25, v19
	s_nop 1
	v_cndmask_b32_e32 v19, v19, v40, vcc
	v_rsq_f32_e32 v19, v19
	s_nop 0
	v_mul_f32_e32 v40, 0x45800000, v19
	v_cndmask_b32_e32 v40, v19, v40, vcc
	v_pk_mul_f32 v[38:39], v[38:39], v[40:41] op_sel_hi:[1,0]
	s_branch .LBB0_303

; DI void chunk_prep(const Params& p, int item, char* smem) {
;     ...
;   {
;     uint4* WN = p.WN + (size_t)item * 1024;
; #pragma unroll
;     for (int i = 0; i < 4; ++i) {
;       int idx = tid + i * 256, f = idx >> 6, ln = idx & 63, mt = f >> 3, ks = f & 7, m = ln & 31, h2 = ln >> 5;
;       int ri = mt * 32 + m, d0 = ks * 16 + h2 * 4;
;       uint2 a = *(const uint2*)(wsb + ri * 136 + d0), c = *(const uint2*)(wsb + ri * 136 + d0 + 8);
;       uint4 o = {a.x, a.y, c.x, c.y};
;       WN[f * 64 + ln] = o;
;     }
;   }
;   __syncthreads();
.LBB0_372:
	s_or_b64 exec, exec, s[48:49]
	s_lshl_b64 s[48:49], s[2:3], 10
	s_waitcnt lgkmcnt(0)
	s_barrier
	ds_read2_b64 v[0:3], v100 offset0:128 offset1:130
	s_lshl_b64 s[48:49], s[48:49], 4
	v_readlane_b32 s36, v254, 57
	v_readlane_b32 s37, v254, 58
	s_add_u32 s48, s36, s48
	s_addc_u32 s49, s37, s49
	v_lshl_add_u64 v[4:5], v[196:197], 4, s[48:49]
	s_waitcnt lgkmcnt(0)
	global_store_dwordx4 v[4:5], v[0:3], off sc1
	ds_read2_b64 v[0:3], v101 offset0:128 offset1:130
	s_add_i32 s2, s2, s34
	s_add_i32 s47, s47, s33
	s_cmpk_lt_i32 s2, 0x400
	v_readlane_b32 s38, v254, 59
	s_waitcnt lgkmcnt(0)
	global_store_dwordx4 v137, v[0:3], s[48:49] sc1
	ds_read2_b64 v[0:3], v102 offset0:128 offset1:130
	v_readlane_b32 s39, v254, 60
	v_readlane_b32 s40, v254, 61
	v_readlane_b32 s41, v254, 62
	v_readlane_b32 s42, v254, 63
	s_waitcnt lgkmcnt(0)
	global_store_dwordx4 v138, v[0:3], s[48:49] sc1
	ds_read2_b64 v[0:3], v103 offset0:128 offset1:130
	v_readlane_b32 s43, v253, 0
	s_waitcnt lgkmcnt(0)
	global_store_dwordx4 v139, v[0:3], s[48:49] sc1
	s_waitcnt vmcnt(63) expcnt(7) lgkmcnt(15)
	s_barrier
	s_cbranch_scc0 .LBB0_444

; DI bfr f2bf(float a) { return (bfr)(pack2(a, 0.f) & 0xffffu); }
; DI int crow(int reg, int h) { return (reg & 3) + 8 * (reg >> 2) + 4 * h; }
; DI void chunk_prep(const Params& p, int item, char* smem) {
;     ...
;     bfr* qkf = (bfr*)(p.QKF + (size_t)item * 512);
; #pragma unroll
;     for (int q = 0; q < 16; ++q) {
;       int i = mi * 32 + crow(q, hl), j = ni * 32 + r;
;       float dec = (i >= j) ? __expf(gcs[i] - gcs[j]) : 0.f;
;       Am[i * 68 + j] = (i > j) ? akk[q] * betas[i] * dec : 0.f;
;       float qv = (i >= j) ? aqk[q] * dec : 0.f;
;       int ksj = j >> 4, jl = j & 15, h2 = (jl >> 2) & 1, jj = ((jl >> 3) << 2) | (jl & 3);
;       qkf[((mi * 4 + ksj) * 64 + h2 * 32 + (i & 31)) * 8 + jj] = f2bf(qv);
;     }
;   }
;   {
;     uint4* QD = p.QD + (size_t)item * 1024;
; #pragma unroll
;     for (int i = 0; i < 4; ++i) {
;       int idx = tid + i * 256, f = idx >> 6, ln = idx & 63, mt = f >> 3, ks = f & 7, m = ln & 31, h2 = ln >> 5;
;       int ri = mt * 32 + m, d0 = ks * 16 + h2 * 4;
;       float sc = egs[ri];
;       const float* src = p.QKV + (row0 + ri) * 1536 + hh * 128 + d0;
;       float4 a = *(const float4*)src, c = *(const float4*)(src + 8);
;       uint4 o;
;       o.x = pack2(a.x * sc, a.y * sc); o.y = pack2(a.z * sc, a.w * sc);
;       o.z = pack2(c.x * sc, c.y * sc); o.w = pack2(c.z * sc, c.w * sc);
;       QD[f * 64 + ln] = o;
;     }
;     uint4* KD = p.KD + (size_t)item * 1024;
; #pragma unroll
;     for (int i = 0; i < 4; ++i) {
;       int idx = tid + i * 256, f = idx >> 6, ln = idx & 63, mt = f >> 2, ks = f & 3, m = ln & 31, h2 = ln >> 5;
;       int d = mt * 32 + m;
;       float vals[8];
; #pragma unroll
;       for (int j = 0; j < 8; ++j) {
;         int c = ks * 16 + 8 * (j >> 2) + 4 * h2 + (j & 3);
;         vals[j] = p.QKV[(row0 + c) * 1536 + 512 + hh * 128 + d] * kscale[c];
;       }
;       uint4 o;
;       o.x = pack2(vals[0], vals[1]); o.y = pack2(vals[2], vals[3]);
;       o.z = pack2(vals[4], vals[5]); o.w = pack2(vals[6], vals[7]);
;       KD[f * 64 + ln] = o;
;     }
.LBB0_440:
	s_or_b64 exec, exec, s[50:51]
	v_mul_f32_e32 v0, v15, v0
	v_cvt_pk_bf16_f32 v0, v0, s0
	v_cndmask_b32_e64 v0, v0, 0, s[10:11]
	global_store_short v136, v0, vcc
	v_or_b32_e32 v0, s48, v50
	v_mov_b64_e32 v[18:19], s[44:45]
	ds_write_b32 v135, v1 offset:35840
	v_mad_u64_u32 v[0:1], s[54:55], v0, s52, v[18:19]
	v_add_u32_e32 v1, s53, v1
	v_lshl_add_u64 v[0:1], v[0:1], 0, s[30:31]
	v_mov_b32_e32 v77, v33
	v_lshl_add_u64 v[4:5], v[0:1], 0, v[76:77]
	global_load_dwordx4 v[0:3], v[4:5], off
	ds_read_b32 v6, v94 offset:512
	v_readlane_b32 s36, v254, 57
	s_lshl_b64 vcc, s[2:3], 14
	v_readlane_b32 s38, v254, 59
	v_readlane_b32 s39, v254, 60
	s_add_u32 s50, s38, vcc_lo
	s_addc_u32 s51, s39, vcc_hi
	v_lshlrev_b64 v[16:17], 4, v[196:197]
	v_mov_b32_e32 v79, v33
	v_mov_b32_e32 v81, v33
	v_mov_b32_e32 v83, v33
	v_readlane_b32 s40, v254, 61
	v_readlane_b32 s41, v254, 62
	s_add_u32 vcc_lo, s40, vcc_lo
	s_addc_u32 vcc_hi, s41, vcc_hi
	v_mov_b32_e32 v85, v33
	v_mov_b32_e32 v87, v33
	v_mov_b32_e32 v89, v33
	v_readlane_b32 s37, v254, 58
	v_readlane_b32 s42, v254, 63
	v_readlane_b32 s43, v253, 0
	s_waitcnt vmcnt(0) lgkmcnt(0)
	v_pk_mul_f32 v[0:1], v[6:7], v[0:1] op_sel_hi:[0,1]
	v_pk_mul_f32 v[2:3], v[6:7], v[2:3] op_sel_hi:[0,1]
	v_cvt_pk_bf16_f32 v0, v0, v1
	v_cvt_pk_bf16_f32 v1, v2, v3
	global_load_dwordx4 v[2:5], v[4:5], off offset:32
	s_waitcnt vmcnt(0)
	v_pk_mul_f32 v[2:3], v[6:7], v[2:3] op_sel_hi:[0,1]
	v_pk_mul_f32 v[4:5], v[6:7], v[4:5] op_sel_hi:[0,1]
	v_cvt_pk_bf16_f32 v2, v2, v3
	v_cvt_pk_bf16_f32 v3, v4, v5
	v_lshl_add_u64 v[4:5], s[50:51], 0, v[16:17]
	global_store_dwordx4 v[4:5], v[0:3], off sc1
	ds_read_b32 v6, v95 offset:512
	v_lshl_add_u64 v[16:17], vcc, 0, v[16:17]
	v_lshl_add_u64 v[0:1], s[48:49], 0, v[52:53]
	v_mad_u64_u32 v[2:3], s[54:55], v0, s52, v[18:19]
	v_mov_b32_e32 v0, v3
	v_mad_u64_u32 v[0:1], s[54:55], v1, s52, v[0:1]
	v_mov_b32_e32 v3, v0
	v_lshl_add_u64 v[0:1], v[2:3], 0, s[30:31]
	v_lshl_add_u64 v[4:5], v[0:1], 0, v[78:79]
	global_load_dwordx4 v[0:3], v[4:5], off
	s_waitcnt vmcnt(0) lgkmcnt(0)
	v_pk_mul_f32 v[0:1], v[6:7], v[0:1] op_sel_hi:[0,1]
	v_pk_mul_f32 v[2:3], v[6:7], v[2:3] op_sel_hi:[0,1]
	v_cvt_pk_bf16_f32 v0, v0, v1
	v_cvt_pk_bf16_f32 v1, v2, v3
	global_load_dwordx4 v[2:5], v[4:5], off offset:32
	s_waitcnt vmcnt(0)
	v_pk_mul_f32 v[2:3], v[6:7], v[2:3] op_sel_hi:[0,1]
	v_pk_mul_f32 v[4:5], v[6:7], v[4:5] op_sel_hi:[0,1]
	v_cvt_pk_bf16_f32 v2, v2, v3
	v_cvt_pk_bf16_f32 v3, v4, v5
	global_store_dwordx4 v137, v[0:3], s[50:51] sc1
	ds_read_b32 v6, v96 offset:512
	s_nop 0
	v_lshl_add_u64 v[0:1], s[48:49], 0, v[54:55]
	v_mad_u64_u32 v[2:3], s[54:55], v0, s52, v[18:19]
	v_mov_b32_e32 v0, v3
	v_mad_u64_u32 v[0:1], s[54:55], v1, s52, v[0:1]
	v_mov_b32_e32 v3, v0
	v_lshl_add_u64 v[0:1], v[2:3], 0, s[30:31]
	v_lshl_add_u64 v[4:5], v[0:1], 0, v[76:77]
	global_load_dwordx4 v[0:3], v[4:5], off
	v_or_b32_e32 v77, s48, v70
	s_waitcnt vmcnt(0) lgkmcnt(0)
	v_pk_mul_f32 v[0:1], v[6:7], v[0:1] op_sel_hi:[0,1]
	v_pk_mul_f32 v[2:3], v[6:7], v[2:3] op_sel_hi:[0,1]
	v_cvt_pk_bf16_f32 v0, v0, v1
	v_cvt_pk_bf16_f32 v1, v2, v3
	global_load_dwordx4 v[2:5], v[4:5], off offset:32
	s_waitcnt vmcnt(0)
	v_pk_mul_f32 v[2:3], v[6:7], v[2:3] op_sel_hi:[0,1]
	v_pk_mul_f32 v[4:5], v[6:7], v[4:5] op_sel_hi:[0,1]
	v_cvt_pk_bf16_f32 v2, v2, v3
	v_cvt_pk_bf16_f32 v3, v4, v5
	global_store_dwordx4 v138, v[0:3], s[50:51] sc1
	ds_read_b32 v6, v97 offset:512
	s_nop 0
	v_lshl_add_u64 v[0:1], s[48:49], 0, v[56:57]
	v_mad_u64_u32 v[2:3], s[54:55], v0, s52, v[18:19]
	v_mov_b32_e32 v0, v3
	v_mad_u64_u32 v[0:1], s[54:55], v1, s52, v[0:1]
	v_mov_b32_e32 v3, v0
	v_lshl_add_u64 v[0:1], v[2:3], 0, s[30:31]
	v_lshl_add_u64 v[4:5], v[0:1], 0, v[80:81]
	global_load_dwordx4 v[0:3], v[4:5], off
	s_waitcnt vmcnt(0) lgkmcnt(0)
	v_pk_mul_f32 v[0:1], v[6:7], v[0:1] op_sel_hi:[0,1]
	v_pk_mul_f32 v[2:3], v[6:7], v[2:3] op_sel_hi:[0,1]
	v_cvt_pk_bf16_f32 v0, v0, v1
	v_cvt_pk_bf16_f32 v1, v2, v3
	global_load_dwordx4 v[2:5], v[4:5], off offset:32
	s_waitcnt vmcnt(0)
	v_pk_mul_f32 v[2:3], v[6:7], v[2:3] op_sel_hi:[0,1]
	v_pk_mul_f32 v[4:5], v[6:7], v[4:5] op_sel_hi:[0,1]
	v_cvt_pk_bf16_f32 v2, v2, v3
	v_cvt_pk_bf16_f32 v3, v4, v5
	global_store_dwordx4 v139, v[0:3], s[50:51] sc1
	s_nop 1
	v_or_b32_e32 v0, s48, v58
	v_mad_u64_u32 v[0:1], s[50:51], v0, s52, v[18:19]
	v_add_u32_e32 v1, s53, v1
	v_lshl_add_u64 v[20:21], v[0:1], 0, s[30:31]
	v_lshl_add_u64 v[0:1], v[20:21], 0, v[82:83]
	global_load_dword v4, v[0:1], off offset:2048
	v_or_b32_e32 v0, s48, v60
	v_mad_u64_u32 v[0:1], s[50:51], v0, s52, v[18:19]
	v_add_u32_e32 v1, s53, v1
	v_lshl_add_u64 v[22:23], v[0:1], 0, s[30:31]
	v_lshl_add_u64 v[0:1], v[22:23], 0, v[82:83]
	global_load_dword v5, v[0:1], off offset:2048
	ds_read2_b64 v[0:3], v98 offset0:96 offset1:97
	s_waitcnt vmcnt(0) lgkmcnt(0)
	v_pk_mul_f32 v[92:93], v[4:5], v[0:1]
	v_or_b32_e32 v4, s48, v62
	v_mad_u64_u32 v[4:5], s[50:51], v4, s52, v[18:19]
	v_add_u32_e32 v5, s53, v5
	v_lshl_add_u64 v[24:25], v[4:5], 0, s[30:31]
	v_lshl_add_u64 v[4:5], v[24:25], 0, v[82:83]
	global_load_dword v12, v[4:5], off offset:2048
	v_or_b32_e32 v4, s48, v64
	v_mad_u64_u32 v[4:5], s[50:51], v4, s52, v[18:19]
	v_add_u32_e32 v5, s53, v5
	v_lshl_add_u64 v[26:27], v[4:5], 0, s[30:31]
	v_lshl_add_u64 v[4:5], v[26:27], 0, v[82:83]
	global_load_dword v13, v[4:5], off offset:2048
	ds_read_b128 v[8:11], v98 offset:768
	ds_read_b128 v[4:7], v98 offset:800
	s_waitcnt vmcnt(0) lgkmcnt(1)
; DI void chunk_prep(const Params& p, int item, char* smem) {
;     ...
;     uint4* KD = p.KD + (size_t)item * 1024;
; #pragma unroll
;     for (int i = 0; i < 4; ++i) {
;       int idx = tid + i * 256, f = idx >> 6, ln = idx & 63, mt = f >> 2, ks = f & 3, m = ln & 31, h2 = ln >> 5;
;       int d = mt * 32 + m;
;       float vals[8];
; #pragma unroll
;       for (int j = 0; j < 8; ++j) {
;         int c = ks * 16 + 8 * (j >> 2) + 4 * h2 + (j & 3);
;         vals[j] = p.QKV[(row0 + c) * 1536 + 512 + hh * 128 + d] * kscale[c];
;       }
;       uint4 o;
;       o.x = pack2(vals[0], vals[1]); o.y = pack2(vals[2], vals[3]);
;       o.z = pack2(vals[4], vals[5]); o.w = pack2(vals[6], vals[7]);
;       KD[f * 64 + ln] = o;
;     }
	v_pk_mul_f32 v[210:211], v[12:13], v[10:11]
	v_or_b32_e32 v12, s48, v66
	v_mad_u64_u32 v[12:13], s[50:51], v12, s52, v[18:19]
	v_add_u32_e32 v13, s53, v13
	v_lshl_add_u64 v[28:29], v[12:13], 0, s[30:31]
	v_lshl_add_u64 v[12:13], v[28:29], 0, v[82:83]
	global_load_dword v90, v[12:13], off offset:2048
	v_or_b32_e32 v12, s48, v68
	v_mad_u64_u32 v[12:13], s[50:51], v12, s52, v[18:19]
	v_add_u32_e32 v13, s53, v13
	v_lshl_add_u64 v[30:31], v[12:13], 0, s[30:31]
	v_lshl_add_u64 v[12:13], v[30:31], 0, v[82:83]
	global_load_dword v91, v[12:13], off offset:2048
	ds_read2_b64 v[12:15], v98 offset0:100 offset1:101
	s_waitcnt vmcnt(0) lgkmcnt(0)
	v_pk_mul_f32 v[212:213], v[90:91], v[12:13]
	v_mad_u64_u32 v[90:91], s[50:51], v77, s52, v[18:19]
	v_or_b32_e32 v77, s48, v72
	v_mad_u64_u32 v[18:19], s[48:49], v77, s52, v[18:19]
	v_add_u32_e32 v91, s53, v91
	v_add_u32_e32 v19, s53, v19
	v_lshl_add_u64 v[90:91], v[90:91], 0, s[30:31]
	v_lshl_add_u64 v[18:19], v[18:19], 0, s[30:31]
	v_lshl_add_u64 v[208:209], v[90:91], 0, v[82:83]
	v_lshl_add_u64 v[214:215], v[18:19], 0, v[82:83]
	global_load_dword v208, v[208:209], off offset:2048
	s_nop 0
	global_load_dword v209, v[214:215], off offset:2048
	s_waitcnt vmcnt(0)
	v_pk_mul_f32 v[214:215], v[208:209], v[6:7]
	v_cvt_pk_bf16_f32 v208, v92, v93
	v_cvt_pk_bf16_f32 v209, v210, v211
	v_cvt_pk_bf16_f32 v210, v212, v213
	v_cvt_pk_bf16_f32 v211, v214, v215
	global_store_dwordx4 v[16:17], v[208:211], off sc1
	v_lshl_add_u64 v[16:17], v[20:21], 0, v[84:85]
	v_lshl_add_u64 v[92:93], v[22:23], 0, v[84:85]
	global_load_dword v16, v[16:17], off offset:2048
	s_nop 0
	global_load_dword v17, v[92:93], off offset:2048
	v_lshl_add_u64 v[92:93], v[26:27], 0, v[84:85]
	s_waitcnt vmcnt(0)
	v_pk_mul_f32 v[0:1], v[16:17], v[0:1]
	v_lshl_add_u64 v[16:17], v[24:25], 0, v[84:85]
	global_load_dword v16, v[16:17], off offset:2048
	s_nop 0
	global_load_dword v17, v[92:93], off offset:2048
	v_lshl_add_u64 v[92:93], v[30:31], 0, v[84:85]
	s_waitcnt vmcnt(0)
	v_pk_mul_f32 v[16:17], v[16:17], v[10:11]
	v_lshl_add_u64 v[10:11], v[28:29], 0, v[84:85]
	global_load_dword v10, v[10:11], off offset:2048
	s_nop 0
	global_load_dword v11, v[92:93], off offset:2048
	v_lshl_add_u64 v[92:93], v[18:19], 0, v[84:85]
	s_waitcnt vmcnt(0)
	v_pk_mul_f32 v[12:13], v[10:11], v[12:13]
	v_lshl_add_u64 v[10:11], v[90:91], 0, v[84:85]
	global_load_dword v10, v[10:11], off offset:2048
	v_cvt_pk_bf16_f32 v12, v12, v13
	global_load_dword v11, v[92:93], off offset:2048
	s_waitcnt vmcnt(0)
	v_pk_mul_f32 v[92:93], v[10:11], v[6:7]
	v_cvt_pk_bf16_f32 v10, v0, v1
	v_cvt_pk_bf16_f32 v11, v16, v17
	v_cvt_pk_bf16_f32 v13, v92, v93
	global_store_dwordx4 v137, v[10:13], vcc sc1
	v_lshl_add_u64 v[0:1], v[20:21], 0, v[86:87]
	global_load_dword v0, v[0:1], off offset:2048
	v_lshl_add_u64 v[10:11], v[22:23], 0, v[86:87]
	global_load_dword v1, v[10:11], off offset:2048
	v_lshl_add_u64 v[10:11], v[24:25], 0, v[86:87]
	v_lshl_add_u64 v[12:13], v[26:27], 0, v[86:87]
	global_load_dword v10, v[10:11], off offset:2048
	v_lshl_add_u64 v[16:17], v[30:31], 0, v[86:87]
	global_load_dword v11, v[12:13], off offset:2048
	v_mov_b32_e32 v6, v14
	s_waitcnt vmcnt(2)
	v_pk_mul_f32 v[0:1], v[0:1], v[8:9]
	s_waitcnt vmcnt(0)
	v_pk_mul_f32 v[12:13], v[10:11], v[2:3]
	v_lshl_add_u64 v[10:11], v[28:29], 0, v[86:87]
	global_load_dword v10, v[10:11], off offset:2048
	s_nop 0
	global_load_dword v11, v[16:17], off offset:2048
	s_waitcnt vmcnt(0)
	v_pk_mul_f32 v[16:17], v[10:11], v[4:5]
	v_lshl_add_u64 v[10:11], v[90:91], 0, v[86:87]
	global_load_dword v92, v[10:11], off offset:2048
	v_lshl_add_u64 v[10:11], v[18:19], 0, v[86:87]
	global_load_dword v93, v[10:11], off offset:2048
	v_cvt_pk_bf16_f32 v10, v0, v1
	v_cvt_pk_bf16_f32 v11, v12, v13
	v_cvt_pk_bf16_f32 v12, v16, v17
	v_lshl_add_u64 v[0:1], v[20:21], 0, v[88:89]
	v_lshl_add_u64 v[20:21], v[24:25], 0, v[88:89]
	v_lshl_add_u64 v[16:17], v[22:23], 0, v[88:89]
	v_lshl_add_u64 v[22:23], v[26:27], 0, v[88:89]
	v_lshl_add_u64 v[24:25], v[28:29], 0, v[88:89]
	v_lshl_add_u64 v[26:27], v[30:31], 0, v[88:89]
	v_lshl_add_u64 v[28:29], v[90:91], 0, v[88:89]
	v_lshl_add_u64 v[18:19], v[18:19], 0, v[88:89]
	s_waitcnt vmcnt(0)
	v_pk_mul_f32 v[6:7], v[92:93], v[6:7]
	s_nop 0
	v_cvt_pk_bf16_f32 v13, v6, v7
	global_store_dwordx4 v138, v[10:13], vcc sc1
	global_load_dword v0, v[0:1], off offset:2048
	s_nop 0
	global_load_dword v1, v[16:17], off offset:2048
	global_load_dword v6, v[20:21], off offset:2048
	global_load_dword v7, v[22:23], off offset:2048
	s_waitcnt vmcnt(2)
	v_pk_mul_f32 v[0:1], v[0:1], v[8:9]
	s_waitcnt vmcnt(0)
	v_pk_mul_f32 v[2:3], v[6:7], v[2:3]
	global_load_dword v6, v[24:25], off offset:2048
	global_load_dword v7, v[26:27], off offset:2048
	v_cvt_pk_bf16_f32 v0, v0, v1
	v_cvt_pk_bf16_f32 v1, v2, v3
	s_waitcnt vmcnt(0)
	v_pk_mul_f32 v[4:5], v[6:7], v[4:5]
	global_load_dword v6, v[28:29], off offset:2048
	global_load_dword v7, v[18:19], off offset:2048
	v_cvt_pk_bf16_f32 v2, v4, v5
	s_waitcnt vmcnt(0)
	v_pk_mul_f32 v[6:7], v[6:7], v[14:15]
	s_nop 0
	v_cvt_pk_bf16_f32 v3, v6, v7
	global_store_dwordx4 v139, v[0:3], vcc sc1
	s_barrier
; DI void chunk_prep(const Params& p, int item, char* smem) {
;     ...
;   {
;     const int c = tid;
;     float sol[64];
; #pragma unroll
;     for (int i = 0; i < 64; ++i) {
;       float rhs = rraw[i] * betas[i];
;       if (c >= 128) rhs *= egs[i];
;       float acc = rhs, acc1 = 0.f;
; #pragma unroll
;       for (int j = 0; j < i; ++j) {
;         if (j & 1) acc1 -= Am[i * 68 + j] * sol[j];
;         else acc -= Am[i * 68 + j] * sol[j];
;       }
;       sol[i] = acc + acc1;
;     }
	ds_read_b128 v[8:11], v33 offset:256
	ds_read_b128 v[12:15], v33 offset:272
	ds_read_b128 v[4:7], v33 offset:288
	ds_read_b128 v[0:3], v33 offset:304
	ds_read_b128 v[16:19], v33 offset:512
	ds_read_b128 v[90:93], v33 offset:41280
	s_waitcnt lgkmcnt(5)
	v_mul_f32_e32 v8, v206, v8
	v_mul_f32_e32 v9, v207, v9
	v_mul_f32_e32 v10, v205, v10
	s_waitcnt lgkmcnt(1)
	v_mul_f32_e32 v16, v8, v16
	v_cndmask_b32_e64 v8, v8, v16, s[8:9]
	v_mul_f32_e32 v16, v9, v17
	v_cndmask_b32_e64 v9, v9, v16, s[8:9]
	ds_read_b32 v16, v33 offset:36112
	v_add_f32_e32 v8, 0, v8
	v_mul_f32_e32 v11, v204, v11
	ds_read_b128 v[20:23], v33 offset:36928
	ds_read_b128 v[28:31], v33 offset:40192
	s_waitcnt lgkmcnt(2)
	v_fma_f32 v9, -v16, v8, v9
	v_mul_f32_e32 v16, v10, v18
	v_cndmask_b32_e64 v10, v10, v16, s[8:9]
	ds_read_b64 v[16:17], v33 offset:36384
	v_add_f32_e32 v9, 0, v9
	v_mul_f32_e32 v12, v203, v12
	v_mul_f32_e32 v13, v202, v13
	v_mul_f32_e32 v14, v201, v14
	s_waitcnt lgkmcnt(0)
	v_fma_f32 v10, -v8, v16, v10
	v_fma_f32 v16, -v9, v17, 0
	v_add_f32_e32 v10, v10, v16
	v_mul_f32_e32 v16, v11, v19
	v_cndmask_b32_e64 v11, v11, v16, s[8:9]
	ds_read_b96 v[16:18], v33 offset:36656
	v_mul_f32_e32 v15, v200, v15
	v_mul_f32_e32 v4, v199, v4
	v_mul_f32_e32 v5, v198, v5
	v_mul_f32_e32 v6, v195, v6
	s_waitcnt lgkmcnt(0)
	v_fma_f32 v11, -v8, v16, v11
	v_fma_f32 v16, -v9, v17, 0
	v_fma_f32 v11, -v10, v18, v11
	v_add_f32_e32 v11, v16, v11
	ds_read_b128 v[16:19], v33 offset:528
	v_mul_f32_e32 v7, v194, v7
	v_mul_f32_e32 v0, v193, v0
	ds_read_b128 v[24:27], v33 offset:576
	s_waitcnt lgkmcnt(1)
	v_mul_f32_e32 v16, v12, v16
	v_cndmask_b32_e64 v12, v12, v16, s[8:9]
	v_fma_f32 v12, -v8, v20, v12
	v_fma_f32 v16, -v9, v21, 0
	v_fma_f32 v12, -v10, v22, v12
	v_fma_f32 v16, -v11, v23, v16
	ds_read_b128 v[20:23], v33 offset:37200
	v_add_f32_e32 v12, v12, v16
	v_mul_f32_e32 v16, v13, v17
	v_cndmask_b32_e64 v13, v13, v16, s[8:9]
	ds_read_b32 v17, v33 offset:37216
	s_waitcnt lgkmcnt(1)
	v_fma_f32 v13, -v8, v20, v13
	v_fma_f32 v16, -v9, v21, 0
	v_fma_f32 v13, -v10, v22, v13
	v_fma_f32 v16, -v11, v23, v16
	ds_read_b128 v[20:23], v33 offset:37472
	s_waitcnt lgkmcnt(1)
	v_fma_f32 v13, -v12, v17, v13
	v_add_f32_e32 v13, v16, v13
	v_mul_f32_e32 v16, v14, v18
	v_cndmask_b32_e64 v14, v14, v16, s[8:9]
	s_waitcnt lgkmcnt(0)
	v_fma_f32 v16, -v9, v21, 0
	v_fma_f32 v18, -v11, v23, v16
	ds_read_b64 v[16:17], v33 offset:37488
	v_fma_f32 v14, -v8, v20, v14
	v_fma_f32 v14, -v10, v22, v14
	ds_read_b128 v[20:23], v33 offset:38016
	s_waitcnt lgkmcnt(1)
	v_fma_f32 v14, -v12, v16, v14
	v_fma_f32 v16, -v13, v17, v18
	v_add_f32_e32 v14, v14, v16
	v_mul_f32_e32 v16, v15, v19
	v_cndmask_b32_e64 v15, v15, v16, s[8:9]
	ds_read_b128 v[16:19], v33 offset:37744
	s_waitcnt lgkmcnt(0)
	v_fma_f32 v15, -v8, v16, v15
	v_fma_f32 v16, -v9, v17, 0
	v_fma_f32 v15, -v10, v18, v15
	v_fma_f32 v19, -v11, v19, v16
	ds_read_b96 v[16:18], v33 offset:37760
	s_waitcnt lgkmcnt(0)
	v_fma_f32 v15, -v12, v16, v15
	v_fma_f32 v16, -v13, v17, v19
	v_fma_f32 v15, -v14, v18, v15
	v_add_f32_e32 v15, v16, v15
	ds_read_b128 v[16:19], v33 offset:544
	s_waitcnt lgkmcnt(0)
	v_mul_f32_e32 v16, v4, v16
	v_cndmask_b32_e64 v4, v4, v16, s[8:9]
	v_fma_f32 v4, -v8, v20, v4
	v_fma_f32 v16, -v9, v21, 0
	v_fma_f32 v4, -v10, v22, v4
	v_fma_f32 v16, -v11, v23, v16
	ds_read_b128 v[20:23], v33 offset:38032
	s_waitcnt lgkmcnt(0)
	v_fma_f32 v4, -v12, v20, v4
	v_fma_f32 v16, -v13, v21, v16
	v_fma_f32 v4, -v14, v22, v4
	v_fma_f32 v16, -v15, v23, v16
	ds_read_b128 v[20:23], v33 offset:38288
	v_add_f32_e32 v4, v4, v16
	v_mul_f32_e32 v16, v5, v17
	v_cndmask_b32_e64 v5, v5, v16, s[8:9]
	ds_read_b32 v17, v33 offset:38320
	s_waitcnt lgkmcnt(1)
	v_fma_f32 v5, -v8, v20, v5
	v_fma_f32 v16, -v9, v21, 0
	v_fma_f32 v5, -v10, v22, v5
	v_fma_f32 v16, -v11, v23, v16
	ds_read_b128 v[20:23], v33 offset:38304
	s_waitcnt lgkmcnt(0)
	v_fma_f32 v5, -v12, v20, v5
	v_fma_f32 v16, -v13, v21, v16
	v_fma_f32 v5, -v14, v22, v5
	v_fma_f32 v16, -v15, v23, v16
	ds_read_b128 v[20:23], v33 offset:38560
	v_fma_f32 v5, -v4, v17, v5
	v_add_f32_e32 v5, v16, v5
	v_mul_f32_e32 v16, v6, v18
	v_cndmask_b32_e64 v6, v6, v16, s[8:9]
	s_waitcnt lgkmcnt(0)
	v_fma_f32 v6, -v8, v20, v6
	v_fma_f32 v16, -v9, v21, 0
	v_fma_f32 v6, -v10, v22, v6
	v_fma_f32 v16, -v11, v23, v16
	ds_read_b128 v[20:23], v33 offset:38576
	s_waitcnt lgkmcnt(0)
	v_fma_f32 v16, -v13, v21, v16
	v_fma_f32 v18, -v15, v23, v16
	ds_read_b64 v[16:17], v33 offset:38592
	v_fma_f32 v6, -v12, v20, v6
	v_fma_f32 v6, -v14, v22, v6
	s_waitcnt lgkmcnt(0)
	v_fma_f32 v6, -v4, v16, v6
	v_fma_f32 v16, -v5, v17, v18
	v_add_f32_e32 v6, v6, v16
	v_mul_f32_e32 v16, v7, v19
	v_cndmask_b32_e64 v7, v7, v16, s[8:9]
	ds_read_b128 v[16:19], v33 offset:38832
	s_waitcnt lgkmcnt(0)
	v_fma_f32 v7, -v8, v16, v7
	v_fma_f32 v16, -v9, v17, 0
	v_fma_f32 v7, -v10, v18, v7
	v_fma_f32 v20, -v11, v19, v16
	ds_read_b128 v[16:19], v33 offset:38848
	s_waitcnt lgkmcnt(0)
	v_fma_f32 v7, -v12, v16, v7
	v_fma_f32 v16, -v13, v17, v20
	v_fma_f32 v7, -v14, v18, v7
	v_fma_f32 v19, -v15, v19, v16
	ds_read_b96 v[16:18], v33 offset:38864
	ds_read_b128 v[20:23], v33 offset:39104
	s_waitcnt lgkmcnt(1)
	v_fma_f32 v7, -v4, v16, v7
	v_fma_f32 v16, -v5, v17, v19
	v_fma_f32 v7, -v6, v18, v7
	v_add_f32_e32 v7, v16, v7
	ds_read_b128 v[16:19], v33 offset:560
	s_waitcnt lgkmcnt(0)
	v_mul_f32_e32 v16, v0, v16
	v_cndmask_b32_e64 v0, v0, v16, s[8:9]
	v_fma_f32 v0, -v8, v20, v0
	v_fma_f32 v16, -v9, v21, 0
	v_fma_f32 v0, -v10, v22, v0
	v_fma_f32 v16, -v11, v23, v16
	ds_read_b128 v[20:23], v33 offset:39120
	s_waitcnt lgkmcnt(0)
	v_fma_f32 v0, -v12, v20, v0
	v_fma_f32 v16, -v13, v21, v16
	v_fma_f32 v0, -v14, v22, v0
	v_fma_f32 v16, -v15, v23, v16
	ds_read_b128 v[20:23], v33 offset:39136
	s_waitcnt lgkmcnt(0)
; DI void chunk_prep(const Params& p, int item, char* smem) {
;     ...
;   {
;     const int c = tid;
;     float sol[64];
; #pragma unroll
;     for (int i = 0; i < 64; ++i) {
;       float rhs = rraw[i] * betas[i];
;       if (c >= 128) rhs *= egs[i];
;       float acc = rhs, acc1 = 0.f;
; #pragma unroll
;       for (int j = 0; j < i; ++j) {
;         if (j & 1) acc1 -= Am[i * 68 + j] * sol[j];
;         else acc -= Am[i * 68 + j] * sol[j];
;       }
;       sol[i] = acc + acc1;
;     }
	v_fma_f32 v0, -v4, v20, v0
	v_fma_f32 v16, -v5, v21, v16
	v_fma_f32 v0, -v6, v22, v0
	v_fma_f32 v16, -v7, v23, v16
	ds_read_b128 v[20:23], v33 offset:39376
	v_add_f32_e32 v16, v0, v16
	v_mul_f32_e32 v0, v192, v1
	v_mul_f32_e32 v1, v0, v17
	v_cndmask_b32_e64 v0, v0, v1, s[8:9]
	s_waitcnt lgkmcnt(0)
	v_fma_f32 v0, -v8, v20, v0
	v_fma_f32 v1, -v9, v21, 0
	v_fma_f32 v0, -v10, v22, v0
	v_fma_f32 v1, -v11, v23, v1
	ds_read_b128 v[20:23], v33 offset:39392
	ds_read_b32 v17, v33 offset:39424
	s_waitcnt lgkmcnt(1)
	v_fma_f32 v0, -v12, v20, v0
	v_fma_f32 v1, -v13, v21, v1
	v_fma_f32 v0, -v14, v22, v0
	v_fma_f32 v1, -v15, v23, v1
	ds_read_b128 v[20:23], v33 offset:39408
	s_waitcnt lgkmcnt(0)
	v_fma_f32 v0, -v4, v20, v0
	v_fma_f32 v1, -v5, v21, v1
	v_fma_f32 v0, -v6, v22, v0
	v_fma_f32 v1, -v7, v23, v1
	ds_read_b128 v[20:23], v33 offset:39648
	v_fma_f32 v0, -v16, v17, v0
	v_add_f32_e32 v17, v1, v0
	v_mul_f32_e32 v0, v190, v2
	v_mul_f32_e32 v1, v0, v18
	v_cndmask_b32_e64 v0, v0, v1, s[8:9]
	s_waitcnt lgkmcnt(0)
	v_fma_f32 v0, -v8, v20, v0
	v_fma_f32 v1, -v9, v21, 0
	v_fma_f32 v0, -v10, v22, v0
	v_fma_f32 v1, -v11, v23, v1
	ds_read_b128 v[20:23], v33 offset:39664
	s_waitcnt lgkmcnt(0)
	v_fma_f32 v0, -v12, v20, v0
	v_fma_f32 v1, -v13, v21, v1
	v_fma_f32 v0, -v14, v22, v0
	v_fma_f32 v1, -v15, v23, v1
	ds_read_b128 v[20:23], v33 offset:39680
	s_waitcnt lgkmcnt(0)
	v_fma_f32 v0, -v4, v20, v0
	v_fma_f32 v1, -v5, v21, v1
	v_fma_f32 v2, -v6, v22, v0
	v_fma_f32 v18, -v7, v23, v1
	ds_read_b64 v[0:1], v33 offset:39696
	s_waitcnt lgkmcnt(0)
	v_fma_f32 v0, -v16, v0, v2
	v_fma_f32 v1, -v17, v1, v18
	v_add_f32_e32 v18, v0, v1
	v_mul_f32_e32 v0, v191, v3
	v_mul_f32_e32 v1, v0, v19
	v_cndmask_b32_e64 v19, v0, v1, s[8:9]
	ds_read_b128 v[0:3], v33 offset:39920
	s_waitcnt lgkmcnt(0)
	v_fma_f32 v0, -v8, v0, v19
	v_fma_f32 v1, -v9, v1, 0
	v_fma_f32 v19, -v10, v2, v0
	v_fma_f32 v20, -v11, v3, v1
	ds_read_b128 v[0:3], v33 offset:39936
	s_waitcnt lgkmcnt(0)
	v_fma_f32 v0, -v12, v0, v19
	v_fma_f32 v1, -v13, v1, v20
	v_fma_f32 v19, -v14, v2, v0
	v_fma_f32 v20, -v15, v3, v1
	ds_read_b128 v[0:3], v33 offset:39952
	s_waitcnt lgkmcnt(0)
	v_fma_f32 v0, -v4, v0, v19
	v_fma_f32 v1, -v5, v1, v20
	v_fma_f32 v19, -v6, v2, v0
	v_fma_f32 v3, -v7, v3, v1
	ds_read_b96 v[0:2], v33 offset:39968
	ds_read_b128 v[20:23], v33 offset:320
	s_waitcnt lgkmcnt(1)
	v_fma_f32 v0, -v16, v0, v19
	v_fma_f32 v1, -v17, v1, v3
	v_fma_f32 v0, -v18, v2, v0
	v_add_f32_e32 v3, v1, v0
	s_waitcnt lgkmcnt(0)
	v_mul_f32_e32 v0, v189, v20
	v_mul_f32_e32 v1, v0, v24
	v_cndmask_b32_e64 v0, v0, v1, s[8:9]
	v_fma_f32 v0, -v8, v28, v0
	v_fma_f32 v1, -v9, v29, 0
	v_fma_f32 v0, -v10, v30, v0
	v_fma_f32 v1, -v11, v31, v1
	ds_read_b128 v[28:31], v33 offset:40208
	ds_read_b32 v2, v33 offset:40528
	s_waitcnt lgkmcnt(1)
	v_fma_f32 v0, -v12, v28, v0
	v_fma_f32 v1, -v13, v29, v1
	v_fma_f32 v0, -v14, v30, v0
	v_fma_f32 v1, -v15, v31, v1
	ds_read_b128 v[28:31], v33 offset:40224
	s_waitcnt lgkmcnt(0)
	v_fma_f32 v0, -v4, v28, v0
	v_fma_f32 v1, -v5, v29, v1
	v_fma_f32 v0, -v6, v30, v0
	v_fma_f32 v1, -v7, v31, v1
	ds_read_b128 v[28:31], v33 offset:40240
	s_waitcnt lgkmcnt(0)
	v_fma_f32 v0, -v16, v28, v0
	v_fma_f32 v1, -v17, v29, v1
	v_fma_f32 v0, -v18, v30, v0
	v_fma_f32 v1, -v3, v31, v1
	ds_read_b128 v[28:31], v33 offset:40464
	v_add_f32_e32 v19, v0, v1
	v_mul_f32_e32 v0, v188, v21
	v_mul_f32_e32 v1, v0, v25
	v_cndmask_b32_e64 v0, v0, v1, s[8:9]
	s_waitcnt lgkmcnt(0)
	v_fma_f32 v0, -v8, v28, v0
	v_fma_f32 v1, -v9, v29, 0
	v_fma_f32 v0, -v10, v30, v0
	v_fma_f32 v1, -v11, v31, v1
	ds_read_b128 v[28:31], v33 offset:40480
	s_waitcnt lgkmcnt(0)
	v_fma_f32 v0, -v12, v28, v0
	v_fma_f32 v1, -v13, v29, v1
	v_fma_f32 v0, -v14, v30, v0
	v_fma_f32 v1, -v15, v31, v1
	ds_read_b128 v[28:31], v33 offset:40496
	s_waitcnt lgkmcnt(0)
	v_fma_f32 v0, -v4, v28, v0
	v_fma_f32 v1, -v5, v29, v1
	v_fma_f32 v0, -v6, v30, v0
	v_fma_f32 v1, -v7, v31, v1
	ds_read_b128 v[28:31], v33 offset:40512
	s_waitcnt lgkmcnt(0)
	v_fma_f32 v0, -v16, v28, v0
	v_fma_f32 v1, -v17, v29, v1
	v_fma_f32 v0, -v18, v30, v0
	v_fma_f32 v1, -v3, v31, v1
	ds_read_b128 v[28:31], v33 offset:40736
	v_fma_f32 v0, -v19, v2, v0
	v_add_f32_e32 v20, v1, v0
	v_mul_f32_e32 v0, v187, v22
	v_mul_f32_e32 v1, v0, v26
	v_cndmask_b32_e64 v0, v0, v1, s[8:9]
	s_waitcnt lgkmcnt(0)
	v_fma_f32 v0, -v8, v28, v0
	v_fma_f32 v1, -v9, v29, 0
	v_fma_f32 v0, -v10, v30, v0
	v_fma_f32 v1, -v11, v31, v1
	ds_read_b128 v[28:31], v33 offset:40752
	s_waitcnt lgkmcnt(0)
	v_fma_f32 v0, -v12, v28, v0
	v_fma_f32 v1, -v13, v29, v1
	v_fma_f32 v0, -v14, v30, v0
	v_fma_f32 v1, -v15, v31, v1
	ds_read_b128 v[28:31], v33 offset:40768
	s_waitcnt lgkmcnt(0)
	v_fma_f32 v0, -v4, v28, v0
	v_fma_f32 v1, -v5, v29, v1
	v_fma_f32 v0, -v6, v30, v0
	v_fma_f32 v1, -v7, v31, v1
	ds_read_b128 v[28:31], v33 offset:40784
	s_waitcnt lgkmcnt(0)
	v_fma_f32 v0, -v16, v28, v0
	v_fma_f32 v1, -v17, v29, v1
	v_fma_f32 v2, -v18, v30, v0
	v_fma_f32 v21, -v3, v31, v1
	ds_read_b64 v[0:1], v33 offset:40800
	ds_read_b128 v[28:31], v33 offset:592
	s_waitcnt lgkmcnt(1)
	v_fma_f32 v0, -v19, v0, v2
	v_fma_f32 v1, -v20, v1, v21
	v_add_f32_e32 v21, v0, v1
	v_mul_f32_e32 v0, v186, v23
	ds_read_b128 v[22:25], v33 offset:41008
	v_mul_f32_e32 v1, v0, v27
	v_cndmask_b32_e64 v0, v0, v1, s[8:9]
	s_waitcnt lgkmcnt(0)
	v_fma_f32 v0, -v8, v22, v0
	v_fma_f32 v1, -v9, v23, 0
	v_fma_f32 v0, -v10, v24, v0
	v_fma_f32 v1, -v11, v25, v1
	ds_read_b128 v[22:25], v33 offset:41024
	s_waitcnt lgkmcnt(0)
	v_fma_f32 v0, -v12, v22, v0
	v_fma_f32 v1, -v13, v23, v1
	v_fma_f32 v0, -v14, v24, v0
	v_fma_f32 v1, -v15, v25, v1
	ds_read_b128 v[22:25], v33 offset:41040
	s_waitcnt lgkmcnt(0)
; DI void chunk_prep(const Params& p, int item, char* smem) {
;     ...
;   {
;     const int c = tid;
;     float sol[64];
; #pragma unroll
;     for (int i = 0; i < 64; ++i) {
;       float rhs = rraw[i] * betas[i];
;       if (c >= 128) rhs *= egs[i];
;       float acc = rhs, acc1 = 0.f;
; #pragma unroll
;       for (int j = 0; j < i; ++j) {
;         if (j & 1) acc1 -= Am[i * 68 + j] * sol[j];
;         else acc -= Am[i * 68 + j] * sol[j];
;       }
;       sol[i] = acc + acc1;
;     }
	v_fma_f32 v0, -v4, v22, v0
	v_fma_f32 v1, -v5, v23, v1
	v_fma_f32 v0, -v6, v24, v0
	v_fma_f32 v1, -v7, v25, v1
	ds_read_b128 v[22:25], v33 offset:41056
	s_waitcnt lgkmcnt(0)
	v_fma_f32 v0, -v16, v22, v0
	v_fma_f32 v1, -v17, v23, v1
	v_fma_f32 v22, -v18, v24, v0
	v_fma_f32 v23, -v3, v25, v1
	ds_read_b96 v[0:2], v33 offset:41072
	ds_read_b128 v[24:27], v33 offset:336
	s_waitcnt lgkmcnt(1)
	v_fma_f32 v0, -v19, v0, v22
	v_fma_f32 v1, -v20, v1, v23
	v_fma_f32 v0, -v21, v2, v0
	v_add_f32_e32 v22, v1, v0
	s_waitcnt lgkmcnt(0)
	v_mul_f32_e32 v0, v185, v24
	v_mul_f32_e32 v1, v0, v28
	v_cndmask_b32_e64 v0, v0, v1, s[8:9]
	v_fma_f32 v0, -v8, v90, v0
	v_fma_f32 v1, -v9, v91, 0
	v_fma_f32 v0, -v10, v92, v0
	v_fma_f32 v1, -v11, v93, v1
	ds_read_b128 v[90:93], v33 offset:41296
	ds_read_b32 v2, v33 offset:41632
	s_waitcnt lgkmcnt(1)
	v_fma_f32 v0, -v12, v90, v0
	v_fma_f32 v1, -v13, v91, v1
	v_fma_f32 v0, -v14, v92, v0
	v_fma_f32 v1, -v15, v93, v1
	ds_read_b128 v[90:93], v33 offset:41312
	s_waitcnt lgkmcnt(0)
	v_fma_f32 v0, -v4, v90, v0
	v_fma_f32 v1, -v5, v91, v1
	v_fma_f32 v0, -v6, v92, v0
	v_fma_f32 v1, -v7, v93, v1
	ds_read_b128 v[90:93], v33 offset:41328
	s_waitcnt lgkmcnt(0)
	v_fma_f32 v0, -v16, v90, v0
	v_fma_f32 v1, -v17, v91, v1
	v_fma_f32 v0, -v18, v92, v0
	v_fma_f32 v1, -v3, v93, v1
	ds_read_b128 v[90:93], v33 offset:41344
	s_waitcnt lgkmcnt(0)
	v_fma_f32 v0, -v19, v90, v0
	v_fma_f32 v1, -v20, v91, v1
	v_fma_f32 v0, -v21, v92, v0
	v_fma_f32 v1, -v22, v93, v1
	ds_read_b128 v[90:93], v33 offset:41552
	v_add_f32_e32 v23, v0, v1
	v_mul_f32_e32 v0, v184, v25
	v_mul_f32_e32 v1, v0, v29
	v_cndmask_b32_e64 v0, v0, v1, s[8:9]
	s_waitcnt lgkmcnt(0)
	v_fma_f32 v0, -v8, v90, v0
	v_fma_f32 v1, -v9, v91, 0
	v_fma_f32 v0, -v10, v92, v0
	v_fma_f32 v1, -v11, v93, v1
	ds_read_b128 v[90:93], v33 offset:41568
	s_waitcnt lgkmcnt(0)
	v_fma_f32 v0, -v12, v90, v0
	v_fma_f32 v1, -v13, v91, v1
	v_fma_f32 v0, -v14, v92, v0
	v_fma_f32 v1, -v15, v93, v1
	ds_read_b128 v[90:93], v33 offset:41584
	s_waitcnt lgkmcnt(0)
	v_fma_f32 v0, -v4, v90, v0
	v_fma_f32 v1, -v5, v91, v1
	v_fma_f32 v0, -v6, v92, v0
	v_fma_f32 v1, -v7, v93, v1
	ds_read_b128 v[90:93], v33 offset:41600
	s_waitcnt lgkmcnt(0)
	v_fma_f32 v0, -v16, v90, v0
	v_fma_f32 v1, -v17, v91, v1
	v_fma_f32 v0, -v18, v92, v0
	v_fma_f32 v1, -v3, v93, v1
	ds_read_b128 v[90:93], v33 offset:41616
	s_waitcnt lgkmcnt(0)
	v_fma_f32 v0, -v19, v90, v0
	v_fma_f32 v1, -v20, v91, v1
	v_fma_f32 v0, -v21, v92, v0
	v_fma_f32 v1, -v22, v93, v1
	ds_read_b128 v[90:93], v33 offset:41824
	v_fma_f32 v0, -v23, v2, v0
	v_add_f32_e32 v24, v1, v0
	v_mul_f32_e32 v0, v183, v26
	v_mul_f32_e32 v1, v0, v30
	v_cndmask_b32_e64 v0, v0, v1, s[8:9]
	s_waitcnt lgkmcnt(0)
	v_fma_f32 v0, -v8, v90, v0
	v_fma_f32 v1, -v9, v91, 0
	v_fma_f32 v0, -v10, v92, v0
	v_fma_f32 v1, -v11, v93, v1
	ds_read_b128 v[90:93], v33 offset:41840
	s_waitcnt lgkmcnt(0)
	v_fma_f32 v0, -v12, v90, v0
	v_fma_f32 v1, -v13, v91, v1
	v_fma_f32 v0, -v14, v92, v0
	v_fma_f32 v1, -v15, v93, v1
	ds_read_b128 v[90:93], v33 offset:41856
	s_waitcnt lgkmcnt(0)
	v_fma_f32 v0, -v4, v90, v0
	v_fma_f32 v1, -v5, v91, v1
	v_fma_f32 v0, -v6, v92, v0
	v_fma_f32 v1, -v7, v93, v1
	ds_read_b128 v[90:93], v33 offset:41872
	s_waitcnt lgkmcnt(0)
	v_fma_f32 v0, -v16, v90, v0
	v_fma_f32 v1, -v17, v91, v1
	v_fma_f32 v0, -v18, v92, v0
	v_fma_f32 v1, -v3, v93, v1
	ds_read_b128 v[90:93], v33 offset:41888
	s_waitcnt lgkmcnt(0)
	v_fma_f32 v0, -v19, v90, v0
	v_fma_f32 v1, -v20, v91, v1
	v_fma_f32 v2, -v21, v92, v0
	v_fma_f32 v25, -v22, v93, v1
	ds_read_b64 v[0:1], v33 offset:41904
	ds_read_b128 v[90:93], v33 offset:608
	s_waitcnt lgkmcnt(1)
	v_fma_f32 v0, -v23, v0, v2
	v_fma_f32 v1, -v24, v1, v25
	v_add_f32_e32 v25, v0, v1
	v_mul_f32_e32 v0, v182, v27
	ds_read_b128 v[26:29], v33 offset:42096
	ds_read_b128 v[182:185], v33 offset:42368
	v_mul_f32_e32 v1, v0, v31
	v_cndmask_b32_e64 v0, v0, v1, s[8:9]
	s_waitcnt lgkmcnt(1)
	v_fma_f32 v0, -v8, v26, v0
	v_fma_f32 v1, -v9, v27, 0
	v_fma_f32 v0, -v10, v28, v0
	v_fma_f32 v1, -v11, v29, v1
	ds_read_b128 v[26:29], v33 offset:42112
	s_waitcnt lgkmcnt(0)
	v_fma_f32 v0, -v12, v26, v0
	v_fma_f32 v1, -v13, v27, v1
	v_fma_f32 v0, -v14, v28, v0
	v_fma_f32 v1, -v15, v29, v1
	ds_read_b128 v[26:29], v33 offset:42128
	s_waitcnt lgkmcnt(0)
	v_fma_f32 v0, -v4, v26, v0
	v_fma_f32 v1, -v5, v27, v1
	v_fma_f32 v0, -v6, v28, v0
	v_fma_f32 v1, -v7, v29, v1
	ds_read_b128 v[26:29], v33 offset:42144
	s_waitcnt lgkmcnt(0)
	v_fma_f32 v0, -v16, v26, v0
	v_fma_f32 v1, -v17, v27, v1
	v_fma_f32 v0, -v18, v28, v0
	v_fma_f32 v1, -v3, v29, v1
	ds_read_b128 v[26:29], v33 offset:42160
	s_waitcnt lgkmcnt(0)
	v_fma_f32 v0, -v19, v26, v0
	v_fma_f32 v1, -v20, v27, v1
	v_fma_f32 v26, -v21, v28, v0
	v_fma_f32 v27, -v22, v29, v1
	ds_read_b96 v[0:2], v33 offset:42176
	ds_read_b128 v[28:31], v33 offset:352
	s_waitcnt lgkmcnt(1)
	v_fma_f32 v0, -v23, v0, v26
	v_fma_f32 v1, -v24, v1, v27
	v_fma_f32 v0, -v25, v2, v0
	v_add_f32_e32 v26, v1, v0
	s_waitcnt lgkmcnt(0)
	v_mul_f32_e32 v0, v181, v28
	v_mul_f32_e32 v1, v0, v90
	v_cndmask_b32_e64 v0, v0, v1, s[8:9]
	v_fma_f32 v0, -v8, v182, v0
	v_fma_f32 v1, -v9, v183, 0
	v_fma_f32 v0, -v10, v184, v0
	v_fma_f32 v1, -v11, v185, v1
	ds_read_b128 v[182:185], v33 offset:42384
	ds_read_b32 v2, v33 offset:42736
	s_waitcnt lgkmcnt(1)
	v_fma_f32 v0, -v12, v182, v0
	v_fma_f32 v1, -v13, v183, v1
	v_fma_f32 v0, -v14, v184, v0
	v_fma_f32 v1, -v15, v185, v1
	ds_read_b128 v[182:185], v33 offset:42400
	s_waitcnt lgkmcnt(0)
	v_fma_f32 v0, -v4, v182, v0
	v_fma_f32 v1, -v5, v183, v1
	v_fma_f32 v0, -v6, v184, v0
	v_fma_f32 v1, -v7, v185, v1
	ds_read_b128 v[182:185], v33 offset:42416
	s_waitcnt lgkmcnt(0)
; DI void chunk_prep(const Params& p, int item, char* smem) {
;     ...
;   {
;     const int c = tid;
;     float sol[64];
; #pragma unroll
;     for (int i = 0; i < 64; ++i) {
;       float rhs = rraw[i] * betas[i];
;       if (c >= 128) rhs *= egs[i];
;       float acc = rhs, acc1 = 0.f;
; #pragma unroll
;       for (int j = 0; j < i; ++j) {
;         if (j & 1) acc1 -= Am[i * 68 + j] * sol[j];
;         else acc -= Am[i * 68 + j] * sol[j];
;       }
;       sol[i] = acc + acc1;
;     }
	v_fma_f32 v0, -v16, v182, v0
	v_fma_f32 v1, -v17, v183, v1
	v_fma_f32 v0, -v18, v184, v0
	v_fma_f32 v1, -v3, v185, v1
	ds_read_b128 v[182:185], v33 offset:42432
	s_waitcnt lgkmcnt(0)
	v_fma_f32 v0, -v19, v182, v0
	v_fma_f32 v1, -v20, v183, v1
	v_fma_f32 v0, -v21, v184, v0
	v_fma_f32 v1, -v22, v185, v1
	ds_read_b128 v[182:185], v33 offset:42448
	s_waitcnt lgkmcnt(0)
	v_fma_f32 v0, -v23, v182, v0
	v_fma_f32 v1, -v24, v183, v1
	v_fma_f32 v0, -v25, v184, v0
	v_fma_f32 v1, -v26, v185, v1
	v_add_f32_e32 v27, v0, v1
	v_mul_f32_e32 v0, v180, v29
	ds_read_b128 v[180:183], v33 offset:42640
	v_mul_f32_e32 v1, v0, v91
	v_cndmask_b32_e64 v0, v0, v1, s[8:9]
	s_waitcnt lgkmcnt(0)
	v_fma_f32 v0, -v8, v180, v0
	v_fma_f32 v1, -v9, v181, 0
	v_fma_f32 v0, -v10, v182, v0
	v_fma_f32 v1, -v11, v183, v1
	ds_read_b128 v[180:183], v33 offset:42656
	s_waitcnt lgkmcnt(0)
	v_fma_f32 v0, -v12, v180, v0
	v_fma_f32 v1, -v13, v181, v1
	v_fma_f32 v0, -v14, v182, v0
	v_fma_f32 v1, -v15, v183, v1
	ds_read_b128 v[180:183], v33 offset:42672
	s_waitcnt lgkmcnt(0)
	v_fma_f32 v0, -v4, v180, v0
	v_fma_f32 v1, -v5, v181, v1
	v_fma_f32 v0, -v6, v182, v0
	v_fma_f32 v1, -v7, v183, v1
	ds_read_b128 v[180:183], v33 offset:42688
	s_waitcnt lgkmcnt(0)
	v_fma_f32 v0, -v16, v180, v0
	v_fma_f32 v1, -v17, v181, v1
	v_fma_f32 v0, -v18, v182, v0
	v_fma_f32 v1, -v3, v183, v1
	ds_read_b128 v[180:183], v33 offset:42704
	s_waitcnt lgkmcnt(0)
	v_fma_f32 v0, -v19, v180, v0
	v_fma_f32 v1, -v20, v181, v1
	v_fma_f32 v0, -v21, v182, v0
	v_fma_f32 v1, -v22, v183, v1
	ds_read_b128 v[180:183], v33 offset:42720
	s_waitcnt lgkmcnt(0)
	v_fma_f32 v0, -v23, v180, v0
	v_fma_f32 v1, -v24, v181, v1
	v_fma_f32 v0, -v25, v182, v0
	v_fma_f32 v1, -v26, v183, v1
	ds_read_b128 v[180:183], v33 offset:42912
	v_fma_f32 v0, -v27, v2, v0
	v_add_f32_e32 v28, v1, v0
	v_mul_f32_e32 v0, v179, v30
	v_mul_f32_e32 v1, v0, v92
	v_cndmask_b32_e64 v0, v0, v1, s[8:9]
	s_waitcnt lgkmcnt(0)
	v_fma_f32 v0, -v8, v180, v0
	v_fma_f32 v1, -v9, v181, 0
	v_fma_f32 v0, -v10, v182, v0
	v_fma_f32 v1, -v11, v183, v1
	ds_read_b128 v[180:183], v33 offset:42928
	s_waitcnt lgkmcnt(0)
	v_fma_f32 v0, -v12, v180, v0
	v_fma_f32 v1, -v13, v181, v1
	v_fma_f32 v0, -v14, v182, v0
	v_fma_f32 v1, -v15, v183, v1
	ds_read_b128 v[180:183], v33 offset:42944
	s_waitcnt lgkmcnt(0)
	v_fma_f32 v0, -v4, v180, v0
	v_fma_f32 v1, -v5, v181, v1
	v_fma_f32 v0, -v6, v182, v0
	v_fma_f32 v1, -v7, v183, v1
	ds_read_b128 v[180:183], v33 offset:42960
	s_waitcnt lgkmcnt(0)
	v_fma_f32 v0, -v16, v180, v0
	v_fma_f32 v1, -v17, v181, v1
	v_fma_f32 v0, -v18, v182, v0
	v_fma_f32 v1, -v3, v183, v1
	ds_read_b128 v[180:183], v33 offset:42976
	s_waitcnt lgkmcnt(0)
	v_fma_f32 v0, -v19, v180, v0
	v_fma_f32 v1, -v20, v181, v1
	v_fma_f32 v0, -v21, v182, v0
	v_fma_f32 v1, -v22, v183, v1
	ds_read_b128 v[180:183], v33 offset:42992
	s_waitcnt lgkmcnt(0)
	v_fma_f32 v0, -v23, v180, v0
	v_fma_f32 v1, -v24, v181, v1
	v_fma_f32 v2, -v25, v182, v0
	v_fma_f32 v29, -v26, v183, v1
	ds_read_b64 v[0:1], v33 offset:43008
	ds_read_b128 v[182:185], v33 offset:43456
	s_waitcnt lgkmcnt(1)
	v_fma_f32 v0, -v27, v0, v2
	v_fma_f32 v1, -v28, v1, v29
	v_add_f32_e32 v29, v0, v1
	v_mul_f32_e32 v0, v178, v31
	v_mul_f32_e32 v1, v0, v93
	ds_read_b128 v[90:93], v33 offset:43184
	v_cndmask_b32_e64 v0, v0, v1, s[8:9]
	ds_read_b128 v[178:181], v33 offset:624
	s_waitcnt lgkmcnt(1)
	v_fma_f32 v0, -v8, v90, v0
	v_fma_f32 v1, -v9, v91, 0
	v_fma_f32 v0, -v10, v92, v0
	v_fma_f32 v1, -v11, v93, v1
	ds_read_b128 v[90:93], v33 offset:43200
	s_waitcnt lgkmcnt(0)
	v_fma_f32 v0, -v12, v90, v0
	v_fma_f32 v1, -v13, v91, v1
	v_fma_f32 v0, -v14, v92, v0
	v_fma_f32 v1, -v15, v93, v1
	ds_read_b128 v[90:93], v33 offset:43216
	s_waitcnt lgkmcnt(0)
	v_fma_f32 v0, -v4, v90, v0
	v_fma_f32 v1, -v5, v91, v1
	v_fma_f32 v0, -v6, v92, v0
	v_fma_f32 v1, -v7, v93, v1
	ds_read_b128 v[90:93], v33 offset:43232
	s_waitcnt lgkmcnt(0)
	v_fma_f32 v0, -v16, v90, v0
	v_fma_f32 v1, -v17, v91, v1
	v_fma_f32 v0, -v18, v92, v0
	v_fma_f32 v1, -v3, v93, v1
	ds_read_b128 v[90:93], v33 offset:43248
	s_waitcnt lgkmcnt(0)
	v_fma_f32 v0, -v19, v90, v0
	v_fma_f32 v1, -v20, v91, v1
	v_fma_f32 v0, -v21, v92, v0
	v_fma_f32 v1, -v22, v93, v1
	ds_read_b128 v[90:93], v33 offset:43264
	s_waitcnt lgkmcnt(0)
	v_fma_f32 v0, -v23, v90, v0
	v_fma_f32 v1, -v24, v91, v1
	v_fma_f32 v30, -v25, v92, v0
	v_fma_f32 v31, -v26, v93, v1
	ds_read_b96 v[0:2], v33 offset:43280
	ds_read_b128 v[90:93], v33 offset:368
	s_waitcnt lgkmcnt(1)
	v_fma_f32 v0, -v27, v0, v30
	v_fma_f32 v1, -v28, v1, v31
	v_fma_f32 v0, -v29, v2, v0
	v_add_f32_e32 v30, v1, v0
	s_waitcnt lgkmcnt(0)
	v_mul_f32_e32 v0, v177, v90
	v_mul_f32_e32 v1, v0, v178
	v_cndmask_b32_e64 v0, v0, v1, s[8:9]
	v_fma_f32 v0, -v8, v182, v0
	v_fma_f32 v1, -v9, v183, 0
	v_fma_f32 v0, -v10, v184, v0
	v_fma_f32 v1, -v11, v185, v1
	ds_read_b128 v[182:185], v33 offset:43472
	ds_read_b32 v2, v33 offset:43840
	s_waitcnt lgkmcnt(1)
	v_fma_f32 v0, -v12, v182, v0
	v_fma_f32 v1, -v13, v183, v1
	v_fma_f32 v0, -v14, v184, v0
	v_fma_f32 v1, -v15, v185, v1
	ds_read_b128 v[182:185], v33 offset:43488
	s_waitcnt lgkmcnt(0)
	v_fma_f32 v0, -v4, v182, v0
	v_fma_f32 v1, -v5, v183, v1
	v_fma_f32 v0, -v6, v184, v0
	v_fma_f32 v1, -v7, v185, v1
	ds_read_b128 v[182:185], v33 offset:43504
	s_waitcnt lgkmcnt(0)
	v_fma_f32 v0, -v16, v182, v0
	v_fma_f32 v1, -v17, v183, v1
	v_fma_f32 v0, -v18, v184, v0
	v_fma_f32 v1, -v3, v185, v1
	ds_read_b128 v[182:185], v33 offset:43520
	s_waitcnt lgkmcnt(0)
	v_fma_f32 v0, -v19, v182, v0
	v_fma_f32 v1, -v20, v183, v1
	v_fma_f32 v0, -v21, v184, v0
	v_fma_f32 v1, -v22, v185, v1
	ds_read_b128 v[182:185], v33 offset:43536
	s_waitcnt lgkmcnt(0)
; DI void chunk_prep(const Params& p, int item, char* smem) {
;     ...
;   {
;     const int c = tid;
;     float sol[64];
; #pragma unroll
;     for (int i = 0; i < 64; ++i) {
;       float rhs = rraw[i] * betas[i];
;       if (c >= 128) rhs *= egs[i];
;       float acc = rhs, acc1 = 0.f;
; #pragma unroll
;       for (int j = 0; j < i; ++j) {
;         if (j & 1) acc1 -= Am[i * 68 + j] * sol[j];
;         else acc -= Am[i * 68 + j] * sol[j];
;       }
;       sol[i] = acc + acc1;
;     }
	v_fma_f32 v0, -v23, v182, v0
	v_fma_f32 v1, -v24, v183, v1
	v_fma_f32 v0, -v25, v184, v0
	v_fma_f32 v1, -v26, v185, v1
	ds_read_b128 v[182:185], v33 offset:43552
	s_waitcnt lgkmcnt(0)
	v_fma_f32 v0, -v27, v182, v0
	v_fma_f32 v1, -v28, v183, v1
	v_fma_f32 v0, -v29, v184, v0
	v_fma_f32 v1, -v30, v185, v1
	v_add_f32_e32 v31, v0, v1
	v_mul_f32_e32 v0, v176, v91
	v_mul_f32_e32 v1, v0, v179
	ds_read_b128 v[176:179], v33 offset:43728
	v_cndmask_b32_e64 v0, v0, v1, s[8:9]
	s_waitcnt lgkmcnt(0)
	v_fma_f32 v0, -v8, v176, v0
	v_fma_f32 v1, -v9, v177, 0
	v_fma_f32 v0, -v10, v178, v0
	v_fma_f32 v1, -v11, v179, v1
	ds_read_b128 v[176:179], v33 offset:43744
	s_waitcnt lgkmcnt(0)
	v_fma_f32 v0, -v12, v176, v0
	v_fma_f32 v1, -v13, v177, v1
	v_fma_f32 v0, -v14, v178, v0
	v_fma_f32 v1, -v15, v179, v1
	ds_read_b128 v[176:179], v33 offset:43760
	s_waitcnt lgkmcnt(0)
	v_fma_f32 v0, -v4, v176, v0
	v_fma_f32 v1, -v5, v177, v1
	v_fma_f32 v0, -v6, v178, v0
	v_fma_f32 v1, -v7, v179, v1
	ds_read_b128 v[176:179], v33 offset:43776
	s_waitcnt lgkmcnt(0)
	v_fma_f32 v0, -v16, v176, v0
	v_fma_f32 v1, -v17, v177, v1
	v_fma_f32 v0, -v18, v178, v0
	v_fma_f32 v1, -v3, v179, v1
	ds_read_b128 v[176:179], v33 offset:43792
	s_waitcnt lgkmcnt(0)
	v_fma_f32 v0, -v19, v176, v0
	v_fma_f32 v1, -v20, v177, v1
	v_fma_f32 v0, -v21, v178, v0
	v_fma_f32 v1, -v22, v179, v1
	ds_read_b128 v[176:179], v33 offset:43808
	s_waitcnt lgkmcnt(0)
	v_fma_f32 v0, -v23, v176, v0
	v_fma_f32 v1, -v24, v177, v1
	v_fma_f32 v0, -v25, v178, v0
	v_fma_f32 v1, -v26, v179, v1
	ds_read_b128 v[176:179], v33 offset:43824
	s_waitcnt lgkmcnt(0)
	v_fma_f32 v0, -v27, v176, v0
	v_fma_f32 v1, -v28, v177, v1
	v_fma_f32 v0, -v29, v178, v0
	v_fma_f32 v1, -v30, v179, v1
	ds_read_b128 v[176:179], v33 offset:44000
	v_fma_f32 v0, -v31, v2, v0
	v_add_f32_e32 v77, v1, v0
	v_mul_f32_e32 v0, v175, v92
	v_mul_f32_e32 v1, v0, v180
	v_cndmask_b32_e64 v0, v0, v1, s[8:9]
	s_waitcnt lgkmcnt(0)
	v_fma_f32 v0, -v8, v176, v0
	v_fma_f32 v1, -v9, v177, 0
	v_fma_f32 v0, -v10, v178, v0
	v_fma_f32 v1, -v11, v179, v1
	ds_read_b128 v[176:179], v33 offset:44016
	s_waitcnt lgkmcnt(0)
	v_fma_f32 v0, -v12, v176, v0
	v_fma_f32 v1, -v13, v177, v1
	v_fma_f32 v0, -v14, v178, v0
	v_fma_f32 v1, -v15, v179, v1
	ds_read_b128 v[176:179], v33 offset:44032
	s_waitcnt lgkmcnt(0)
	v_fma_f32 v0, -v4, v176, v0
	v_fma_f32 v1, -v5, v177, v1
	v_fma_f32 v0, -v6, v178, v0
	v_fma_f32 v1, -v7, v179, v1
	ds_read_b128 v[176:179], v33 offset:44048
	s_waitcnt lgkmcnt(0)
	v_fma_f32 v0, -v16, v176, v0
	v_fma_f32 v1, -v17, v177, v1
	v_fma_f32 v0, -v18, v178, v0
	v_fma_f32 v1, -v3, v179, v1
	ds_read_b128 v[176:179], v33 offset:44064
	s_waitcnt lgkmcnt(0)
	v_fma_f32 v0, -v19, v176, v0
	v_fma_f32 v1, -v20, v177, v1
	v_fma_f32 v0, -v21, v178, v0
	v_fma_f32 v1, -v22, v179, v1
	ds_read_b128 v[176:179], v33 offset:44080
	s_waitcnt lgkmcnt(0)
	v_fma_f32 v0, -v23, v176, v0
	v_fma_f32 v1, -v24, v177, v1
	v_fma_f32 v0, -v25, v178, v0
	v_fma_f32 v1, -v26, v179, v1
	ds_read_b128 v[176:179], v33 offset:44096
	s_waitcnt lgkmcnt(0)
	v_fma_f32 v0, -v27, v176, v0
	v_fma_f32 v1, -v28, v177, v1
	v_fma_f32 v2, -v29, v178, v0
	v_fma_f32 v79, -v30, v179, v1
	ds_read_b64 v[0:1], v33 offset:44112
	s_waitcnt lgkmcnt(0)
	v_fma_f32 v0, -v31, v0, v2
	v_fma_f32 v1, -v77, v1, v79
	v_add_f32_e32 v79, v0, v1
	v_mul_f32_e32 v0, v174, v93
	ds_read_b128 v[90:93], v33 offset:44272
	ds_read_b128 v[174:177], v33 offset:640
	v_mul_f32_e32 v1, v0, v181
	v_cndmask_b32_e64 v0, v0, v1, s[8:9]
	ds_read_b128 v[178:181], v33 offset:44544
	s_waitcnt lgkmcnt(2)
	v_fma_f32 v0, -v8, v90, v0
	v_fma_f32 v1, -v9, v91, 0
	v_fma_f32 v0, -v10, v92, v0
	v_fma_f32 v1, -v11, v93, v1
	ds_read_b128 v[90:93], v33 offset:44288
	s_waitcnt lgkmcnt(0)
	v_fma_f32 v0, -v12, v90, v0
	v_fma_f32 v1, -v13, v91, v1
	v_fma_f32 v0, -v14, v92, v0
	v_fma_f32 v1, -v15, v93, v1
	ds_read_b128 v[90:93], v33 offset:44304
	s_waitcnt lgkmcnt(0)
	v_fma_f32 v0, -v4, v90, v0
	v_fma_f32 v1, -v5, v91, v1
	v_fma_f32 v0, -v6, v92, v0
	v_fma_f32 v1, -v7, v93, v1
	ds_read_b128 v[90:93], v33 offset:44320
	s_waitcnt lgkmcnt(0)
	v_fma_f32 v0, -v16, v90, v0
	v_fma_f32 v1, -v17, v91, v1
	v_fma_f32 v0, -v18, v92, v0
	v_fma_f32 v1, -v3, v93, v1
	ds_read_b128 v[90:93], v33 offset:44336
	s_waitcnt lgkmcnt(0)
	v_fma_f32 v0, -v19, v90, v0
	v_fma_f32 v1, -v20, v91, v1
	v_fma_f32 v0, -v21, v92, v0
	v_fma_f32 v1, -v22, v93, v1
	ds_read_b128 v[90:93], v33 offset:44352
	s_waitcnt lgkmcnt(0)
	v_fma_f32 v0, -v23, v90, v0
	v_fma_f32 v1, -v24, v91, v1
	v_fma_f32 v0, -v25, v92, v0
	v_fma_f32 v1, -v26, v93, v1
	ds_read_b128 v[90:93], v33 offset:44368
	s_waitcnt lgkmcnt(0)
	v_fma_f32 v0, -v27, v90, v0
	v_fma_f32 v1, -v28, v91, v1
	v_fma_f32 v81, -v29, v92, v0
	v_fma_f32 v83, -v30, v93, v1
	ds_read_b96 v[0:2], v33 offset:44384
	ds_read_b128 v[90:93], v33 offset:384
	s_waitcnt lgkmcnt(1)
	v_fma_f32 v0, -v31, v0, v81
	v_fma_f32 v1, -v77, v1, v83
	v_fma_f32 v0, -v79, v2, v0
	v_add_f32_e32 v81, v1, v0
	s_waitcnt lgkmcnt(0)
	v_mul_f32_e32 v0, v173, v90
	v_mul_f32_e32 v1, v0, v174
	v_cndmask_b32_e64 v0, v0, v1, s[8:9]
	v_fma_f32 v0, -v8, v178, v0
	v_fma_f32 v1, -v9, v179, 0
	v_fma_f32 v0, -v10, v180, v0
	v_fma_f32 v1, -v11, v181, v1
	ds_read_b128 v[178:181], v33 offset:44560
	ds_read_b32 v2, v33 offset:44944
	s_waitcnt lgkmcnt(1)
	v_fma_f32 v0, -v12, v178, v0
	v_fma_f32 v1, -v13, v179, v1
	v_fma_f32 v0, -v14, v180, v0
	v_fma_f32 v1, -v15, v181, v1
	ds_read_b128 v[178:181], v33 offset:44576
	s_waitcnt lgkmcnt(0)
	v_fma_f32 v0, -v4, v178, v0
	v_fma_f32 v1, -v5, v179, v1
	v_fma_f32 v0, -v6, v180, v0
	v_fma_f32 v1, -v7, v181, v1
	ds_read_b128 v[178:181], v33 offset:44592
	s_waitcnt lgkmcnt(0)
; DI void chunk_prep(const Params& p, int item, char* smem) {
;     ...
;   {
;     const int c = tid;
;     float sol[64];
; #pragma unroll
;     for (int i = 0; i < 64; ++i) {
;       float rhs = rraw[i] * betas[i];
;       if (c >= 128) rhs *= egs[i];
;       float acc = rhs, acc1 = 0.f;
; #pragma unroll
;       for (int j = 0; j < i; ++j) {
;         if (j & 1) acc1 -= Am[i * 68 + j] * sol[j];
;         else acc -= Am[i * 68 + j] * sol[j];
;       }
;       sol[i] = acc + acc1;
;     }
	v_fma_f32 v0, -v16, v178, v0
	v_fma_f32 v1, -v17, v179, v1
	v_fma_f32 v0, -v18, v180, v0
	v_fma_f32 v1, -v3, v181, v1
	ds_read_b128 v[178:181], v33 offset:44608
	s_waitcnt lgkmcnt(0)
	v_fma_f32 v0, -v19, v178, v0
	v_fma_f32 v1, -v20, v179, v1
	v_fma_f32 v0, -v21, v180, v0
	v_fma_f32 v1, -v22, v181, v1
	ds_read_b128 v[178:181], v33 offset:44624
	s_waitcnt lgkmcnt(0)
	v_fma_f32 v0, -v23, v178, v0
	v_fma_f32 v1, -v24, v179, v1
	v_fma_f32 v0, -v25, v180, v0
	v_fma_f32 v1, -v26, v181, v1
	ds_read_b128 v[178:181], v33 offset:44640
	s_waitcnt lgkmcnt(0)
	v_fma_f32 v0, -v27, v178, v0
	v_fma_f32 v1, -v28, v179, v1
	v_fma_f32 v0, -v29, v180, v0
	v_fma_f32 v1, -v30, v181, v1
	ds_read_b128 v[178:181], v33 offset:44656
	s_waitcnt lgkmcnt(0)
	v_fma_f32 v0, -v31, v178, v0
	v_fma_f32 v1, -v77, v179, v1
	v_fma_f32 v0, -v79, v180, v0
	v_fma_f32 v1, -v81, v181, v1
	v_add_f32_e32 v83, v0, v1
	v_mul_f32_e32 v0, v172, v91
	v_mul_f32_e32 v1, v0, v175
	ds_read_b128 v[172:175], v33 offset:44816
	v_cndmask_b32_e64 v0, v0, v1, s[8:9]
	s_waitcnt lgkmcnt(0)
	v_fma_f32 v0, -v8, v172, v0
	v_fma_f32 v1, -v9, v173, 0
	v_fma_f32 v0, -v10, v174, v0
	v_fma_f32 v1, -v11, v175, v1
	ds_read_b128 v[172:175], v33 offset:44832
	s_waitcnt lgkmcnt(0)
	v_fma_f32 v0, -v12, v172, v0
	v_fma_f32 v1, -v13, v173, v1
	v_fma_f32 v0, -v14, v174, v0
	v_fma_f32 v1, -v15, v175, v1
	ds_read_b128 v[172:175], v33 offset:44848
	s_waitcnt lgkmcnt(0)
	v_fma_f32 v0, -v4, v172, v0
	v_fma_f32 v1, -v5, v173, v1
	v_fma_f32 v0, -v6, v174, v0
	v_fma_f32 v1, -v7, v175, v1
	ds_read_b128 v[172:175], v33 offset:44864
	s_waitcnt lgkmcnt(0)
	v_fma_f32 v0, -v16, v172, v0
	v_fma_f32 v1, -v17, v173, v1
	v_fma_f32 v0, -v18, v174, v0
	v_fma_f32 v1, -v3, v175, v1
	ds_read_b128 v[172:175], v33 offset:44880
	s_waitcnt lgkmcnt(0)
	v_fma_f32 v0, -v19, v172, v0
	v_fma_f32 v1, -v20, v173, v1
	v_fma_f32 v0, -v21, v174, v0
	v_fma_f32 v1, -v22, v175, v1
	ds_read_b128 v[172:175], v33 offset:44896
	s_waitcnt lgkmcnt(0)
	v_fma_f32 v0, -v23, v172, v0
	v_fma_f32 v1, -v24, v173, v1
	v_fma_f32 v0, -v25, v174, v0
	v_fma_f32 v1, -v26, v175, v1
	ds_read_b128 v[172:175], v33 offset:44912
	s_waitcnt lgkmcnt(0)
	v_fma_f32 v0, -v27, v172, v0
	v_fma_f32 v1, -v28, v173, v1
	v_fma_f32 v0, -v29, v174, v0
	v_fma_f32 v1, -v30, v175, v1
	ds_read_b128 v[172:175], v33 offset:44928
	s_waitcnt lgkmcnt(0)
	v_fma_f32 v0, -v31, v172, v0
	v_fma_f32 v1, -v77, v173, v1
	v_fma_f32 v0, -v79, v174, v0
	v_fma_f32 v1, -v81, v175, v1
	ds_read_b128 v[172:175], v33 offset:45088
	v_fma_f32 v0, -v83, v2, v0
	v_add_f32_e32 v85, v1, v0
	v_mul_f32_e32 v0, v171, v92
	v_mul_f32_e32 v1, v0, v176
	v_cndmask_b32_e64 v0, v0, v1, s[8:9]
	s_waitcnt lgkmcnt(0)
	v_fma_f32 v0, -v8, v172, v0
	v_fma_f32 v1, -v9, v173, 0
	v_fma_f32 v0, -v10, v174, v0
	v_fma_f32 v1, -v11, v175, v1
	ds_read_b128 v[172:175], v33 offset:45104
	s_waitcnt lgkmcnt(0)
	v_fma_f32 v0, -v12, v172, v0
	v_fma_f32 v1, -v13, v173, v1
	v_fma_f32 v0, -v14, v174, v0
	v_fma_f32 v1, -v15, v175, v1
	ds_read_b128 v[172:175], v33 offset:45120
	s_waitcnt lgkmcnt(0)
	v_fma_f32 v0, -v4, v172, v0
	v_fma_f32 v1, -v5, v173, v1
	v_fma_f32 v0, -v6, v174, v0
	v_fma_f32 v1, -v7, v175, v1
	ds_read_b128 v[172:175], v33 offset:45136
	s_waitcnt lgkmcnt(0)
	v_fma_f32 v0, -v16, v172, v0
	v_fma_f32 v1, -v17, v173, v1
	v_fma_f32 v0, -v18, v174, v0
	v_fma_f32 v1, -v3, v175, v1
	ds_read_b128 v[172:175], v33 offset:45152
	s_waitcnt lgkmcnt(0)
	v_fma_f32 v0, -v19, v172, v0
	v_fma_f32 v1, -v20, v173, v1
	v_fma_f32 v0, -v21, v174, v0
	v_fma_f32 v1, -v22, v175, v1
	ds_read_b128 v[172:175], v33 offset:45168
	s_waitcnt lgkmcnt(0)
	v_fma_f32 v0, -v23, v172, v0
	v_fma_f32 v1, -v24, v173, v1
	v_fma_f32 v0, -v25, v174, v0
	v_fma_f32 v1, -v26, v175, v1
	ds_read_b128 v[172:175], v33 offset:45184
	s_waitcnt lgkmcnt(0)
	v_fma_f32 v0, -v27, v172, v0
	v_fma_f32 v1, -v28, v173, v1
	v_fma_f32 v0, -v29, v174, v0
	v_fma_f32 v1, -v30, v175, v1
	ds_read_b128 v[172:175], v33 offset:45200
	s_waitcnt lgkmcnt(0)
	v_fma_f32 v0, -v31, v172, v0
	v_fma_f32 v1, -v77, v173, v1
	v_fma_f32 v2, -v79, v174, v0
	v_fma_f32 v87, -v81, v175, v1
	ds_read_b64 v[0:1], v33 offset:45216
	s_waitcnt lgkmcnt(0)
	v_fma_f32 v0, -v83, v0, v2
	v_fma_f32 v1, -v85, v1, v87
	v_add_f32_e32 v87, v0, v1
	v_mul_f32_e32 v0, v170, v93
	ds_read_b128 v[90:93], v33 offset:45360
	ds_read_b128 v[170:173], v33 offset:656
	v_mul_f32_e32 v1, v0, v177
	v_cndmask_b32_e64 v0, v0, v1, s[8:9]
	ds_read_b128 v[174:177], v33 offset:45632
	s_waitcnt lgkmcnt(2)
	v_fma_f32 v0, -v8, v90, v0
	v_fma_f32 v1, -v9, v91, 0
	v_fma_f32 v0, -v10, v92, v0
	v_fma_f32 v1, -v11, v93, v1
	ds_read_b128 v[90:93], v33 offset:45376
	s_waitcnt lgkmcnt(0)
	v_fma_f32 v0, -v12, v90, v0
	v_fma_f32 v1, -v13, v91, v1
	v_fma_f32 v0, -v14, v92, v0
	v_fma_f32 v1, -v15, v93, v1
	ds_read_b128 v[90:93], v33 offset:45392
	s_waitcnt lgkmcnt(0)
	v_fma_f32 v0, -v4, v90, v0
	v_fma_f32 v1, -v5, v91, v1
	v_fma_f32 v0, -v6, v92, v0
	v_fma_f32 v1, -v7, v93, v1
	ds_read_b128 v[90:93], v33 offset:45408
	s_waitcnt lgkmcnt(0)
	v_fma_f32 v0, -v16, v90, v0
	v_fma_f32 v1, -v17, v91, v1
	v_fma_f32 v0, -v18, v92, v0
	v_fma_f32 v1, -v3, v93, v1
	ds_read_b128 v[90:93], v33 offset:45424
	s_waitcnt lgkmcnt(0)
	v_fma_f32 v0, -v19, v90, v0
	v_fma_f32 v1, -v20, v91, v1
	v_fma_f32 v0, -v21, v92, v0
	v_fma_f32 v1, -v22, v93, v1
	ds_read_b128 v[90:93], v33 offset:45440
	s_waitcnt lgkmcnt(0)
	v_fma_f32 v0, -v23, v90, v0
	v_fma_f32 v1, -v24, v91, v1
	v_fma_f32 v0, -v25, v92, v0
	v_fma_f32 v1, -v26, v93, v1
	ds_read_b128 v[90:93], v33 offset:45456
	s_waitcnt lgkmcnt(0)
	v_fma_f32 v0, -v27, v90, v0
	v_fma_f32 v1, -v28, v91, v1
	v_fma_f32 v0, -v29, v92, v0
	v_fma_f32 v1, -v30, v93, v1
	ds_read_b128 v[90:93], v33 offset:45472
	s_waitcnt lgkmcnt(0)
; DI void chunk_prep(const Params& p, int item, char* smem) {
;     ...
;   {
;     const int c = tid;
;     float sol[64];
; #pragma unroll
;     for (int i = 0; i < 64; ++i) {
;       float rhs = rraw[i] * betas[i];
;       if (c >= 128) rhs *= egs[i];
;       float acc = rhs, acc1 = 0.f;
; #pragma unroll
;       for (int j = 0; j < i; ++j) {
;         if (j & 1) acc1 -= Am[i * 68 + j] * sol[j];
;         else acc -= Am[i * 68 + j] * sol[j];
;       }
;       sol[i] = acc + acc1;
;     }
	v_fma_f32 v0, -v31, v90, v0
	v_fma_f32 v1, -v77, v91, v1
	v_fma_f32 v89, -v79, v92, v0
	v_fma_f32 v90, -v81, v93, v1
	ds_read_b96 v[0:2], v33 offset:45488
	s_waitcnt lgkmcnt(0)
	v_fma_f32 v1, -v85, v1, v90
	ds_read_b128 v[90:93], v33 offset:400
	v_fma_f32 v0, -v83, v0, v89
	v_fma_f32 v0, -v87, v2, v0
	v_add_f32_e32 v89, v1, v0
	ds_read_b32 v2, v33 offset:46048
	s_waitcnt lgkmcnt(1)
	v_mul_f32_e32 v0, v169, v90
	v_mul_f32_e32 v1, v0, v170
	v_cndmask_b32_e64 v0, v0, v1, s[8:9]
	v_fma_f32 v0, -v8, v174, v0
	v_fma_f32 v1, -v9, v175, 0
	v_fma_f32 v0, -v10, v176, v0
	v_fma_f32 v1, -v11, v177, v1
	ds_read_b128 v[174:177], v33 offset:45648
	s_waitcnt lgkmcnt(0)
	v_fma_f32 v0, -v12, v174, v0
	v_fma_f32 v1, -v13, v175, v1
	v_fma_f32 v0, -v14, v176, v0
	v_fma_f32 v1, -v15, v177, v1
	ds_read_b128 v[174:177], v33 offset:45664
	s_waitcnt lgkmcnt(0)
	v_fma_f32 v0, -v4, v174, v0
	v_fma_f32 v1, -v5, v175, v1
	v_fma_f32 v0, -v6, v176, v0
	v_fma_f32 v1, -v7, v177, v1
	ds_read_b128 v[174:177], v33 offset:45680
	s_waitcnt lgkmcnt(0)
	v_fma_f32 v0, -v16, v174, v0
	v_fma_f32 v1, -v17, v175, v1
	v_fma_f32 v0, -v18, v176, v0
	v_fma_f32 v1, -v3, v177, v1
	ds_read_b128 v[174:177], v33 offset:45696
	s_waitcnt lgkmcnt(0)
	v_fma_f32 v0, -v19, v174, v0
	v_fma_f32 v1, -v20, v175, v1
	v_fma_f32 v0, -v21, v176, v0
	v_fma_f32 v1, -v22, v177, v1
	ds_read_b128 v[174:177], v33 offset:45712
	s_waitcnt lgkmcnt(0)
	v_fma_f32 v0, -v23, v174, v0
	v_fma_f32 v1, -v24, v175, v1
	v_fma_f32 v0, -v25, v176, v0
	v_fma_f32 v1, -v26, v177, v1
	ds_read_b128 v[174:177], v33 offset:45728
	s_waitcnt lgkmcnt(0)
	v_fma_f32 v0, -v27, v174, v0
	v_fma_f32 v1, -v28, v175, v1
	v_fma_f32 v0, -v29, v176, v0
	v_fma_f32 v1, -v30, v177, v1
	ds_read_b128 v[174:177], v33 offset:45744
	s_waitcnt lgkmcnt(0)
	v_fma_f32 v0, -v31, v174, v0
	v_fma_f32 v1, -v77, v175, v1
	v_fma_f32 v0, -v79, v176, v0
	v_fma_f32 v1, -v81, v177, v1
	ds_read_b128 v[174:177], v33 offset:45760
	s_waitcnt lgkmcnt(0)
	v_fma_f32 v0, -v83, v174, v0
	v_fma_f32 v1, -v85, v175, v1
	v_fma_f32 v0, -v87, v176, v0
	v_fma_f32 v1, -v89, v177, v1
	v_add_f32_e32 v90, v0, v1
	v_mul_f32_e32 v0, v168, v91
	v_mul_f32_e32 v1, v0, v171
	ds_read_b128 v[168:171], v33 offset:45904
	v_cndmask_b32_e64 v0, v0, v1, s[8:9]
	ds_read_b128 v[174:177], v33 offset:46720
	s_waitcnt lgkmcnt(1)
	v_fma_f32 v0, -v8, v168, v0
	v_fma_f32 v1, -v9, v169, 0
	v_fma_f32 v0, -v10, v170, v0
	v_fma_f32 v1, -v11, v171, v1
	ds_read_b128 v[168:171], v33 offset:45920
	s_waitcnt lgkmcnt(0)
	v_fma_f32 v0, -v12, v168, v0
	v_fma_f32 v1, -v13, v169, v1
	v_fma_f32 v0, -v14, v170, v0
	v_fma_f32 v1, -v15, v171, v1
	ds_read_b128 v[168:171], v33 offset:45936
	s_waitcnt lgkmcnt(0)
	v_fma_f32 v0, -v4, v168, v0
	v_fma_f32 v1, -v5, v169, v1
	v_fma_f32 v0, -v6, v170, v0
	v_fma_f32 v1, -v7, v171, v1
	ds_read_b128 v[168:171], v33 offset:45952
	s_waitcnt lgkmcnt(0)
	v_fma_f32 v0, -v16, v168, v0
	v_fma_f32 v1, -v17, v169, v1
	v_fma_f32 v0, -v18, v170, v0
	v_fma_f32 v1, -v3, v171, v1
	ds_read_b128 v[168:171], v33 offset:45968
	s_waitcnt lgkmcnt(0)
	v_fma_f32 v0, -v19, v168, v0
	v_fma_f32 v1, -v20, v169, v1
	v_fma_f32 v0, -v21, v170, v0
	v_fma_f32 v1, -v22, v171, v1
	ds_read_b128 v[168:171], v33 offset:45984
	s_waitcnt lgkmcnt(0)
	v_fma_f32 v0, -v23, v168, v0
	v_fma_f32 v1, -v24, v169, v1
	v_fma_f32 v0, -v25, v170, v0
	v_fma_f32 v1, -v26, v171, v1
	ds_read_b128 v[168:171], v33 offset:46000
	s_waitcnt lgkmcnt(0)
	v_fma_f32 v0, -v27, v168, v0
	v_fma_f32 v1, -v28, v169, v1
	v_fma_f32 v0, -v29, v170, v0
	v_fma_f32 v1, -v30, v171, v1
	ds_read_b128 v[168:171], v33 offset:46016
	s_waitcnt lgkmcnt(0)
	v_fma_f32 v0, -v31, v168, v0
	v_fma_f32 v1, -v77, v169, v1
	v_fma_f32 v0, -v79, v170, v0
	v_fma_f32 v1, -v81, v171, v1
	ds_read_b128 v[168:171], v33 offset:46032
	s_waitcnt lgkmcnt(0)
	v_fma_f32 v0, -v83, v168, v0
	v_fma_f32 v1, -v85, v169, v1
	v_fma_f32 v0, -v87, v170, v0
	v_fma_f32 v1, -v89, v171, v1
	ds_read_b128 v[168:171], v33 offset:46176
	v_fma_f32 v0, -v90, v2, v0
	v_add_f32_e32 v91, v1, v0
	v_mul_f32_e32 v0, v167, v92
	v_mul_f32_e32 v1, v0, v172
	v_cndmask_b32_e64 v0, v0, v1, s[8:9]
	s_waitcnt lgkmcnt(0)
	v_fma_f32 v0, -v8, v168, v0
	v_fma_f32 v1, -v9, v169, 0
	v_fma_f32 v0, -v10, v170, v0
	v_fma_f32 v1, -v11, v171, v1
	ds_read_b128 v[168:171], v33 offset:46192
	s_waitcnt lgkmcnt(0)
	v_fma_f32 v0, -v12, v168, v0
	v_fma_f32 v1, -v13, v169, v1
	v_fma_f32 v0, -v14, v170, v0
	v_fma_f32 v1, -v15, v171, v1
	ds_read_b128 v[168:171], v33 offset:46208
	s_waitcnt lgkmcnt(0)
	v_fma_f32 v0, -v4, v168, v0
	v_fma_f32 v1, -v5, v169, v1
	v_fma_f32 v0, -v6, v170, v0
	v_fma_f32 v1, -v7, v171, v1
	ds_read_b128 v[168:171], v33 offset:46224
	s_waitcnt lgkmcnt(0)
	v_fma_f32 v0, -v16, v168, v0
	v_fma_f32 v1, -v17, v169, v1
	v_fma_f32 v0, -v18, v170, v0
	v_fma_f32 v1, -v3, v171, v1
	ds_read_b128 v[168:171], v33 offset:46240
	s_waitcnt lgkmcnt(0)
	v_fma_f32 v0, -v19, v168, v0
	v_fma_f32 v1, -v20, v169, v1
	v_fma_f32 v0, -v21, v170, v0
	v_fma_f32 v1, -v22, v171, v1
	ds_read_b128 v[168:171], v33 offset:46256
	s_waitcnt lgkmcnt(0)
	v_fma_f32 v0, -v23, v168, v0
	v_fma_f32 v1, -v24, v169, v1
	v_fma_f32 v0, -v25, v170, v0
	v_fma_f32 v1, -v26, v171, v1
	ds_read_b128 v[168:171], v33 offset:46272
	s_waitcnt lgkmcnt(0)
	v_fma_f32 v0, -v27, v168, v0
	v_fma_f32 v1, -v28, v169, v1
	v_fma_f32 v0, -v29, v170, v0
	v_fma_f32 v1, -v30, v171, v1
	ds_read_b128 v[168:171], v33 offset:46288
	s_waitcnt lgkmcnt(0)
	v_fma_f32 v0, -v31, v168, v0
	v_fma_f32 v1, -v77, v169, v1
	v_fma_f32 v0, -v79, v170, v0
	v_fma_f32 v1, -v81, v171, v1
	ds_read_b128 v[168:171], v33 offset:46304
	s_waitcnt lgkmcnt(0)
; DI void chunk_prep(const Params& p, int item, char* smem) {
;     ...
;   {
;     const int c = tid;
;     float sol[64];
; #pragma unroll
;     for (int i = 0; i < 64; ++i) {
;       float rhs = rraw[i] * betas[i];
;       if (c >= 128) rhs *= egs[i];
;       float acc = rhs, acc1 = 0.f;
; #pragma unroll
;       for (int j = 0; j < i; ++j) {
;         if (j & 1) acc1 -= Am[i * 68 + j] * sol[j];
;         else acc -= Am[i * 68 + j] * sol[j];
;       }
;       sol[i] = acc + acc1;
;     }
	v_fma_f32 v0, -v83, v168, v0
	v_fma_f32 v1, -v85, v169, v1
	v_fma_f32 v2, -v87, v170, v0
	v_fma_f32 v92, -v89, v171, v1
	ds_read_b64 v[0:1], v33 offset:46320
	s_waitcnt lgkmcnt(0)
	v_fma_f32 v0, -v90, v0, v2
	v_fma_f32 v1, -v91, v1, v92
	v_add_f32_e32 v92, v0, v1
	v_mul_f32_e32 v0, v166, v93
	ds_read_b128 v[166:169], v33 offset:46448
	v_mul_f32_e32 v1, v0, v173
	v_cndmask_b32_e64 v0, v0, v1, s[8:9]
	ds_read_b128 v[170:173], v33 offset:672
	s_waitcnt lgkmcnt(1)
	v_fma_f32 v0, -v8, v166, v0
	v_fma_f32 v1, -v9, v167, 0
	v_fma_f32 v0, -v10, v168, v0
	v_fma_f32 v1, -v11, v169, v1
	ds_read_b128 v[166:169], v33 offset:46464
	s_waitcnt lgkmcnt(0)
	v_fma_f32 v0, -v12, v166, v0
	v_fma_f32 v1, -v13, v167, v1
	v_fma_f32 v0, -v14, v168, v0
	v_fma_f32 v1, -v15, v169, v1
	ds_read_b128 v[166:169], v33 offset:46480
	s_waitcnt lgkmcnt(0)
	v_fma_f32 v0, -v4, v166, v0
	v_fma_f32 v1, -v5, v167, v1
	v_fma_f32 v0, -v6, v168, v0
	v_fma_f32 v1, -v7, v169, v1
	ds_read_b128 v[166:169], v33 offset:46496
	s_waitcnt lgkmcnt(0)
	v_fma_f32 v0, -v16, v166, v0
	v_fma_f32 v1, -v17, v167, v1
	v_fma_f32 v0, -v18, v168, v0
	v_fma_f32 v1, -v3, v169, v1
	ds_read_b128 v[166:169], v33 offset:46512
	s_waitcnt lgkmcnt(0)
	v_fma_f32 v0, -v19, v166, v0
	v_fma_f32 v1, -v20, v167, v1
	v_fma_f32 v0, -v21, v168, v0
	v_fma_f32 v1, -v22, v169, v1
	ds_read_b128 v[166:169], v33 offset:46528
	s_waitcnt lgkmcnt(0)
	v_fma_f32 v0, -v23, v166, v0
	v_fma_f32 v1, -v24, v167, v1
	v_fma_f32 v0, -v25, v168, v0
	v_fma_f32 v1, -v26, v169, v1
	ds_read_b128 v[166:169], v33 offset:46544
	s_waitcnt lgkmcnt(0)
	v_fma_f32 v0, -v27, v166, v0
	v_fma_f32 v1, -v28, v167, v1
	v_fma_f32 v0, -v29, v168, v0
	v_fma_f32 v1, -v30, v169, v1
	ds_read_b128 v[166:169], v33 offset:46560
	s_waitcnt lgkmcnt(0)
	v_fma_f32 v0, -v31, v166, v0
	v_fma_f32 v1, -v77, v167, v1
	v_fma_f32 v0, -v79, v168, v0
	v_fma_f32 v1, -v81, v169, v1
	ds_read_b128 v[166:169], v33 offset:46576
	s_waitcnt lgkmcnt(0)
	v_fma_f32 v0, -v83, v166, v0
	v_fma_f32 v1, -v85, v167, v1
	v_fma_f32 v93, -v87, v168, v0
	v_fma_f32 v166, -v89, v169, v1
	ds_read_b96 v[0:2], v33 offset:46592
	s_waitcnt lgkmcnt(0)
	v_fma_f32 v1, -v91, v1, v166
	ds_read_b128 v[166:169], v33 offset:416
	v_fma_f32 v0, -v90, v0, v93
	v_fma_f32 v0, -v92, v2, v0
	v_add_f32_e32 v93, v1, v0
	ds_read_b32 v2, v33 offset:47152
	s_waitcnt lgkmcnt(1)
	v_mul_f32_e32 v0, v142, v166
	v_mul_f32_e32 v1, v0, v170
	v_cndmask_b32_e64 v0, v0, v1, s[8:9]
	v_fma_f32 v0, -v8, v174, v0
	v_fma_f32 v1, -v9, v175, 0
	v_fma_f32 v0, -v10, v176, v0
	v_fma_f32 v1, -v11, v177, v1
	ds_read_b128 v[174:177], v33 offset:46736
	s_waitcnt lgkmcnt(0)
	v_fma_f32 v0, -v12, v174, v0
	v_fma_f32 v1, -v13, v175, v1
	v_fma_f32 v0, -v14, v176, v0
	v_fma_f32 v1, -v15, v177, v1
	ds_read_b128 v[174:177], v33 offset:46752
	s_waitcnt lgkmcnt(0)
	v_fma_f32 v0, -v4, v174, v0
	v_fma_f32 v1, -v5, v175, v1
	v_fma_f32 v0, -v6, v176, v0
	v_fma_f32 v1, -v7, v177, v1
	ds_read_b128 v[174:177], v33 offset:46768
	s_waitcnt lgkmcnt(0)
	v_fma_f32 v0, -v16, v174, v0
	v_fma_f32 v1, -v17, v175, v1
	v_fma_f32 v0, -v18, v176, v0
	v_fma_f32 v1, -v3, v177, v1
	ds_read_b128 v[174:177], v33 offset:46784
	s_waitcnt lgkmcnt(0)
	v_fma_f32 v0, -v19, v174, v0
	v_fma_f32 v1, -v20, v175, v1
	v_fma_f32 v0, -v21, v176, v0
	v_fma_f32 v1, -v22, v177, v1
	ds_read_b128 v[174:177], v33 offset:46800
	s_waitcnt lgkmcnt(0)
	v_fma_f32 v0, -v23, v174, v0
	v_fma_f32 v1, -v24, v175, v1
	v_fma_f32 v0, -v25, v176, v0
	v_fma_f32 v1, -v26, v177, v1
	ds_read_b128 v[174:177], v33 offset:46816
	s_waitcnt lgkmcnt(0)
	v_fma_f32 v0, -v27, v174, v0
	v_fma_f32 v1, -v28, v175, v1
	v_fma_f32 v0, -v29, v176, v0
	v_fma_f32 v1, -v30, v177, v1
	ds_read_b128 v[174:177], v33 offset:46832
	s_waitcnt lgkmcnt(0)
	v_fma_f32 v0, -v31, v174, v0
	v_fma_f32 v1, -v77, v175, v1
	v_fma_f32 v0, -v79, v176, v0
	v_fma_f32 v1, -v81, v177, v1
	ds_read_b128 v[174:177], v33 offset:46848
	s_waitcnt lgkmcnt(0)
	v_fma_f32 v0, -v83, v174, v0
	v_fma_f32 v1, -v85, v175, v1
	v_fma_f32 v0, -v87, v176, v0
	v_fma_f32 v1, -v89, v177, v1
	ds_read_b128 v[174:177], v33 offset:46864
	s_waitcnt lgkmcnt(0)
	v_fma_f32 v0, -v90, v174, v0
	v_fma_f32 v1, -v91, v175, v1
	v_fma_f32 v0, -v92, v176, v0
	v_fma_f32 v1, -v93, v177, v1
	ds_read_b128 v[174:177], v33 offset:46992
	v_add_f32_e32 v142, v0, v1
	v_mul_f32_e32 v0, v143, v167
	v_mul_f32_e32 v1, v0, v171
	v_cndmask_b32_e64 v0, v0, v1, s[8:9]
	s_waitcnt lgkmcnt(0)
	v_fma_f32 v0, -v8, v174, v0
	v_fma_f32 v1, -v9, v175, 0
	v_fma_f32 v0, -v10, v176, v0
	v_fma_f32 v1, -v11, v177, v1
	ds_read_b128 v[174:177], v33 offset:47008
	s_waitcnt lgkmcnt(0)
	v_fma_f32 v0, -v12, v174, v0
	v_fma_f32 v1, -v13, v175, v1
	v_fma_f32 v0, -v14, v176, v0
	v_fma_f32 v1, -v15, v177, v1
	ds_read_b128 v[174:177], v33 offset:47024
	s_waitcnt lgkmcnt(0)
	v_fma_f32 v0, -v4, v174, v0
	v_fma_f32 v1, -v5, v175, v1
	v_fma_f32 v0, -v6, v176, v0
	v_fma_f32 v1, -v7, v177, v1
	ds_read_b128 v[174:177], v33 offset:47040
	s_waitcnt lgkmcnt(0)
	v_fma_f32 v0, -v16, v174, v0
	v_fma_f32 v1, -v17, v175, v1
	v_fma_f32 v0, -v18, v176, v0
	v_fma_f32 v1, -v3, v177, v1
	ds_read_b128 v[174:177], v33 offset:47056
	s_waitcnt lgkmcnt(0)
	v_fma_f32 v0, -v19, v174, v0
	v_fma_f32 v1, -v20, v175, v1
	v_fma_f32 v0, -v21, v176, v0
	v_fma_f32 v1, -v22, v177, v1
	ds_read_b128 v[174:177], v33 offset:47072
	s_waitcnt lgkmcnt(0)
	v_fma_f32 v0, -v23, v174, v0
	v_fma_f32 v1, -v24, v175, v1
	v_fma_f32 v0, -v25, v176, v0
	v_fma_f32 v1, -v26, v177, v1
	ds_read_b128 v[174:177], v33 offset:47088
	s_waitcnt lgkmcnt(0)
	v_fma_f32 v0, -v27, v174, v0
	v_fma_f32 v1, -v28, v175, v1
	v_fma_f32 v0, -v29, v176, v0
	v_fma_f32 v1, -v30, v177, v1
	ds_read_b128 v[174:177], v33 offset:47104
	s_waitcnt lgkmcnt(0)
; DI void chunk_prep(const Params& p, int item, char* smem) {
;     ...
;   {
;     const int c = tid;
;     float sol[64];
; #pragma unroll
;     for (int i = 0; i < 64; ++i) {
;       float rhs = rraw[i] * betas[i];
;       if (c >= 128) rhs *= egs[i];
;       float acc = rhs, acc1 = 0.f;
; #pragma unroll
;       for (int j = 0; j < i; ++j) {
;         if (j & 1) acc1 -= Am[i * 68 + j] * sol[j];
;         else acc -= Am[i * 68 + j] * sol[j];
;       }
;       sol[i] = acc + acc1;
;     }
	v_fma_f32 v0, -v31, v174, v0
	v_fma_f32 v1, -v77, v175, v1
	v_fma_f32 v0, -v79, v176, v0
	v_fma_f32 v1, -v81, v177, v1
	ds_read_b128 v[174:177], v33 offset:47120
	s_waitcnt lgkmcnt(0)
	v_fma_f32 v0, -v83, v174, v0
	v_fma_f32 v1, -v85, v175, v1
	v_fma_f32 v0, -v87, v176, v0
	v_fma_f32 v1, -v89, v177, v1
	ds_read_b128 v[174:177], v33 offset:47136
	s_waitcnt lgkmcnt(0)
	v_fma_f32 v0, -v90, v174, v0
	v_fma_f32 v1, -v91, v175, v1
	v_fma_f32 v0, -v92, v176, v0
	v_fma_f32 v1, -v93, v177, v1
	ds_read_b128 v[174:177], v33 offset:47264
	v_fma_f32 v0, -v142, v2, v0
	v_add_f32_e32 v143, v1, v0
	v_mul_f32_e32 v0, v144, v168
	v_mul_f32_e32 v1, v0, v172
	v_cndmask_b32_e64 v0, v0, v1, s[8:9]
	s_waitcnt lgkmcnt(0)
	v_fma_f32 v0, -v8, v174, v0
	v_fma_f32 v1, -v9, v175, 0
	v_fma_f32 v0, -v10, v176, v0
	v_fma_f32 v1, -v11, v177, v1
	ds_read_b128 v[174:177], v33 offset:47280
	s_waitcnt lgkmcnt(0)
	v_fma_f32 v0, -v12, v174, v0
	v_fma_f32 v1, -v13, v175, v1
	v_fma_f32 v0, -v14, v176, v0
	v_fma_f32 v1, -v15, v177, v1
	ds_read_b128 v[174:177], v33 offset:47296
	s_waitcnt lgkmcnt(0)
	v_fma_f32 v0, -v4, v174, v0
	v_fma_f32 v1, -v5, v175, v1
	v_fma_f32 v0, -v6, v176, v0
	v_fma_f32 v1, -v7, v177, v1
	ds_read_b128 v[174:177], v33 offset:47312
	s_waitcnt lgkmcnt(0)
	v_fma_f32 v0, -v16, v174, v0
	v_fma_f32 v1, -v17, v175, v1
	v_fma_f32 v0, -v18, v176, v0
	v_fma_f32 v1, -v3, v177, v1
	ds_read_b128 v[174:177], v33 offset:47328
	s_waitcnt lgkmcnt(0)
	v_fma_f32 v0, -v19, v174, v0
	v_fma_f32 v1, -v20, v175, v1
	v_fma_f32 v0, -v21, v176, v0
	v_fma_f32 v1, -v22, v177, v1
	ds_read_b128 v[174:177], v33 offset:47344
	s_waitcnt lgkmcnt(0)
	v_fma_f32 v0, -v23, v174, v0
	v_fma_f32 v1, -v24, v175, v1
	v_fma_f32 v0, -v25, v176, v0
	v_fma_f32 v1, -v26, v177, v1
	ds_read_b128 v[174:177], v33 offset:47360
	s_waitcnt lgkmcnt(0)
	v_fma_f32 v0, -v27, v174, v0
	v_fma_f32 v1, -v28, v175, v1
	v_fma_f32 v0, -v29, v176, v0
	v_fma_f32 v1, -v30, v177, v1
	ds_read_b128 v[174:177], v33 offset:47376
	s_waitcnt lgkmcnt(0)
	v_fma_f32 v0, -v31, v174, v0
	v_fma_f32 v1, -v77, v175, v1
	v_fma_f32 v0, -v79, v176, v0
	v_fma_f32 v1, -v81, v177, v1
	ds_read_b128 v[174:177], v33 offset:47392
	s_waitcnt lgkmcnt(0)
	v_fma_f32 v0, -v83, v174, v0
	v_fma_f32 v1, -v85, v175, v1
	v_fma_f32 v0, -v87, v176, v0
	v_fma_f32 v1, -v89, v177, v1
	ds_read_b128 v[174:177], v33 offset:47408
	s_waitcnt lgkmcnt(0)
	v_fma_f32 v0, -v90, v174, v0
	v_fma_f32 v1, -v91, v175, v1
	v_fma_f32 v2, -v92, v176, v0
	v_fma_f32 v144, -v93, v177, v1
	ds_read_b64 v[0:1], v33 offset:47424
	ds_read_b128 v[174:177], v33 offset:47808
	s_waitcnt lgkmcnt(1)
	v_fma_f32 v0, -v142, v0, v2
	v_fma_f32 v1, -v143, v1, v144
	v_add_f32_e32 v144, v0, v1
	v_mul_f32_e32 v0, v145, v169
	ds_read_b128 v[166:169], v33 offset:47536
	v_mul_f32_e32 v1, v0, v173
	v_cndmask_b32_e64 v0, v0, v1, s[8:9]
	ds_read_b128 v[170:173], v33 offset:688
	s_waitcnt lgkmcnt(1)
	v_fma_f32 v0, -v8, v166, v0
	v_fma_f32 v1, -v9, v167, 0
	v_fma_f32 v0, -v10, v168, v0
	v_fma_f32 v1, -v11, v169, v1
	ds_read_b128 v[166:169], v33 offset:47552
	s_waitcnt lgkmcnt(0)
	v_fma_f32 v0, -v12, v166, v0
	v_fma_f32 v1, -v13, v167, v1
	v_fma_f32 v0, -v14, v168, v0
	v_fma_f32 v1, -v15, v169, v1
	ds_read_b128 v[166:169], v33 offset:47568
	s_waitcnt lgkmcnt(0)
	v_fma_f32 v0, -v4, v166, v0
	v_fma_f32 v1, -v5, v167, v1
	v_fma_f32 v0, -v6, v168, v0
	v_fma_f32 v1, -v7, v169, v1
	ds_read_b128 v[166:169], v33 offset:47584
	s_waitcnt lgkmcnt(0)
	v_fma_f32 v0, -v16, v166, v0
	v_fma_f32 v1, -v17, v167, v1
	v_fma_f32 v0, -v18, v168, v0
	v_fma_f32 v1, -v3, v169, v1
	ds_read_b128 v[166:169], v33 offset:47600
	s_waitcnt lgkmcnt(0)
	v_fma_f32 v0, -v19, v166, v0
	v_fma_f32 v1, -v20, v167, v1
	v_fma_f32 v0, -v21, v168, v0
	v_fma_f32 v1, -v22, v169, v1
	ds_read_b128 v[166:169], v33 offset:47616
	s_waitcnt lgkmcnt(0)
	v_fma_f32 v0, -v23, v166, v0
	v_fma_f32 v1, -v24, v167, v1
	v_fma_f32 v0, -v25, v168, v0
	v_fma_f32 v1, -v26, v169, v1
	ds_read_b128 v[166:169], v33 offset:47632
	s_waitcnt lgkmcnt(0)
	v_fma_f32 v0, -v27, v166, v0
	v_fma_f32 v1, -v28, v167, v1
	v_fma_f32 v0, -v29, v168, v0
	v_fma_f32 v1, -v30, v169, v1
	ds_read_b128 v[166:169], v33 offset:47648
	s_waitcnt lgkmcnt(0)
	v_fma_f32 v0, -v31, v166, v0
	v_fma_f32 v1, -v77, v167, v1
	v_fma_f32 v0, -v79, v168, v0
	v_fma_f32 v1, -v81, v169, v1
	ds_read_b128 v[166:169], v33 offset:47664
	s_waitcnt lgkmcnt(0)
	v_fma_f32 v0, -v83, v166, v0
	v_fma_f32 v1, -v85, v167, v1
	v_fma_f32 v0, -v87, v168, v0
	v_fma_f32 v1, -v89, v169, v1
	ds_read_b128 v[166:169], v33 offset:47680
	s_waitcnt lgkmcnt(0)
	v_fma_f32 v0, -v90, v166, v0
	v_fma_f32 v1, -v91, v167, v1
	v_fma_f32 v145, -v92, v168, v0
	v_fma_f32 v166, -v93, v169, v1
	ds_read_b96 v[0:2], v33 offset:47696
	s_waitcnt lgkmcnt(0)
	v_fma_f32 v1, -v143, v1, v166
	ds_read_b128 v[166:169], v33 offset:432
	v_fma_f32 v0, -v142, v0, v145
	v_fma_f32 v0, -v144, v2, v0
	v_add_f32_e32 v145, v1, v0
	ds_read_b32 v2, v33 offset:48256
	s_waitcnt lgkmcnt(1)
	v_mul_f32_e32 v0, v146, v166
	v_mul_f32_e32 v1, v0, v170
	v_cndmask_b32_e64 v0, v0, v1, s[8:9]
	v_fma_f32 v0, -v8, v174, v0
	v_fma_f32 v1, -v9, v175, 0
	v_fma_f32 v0, -v10, v176, v0
	v_fma_f32 v1, -v11, v177, v1
	ds_read_b128 v[174:177], v33 offset:47824
	s_waitcnt lgkmcnt(0)
	v_fma_f32 v0, -v12, v174, v0
	v_fma_f32 v1, -v13, v175, v1
	v_fma_f32 v0, -v14, v176, v0
	v_fma_f32 v1, -v15, v177, v1
	ds_read_b128 v[174:177], v33 offset:47840
	s_waitcnt lgkmcnt(0)
	v_fma_f32 v0, -v4, v174, v0
	v_fma_f32 v1, -v5, v175, v1
	v_fma_f32 v0, -v6, v176, v0
	v_fma_f32 v1, -v7, v177, v1
	ds_read_b128 v[174:177], v33 offset:47856
	s_waitcnt lgkmcnt(0)
; DI void chunk_prep(const Params& p, int item, char* smem) {
;     ...
;   {
;     const int c = tid;
;     float sol[64];
; #pragma unroll
;     for (int i = 0; i < 64; ++i) {
;       float rhs = rraw[i] * betas[i];
;       if (c >= 128) rhs *= egs[i];
;       float acc = rhs, acc1 = 0.f;
; #pragma unroll
;       for (int j = 0; j < i; ++j) {
;         if (j & 1) acc1 -= Am[i * 68 + j] * sol[j];
;         else acc -= Am[i * 68 + j] * sol[j];
;       }
;       sol[i] = acc + acc1;
;     }
	v_fma_f32 v0, -v16, v174, v0
	v_fma_f32 v1, -v17, v175, v1
	v_fma_f32 v0, -v18, v176, v0
	v_fma_f32 v1, -v3, v177, v1
	ds_read_b128 v[174:177], v33 offset:47872
	s_waitcnt lgkmcnt(0)
	v_fma_f32 v0, -v19, v174, v0
	v_fma_f32 v1, -v20, v175, v1
	v_fma_f32 v0, -v21, v176, v0
	v_fma_f32 v1, -v22, v177, v1
	ds_read_b128 v[174:177], v33 offset:47888
	s_waitcnt lgkmcnt(0)
	v_fma_f32 v0, -v23, v174, v0
	v_fma_f32 v1, -v24, v175, v1
	v_fma_f32 v0, -v25, v176, v0
	v_fma_f32 v1, -v26, v177, v1
	ds_read_b128 v[174:177], v33 offset:47904
	s_waitcnt lgkmcnt(0)
	v_fma_f32 v0, -v27, v174, v0
	v_fma_f32 v1, -v28, v175, v1
	v_fma_f32 v0, -v29, v176, v0
	v_fma_f32 v1, -v30, v177, v1
	ds_read_b128 v[174:177], v33 offset:47920
	s_waitcnt lgkmcnt(0)
	v_fma_f32 v0, -v31, v174, v0
	v_fma_f32 v1, -v77, v175, v1
	v_fma_f32 v0, -v79, v176, v0
	v_fma_f32 v1, -v81, v177, v1
	ds_read_b128 v[174:177], v33 offset:47936
	s_waitcnt lgkmcnt(0)
	v_fma_f32 v0, -v83, v174, v0
	v_fma_f32 v1, -v85, v175, v1
	v_fma_f32 v0, -v87, v176, v0
	v_fma_f32 v1, -v89, v177, v1
	ds_read_b128 v[174:177], v33 offset:47952
	s_waitcnt lgkmcnt(0)
	v_fma_f32 v0, -v90, v174, v0
	v_fma_f32 v1, -v91, v175, v1
	v_fma_f32 v0, -v92, v176, v0
	v_fma_f32 v1, -v93, v177, v1
	ds_read_b128 v[174:177], v33 offset:47968
	s_waitcnt lgkmcnt(0)
	v_fma_f32 v0, -v142, v174, v0
	v_fma_f32 v1, -v143, v175, v1
	v_fma_f32 v0, -v144, v176, v0
	v_fma_f32 v1, -v145, v177, v1
	ds_read_b128 v[174:177], v33 offset:48080
	v_add_f32_e32 v146, v0, v1
	v_mul_f32_e32 v0, v147, v167
	v_mul_f32_e32 v1, v0, v171
	v_cndmask_b32_e64 v0, v0, v1, s[8:9]
	s_waitcnt lgkmcnt(0)
	v_fma_f32 v0, -v8, v174, v0
	v_fma_f32 v1, -v9, v175, 0
	v_fma_f32 v0, -v10, v176, v0
	v_fma_f32 v1, -v11, v177, v1
	ds_read_b128 v[174:177], v33 offset:48096
	s_waitcnt lgkmcnt(0)
	v_fma_f32 v0, -v12, v174, v0
	v_fma_f32 v1, -v13, v175, v1
	v_fma_f32 v0, -v14, v176, v0
	v_fma_f32 v1, -v15, v177, v1
	ds_read_b128 v[174:177], v33 offset:48112
	s_waitcnt lgkmcnt(0)
	v_fma_f32 v0, -v4, v174, v0
	v_fma_f32 v1, -v5, v175, v1
	v_fma_f32 v0, -v6, v176, v0
	v_fma_f32 v1, -v7, v177, v1
	ds_read_b128 v[174:177], v33 offset:48128
	s_waitcnt lgkmcnt(0)
	v_fma_f32 v0, -v16, v174, v0
	v_fma_f32 v1, -v17, v175, v1
	v_fma_f32 v0, -v18, v176, v0
	v_fma_f32 v1, -v3, v177, v1
	ds_read_b128 v[174:177], v33 offset:48144
	s_waitcnt lgkmcnt(0)
	v_fma_f32 v0, -v19, v174, v0
	v_fma_f32 v1, -v20, v175, v1
	v_fma_f32 v0, -v21, v176, v0
	v_fma_f32 v1, -v22, v177, v1
	ds_read_b128 v[174:177], v33 offset:48160
	s_waitcnt lgkmcnt(0)
	v_fma_f32 v0, -v23, v174, v0
	v_fma_f32 v1, -v24, v175, v1
	v_fma_f32 v0, -v25, v176, v0
	v_fma_f32 v1, -v26, v177, v1
	ds_read_b128 v[174:177], v33 offset:48176
	s_waitcnt lgkmcnt(0)
	v_fma_f32 v0, -v27, v174, v0
	v_fma_f32 v1, -v28, v175, v1
	v_fma_f32 v0, -v29, v176, v0
	v_fma_f32 v1, -v30, v177, v1
	ds_read_b128 v[174:177], v33 offset:48192
	s_waitcnt lgkmcnt(0)
	v_fma_f32 v0, -v31, v174, v0
	v_fma_f32 v1, -v77, v175, v1
	v_fma_f32 v0, -v79, v176, v0
	v_fma_f32 v1, -v81, v177, v1
	ds_read_b128 v[174:177], v33 offset:48208
	s_waitcnt lgkmcnt(0)
	v_fma_f32 v0, -v83, v174, v0
	v_fma_f32 v1, -v85, v175, v1
	v_fma_f32 v0, -v87, v176, v0
	v_fma_f32 v1, -v89, v177, v1
	ds_read_b128 v[174:177], v33 offset:48224
	s_waitcnt lgkmcnt(0)
	v_fma_f32 v0, -v90, v174, v0
	v_fma_f32 v1, -v91, v175, v1
	v_fma_f32 v0, -v92, v176, v0
	v_fma_f32 v1, -v93, v177, v1
	ds_read_b128 v[174:177], v33 offset:48240
	s_waitcnt lgkmcnt(0)
	v_fma_f32 v0, -v142, v174, v0
	v_fma_f32 v1, -v143, v175, v1
	v_fma_f32 v0, -v144, v176, v0
	v_fma_f32 v1, -v145, v177, v1
	ds_read_b128 v[174:177], v33 offset:48352
	v_fma_f32 v0, -v146, v2, v0
	v_add_f32_e32 v147, v1, v0
	v_mul_f32_e32 v0, v148, v168
	v_mul_f32_e32 v1, v0, v172
	v_cndmask_b32_e64 v0, v0, v1, s[8:9]
	s_waitcnt lgkmcnt(0)
	v_fma_f32 v0, -v8, v174, v0
	v_fma_f32 v1, -v9, v175, 0
	v_fma_f32 v0, -v10, v176, v0
	v_fma_f32 v1, -v11, v177, v1
	ds_read_b128 v[174:177], v33 offset:48368
	s_waitcnt lgkmcnt(0)
	v_fma_f32 v0, -v12, v174, v0
	v_fma_f32 v1, -v13, v175, v1
	v_fma_f32 v0, -v14, v176, v0
	v_fma_f32 v1, -v15, v177, v1
	ds_read_b128 v[174:177], v33 offset:48384
	s_waitcnt lgkmcnt(0)
	v_fma_f32 v0, -v4, v174, v0
	v_fma_f32 v1, -v5, v175, v1
	v_fma_f32 v0, -v6, v176, v0
	v_fma_f32 v1, -v7, v177, v1
	ds_read_b128 v[174:177], v33 offset:48400
	s_waitcnt lgkmcnt(0)
	v_fma_f32 v0, -v16, v174, v0
	v_fma_f32 v1, -v17, v175, v1
	v_fma_f32 v0, -v18, v176, v0
	v_fma_f32 v1, -v3, v177, v1
	ds_read_b128 v[174:177], v33 offset:48416
	s_waitcnt lgkmcnt(0)
	v_fma_f32 v0, -v19, v174, v0
	v_fma_f32 v1, -v20, v175, v1
	v_fma_f32 v0, -v21, v176, v0
	v_fma_f32 v1, -v22, v177, v1
	ds_read_b128 v[174:177], v33 offset:48432
	s_waitcnt lgkmcnt(0)
	v_fma_f32 v0, -v23, v174, v0
	v_fma_f32 v1, -v24, v175, v1
	v_fma_f32 v0, -v25, v176, v0
	v_fma_f32 v1, -v26, v177, v1
	ds_read_b128 v[174:177], v33 offset:48448
	s_waitcnt lgkmcnt(0)
	v_fma_f32 v0, -v27, v174, v0
	v_fma_f32 v1, -v28, v175, v1
	v_fma_f32 v0, -v29, v176, v0
	v_fma_f32 v1, -v30, v177, v1
	ds_read_b128 v[174:177], v33 offset:48464
	s_waitcnt lgkmcnt(0)
	v_fma_f32 v0, -v31, v174, v0
	v_fma_f32 v1, -v77, v175, v1
	v_fma_f32 v0, -v79, v176, v0
	v_fma_f32 v1, -v81, v177, v1
	ds_read_b128 v[174:177], v33 offset:48480
	s_waitcnt lgkmcnt(0)
	v_fma_f32 v0, -v83, v174, v0
	v_fma_f32 v1, -v85, v175, v1
	v_fma_f32 v0, -v87, v176, v0
	v_fma_f32 v1, -v89, v177, v1
	ds_read_b128 v[174:177], v33 offset:48496
	s_waitcnt lgkmcnt(0)
	v_fma_f32 v0, -v90, v174, v0
	v_fma_f32 v1, -v91, v175, v1
	v_fma_f32 v0, -v92, v176, v0
	v_fma_f32 v1, -v93, v177, v1
	ds_read_b128 v[174:177], v33 offset:48512
	s_waitcnt lgkmcnt(0)
; DI void chunk_prep(const Params& p, int item, char* smem) {
;     ...
;   {
;     const int c = tid;
;     float sol[64];
; #pragma unroll
;     for (int i = 0; i < 64; ++i) {
;       float rhs = rraw[i] * betas[i];
;       if (c >= 128) rhs *= egs[i];
;       float acc = rhs, acc1 = 0.f;
; #pragma unroll
;       for (int j = 0; j < i; ++j) {
;         if (j & 1) acc1 -= Am[i * 68 + j] * sol[j];
;         else acc -= Am[i * 68 + j] * sol[j];
;       }
;       sol[i] = acc + acc1;
;     }
	v_fma_f32 v0, -v142, v174, v0
	v_fma_f32 v1, -v143, v175, v1
	v_fma_f32 v2, -v144, v176, v0
	v_fma_f32 v148, -v145, v177, v1
	ds_read_b64 v[0:1], v33 offset:48528
	ds_read_b128 v[174:177], v33 offset:48896
	s_waitcnt lgkmcnt(1)
	v_fma_f32 v0, -v146, v0, v2
	v_fma_f32 v1, -v147, v1, v148
	v_add_f32_e32 v148, v0, v1
	v_mul_f32_e32 v0, v149, v169
	ds_read_b128 v[166:169], v33 offset:48624
	v_mul_f32_e32 v1, v0, v173
	v_cndmask_b32_e64 v0, v0, v1, s[8:9]
	ds_read_b128 v[170:173], v33 offset:704
	s_waitcnt lgkmcnt(1)
	v_fma_f32 v0, -v8, v166, v0
	v_fma_f32 v1, -v9, v167, 0
	v_fma_f32 v0, -v10, v168, v0
	v_fma_f32 v1, -v11, v169, v1
	ds_read_b128 v[166:169], v33 offset:48640
	s_waitcnt lgkmcnt(0)
	v_fma_f32 v0, -v12, v166, v0
	v_fma_f32 v1, -v13, v167, v1
	v_fma_f32 v0, -v14, v168, v0
	v_fma_f32 v1, -v15, v169, v1
	ds_read_b128 v[166:169], v33 offset:48656
	s_waitcnt lgkmcnt(0)
	v_fma_f32 v0, -v4, v166, v0
	v_fma_f32 v1, -v5, v167, v1
	v_fma_f32 v0, -v6, v168, v0
	v_fma_f32 v1, -v7, v169, v1
	ds_read_b128 v[166:169], v33 offset:48672
	s_waitcnt lgkmcnt(0)
	v_fma_f32 v0, -v16, v166, v0
	v_fma_f32 v1, -v17, v167, v1
	v_fma_f32 v0, -v18, v168, v0
	v_fma_f32 v1, -v3, v169, v1
	ds_read_b128 v[166:169], v33 offset:48688
	s_waitcnt lgkmcnt(0)
	v_fma_f32 v0, -v19, v166, v0
	v_fma_f32 v1, -v20, v167, v1
	v_fma_f32 v0, -v21, v168, v0
	v_fma_f32 v1, -v22, v169, v1
	ds_read_b128 v[166:169], v33 offset:48704
	s_waitcnt lgkmcnt(0)
	v_fma_f32 v0, -v23, v166, v0
	v_fma_f32 v1, -v24, v167, v1
	v_fma_f32 v0, -v25, v168, v0
	v_fma_f32 v1, -v26, v169, v1
	ds_read_b128 v[166:169], v33 offset:48720
	s_waitcnt lgkmcnt(0)
	v_fma_f32 v0, -v27, v166, v0
	v_fma_f32 v1, -v28, v167, v1
	v_fma_f32 v0, -v29, v168, v0
	v_fma_f32 v1, -v30, v169, v1
	ds_read_b128 v[166:169], v33 offset:48736
	s_waitcnt lgkmcnt(0)
	v_fma_f32 v0, -v31, v166, v0
	v_fma_f32 v1, -v77, v167, v1
	v_fma_f32 v0, -v79, v168, v0
	v_fma_f32 v1, -v81, v169, v1
	ds_read_b128 v[166:169], v33 offset:48752
	s_waitcnt lgkmcnt(0)
	v_fma_f32 v0, -v83, v166, v0
	v_fma_f32 v1, -v85, v167, v1
	v_fma_f32 v0, -v87, v168, v0
	v_fma_f32 v1, -v89, v169, v1
	ds_read_b128 v[166:169], v33 offset:48768
	s_waitcnt lgkmcnt(0)
	v_fma_f32 v0, -v90, v166, v0
	v_fma_f32 v1, -v91, v167, v1
	v_fma_f32 v0, -v92, v168, v0
	v_fma_f32 v1, -v93, v169, v1
	ds_read_b128 v[166:169], v33 offset:48784
	s_waitcnt lgkmcnt(0)
	v_fma_f32 v0, -v142, v166, v0
	v_fma_f32 v1, -v143, v167, v1
	v_fma_f32 v149, -v144, v168, v0
	v_fma_f32 v166, -v145, v169, v1
	ds_read_b96 v[0:2], v33 offset:48800
	s_waitcnt lgkmcnt(0)
	v_fma_f32 v1, -v147, v1, v166
	ds_read_b128 v[166:169], v33 offset:448
	v_fma_f32 v0, -v146, v0, v149
	v_fma_f32 v0, -v148, v2, v0
	v_add_f32_e32 v149, v1, v0
	ds_read_b32 v2, v33 offset:49360
	s_waitcnt lgkmcnt(1)
	v_mul_f32_e32 v0, v150, v166
	v_mul_f32_e32 v1, v0, v170
	v_cndmask_b32_e64 v0, v0, v1, s[8:9]
	v_fma_f32 v0, -v8, v174, v0
	v_fma_f32 v1, -v9, v175, 0
	v_fma_f32 v0, -v10, v176, v0
	v_fma_f32 v1, -v11, v177, v1
	ds_read_b128 v[174:177], v33 offset:48912
	s_waitcnt lgkmcnt(0)
	v_fma_f32 v0, -v12, v174, v0
	v_fma_f32 v1, -v13, v175, v1
	v_fma_f32 v0, -v14, v176, v0
	v_fma_f32 v1, -v15, v177, v1
	ds_read_b128 v[174:177], v33 offset:48928
	s_waitcnt lgkmcnt(0)
	v_fma_f32 v0, -v4, v174, v0
	v_fma_f32 v1, -v5, v175, v1
	v_fma_f32 v0, -v6, v176, v0
	v_fma_f32 v1, -v7, v177, v1
	ds_read_b128 v[174:177], v33 offset:48944
	s_waitcnt lgkmcnt(0)
	v_fma_f32 v0, -v16, v174, v0
	v_fma_f32 v1, -v17, v175, v1
	v_fma_f32 v0, -v18, v176, v0
	v_fma_f32 v1, -v3, v177, v1
	ds_read_b128 v[174:177], v33 offset:48960
	s_waitcnt lgkmcnt(0)
	v_fma_f32 v0, -v19, v174, v0
	v_fma_f32 v1, -v20, v175, v1
	v_fma_f32 v0, -v21, v176, v0
	v_fma_f32 v1, -v22, v177, v1
	ds_read_b128 v[174:177], v33 offset:48976
	s_waitcnt lgkmcnt(0)
	v_fma_f32 v0, -v23, v174, v0
	v_fma_f32 v1, -v24, v175, v1
	v_fma_f32 v0, -v25, v176, v0
	v_fma_f32 v1, -v26, v177, v1
	ds_read_b128 v[174:177], v33 offset:48992
	s_waitcnt lgkmcnt(0)
	v_fma_f32 v0, -v27, v174, v0
	v_fma_f32 v1, -v28, v175, v1
	v_fma_f32 v0, -v29, v176, v0
	v_fma_f32 v1, -v30, v177, v1
	ds_read_b128 v[174:177], v33 offset:49008
	s_waitcnt lgkmcnt(0)
	v_fma_f32 v0, -v31, v174, v0
	v_fma_f32 v1, -v77, v175, v1
	v_fma_f32 v0, -v79, v176, v0
	v_fma_f32 v1, -v81, v177, v1
	ds_read_b128 v[174:177], v33 offset:49024
	s_waitcnt lgkmcnt(0)
	v_fma_f32 v0, -v83, v174, v0
	v_fma_f32 v1, -v85, v175, v1
	v_fma_f32 v0, -v87, v176, v0
	v_fma_f32 v1, -v89, v177, v1
	ds_read_b128 v[174:177], v33 offset:49040
	s_waitcnt lgkmcnt(0)
	v_fma_f32 v0, -v90, v174, v0
	v_fma_f32 v1, -v91, v175, v1
	v_fma_f32 v0, -v92, v176, v0
	v_fma_f32 v1, -v93, v177, v1
	ds_read_b128 v[174:177], v33 offset:49056
	s_waitcnt lgkmcnt(0)
	v_fma_f32 v0, -v142, v174, v0
	v_fma_f32 v1, -v143, v175, v1
	v_fma_f32 v0, -v144, v176, v0
	v_fma_f32 v1, -v145, v177, v1
	ds_read_b128 v[174:177], v33 offset:49072
	s_waitcnt lgkmcnt(0)
	v_fma_f32 v0, -v146, v174, v0
	v_fma_f32 v1, -v147, v175, v1
	v_fma_f32 v0, -v148, v176, v0
	v_fma_f32 v1, -v149, v177, v1
	ds_read_b128 v[174:177], v33 offset:49168
	v_add_f32_e32 v150, v0, v1
	v_mul_f32_e32 v0, v151, v167
	v_mul_f32_e32 v1, v0, v171
	v_cndmask_b32_e64 v0, v0, v1, s[8:9]
	s_waitcnt lgkmcnt(0)
	v_fma_f32 v0, -v8, v174, v0
	v_fma_f32 v1, -v9, v175, 0
	v_fma_f32 v0, -v10, v176, v0
	v_fma_f32 v1, -v11, v177, v1
	ds_read_b128 v[174:177], v33 offset:49184
	s_waitcnt lgkmcnt(0)
	v_fma_f32 v0, -v12, v174, v0
	v_fma_f32 v1, -v13, v175, v1
	v_fma_f32 v0, -v14, v176, v0
	v_fma_f32 v1, -v15, v177, v1
	ds_read_b128 v[174:177], v33 offset:49200
	s_waitcnt lgkmcnt(0)
; DI void chunk_prep(const Params& p, int item, char* smem) {
;     ...
;   {
;     const int c = tid;
;     float sol[64];
; #pragma unroll
;     for (int i = 0; i < 64; ++i) {
;       float rhs = rraw[i] * betas[i];
;       if (c >= 128) rhs *= egs[i];
;       float acc = rhs, acc1 = 0.f;
; #pragma unroll
;       for (int j = 0; j < i; ++j) {
;         if (j & 1) acc1 -= Am[i * 68 + j] * sol[j];
;         else acc -= Am[i * 68 + j] * sol[j];
;       }
;       sol[i] = acc + acc1;
;     }
	v_fma_f32 v0, -v4, v174, v0
	v_fma_f32 v1, -v5, v175, v1
	v_fma_f32 v0, -v6, v176, v0
	v_fma_f32 v1, -v7, v177, v1
	ds_read_b128 v[174:177], v33 offset:49216
	s_waitcnt lgkmcnt(0)
	v_fma_f32 v0, -v16, v174, v0
	v_fma_f32 v1, -v17, v175, v1
	v_fma_f32 v0, -v18, v176, v0
	v_fma_f32 v1, -v3, v177, v1
	ds_read_b128 v[174:177], v33 offset:49232
	s_waitcnt lgkmcnt(0)
	v_fma_f32 v0, -v19, v174, v0
	v_fma_f32 v1, -v20, v175, v1
	v_fma_f32 v0, -v21, v176, v0
	v_fma_f32 v1, -v22, v177, v1
	ds_read_b128 v[174:177], v33 offset:49248
	s_waitcnt lgkmcnt(0)
	v_fma_f32 v0, -v23, v174, v0
	v_fma_f32 v1, -v24, v175, v1
	v_fma_f32 v0, -v25, v176, v0
	v_fma_f32 v1, -v26, v177, v1
	ds_read_b128 v[174:177], v33 offset:49264
	s_waitcnt lgkmcnt(0)
	v_fma_f32 v0, -v27, v174, v0
	v_fma_f32 v1, -v28, v175, v1
	v_fma_f32 v0, -v29, v176, v0
	v_fma_f32 v1, -v30, v177, v1
	ds_read_b128 v[174:177], v33 offset:49280
	s_waitcnt lgkmcnt(0)
	v_fma_f32 v0, -v31, v174, v0
	v_fma_f32 v1, -v77, v175, v1
	v_fma_f32 v0, -v79, v176, v0
	v_fma_f32 v1, -v81, v177, v1
	ds_read_b128 v[174:177], v33 offset:49296
	s_waitcnt lgkmcnt(0)
	v_fma_f32 v0, -v83, v174, v0
	v_fma_f32 v1, -v85, v175, v1
	v_fma_f32 v0, -v87, v176, v0
	v_fma_f32 v1, -v89, v177, v1
	ds_read_b128 v[174:177], v33 offset:49312
	s_waitcnt lgkmcnt(0)
	v_fma_f32 v0, -v90, v174, v0
	v_fma_f32 v1, -v91, v175, v1
	v_fma_f32 v0, -v92, v176, v0
	v_fma_f32 v1, -v93, v177, v1
	ds_read_b128 v[174:177], v33 offset:49328
	s_waitcnt lgkmcnt(0)
	v_fma_f32 v0, -v142, v174, v0
	v_fma_f32 v1, -v143, v175, v1
	v_fma_f32 v0, -v144, v176, v0
	v_fma_f32 v1, -v145, v177, v1
	ds_read_b128 v[174:177], v33 offset:49344
	s_waitcnt lgkmcnt(0)
	v_fma_f32 v0, -v146, v174, v0
	v_fma_f32 v1, -v147, v175, v1
	v_fma_f32 v0, -v148, v176, v0
	v_fma_f32 v1, -v149, v177, v1
	ds_read_b128 v[174:177], v33 offset:49440
	v_fma_f32 v0, -v150, v2, v0
	v_add_f32_e32 v151, v1, v0
	v_mul_f32_e32 v0, v152, v168
	v_mul_f32_e32 v1, v0, v172
	v_cndmask_b32_e64 v0, v0, v1, s[8:9]
	s_waitcnt lgkmcnt(0)
	v_fma_f32 v0, -v8, v174, v0
	v_fma_f32 v1, -v9, v175, 0
	v_fma_f32 v0, -v10, v176, v0
	v_fma_f32 v1, -v11, v177, v1
	ds_read_b128 v[174:177], v33 offset:49456
	s_waitcnt lgkmcnt(0)
	v_fma_f32 v0, -v12, v174, v0
	v_fma_f32 v1, -v13, v175, v1
	v_fma_f32 v0, -v14, v176, v0
	v_fma_f32 v1, -v15, v177, v1
	ds_read_b128 v[174:177], v33 offset:49472
	s_waitcnt lgkmcnt(0)
	v_fma_f32 v0, -v4, v174, v0
	v_fma_f32 v1, -v5, v175, v1
	v_fma_f32 v0, -v6, v176, v0
	v_fma_f32 v1, -v7, v177, v1
	ds_read_b128 v[174:177], v33 offset:49488
	s_waitcnt lgkmcnt(0)
	v_fma_f32 v0, -v16, v174, v0
	v_fma_f32 v1, -v17, v175, v1
	v_fma_f32 v0, -v18, v176, v0
	v_fma_f32 v1, -v3, v177, v1
	ds_read_b128 v[174:177], v33 offset:49504
	s_waitcnt lgkmcnt(0)
	v_fma_f32 v0, -v19, v174, v0
	v_fma_f32 v1, -v20, v175, v1
	v_fma_f32 v0, -v21, v176, v0
	v_fma_f32 v1, -v22, v177, v1
	ds_read_b128 v[174:177], v33 offset:49520
	s_waitcnt lgkmcnt(0)
	v_fma_f32 v0, -v23, v174, v0
	v_fma_f32 v1, -v24, v175, v1
	v_fma_f32 v0, -v25, v176, v0
	v_fma_f32 v1, -v26, v177, v1
	ds_read_b128 v[174:177], v33 offset:49536
	s_waitcnt lgkmcnt(0)
	v_fma_f32 v0, -v27, v174, v0
	v_fma_f32 v1, -v28, v175, v1
	v_fma_f32 v0, -v29, v176, v0
	v_fma_f32 v1, -v30, v177, v1
	ds_read_b128 v[174:177], v33 offset:49552
	s_waitcnt lgkmcnt(0)
	v_fma_f32 v0, -v31, v174, v0
	v_fma_f32 v1, -v77, v175, v1
	v_fma_f32 v0, -v79, v176, v0
	v_fma_f32 v1, -v81, v177, v1
	ds_read_b128 v[174:177], v33 offset:49568
	s_waitcnt lgkmcnt(0)
	v_fma_f32 v0, -v83, v174, v0
	v_fma_f32 v1, -v85, v175, v1
	v_fma_f32 v0, -v87, v176, v0
	v_fma_f32 v1, -v89, v177, v1
	ds_read_b128 v[174:177], v33 offset:49584
	s_waitcnt lgkmcnt(0)
	v_fma_f32 v0, -v90, v174, v0
	v_fma_f32 v1, -v91, v175, v1
	v_fma_f32 v0, -v92, v176, v0
	v_fma_f32 v1, -v93, v177, v1
	ds_read_b128 v[174:177], v33 offset:49600
	s_waitcnt lgkmcnt(0)
	v_fma_f32 v0, -v142, v174, v0
	v_fma_f32 v1, -v143, v175, v1
	v_fma_f32 v0, -v144, v176, v0
	v_fma_f32 v1, -v145, v177, v1
	ds_read_b128 v[174:177], v33 offset:49616
	s_waitcnt lgkmcnt(0)
	v_fma_f32 v0, -v146, v174, v0
	v_fma_f32 v1, -v147, v175, v1
	v_fma_f32 v2, -v148, v176, v0
	v_fma_f32 v152, -v149, v177, v1
	ds_read_b64 v[0:1], v33 offset:49632
	ds_read_b128 v[174:177], v33 offset:49984
	s_waitcnt lgkmcnt(1)
	v_fma_f32 v0, -v150, v0, v2
	v_fma_f32 v1, -v151, v1, v152
	v_add_f32_e32 v152, v0, v1
	v_mul_f32_e32 v0, v153, v169
	ds_read_b128 v[166:169], v33 offset:49712
	v_mul_f32_e32 v1, v0, v173
	v_cndmask_b32_e64 v0, v0, v1, s[8:9]
	ds_read_b128 v[170:173], v33 offset:720
	s_waitcnt lgkmcnt(1)
	v_fma_f32 v0, -v8, v166, v0
	v_fma_f32 v1, -v9, v167, 0
	v_fma_f32 v0, -v10, v168, v0
	v_fma_f32 v1, -v11, v169, v1
	ds_read_b128 v[166:169], v33 offset:49728
	s_waitcnt lgkmcnt(0)
	v_fma_f32 v0, -v12, v166, v0
	v_fma_f32 v1, -v13, v167, v1
	v_fma_f32 v0, -v14, v168, v0
	v_fma_f32 v1, -v15, v169, v1
	ds_read_b128 v[166:169], v33 offset:49744
	s_waitcnt lgkmcnt(0)
	v_fma_f32 v0, -v4, v166, v0
	v_fma_f32 v1, -v5, v167, v1
	v_fma_f32 v0, -v6, v168, v0
	v_fma_f32 v1, -v7, v169, v1
	ds_read_b128 v[166:169], v33 offset:49760
	s_waitcnt lgkmcnt(0)
	v_fma_f32 v0, -v16, v166, v0
	v_fma_f32 v1, -v17, v167, v1
	v_fma_f32 v0, -v18, v168, v0
	v_fma_f32 v1, -v3, v169, v1
	ds_read_b128 v[166:169], v33 offset:49776
	s_waitcnt lgkmcnt(0)
	v_fma_f32 v0, -v19, v166, v0
	v_fma_f32 v1, -v20, v167, v1
	v_fma_f32 v0, -v21, v168, v0
	v_fma_f32 v1, -v22, v169, v1
	ds_read_b128 v[166:169], v33 offset:49792
	s_waitcnt lgkmcnt(0)
	v_fma_f32 v0, -v23, v166, v0
	v_fma_f32 v1, -v24, v167, v1
	v_fma_f32 v0, -v25, v168, v0
	v_fma_f32 v1, -v26, v169, v1
	ds_read_b128 v[166:169], v33 offset:49808
	s_waitcnt lgkmcnt(0)
; DI void chunk_prep(const Params& p, int item, char* smem) {
;     ...
;   {
;     const int c = tid;
;     float sol[64];
; #pragma unroll
;     for (int i = 0; i < 64; ++i) {
;       float rhs = rraw[i] * betas[i];
;       if (c >= 128) rhs *= egs[i];
;       float acc = rhs, acc1 = 0.f;
; #pragma unroll
;       for (int j = 0; j < i; ++j) {
;         if (j & 1) acc1 -= Am[i * 68 + j] * sol[j];
;         else acc -= Am[i * 68 + j] * sol[j];
;       }
;       sol[i] = acc + acc1;
;     }
	v_fma_f32 v0, -v27, v166, v0
	v_fma_f32 v1, -v28, v167, v1
	v_fma_f32 v0, -v29, v168, v0
	v_fma_f32 v1, -v30, v169, v1
	ds_read_b128 v[166:169], v33 offset:49824
	s_waitcnt lgkmcnt(0)
	v_fma_f32 v0, -v31, v166, v0
	v_fma_f32 v1, -v77, v167, v1
	v_fma_f32 v0, -v79, v168, v0
	v_fma_f32 v1, -v81, v169, v1
	ds_read_b128 v[166:169], v33 offset:49840
	s_waitcnt lgkmcnt(0)
	v_fma_f32 v0, -v83, v166, v0
	v_fma_f32 v1, -v85, v167, v1
	v_fma_f32 v0, -v87, v168, v0
	v_fma_f32 v1, -v89, v169, v1
	ds_read_b128 v[166:169], v33 offset:49856
	s_waitcnt lgkmcnt(0)
	v_fma_f32 v0, -v90, v166, v0
	v_fma_f32 v1, -v91, v167, v1
	v_fma_f32 v0, -v92, v168, v0
	v_fma_f32 v1, -v93, v169, v1
	ds_read_b128 v[166:169], v33 offset:49872
	s_waitcnt lgkmcnt(0)
	v_fma_f32 v0, -v142, v166, v0
	v_fma_f32 v1, -v143, v167, v1
	v_fma_f32 v0, -v144, v168, v0
	v_fma_f32 v1, -v145, v169, v1
	ds_read_b128 v[166:169], v33 offset:49888
	s_waitcnt lgkmcnt(0)
	v_fma_f32 v0, -v146, v166, v0
	v_fma_f32 v1, -v147, v167, v1
	v_fma_f32 v153, -v148, v168, v0
	v_fma_f32 v166, -v149, v169, v1
	ds_read_b96 v[0:2], v33 offset:49904
	s_waitcnt lgkmcnt(0)
	v_fma_f32 v1, -v151, v1, v166
	ds_read_b128 v[166:169], v33 offset:464
	v_fma_f32 v0, -v150, v0, v153
	v_fma_f32 v0, -v152, v2, v0
	v_add_f32_e32 v153, v1, v0
	ds_read_b32 v2, v33 offset:50464
	s_waitcnt lgkmcnt(1)
	v_mul_f32_e32 v0, v154, v166
	v_mul_f32_e32 v1, v0, v170
	v_cndmask_b32_e64 v0, v0, v1, s[8:9]
	v_fma_f32 v0, -v8, v174, v0
	v_fma_f32 v1, -v9, v175, 0
	v_fma_f32 v0, -v10, v176, v0
	v_fma_f32 v1, -v11, v177, v1
	ds_read_b128 v[174:177], v33 offset:50000
	s_waitcnt lgkmcnt(0)
	v_fma_f32 v0, -v12, v174, v0
	v_fma_f32 v1, -v13, v175, v1
	v_fma_f32 v0, -v14, v176, v0
	v_fma_f32 v1, -v15, v177, v1
	ds_read_b128 v[174:177], v33 offset:50016
	s_waitcnt lgkmcnt(0)
	v_fma_f32 v0, -v4, v174, v0
	v_fma_f32 v1, -v5, v175, v1
	v_fma_f32 v0, -v6, v176, v0
	v_fma_f32 v1, -v7, v177, v1
	ds_read_b128 v[174:177], v33 offset:50032
	s_waitcnt lgkmcnt(0)
	v_fma_f32 v0, -v16, v174, v0
	v_fma_f32 v1, -v17, v175, v1
	v_fma_f32 v0, -v18, v176, v0
	v_fma_f32 v1, -v3, v177, v1
	ds_read_b128 v[174:177], v33 offset:50048
	s_waitcnt lgkmcnt(0)
	v_fma_f32 v0, -v19, v174, v0
	v_fma_f32 v1, -v20, v175, v1
	v_fma_f32 v0, -v21, v176, v0
	v_fma_f32 v1, -v22, v177, v1
	ds_read_b128 v[174:177], v33 offset:50064
	s_waitcnt lgkmcnt(0)
	v_fma_f32 v0, -v23, v174, v0
	v_fma_f32 v1, -v24, v175, v1
	v_fma_f32 v0, -v25, v176, v0
	v_fma_f32 v1, -v26, v177, v1
	ds_read_b128 v[174:177], v33 offset:50080
	s_waitcnt lgkmcnt(0)
	v_fma_f32 v0, -v27, v174, v0
	v_fma_f32 v1, -v28, v175, v1
	v_fma_f32 v0, -v29, v176, v0
	v_fma_f32 v1, -v30, v177, v1
	ds_read_b128 v[174:177], v33 offset:50096
	s_waitcnt lgkmcnt(0)
	v_fma_f32 v0, -v31, v174, v0
	v_fma_f32 v1, -v77, v175, v1
	v_fma_f32 v0, -v79, v176, v0
	v_fma_f32 v1, -v81, v177, v1
	ds_read_b128 v[174:177], v33 offset:50112
	s_waitcnt lgkmcnt(0)
	v_fma_f32 v0, -v83, v174, v0
	v_fma_f32 v1, -v85, v175, v1
	v_fma_f32 v0, -v87, v176, v0
	v_fma_f32 v1, -v89, v177, v1
	ds_read_b128 v[174:177], v33 offset:50128
	s_waitcnt lgkmcnt(0)
	v_fma_f32 v0, -v90, v174, v0
	v_fma_f32 v1, -v91, v175, v1
	v_fma_f32 v0, -v92, v176, v0
	v_fma_f32 v1, -v93, v177, v1
	ds_read_b128 v[174:177], v33 offset:50144
	s_waitcnt lgkmcnt(0)
	v_fma_f32 v0, -v142, v174, v0
	v_fma_f32 v1, -v143, v175, v1
	v_fma_f32 v0, -v144, v176, v0
	v_fma_f32 v1, -v145, v177, v1
	ds_read_b128 v[174:177], v33 offset:50160
	s_waitcnt lgkmcnt(0)
	v_fma_f32 v0, -v146, v174, v0
	v_fma_f32 v1, -v147, v175, v1
	v_fma_f32 v0, -v148, v176, v0
	v_fma_f32 v1, -v149, v177, v1
	ds_read_b128 v[174:177], v33 offset:50176
	s_waitcnt lgkmcnt(0)
	v_fma_f32 v0, -v150, v174, v0
	v_fma_f32 v1, -v151, v175, v1
	v_fma_f32 v0, -v152, v176, v0
	v_fma_f32 v1, -v153, v177, v1
	ds_read_b128 v[174:177], v33 offset:50256
	v_add_f32_e32 v154, v0, v1
	v_mul_f32_e32 v0, v155, v167
	v_mul_f32_e32 v1, v0, v171
	v_cndmask_b32_e64 v0, v0, v1, s[8:9]
	s_waitcnt lgkmcnt(0)
	v_fma_f32 v0, -v8, v174, v0
	v_fma_f32 v1, -v9, v175, 0
	v_fma_f32 v0, -v10, v176, v0
	v_fma_f32 v1, -v11, v177, v1
	ds_read_b128 v[174:177], v33 offset:50272
	s_waitcnt lgkmcnt(0)
	v_fma_f32 v0, -v12, v174, v0
	v_fma_f32 v1, -v13, v175, v1
	v_fma_f32 v0, -v14, v176, v0
	v_fma_f32 v1, -v15, v177, v1
	ds_read_b128 v[174:177], v33 offset:50288
	s_waitcnt lgkmcnt(0)
	v_fma_f32 v0, -v4, v174, v0
	v_fma_f32 v1, -v5, v175, v1
	v_fma_f32 v0, -v6, v176, v0
	v_fma_f32 v1, -v7, v177, v1
	ds_read_b128 v[174:177], v33 offset:50304
	s_waitcnt lgkmcnt(0)
	v_fma_f32 v0, -v16, v174, v0
	v_fma_f32 v1, -v17, v175, v1
	v_fma_f32 v0, -v18, v176, v0
	v_fma_f32 v1, -v3, v177, v1
	ds_read_b128 v[174:177], v33 offset:50320
	s_waitcnt lgkmcnt(0)
	v_fma_f32 v0, -v19, v174, v0
	v_fma_f32 v1, -v20, v175, v1
	v_fma_f32 v0, -v21, v176, v0
	v_fma_f32 v1, -v22, v177, v1
	ds_read_b128 v[174:177], v33 offset:50336
	s_waitcnt lgkmcnt(0)
	v_fma_f32 v0, -v23, v174, v0
	v_fma_f32 v1, -v24, v175, v1
	v_fma_f32 v0, -v25, v176, v0
	v_fma_f32 v1, -v26, v177, v1
	ds_read_b128 v[174:177], v33 offset:50352
	s_waitcnt lgkmcnt(0)
	v_fma_f32 v0, -v27, v174, v0
	v_fma_f32 v1, -v28, v175, v1
	v_fma_f32 v0, -v29, v176, v0
	v_fma_f32 v1, -v30, v177, v1
	ds_read_b128 v[174:177], v33 offset:50368
	s_waitcnt lgkmcnt(0)
	v_fma_f32 v0, -v31, v174, v0
	v_fma_f32 v1, -v77, v175, v1
	v_fma_f32 v0, -v79, v176, v0
	v_fma_f32 v1, -v81, v177, v1
	ds_read_b128 v[174:177], v33 offset:50384
	s_waitcnt lgkmcnt(0)
	v_fma_f32 v0, -v83, v174, v0
	v_fma_f32 v1, -v85, v175, v1
	v_fma_f32 v0, -v87, v176, v0
	v_fma_f32 v1, -v89, v177, v1
	ds_read_b128 v[174:177], v33 offset:50400
	s_waitcnt lgkmcnt(0)
; DI void chunk_prep(const Params& p, int item, char* smem) {
;     ...
;   {
;     const int c = tid;
;     float sol[64];
; #pragma unroll
;     for (int i = 0; i < 64; ++i) {
;       float rhs = rraw[i] * betas[i];
;       if (c >= 128) rhs *= egs[i];
;       float acc = rhs, acc1 = 0.f;
; #pragma unroll
;       for (int j = 0; j < i; ++j) {
;         if (j & 1) acc1 -= Am[i * 68 + j] * sol[j];
;         else acc -= Am[i * 68 + j] * sol[j];
;       }
;       sol[i] = acc + acc1;
;     }
	v_fma_f32 v0, -v90, v174, v0
	v_fma_f32 v1, -v91, v175, v1
	v_fma_f32 v0, -v92, v176, v0
	v_fma_f32 v1, -v93, v177, v1
	ds_read_b128 v[174:177], v33 offset:50416
	s_waitcnt lgkmcnt(0)
	v_fma_f32 v0, -v142, v174, v0
	v_fma_f32 v1, -v143, v175, v1
	v_fma_f32 v0, -v144, v176, v0
	v_fma_f32 v1, -v145, v177, v1
	ds_read_b128 v[174:177], v33 offset:50432
	s_waitcnt lgkmcnt(0)
	v_fma_f32 v0, -v146, v174, v0
	v_fma_f32 v1, -v147, v175, v1
	v_fma_f32 v0, -v148, v176, v0
	v_fma_f32 v1, -v149, v177, v1
	ds_read_b128 v[174:177], v33 offset:50448
	s_waitcnt lgkmcnt(0)
	v_fma_f32 v0, -v150, v174, v0
	v_fma_f32 v1, -v151, v175, v1
	v_fma_f32 v0, -v152, v176, v0
	v_fma_f32 v1, -v153, v177, v1
	ds_read_b128 v[174:177], v33 offset:50528
	v_fma_f32 v0, -v154, v2, v0
	v_add_f32_e32 v155, v1, v0
	v_mul_f32_e32 v0, v156, v168
	v_mul_f32_e32 v1, v0, v172
	v_cndmask_b32_e64 v0, v0, v1, s[8:9]
	s_waitcnt lgkmcnt(0)
	v_fma_f32 v0, -v8, v174, v0
	v_fma_f32 v1, -v9, v175, 0
	v_fma_f32 v0, -v10, v176, v0
	v_fma_f32 v1, -v11, v177, v1
	ds_read_b128 v[174:177], v33 offset:50544
	s_waitcnt lgkmcnt(0)
	v_fma_f32 v0, -v12, v174, v0
	v_fma_f32 v1, -v13, v175, v1
	v_fma_f32 v0, -v14, v176, v0
	v_fma_f32 v1, -v15, v177, v1
	ds_read_b128 v[174:177], v33 offset:50560
	s_waitcnt lgkmcnt(0)
	v_fma_f32 v0, -v4, v174, v0
	v_fma_f32 v1, -v5, v175, v1
	v_fma_f32 v0, -v6, v176, v0
	v_fma_f32 v1, -v7, v177, v1
	ds_read_b128 v[174:177], v33 offset:50576
	s_waitcnt lgkmcnt(0)
	v_fma_f32 v0, -v16, v174, v0
	v_fma_f32 v1, -v17, v175, v1
	v_fma_f32 v0, -v18, v176, v0
	v_fma_f32 v1, -v3, v177, v1
	ds_read_b128 v[174:177], v33 offset:50592
	s_waitcnt lgkmcnt(0)
	v_fma_f32 v0, -v19, v174, v0
	v_fma_f32 v1, -v20, v175, v1
	v_fma_f32 v0, -v21, v176, v0
	v_fma_f32 v1, -v22, v177, v1
	ds_read_b128 v[174:177], v33 offset:50608
	s_waitcnt lgkmcnt(0)
	v_fma_f32 v0, -v23, v174, v0
	v_fma_f32 v1, -v24, v175, v1
	v_fma_f32 v0, -v25, v176, v0
	v_fma_f32 v1, -v26, v177, v1
	ds_read_b128 v[174:177], v33 offset:50624
	s_waitcnt lgkmcnt(0)
	v_fma_f32 v0, -v27, v174, v0
	v_fma_f32 v1, -v28, v175, v1
	v_fma_f32 v0, -v29, v176, v0
	v_fma_f32 v1, -v30, v177, v1
	ds_read_b128 v[174:177], v33 offset:50640
	s_waitcnt lgkmcnt(0)
	v_fma_f32 v0, -v31, v174, v0
	v_fma_f32 v1, -v77, v175, v1
	v_fma_f32 v0, -v79, v176, v0
	v_fma_f32 v1, -v81, v177, v1
	ds_read_b128 v[174:177], v33 offset:50656
	s_waitcnt lgkmcnt(0)
	v_fma_f32 v0, -v83, v174, v0
	v_fma_f32 v1, -v85, v175, v1
	v_fma_f32 v0, -v87, v176, v0
	v_fma_f32 v1, -v89, v177, v1
	ds_read_b128 v[174:177], v33 offset:50672
	s_waitcnt lgkmcnt(0)
	v_fma_f32 v0, -v90, v174, v0
	v_fma_f32 v1, -v91, v175, v1
	v_fma_f32 v0, -v92, v176, v0
	v_fma_f32 v1, -v93, v177, v1
	ds_read_b128 v[174:177], v33 offset:50688
	s_waitcnt lgkmcnt(0)
	v_fma_f32 v0, -v142, v174, v0
	v_fma_f32 v1, -v143, v175, v1
	v_fma_f32 v0, -v144, v176, v0
	v_fma_f32 v1, -v145, v177, v1
	ds_read_b128 v[174:177], v33 offset:50704
	s_waitcnt lgkmcnt(0)
	v_fma_f32 v0, -v146, v174, v0
	v_fma_f32 v1, -v147, v175, v1
	v_fma_f32 v0, -v148, v176, v0
	v_fma_f32 v1, -v149, v177, v1
	ds_read_b128 v[174:177], v33 offset:50720
	s_waitcnt lgkmcnt(0)
	v_fma_f32 v0, -v150, v174, v0
	v_fma_f32 v1, -v151, v175, v1
	v_fma_f32 v2, -v152, v176, v0
	v_fma_f32 v156, -v153, v177, v1
	ds_read_b64 v[0:1], v33 offset:50736
	ds_read_b128 v[174:177], v33 offset:51072
	s_waitcnt lgkmcnt(1)
	v_fma_f32 v0, -v154, v0, v2
	v_fma_f32 v1, -v155, v1, v156
	v_add_f32_e32 v156, v0, v1
	v_mul_f32_e32 v0, v157, v169
	ds_read_b128 v[166:169], v33 offset:50800
	v_mul_f32_e32 v1, v0, v173
	v_cndmask_b32_e64 v0, v0, v1, s[8:9]
	ds_read_b128 v[170:173], v33 offset:736
	s_waitcnt lgkmcnt(1)
	v_fma_f32 v0, -v8, v166, v0
	v_fma_f32 v1, -v9, v167, 0
	v_fma_f32 v0, -v10, v168, v0
	v_fma_f32 v1, -v11, v169, v1
	ds_read_b128 v[166:169], v33 offset:50816
	s_waitcnt lgkmcnt(0)
	v_fma_f32 v0, -v12, v166, v0
	v_fma_f32 v1, -v13, v167, v1
	v_fma_f32 v0, -v14, v168, v0
	v_fma_f32 v1, -v15, v169, v1
	ds_read_b128 v[166:169], v33 offset:50832
	s_waitcnt lgkmcnt(0)
	v_fma_f32 v0, -v4, v166, v0
	v_fma_f32 v1, -v5, v167, v1
	v_fma_f32 v0, -v6, v168, v0
	v_fma_f32 v1, -v7, v169, v1
	ds_read_b128 v[166:169], v33 offset:50848
	s_waitcnt lgkmcnt(0)
	v_fma_f32 v0, -v16, v166, v0
	v_fma_f32 v1, -v17, v167, v1
	v_fma_f32 v0, -v18, v168, v0
	v_fma_f32 v1, -v3, v169, v1
	ds_read_b128 v[166:169], v33 offset:50864
	s_waitcnt lgkmcnt(0)
	v_fma_f32 v0, -v19, v166, v0
	v_fma_f32 v1, -v20, v167, v1
	v_fma_f32 v0, -v21, v168, v0
	v_fma_f32 v1, -v22, v169, v1
	ds_read_b128 v[166:169], v33 offset:50880
	s_waitcnt lgkmcnt(0)
	v_fma_f32 v0, -v23, v166, v0
	v_fma_f32 v1, -v24, v167, v1
	v_fma_f32 v0, -v25, v168, v0
	v_fma_f32 v1, -v26, v169, v1
	ds_read_b128 v[166:169], v33 offset:50896
	s_waitcnt lgkmcnt(0)
	v_fma_f32 v0, -v27, v166, v0
	v_fma_f32 v1, -v28, v167, v1
	v_fma_f32 v0, -v29, v168, v0
	v_fma_f32 v1, -v30, v169, v1
	ds_read_b128 v[166:169], v33 offset:50912
	s_waitcnt lgkmcnt(0)
	v_fma_f32 v0, -v31, v166, v0
	v_fma_f32 v1, -v77, v167, v1
	v_fma_f32 v0, -v79, v168, v0
	v_fma_f32 v1, -v81, v169, v1
	ds_read_b128 v[166:169], v33 offset:50928
	s_waitcnt lgkmcnt(0)
	v_fma_f32 v0, -v83, v166, v0
	v_fma_f32 v1, -v85, v167, v1
	v_fma_f32 v0, -v87, v168, v0
	v_fma_f32 v1, -v89, v169, v1
	ds_read_b128 v[166:169], v33 offset:50944
	s_waitcnt lgkmcnt(0)
	v_fma_f32 v0, -v90, v166, v0
	v_fma_f32 v1, -v91, v167, v1
	v_fma_f32 v0, -v92, v168, v0
	v_fma_f32 v1, -v93, v169, v1
	ds_read_b128 v[166:169], v33 offset:50960
	s_waitcnt lgkmcnt(0)
	v_fma_f32 v0, -v142, v166, v0
	v_fma_f32 v1, -v143, v167, v1
	v_fma_f32 v0, -v144, v168, v0
	v_fma_f32 v1, -v145, v169, v1
	ds_read_b128 v[166:169], v33 offset:50976
	s_waitcnt lgkmcnt(0)
; DI void chunk_prep(const Params& p, int item, char* smem) {
;     ...
;   {
;     const int c = tid;
;     float sol[64];
; #pragma unroll
;     for (int i = 0; i < 64; ++i) {
;       float rhs = rraw[i] * betas[i];
;       if (c >= 128) rhs *= egs[i];
;       float acc = rhs, acc1 = 0.f;
; #pragma unroll
;       for (int j = 0; j < i; ++j) {
;         if (j & 1) acc1 -= Am[i * 68 + j] * sol[j];
;         else acc -= Am[i * 68 + j] * sol[j];
;       }
;       sol[i] = acc + acc1;
;     }
	v_fma_f32 v0, -v146, v166, v0
	v_fma_f32 v1, -v147, v167, v1
	v_fma_f32 v0, -v148, v168, v0
	v_fma_f32 v1, -v149, v169, v1
	ds_read_b128 v[166:169], v33 offset:50992
	s_waitcnt lgkmcnt(0)
	v_fma_f32 v0, -v150, v166, v0
	v_fma_f32 v1, -v151, v167, v1
	v_fma_f32 v157, -v152, v168, v0
	v_fma_f32 v166, -v153, v169, v1
	ds_read_b96 v[0:2], v33 offset:51008
	s_waitcnt lgkmcnt(0)
	v_fma_f32 v1, -v155, v1, v166
	ds_read_b128 v[166:169], v33 offset:480
	v_fma_f32 v0, -v154, v0, v157
	v_fma_f32 v0, -v156, v2, v0
	v_add_f32_e32 v157, v1, v0
	ds_read_b32 v2, v33 offset:51568
	s_waitcnt lgkmcnt(1)
	v_mul_f32_e32 v0, v158, v166
	v_mul_f32_e32 v1, v0, v170
	v_cndmask_b32_e64 v0, v0, v1, s[8:9]
	v_fma_f32 v0, -v8, v174, v0
	v_fma_f32 v1, -v9, v175, 0
	v_fma_f32 v0, -v10, v176, v0
	v_fma_f32 v1, -v11, v177, v1
	ds_read_b128 v[174:177], v33 offset:51088
	s_waitcnt lgkmcnt(0)
	v_fma_f32 v0, -v12, v174, v0
	v_fma_f32 v1, -v13, v175, v1
	v_fma_f32 v0, -v14, v176, v0
	v_fma_f32 v1, -v15, v177, v1
	ds_read_b128 v[174:177], v33 offset:51104
	s_waitcnt lgkmcnt(0)
	v_fma_f32 v0, -v4, v174, v0
	v_fma_f32 v1, -v5, v175, v1
	v_fma_f32 v0, -v6, v176, v0
	v_fma_f32 v1, -v7, v177, v1
	ds_read_b128 v[174:177], v33 offset:51120
	s_waitcnt lgkmcnt(0)
	v_fma_f32 v0, -v16, v174, v0
	v_fma_f32 v1, -v17, v175, v1
	v_fma_f32 v0, -v18, v176, v0
	v_fma_f32 v1, -v3, v177, v1
	ds_read_b128 v[174:177], v33 offset:51136
	s_waitcnt lgkmcnt(0)
	v_fma_f32 v0, -v19, v174, v0
	v_fma_f32 v1, -v20, v175, v1
	v_fma_f32 v0, -v21, v176, v0
	v_fma_f32 v1, -v22, v177, v1
	ds_read_b128 v[174:177], v33 offset:51152
	s_waitcnt lgkmcnt(0)
	v_fma_f32 v0, -v23, v174, v0
	v_fma_f32 v1, -v24, v175, v1
	v_fma_f32 v0, -v25, v176, v0
	v_fma_f32 v1, -v26, v177, v1
	ds_read_b128 v[174:177], v33 offset:51168
	s_waitcnt lgkmcnt(0)
	v_fma_f32 v0, -v27, v174, v0
	v_fma_f32 v1, -v28, v175, v1
	v_fma_f32 v0, -v29, v176, v0
	v_fma_f32 v1, -v30, v177, v1
	ds_read_b128 v[174:177], v33 offset:51184
	s_waitcnt lgkmcnt(0)
	v_fma_f32 v0, -v31, v174, v0
	v_fma_f32 v1, -v77, v175, v1
	v_fma_f32 v0, -v79, v176, v0
	v_fma_f32 v1, -v81, v177, v1
	ds_read_b128 v[174:177], v33 offset:51200
	s_waitcnt lgkmcnt(0)
	v_fma_f32 v0, -v83, v174, v0
	v_fma_f32 v1, -v85, v175, v1
	v_fma_f32 v0, -v87, v176, v0
	v_fma_f32 v1, -v89, v177, v1
	ds_read_b128 v[174:177], v33 offset:51216
	s_waitcnt lgkmcnt(0)
	v_fma_f32 v0, -v90, v174, v0
	v_fma_f32 v1, -v91, v175, v1
	v_fma_f32 v0, -v92, v176, v0
	v_fma_f32 v1, -v93, v177, v1
	ds_read_b128 v[174:177], v33 offset:51232
	s_waitcnt lgkmcnt(0)
	v_fma_f32 v0, -v142, v174, v0
	v_fma_f32 v1, -v143, v175, v1
	v_fma_f32 v0, -v144, v176, v0
	v_fma_f32 v1, -v145, v177, v1
	ds_read_b128 v[174:177], v33 offset:51248
	s_waitcnt lgkmcnt(0)
	v_fma_f32 v0, -v146, v174, v0
	v_fma_f32 v1, -v147, v175, v1
	v_fma_f32 v0, -v148, v176, v0
	v_fma_f32 v1, -v149, v177, v1
	ds_read_b128 v[174:177], v33 offset:51264
	s_waitcnt lgkmcnt(0)
	v_fma_f32 v0, -v150, v174, v0
	v_fma_f32 v1, -v151, v175, v1
	v_fma_f32 v0, -v152, v176, v0
	v_fma_f32 v1, -v153, v177, v1
	ds_read_b128 v[174:177], v33 offset:51280
	s_waitcnt lgkmcnt(0)
	v_fma_f32 v0, -v154, v174, v0
	v_fma_f32 v1, -v155, v175, v1
	v_fma_f32 v0, -v156, v176, v0
	v_fma_f32 v1, -v157, v177, v1
	ds_read_b128 v[174:177], v33 offset:51344
	v_add_f32_e32 v158, v0, v1
	v_mul_f32_e32 v0, v159, v167
	v_mul_f32_e32 v1, v0, v171
	v_cndmask_b32_e64 v0, v0, v1, s[8:9]
	s_waitcnt lgkmcnt(0)
	v_fma_f32 v0, -v8, v174, v0
	v_fma_f32 v1, -v9, v175, 0
	v_fma_f32 v0, -v10, v176, v0
	v_fma_f32 v1, -v11, v177, v1
	ds_read_b128 v[174:177], v33 offset:51360
	s_waitcnt lgkmcnt(0)
	v_fma_f32 v0, -v12, v174, v0
	v_fma_f32 v1, -v13, v175, v1
	v_fma_f32 v0, -v14, v176, v0
	v_fma_f32 v1, -v15, v177, v1
	ds_read_b128 v[174:177], v33 offset:51376
	s_waitcnt lgkmcnt(0)
	v_fma_f32 v0, -v4, v174, v0
	v_fma_f32 v1, -v5, v175, v1
	v_fma_f32 v0, -v6, v176, v0
	v_fma_f32 v1, -v7, v177, v1
	ds_read_b128 v[174:177], v33 offset:51392
	s_waitcnt lgkmcnt(0)
	v_fma_f32 v0, -v16, v174, v0
	v_fma_f32 v1, -v17, v175, v1
	v_fma_f32 v0, -v18, v176, v0
	v_fma_f32 v1, -v3, v177, v1
	ds_read_b128 v[174:177], v33 offset:51408
	s_waitcnt lgkmcnt(0)
	v_fma_f32 v0, -v19, v174, v0
	v_fma_f32 v1, -v20, v175, v1
	v_fma_f32 v0, -v21, v176, v0
	v_fma_f32 v1, -v22, v177, v1
	ds_read_b128 v[174:177], v33 offset:51424
	s_waitcnt lgkmcnt(0)
	v_fma_f32 v0, -v23, v174, v0
	v_fma_f32 v1, -v24, v175, v1
	v_fma_f32 v0, -v25, v176, v0
	v_fma_f32 v1, -v26, v177, v1
	ds_read_b128 v[174:177], v33 offset:51440
	s_waitcnt lgkmcnt(0)
	v_fma_f32 v0, -v27, v174, v0
	v_fma_f32 v1, -v28, v175, v1
	v_fma_f32 v0, -v29, v176, v0
	v_fma_f32 v1, -v30, v177, v1
	ds_read_b128 v[174:177], v33 offset:51456
	s_waitcnt lgkmcnt(0)
	v_fma_f32 v0, -v31, v174, v0
	v_fma_f32 v1, -v77, v175, v1
	v_fma_f32 v0, -v79, v176, v0
	v_fma_f32 v1, -v81, v177, v1
	ds_read_b128 v[174:177], v33 offset:51472
	s_waitcnt lgkmcnt(0)
	v_fma_f32 v0, -v83, v174, v0
	v_fma_f32 v1, -v85, v175, v1
	v_fma_f32 v0, -v87, v176, v0
	v_fma_f32 v1, -v89, v177, v1
	ds_read_b128 v[174:177], v33 offset:51488
	s_waitcnt lgkmcnt(0)
	v_fma_f32 v0, -v90, v174, v0
	v_fma_f32 v1, -v91, v175, v1
	v_fma_f32 v0, -v92, v176, v0
	v_fma_f32 v1, -v93, v177, v1
	ds_read_b128 v[174:177], v33 offset:51504
	s_waitcnt lgkmcnt(0)
	v_fma_f32 v0, -v142, v174, v0
	v_fma_f32 v1, -v143, v175, v1
	v_fma_f32 v0, -v144, v176, v0
	v_fma_f32 v1, -v145, v177, v1
	ds_read_b128 v[174:177], v33 offset:51520
	s_waitcnt lgkmcnt(0)
	v_fma_f32 v0, -v146, v174, v0
	v_fma_f32 v1, -v147, v175, v1
	v_fma_f32 v0, -v148, v176, v0
	v_fma_f32 v1, -v149, v177, v1
	ds_read_b128 v[174:177], v33 offset:51536
	s_waitcnt lgkmcnt(0)
; DI void chunk_prep(const Params& p, int item, char* smem) {
;     ...
;   {
;     const int c = tid;
;     float sol[64];
; #pragma unroll
;     for (int i = 0; i < 64; ++i) {
;       float rhs = rraw[i] * betas[i];
;       if (c >= 128) rhs *= egs[i];
;       float acc = rhs, acc1 = 0.f;
; #pragma unroll
;       for (int j = 0; j < i; ++j) {
;         if (j & 1) acc1 -= Am[i * 68 + j] * sol[j];
;         else acc -= Am[i * 68 + j] * sol[j];
;       }
;       sol[i] = acc + acc1;
;     }
	v_fma_f32 v0, -v150, v174, v0
	v_fma_f32 v1, -v151, v175, v1
	v_fma_f32 v0, -v152, v176, v0
	v_fma_f32 v1, -v153, v177, v1
	ds_read_b128 v[174:177], v33 offset:51552
	s_waitcnt lgkmcnt(0)
	v_fma_f32 v0, -v154, v174, v0
	v_fma_f32 v1, -v155, v175, v1
	v_fma_f32 v0, -v156, v176, v0
	v_fma_f32 v1, -v157, v177, v1
	ds_read_b128 v[174:177], v33 offset:51616
	v_fma_f32 v0, -v158, v2, v0
	v_add_f32_e32 v159, v1, v0
	v_mul_f32_e32 v0, v160, v168
	v_mul_f32_e32 v1, v0, v172
	v_cndmask_b32_e64 v0, v0, v1, s[8:9]
	s_waitcnt lgkmcnt(0)
	v_fma_f32 v0, -v8, v174, v0
	v_fma_f32 v1, -v9, v175, 0
	v_fma_f32 v0, -v10, v176, v0
	v_fma_f32 v1, -v11, v177, v1
	ds_read_b128 v[174:177], v33 offset:51632
	s_waitcnt lgkmcnt(0)
	v_fma_f32 v0, -v12, v174, v0
	v_fma_f32 v1, -v13, v175, v1
	v_fma_f32 v0, -v14, v176, v0
	v_fma_f32 v1, -v15, v177, v1
	ds_read_b128 v[174:177], v33 offset:51648
	s_waitcnt lgkmcnt(0)
	v_fma_f32 v0, -v4, v174, v0
	v_fma_f32 v1, -v5, v175, v1
	v_fma_f32 v0, -v6, v176, v0
	v_fma_f32 v1, -v7, v177, v1
	ds_read_b128 v[174:177], v33 offset:51664
	s_waitcnt lgkmcnt(0)
	v_fma_f32 v0, -v16, v174, v0
	v_fma_f32 v1, -v17, v175, v1
	v_fma_f32 v0, -v18, v176, v0
	v_fma_f32 v1, -v3, v177, v1
	ds_read_b128 v[174:177], v33 offset:51680
	s_waitcnt lgkmcnt(0)
	v_fma_f32 v0, -v19, v174, v0
	v_fma_f32 v1, -v20, v175, v1
	v_fma_f32 v0, -v21, v176, v0
	v_fma_f32 v1, -v22, v177, v1
	ds_read_b128 v[174:177], v33 offset:51696
	s_waitcnt lgkmcnt(0)
	v_fma_f32 v0, -v23, v174, v0
	v_fma_f32 v1, -v24, v175, v1
	v_fma_f32 v0, -v25, v176, v0
	v_fma_f32 v1, -v26, v177, v1
	ds_read_b128 v[174:177], v33 offset:51712
	s_waitcnt lgkmcnt(0)
	v_fma_f32 v0, -v27, v174, v0
	v_fma_f32 v1, -v28, v175, v1
	v_fma_f32 v0, -v29, v176, v0
	v_fma_f32 v1, -v30, v177, v1
	ds_read_b128 v[174:177], v33 offset:51728
	s_waitcnt lgkmcnt(0)
	v_fma_f32 v0, -v31, v174, v0
	v_fma_f32 v1, -v77, v175, v1
	v_fma_f32 v0, -v79, v176, v0
	v_fma_f32 v1, -v81, v177, v1
	ds_read_b128 v[174:177], v33 offset:51744
	s_waitcnt lgkmcnt(0)
	v_fma_f32 v0, -v83, v174, v0
	v_fma_f32 v1, -v85, v175, v1
	v_fma_f32 v0, -v87, v176, v0
	v_fma_f32 v1, -v89, v177, v1
	ds_read_b128 v[174:177], v33 offset:51760
	s_waitcnt lgkmcnt(0)
	v_fma_f32 v0, -v90, v174, v0
	v_fma_f32 v1, -v91, v175, v1
	v_fma_f32 v0, -v92, v176, v0
	v_fma_f32 v1, -v93, v177, v1
	ds_read_b128 v[174:177], v33 offset:51776
	s_waitcnt lgkmcnt(0)
	v_fma_f32 v0, -v142, v174, v0
	v_fma_f32 v1, -v143, v175, v1
	v_fma_f32 v0, -v144, v176, v0
	v_fma_f32 v1, -v145, v177, v1
	ds_read_b128 v[174:177], v33 offset:51792
	s_waitcnt lgkmcnt(0)
	v_fma_f32 v0, -v146, v174, v0
	v_fma_f32 v1, -v147, v175, v1
	v_fma_f32 v0, -v148, v176, v0
	v_fma_f32 v1, -v149, v177, v1
	ds_read_b128 v[174:177], v33 offset:51808
	s_waitcnt lgkmcnt(0)
	v_fma_f32 v0, -v150, v174, v0
	v_fma_f32 v1, -v151, v175, v1
	v_fma_f32 v0, -v152, v176, v0
	v_fma_f32 v1, -v153, v177, v1
	ds_read_b128 v[174:177], v33 offset:51824
	s_waitcnt lgkmcnt(0)
	v_fma_f32 v0, -v154, v174, v0
	v_fma_f32 v1, -v155, v175, v1
	v_fma_f32 v2, -v156, v176, v0
	v_fma_f32 v160, -v157, v177, v1
	ds_read_b64 v[0:1], v33 offset:51840
	ds_read_b128 v[174:177], v33 offset:52160
	s_waitcnt lgkmcnt(1)
	v_fma_f32 v0, -v158, v0, v2
	v_fma_f32 v1, -v159, v1, v160
	v_add_f32_e32 v160, v0, v1
	v_mul_f32_e32 v0, v161, v169
	ds_read_b128 v[166:169], v33 offset:51888
	v_mul_f32_e32 v1, v0, v173
	v_cndmask_b32_e64 v0, v0, v1, s[8:9]
	ds_read_b128 v[170:173], v33 offset:752
	s_waitcnt lgkmcnt(1)
	v_fma_f32 v0, -v8, v166, v0
	v_fma_f32 v1, -v9, v167, 0
	v_fma_f32 v0, -v10, v168, v0
	v_fma_f32 v1, -v11, v169, v1
	ds_read_b128 v[166:169], v33 offset:51904
	s_waitcnt lgkmcnt(0)
	v_fma_f32 v0, -v12, v166, v0
	v_fma_f32 v1, -v13, v167, v1
	v_fma_f32 v0, -v14, v168, v0
	v_fma_f32 v1, -v15, v169, v1
	ds_read_b128 v[166:169], v33 offset:51920
	s_waitcnt lgkmcnt(0)
	v_fma_f32 v0, -v4, v166, v0
	v_fma_f32 v1, -v5, v167, v1
	v_fma_f32 v0, -v6, v168, v0
	v_fma_f32 v1, -v7, v169, v1
	ds_read_b128 v[166:169], v33 offset:51936
	s_waitcnt lgkmcnt(0)
	v_fma_f32 v0, -v16, v166, v0
	v_fma_f32 v1, -v17, v167, v1
	v_fma_f32 v0, -v18, v168, v0
	v_fma_f32 v1, -v3, v169, v1
	ds_read_b128 v[166:169], v33 offset:51952
	s_waitcnt lgkmcnt(0)
	v_fma_f32 v0, -v19, v166, v0
	v_fma_f32 v1, -v20, v167, v1
	v_fma_f32 v0, -v21, v168, v0
	v_fma_f32 v1, -v22, v169, v1
	ds_read_b128 v[166:169], v33 offset:51968
	s_waitcnt lgkmcnt(0)
	v_fma_f32 v0, -v23, v166, v0
	v_fma_f32 v1, -v24, v167, v1
	v_fma_f32 v0, -v25, v168, v0
	v_fma_f32 v1, -v26, v169, v1
	ds_read_b128 v[166:169], v33 offset:51984
	s_waitcnt lgkmcnt(0)
	v_fma_f32 v0, -v27, v166, v0
	v_fma_f32 v1, -v28, v167, v1
	v_fma_f32 v0, -v29, v168, v0
	v_fma_f32 v1, -v30, v169, v1
	ds_read_b128 v[166:169], v33 offset:52000
	s_waitcnt lgkmcnt(0)
	v_fma_f32 v0, -v31, v166, v0
	v_fma_f32 v1, -v77, v167, v1
	v_fma_f32 v0, -v79, v168, v0
	v_fma_f32 v1, -v81, v169, v1
	ds_read_b128 v[166:169], v33 offset:52016
	s_waitcnt lgkmcnt(0)
	v_fma_f32 v0, -v83, v166, v0
	v_fma_f32 v1, -v85, v167, v1
	v_fma_f32 v0, -v87, v168, v0
	v_fma_f32 v1, -v89, v169, v1
	ds_read_b128 v[166:169], v33 offset:52032
	s_waitcnt lgkmcnt(0)
	v_fma_f32 v0, -v90, v166, v0
	v_fma_f32 v1, -v91, v167, v1
	v_fma_f32 v0, -v92, v168, v0
	v_fma_f32 v1, -v93, v169, v1
	ds_read_b128 v[166:169], v33 offset:52048
	s_waitcnt lgkmcnt(0)
	v_fma_f32 v0, -v142, v166, v0
	v_fma_f32 v1, -v143, v167, v1
	v_fma_f32 v0, -v144, v168, v0
	v_fma_f32 v1, -v145, v169, v1
	ds_read_b128 v[166:169], v33 offset:52064
	s_waitcnt lgkmcnt(0)
	v_fma_f32 v0, -v146, v166, v0
	v_fma_f32 v1, -v147, v167, v1
	v_fma_f32 v0, -v148, v168, v0
	v_fma_f32 v1, -v149, v169, v1
	ds_read_b128 v[166:169], v33 offset:52080
	s_waitcnt lgkmcnt(0)
; DI void chunk_prep(const Params& p, int item, char* smem) {
;     ...
;   {
;     const int c = tid;
;     float sol[64];
; #pragma unroll
;     for (int i = 0; i < 64; ++i) {
;       float rhs = rraw[i] * betas[i];
;       if (c >= 128) rhs *= egs[i];
;       float acc = rhs, acc1 = 0.f;
; #pragma unroll
;       for (int j = 0; j < i; ++j) {
;         if (j & 1) acc1 -= Am[i * 68 + j] * sol[j];
;         else acc -= Am[i * 68 + j] * sol[j];
;       }
;       sol[i] = acc + acc1;
;     }
	v_fma_f32 v0, -v150, v166, v0
	v_fma_f32 v1, -v151, v167, v1
	v_fma_f32 v0, -v152, v168, v0
	v_fma_f32 v1, -v153, v169, v1
	ds_read_b128 v[166:169], v33 offset:52096
	s_waitcnt lgkmcnt(0)
	v_fma_f32 v0, -v154, v166, v0
	v_fma_f32 v1, -v155, v167, v1
	v_fma_f32 v161, -v156, v168, v0
	v_fma_f32 v166, -v157, v169, v1
	ds_read_b96 v[0:2], v33 offset:52112
	s_waitcnt lgkmcnt(0)
	v_fma_f32 v1, -v159, v1, v166
	ds_read_b128 v[166:169], v33 offset:496
	v_fma_f32 v0, -v158, v0, v161
	v_fma_f32 v0, -v160, v2, v0
	v_add_f32_e32 v161, v1, v0
	ds_read_b32 v2, v33 offset:52672
	s_waitcnt lgkmcnt(1)
	v_mul_f32_e32 v0, v162, v166
	v_mul_f32_e32 v1, v0, v170
	v_cndmask_b32_e64 v0, v0, v1, s[8:9]
	v_fma_f32 v0, -v8, v174, v0
	v_fma_f32 v1, -v9, v175, 0
	v_fma_f32 v0, -v10, v176, v0
	v_fma_f32 v1, -v11, v177, v1
	ds_read_b128 v[174:177], v33 offset:52176
	s_waitcnt lgkmcnt(0)
	v_fma_f32 v0, -v12, v174, v0
	v_fma_f32 v1, -v13, v175, v1
	v_fma_f32 v0, -v14, v176, v0
	v_fma_f32 v1, -v15, v177, v1
	ds_read_b128 v[174:177], v33 offset:52192
	s_waitcnt lgkmcnt(0)
	v_fma_f32 v0, -v4, v174, v0
	v_fma_f32 v1, -v5, v175, v1
	v_fma_f32 v0, -v6, v176, v0
	v_fma_f32 v1, -v7, v177, v1
	ds_read_b128 v[174:177], v33 offset:52208
	s_waitcnt lgkmcnt(0)
	v_fma_f32 v0, -v16, v174, v0
	v_fma_f32 v1, -v17, v175, v1
	v_fma_f32 v0, -v18, v176, v0
	v_fma_f32 v1, -v3, v177, v1
	ds_read_b128 v[174:177], v33 offset:52224
	s_waitcnt lgkmcnt(0)
	v_fma_f32 v0, -v19, v174, v0
	v_fma_f32 v1, -v20, v175, v1
	v_fma_f32 v0, -v21, v176, v0
	v_fma_f32 v1, -v22, v177, v1
	ds_read_b128 v[174:177], v33 offset:52240
	s_waitcnt lgkmcnt(0)
	v_fma_f32 v0, -v23, v174, v0
	v_fma_f32 v1, -v24, v175, v1
	v_fma_f32 v0, -v25, v176, v0
	v_fma_f32 v1, -v26, v177, v1
	ds_read_b128 v[174:177], v33 offset:52256
	s_waitcnt lgkmcnt(0)
	v_fma_f32 v0, -v27, v174, v0
	v_fma_f32 v1, -v28, v175, v1
	v_fma_f32 v0, -v29, v176, v0
	v_fma_f32 v1, -v30, v177, v1
	ds_read_b128 v[174:177], v33 offset:52272
	s_waitcnt lgkmcnt(0)
	v_fma_f32 v0, -v31, v174, v0
	v_fma_f32 v1, -v77, v175, v1
	v_fma_f32 v0, -v79, v176, v0
	v_fma_f32 v1, -v81, v177, v1
	ds_read_b128 v[174:177], v33 offset:52288
	s_waitcnt lgkmcnt(0)
	v_fma_f32 v0, -v83, v174, v0
	v_fma_f32 v1, -v85, v175, v1
	v_fma_f32 v0, -v87, v176, v0
	v_fma_f32 v1, -v89, v177, v1
	ds_read_b128 v[174:177], v33 offset:52304
	s_waitcnt lgkmcnt(0)
	v_fma_f32 v0, -v90, v174, v0
	v_fma_f32 v1, -v91, v175, v1
	v_fma_f32 v0, -v92, v176, v0
	v_fma_f32 v1, -v93, v177, v1
	ds_read_b128 v[174:177], v33 offset:52320
	s_waitcnt lgkmcnt(0)
	v_fma_f32 v0, -v142, v174, v0
	v_fma_f32 v1, -v143, v175, v1
	v_fma_f32 v0, -v144, v176, v0
	v_fma_f32 v1, -v145, v177, v1
	ds_read_b128 v[174:177], v33 offset:52336
	s_waitcnt lgkmcnt(0)
	v_fma_f32 v0, -v146, v174, v0
	v_fma_f32 v1, -v147, v175, v1
	v_fma_f32 v0, -v148, v176, v0
	v_fma_f32 v1, -v149, v177, v1
	ds_read_b128 v[174:177], v33 offset:52352
	s_waitcnt lgkmcnt(0)
	v_fma_f32 v0, -v150, v174, v0
	v_fma_f32 v1, -v151, v175, v1
	v_fma_f32 v0, -v152, v176, v0
	v_fma_f32 v1, -v153, v177, v1
	ds_read_b128 v[174:177], v33 offset:52368
	s_waitcnt lgkmcnt(0)
	v_fma_f32 v0, -v154, v174, v0
	v_fma_f32 v1, -v155, v175, v1
	v_fma_f32 v0, -v156, v176, v0
	v_fma_f32 v1, -v157, v177, v1
	ds_read_b128 v[174:177], v33 offset:52384
	s_waitcnt lgkmcnt(0)
	v_fma_f32 v0, -v158, v174, v0
	v_fma_f32 v1, -v159, v175, v1
	v_fma_f32 v0, -v160, v176, v0
	v_fma_f32 v1, -v161, v177, v1
	ds_read_b128 v[174:177], v33 offset:52432
	v_add_f32_e32 v162, v0, v1
	v_mul_f32_e32 v0, v163, v167
	v_mul_f32_e32 v1, v0, v171
	v_cndmask_b32_e64 v0, v0, v1, s[8:9]
	s_waitcnt lgkmcnt(0)
	v_fma_f32 v0, -v8, v174, v0
	v_fma_f32 v1, -v9, v175, 0
	v_fma_f32 v0, -v10, v176, v0
	v_fma_f32 v1, -v11, v177, v1
	ds_read_b128 v[174:177], v33 offset:52448
	s_waitcnt lgkmcnt(0)
	v_fma_f32 v0, -v12, v174, v0
	v_fma_f32 v1, -v13, v175, v1
	v_fma_f32 v0, -v14, v176, v0
	v_fma_f32 v1, -v15, v177, v1
	ds_read_b128 v[174:177], v33 offset:52464
	s_waitcnt lgkmcnt(0)
	v_fma_f32 v0, -v4, v174, v0
	v_fma_f32 v1, -v5, v175, v1
	v_fma_f32 v0, -v6, v176, v0
	v_fma_f32 v1, -v7, v177, v1
	ds_read_b128 v[174:177], v33 offset:52480
	s_waitcnt lgkmcnt(0)
	v_fma_f32 v0, -v16, v174, v0
	v_fma_f32 v1, -v17, v175, v1
	v_fma_f32 v0, -v18, v176, v0
	v_fma_f32 v1, -v3, v177, v1
	ds_read_b128 v[174:177], v33 offset:52496
	s_waitcnt lgkmcnt(0)
	v_fma_f32 v0, -v19, v174, v0
	v_fma_f32 v1, -v20, v175, v1
	v_fma_f32 v0, -v21, v176, v0
	v_fma_f32 v1, -v22, v177, v1
	ds_read_b128 v[174:177], v33 offset:52512
	s_waitcnt lgkmcnt(0)
	v_fma_f32 v0, -v23, v174, v0
	v_fma_f32 v1, -v24, v175, v1
	v_fma_f32 v0, -v25, v176, v0
	v_fma_f32 v1, -v26, v177, v1
	ds_read_b128 v[174:177], v33 offset:52528
	s_waitcnt lgkmcnt(0)
	v_fma_f32 v0, -v27, v174, v0
	v_fma_f32 v1, -v28, v175, v1
	v_fma_f32 v0, -v29, v176, v0
	v_fma_f32 v1, -v30, v177, v1
	ds_read_b128 v[174:177], v33 offset:52544
	s_waitcnt lgkmcnt(0)
	v_fma_f32 v0, -v31, v174, v0
	v_fma_f32 v1, -v77, v175, v1
	v_fma_f32 v0, -v79, v176, v0
	v_fma_f32 v1, -v81, v177, v1
	ds_read_b128 v[174:177], v33 offset:52560
	s_waitcnt lgkmcnt(0)
	v_fma_f32 v0, -v83, v174, v0
	v_fma_f32 v1, -v85, v175, v1
	v_fma_f32 v0, -v87, v176, v0
	v_fma_f32 v1, -v89, v177, v1
	ds_read_b128 v[174:177], v33 offset:52576
	s_waitcnt lgkmcnt(0)
	v_fma_f32 v0, -v90, v174, v0
	v_fma_f32 v1, -v91, v175, v1
	v_fma_f32 v0, -v92, v176, v0
	v_fma_f32 v1, -v93, v177, v1
	ds_read_b128 v[174:177], v33 offset:52592
	s_waitcnt lgkmcnt(0)
	v_fma_f32 v0, -v142, v174, v0
	v_fma_f32 v1, -v143, v175, v1
	v_fma_f32 v0, -v144, v176, v0
	v_fma_f32 v1, -v145, v177, v1
	ds_read_b128 v[174:177], v33 offset:52608
	s_waitcnt lgkmcnt(0)
; DI void chunk_prep(const Params& p, int item, char* smem) {
;     ...
;   {
;     const int c = tid;
;     float sol[64];
; #pragma unroll
;     for (int i = 0; i < 64; ++i) {
;       float rhs = rraw[i] * betas[i];
;       if (c >= 128) rhs *= egs[i];
;       float acc = rhs, acc1 = 0.f;
; #pragma unroll
;       for (int j = 0; j < i; ++j) {
;         if (j & 1) acc1 -= Am[i * 68 + j] * sol[j];
;         else acc -= Am[i * 68 + j] * sol[j];
;       }
;       sol[i] = acc + acc1;
;     }
;     if (c < 128) {
	v_fma_f32 v0, -v146, v174, v0
	v_fma_f32 v1, -v147, v175, v1
	v_fma_f32 v0, -v148, v176, v0
	v_fma_f32 v1, -v149, v177, v1
	ds_read_b128 v[174:177], v33 offset:52624
	s_waitcnt lgkmcnt(0)
	v_fma_f32 v0, -v150, v174, v0
	v_fma_f32 v1, -v151, v175, v1
	v_fma_f32 v0, -v152, v176, v0
	v_fma_f32 v1, -v153, v177, v1
	ds_read_b128 v[174:177], v33 offset:52640
	s_waitcnt lgkmcnt(0)
	v_fma_f32 v0, -v154, v174, v0
	v_fma_f32 v1, -v155, v175, v1
	v_fma_f32 v0, -v156, v176, v0
	v_fma_f32 v1, -v157, v177, v1
	ds_read_b128 v[174:177], v33 offset:52656
	s_waitcnt lgkmcnt(0)
	v_fma_f32 v0, -v158, v174, v0
	v_fma_f32 v1, -v159, v175, v1
	v_fma_f32 v0, -v160, v176, v0
	v_fma_f32 v1, -v161, v177, v1
	ds_read_b128 v[174:177], v33 offset:52704
	v_fma_f32 v0, -v162, v2, v0
	v_add_f32_e32 v163, v1, v0
	v_mul_f32_e32 v0, v164, v168
	v_mul_f32_e32 v1, v0, v172
	v_cndmask_b32_e64 v0, v0, v1, s[8:9]
	s_waitcnt lgkmcnt(0)
	v_fma_f32 v0, -v8, v174, v0
	v_fma_f32 v1, -v9, v175, 0
	v_fma_f32 v0, -v10, v176, v0
	v_fma_f32 v1, -v11, v177, v1
	ds_read_b128 v[174:177], v33 offset:52720
	s_waitcnt lgkmcnt(0)
	v_fma_f32 v0, -v12, v174, v0
	v_fma_f32 v1, -v13, v175, v1
	v_fma_f32 v0, -v14, v176, v0
	v_fma_f32 v1, -v15, v177, v1
	ds_read_b128 v[174:177], v33 offset:52736
	s_waitcnt lgkmcnt(0)
	v_fma_f32 v0, -v4, v174, v0
	v_fma_f32 v1, -v5, v175, v1
	v_fma_f32 v0, -v6, v176, v0
	v_fma_f32 v1, -v7, v177, v1
	ds_read_b128 v[174:177], v33 offset:52752
	s_waitcnt lgkmcnt(0)
	v_fma_f32 v0, -v16, v174, v0
	v_fma_f32 v1, -v17, v175, v1
	v_fma_f32 v0, -v18, v176, v0
	v_fma_f32 v1, -v3, v177, v1
	ds_read_b128 v[174:177], v33 offset:52768
	s_waitcnt lgkmcnt(0)
	v_fma_f32 v0, -v19, v174, v0
	v_fma_f32 v1, -v20, v175, v1
	v_fma_f32 v0, -v21, v176, v0
	v_fma_f32 v1, -v22, v177, v1
	ds_read_b128 v[174:177], v33 offset:52784
	s_waitcnt lgkmcnt(0)
	v_fma_f32 v0, -v23, v174, v0
	v_fma_f32 v1, -v24, v175, v1
	v_fma_f32 v0, -v25, v176, v0
	v_fma_f32 v1, -v26, v177, v1
	ds_read_b128 v[174:177], v33 offset:52800
	s_waitcnt lgkmcnt(0)
	v_fma_f32 v0, -v27, v174, v0
	v_fma_f32 v1, -v28, v175, v1
	v_fma_f32 v0, -v29, v176, v0
	v_fma_f32 v1, -v30, v177, v1
	ds_read_b128 v[174:177], v33 offset:52816
	s_waitcnt lgkmcnt(0)
	v_fma_f32 v0, -v31, v174, v0
	v_fma_f32 v1, -v77, v175, v1
	v_fma_f32 v0, -v79, v176, v0
	v_fma_f32 v1, -v81, v177, v1
	ds_read_b128 v[174:177], v33 offset:52832
	s_waitcnt lgkmcnt(0)
	v_fma_f32 v0, -v83, v174, v0
	v_fma_f32 v1, -v85, v175, v1
	v_fma_f32 v0, -v87, v176, v0
	v_fma_f32 v1, -v89, v177, v1
	ds_read_b128 v[174:177], v33 offset:52848
	s_waitcnt lgkmcnt(0)
	v_fma_f32 v0, -v90, v174, v0
	v_fma_f32 v1, -v91, v175, v1
	v_fma_f32 v0, -v92, v176, v0
	v_fma_f32 v1, -v93, v177, v1
	ds_read_b128 v[174:177], v33 offset:52864
	s_waitcnt lgkmcnt(0)
	v_fma_f32 v0, -v142, v174, v0
	v_fma_f32 v1, -v143, v175, v1
	v_fma_f32 v0, -v144, v176, v0
	v_fma_f32 v1, -v145, v177, v1
	ds_read_b128 v[174:177], v33 offset:52880
	s_waitcnt lgkmcnt(0)
	v_fma_f32 v0, -v146, v174, v0
	v_fma_f32 v1, -v147, v175, v1
	v_fma_f32 v0, -v148, v176, v0
	v_fma_f32 v1, -v149, v177, v1
	ds_read_b128 v[174:177], v33 offset:52896
	s_waitcnt lgkmcnt(0)
	v_fma_f32 v0, -v150, v174, v0
	v_fma_f32 v1, -v151, v175, v1
	v_fma_f32 v0, -v152, v176, v0
	v_fma_f32 v1, -v153, v177, v1
	ds_read_b128 v[174:177], v33 offset:52912
	s_waitcnt lgkmcnt(0)
	v_fma_f32 v0, -v154, v174, v0
	v_fma_f32 v1, -v155, v175, v1
	v_fma_f32 v0, -v156, v176, v0
	v_fma_f32 v1, -v157, v177, v1
	ds_read_b128 v[174:177], v33 offset:52928
	s_waitcnt lgkmcnt(0)
	v_fma_f32 v0, -v158, v174, v0
	v_fma_f32 v1, -v159, v175, v1
	v_fma_f32 v2, -v160, v176, v0
	v_fma_f32 v164, -v161, v177, v1
	ds_read_b64 v[0:1], v33 offset:52944
	s_waitcnt lgkmcnt(0)
	v_fma_f32 v0, -v162, v0, v2
	v_fma_f32 v1, -v163, v1, v164
	v_add_f32_e32 v164, v0, v1
	v_mul_f32_e32 v0, v165, v169
	ds_read_b128 v[166:169], v33 offset:52976
	v_mul_f32_e32 v1, v0, v173
	v_cndmask_b32_e64 v0, v0, v1, s[8:9]
	s_waitcnt lgkmcnt(0)
	v_fma_f32 v0, -v8, v166, v0
	v_fma_f32 v1, -v9, v167, 0
	v_fma_f32 v0, -v10, v168, v0
	v_fma_f32 v1, -v11, v169, v1
	ds_read_b128 v[166:169], v33 offset:52992
	s_waitcnt lgkmcnt(0)
	v_fma_f32 v0, -v12, v166, v0
	v_fma_f32 v1, -v13, v167, v1
	v_fma_f32 v0, -v14, v168, v0
	v_fma_f32 v1, -v15, v169, v1
	ds_read_b128 v[166:169], v33 offset:53008
	s_waitcnt lgkmcnt(0)
	v_fma_f32 v0, -v4, v166, v0
	v_fma_f32 v1, -v5, v167, v1
	v_fma_f32 v0, -v6, v168, v0
	v_fma_f32 v1, -v7, v169, v1
	ds_read_b128 v[166:169], v33 offset:53024
	s_waitcnt lgkmcnt(0)
	v_fma_f32 v0, -v16, v166, v0
	v_fma_f32 v1, -v17, v167, v1
	v_fma_f32 v0, -v18, v168, v0
	v_fma_f32 v1, -v3, v169, v1
	ds_read_b128 v[166:169], v33 offset:53040
	s_waitcnt lgkmcnt(0)
	v_fma_f32 v0, -v19, v166, v0
	v_fma_f32 v1, -v20, v167, v1
	v_fma_f32 v0, -v21, v168, v0
	v_fma_f32 v1, -v22, v169, v1
	ds_read_b128 v[166:169], v33 offset:53056
	s_waitcnt lgkmcnt(0)
	v_fma_f32 v0, -v23, v166, v0
	v_fma_f32 v1, -v24, v167, v1
	v_fma_f32 v0, -v25, v168, v0
	v_fma_f32 v1, -v26, v169, v1
	ds_read_b128 v[166:169], v33 offset:53072
	s_waitcnt lgkmcnt(0)
	v_fma_f32 v0, -v27, v166, v0
	v_fma_f32 v1, -v28, v167, v1
	v_fma_f32 v0, -v29, v168, v0
	v_fma_f32 v1, -v30, v169, v1
	ds_read_b128 v[166:169], v33 offset:53088
	s_waitcnt lgkmcnt(0)
	v_fma_f32 v0, -v31, v166, v0
	v_fma_f32 v1, -v77, v167, v1
	v_fma_f32 v0, -v79, v168, v0
	v_fma_f32 v1, -v81, v169, v1
	ds_read_b128 v[166:169], v33 offset:53104
	s_waitcnt lgkmcnt(0)
	v_fma_f32 v0, -v83, v166, v0
	v_fma_f32 v1, -v85, v167, v1
	v_fma_f32 v0, -v87, v168, v0
	v_fma_f32 v1, -v89, v169, v1
	ds_read_b128 v[166:169], v33 offset:53120
	s_waitcnt lgkmcnt(0)
	v_fma_f32 v0, -v90, v166, v0
	v_fma_f32 v1, -v91, v167, v1
	v_fma_f32 v0, -v92, v168, v0
	v_fma_f32 v1, -v93, v169, v1
	ds_read_b128 v[166:169], v33 offset:53136
	s_waitcnt lgkmcnt(0)
	v_fma_f32 v0, -v142, v166, v0
	v_fma_f32 v1, -v143, v167, v1
	v_fma_f32 v0, -v144, v168, v0
	v_fma_f32 v1, -v145, v169, v1
	ds_read_b128 v[166:169], v33 offset:53152
	s_waitcnt lgkmcnt(0)
	v_fma_f32 v0, -v146, v166, v0
	v_fma_f32 v1, -v147, v167, v1
	v_fma_f32 v0, -v148, v168, v0
	v_fma_f32 v1, -v149, v169, v1
	ds_read_b128 v[166:169], v33 offset:53168
	s_waitcnt lgkmcnt(0)
	v_fma_f32 v0, -v150, v166, v0
	v_fma_f32 v1, -v151, v167, v1
	v_fma_f32 v0, -v152, v168, v0
	v_fma_f32 v1, -v153, v169, v1
	ds_read_b128 v[166:169], v33 offset:53184
	s_waitcnt lgkmcnt(0)
	v_fma_f32 v0, -v154, v166, v0
	v_fma_f32 v1, -v155, v167, v1
	v_fma_f32 v0, -v156, v168, v0
	v_fma_f32 v1, -v157, v169, v1
	ds_read_b128 v[166:169], v33 offset:53200
	s_waitcnt lgkmcnt(0)
	v_fma_f32 v0, -v158, v166, v0
	v_fma_f32 v1, -v159, v167, v1
	v_fma_f32 v165, -v160, v168, v0
	v_fma_f32 v166, -v161, v169, v1
	ds_read_b96 v[0:2], v33 offset:53216
	s_waitcnt lgkmcnt(0)
	v_fma_f32 v0, -v162, v0, v165
	v_fma_f32 v1, -v163, v1, v166
	v_fma_f32 v0, -v164, v2, v0
	v_add_f32_e32 v0, v1, v0
	s_and_saveexec_b64 s[48:49], s[8:9]
	s_xor_b64 s[48:49], exec, s[48:49]
	s_cbranch_execz .LBB0_442
; DI bfr f2bf(float a) { return (bfr)(pack2(a, 0.f) & 0xffffu); }
; DI void chunk_prep(const Params& p, int item, char* smem) {
;     ...
;     } else {
; #pragma unroll
;       for (int i = 0; i < 64; ++i) wsb[i * 136 + (c - 128)] = f2bf(-sol[i]);
;     }
	v_cvt_pk_bf16_f32 v1, -v8, s0
	ds_write_b16 v99, v1 offset:768
	v_cvt_pk_bf16_f32 v1, -v9, s0
	ds_write_b16 v99, v1 offset:1040
	v_cvt_pk_bf16_f32 v1, -v10, s0
	ds_write_b16 v99, v1 offset:1312
	v_cvt_pk_bf16_f32 v1, -v11, s0
	ds_write_b16 v99, v1 offset:1584
	v_cvt_pk_bf16_f32 v1, -v12, s0
	ds_write_b16 v99, v1 offset:1856
	v_cvt_pk_bf16_f32 v1, -v13, s0
	ds_write_b16 v99, v1 offset:2128
	v_cvt_pk_bf16_f32 v1, -v14, s0
	ds_write_b16 v99, v1 offset:2400
	v_cvt_pk_bf16_f32 v1, -v15, s0
	ds_write_b16 v99, v1 offset:2672
	v_cvt_pk_bf16_f32 v1, -v4, s0
	ds_write_b16 v99, v1 offset:2944
	v_cvt_pk_bf16_f32 v1, -v5, s0
	ds_write_b16 v99, v1 offset:3216
	v_cvt_pk_bf16_f32 v1, -v6, s0
	ds_write_b16 v99, v1 offset:3488
	v_cvt_pk_bf16_f32 v1, -v7, s0
	ds_write_b16 v99, v1 offset:3760
	v_cvt_pk_bf16_f32 v1, -v16, s0
	ds_write_b16 v99, v1 offset:4032
	v_cvt_pk_bf16_f32 v1, -v17, s0
	ds_write_b16 v99, v1 offset:4304
	v_cvt_pk_bf16_f32 v1, -v18, s0
	ds_write_b16 v99, v1 offset:4576
	v_cvt_pk_bf16_f32 v1, -v3, s0
	ds_write_b16 v99, v1 offset:4848
	v_cvt_pk_bf16_f32 v1, -v19, s0
	ds_write_b16 v99, v1 offset:5120
	v_cvt_pk_bf16_f32 v1, -v20, s0
	ds_write_b16 v99, v1 offset:5392
	v_cvt_pk_bf16_f32 v1, -v21, s0
	ds_write_b16 v99, v1 offset:5664
	v_cvt_pk_bf16_f32 v1, -v22, s0
	ds_write_b16 v99, v1 offset:5936
	v_cvt_pk_bf16_f32 v1, -v23, s0
	ds_write_b16 v99, v1 offset:6208
	v_cvt_pk_bf16_f32 v1, -v24, s0
	ds_write_b16 v99, v1 offset:6480
	v_cvt_pk_bf16_f32 v1, -v25, s0
	ds_write_b16 v99, v1 offset:6752
	v_cvt_pk_bf16_f32 v1, -v26, s0
	ds_write_b16 v99, v1 offset:7024
	v_cvt_pk_bf16_f32 v1, -v27, s0
	ds_write_b16 v99, v1 offset:7296
	v_cvt_pk_bf16_f32 v1, -v28, s0
	ds_write_b16 v99, v1 offset:7568
	v_cvt_pk_bf16_f32 v1, -v29, s0
	ds_write_b16 v99, v1 offset:7840
	v_cvt_pk_bf16_f32 v1, -v30, s0
	ds_write_b16 v99, v1 offset:8112
	v_cvt_pk_bf16_f32 v1, -v31, s0
	ds_write_b16 v99, v1 offset:8384
	v_cvt_pk_bf16_f32 v1, -v77, s0
	ds_write_b16 v99, v1 offset:8656
	v_cvt_pk_bf16_f32 v1, -v79, s0
	ds_write_b16 v99, v1 offset:8928
	v_cvt_pk_bf16_f32 v1, -v81, s0
	ds_write_b16 v99, v1 offset:9200
	v_cvt_pk_bf16_f32 v1, -v83, s0
	ds_write_b16 v99, v1 offset:9472
	v_cvt_pk_bf16_f32 v1, -v85, s0
	ds_write_b16 v99, v1 offset:9744
	v_cvt_pk_bf16_f32 v1, -v87, s0
	ds_write_b16 v99, v1 offset:10016
	v_cvt_pk_bf16_f32 v1, -v89, s0
	ds_write_b16 v99, v1 offset:10288
	v_cvt_pk_bf16_f32 v1, -v90, s0
	ds_write_b16 v99, v1 offset:10560
	v_cvt_pk_bf16_f32 v1, -v91, s0
	ds_write_b16 v99, v1 offset:10832
	v_cvt_pk_bf16_f32 v1, -v92, s0
	ds_write_b16 v99, v1 offset:11104
	v_cvt_pk_bf16_f32 v1, -v93, s0
	ds_write_b16 v99, v1 offset:11376
	v_cvt_pk_bf16_f32 v1, -v142, s0
	ds_write_b16 v99, v1 offset:11648
	v_cvt_pk_bf16_f32 v1, -v143, s0
	ds_write_b16 v99, v1 offset:11920
	v_cvt_pk_bf16_f32 v1, -v144, s0
	ds_write_b16 v99, v1 offset:12192
	v_cvt_pk_bf16_f32 v1, -v145, s0
	ds_write_b16 v99, v1 offset:12464
	v_cvt_pk_bf16_f32 v1, -v146, s0
	ds_write_b16 v99, v1 offset:12736
	v_cvt_pk_bf16_f32 v1, -v147, s0
	ds_write_b16 v99, v1 offset:13008
	v_cvt_pk_bf16_f32 v1, -v148, s0
	ds_write_b16 v99, v1 offset:13280
	v_cvt_pk_bf16_f32 v1, -v149, s0
	ds_write_b16 v99, v1 offset:13552
	v_cvt_pk_bf16_f32 v1, -v150, s0
	ds_write_b16 v99, v1 offset:13824
	v_cvt_pk_bf16_f32 v1, -v151, s0
	ds_write_b16 v99, v1 offset:14096
	v_cvt_pk_bf16_f32 v1, -v152, s0
	ds_write_b16 v99, v1 offset:14368
	v_cvt_pk_bf16_f32 v1, -v153, s0
	ds_write_b16 v99, v1 offset:14640
	v_cvt_pk_bf16_f32 v1, -v154, s0
	ds_write_b16 v99, v1 offset:14912
	v_cvt_pk_bf16_f32 v1, -v155, s0
	ds_write_b16 v99, v1 offset:15184
	v_cvt_pk_bf16_f32 v1, -v156, s0
	ds_write_b16 v99, v1 offset:15456
	v_cvt_pk_bf16_f32 v1, -v157, s0
	ds_write_b16 v99, v1 offset:15728
	v_cvt_pk_bf16_f32 v1, -v158, s0
	ds_write_b16 v99, v1 offset:16000
	v_cvt_pk_bf16_f32 v1, -v159, s0
	ds_write_b16 v99, v1 offset:16272
	v_cvt_pk_bf16_f32 v1, -v160, s0
	ds_write_b16 v99, v1 offset:16544
	v_cvt_pk_bf16_f32 v1, -v161, s0
	ds_write_b16 v99, v1 offset:16816
	v_cvt_pk_bf16_f32 v1, -v162, s0
	ds_write_b16 v99, v1 offset:17088
	v_cvt_pk_bf16_f32 v1, -v163, s0
	ds_write_b16 v99, v1 offset:17360
	v_cvt_pk_bf16_f32 v1, -v164, s0
	v_cvt_pk_bf16_f32 v0, -v0, s0
	ds_write_b16 v99, v1 offset:17632
	ds_write_b16 v99, v0 offset:17904

; DI void branch_a_final_row(const Params& p, int row, int lane) {
;   const float* cr = p.CONV + (size_t)row * 512;
;   float4 v[2];
;   float s = 0.f;
; #pragma unroll
;   for (int j = 0; j < 2; ++j) {
;     v[j] = ((const float4*)cr)[j * 64 + lane];
;     s += v[j].x + v[j].y + v[j].z + v[j].w;
;   }
;   float mean = wave_sum(s) * (1.0f / 512.0f);
;   float vs = 0.f;
; #pragma unroll
;   for (int j = 0; j < 2; ++j) {
;     v[j].x -= mean; v[j].y -= mean; v[j].z -= mean; v[j].w -= mean;
;     vs += v[j].x * v[j].x + v[j].y * v[j].y + v[j].z * v[j].z + v[j].w * v[j].w;
;   }
;   float inv = rsqrtf(wave_sum(vs) * (1.0f / 512.0f) + EPSF);
; #pragma unroll
;   for (int j = 0; j < 2; ++j) {
;     int c = (j * 64 + lane) * 4;
;     float4 g = *(const float4*)(p.ln_a_g + c), bb = *(const float4*)(p.ln_a_b + c);
;     uint2 gu = *(const uint2*)(p.PB + (size_t)row * EINP + 1024 + c);
; DI void branch_a_unit(const Params& p, int u, char* smem) {
;     ...
;     conv_a_sample_item(p, u - 512);
;     __syncthreads();
;     if (wid == 0) branch_a_final_row(p, NPR + (u - 512), lane);
.LBB0_526:
	v_add_u32_e32 v2, s1, v62
	v_mov_b32_e32 v3, v60
	v_lshl_add_u64 v[2:3], v[2:3], 2, s[22:23]
	v_cmp_gt_u32_e32 vcc, 64, v99
	global_store_dword v[2:3], v9, off
	global_store_dword v[0:1], v8, off offset:1024
	s_barrier
	s_and_saveexec_b64 s[8:9], vcc
	s_cbranch_execz .LBB0_528
	s_mov_b32 s1, s3
	s_lshl_b64 s[12:13], s[0:1], 11
	s_add_u32 s4, s40, s12
	s_addc_u32 s5, s41, s13
	s_mul_hi_u32 s1, s0, 0x1c00
	s_mulk_i32 s0, 0x1c00
	v_lshlrev_b32_e32 v0, 4, v98
	s_add_u32 s10, s36, s0
	global_load_dwordx4 v[4:7], v0, s[4:5]
	global_load_dwordx4 v[8:11], v0, s[4:5] offset:1024
	s_addc_u32 s11, s37, s1
	v_lshlrev_b32_e32 v32, 3, v99
	global_load_dwordx2 v[20:21], v32, s[10:11] offset:2048
	v_lshlrev_b32_e32 v0, 2, v99
	v_mov_b32_e32 v1, v60
	v_lshlrev_b64 v[0:1], 2, v[0:1]
	v_lshl_add_u64 v[2:3], s[28:29], 0, v[0:1]
	v_lshl_add_u64 v[0:1], s[30:31], 0, v[0:1]
	global_load_dwordx4 v[12:15], v[2:3], off
	global_load_dwordx4 v[16:19], v[0:1], off
	v_mov_b32_e32 v28, v60
	v_mov_b32_e32 v29, v60
	s_waitcnt vmcnt(4)
	v_mov_b32_e32 v22, v5
	v_pk_add_f32 v[22:23], v[4:5], v[22:23]
	v_mov_b32_e32 v24, v6
	s_waitcnt vmcnt(3)
	v_mov_b32_e32 v25, v9
	s_waitcnt vmcnt(2)
	v_lshlrev_b32_e32 v30, 16, v20
	v_and_b32_e32 v31, 0xffff0000, v20
	v_lshlrev_b32_e32 v33, 16, v21
	v_and_b32_e32 v34, 0xffff0000, v21
	v_mov_b32_e32 v23, v8
	v_mul_f32_e32 v35, 0xbfb8aa3b, v30
	v_mul_f32_e32 v36, 0xbfb8aa3b, v31
	v_pk_mov_b32 v[26:27], v[6:7], v[10:11] op_sel:[1,0]
	v_pk_add_f32 v[20:21], v[22:23], v[24:25]
	v_mul_f32_e32 v24, 0xbfb8aa3b, v33
	v_mul_f32_e32 v25, 0xbfb8aa3b, v34
	v_exp_f32_e32 v22, v35
	v_exp_f32_e32 v23, v36
	v_mov_b32_e32 v61, v11
	v_pk_add_f32 v[20:21], v[20:21], v[26:27]
	v_exp_f32_e32 v24, v24
	v_exp_f32_e32 v25, v25
	v_pk_add_f32 v[20:21], v[20:21], v[60:61]
	s_nop 0
	v_add_f32_e32 v20, v20, v21
	s_nop 1
	v_add_f32_dpp v26, v20, v20 quad_perm:[1,0,3,2] row_mask:0xf bank_mask:0xf bound_ctrl:1
	v_pk_add_f32 v[20:21], v[22:23], 1.0 op_sel_hi:[1,0]
	v_pk_add_f32 v[22:23], v[24:25], 1.0 op_sel_hi:[1,0]
	v_div_scale_f32 v25, s[0:1], v21, v21, v31
	v_add_f32_dpp v26, v26, v26 quad_perm:[2,3,0,1] row_mask:0xf bank_mask:0xf bound_ctrl:1
	v_div_scale_f32 v35, s[0:1], v20, v20, v30
	v_rcp_f32_e32 v40, v25
	v_add_f32_dpp v24, v26, v26 row_half_mirror row_mask:0xf bank_mask:0xf bound_ctrl:1
	v_div_scale_f32 v26, s[0:1], v23, v23, v34
	v_div_scale_f32 v38, s[0:1], v22, v22, v33
	v_rcp_f32_e32 v41, v35
	v_add_f32_dpp v24, v24, v24 row_mirror row_mask:0xf bank_mask:0xf bound_ctrl:1
	v_rcp_f32_e32 v42, v26
	v_rcp_f32_e32 v43, v38
	v_mov_b32_dpp v28, v24 row_bcast:15 row_mask:0xa bank_mask:0xf
	v_add_f32_e32 v24, v24, v28
	v_fma_f32 v28, -v25, v40, 1.0
	v_div_scale_f32 v27, vcc, v31, v21, v31
	v_mov_b32_dpp v29, v24 row_bcast:31 row_mask:0xc bank_mask:0xf
	v_fma_f32 v44, -v35, v41, 1.0
	v_fmac_f32_e32 v40, v28, v40
	v_div_scale_f32 v36, s[4:5], v30, v20, v30
	v_add_f32_e32 v24, v24, v29
	v_fma_f32 v29, -v26, v42, 1.0
	v_fma_f32 v45, -v38, v43, 1.0
	v_fmac_f32_e32 v41, v44, v41
	v_mul_f32_e32 v28, v27, v40
	v_div_scale_f32 v37, s[6:7], v34, v23, v34
	v_readlane_b32 s2, v24, 63
	v_fmac_f32_e32 v42, v29, v42
	v_fmac_f32_e32 v43, v45, v43
	v_mul_f32_e32 v29, v36, v41
	v_fma_f32 v45, -v25, v28, v27
	v_mul_f32_e32 v24, s2, v97
	v_mul_f32_e32 v44, v37, v42
	v_fma_f32 v46, -v35, v29, v36
	v_fmac_f32_e32 v28, v45, v40
	v_pk_add_f32 v[4:5], v[4:5], v[24:25] op_sel_hi:[1,0] neg_lo:[0,1] neg_hi:[0,1]
	v_pk_add_f32 v[6:7], v[6:7], v[24:25] op_sel_hi:[1,0] neg_lo:[0,1] neg_hi:[0,1]
	v_fma_f32 v47, -v26, v44, v37
	v_fmac_f32_e32 v29, v46, v41
	v_fma_f32 v25, -v25, v28, v27
	v_fmac_f32_e32 v44, v47, v42
	v_fma_f32 v27, -v35, v29, v36
	v_div_fmas_f32 v25, v25, v40, v28
	s_mov_b64 vcc, s[4:5]
	v_fma_f32 v26, -v26, v44, v37
	v_div_fixup_f32 v21, v25, v21, v31
	v_div_fmas_f32 v25, v27, v41, v29
	s_mov_b64 vcc, s[6:7]
	v_div_fixup_f32 v20, v25, v20, v30
	v_div_fmas_f32 v25, v26, v42, v44
	v_div_fixup_f32 v23, v25, v23, v34
	v_pk_add_f32 v[10:11], v[10:11], v[24:25] op_sel_hi:[1,0] neg_lo:[0,1] neg_hi:[0,1]
	v_pk_add_f32 v[24:25], v[8:9], v[24:25] op_sel_hi:[1,0] neg_lo:[0,1] neg_hi:[0,1]
	v_mov_b32_e32 v30, v5
	v_mov_b32_e32 v31, v25
	v_mov_b32_e32 v28, v4
	v_mov_b32_e32 v29, v24
	v_pk_mul_f32 v[30:31], v[30:31], v[30:31]
	v_mov_b32_e32 v8, v6
	v_mov_b32_e32 v9, v10
	v_pk_fma_f32 v[28:29], v[28:29], v[28:29], v[30:31]
	v_mov_b32_e32 v26, v7
	v_mov_b32_e32 v27, v11
	v_pk_fma_f32 v[8:9], v[8:9], v[8:9], v[28:29]
	v_div_scale_f32 v39, s[0:1], v33, v22, v33
	v_pk_fma_f32 v[8:9], v[26:27], v[26:27], v[8:9]
	v_mul_f32_e32 v27, v39, v43
	v_add_f32_e32 v8, v8, v9
	v_mov_b32_e32 v9, v60
	s_nop 0
	v_add_f32_dpp v8, v8, v8 quad_perm:[1,0,3,2] row_mask:0xf bank_mask:0xf bound_ctrl:1
	s_nop 1
	v_add_f32_dpp v8, v8, v8 quad_perm:[2,3,0,1] row_mask:0xf bank_mask:0xf bound_ctrl:1
	s_nop 1
	v_add_f32_dpp v8, v8, v8 row_half_mirror row_mask:0xf bank_mask:0xf bound_ctrl:1
	s_nop 1
	v_add_f32_dpp v8, v8, v8 row_mirror row_mask:0xf bank_mask:0xf bound_ctrl:1
	s_nop 1
	v_mov_b32_dpp v9, v8 row_bcast:15 row_mask:0xa bank_mask:0xf
	v_add_f32_e32 v8, v8, v9
	v_mov_b32_e32 v9, v60
	s_nop 1
	v_mov_b32_dpp v9, v8 row_bcast:31 row_mask:0xc bank_mask:0xf
	v_add_f32_e32 v8, v8, v9
	s_nop 0
	v_readlane_b32 s2, v8, 63
	s_nop 1
	v_fma_f32 v8, s2, v97, v63
	v_mul_f32_e32 v9, 0x4b800000, v8
	v_cmp_gt_f32_e32 vcc, s65, v8
	s_nop 1
	v_cndmask_b32_e32 v8, v8, v9, vcc
	v_rsq_f32_e32 v8, v8
	v_fma_f32 v9, -v38, v27, v39
	v_fmac_f32_e32 v27, v9, v43
	v_mul_f32_e32 v9, 0x45800000, v8
	v_cndmask_b32_e32 v26, v8, v9, vcc
	v_pk_mul_f32 v[4:5], v[4:5], v[26:27] op_sel_hi:[1,0]
	s_mov_b64 vcc, s[0:1]
	s_waitcnt vmcnt(0)
; DI float bflo(unsigned u) { return __uint_as_float(u << 16); }
; DI float bfhi(unsigned u) { return __uint_as_float(u & 0xffff0000u); }
; DI float siluf_(float x) { return x / (1.0f + __expf(-x)); }
; DI void branch_a_final_row(const Params& p, int row, int lane) {
;     ...
;     float y0 = siluf_(v[j].x * inv * g.x + bb.x) * siluf_(bflo(gu.x));
;     float y1 = siluf_(v[j].y * inv * g.y + bb.y) * siluf_(bfhi(gu.x));
;     float y2 = siluf_(v[j].z * inv * g.z + bb.z) * siluf_(bflo(gu.y));
;     float y3 = siluf_(v[j].w * inv * g.w + bb.w) * siluf_(bfhi(gu.y));
;     uint2 o;
;     o.x = pack2(y0, y1); o.y = pack2(y2, y3);
;     *(uint2*)(p.MIX + (size_t)row * 1024 + c) = o;
	v_pk_fma_f32 v[4:5], v[12:13], v[4:5], v[16:17]
	v_fma_f32 v12, -v38, v27, v39
	v_mul_f32_e32 v8, 0xbfb8aa3b, v4
	v_mul_f32_e32 v9, 0xbfb8aa3b, v5
	v_exp_f32_e32 v8, v8
	v_exp_f32_e32 v9, v9
	v_div_fmas_f32 v12, v12, v43, v27
	v_div_fixup_f32 v22, v12, v22, v33
	v_pk_add_f32 v[8:9], v[8:9], 1.0 op_sel_hi:[1,0]
	s_nop 0
	v_div_scale_f32 v13, s[0:1], v9, v9, v5
	v_rcp_f32_e32 v16, v13
	s_add_u32 s0, s38, s12
	s_addc_u32 s1, s39, s13
	v_fma_f32 v12, -v13, v16, 1.0
	v_fmac_f32_e32 v16, v12, v16
	v_div_scale_f32 v12, vcc, v5, v9, v5
	v_mul_f32_e32 v17, v12, v16
	v_fma_f32 v27, -v13, v17, v12
	v_fmac_f32_e32 v17, v27, v16
	v_div_scale_f32 v27, s[4:5], v8, v8, v4
	v_fma_f32 v12, -v13, v17, v12
	v_rcp_f32_e32 v28, v27
	v_pk_mul_f32 v[6:7], v[6:7], v[26:27] op_sel_hi:[1,0]
	v_div_fmas_f32 v12, v12, v16, v17
	v_pk_fma_f32 v[6:7], v[14:15], v[6:7], v[18:19]
	v_div_fixup_f32 v5, v12, v9, v5
	v_mul_f32_e32 v12, 0xbfb8aa3b, v6
	v_mul_f32_e32 v13, 0xbfb8aa3b, v7
	v_exp_f32_e32 v12, v12
	v_exp_f32_e32 v13, v13
	v_fma_f32 v9, -v27, v28, 1.0
	v_fmac_f32_e32 v28, v9, v28
	v_div_scale_f32 v9, vcc, v4, v8, v4
	v_mul_f32_e32 v16, v9, v28
	v_fma_f32 v14, -v27, v16, v9
	v_pk_add_f32 v[12:13], v[12:13], 1.0 op_sel_hi:[1,0]
	v_fmac_f32_e32 v16, v14, v28
	v_div_scale_f32 v14, s[4:5], v13, v13, v7
	v_rcp_f32_e32 v15, v14
	v_fma_f32 v9, -v27, v16, v9
	v_div_fmas_f32 v9, v9, v28, v16
	v_div_fixup_f32 v4, v9, v8, v4
	v_fma_f32 v8, -v14, v15, 1.0
	v_fmac_f32_e32 v15, v8, v15
	v_div_scale_f32 v8, vcc, v7, v13, v7
	v_mul_f32_e32 v9, v8, v15
	v_fma_f32 v16, -v14, v9, v8
	v_fmac_f32_e32 v9, v16, v15
	v_fma_f32 v8, -v14, v9, v8
	v_div_scale_f32 v14, s[4:5], v12, v12, v6
	v_rcp_f32_e32 v16, v14
	v_div_fmas_f32 v8, v8, v15, v9
	v_div_fixup_f32 v7, v8, v13, v7
	v_pk_mul_f32 v[4:5], v[4:5], v[20:21]
	v_fma_f32 v8, -v14, v16, 1.0
	v_fmac_f32_e32 v16, v8, v16
	v_div_scale_f32 v8, vcc, v6, v12, v6
	v_mul_f32_e32 v9, v8, v16
	v_fma_f32 v13, -v14, v9, v8
	v_fmac_f32_e32 v9, v13, v16
	v_fma_f32 v8, -v14, v9, v8
	v_div_fmas_f32 v8, v8, v16, v9
	v_div_fixup_f32 v6, v8, v12, v6
	v_pk_mul_f32 v[6:7], v[6:7], v[22:23]
	v_cvt_pk_bf16_f32 v4, v4, v5
	v_cvt_pk_bf16_f32 v5, v6, v7
	global_store_dwordx2 v32, v[4:5], s[0:1] sc1
	global_load_dwordx4 v[2:5], v[2:3], off offset:1024
	s_nop 0
	global_load_dwordx4 v[6:9], v[0:1], off offset:1024
	s_nop 0
	global_load_dwordx2 v[0:1], v32, s[10:11] offset:2560
	v_pk_mul_f32 v[12:13], v[24:25], v[26:27] op_sel_hi:[1,0]
	v_pk_mul_f32 v[10:11], v[10:11], v[26:27] op_sel_hi:[1,0]
	s_waitcnt vmcnt(1)
	v_pk_fma_f32 v[2:3], v[12:13], v[2:3], v[6:7]
	s_nop 0
	v_mul_f32_e32 v6, 0xbfb8aa3b, v2
	v_mul_f32_e32 v7, 0xbfb8aa3b, v3
	v_exp_f32_e32 v6, v6
	v_exp_f32_e32 v7, v7
	s_waitcnt vmcnt(0)
	v_lshlrev_b32_e32 v14, 16, v0
	v_and_b32_e32 v0, 0xffff0000, v0
	v_mul_f32_e32 v12, 0xbfb8aa3b, v14
	v_pk_add_f32 v[6:7], v[6:7], 1.0 op_sel_hi:[1,0]
	v_exp_f32_e32 v12, v12
	v_div_scale_f32 v13, s[4:5], v7, v7, v3
	v_rcp_f32_e32 v15, v13
	v_div_scale_f32 v16, vcc, v3, v7, v3
	v_pk_fma_f32 v[4:5], v[10:11], v[4:5], v[8:9]
	v_fma_f32 v17, -v13, v15, 1.0
	v_fmac_f32_e32 v15, v17, v15
	v_mul_f32_e32 v17, v16, v15
	v_fma_f32 v18, -v13, v17, v16
	v_fmac_f32_e32 v17, v18, v15
	v_fma_f32 v13, -v13, v17, v16
	v_div_scale_f32 v16, s[4:5], v6, v6, v2
	v_rcp_f32_e32 v18, v16
	v_div_fmas_f32 v13, v13, v15, v17
	v_div_fixup_f32 v3, v13, v7, v3
	v_mul_f32_e32 v13, 0xbfb8aa3b, v0
	v_fma_f32 v7, -v16, v18, 1.0
	v_exp_f32_e32 v13, v13
	v_fmac_f32_e32 v18, v7, v18
	v_div_scale_f32 v7, vcc, v2, v6, v2
	v_mul_f32_e32 v15, v7, v18
	v_fma_f32 v17, -v16, v15, v7
	v_fmac_f32_e32 v15, v17, v18
	v_pk_add_f32 v[12:13], v[12:13], 1.0 op_sel_hi:[1,0]
	v_fma_f32 v7, -v16, v15, v7
	v_div_scale_f32 v16, s[4:5], v13, v13, v0
	v_rcp_f32_e32 v17, v16
	v_div_fmas_f32 v7, v7, v18, v15
	v_div_fixup_f32 v2, v7, v6, v2
	v_lshlrev_b32_e32 v10, 16, v1
	v_fma_f32 v6, -v16, v17, 1.0
	v_fmac_f32_e32 v17, v6, v17
	v_div_scale_f32 v6, vcc, v0, v13, v0
	v_mul_f32_e32 v7, v6, v17
	v_fma_f32 v15, -v16, v7, v6
	v_fmac_f32_e32 v7, v15, v17
	v_div_scale_f32 v15, s[4:5], v12, v12, v14
	v_fma_f32 v6, -v16, v7, v6
	v_rcp_f32_e32 v16, v15
	v_div_fmas_f32 v6, v6, v17, v7
	v_div_fixup_f32 v7, v6, v13, v0
	v_and_b32_e32 v11, 0xffff0000, v1
	v_fma_f32 v0, -v15, v16, 1.0
	v_fmac_f32_e32 v16, v0, v16
	v_div_scale_f32 v0, vcc, v14, v12, v14
	v_mul_f32_e32 v6, v0, v16
	v_fma_f32 v13, -v15, v6, v0
	v_fmac_f32_e32 v6, v13, v16
	v_fma_f32 v0, -v15, v6, v0
	v_div_fmas_f32 v0, v0, v16, v6
	v_mul_f32_e32 v6, 0xbfb8aa3b, v4
	v_exp_f32_e32 v8, v6
	v_mul_f32_e32 v6, 0xbfb8aa3b, v5
	v_exp_f32_e32 v9, v6
	v_div_fixup_f32 v6, v0, v12, v14
	v_pk_mul_f32 v[2:3], v[2:3], v[6:7]
	v_mul_f32_e32 v0, 0xbfb8aa3b, v10
	v_pk_add_f32 v[6:7], v[8:9], 1.0 op_sel_hi:[1,0]
	v_exp_f32_e32 v0, v0
	v_div_scale_f32 v8, s[4:5], v7, v7, v5
	v_rcp_f32_e32 v9, v8
	v_cvt_pk_bf16_f32 v2, v2, v3
	v_fma_f32 v1, -v8, v9, 1.0
	v_fmac_f32_e32 v9, v1, v9
	v_div_scale_f32 v1, vcc, v5, v7, v5
	v_mul_f32_e32 v12, v1, v9
	v_fma_f32 v13, -v8, v12, v1
	v_fmac_f32_e32 v12, v13, v9
	v_fma_f32 v1, -v8, v12, v1
	v_div_scale_f32 v8, s[4:5], v6, v6, v4
	v_rcp_f32_e32 v13, v8
	v_div_fmas_f32 v1, v1, v9, v12
	v_div_fixup_f32 v5, v1, v7, v5
	v_div_scale_f32 v7, vcc, v4, v6, v4
	v_fma_f32 v1, -v8, v13, 1.0
	v_fmac_f32_e32 v13, v1, v13
	v_mul_f32_e32 v1, 0xbfb8aa3b, v11
	v_exp_f32_e32 v1, v1
	v_mul_f32_e32 v9, v7, v13
	v_fma_f32 v12, -v8, v9, v7
	v_fmac_f32_e32 v9, v12, v13
	v_pk_add_f32 v[0:1], v[0:1], 1.0 op_sel_hi:[1,0]
	v_fma_f32 v7, -v8, v9, v7
	v_div_scale_f32 v8, s[4:5], v1, v1, v11
	v_rcp_f32_e32 v12, v8
	v_div_fmas_f32 v7, v7, v13, v9
	v_div_fixup_f32 v4, v7, v6, v4
	v_fma_f32 v6, -v8, v12, 1.0
	v_fmac_f32_e32 v12, v6, v12
	v_div_scale_f32 v6, vcc, v11, v1, v11
	v_mul_f32_e32 v7, v6, v12
	v_fma_f32 v9, -v8, v7, v6
	v_fmac_f32_e32 v7, v9, v12
	v_fma_f32 v6, -v8, v7, v6
	v_div_scale_f32 v8, s[4:5], v0, v0, v10
	v_rcp_f32_e32 v9, v8
	v_div_fmas_f32 v6, v6, v12, v7
	v_div_fixup_f32 v1, v6, v1, v11
	v_fma_f32 v6, -v8, v9, 1.0
	v_fmac_f32_e32 v9, v6, v9
	v_div_scale_f32 v6, vcc, v10, v0, v10
	v_mul_f32_e32 v7, v6, v9
	v_fma_f32 v11, -v8, v7, v6
	v_fmac_f32_e32 v7, v11, v9
	v_fma_f32 v6, -v8, v7, v6
	v_div_fmas_f32 v6, v6, v9, v7
	v_div_fixup_f32 v0, v6, v0, v10
	v_pk_mul_f32 v[0:1], v[4:5], v[0:1]
	s_nop 0
	v_cvt_pk_bf16_f32 v3, v0, v1
	global_store_dwordx2 v32, v[2:3], s[0:1] offset:512 sc1

; DI void branch_a_final_row(const Params& p, int row, int lane) {
;   const float* cr = p.CONV + (size_t)row * 512;
;   float4 v[2];
;   float s = 0.f;
; #pragma unroll
;   for (int j = 0; j < 2; ++j) {
;     v[j] = ((const float4*)cr)[j * 64 + lane];
;     s += v[j].x + v[j].y + v[j].z + v[j].w;
;   }
;   float mean = wave_sum(s) * (1.0f / 512.0f);
;   float vs = 0.f;
; #pragma unroll
;   for (int j = 0; j < 2; ++j) {
;     v[j].x -= mean; v[j].y -= mean; v[j].z -= mean; v[j].w -= mean;
;     vs += v[j].x * v[j].x + v[j].y * v[j].y + v[j].z * v[j].z + v[j].w * v[j].w;
;   }
;   float inv = rsqrtf(wave_sum(vs) * (1.0f / 512.0f) + EPSF);
; #pragma unroll
;   for (int j = 0; j < 2; ++j) {
;     int c = (j * 64 + lane) * 4;
;     float4 g = *(const float4*)(p.ln_a_g + c), bb = *(const float4*)(p.ln_a_b + c);
;     uint2 gu = *(const uint2*)(p.PB + (size_t)row * EINP + 1024 + c);
; DI void branch_a_unit(const Params& p, int u, char* smem) {
;     ...
;     for (int k = wid; k < 32; k += 4) branch_a_final_row(p, row0 + k, lane);
.LBB0_560:
	v_lshl_add_u64 v[30:31], v[22:23], 0, v[20:21]
	global_load_dwordx4 v[0:3], v[16:17], off
	global_load_dwordx4 v[4:7], v[18:19], off
	global_load_dwordx4 v[8:11], v[26:27], off offset:-1024
	global_load_dwordx4 v[12:15], v[26:27], off
	global_load_dwordx2 v[34:35], v[30:31], off offset:2048
	v_mov_b32_e32 v33, v60
	v_mov_b32_e32 v42, v60
	v_add_u32_e32 v32, 4, v32
	v_cmp_lt_i32_e32 vcc, 27, v32
	s_or_b64 s[18:19], vcc, s[18:19]
	v_mov_b32_e32 v46, v60
	v_mov_b32_e32 v47, v60
	v_lshl_add_u64 v[28:29], v[24:25], 0, v[20:21]
	v_lshl_add_u64 v[22:23], v[22:23], 0, s[48:49]
	v_lshl_add_u64 v[24:25], v[24:25], 0, s[50:51]
	v_lshl_add_u64 v[26:27], v[26:27], 0, s[50:51]
	s_waitcnt vmcnt(2)
	v_mov_b32_e32 v36, v9
	v_mov_b32_e32 v38, v10
	s_waitcnt vmcnt(0)
	v_lshlrev_b32_e32 v48, 16, v34
	v_and_b32_e32 v49, 0xffff0000, v34
	v_lshlrev_b32_e32 v50, 16, v35
	v_and_b32_e32 v51, 0xffff0000, v35
	v_pk_add_f32 v[34:35], v[8:9], v[36:37]
	v_mov_b32_e32 v39, v13
	v_mul_f32_e32 v36, 0xbfb8aa3b, v48
	v_mul_f32_e32 v37, 0xbfb8aa3b, v49
	v_mov_b32_e32 v35, v12
	v_mul_f32_e32 v43, 0xbfb8aa3b, v50
	v_mul_f32_e32 v44, 0xbfb8aa3b, v51
	v_pk_mov_b32 v[40:41], v[10:11], v[14:15] op_sel:[1,0]
	v_exp_f32_e32 v36, v36
	v_exp_f32_e32 v37, v37
	v_pk_add_f32 v[34:35], v[34:35], v[38:39]
	v_exp_f32_e32 v38, v43
	v_exp_f32_e32 v39, v44
	v_mov_b32_e32 v61, v15
	v_pk_add_f32 v[34:35], v[34:35], v[40:41]
	s_nop 0
	v_pk_add_f32 v[34:35], v[34:35], v[60:61]
	s_nop 0
	v_add_f32_e32 v40, v34, v35
	v_pk_add_f32 v[34:35], v[36:37], 1.0 op_sel_hi:[1,0]
	v_pk_add_f32 v[36:37], v[38:39], 1.0 op_sel_hi:[1,0]
	v_add_f32_dpp v40, v40, v40 quad_perm:[1,0,3,2] row_mask:0xf bank_mask:0xf bound_ctrl:1
	v_div_scale_f32 v39, s[0:1], v35, v35, v49
	v_div_scale_f32 v43, s[0:1], v34, v34, v48
	v_add_f32_dpp v38, v40, v40 quad_perm:[2,3,0,1] row_mask:0xf bank_mask:0xf bound_ctrl:1
	v_div_scale_f32 v40, s[4:5], v37, v37, v51
	v_div_scale_f32 v52, s[6:7], v36, v36, v50
	v_rcp_f32_e32 v54, v39
	v_rcp_f32_e32 v55, v43
	v_add_f32_dpp v38, v38, v38 row_half_mirror row_mask:0xf bank_mask:0xf bound_ctrl:1
	v_rcp_f32_e32 v56, v40
	v_rcp_f32_e32 v57, v52
	v_add_f32_dpp v38, v38, v38 row_mirror row_mask:0xf bank_mask:0xf bound_ctrl:1
	v_fma_f32 v58, -v43, v55, 1.0
	v_fma_f32 v59, -v40, v56, 1.0
	v_mov_b32_dpp v33, v38 row_bcast:15 row_mask:0xa bank_mask:0xf
	v_add_f32_e32 v33, v38, v33
	v_fma_f32 v38, -v39, v54, 1.0
	v_div_scale_f32 v41, vcc, v49, v35, v49
	v_mov_b32_dpp v42, v33 row_bcast:31 row_mask:0xc bank_mask:0xf
	v_div_scale_f32 v44, s[0:1], v48, v34, v48
	v_div_scale_f32 v45, s[4:5], v51, v37, v51
	v_fma_f32 v61, -v52, v57, 1.0
	v_fmac_f32_e32 v54, v38, v54
	v_fmac_f32_e32 v55, v58, v55
	v_add_f32_e32 v33, v33, v42
	v_fmac_f32_e32 v56, v59, v56
	v_div_scale_f32 v53, s[6:7], v50, v36, v50
	v_fmac_f32_e32 v57, v61, v57
	v_mul_f32_e32 v58, v41, v54
	v_mul_f32_e32 v59, v44, v55
	v_readlane_b32 s2, v33, 63
	v_mul_f32_e32 v33, v45, v56
	v_mul_f32_e32 v61, v53, v57
	v_fma_f32 v42, -v39, v58, v41
	v_fma_f32 v88, -v43, v59, v44
	v_mul_f32_e32 v38, s2, v97
	v_fma_f32 v89, -v40, v33, v45
	v_fma_f32 v90, -v52, v61, v53
	v_fmac_f32_e32 v58, v42, v54
	v_fmac_f32_e32 v59, v88, v55
	v_pk_add_f32 v[8:9], v[8:9], v[38:39] op_sel_hi:[1,0] neg_lo:[0,1] neg_hi:[0,1]
	v_fmac_f32_e32 v33, v89, v56
	v_pk_add_f32 v[12:13], v[12:13], v[38:39] op_sel_hi:[1,0] neg_lo:[0,1] neg_hi:[0,1]
	v_fmac_f32_e32 v61, v90, v57
	v_fma_f32 v88, -v39, v58, v41
	v_fma_f32 v89, -v43, v59, v44
	v_fma_f32 v90, -v40, v33, v45
	v_mov_b32_e32 v44, v9
	v_mov_b32_e32 v45, v13
	v_pk_add_f32 v[10:11], v[10:11], v[38:39] op_sel_hi:[1,0] neg_lo:[0,1] neg_hi:[0,1]
	v_pk_add_f32 v[14:15], v[14:15], v[38:39] op_sel_hi:[1,0] neg_lo:[0,1] neg_hi:[0,1]
	v_fma_f32 v52, -v52, v61, v53
	v_mov_b32_e32 v42, v8
	v_mov_b32_e32 v43, v12
	v_div_fmas_f32 v53, v88, v54, v58
	v_pk_mul_f32 v[44:45], v[44:45], v[44:45]
	s_mov_b64 vcc, s[0:1]
	v_mov_b32_e32 v38, v10
	v_mov_b32_e32 v39, v14
	v_div_fixup_f32 v35, v53, v35, v49
	v_div_fmas_f32 v49, v89, v55, v59
	v_pk_fma_f32 v[42:43], v[42:43], v[42:43], v[44:45]
	s_mov_b64 vcc, s[4:5]
	v_mov_b32_e32 v40, v11
	v_mov_b32_e32 v41, v15
	v_div_fmas_f32 v33, v90, v56, v33
	v_pk_fma_f32 v[38:39], v[38:39], v[38:39], v[42:43]
	s_mov_b64 vcc, s[6:7]
	v_div_fixup_f32 v37, v33, v37, v51
	v_div_fmas_f32 v33, v52, v57, v61
	v_pk_fma_f32 v[38:39], v[40:41], v[40:41], v[38:39]
	v_div_fixup_f32 v36, v33, v36, v50
	v_add_f32_e32 v33, v38, v39
	v_div_fixup_f32 v34, v49, v34, v48
	s_nop 0
	v_add_f32_dpp v33, v33, v33 quad_perm:[1,0,3,2] row_mask:0xf bank_mask:0xf bound_ctrl:1
	s_nop 1
	v_add_f32_dpp v33, v33, v33 quad_perm:[2,3,0,1] row_mask:0xf bank_mask:0xf bound_ctrl:1
	s_nop 1
	v_add_f32_dpp v33, v33, v33 row_half_mirror row_mask:0xf bank_mask:0xf bound_ctrl:1
	s_nop 1
	v_add_f32_dpp v33, v33, v33 row_mirror row_mask:0xf bank_mask:0xf bound_ctrl:1
	s_nop 1
	v_mov_b32_dpp v46, v33 row_bcast:15 row_mask:0xa bank_mask:0xf
	v_add_f32_e32 v33, v33, v46
	s_nop 1
	v_mov_b32_dpp v47, v33 row_bcast:31 row_mask:0xc bank_mask:0xf
	v_add_f32_e32 v33, v33, v47
	s_nop 0
	v_readlane_b32 s0, v33, 63
	s_nop 1
	v_fma_f32 v33, s0, v97, v63
	v_mul_f32_e32 v38, 0x4b800000, v33
	v_cmp_gt_f32_e32 vcc, s65, v33
	s_nop 1
	v_cndmask_b32_e32 v33, v33, v38, vcc
	v_rsq_f32_e32 v33, v33
	s_nop 0
	v_mul_f32_e32 v38, 0x45800000, v33
	v_cndmask_b32_e32 v38, v33, v38, vcc
	v_pk_mul_f32 v[8:9], v[8:9], v[38:39] op_sel_hi:[1,0]
	v_pk_mul_f32 v[10:11], v[10:11], v[38:39] op_sel_hi:[1,0]
	v_pk_fma_f32 v[0:1], v[0:1], v[8:9], v[4:5]
	v_pk_fma_f32 v[2:3], v[2:3], v[10:11], v[6:7]
	v_mul_f32_e32 v4, 0xbfb8aa3b, v0
	v_mul_f32_e32 v5, 0xbfb8aa3b, v1
	v_exp_f32_e32 v4, v4
; DI float bflo(unsigned u) { return __uint_as_float(u << 16); }
; DI float bfhi(unsigned u) { return __uint_as_float(u & 0xffff0000u); }
; DI float siluf_(float x) { return x / (1.0f + __expf(-x)); }
; DI void branch_a_final_row(const Params& p, int row, int lane) {
;     ...
;     float y0 = siluf_(v[j].x * inv * g.x + bb.x) * siluf_(bflo(gu.x));
;     float y1 = siluf_(v[j].y * inv * g.y + bb.y) * siluf_(bfhi(gu.x));
;     float y2 = siluf_(v[j].z * inv * g.z + bb.z) * siluf_(bflo(gu.y));
;     float y3 = siluf_(v[j].w * inv * g.w + bb.w) * siluf_(bfhi(gu.y));
;     uint2 o;
;     o.x = pack2(y0, y1); o.y = pack2(y2, y3);
;     *(uint2*)(p.MIX + (size_t)row * 1024 + c) = o;
;   }
	v_exp_f32_e32 v5, v5
	v_mul_f32_e32 v6, 0xbfb8aa3b, v2
	v_mul_f32_e32 v7, 0xbfb8aa3b, v3
	v_exp_f32_e32 v6, v6
	v_exp_f32_e32 v7, v7
	v_pk_add_f32 v[4:5], v[4:5], 1.0 op_sel_hi:[1,0]
	v_pk_mul_f32 v[12:13], v[12:13], v[38:39] op_sel_hi:[1,0]
	v_div_scale_f32 v8, s[0:1], v5, v5, v1
	v_pk_add_f32 v[6:7], v[6:7], 1.0 op_sel_hi:[1,0]
	v_div_scale_f32 v10, s[0:1], v4, v4, v0
	v_rcp_f32_e32 v41, v8
	v_div_scale_f32 v33, s[4:5], v7, v7, v3
	v_rcp_f32_e32 v42, v10
	v_pk_mul_f32 v[14:15], v[14:15], v[38:39] op_sel_hi:[1,0]
	v_div_scale_f32 v39, s[6:7], v6, v6, v2
	v_rcp_f32_e32 v43, v33
	v_rcp_f32_e32 v44, v39
	v_fma_f32 v45, -v8, v41, 1.0
	v_div_scale_f32 v9, vcc, v1, v5, v1
	v_fma_f32 v46, -v10, v42, 1.0
	v_fmac_f32_e32 v41, v45, v41
	v_div_scale_f32 v11, s[0:1], v0, v4, v0
	v_fma_f32 v47, -v33, v43, 1.0
	v_fmac_f32_e32 v42, v46, v42
	v_mul_f32_e32 v45, v9, v41
	v_div_scale_f32 v38, s[4:5], v3, v7, v3
	v_fma_f32 v48, -v39, v44, 1.0
	v_fmac_f32_e32 v43, v47, v43
	v_mul_f32_e32 v46, v11, v42
	v_fma_f32 v49, -v8, v45, v9
	v_div_scale_f32 v40, s[6:7], v2, v6, v2
	v_fmac_f32_e32 v44, v48, v44
	v_mul_f32_e32 v47, v38, v43
	v_fma_f32 v50, -v10, v46, v11
	v_fmac_f32_e32 v45, v49, v41
	v_mul_f32_e32 v48, v40, v44
	v_fma_f32 v51, -v33, v47, v38
	v_fmac_f32_e32 v46, v50, v42
	v_fma_f32 v8, -v8, v45, v9
	v_fma_f32 v52, -v39, v48, v40
	v_fmac_f32_e32 v47, v51, v43
	v_fma_f32 v9, -v10, v46, v11
	v_div_fmas_f32 v8, v8, v41, v45
	s_mov_b64 vcc, s[0:1]
	v_fmac_f32_e32 v48, v52, v44
	v_fma_f32 v10, -v33, v47, v38
	v_div_fixup_f32 v1, v8, v5, v1
	v_div_fmas_f32 v5, v9, v42, v46
	s_mov_b64 vcc, s[4:5]
	v_fma_f32 v11, -v39, v48, v40
	v_div_fixup_f32 v0, v5, v4, v0
	v_div_fmas_f32 v4, v10, v43, v47
	s_mov_b64 vcc, s[6:7]
	v_div_fixup_f32 v3, v4, v7, v3
	v_div_fmas_f32 v4, v11, v44, v48
	v_div_fixup_f32 v2, v4, v6, v2
	v_pk_mul_f32 v[0:1], v[0:1], v[34:35]
	v_pk_mul_f32 v[2:3], v[2:3], v[36:37]
	v_cvt_pk_bf16_f32 v0, v0, v1
	v_cvt_pk_bf16_f32 v1, v2, v3
	global_store_dwordx2 v[28:29], v[0:1], off sc1
	global_load_dwordx4 v[0:3], v[16:17], off offset:1024
	s_nop 0
	global_load_dwordx4 v[4:7], v[18:19], off offset:1024
	global_load_dwordx2 v[8:9], v[30:31], off offset:2560
	s_waitcnt vmcnt(1)
	v_pk_fma_f32 v[0:1], v[12:13], v[0:1], v[4:5]
	s_waitcnt vmcnt(0)
	v_lshlrev_b32_e32 v12, 16, v8
	v_pk_fma_f32 v[2:3], v[14:15], v[2:3], v[6:7]
	v_mul_f32_e32 v4, 0xbfb8aa3b, v0
	v_mul_f32_e32 v5, 0xbfb8aa3b, v12
	v_mul_f32_e32 v7, 0xbfb8aa3b, v1
	v_and_b32_e32 v13, 0xffff0000, v8
	v_exp_f32_e32 v4, v4
	v_exp_f32_e32 v6, v5
	v_exp_f32_e32 v5, v7
	v_mul_f32_e32 v8, 0xbfb8aa3b, v13
	v_exp_f32_e32 v7, v8
	v_lshlrev_b32_e32 v14, 16, v9
	v_and_b32_e32 v15, 0xffff0000, v9
	v_mul_f32_e32 v9, 0xbfb8aa3b, v2
	v_mul_f32_e32 v11, 0xbfb8aa3b, v3
	v_mul_f32_e32 v30, 0xbfb8aa3b, v15
	v_exp_f32_e32 v8, v9
	v_exp_f32_e32 v9, v11
	v_pk_add_f32 v[4:5], v[4:5], 1.0 op_sel_hi:[1,0]
	v_mul_f32_e32 v10, 0xbfb8aa3b, v14
	v_exp_f32_e32 v11, v30
	v_div_scale_f32 v30, s[0:1], v5, v5, v1
	v_exp_f32_e32 v10, v10
	v_pk_add_f32 v[6:7], v[6:7], 1.0 op_sel_hi:[1,0]
	v_div_scale_f32 v33, s[0:1], v4, v4, v0
	v_rcp_f32_e32 v47, v30
	v_div_scale_f32 v35, s[4:5], v7, v7, v13
	v_rcp_f32_e32 v48, v33
	v_pk_add_f32 v[8:9], v[8:9], 1.0 op_sel_hi:[1,0]
	v_div_scale_f32 v37, s[6:7], v6, v6, v12
	v_rcp_f32_e32 v49, v35
	v_div_scale_f32 v39, s[8:9], v9, v9, v3
	v_rcp_f32_e32 v50, v37
	v_pk_add_f32 v[10:11], v[10:11], 1.0 op_sel_hi:[1,0]
	v_div_scale_f32 v41, s[10:11], v8, v8, v2
	v_rcp_f32_e32 v51, v39
	v_fma_f32 v55, -v30, v47, 1.0
	v_div_scale_f32 v31, vcc, v1, v5, v1
	v_div_scale_f32 v43, s[12:13], v11, v11, v15
	v_rcp_f32_e32 v52, v41
	v_fma_f32 v56, -v33, v48, 1.0
	v_fmac_f32_e32 v47, v55, v47
	v_div_scale_f32 v34, s[0:1], v0, v4, v0
	v_div_scale_f32 v45, s[14:15], v10, v10, v14
	v_rcp_f32_e32 v53, v43
	v_fma_f32 v57, -v35, v49, 1.0
	v_fmac_f32_e32 v48, v56, v48
	v_mul_f32_e32 v55, v31, v47
	v_div_scale_f32 v36, s[4:5], v13, v7, v13
	v_rcp_f32_e32 v54, v45
	v_fma_f32 v58, -v37, v50, 1.0
	v_fmac_f32_e32 v49, v57, v49
	v_mul_f32_e32 v56, v34, v48
	v_fma_f32 v90, -v30, v55, v31
	v_div_scale_f32 v38, s[6:7], v12, v6, v12
	v_fma_f32 v59, -v39, v51, 1.0
	v_fmac_f32_e32 v50, v58, v50
	v_mul_f32_e32 v57, v36, v49
	v_fma_f32 v91, -v33, v56, v34
	v_fmac_f32_e32 v55, v90, v47
	v_div_scale_f32 v40, s[8:9], v3, v9, v3
	v_fma_f32 v61, -v41, v52, 1.0
	v_fmac_f32_e32 v51, v59, v51
	v_mul_f32_e32 v58, v38, v50
	v_fma_f32 v92, -v35, v57, v36
	v_fmac_f32_e32 v56, v91, v48
	v_fma_f32 v30, -v30, v55, v31
	v_div_scale_f32 v42, s[10:11], v2, v8, v2
	v_fma_f32 v88, -v43, v53, 1.0
	v_fmac_f32_e32 v52, v61, v52
	v_mul_f32_e32 v59, v40, v51
	v_fma_f32 v93, -v37, v58, v38
	v_fmac_f32_e32 v57, v92, v49
	v_fma_f32 v31, -v33, v56, v34
	v_div_fmas_f32 v30, v30, v47, v55
	s_mov_b64 vcc, s[0:1]
	v_div_scale_f32 v44, s[12:13], v15, v11, v15
	v_fma_f32 v89, -v45, v54, 1.0
	v_fmac_f32_e32 v53, v88, v53
	v_mul_f32_e32 v61, v42, v52
	v_fma_f32 v94, -v39, v59, v40
	v_fmac_f32_e32 v58, v93, v50
	v_fma_f32 v33, -v35, v57, v36
	v_div_fixup_f32 v1, v30, v5, v1
	v_div_fmas_f32 v5, v31, v48, v56
	s_mov_b64 vcc, s[4:5]
	v_div_scale_f32 v46, s[14:15], v14, v10, v14
	v_fmac_f32_e32 v54, v89, v54
	v_mul_f32_e32 v88, v44, v53
	v_fma_f32 v95, -v41, v61, v42
	v_fmac_f32_e32 v59, v94, v51
	v_fma_f32 v34, -v37, v58, v38
	v_div_fixup_f32 v0, v5, v4, v0
	v_div_fmas_f32 v4, v33, v49, v57
	s_mov_b64 vcc, s[6:7]
	v_mul_f32_e32 v89, v46, v54
	v_fma_f32 v98, -v43, v88, v44
	v_fmac_f32_e32 v61, v95, v52
	v_fma_f32 v35, -v39, v59, v40
	v_div_fixup_f32 v5, v4, v7, v13
	v_div_fmas_f32 v4, v34, v50, v58
	s_mov_b64 vcc, s[8:9]
	v_fma_f32 v99, -v45, v89, v46
	v_fmac_f32_e32 v88, v98, v53
	v_fma_f32 v36, -v41, v61, v42
	v_div_fixup_f32 v4, v4, v6, v12
	v_div_fmas_f32 v6, v35, v51, v59
	s_mov_b64 vcc, s[10:11]
	v_fmac_f32_e32 v89, v99, v54
	v_fma_f32 v37, -v43, v88, v44
	v_pk_mul_f32 v[0:1], v[0:1], v[4:5]
	v_div_fmas_f32 v4, v36, v52, v61
	s_mov_b64 vcc, s[12:13]
	v_fma_f32 v38, -v45, v89, v46
	v_div_fixup_f32 v2, v4, v8, v2
	v_div_fmas_f32 v4, v37, v53, v88
	s_mov_b64 vcc, s[14:15]
	v_cvt_pk_bf16_f32 v0, v0, v1
	v_div_fmas_f32 v1, v38, v54, v89
	v_div_fixup_f32 v3, v6, v9, v3
	v_div_fixup_f32 v5, v4, v11, v15
	v_div_fixup_f32 v4, v1, v10, v14
	v_pk_mul_f32 v[2:3], v[2:3], v[4:5]
	s_nop 0
	v_cvt_pk_bf16_f32 v1, v2, v3
	global_store_dwordx2 v[28:29], v[0:1], off offset:512 sc1
	s_andn2_b64 exec, exec, s[18:19]
	s_cbranch_execnz .LBB0_560
	s_branch .LBB0_515

; DI void branch_a_final_row(const Params& p, int row, int lane) {
;   const float* cr = p.CONV + (size_t)row * 512;
;   float4 v[2];
;   float s = 0.f;
; #pragma unroll
;   for (int j = 0; j < 2; ++j) {
;     v[j] = ((const float4*)cr)[j * 64 + lane];
;     s += v[j].x + v[j].y + v[j].z + v[j].w;
;   }
;   float mean = wave_sum(s) * (1.0f / 512.0f);
;   float vs = 0.f;
; #pragma unroll
;   for (int j = 0; j < 2; ++j) {
;     v[j].x -= mean; v[j].y -= mean; v[j].z -= mean; v[j].w -= mean;
;     vs += v[j].x * v[j].x + v[j].y * v[j].y + v[j].z * v[j].z + v[j].w * v[j].w;
;   }
;   float inv = rsqrtf(wave_sum(vs) * (1.0f / 512.0f) + EPSF);
; #pragma unroll
;   for (int j = 0; j < 2; ++j) {
;     int c = (j * 64 + lane) * 4;
;     float4 g = *(const float4*)(p.ln_a_g + c), bb = *(const float4*)(p.ln_a_b + c);
;     uint2 gu = *(const uint2*)(p.PB + (size_t)row * EINP + 1024 + c);
; DI void branch_a_unit(const Params& p, int u, char* smem) {
;     ...
;     conv_a_sample_item(p, u - 512);
;     __syncthreads();
;     if (wid == 0) branch_a_final_row(p, NPR + (u - 512), lane);
.LBB0_648:
	v_add_u32_e32 v2, s5, v62
	v_mov_b32_e32 v3, v60
	v_lshl_add_u64 v[2:3], v[2:3], 2, s[52:53]
	v_cmp_gt_u32_e32 vcc, 64, v125
	global_store_dword v[2:3], v9, off
	global_store_dword v[0:1], v8, off offset:1024
	s_barrier
	s_and_saveexec_b64 s[10:11], vcc
	s_cbranch_execz .LBB0_650
	s_mov_b32 s5, s3
	s_lshl_b64 s[14:15], s[4:5], 11
	s_add_u32 s6, s42, s14
	s_addc_u32 s7, s43, s15
	s_mul_hi_u32 s2, s4, 0x1c00
	s_mulk_i32 s4, 0x1c00
	v_lshlrev_b32_e32 v0, 4, v123
	s_add_u32 s12, s48, s4
	global_load_dwordx4 v[4:7], v0, s[6:7]
	global_load_dwordx4 v[8:11], v0, s[6:7] offset:1024
	s_addc_u32 s13, s49, s2
	v_lshlrev_b32_e32 v32, 3, v125
	global_load_dwordx2 v[20:21], v32, s[12:13] offset:2048
	v_lshlrev_b32_e32 v0, 2, v125
	v_mov_b32_e32 v1, v60
	v_lshlrev_b64 v[0:1], 2, v[0:1]
	v_lshl_add_u64 v[2:3], s[30:31], 0, v[0:1]
	v_lshl_add_u64 v[0:1], s[54:55], 0, v[0:1]
	global_load_dwordx4 v[12:15], v[2:3], off
	global_load_dwordx4 v[16:19], v[0:1], off
	v_mov_b32_e32 v28, v60
	v_mov_b32_e32 v29, v60
	s_waitcnt vmcnt(4)
	v_mov_b32_e32 v22, v5
	v_pk_add_f32 v[22:23], v[4:5], v[22:23]
	v_mov_b32_e32 v24, v6
	s_waitcnt vmcnt(3)
	v_mov_b32_e32 v25, v9
	s_waitcnt vmcnt(2)
	v_lshlrev_b32_e32 v30, 16, v20
	v_and_b32_e32 v31, 0xffff0000, v20
	v_lshlrev_b32_e32 v33, 16, v21
	v_and_b32_e32 v34, 0xffff0000, v21
	v_mov_b32_e32 v23, v8
	v_mul_f32_e32 v35, 0xbfb8aa3b, v30
	v_mul_f32_e32 v36, 0xbfb8aa3b, v31
	v_pk_mov_b32 v[26:27], v[6:7], v[10:11] op_sel:[1,0]
	v_pk_add_f32 v[20:21], v[22:23], v[24:25]
	v_mul_f32_e32 v24, 0xbfb8aa3b, v33
	v_mul_f32_e32 v25, 0xbfb8aa3b, v34
	v_exp_f32_e32 v22, v35
	v_exp_f32_e32 v23, v36
	v_mov_b32_e32 v61, v11
	v_pk_add_f32 v[20:21], v[20:21], v[26:27]
	v_exp_f32_e32 v24, v24
	v_exp_f32_e32 v25, v25
	v_pk_add_f32 v[20:21], v[20:21], v[60:61]
	s_nop 0
	v_add_f32_e32 v20, v20, v21
	s_nop 1
	v_add_f32_dpp v26, v20, v20 quad_perm:[1,0,3,2] row_mask:0xf bank_mask:0xf bound_ctrl:1
	v_pk_add_f32 v[20:21], v[22:23], 1.0 op_sel_hi:[1,0]
	v_pk_add_f32 v[22:23], v[24:25], 1.0 op_sel_hi:[1,0]
	v_div_scale_f32 v25, s[4:5], v21, v21, v31
	v_add_f32_dpp v26, v26, v26 quad_perm:[2,3,0,1] row_mask:0xf bank_mask:0xf bound_ctrl:1
	v_div_scale_f32 v35, s[4:5], v20, v20, v30
	v_rcp_f32_e32 v40, v25
	v_add_f32_dpp v24, v26, v26 row_half_mirror row_mask:0xf bank_mask:0xf bound_ctrl:1
	v_div_scale_f32 v26, s[4:5], v23, v23, v34
	v_div_scale_f32 v38, s[4:5], v22, v22, v33
	v_rcp_f32_e32 v41, v35
	v_add_f32_dpp v24, v24, v24 row_mirror row_mask:0xf bank_mask:0xf bound_ctrl:1
	v_rcp_f32_e32 v42, v26
	v_rcp_f32_e32 v43, v38
	v_mov_b32_dpp v28, v24 row_bcast:15 row_mask:0xa bank_mask:0xf
	v_add_f32_e32 v24, v24, v28
	v_fma_f32 v28, -v25, v40, 1.0
	v_div_scale_f32 v27, vcc, v31, v21, v31
	v_mov_b32_dpp v29, v24 row_bcast:31 row_mask:0xc bank_mask:0xf
	v_fma_f32 v44, -v35, v41, 1.0
	v_fmac_f32_e32 v40, v28, v40
	v_div_scale_f32 v36, s[6:7], v30, v20, v30
	v_add_f32_e32 v24, v24, v29
	v_fma_f32 v29, -v26, v42, 1.0
	v_fma_f32 v45, -v38, v43, 1.0
	v_fmac_f32_e32 v41, v44, v41
	v_mul_f32_e32 v28, v27, v40
	v_div_scale_f32 v37, s[8:9], v34, v23, v34
	v_readlane_b32 s2, v24, 63
	v_fmac_f32_e32 v42, v29, v42
	v_fmac_f32_e32 v43, v45, v43
	v_mul_f32_e32 v29, v36, v41
	v_fma_f32 v45, -v25, v28, v27
	v_mul_f32_e32 v24, s2, v177
	v_mul_f32_e32 v44, v37, v42
	v_fma_f32 v46, -v35, v29, v36
	v_fmac_f32_e32 v28, v45, v40
	v_pk_add_f32 v[4:5], v[4:5], v[24:25] op_sel_hi:[1,0] neg_lo:[0,1] neg_hi:[0,1]
	v_pk_add_f32 v[6:7], v[6:7], v[24:25] op_sel_hi:[1,0] neg_lo:[0,1] neg_hi:[0,1]
	v_fma_f32 v47, -v26, v44, v37
	v_fmac_f32_e32 v29, v46, v41
	v_fma_f32 v25, -v25, v28, v27
	v_fmac_f32_e32 v44, v47, v42
	v_fma_f32 v27, -v35, v29, v36
	v_div_fmas_f32 v25, v25, v40, v28
	s_mov_b64 vcc, s[6:7]
	v_fma_f32 v26, -v26, v44, v37
	v_div_fixup_f32 v21, v25, v21, v31
	v_div_fmas_f32 v25, v27, v41, v29
	s_mov_b64 vcc, s[8:9]
	v_div_fixup_f32 v20, v25, v20, v30
	v_div_fmas_f32 v25, v26, v42, v44
	v_div_fixup_f32 v23, v25, v23, v34
	v_pk_add_f32 v[10:11], v[10:11], v[24:25] op_sel_hi:[1,0] neg_lo:[0,1] neg_hi:[0,1]
	v_pk_add_f32 v[24:25], v[8:9], v[24:25] op_sel_hi:[1,0] neg_lo:[0,1] neg_hi:[0,1]
	v_mov_b32_e32 v30, v5
	v_mov_b32_e32 v31, v25
	v_mov_b32_e32 v28, v4
	v_mov_b32_e32 v29, v24
	v_pk_mul_f32 v[30:31], v[30:31], v[30:31]
	v_mov_b32_e32 v8, v6
	v_mov_b32_e32 v9, v10
	v_pk_fma_f32 v[28:29], v[28:29], v[28:29], v[30:31]
	v_mov_b32_e32 v26, v7
	v_mov_b32_e32 v27, v11
	v_pk_fma_f32 v[8:9], v[8:9], v[8:9], v[28:29]
	v_div_scale_f32 v39, s[4:5], v33, v22, v33
	v_pk_fma_f32 v[8:9], v[26:27], v[26:27], v[8:9]
	v_mul_f32_e32 v27, v39, v43
	v_add_f32_e32 v8, v8, v9
	v_mov_b32_e32 v9, v60
	s_nop 0
	v_add_f32_dpp v8, v8, v8 quad_perm:[1,0,3,2] row_mask:0xf bank_mask:0xf bound_ctrl:1
	s_nop 1
	v_add_f32_dpp v8, v8, v8 quad_perm:[2,3,0,1] row_mask:0xf bank_mask:0xf bound_ctrl:1
	s_nop 1
	v_add_f32_dpp v8, v8, v8 row_half_mirror row_mask:0xf bank_mask:0xf bound_ctrl:1
	s_nop 1
	v_add_f32_dpp v8, v8, v8 row_mirror row_mask:0xf bank_mask:0xf bound_ctrl:1
	s_nop 1
	v_mov_b32_dpp v9, v8 row_bcast:15 row_mask:0xa bank_mask:0xf
	v_add_f32_e32 v8, v8, v9
	v_mov_b32_e32 v9, v60
	s_nop 1
	v_mov_b32_dpp v9, v8 row_bcast:31 row_mask:0xc bank_mask:0xf
	v_add_f32_e32 v8, v8, v9
	s_nop 0
	v_readlane_b32 s2, v8, 63
	s_nop 1
	v_fma_f32 v8, s2, v177, v175
	v_mul_f32_e32 v9, 0x4b800000, v8
	v_cmp_gt_f32_e32 vcc, s85, v8
	s_nop 1
	v_cndmask_b32_e32 v8, v8, v9, vcc
	v_rsq_f32_e32 v8, v8
	v_fma_f32 v9, -v38, v27, v39
	v_fmac_f32_e32 v27, v9, v43
	v_mul_f32_e32 v9, 0x45800000, v8
	v_cndmask_b32_e32 v26, v8, v9, vcc
	v_pk_mul_f32 v[4:5], v[4:5], v[26:27] op_sel_hi:[1,0]
	s_mov_b64 vcc, s[4:5]
	s_waitcnt vmcnt(0)
; DI float bflo(unsigned u) { return __uint_as_float(u << 16); }
; DI float bfhi(unsigned u) { return __uint_as_float(u & 0xffff0000u); }
; DI float siluf_(float x) { return x / (1.0f + __expf(-x)); }
; DI void branch_a_final_row(const Params& p, int row, int lane) {
;     ...
;     float y0 = siluf_(v[j].x * inv * g.x + bb.x) * siluf_(bflo(gu.x));
;     float y1 = siluf_(v[j].y * inv * g.y + bb.y) * siluf_(bfhi(gu.x));
;     float y2 = siluf_(v[j].z * inv * g.z + bb.z) * siluf_(bflo(gu.y));
;     float y3 = siluf_(v[j].w * inv * g.w + bb.w) * siluf_(bfhi(gu.y));
;     uint2 o;
;     o.x = pack2(y0, y1); o.y = pack2(y2, y3);
;     *(uint2*)(p.MIX + (size_t)row * 1024 + c) = o;
	v_pk_fma_f32 v[4:5], v[12:13], v[4:5], v[16:17]
	v_fma_f32 v12, -v38, v27, v39
	v_mul_f32_e32 v8, 0xbfb8aa3b, v4
	v_mul_f32_e32 v9, 0xbfb8aa3b, v5
	v_exp_f32_e32 v8, v8
	v_exp_f32_e32 v9, v9
	v_div_fmas_f32 v12, v12, v43, v27
	v_div_fixup_f32 v22, v12, v22, v33
	v_pk_add_f32 v[8:9], v[8:9], 1.0 op_sel_hi:[1,0]
	s_nop 0
	v_div_scale_f32 v13, s[4:5], v9, v9, v5
	v_rcp_f32_e32 v16, v13
	s_add_u32 s4, s50, s14
	s_addc_u32 s5, s51, s15
	v_fma_f32 v12, -v13, v16, 1.0
	v_fmac_f32_e32 v16, v12, v16
	v_div_scale_f32 v12, vcc, v5, v9, v5
	v_mul_f32_e32 v17, v12, v16
	v_fma_f32 v27, -v13, v17, v12
	v_fmac_f32_e32 v17, v27, v16
	v_div_scale_f32 v27, s[6:7], v8, v8, v4
	v_fma_f32 v12, -v13, v17, v12
	v_rcp_f32_e32 v28, v27
	v_pk_mul_f32 v[6:7], v[6:7], v[26:27] op_sel_hi:[1,0]
	v_div_fmas_f32 v12, v12, v16, v17
	v_pk_fma_f32 v[6:7], v[14:15], v[6:7], v[18:19]
	v_div_fixup_f32 v5, v12, v9, v5
	v_mul_f32_e32 v12, 0xbfb8aa3b, v6
	v_mul_f32_e32 v13, 0xbfb8aa3b, v7
	v_exp_f32_e32 v12, v12
	v_exp_f32_e32 v13, v13
	v_fma_f32 v9, -v27, v28, 1.0
	v_fmac_f32_e32 v28, v9, v28
	v_div_scale_f32 v9, vcc, v4, v8, v4
	v_mul_f32_e32 v16, v9, v28
	v_fma_f32 v14, -v27, v16, v9
	v_pk_add_f32 v[12:13], v[12:13], 1.0 op_sel_hi:[1,0]
	v_fmac_f32_e32 v16, v14, v28
	v_div_scale_f32 v14, s[6:7], v13, v13, v7
	v_rcp_f32_e32 v15, v14
	v_fma_f32 v9, -v27, v16, v9
	v_div_fmas_f32 v9, v9, v28, v16
	v_div_fixup_f32 v4, v9, v8, v4
	v_fma_f32 v8, -v14, v15, 1.0
	v_fmac_f32_e32 v15, v8, v15
	v_div_scale_f32 v8, vcc, v7, v13, v7
	v_mul_f32_e32 v9, v8, v15
	v_fma_f32 v16, -v14, v9, v8
	v_fmac_f32_e32 v9, v16, v15
	v_fma_f32 v8, -v14, v9, v8
	v_div_scale_f32 v14, s[6:7], v12, v12, v6
	v_rcp_f32_e32 v16, v14
	v_div_fmas_f32 v8, v8, v15, v9
	v_div_fixup_f32 v7, v8, v13, v7
	v_pk_mul_f32 v[4:5], v[4:5], v[20:21]
	v_fma_f32 v8, -v14, v16, 1.0
	v_fmac_f32_e32 v16, v8, v16
	v_div_scale_f32 v8, vcc, v6, v12, v6
	v_mul_f32_e32 v9, v8, v16
	v_fma_f32 v13, -v14, v9, v8
	v_fmac_f32_e32 v9, v13, v16
	v_fma_f32 v8, -v14, v9, v8
	v_div_fmas_f32 v8, v8, v16, v9
	v_div_fixup_f32 v6, v8, v12, v6
	v_pk_mul_f32 v[6:7], v[6:7], v[22:23]
	v_cvt_pk_bf16_f32 v4, v4, v5
	v_cvt_pk_bf16_f32 v5, v6, v7
	global_store_dwordx2 v32, v[4:5], s[4:5] sc1
	global_load_dwordx4 v[2:5], v[2:3], off offset:1024
	s_nop 0
	global_load_dwordx4 v[6:9], v[0:1], off offset:1024
	s_nop 0
	global_load_dwordx2 v[0:1], v32, s[12:13] offset:2560
	v_pk_mul_f32 v[12:13], v[24:25], v[26:27] op_sel_hi:[1,0]
	v_pk_mul_f32 v[10:11], v[10:11], v[26:27] op_sel_hi:[1,0]
	s_waitcnt vmcnt(1)
	v_pk_fma_f32 v[2:3], v[12:13], v[2:3], v[6:7]
	s_nop 0
	v_mul_f32_e32 v6, 0xbfb8aa3b, v2
	v_mul_f32_e32 v7, 0xbfb8aa3b, v3
	v_exp_f32_e32 v6, v6
	v_exp_f32_e32 v7, v7
	s_waitcnt vmcnt(0)
	v_lshlrev_b32_e32 v14, 16, v0
	v_and_b32_e32 v0, 0xffff0000, v0
	v_mul_f32_e32 v12, 0xbfb8aa3b, v14
	v_pk_add_f32 v[6:7], v[6:7], 1.0 op_sel_hi:[1,0]
	v_exp_f32_e32 v12, v12
	v_div_scale_f32 v13, s[6:7], v7, v7, v3
	v_rcp_f32_e32 v15, v13
	v_div_scale_f32 v16, vcc, v3, v7, v3
	v_pk_fma_f32 v[4:5], v[10:11], v[4:5], v[8:9]
	v_fma_f32 v17, -v13, v15, 1.0
	v_fmac_f32_e32 v15, v17, v15
	v_mul_f32_e32 v17, v16, v15
	v_fma_f32 v18, -v13, v17, v16
	v_fmac_f32_e32 v17, v18, v15
	v_fma_f32 v13, -v13, v17, v16
	v_div_scale_f32 v16, s[6:7], v6, v6, v2
	v_rcp_f32_e32 v18, v16
	v_div_fmas_f32 v13, v13, v15, v17
	v_div_fixup_f32 v3, v13, v7, v3
	v_mul_f32_e32 v13, 0xbfb8aa3b, v0
	v_fma_f32 v7, -v16, v18, 1.0
	v_exp_f32_e32 v13, v13
	v_fmac_f32_e32 v18, v7, v18
	v_div_scale_f32 v7, vcc, v2, v6, v2
	v_mul_f32_e32 v15, v7, v18
	v_fma_f32 v17, -v16, v15, v7
	v_fmac_f32_e32 v15, v17, v18
	v_pk_add_f32 v[12:13], v[12:13], 1.0 op_sel_hi:[1,0]
	v_fma_f32 v7, -v16, v15, v7
	v_div_scale_f32 v16, s[6:7], v13, v13, v0
	v_rcp_f32_e32 v17, v16
	v_div_fmas_f32 v7, v7, v18, v15
	v_div_fixup_f32 v2, v7, v6, v2
	v_lshlrev_b32_e32 v10, 16, v1
	v_fma_f32 v6, -v16, v17, 1.0
	v_fmac_f32_e32 v17, v6, v17
	v_div_scale_f32 v6, vcc, v0, v13, v0
	v_mul_f32_e32 v7, v6, v17
	v_fma_f32 v15, -v16, v7, v6
	v_fmac_f32_e32 v7, v15, v17
	v_div_scale_f32 v15, s[6:7], v12, v12, v14
	v_fma_f32 v6, -v16, v7, v6
	v_rcp_f32_e32 v16, v15
	v_div_fmas_f32 v6, v6, v17, v7
	v_div_fixup_f32 v7, v6, v13, v0
	v_and_b32_e32 v11, 0xffff0000, v1
	v_fma_f32 v0, -v15, v16, 1.0
	v_fmac_f32_e32 v16, v0, v16
	v_div_scale_f32 v0, vcc, v14, v12, v14
	v_mul_f32_e32 v6, v0, v16
	v_fma_f32 v13, -v15, v6, v0
	v_fmac_f32_e32 v6, v13, v16
	v_fma_f32 v0, -v15, v6, v0
	v_div_fmas_f32 v0, v0, v16, v6
	v_mul_f32_e32 v6, 0xbfb8aa3b, v4
	v_exp_f32_e32 v8, v6
	v_mul_f32_e32 v6, 0xbfb8aa3b, v5
	v_exp_f32_e32 v9, v6
	v_div_fixup_f32 v6, v0, v12, v14
	v_pk_mul_f32 v[2:3], v[2:3], v[6:7]
	v_mul_f32_e32 v0, 0xbfb8aa3b, v10
	v_pk_add_f32 v[6:7], v[8:9], 1.0 op_sel_hi:[1,0]
	v_exp_f32_e32 v0, v0
	v_div_scale_f32 v8, s[6:7], v7, v7, v5
	v_rcp_f32_e32 v9, v8
	v_cvt_pk_bf16_f32 v2, v2, v3
	v_fma_f32 v1, -v8, v9, 1.0
	v_fmac_f32_e32 v9, v1, v9
	v_div_scale_f32 v1, vcc, v5, v7, v5
	v_mul_f32_e32 v12, v1, v9
	v_fma_f32 v13, -v8, v12, v1
	v_fmac_f32_e32 v12, v13, v9
	v_fma_f32 v1, -v8, v12, v1
	v_div_scale_f32 v8, s[6:7], v6, v6, v4
	v_rcp_f32_e32 v13, v8
	v_div_fmas_f32 v1, v1, v9, v12
	v_div_fixup_f32 v5, v1, v7, v5
	v_div_scale_f32 v7, vcc, v4, v6, v4
	v_fma_f32 v1, -v8, v13, 1.0
	v_fmac_f32_e32 v13, v1, v13
	v_mul_f32_e32 v1, 0xbfb8aa3b, v11
	v_exp_f32_e32 v1, v1
	v_mul_f32_e32 v9, v7, v13
	v_fma_f32 v12, -v8, v9, v7
	v_fmac_f32_e32 v9, v12, v13
	v_pk_add_f32 v[0:1], v[0:1], 1.0 op_sel_hi:[1,0]
	v_fma_f32 v7, -v8, v9, v7
	v_div_scale_f32 v8, s[6:7], v1, v1, v11
	v_rcp_f32_e32 v12, v8
	v_div_fmas_f32 v7, v7, v13, v9
	v_div_fixup_f32 v4, v7, v6, v4
	v_fma_f32 v6, -v8, v12, 1.0
	v_fmac_f32_e32 v12, v6, v12
	v_div_scale_f32 v6, vcc, v11, v1, v11
	v_mul_f32_e32 v7, v6, v12
	v_fma_f32 v9, -v8, v7, v6
	v_fmac_f32_e32 v7, v9, v12
	v_fma_f32 v6, -v8, v7, v6
	v_div_scale_f32 v8, s[6:7], v0, v0, v10
	v_rcp_f32_e32 v9, v8
	v_div_fmas_f32 v6, v6, v12, v7
	v_div_fixup_f32 v1, v6, v1, v11
	v_fma_f32 v6, -v8, v9, 1.0
	v_fmac_f32_e32 v9, v6, v9
	v_div_scale_f32 v6, vcc, v10, v0, v10
	v_mul_f32_e32 v7, v6, v9
	v_fma_f32 v11, -v8, v7, v6
	v_fmac_f32_e32 v7, v11, v9
	v_fma_f32 v6, -v8, v7, v6
	v_div_fmas_f32 v6, v6, v9, v7
	v_div_fixup_f32 v0, v6, v0, v10
	v_pk_mul_f32 v[0:1], v[4:5], v[0:1]
	s_nop 0
	v_cvt_pk_bf16_f32 v3, v0, v1
	global_store_dwordx2 v32, v[2:3], s[4:5] offset:512 sc1

; DI void branch_a_final_row(const Params& p, int row, int lane) {
;   const float* cr = p.CONV + (size_t)row * 512;
;   float4 v[2];
;   float s = 0.f;
; #pragma unroll
;   for (int j = 0; j < 2; ++j) {
;     v[j] = ((const float4*)cr)[j * 64 + lane];
;     s += v[j].x + v[j].y + v[j].z + v[j].w;
;   }
;   float mean = wave_sum(s) * (1.0f / 512.0f);
;   float vs = 0.f;
; #pragma unroll
;   for (int j = 0; j < 2; ++j) {
;     v[j].x -= mean; v[j].y -= mean; v[j].z -= mean; v[j].w -= mean;
;     vs += v[j].x * v[j].x + v[j].y * v[j].y + v[j].z * v[j].z + v[j].w * v[j].w;
;   }
;   float inv = rsqrtf(wave_sum(vs) * (1.0f / 512.0f) + EPSF);
; #pragma unroll
;   for (int j = 0; j < 2; ++j) {
;     int c = (j * 64 + lane) * 4;
;     float4 g = *(const float4*)(p.ln_a_g + c), bb = *(const float4*)(p.ln_a_b + c);
;     uint2 gu = *(const uint2*)(p.PB + (size_t)row * EINP + 1024 + c);
; DI void branch_a_unit(const Params& p, int u, char* smem) {
;     ...
;     for (int k = wid; k < 32; k += 4) branch_a_final_row(p, row0 + k, lane);
.LBB0_682:
	v_lshl_add_u64 v[30:31], v[22:23], 0, v[20:21]
	global_load_dwordx4 v[0:3], v[16:17], off
	global_load_dwordx4 v[4:7], v[18:19], off
	global_load_dwordx4 v[8:11], v[26:27], off offset:-1024
	global_load_dwordx4 v[12:15], v[26:27], off
	global_load_dwordx2 v[34:35], v[30:31], off offset:2048
	v_mov_b32_e32 v33, v60
	v_mov_b32_e32 v42, v60
	v_add_u32_e32 v32, 4, v32
	v_cmp_lt_i32_e32 vcc, 27, v32
	s_or_b64 s[20:21], vcc, s[20:21]
	v_mov_b32_e32 v46, v60
	v_mov_b32_e32 v47, v60
	v_lshl_add_u64 v[28:29], v[24:25], 0, v[20:21]
	v_lshl_add_u64 v[22:23], v[22:23], 0, s[58:59]
	v_lshl_add_u64 v[24:25], v[24:25], 0, s[60:61]
	v_lshl_add_u64 v[26:27], v[26:27], 0, s[60:61]
	s_waitcnt vmcnt(2)
	v_mov_b32_e32 v36, v9
	v_mov_b32_e32 v38, v10
	s_waitcnt vmcnt(0)
	v_lshlrev_b32_e32 v48, 16, v34
	v_and_b32_e32 v49, 0xffff0000, v34
	v_lshlrev_b32_e32 v50, 16, v35
	v_and_b32_e32 v51, 0xffff0000, v35
	v_pk_add_f32 v[34:35], v[8:9], v[36:37]
	v_mov_b32_e32 v39, v13
	v_mul_f32_e32 v36, 0xbfb8aa3b, v48
	v_mul_f32_e32 v37, 0xbfb8aa3b, v49
	v_mov_b32_e32 v35, v12
	v_mul_f32_e32 v43, 0xbfb8aa3b, v50
	v_mul_f32_e32 v44, 0xbfb8aa3b, v51
	v_pk_mov_b32 v[40:41], v[10:11], v[14:15] op_sel:[1,0]
	v_exp_f32_e32 v36, v36
	v_exp_f32_e32 v37, v37
	v_pk_add_f32 v[34:35], v[34:35], v[38:39]
	v_exp_f32_e32 v38, v43
	v_exp_f32_e32 v39, v44
	v_mov_b32_e32 v61, v15
	v_pk_add_f32 v[34:35], v[34:35], v[40:41]
	s_nop 0
	v_pk_add_f32 v[34:35], v[34:35], v[60:61]
	s_nop 0
	v_add_f32_e32 v40, v34, v35
	v_pk_add_f32 v[34:35], v[36:37], 1.0 op_sel_hi:[1,0]
	v_pk_add_f32 v[36:37], v[38:39], 1.0 op_sel_hi:[1,0]
	v_add_f32_dpp v40, v40, v40 quad_perm:[1,0,3,2] row_mask:0xf bank_mask:0xf bound_ctrl:1
	v_div_scale_f32 v39, s[4:5], v35, v35, v49
	v_div_scale_f32 v43, s[4:5], v34, v34, v48
	v_add_f32_dpp v38, v40, v40 quad_perm:[2,3,0,1] row_mask:0xf bank_mask:0xf bound_ctrl:1
	v_div_scale_f32 v40, s[6:7], v37, v37, v51
	v_div_scale_f32 v52, s[8:9], v36, v36, v50
	v_rcp_f32_e32 v54, v39
	v_rcp_f32_e32 v55, v43
	v_add_f32_dpp v38, v38, v38 row_half_mirror row_mask:0xf bank_mask:0xf bound_ctrl:1
	v_rcp_f32_e32 v56, v40
	v_rcp_f32_e32 v57, v52
	v_add_f32_dpp v38, v38, v38 row_mirror row_mask:0xf bank_mask:0xf bound_ctrl:1
	v_fma_f32 v58, -v43, v55, 1.0
	v_fma_f32 v59, -v40, v56, 1.0
	v_mov_b32_dpp v33, v38 row_bcast:15 row_mask:0xa bank_mask:0xf
	v_add_f32_e32 v33, v38, v33
	v_fma_f32 v38, -v39, v54, 1.0
	v_div_scale_f32 v41, vcc, v49, v35, v49
	v_mov_b32_dpp v42, v33 row_bcast:31 row_mask:0xc bank_mask:0xf
	v_div_scale_f32 v44, s[4:5], v48, v34, v48
	v_div_scale_f32 v45, s[6:7], v51, v37, v51
	v_fma_f32 v61, -v52, v57, 1.0
	v_fmac_f32_e32 v54, v38, v54
	v_fmac_f32_e32 v55, v58, v55
	v_add_f32_e32 v33, v33, v42
	v_fmac_f32_e32 v56, v59, v56
	v_div_scale_f32 v53, s[8:9], v50, v36, v50
	v_fmac_f32_e32 v57, v61, v57
	v_mul_f32_e32 v58, v41, v54
	v_mul_f32_e32 v59, v44, v55
	v_readlane_b32 s2, v33, 63
	v_mul_f32_e32 v33, v45, v56
	v_mul_f32_e32 v61, v53, v57
	v_fma_f32 v42, -v39, v58, v41
	v_fma_f32 v123, -v43, v59, v44
	v_mul_f32_e32 v38, s2, v177
	v_fma_f32 v125, -v40, v33, v45
	v_fma_f32 v129, -v52, v61, v53
	v_fmac_f32_e32 v58, v42, v54
	v_fmac_f32_e32 v59, v123, v55
	v_pk_add_f32 v[8:9], v[8:9], v[38:39] op_sel_hi:[1,0] neg_lo:[0,1] neg_hi:[0,1]
	v_fmac_f32_e32 v33, v125, v56
	v_pk_add_f32 v[12:13], v[12:13], v[38:39] op_sel_hi:[1,0] neg_lo:[0,1] neg_hi:[0,1]
	v_fmac_f32_e32 v61, v129, v57
	v_fma_f32 v123, -v39, v58, v41
	v_fma_f32 v125, -v43, v59, v44
	v_fma_f32 v129, -v40, v33, v45
	v_mov_b32_e32 v44, v9
	v_mov_b32_e32 v45, v13
	v_pk_add_f32 v[10:11], v[10:11], v[38:39] op_sel_hi:[1,0] neg_lo:[0,1] neg_hi:[0,1]
	v_pk_add_f32 v[14:15], v[14:15], v[38:39] op_sel_hi:[1,0] neg_lo:[0,1] neg_hi:[0,1]
	v_fma_f32 v52, -v52, v61, v53
	v_mov_b32_e32 v42, v8
	v_mov_b32_e32 v43, v12
	v_div_fmas_f32 v53, v123, v54, v58
	v_pk_mul_f32 v[44:45], v[44:45], v[44:45]
	s_mov_b64 vcc, s[4:5]
	v_mov_b32_e32 v38, v10
	v_mov_b32_e32 v39, v14
	v_div_fixup_f32 v35, v53, v35, v49
	v_div_fmas_f32 v49, v125, v55, v59
	v_pk_fma_f32 v[42:43], v[42:43], v[42:43], v[44:45]
	s_mov_b64 vcc, s[6:7]
	v_mov_b32_e32 v40, v11
	v_mov_b32_e32 v41, v15
	v_div_fmas_f32 v33, v129, v56, v33
	v_pk_fma_f32 v[38:39], v[38:39], v[38:39], v[42:43]
	s_mov_b64 vcc, s[8:9]
	v_div_fixup_f32 v37, v33, v37, v51
	v_div_fmas_f32 v33, v52, v57, v61
	v_pk_fma_f32 v[38:39], v[40:41], v[40:41], v[38:39]
	v_div_fixup_f32 v36, v33, v36, v50
	v_add_f32_e32 v33, v38, v39
	v_div_fixup_f32 v34, v49, v34, v48
	s_nop 0
	v_add_f32_dpp v33, v33, v33 quad_perm:[1,0,3,2] row_mask:0xf bank_mask:0xf bound_ctrl:1
	s_nop 1
	v_add_f32_dpp v33, v33, v33 quad_perm:[2,3,0,1] row_mask:0xf bank_mask:0xf bound_ctrl:1
	s_nop 1
	v_add_f32_dpp v33, v33, v33 row_half_mirror row_mask:0xf bank_mask:0xf bound_ctrl:1
	s_nop 1
	v_add_f32_dpp v33, v33, v33 row_mirror row_mask:0xf bank_mask:0xf bound_ctrl:1
	s_nop 1
	v_mov_b32_dpp v46, v33 row_bcast:15 row_mask:0xa bank_mask:0xf
	v_add_f32_e32 v33, v33, v46
	s_nop 1
	v_mov_b32_dpp v47, v33 row_bcast:31 row_mask:0xc bank_mask:0xf
	v_add_f32_e32 v33, v33, v47
	s_nop 0
	v_readlane_b32 s2, v33, 63
	s_nop 1
	v_fma_f32 v33, s2, v177, v175
	v_mul_f32_e32 v38, 0x4b800000, v33
	v_cmp_gt_f32_e32 vcc, s85, v33
	s_nop 1
	v_cndmask_b32_e32 v33, v33, v38, vcc
	v_rsq_f32_e32 v33, v33
	s_nop 0
	v_mul_f32_e32 v38, 0x45800000, v33
	v_cndmask_b32_e32 v38, v33, v38, vcc
	v_pk_mul_f32 v[8:9], v[8:9], v[38:39] op_sel_hi:[1,0]
	v_pk_mul_f32 v[10:11], v[10:11], v[38:39] op_sel_hi:[1,0]
	v_pk_fma_f32 v[0:1], v[0:1], v[8:9], v[4:5]
	v_pk_fma_f32 v[2:3], v[2:3], v[10:11], v[6:7]
	v_mul_f32_e32 v4, 0xbfb8aa3b, v0
	v_mul_f32_e32 v5, 0xbfb8aa3b, v1
; DI float bflo(unsigned u) { return __uint_as_float(u << 16); }
; DI float bfhi(unsigned u) { return __uint_as_float(u & 0xffff0000u); }
; DI float siluf_(float x) { return x / (1.0f + __expf(-x)); }
; DI void branch_a_final_row(const Params& p, int row, int lane) {
;     ...
;     float y0 = siluf_(v[j].x * inv * g.x + bb.x) * siluf_(bflo(gu.x));
;     float y1 = siluf_(v[j].y * inv * g.y + bb.y) * siluf_(bfhi(gu.x));
;     float y2 = siluf_(v[j].z * inv * g.z + bb.z) * siluf_(bflo(gu.y));
;     float y3 = siluf_(v[j].w * inv * g.w + bb.w) * siluf_(bfhi(gu.y));
;     uint2 o;
;     o.x = pack2(y0, y1); o.y = pack2(y2, y3);
;     *(uint2*)(p.MIX + (size_t)row * 1024 + c) = o;
;   }
	v_exp_f32_e32 v4, v4
	v_exp_f32_e32 v5, v5
	v_mul_f32_e32 v6, 0xbfb8aa3b, v2
	v_mul_f32_e32 v7, 0xbfb8aa3b, v3
	v_exp_f32_e32 v6, v6
	v_exp_f32_e32 v7, v7
	v_pk_add_f32 v[4:5], v[4:5], 1.0 op_sel_hi:[1,0]
	v_pk_mul_f32 v[12:13], v[12:13], v[38:39] op_sel_hi:[1,0]
	v_div_scale_f32 v8, s[4:5], v5, v5, v1
	v_pk_add_f32 v[6:7], v[6:7], 1.0 op_sel_hi:[1,0]
	v_div_scale_f32 v10, s[4:5], v4, v4, v0
	v_rcp_f32_e32 v41, v8
	v_div_scale_f32 v33, s[6:7], v7, v7, v3
	v_rcp_f32_e32 v42, v10
	v_pk_mul_f32 v[14:15], v[14:15], v[38:39] op_sel_hi:[1,0]
	v_div_scale_f32 v39, s[8:9], v6, v6, v2
	v_rcp_f32_e32 v43, v33
	v_rcp_f32_e32 v44, v39
	v_fma_f32 v45, -v8, v41, 1.0
	v_div_scale_f32 v9, vcc, v1, v5, v1
	v_fma_f32 v46, -v10, v42, 1.0
	v_fmac_f32_e32 v41, v45, v41
	v_div_scale_f32 v11, s[4:5], v0, v4, v0
	v_fma_f32 v47, -v33, v43, 1.0
	v_fmac_f32_e32 v42, v46, v42
	v_mul_f32_e32 v45, v9, v41
	v_div_scale_f32 v38, s[6:7], v3, v7, v3
	v_fma_f32 v48, -v39, v44, 1.0
	v_fmac_f32_e32 v43, v47, v43
	v_mul_f32_e32 v46, v11, v42
	v_fma_f32 v49, -v8, v45, v9
	v_div_scale_f32 v40, s[8:9], v2, v6, v2
	v_fmac_f32_e32 v44, v48, v44
	v_mul_f32_e32 v47, v38, v43
	v_fma_f32 v50, -v10, v46, v11
	v_fmac_f32_e32 v45, v49, v41
	v_mul_f32_e32 v48, v40, v44
	v_fma_f32 v51, -v33, v47, v38
	v_fmac_f32_e32 v46, v50, v42
	v_fma_f32 v8, -v8, v45, v9
	v_fma_f32 v52, -v39, v48, v40
	v_fmac_f32_e32 v47, v51, v43
	v_fma_f32 v9, -v10, v46, v11
	v_div_fmas_f32 v8, v8, v41, v45
	s_mov_b64 vcc, s[4:5]
	v_fmac_f32_e32 v48, v52, v44
	v_fma_f32 v10, -v33, v47, v38
	v_div_fixup_f32 v1, v8, v5, v1
	v_div_fmas_f32 v5, v9, v42, v46
	s_mov_b64 vcc, s[6:7]
	v_fma_f32 v11, -v39, v48, v40
	v_div_fixup_f32 v0, v5, v4, v0
	v_div_fmas_f32 v4, v10, v43, v47
	s_mov_b64 vcc, s[8:9]
	v_div_fixup_f32 v3, v4, v7, v3
	v_div_fmas_f32 v4, v11, v44, v48
	v_div_fixup_f32 v2, v4, v6, v2
	v_pk_mul_f32 v[0:1], v[0:1], v[34:35]
	v_pk_mul_f32 v[2:3], v[2:3], v[36:37]
	v_cvt_pk_bf16_f32 v0, v0, v1
	v_cvt_pk_bf16_f32 v1, v2, v3
	global_store_dwordx2 v[28:29], v[0:1], off sc1
	global_load_dwordx4 v[0:3], v[16:17], off offset:1024
	s_nop 0
	global_load_dwordx4 v[4:7], v[18:19], off offset:1024
	global_load_dwordx2 v[8:9], v[30:31], off offset:2560
	s_waitcnt vmcnt(1)
	v_pk_fma_f32 v[0:1], v[12:13], v[0:1], v[4:5]
	s_waitcnt vmcnt(0)
	v_lshlrev_b32_e32 v12, 16, v8
	v_pk_fma_f32 v[2:3], v[14:15], v[2:3], v[6:7]
	v_mul_f32_e32 v4, 0xbfb8aa3b, v0
	v_mul_f32_e32 v5, 0xbfb8aa3b, v12
	v_mul_f32_e32 v7, 0xbfb8aa3b, v1
	v_and_b32_e32 v13, 0xffff0000, v8
	v_exp_f32_e32 v4, v4
	v_exp_f32_e32 v6, v5
	v_exp_f32_e32 v5, v7
	v_mul_f32_e32 v8, 0xbfb8aa3b, v13
	v_exp_f32_e32 v7, v8
	v_lshlrev_b32_e32 v14, 16, v9
	v_and_b32_e32 v15, 0xffff0000, v9
	v_mul_f32_e32 v9, 0xbfb8aa3b, v2
	v_mul_f32_e32 v11, 0xbfb8aa3b, v3
	v_mul_f32_e32 v30, 0xbfb8aa3b, v15
	v_exp_f32_e32 v8, v9
	v_exp_f32_e32 v9, v11
	v_pk_add_f32 v[4:5], v[4:5], 1.0 op_sel_hi:[1,0]
	v_mul_f32_e32 v10, 0xbfb8aa3b, v14
	v_exp_f32_e32 v11, v30
	v_div_scale_f32 v30, s[4:5], v5, v5, v1
	v_exp_f32_e32 v10, v10
	v_pk_add_f32 v[6:7], v[6:7], 1.0 op_sel_hi:[1,0]
	v_div_scale_f32 v33, s[4:5], v4, v4, v0
	v_rcp_f32_e32 v47, v30
	v_div_scale_f32 v35, s[6:7], v7, v7, v13
	v_rcp_f32_e32 v48, v33
	v_pk_add_f32 v[8:9], v[8:9], 1.0 op_sel_hi:[1,0]
	v_div_scale_f32 v37, s[8:9], v6, v6, v12
	v_rcp_f32_e32 v49, v35
	v_div_scale_f32 v39, s[10:11], v9, v9, v3
	v_rcp_f32_e32 v50, v37
	v_pk_add_f32 v[10:11], v[10:11], 1.0 op_sel_hi:[1,0]
	v_div_scale_f32 v41, s[12:13], v8, v8, v2
	v_rcp_f32_e32 v51, v39
	v_fma_f32 v55, -v30, v47, 1.0
	v_div_scale_f32 v31, vcc, v1, v5, v1
	v_div_scale_f32 v43, s[14:15], v11, v11, v15
	v_rcp_f32_e32 v52, v41
	v_fma_f32 v56, -v33, v48, 1.0
	v_fmac_f32_e32 v47, v55, v47
	v_div_scale_f32 v34, s[4:5], v0, v4, v0
	v_div_scale_f32 v45, s[16:17], v10, v10, v14
	v_rcp_f32_e32 v53, v43
	v_fma_f32 v57, -v35, v49, 1.0
	v_fmac_f32_e32 v48, v56, v48
	v_mul_f32_e32 v55, v31, v47
	v_div_scale_f32 v36, s[6:7], v13, v7, v13
	v_rcp_f32_e32 v54, v45
	v_fma_f32 v58, -v37, v50, 1.0
	v_fmac_f32_e32 v49, v57, v49
	v_mul_f32_e32 v56, v34, v48
	v_fma_f32 v129, -v30, v55, v31
	v_div_scale_f32 v38, s[8:9], v12, v6, v12
	v_fma_f32 v59, -v39, v51, 1.0
	v_fmac_f32_e32 v50, v58, v50
	v_mul_f32_e32 v57, v36, v49
	v_fma_f32 v130, -v33, v56, v34
	v_fmac_f32_e32 v55, v129, v47
	v_div_scale_f32 v40, s[10:11], v3, v9, v3
	v_fma_f32 v61, -v41, v52, 1.0
	v_fmac_f32_e32 v51, v59, v51
	v_mul_f32_e32 v58, v38, v50
	v_fma_f32 v131, -v35, v57, v36
	v_fmac_f32_e32 v56, v130, v48
	v_fma_f32 v30, -v30, v55, v31
	v_div_scale_f32 v42, s[12:13], v2, v8, v2
	v_fma_f32 v123, -v43, v53, 1.0
	v_fmac_f32_e32 v52, v61, v52
	v_mul_f32_e32 v59, v40, v51
	v_fma_f32 v132, -v37, v58, v38
	v_fmac_f32_e32 v57, v131, v49
	v_fma_f32 v31, -v33, v56, v34
	v_div_fmas_f32 v30, v30, v47, v55
	s_mov_b64 vcc, s[4:5]
	v_div_scale_f32 v44, s[14:15], v15, v11, v15
	v_fma_f32 v125, -v45, v54, 1.0
	v_fmac_f32_e32 v53, v123, v53
	v_mul_f32_e32 v61, v42, v52
	v_fma_f32 v133, -v39, v59, v40
	v_fmac_f32_e32 v58, v132, v50
	v_fma_f32 v33, -v35, v57, v36
	v_div_fixup_f32 v1, v30, v5, v1
	v_div_fmas_f32 v5, v31, v48, v56
	s_mov_b64 vcc, s[6:7]
	v_div_scale_f32 v46, s[16:17], v14, v10, v14
	v_fmac_f32_e32 v54, v125, v54
	v_mul_f32_e32 v123, v44, v53
	v_fma_f32 v134, -v41, v61, v42
	v_fmac_f32_e32 v59, v133, v51
	v_fma_f32 v34, -v37, v58, v38
	v_div_fixup_f32 v0, v5, v4, v0
	v_div_fmas_f32 v4, v33, v49, v57
	s_mov_b64 vcc, s[8:9]
	v_mul_f32_e32 v125, v46, v54
	v_fma_f32 v135, -v43, v123, v44
	v_fmac_f32_e32 v61, v134, v52
	v_fma_f32 v35, -v39, v59, v40
	v_div_fixup_f32 v5, v4, v7, v13
	v_div_fmas_f32 v4, v34, v50, v58
	s_mov_b64 vcc, s[10:11]
	v_fma_f32 v136, -v45, v125, v46
	v_fmac_f32_e32 v123, v135, v53
	v_fma_f32 v36, -v41, v61, v42
	v_div_fixup_f32 v4, v4, v6, v12
	v_div_fmas_f32 v6, v35, v51, v59
	s_mov_b64 vcc, s[12:13]
	v_fmac_f32_e32 v125, v136, v54
	v_fma_f32 v37, -v43, v123, v44
	v_pk_mul_f32 v[0:1], v[0:1], v[4:5]
	v_div_fmas_f32 v4, v36, v52, v61
	s_mov_b64 vcc, s[14:15]
	v_fma_f32 v38, -v45, v125, v46
	v_div_fixup_f32 v2, v4, v8, v2
	v_div_fmas_f32 v4, v37, v53, v123
	s_mov_b64 vcc, s[16:17]
	v_cvt_pk_bf16_f32 v0, v0, v1
	v_div_fmas_f32 v1, v38, v54, v125
	v_div_fixup_f32 v3, v6, v9, v3
	v_div_fixup_f32 v5, v4, v11, v15
	v_div_fixup_f32 v4, v1, v10, v14
	v_pk_mul_f32 v[2:3], v[2:3], v[4:5]
	s_nop 0
	v_cvt_pk_bf16_f32 v1, v2, v3
	global_store_dwordx2 v[28:29], v[0:1], off offset:512 sc1
	s_andn2_b64 exec, exec, s[20:21]
	s_cbranch_execnz .LBB0_682
	s_branch .LBB0_611

; #define MFMA32(a, b, c) __builtin_amdgcn_mfma_f32_32x32x16_bf16((a), (b), (c), 0, 0, 0)
; #define LOADK(c_) do { _Pragma("unroll") for (int i = 0; i < 4; ++i) { const int ch = tid + i * 256; \
;     sr[i] = *(const u32x4*)(Kg + (ch >> 2) * 1024 + (c_) * 32 + (ch & 3) * 8); } } while (0)
; #define STOREK() do { _Pragma("unroll") for (int i = 0; i < 4; ++i) { const int ch = tid + i * 256; \
;     *(u32x4*)(kbuf + (ch >> 2) * 40 + (ch & 3) * 8) = sr[i]; } } while (0)
; #define LOADV(v_, tid) do { _Pragma("unroll") for (int i = 0; i < 8; ++i) { const int idx = tid + i * 256, f = idx >> 6; \
;     sr[i] = VTg[(((v_) >> 1) * 4 + (f >> 3)) * 1024 + (((v_) & 1) * 8 + (f & 7)) * 64 + (idx & 63)]; } } while (0)
; DI void attn_prompt_block(const Params& p, int l, int b, int hh, int tt4, char* smem, bfr* Obuf) {
;   int tid = threadIdx.x;
;   asm volatile("" : "+v"(tid));
;   const int lane = tid & 63, wid = tid >> 6, r = lane & 31, hl = lane >> 5;
;   const int row0 = b * 2048 + (tt4 * 4 + wid) * 32;
;   const int qoff = (row0 + r) * 1024 + hh * 256 + hl * 8;
;   const bfr* Kg = p.KB + (size_t)l * 2097152 + (size_t)(b * 256) * 1024 + hh * 256;
;   const u32x4* VTg = (const u32x4*)(p.VT + (size_t)l * 2097152) + (size_t)((b * 4 + hh) * 8) * 16 * 64;
;   bfr* kbuf = (bfr*)smem;
;   u32x4* vbuf = (u32x4*)smem;
;   u32x4 sr[8];
;     ...
;   f32x16 st[8];
; #pragma unroll
;   for (int m = 0; m < 8; ++m)
; #pragma unroll
;     for (int q = 0; q < 16; ++q) st[m][q] = 0.f;
;   LOADK(0);
;   STOREK();
;   __syncthreads();
; #pragma unroll
;   for (int c = 0; c < 8; ++c) {
;     if (c < 7) LOADK(c + 1); else LOADV(0, tid);
;     bf16x8 qf[2];
; #pragma unroll
;     for (int ksl = 0; ksl < 2; ++ksl) qf[ksl] = *(const bf16x8*)(p.ACT2 + qoff + (c * 2 + ksl) * 16);
; #pragma unroll
;     for (int ksl = 0; ksl < 2; ++ksl)
; #pragma unroll
;       for (int m = 0; m < 8; ++m) {
;         bf16x8 kf = *(const bf16x8*)(kbuf + (m * 32 + r) * 40 + ksl * 16 + hl * 8);
;         st[m] = MFMA32(kf, qf[ksl], st[m]);
.LBB0_1024:
	s_ashr_i32 s56, s20, 6
	s_and_b32 s54, s20, 15
	s_bfe_u32 s55, s20, 0x20004
	s_lshl_b32 s20, s56, 8
	s_ashr_i32 s21, s20, 31
	s_lshl_b64 s[22:23], s[20:21], 11
	s_lshl_b32 s20, s56, 5
	s_lshl_b32 s21, s55, 3
	s_or_b32 s20, s21, s20
	v_mov_b32_e32 v148, v196
	s_ashr_i32 s21, s20, 31
	s_lshl_b32 s52, s56, 11
	s_lshl_b32 s53, s55, 8
	s_lshl_b64 s[20:21], s[20:21], 14
	v_lshlrev_b32_e32 v0, 8, v148
	s_waitcnt lgkmcnt(0)
	s_add_u32 s22, s16, s22
	v_and_b32_e32 v10, 0xfffffc00, v0
	s_addc_u32 s23, s17, s23
	s_lshl_b32 s55, s55, 9
	v_ashrrev_i32_e32 v11, 31, v10
	s_add_u32 s22, s22, s55
	v_lshlrev_b32_e32 v147, 4, v148
	v_lshlrev_b64 v[182:183], 1, v[10:11]
	v_add_u32_e32 v2, 0x10000, v10
	v_add_u32_e32 v12, 0x20000, v10
	v_add_u32_e32 v10, 0x30000, v10
	s_addc_u32 s23, s23, 0
	v_and_b32_e32 v160, 48, v147
	v_ashrrev_i32_e32 v3, 31, v2
	v_ashrrev_i32_e32 v13, 31, v12
	v_ashrrev_i32_e32 v11, 31, v10
	v_lshl_add_u64 v[8:9], s[22:23], 0, v[160:161]
	v_lshlrev_b64 v[194:195], 1, v[2:3]
	v_lshlrev_b64 v[210:211], 1, v[12:13]
	v_lshlrev_b64 v[212:213], 1, v[10:11]
	v_lshl_add_u64 v[0:1], v[8:9], 0, v[182:183]
	v_lshl_add_u64 v[4:5], v[8:9], 0, v[194:195]
	v_lshl_add_u64 v[12:13], v[8:9], 0, v[210:211]
	v_lshl_add_u64 v[14:15], v[8:9], 0, v[212:213]
	global_load_dwordx4 v[0:3], v[0:1], off
	s_nop 0
	global_load_dwordx4 v[4:7], v[4:5], off
	s_nop 0
	global_load_dwordx4 v[8:11], v[12:13], off
	s_nop 0
	global_load_dwordx4 v[12:15], v[14:15], off
	v_or_b32_e32 v16, s54, v181
	v_lshrrev_b32_e32 v17, 6, v148
	v_lshlrev_b32_e32 v146, 2, v16
	v_add_u32_e32 v17, v146, v17
	v_and_b32_e32 v18, 31, v148
	v_lshrrev_b32_e32 v16, 2, v148
	v_lshl_add_u32 v17, v17, 5, s52
	v_and_b32_e32 v19, 8, v16
	v_mad_u64_u32 v[130:131], s[54:55], v16, s42, v[160:161]
	v_or_b32_e32 v16, v17, v18
	v_lshlrev_b32_e32 v16, 10, v16
	v_or3_b32 v16, v16, s53, v19
	v_add_u32_e32 v151, 0x100, v148
	v_add_u32_e32 v150, 0x200, v148
	v_add_u32_e32 v149, 0x300, v148
	v_ashrrev_i32_e32 v17, 31, v16
	v_lshrrev_b32_e32 v20, 2, v151
	v_lshrrev_b32_e32 v21, 2, v150
	v_lshrrev_b32_e32 v22, 2, v149
	v_lshl_add_u64 v[128:129], v[16:17], 1, s[12:13]
	v_mad_u64_u32 v[132:133], s[54:55], v20, s42, v[160:161]
	v_mad_u64_u32 v[134:135], s[54:55], v21, s42, v[160:161]
	v_mad_u64_u32 v[136:137], s[54:55], v22, s42, v[160:161]
	s_add_u32 s20, s18, s20
	s_addc_u32 s21, s19, s21
	v_cmp_lt_i32_e32 vcc, v191, v192
	s_waitcnt vmcnt(3)
	ds_write_b128 v130, v[0:3]
	s_waitcnt vmcnt(2)
	ds_write_b128 v132, v[4:7]
	s_waitcnt vmcnt(1)
	ds_write_b128 v134, v[8:11]
	s_waitcnt vmcnt(0)
	ds_write_b128 v136, v[12:15]
	s_waitcnt lgkmcnt(0)
	s_barrier
	global_load_dwordx4 v[0:3], v[128:129], off
	global_load_dwordx4 v[152:155], v[128:129], off offset:32
	v_mul_u32_u24_e32 v4, 0x50, v18
	v_lshl_add_u32 v133, v19, 1, v4
	ds_read_b128 v[4:7], v133
	ds_read_b128 v[138:141], v133 offset:32
	s_waitcnt vmcnt(1) lgkmcnt(1)
	v_mfma_f32_32x32x16_bf16 v[112:127], v[4:7], v[0:3], 0
	ds_read_b128 v[4:7], v133 offset:2560
	ds_read_b128 v[142:145], v133 offset:2592
	s_waitcnt lgkmcnt(1)
	v_mfma_f32_32x32x16_bf16 v[96:111], v[4:7], v[0:3], 0
	ds_read_b128 v[4:7], v133 offset:5120
	ds_read_b128 v[156:159], v133 offset:5152
	s_waitcnt lgkmcnt(1)
	v_mfma_f32_32x32x16_bf16 v[80:95], v[4:7], v[0:3], 0
	ds_read_b128 v[4:7], v133 offset:7680
	ds_read_b128 v[198:201], v133 offset:7712
	s_waitcnt lgkmcnt(1)
	v_mfma_f32_32x32x16_bf16 v[64:79], v[4:7], v[0:3], 0
	ds_read_b128 v[4:7], v133 offset:10240
	ds_read_b128 v[202:205], v133 offset:10272
	s_waitcnt lgkmcnt(1)
	v_mfma_f32_32x32x16_bf16 v[48:63], v[4:7], v[0:3], 0
	ds_read_b128 v[4:7], v133 offset:12800
	ds_read_b128 v[206:209], v133 offset:12832
	s_waitcnt lgkmcnt(1)
	v_mfma_f32_32x32x16_bf16 v[32:47], v[4:7], v[0:3], 0
	ds_read_b128 v[4:7], v133 offset:15360
	ds_read_b128 v[216:219], v133 offset:15392
	s_waitcnt vmcnt(0)
	v_mfma_f32_32x32x16_bf16 v[112:127], v[138:141], v[152:155], v[112:127]
	v_lshl_add_u64 v[138:139], s[22:23], 0, v[182:183]
	v_lshl_add_u64 v[140:141], s[22:23], 0, v[194:195]
	v_mfma_f32_32x32x16_bf16 v[80:95], v[156:159], v[152:155], v[80:95]
	v_lshl_add_u64 v[156:157], s[22:23], 0, v[210:211]
	v_lshl_add_u64 v[158:159], s[22:23], 0, v[212:213]
	v_mfma_f32_32x32x16_bf16 v[96:111], v[142:145], v[152:155], v[96:111]
	v_lshl_add_u64 v[142:143], v[138:139], 0, v[160:161]
	v_lshl_add_u64 v[138:139], v[156:157], 0, v[160:161]
	v_lshl_add_u64 v[144:145], v[140:141], 0, v[160:161]
	v_lshl_add_u64 v[140:141], v[158:159], 0, v[160:161]
	s_waitcnt lgkmcnt(1)
	v_mfma_f32_32x32x16_bf16 v[16:31], v[4:7], v[0:3], 0
	ds_read_b128 v[4:7], v133 offset:17920
	ds_read_b128 v[220:223], v133 offset:17952
	v_mfma_f32_32x32x16_bf16 v[64:79], v[198:201], v[152:155], v[64:79]
	global_load_dwordx4 v[156:159], v[142:143], off offset:64
	global_load_dwordx4 v[198:201], v[144:145], off offset:64
	v_mfma_f32_32x32x16_bf16 v[48:63], v[202:205], v[152:155], v[48:63]
	global_load_dwordx4 v[202:205], v[138:139], off offset:64
	global_load_dwordx4 v[224:227], v[140:141], off offset:64
	s_waitcnt lgkmcnt(0)
	s_barrier
	s_waitcnt vmcnt(3)
	ds_write_b128 v130, v[156:159]
	s_waitcnt vmcnt(2)
	ds_write_b128 v132, v[198:201]
	s_waitcnt vmcnt(1)
	ds_write_b128 v134, v[202:205]
	s_waitcnt vmcnt(0)
	ds_write_b128 v136, v[224:227]
	s_waitcnt lgkmcnt(0)
	s_barrier
; #define MFMA32(a, b, c) __builtin_amdgcn_mfma_f32_32x32x16_bf16((a), (b), (c), 0, 0, 0)
; #define LOADK(c_) do { _Pragma("unroll") for (int i = 0; i < 4; ++i) { const int ch = tid + i * 256; \
;     sr[i] = *(const u32x4*)(Kg + (ch >> 2) * 1024 + (c_) * 32 + (ch & 3) * 8); } } while (0)
; #define STOREK() do { _Pragma("unroll") for (int i = 0; i < 4; ++i) { const int ch = tid + i * 256; \
;     *(u32x4*)(kbuf + (ch >> 2) * 40 + (ch & 3) * 8) = sr[i]; } } while (0)
; #define LOADV(v_, tid) do { _Pragma("unroll") for (int i = 0; i < 8; ++i) { const int idx = tid + i * 256, f = idx >> 6; \
;     sr[i] = VTg[(((v_) >> 1) * 4 + (f >> 3)) * 1024 + (((v_) & 1) * 8 + (f & 7)) * 64 + (idx & 63)]; } } while (0)
; #define STOREV(tid) do { _Pragma("unroll") for (int i = 0; i < 8; ++i) vbuf[tid + i * 256] = sr[i]; } while (0)
; DI void attn_prompt_block(const Params& p, int l, int b, int hh, int tt4, char* smem, bfr* Obuf) {
;     ...
;   for (int c = 0; c < 8; ++c) {
;     if (c < 7) LOADK(c + 1); else LOADV(0, tid);
;     bf16x8 qf[2];
; #pragma unroll
;     for (int ksl = 0; ksl < 2; ++ksl) qf[ksl] = *(const bf16x8*)(p.ACT2 + qoff + (c * 2 + ksl) * 16);
; #pragma unroll
;     for (int ksl = 0; ksl < 2; ++ksl)
; #pragma unroll
;       for (int m = 0; m < 8; ++m) {
;         bf16x8 kf = *(const bf16x8*)(kbuf + (m * 32 + r) * 40 + ksl * 16 + hl * 8);
;         st[m] = MFMA32(kf, qf[ksl], st[m]);
;       }
;     __syncthreads();
;     if (c < 7) STOREK(); else STOREV(tid);
;     __syncthreads();
	global_load_dwordx4 v[156:159], v[128:129], off offset:64
	global_load_dwordx4 v[198:201], v[128:129], off offset:96
	v_mfma_f32_32x32x16_bf16 v[0:15], v[4:7], v[0:3], 0
	ds_read_b128 v[202:205], v133 offset:32
	v_mfma_f32_32x32x16_bf16 v[32:47], v[206:209], v[152:155], v[32:47]
	v_mfma_f32_32x32x16_bf16 v[16:31], v[216:219], v[152:155], v[16:31]
	v_mfma_f32_32x32x16_bf16 v[0:15], v[220:223], v[152:155], v[0:15]
	ds_read_b128 v[152:155], v133
	s_waitcnt vmcnt(1) lgkmcnt(0)
	v_mfma_f32_32x32x16_bf16 v[112:127], v[152:155], v[156:159], v[112:127]
	ds_read_b128 v[152:155], v133 offset:2560
	ds_read_b128 v[206:209], v133 offset:2592
	s_waitcnt lgkmcnt(1)
	v_mfma_f32_32x32x16_bf16 v[96:111], v[152:155], v[156:159], v[96:111]
	ds_read_b128 v[152:155], v133 offset:5120
	ds_read_b128 v[216:219], v133 offset:5152
	s_waitcnt lgkmcnt(1)
	v_mfma_f32_32x32x16_bf16 v[80:95], v[152:155], v[156:159], v[80:95]
	ds_read_b128 v[152:155], v133 offset:7680
	ds_read_b128 v[220:223], v133 offset:7712
	s_waitcnt lgkmcnt(1)
	v_mfma_f32_32x32x16_bf16 v[64:79], v[152:155], v[156:159], v[64:79]
	ds_read_b128 v[152:155], v133 offset:10240
	ds_read_b128 v[224:227], v133 offset:10272
	s_waitcnt lgkmcnt(1)
	v_mfma_f32_32x32x16_bf16 v[48:63], v[152:155], v[156:159], v[48:63]
	ds_read_b128 v[152:155], v133 offset:12800
	ds_read_b128 v[228:231], v133 offset:12832
	s_waitcnt lgkmcnt(1)
	v_mfma_f32_32x32x16_bf16 v[32:47], v[152:155], v[156:159], v[32:47]
	ds_read_b128 v[152:155], v133 offset:15360
	ds_read_b128 v[232:235], v133 offset:15392
	s_waitcnt lgkmcnt(1)
	v_mfma_f32_32x32x16_bf16 v[16:31], v[152:155], v[156:159], v[16:31]
	ds_read_b128 v[152:155], v133 offset:17920
	ds_read_b128 v[236:239], v133 offset:17952
	s_waitcnt lgkmcnt(1)
	v_mfma_f32_32x32x16_bf16 v[0:15], v[152:155], v[156:159], v[0:15]
	global_load_dwordx4 v[152:155], v[142:143], off offset:128
	global_load_dwordx4 v[156:159], v[144:145], off offset:128
	s_waitcnt vmcnt(2)
	v_mfma_f32_32x32x16_bf16 v[112:127], v[202:205], v[198:201], v[112:127]
	v_mfma_f32_32x32x16_bf16 v[96:111], v[206:209], v[198:201], v[96:111]
	global_load_dwordx4 v[202:205], v[138:139], off offset:128
	global_load_dwordx4 v[206:209], v[140:141], off offset:128
	s_waitcnt lgkmcnt(0)
	s_barrier
	s_waitcnt vmcnt(3)
	ds_write_b128 v130, v[152:155]
	s_waitcnt vmcnt(2)
	ds_write_b128 v132, v[156:159]
	s_waitcnt vmcnt(1)
	ds_write_b128 v134, v[202:205]
	s_waitcnt vmcnt(0)
	ds_write_b128 v136, v[206:209]
	s_waitcnt lgkmcnt(0)
	s_barrier
	global_load_dwordx4 v[152:155], v[128:129], off offset:128
	v_mfma_f32_32x32x16_bf16 v[80:95], v[216:219], v[198:201], v[80:95]
	ds_read_b128 v[156:159], v133
	ds_read_b128 v[202:205], v133 offset:32
	v_mfma_f32_32x32x16_bf16 v[64:79], v[220:223], v[198:201], v[64:79]
	v_mfma_f32_32x32x16_bf16 v[48:63], v[224:227], v[198:201], v[48:63]
	v_mfma_f32_32x32x16_bf16 v[32:47], v[228:231], v[198:201], v[32:47]
	v_mfma_f32_32x32x16_bf16 v[16:31], v[232:235], v[198:201], v[16:31]
	v_mfma_f32_32x32x16_bf16 v[0:15], v[236:239], v[198:201], v[0:15]
	global_load_dwordx4 v[198:201], v[128:129], off offset:160
	s_waitcnt vmcnt(1) lgkmcnt(1)
	v_mfma_f32_32x32x16_bf16 v[112:127], v[156:159], v[152:155], v[112:127]
	ds_read_b128 v[156:159], v133 offset:2560
	ds_read_b128 v[206:209], v133 offset:2592
	s_waitcnt lgkmcnt(1)
	v_mfma_f32_32x32x16_bf16 v[96:111], v[156:159], v[152:155], v[96:111]
	ds_read_b128 v[156:159], v133 offset:5120
	ds_read_b128 v[216:219], v133 offset:5152
	s_waitcnt lgkmcnt(1)
	v_mfma_f32_32x32x16_bf16 v[80:95], v[156:159], v[152:155], v[80:95]
	ds_read_b128 v[156:159], v133 offset:7680
	ds_read_b128 v[220:223], v133 offset:7712
	s_waitcnt lgkmcnt(1)
	v_mfma_f32_32x32x16_bf16 v[64:79], v[156:159], v[152:155], v[64:79]
	ds_read_b128 v[156:159], v133 offset:10240
	ds_read_b128 v[224:227], v133 offset:10272
	s_waitcnt lgkmcnt(1)
	v_mfma_f32_32x32x16_bf16 v[48:63], v[156:159], v[152:155], v[48:63]
	ds_read_b128 v[156:159], v133 offset:12800
	ds_read_b128 v[228:231], v133 offset:12832
	s_waitcnt lgkmcnt(1)
	v_mfma_f32_32x32x16_bf16 v[32:47], v[156:159], v[152:155], v[32:47]
	ds_read_b128 v[156:159], v133 offset:15360
	ds_read_b128 v[232:235], v133 offset:15392
	s_waitcnt lgkmcnt(1)
	v_mfma_f32_32x32x16_bf16 v[16:31], v[156:159], v[152:155], v[16:31]
	ds_read_b128 v[156:159], v133 offset:17920
	ds_read_b128 v[236:239], v133 offset:17952
	s_waitcnt lgkmcnt(1)
	v_mfma_f32_32x32x16_bf16 v[0:15], v[156:159], v[152:155], v[0:15]
	global_load_dwordx4 v[152:155], v[142:143], off offset:192
	global_load_dwordx4 v[156:159], v[144:145], off offset:192
	s_waitcnt vmcnt(2)
	v_mfma_f32_32x32x16_bf16 v[112:127], v[202:205], v[198:201], v[112:127]
	v_mfma_f32_32x32x16_bf16 v[96:111], v[206:209], v[198:201], v[96:111]
	global_load_dwordx4 v[202:205], v[138:139], off offset:192
	global_load_dwordx4 v[206:209], v[140:141], off offset:192
	s_waitcnt lgkmcnt(0)
	s_barrier
	s_waitcnt vmcnt(3)
	ds_write_b128 v130, v[152:155]
	s_waitcnt vmcnt(2)
	ds_write_b128 v132, v[156:159]
	s_waitcnt vmcnt(1)
	ds_write_b128 v134, v[202:205]
	s_waitcnt vmcnt(0)
	ds_write_b128 v136, v[206:209]
	s_waitcnt lgkmcnt(0)
	s_barrier
; #define MFMA32(a, b, c) __builtin_amdgcn_mfma_f32_32x32x16_bf16((a), (b), (c), 0, 0, 0)
; #define LOADK(c_) do { _Pragma("unroll") for (int i = 0; i < 4; ++i) { const int ch = tid + i * 256; \
;     sr[i] = *(const u32x4*)(Kg + (ch >> 2) * 1024 + (c_) * 32 + (ch & 3) * 8); } } while (0)
; #define STOREK() do { _Pragma("unroll") for (int i = 0; i < 4; ++i) { const int ch = tid + i * 256; \
;     *(u32x4*)(kbuf + (ch >> 2) * 40 + (ch & 3) * 8) = sr[i]; } } while (0)
; #define LOADV(v_, tid) do { _Pragma("unroll") for (int i = 0; i < 8; ++i) { const int idx = tid + i * 256, f = idx >> 6; \
;     sr[i] = VTg[(((v_) >> 1) * 4 + (f >> 3)) * 1024 + (((v_) & 1) * 8 + (f & 7)) * 64 + (idx & 63)]; } } while (0)
; #define STOREV(tid) do { _Pragma("unroll") for (int i = 0; i < 8; ++i) vbuf[tid + i * 256] = sr[i]; } while (0)
; DI void attn_prompt_block(const Params& p, int l, int b, int hh, int tt4, char* smem, bfr* Obuf) {
;     ...
;   for (int c = 0; c < 8; ++c) {
;     if (c < 7) LOADK(c + 1); else LOADV(0, tid);
;     bf16x8 qf[2];
; #pragma unroll
;     for (int ksl = 0; ksl < 2; ++ksl) qf[ksl] = *(const bf16x8*)(p.ACT2 + qoff + (c * 2 + ksl) * 16);
; #pragma unroll
;     for (int ksl = 0; ksl < 2; ++ksl)
; #pragma unroll
;       for (int m = 0; m < 8; ++m) {
;         bf16x8 kf = *(const bf16x8*)(kbuf + (m * 32 + r) * 40 + ksl * 16 + hl * 8);
;         st[m] = MFMA32(kf, qf[ksl], st[m]);
;       }
;     __syncthreads();
;     if (c < 7) STOREK(); else STOREV(tid);
;     __syncthreads();
	global_load_dwordx4 v[152:155], v[128:129], off offset:192
	v_mfma_f32_32x32x16_bf16 v[80:95], v[216:219], v[198:201], v[80:95]
	ds_read_b128 v[156:159], v133
	ds_read_b128 v[202:205], v133 offset:32
	v_mfma_f32_32x32x16_bf16 v[64:79], v[220:223], v[198:201], v[64:79]
	v_mfma_f32_32x32x16_bf16 v[48:63], v[224:227], v[198:201], v[48:63]
	v_mfma_f32_32x32x16_bf16 v[32:47], v[228:231], v[198:201], v[32:47]
	v_mfma_f32_32x32x16_bf16 v[16:31], v[232:235], v[198:201], v[16:31]
	v_mfma_f32_32x32x16_bf16 v[0:15], v[236:239], v[198:201], v[0:15]
	global_load_dwordx4 v[198:201], v[128:129], off offset:224
	s_waitcnt vmcnt(1) lgkmcnt(1)
	v_mfma_f32_32x32x16_bf16 v[112:127], v[156:159], v[152:155], v[112:127]
	ds_read_b128 v[156:159], v133 offset:2560
	ds_read_b128 v[206:209], v133 offset:2592
	s_waitcnt lgkmcnt(1)
	v_mfma_f32_32x32x16_bf16 v[96:111], v[156:159], v[152:155], v[96:111]
	ds_read_b128 v[156:159], v133 offset:5120
	ds_read_b128 v[216:219], v133 offset:5152
	s_waitcnt lgkmcnt(1)
	v_mfma_f32_32x32x16_bf16 v[80:95], v[156:159], v[152:155], v[80:95]
	ds_read_b128 v[156:159], v133 offset:7680
	ds_read_b128 v[220:223], v133 offset:7712
	s_waitcnt lgkmcnt(1)
	v_mfma_f32_32x32x16_bf16 v[64:79], v[156:159], v[152:155], v[64:79]
	ds_read_b128 v[156:159], v133 offset:10240
	ds_read_b128 v[224:227], v133 offset:10272
	s_waitcnt lgkmcnt(1)
	v_mfma_f32_32x32x16_bf16 v[48:63], v[156:159], v[152:155], v[48:63]
	ds_read_b128 v[156:159], v133 offset:12800
	ds_read_b128 v[228:231], v133 offset:12832
	s_waitcnt lgkmcnt(1)
	v_mfma_f32_32x32x16_bf16 v[32:47], v[156:159], v[152:155], v[32:47]
	ds_read_b128 v[156:159], v133 offset:15360
	ds_read_b128 v[232:235], v133 offset:15392
	s_waitcnt lgkmcnt(1)
	v_mfma_f32_32x32x16_bf16 v[16:31], v[156:159], v[152:155], v[16:31]
	ds_read_b128 v[156:159], v133 offset:17920
	ds_read_b128 v[236:239], v133 offset:17952
	s_waitcnt lgkmcnt(1)
	v_mfma_f32_32x32x16_bf16 v[0:15], v[156:159], v[152:155], v[0:15]
	global_load_dwordx4 v[152:155], v[142:143], off offset:256
	global_load_dwordx4 v[156:159], v[144:145], off offset:256
	s_waitcnt vmcnt(2)
	v_mfma_f32_32x32x16_bf16 v[112:127], v[202:205], v[198:201], v[112:127]
	v_mfma_f32_32x32x16_bf16 v[96:111], v[206:209], v[198:201], v[96:111]
	global_load_dwordx4 v[202:205], v[138:139], off offset:256
	global_load_dwordx4 v[206:209], v[140:141], off offset:256
	s_waitcnt lgkmcnt(0)
	s_barrier
	s_waitcnt vmcnt(3)
	ds_write_b128 v130, v[152:155]
	s_waitcnt vmcnt(2)
	ds_write_b128 v132, v[156:159]
	s_waitcnt vmcnt(1)
	ds_write_b128 v134, v[202:205]
	s_waitcnt vmcnt(0)
	ds_write_b128 v136, v[206:209]
	s_waitcnt lgkmcnt(0)
	s_barrier
	global_load_dwordx4 v[152:155], v[128:129], off offset:256
	v_mfma_f32_32x32x16_bf16 v[80:95], v[216:219], v[198:201], v[80:95]
	ds_read_b128 v[156:159], v133
	ds_read_b128 v[202:205], v133 offset:32
	v_mfma_f32_32x32x16_bf16 v[64:79], v[220:223], v[198:201], v[64:79]
	v_mfma_f32_32x32x16_bf16 v[48:63], v[224:227], v[198:201], v[48:63]
	v_mfma_f32_32x32x16_bf16 v[32:47], v[228:231], v[198:201], v[32:47]
	v_mfma_f32_32x32x16_bf16 v[16:31], v[232:235], v[198:201], v[16:31]
	v_mfma_f32_32x32x16_bf16 v[0:15], v[236:239], v[198:201], v[0:15]
	global_load_dwordx4 v[198:201], v[128:129], off offset:288
	s_waitcnt vmcnt(1) lgkmcnt(1)
	v_mfma_f32_32x32x16_bf16 v[112:127], v[156:159], v[152:155], v[112:127]
	ds_read_b128 v[156:159], v133 offset:2560
	ds_read_b128 v[206:209], v133 offset:2592
	s_waitcnt lgkmcnt(1)
	v_mfma_f32_32x32x16_bf16 v[96:111], v[156:159], v[152:155], v[96:111]
	ds_read_b128 v[156:159], v133 offset:5120
	ds_read_b128 v[216:219], v133 offset:5152
	s_waitcnt lgkmcnt(1)
	v_mfma_f32_32x32x16_bf16 v[80:95], v[156:159], v[152:155], v[80:95]
	ds_read_b128 v[156:159], v133 offset:7680
	ds_read_b128 v[220:223], v133 offset:7712
	s_waitcnt lgkmcnt(1)
	v_mfma_f32_32x32x16_bf16 v[64:79], v[156:159], v[152:155], v[64:79]
	ds_read_b128 v[156:159], v133 offset:10240
	ds_read_b128 v[224:227], v133 offset:10272
	s_waitcnt lgkmcnt(1)
	v_mfma_f32_32x32x16_bf16 v[48:63], v[156:159], v[152:155], v[48:63]
	ds_read_b128 v[156:159], v133 offset:12800
	ds_read_b128 v[228:231], v133 offset:12832
	s_waitcnt lgkmcnt(1)
	v_mfma_f32_32x32x16_bf16 v[32:47], v[156:159], v[152:155], v[32:47]
	ds_read_b128 v[156:159], v133 offset:15360
	ds_read_b128 v[232:235], v133 offset:15392
	s_waitcnt lgkmcnt(1)
	v_mfma_f32_32x32x16_bf16 v[16:31], v[156:159], v[152:155], v[16:31]
	ds_read_b128 v[156:159], v133 offset:17920
	ds_read_b128 v[236:239], v133 offset:17952
	s_waitcnt lgkmcnt(1)
	v_mfma_f32_32x32x16_bf16 v[0:15], v[156:159], v[152:155], v[0:15]
	global_load_dwordx4 v[152:155], v[142:143], off offset:320
	global_load_dwordx4 v[156:159], v[144:145], off offset:320
	s_waitcnt vmcnt(2)
	v_mfma_f32_32x32x16_bf16 v[112:127], v[202:205], v[198:201], v[112:127]
	v_mfma_f32_32x32x16_bf16 v[96:111], v[206:209], v[198:201], v[96:111]
	global_load_dwordx4 v[202:205], v[138:139], off offset:320
	global_load_dwordx4 v[206:209], v[140:141], off offset:320
	s_waitcnt lgkmcnt(0)
	s_barrier
	s_waitcnt vmcnt(3)
	ds_write_b128 v130, v[152:155]
	s_waitcnt vmcnt(2)
	ds_write_b128 v132, v[156:159]
	s_waitcnt vmcnt(1)
	ds_write_b128 v134, v[202:205]
	s_waitcnt vmcnt(0)
	ds_write_b128 v136, v[206:209]
	s_waitcnt lgkmcnt(0)
	s_barrier
; #define MFMA32(a, b, c) __builtin_amdgcn_mfma_f32_32x32x16_bf16((a), (b), (c), 0, 0, 0)
; #define LOADK(c_) do { _Pragma("unroll") for (int i = 0; i < 4; ++i) { const int ch = tid + i * 256; \
;     sr[i] = *(const u32x4*)(Kg + (ch >> 2) * 1024 + (c_) * 32 + (ch & 3) * 8); } } while (0)
; #define STOREK() do { _Pragma("unroll") for (int i = 0; i < 4; ++i) { const int ch = tid + i * 256; \
;     *(u32x4*)(kbuf + (ch >> 2) * 40 + (ch & 3) * 8) = sr[i]; } } while (0)
; #define LOADV(v_, tid) do { _Pragma("unroll") for (int i = 0; i < 8; ++i) { const int idx = tid + i * 256, f = idx >> 6; \
;     sr[i] = VTg[(((v_) >> 1) * 4 + (f >> 3)) * 1024 + (((v_) & 1) * 8 + (f & 7)) * 64 + (idx & 63)]; } } while (0)
; #define STOREV(tid) do { _Pragma("unroll") for (int i = 0; i < 8; ++i) vbuf[tid + i * 256] = sr[i]; } while (0)
; DI void attn_prompt_block(const Params& p, int l, int b, int hh, int tt4, char* smem, bfr* Obuf) {
;     ...
;   for (int c = 0; c < 8; ++c) {
;     if (c < 7) LOADK(c + 1); else LOADV(0, tid);
;     bf16x8 qf[2];
; #pragma unroll
;     for (int ksl = 0; ksl < 2; ++ksl) qf[ksl] = *(const bf16x8*)(p.ACT2 + qoff + (c * 2 + ksl) * 16);
; #pragma unroll
;     for (int ksl = 0; ksl < 2; ++ksl)
; #pragma unroll
;       for (int m = 0; m < 8; ++m) {
;         bf16x8 kf = *(const bf16x8*)(kbuf + (m * 32 + r) * 40 + ksl * 16 + hl * 8);
;         st[m] = MFMA32(kf, qf[ksl], st[m]);
;       }
;     __syncthreads();
;     if (c < 7) STOREK(); else STOREV(tid);
;     __syncthreads();
	global_load_dwordx4 v[152:155], v[128:129], off offset:320
	v_mfma_f32_32x32x16_bf16 v[80:95], v[216:219], v[198:201], v[80:95]
	ds_read_b128 v[156:159], v133
	ds_read_b128 v[202:205], v133 offset:32
	v_mfma_f32_32x32x16_bf16 v[64:79], v[220:223], v[198:201], v[64:79]
	v_mfma_f32_32x32x16_bf16 v[48:63], v[224:227], v[198:201], v[48:63]
	v_mfma_f32_32x32x16_bf16 v[32:47], v[228:231], v[198:201], v[32:47]
	v_mfma_f32_32x32x16_bf16 v[16:31], v[232:235], v[198:201], v[16:31]
	v_mfma_f32_32x32x16_bf16 v[0:15], v[236:239], v[198:201], v[0:15]
	global_load_dwordx4 v[198:201], v[128:129], off offset:352
	s_waitcnt vmcnt(1) lgkmcnt(1)
	v_mfma_f32_32x32x16_bf16 v[112:127], v[156:159], v[152:155], v[112:127]
	ds_read_b128 v[156:159], v133 offset:2560
	ds_read_b128 v[206:209], v133 offset:2592
	s_waitcnt lgkmcnt(1)
	v_mfma_f32_32x32x16_bf16 v[96:111], v[156:159], v[152:155], v[96:111]
	ds_read_b128 v[156:159], v133 offset:5120
	ds_read_b128 v[216:219], v133 offset:5152
	s_waitcnt lgkmcnt(1)
	v_mfma_f32_32x32x16_bf16 v[80:95], v[156:159], v[152:155], v[80:95]
	ds_read_b128 v[156:159], v133 offset:7680
	ds_read_b128 v[220:223], v133 offset:7712
	s_waitcnt lgkmcnt(1)
	v_mfma_f32_32x32x16_bf16 v[64:79], v[156:159], v[152:155], v[64:79]
	ds_read_b128 v[156:159], v133 offset:10240
	ds_read_b128 v[224:227], v133 offset:10272
	s_waitcnt lgkmcnt(1)
	v_mfma_f32_32x32x16_bf16 v[48:63], v[156:159], v[152:155], v[48:63]
	ds_read_b128 v[156:159], v133 offset:12800
	ds_read_b128 v[228:231], v133 offset:12832
	s_waitcnt lgkmcnt(1)
	v_mfma_f32_32x32x16_bf16 v[32:47], v[156:159], v[152:155], v[32:47]
	ds_read_b128 v[156:159], v133 offset:15360
	ds_read_b128 v[232:235], v133 offset:15392
	s_waitcnt lgkmcnt(1)
	v_mfma_f32_32x32x16_bf16 v[16:31], v[156:159], v[152:155], v[16:31]
	ds_read_b128 v[156:159], v133 offset:17920
	ds_read_b128 v[236:239], v133 offset:17952
	s_waitcnt lgkmcnt(1)
	v_mfma_f32_32x32x16_bf16 v[0:15], v[156:159], v[152:155], v[0:15]
	global_load_dwordx4 v[152:155], v[142:143], off offset:384
	global_load_dwordx4 v[156:159], v[144:145], off offset:384
	s_waitcnt vmcnt(2)
	v_mfma_f32_32x32x16_bf16 v[112:127], v[202:205], v[198:201], v[112:127]
	v_mfma_f32_32x32x16_bf16 v[96:111], v[206:209], v[198:201], v[96:111]
	global_load_dwordx4 v[202:205], v[138:139], off offset:384
	global_load_dwordx4 v[206:209], v[140:141], off offset:384
	s_waitcnt lgkmcnt(0)
	s_barrier
	s_waitcnt vmcnt(3)
	ds_write_b128 v130, v[152:155]
	s_waitcnt vmcnt(2)
	ds_write_b128 v132, v[156:159]
	s_waitcnt vmcnt(1)
	ds_write_b128 v134, v[202:205]
	s_waitcnt vmcnt(0)
	ds_write_b128 v136, v[206:209]
	s_waitcnt lgkmcnt(0)
	s_barrier
	global_load_dwordx4 v[152:155], v[128:129], off offset:384
	ds_read_b128 v[156:159], v133
	ds_read_b128 v[202:205], v133 offset:32
	v_mfma_f32_32x32x16_bf16 v[80:95], v[216:219], v[198:201], v[80:95]
	v_mfma_f32_32x32x16_bf16 v[64:79], v[220:223], v[198:201], v[64:79]
	v_mfma_f32_32x32x16_bf16 v[48:63], v[224:227], v[198:201], v[48:63]
	v_mfma_f32_32x32x16_bf16 v[32:47], v[228:231], v[198:201], v[32:47]
	v_mfma_f32_32x32x16_bf16 v[16:31], v[232:235], v[198:201], v[16:31]
	v_mfma_f32_32x32x16_bf16 v[0:15], v[236:239], v[198:201], v[0:15]
	global_load_dwordx4 v[198:201], v[128:129], off offset:416
	s_waitcnt vmcnt(1) lgkmcnt(1)
	v_mfma_f32_32x32x16_bf16 v[112:127], v[156:159], v[152:155], v[112:127]
	ds_read_b128 v[156:159], v133 offset:2560
	ds_read_b128 v[206:209], v133 offset:2592
	s_waitcnt lgkmcnt(1)
	v_mfma_f32_32x32x16_bf16 v[96:111], v[156:159], v[152:155], v[96:111]
	ds_read_b128 v[156:159], v133 offset:5120
	ds_read_b128 v[216:219], v133 offset:5152
	s_waitcnt lgkmcnt(1)
	v_mfma_f32_32x32x16_bf16 v[80:95], v[156:159], v[152:155], v[80:95]
	ds_read_b128 v[156:159], v133 offset:7680
	ds_read_b128 v[220:223], v133 offset:7712
	s_waitcnt lgkmcnt(1)
	v_mfma_f32_32x32x16_bf16 v[64:79], v[156:159], v[152:155], v[64:79]
	ds_read_b128 v[156:159], v133 offset:10240
	ds_read_b128 v[224:227], v133 offset:10272
	s_waitcnt lgkmcnt(1)
	v_mfma_f32_32x32x16_bf16 v[48:63], v[156:159], v[152:155], v[48:63]
	ds_read_b128 v[156:159], v133 offset:12800
	ds_read_b128 v[228:231], v133 offset:12832
	s_waitcnt lgkmcnt(1)
	v_mfma_f32_32x32x16_bf16 v[32:47], v[156:159], v[152:155], v[32:47]
	ds_read_b128 v[156:159], v133 offset:15360
	ds_read_b128 v[232:235], v133 offset:15392
	s_waitcnt lgkmcnt(1)
	v_mfma_f32_32x32x16_bf16 v[16:31], v[156:159], v[152:155], v[16:31]
	ds_read_b128 v[156:159], v133 offset:17920
	ds_read_b128 v[236:239], v133 offset:17952
	s_waitcnt lgkmcnt(1)
	v_mfma_f32_32x32x16_bf16 v[0:15], v[156:159], v[152:155], v[0:15]
	global_load_dwordx4 v[152:155], v[142:143], off offset:448
	s_nop 0
	global_load_dwordx4 v[142:145], v[144:145], off offset:448
	s_nop 0
	global_load_dwordx4 v[156:159], v[138:139], off offset:448
	s_nop 0
	global_load_dwordx4 v[138:141], v[140:141], off offset:448
	s_waitcnt lgkmcnt(0)
	s_barrier
	s_waitcnt vmcnt(3)
	ds_write_b128 v130, v[152:155]
	s_waitcnt vmcnt(2)
	ds_write_b128 v132, v[142:145]
	s_waitcnt vmcnt(1)
	ds_write_b128 v134, v[156:159]
	s_waitcnt vmcnt(0)
	ds_write_b128 v136, v[138:141]
	s_waitcnt lgkmcnt(0)
	s_barrier
; #define MFMA32(a, b, c) __builtin_amdgcn_mfma_f32_32x32x16_bf16((a), (b), (c), 0, 0, 0)
; #define LOADK(c_) do { _Pragma("unroll") for (int i = 0; i < 4; ++i) { const int ch = tid + i * 256; \
;     sr[i] = *(const u32x4*)(Kg + (ch >> 2) * 1024 + (c_) * 32 + (ch & 3) * 8); } } while (0)
; #define STOREK() do { _Pragma("unroll") for (int i = 0; i < 4; ++i) { const int ch = tid + i * 256; \
;     *(u32x4*)(kbuf + (ch >> 2) * 40 + (ch & 3) * 8) = sr[i]; } } while (0)
; #define LOADV(v_, tid) do { _Pragma("unroll") for (int i = 0; i < 8; ++i) { const int idx = tid + i * 256, f = idx >> 6; \
;     sr[i] = VTg[(((v_) >> 1) * 4 + (f >> 3)) * 1024 + (((v_) & 1) * 8 + (f & 7)) * 64 + (idx & 63)]; } } while (0)
; #define STOREV(tid) do { _Pragma("unroll") for (int i = 0; i < 8; ++i) vbuf[tid + i * 256] = sr[i]; } while (0)
; DI void attn_prompt_block(const Params& p, int l, int b, int hh, int tt4, char* smem, bfr* Obuf) {
;     ...
;   for (int c = 0; c < 8; ++c) {
;     if (c < 7) LOADK(c + 1); else LOADV(0, tid);
;     bf16x8 qf[2];
; #pragma unroll
;     for (int ksl = 0; ksl < 2; ++ksl) qf[ksl] = *(const bf16x8*)(p.ACT2 + qoff + (c * 2 + ksl) * 16);
; #pragma unroll
;     for (int ksl = 0; ksl < 2; ++ksl)
; #pragma unroll
;       for (int m = 0; m < 8; ++m) {
;         bf16x8 kf = *(const bf16x8*)(kbuf + (m * 32 + r) * 40 + ksl * 16 + hl * 8);
;         st[m] = MFMA32(kf, qf[ksl], st[m]);
;       }
;     __syncthreads();
;     if (c < 7) STOREK(); else STOREV(tid);
;     __syncthreads();
;   }
;   float mx = -3.0e38f;
; #pragma unroll
;   for (int m = 0; m < 8; ++m)
; #pragma unroll
;     for (int q = 0; q < 16; ++q) mx = fmaxf(mx, st[m][q]);
	global_load_dwordx4 v[134:137], v[128:129], off offset:448
	v_lshlrev_b32_e32 v138, 1, v151
	v_and_b32_e32 v132, 63, v148
	v_lshlrev_b32_e32 v130, 1, v148
	v_and_b32_e32 v152, 0x1ff, v148
	v_and_b32_e32 v138, 0xfffffc00, v138
	v_and_b32_e32 v139, 0x1c0, v151
	v_and_or_b32 v158, v130, s41, v152
	v_or3_b32 v138, v139, v138, v132
	v_ashrrev_i32_e32 v159, 31, v158
	v_ashrrev_i32_e32 v139, 31, v138
	v_lshl_add_u64 v[130:131], v[158:159], 4, s[20:21]
	v_lshl_add_u64 v[142:143], v[138:139], 4, s[20:21]
	global_load_dwordx4 v[138:141], v[130:131], off
	s_nop 0
	global_load_dwordx4 v[142:145], v[142:143], off
	v_mfma_f32_32x32x16_bf16 v[112:127], v[202:205], v[198:201], v[112:127]
	global_load_dwordx4 v[154:157], v[128:129], off offset:480
	v_lshlrev_b32_e32 v130, 1, v150
	v_and_or_b32 v130, v130, s41, v152
	v_ashrrev_i32_e32 v131, 31, v130
	v_lshl_add_u64 v[130:131], v[130:131], 4, s[20:21]
	global_load_dwordx4 v[150:153], v[130:131], off
	v_mfma_f32_32x32x16_bf16 v[96:111], v[206:209], v[198:201], v[96:111]
	v_mfma_f32_32x32x16_bf16 v[80:95], v[216:219], v[198:201], v[80:95]
	v_mfma_f32_32x32x16_bf16 v[64:79], v[220:223], v[198:201], v[64:79]
	v_mfma_f32_32x32x16_bf16 v[48:63], v[224:227], v[198:201], v[48:63]
	v_mfma_f32_32x32x16_bf16 v[32:47], v[228:231], v[198:201], v[32:47]
	v_mfma_f32_32x32x16_bf16 v[16:31], v[232:235], v[198:201], v[16:31]
	v_mfma_f32_32x32x16_bf16 v[0:15], v[236:239], v[198:201], v[0:15]
	ds_read_b128 v[128:131], v133
	ds_read_b128 v[198:201], v133 offset:32
	ds_read_b128 v[202:205], v133 offset:2560
	s_waitcnt vmcnt(4) lgkmcnt(2)
	v_mfma_f32_32x32x16_bf16 v[112:127], v[128:131], v[134:137], v[112:127]
	v_lshlrev_b32_e32 v128, 1, v149
	v_and_b32_e32 v128, 0xfffffc00, v128
	v_and_b32_e32 v129, 0x1c0, v149
	v_or3_b32 v182, v129, v128, v132
	ds_read_b128 v[128:131], v133 offset:5120
	ds_read_b128 v[206:209], v133 offset:2592
	v_ashrrev_i32_e32 v183, 31, v182
	v_lshl_add_u64 v[182:183], v[182:183], 4, s[20:21]
	s_waitcnt lgkmcnt(1)
	v_mfma_f32_32x32x16_bf16 v[80:95], v[128:131], v[134:137], v[80:95]
	v_add_u32_e32 v128, 0x500, v148
	v_lshlrev_b32_e32 v129, 1, v128
	v_and_b32_e32 v129, 0xfffffc00, v129
	v_and_b32_e32 v128, 0x1c0, v128
	v_or3_b32 v194, v128, v129, v132
	v_ashrrev_i32_e32 v195, 31, v194
	v_lshl_add_u64 v[194:195], v[194:195], 4, s[20:21]
	v_mfma_f32_32x32x16_bf16 v[96:111], v[202:205], v[134:137], v[96:111]
	global_load_dwordx4 v[202:205], v[182:183], off
	ds_read_b128 v[216:219], v133 offset:7680
	ds_read_b128 v[220:223], v133 offset:5152
	ds_read_b128 v[128:131], v133 offset:10240
	ds_read_b128 v[224:227], v133 offset:7712
	v_add_u32_e32 v182, 0x800, v158
	v_ashrrev_i32_e32 v183, 31, v182
	v_lshl_add_u64 v[182:183], v[182:183], 4, s[20:21]
	v_add_u32_e32 v158, 0xc00, v158
	s_waitcnt vmcnt(2)
	v_mfma_f32_32x32x16_bf16 v[112:127], v[198:201], v[154:157], v[112:127]
	v_ashrrev_i32_e32 v159, 31, v158
	s_waitcnt lgkmcnt(1)
	v_mfma_f32_32x32x16_bf16 v[48:63], v[128:131], v[134:137], v[48:63]
	v_add_u32_e32 v130, 0x700, v148
	v_lshlrev_b32_e32 v131, 1, v130
	v_and_b32_e32 v131, 0xfffffc00, v131
	v_and_b32_e32 v130, 0x1c0, v130
	v_or3_b32 v130, v130, v131, v132
	s_nop 3
	v_max3_f32 v132, v112, s44, v113
	v_max3_f32 v132, v132, v114, v115
	v_mfma_f32_32x32x16_bf16 v[96:111], v[206:209], v[154:157], v[96:111]
	v_max3_f32 v132, v132, v116, v117
	v_max3_f32 v132, v132, v118, v119
	v_max3_f32 v132, v132, v120, v121
	v_max3_f32 v132, v132, v122, v123
	v_max3_f32 v132, v132, v124, v125
	v_max3_f32 v132, v132, v126, v127
	v_ashrrev_i32_e32 v131, 31, v130
	v_mfma_f32_32x32x16_bf16 v[64:79], v[216:219], v[134:137], v[64:79]
	s_nop 3
	v_max3_f32 v132, v132, v96, v97
	v_max3_f32 v132, v132, v98, v99
	v_max3_f32 v132, v132, v100, v101
	v_max3_f32 v132, v132, v102, v103
	v_max3_f32 v132, v132, v104, v105
	v_max3_f32 v132, v132, v106, v107
	v_max3_f32 v132, v132, v108, v109
	v_mfma_f32_32x32x16_bf16 v[80:95], v[220:223], v[154:157], v[80:95]
	v_max3_f32 v132, v132, v110, v111
	global_load_dwordx4 v[216:219], v[182:183], off
	global_load_dwordx4 v[228:231], v[194:195], off
	ds_read_b128 v[232:235], v133 offset:12800
	ds_read_b128 v[236:239], v133 offset:10272
	ds_read_b128 v[240:243], v133 offset:15360
	ds_read_b128 v[244:247], v133 offset:12832
	v_lshl_add_u64 v[128:129], v[158:159], 4, s[20:21]
	v_lshl_add_u64 v[130:131], v[130:131], 4, s[20:21]
	s_nop 2
	v_max3_f32 v132, v132, v80, v81
	s_waitcnt lgkmcnt(4)
	v_mfma_f32_32x32x16_bf16 v[64:79], v[224:227], v[154:157], v[64:79]
	v_max3_f32 v132, v132, v82, v83
	v_max3_f32 v132, v132, v84, v85
	v_max3_f32 v132, v132, v86, v87
	v_max3_f32 v132, v132, v88, v89
	v_max3_f32 v132, v132, v90, v91
	v_max3_f32 v132, v132, v92, v93
	v_max3_f32 v132, v132, v94, v95
	s_waitcnt lgkmcnt(3)
	v_mfma_f32_32x32x16_bf16 v[32:47], v[232:235], v[134:137], v[32:47]
	s_nop 2
	v_max3_f32 v132, v132, v64, v65
	v_max3_f32 v132, v132, v66, v67
	v_max3_f32 v132, v132, v68, v69
	v_max3_f32 v132, v132, v70, v71
	v_max3_f32 v132, v132, v72, v73
	v_max3_f32 v132, v132, v74, v75
	v_max3_f32 v132, v132, v76, v77
	s_waitcnt lgkmcnt(2)
	v_mfma_f32_32x32x16_bf16 v[48:63], v[236:239], v[154:157], v[48:63]
	global_load_dwordx4 v[232:235], v[128:129], off
	s_nop 0
	global_load_dwordx4 v[128:131], v[130:131], off
	ds_read_b128 v[248:251], v133 offset:15392
	v_max3_f32 v132, v132, v78, v79
	s_nop 6
	v_max3_f32 v132, v132, v48, v49
	s_waitcnt lgkmcnt(2)
	v_mfma_f32_32x32x16_bf16 v[16:31], v[240:243], v[134:137], v[16:31]
	v_max3_f32 v132, v132, v50, v51
	v_max3_f32 v132, v132, v52, v53
	v_max3_f32 v132, v132, v54, v55
	ds_read_b128 v[240:243], v133 offset:17920
	ds_read_b128 v[210:213], v133 offset:17952
	v_max3_f32 v132, v132, v56, v57
	v_max3_f32 v132, v132, v58, v59
	v_max3_f32 v132, v132, v60, v61
	s_waitcnt lgkmcnt(3)
	v_mfma_f32_32x32x16_bf16 v[32:47], v[244:247], v[154:157], v[32:47]
	v_max3_f32 v132, v132, v62, v63
	s_waitcnt lgkmcnt(0)
	s_barrier
; #define STOREK() do { _Pragma("unroll") for (int i = 0; i < 4; ++i) { const int ch = tid + i * 256; \
;     *(u32x4*)(kbuf + (ch >> 2) * 40 + (ch & 3) * 8) = sr[i]; } } while (0)
; #define STOREV(tid) do { _Pragma("unroll") for (int i = 0; i < 8; ++i) vbuf[tid + i * 256] = sr[i]; } while (0)
; DI void attn_prompt_block(const Params& p, int l, int b, int hh, int tt4, char* smem, bfr* Obuf) {
;     ...
;     if (c < 7) STOREK(); else STOREV(tid);
;     __syncthreads();
;   }
;   float mx = -3.0e38f;
; #pragma unroll
;   for (int m = 0; m < 8; ++m)
; #pragma unroll
;     for (int q = 0; q < 16; ++q) mx = fmaxf(mx, st[m][q]);
;   mx = fmaxf(mx, __shfl_xor(mx, 32));
;   float sum = 0.f;
; #pragma unroll
;   for (int m = 0; m < 8; ++m)
; #pragma unroll
;     for (int q = 0; q < 16; ++q) {
;       float e = __expf((st[m][q] - mx) * 0.0625f);
;       st[m][q] = e;
;       sum += e;
;     }
	ds_write_b128 v147, v[138:141]
	ds_write_b128 v147, v[142:145] offset:4096
	s_waitcnt vmcnt(5)
	ds_write_b128 v147, v[150:153] offset:8192
	s_waitcnt vmcnt(4)
	ds_write_b128 v147, v[202:205] offset:12288
	s_waitcnt vmcnt(3)
	ds_write_b128 v147, v[216:219] offset:16384
	s_waitcnt vmcnt(2)
	ds_write_b128 v147, v[228:231] offset:20480
	s_waitcnt vmcnt(1)
	ds_write_b128 v147, v[232:235] offset:24576
	v_max3_f32 v132, v132, v32, v33
	v_mfma_f32_32x32x16_bf16 v[16:31], v[248:251], v[154:157], v[16:31]
	v_max3_f32 v132, v132, v34, v35
	v_max3_f32 v132, v132, v36, v37
	v_max3_f32 v132, v132, v38, v39
	v_max3_f32 v132, v132, v40, v41
	v_max3_f32 v132, v132, v42, v43
	v_max3_f32 v132, v132, v44, v45
	v_max3_f32 v132, v132, v46, v47
	v_mfma_f32_32x32x16_bf16 v[0:15], v[240:243], v[134:137], v[0:15]
	s_nop 3
	v_max3_f32 v132, v132, v16, v17
	v_max3_f32 v132, v132, v18, v19
	v_max3_f32 v132, v132, v20, v21
	v_max3_f32 v132, v132, v22, v23
	v_max3_f32 v132, v132, v24, v25
	v_max3_f32 v132, v132, v26, v27
	v_max3_f32 v132, v132, v28, v29
	v_mfma_f32_32x32x16_bf16 v[0:15], v[210:213], v[154:157], v[0:15]
	v_max3_f32 v132, v132, v30, v31
	v_mov_b32_e32 v210, v196
	s_waitcnt vmcnt(0)
	ds_write_b128 v147, v[128:131] offset:28672
	s_waitcnt lgkmcnt(0)
	s_barrier
	s_nop 5
	v_max3_f32 v132, v132, v0, v1
	v_max3_f32 v132, v132, v2, v3
	v_max3_f32 v132, v132, v4, v5
	v_max3_f32 v132, v132, v6, v7
	v_max3_f32 v132, v132, v8, v9
	v_max3_f32 v132, v132, v10, v11
	v_max3_f32 v132, v132, v12, v13
	v_max3_f32 v133, v132, v14, v15
	v_cndmask_b32_e32 v132, v190, v191, vcc
	v_lshlrev_b32_e32 v132, 2, v132
	ds_bpermute_b32 v134, v132, v133
	v_and_b32_e32 v212, 0x1ff, v210
	v_or_b32_e32 v194, 0x200, v212
	s_waitcnt lgkmcnt(0)
	v_max_f32_e32 v134, v134, v134
	v_max_f32_e32 v133, v133, v134
	v_sub_f32_e32 v112, v112, v133
	v_mul_f32_e32 v112, 0x3d800000, v112
	v_sub_f32_e32 v113, v113, v133
	v_mul_f32_e32 v112, 0x3fb8aa3b, v112
	v_mul_f32_e32 v113, 0x3d800000, v113
	v_sub_f32_e32 v114, v114, v133
	v_exp_f32_e32 v112, v112
	v_mul_f32_e32 v113, 0x3fb8aa3b, v113
	v_mul_f32_e32 v114, 0x3d800000, v114
	v_sub_f32_e32 v115, v115, v133
	v_exp_f32_e32 v113, v113
	v_mul_f32_e32 v114, 0x3fb8aa3b, v114
	v_mul_f32_e32 v115, 0x3d800000, v115
	v_sub_f32_e32 v116, v116, v133
	v_exp_f32_e32 v114, v114
	v_mul_f32_e32 v115, 0x3fb8aa3b, v115
	v_mul_f32_e32 v116, 0x3d800000, v116
	v_sub_f32_e32 v117, v117, v133
	v_exp_f32_e32 v115, v115
	v_mul_f32_e32 v116, 0x3fb8aa3b, v116
	v_mul_f32_e32 v117, 0x3d800000, v117
	v_sub_f32_e32 v118, v118, v133
	v_add_f32_e32 v134, 0, v112
	v_exp_f32_e32 v116, v116
	v_mul_f32_e32 v117, 0x3fb8aa3b, v117
	v_mul_f32_e32 v118, 0x3d800000, v118
	v_sub_f32_e32 v119, v119, v133
	v_add_f32_e32 v134, v113, v134
	v_exp_f32_e32 v117, v117
	v_mul_f32_e32 v118, 0x3fb8aa3b, v118
	v_mul_f32_e32 v119, 0x3d800000, v119
	v_sub_f32_e32 v120, v120, v133
	v_add_f32_e32 v134, v114, v134
	v_exp_f32_e32 v118, v118
	v_mul_f32_e32 v119, 0x3fb8aa3b, v119
	v_mul_f32_e32 v120, 0x3d800000, v120
	v_sub_f32_e32 v121, v121, v133
	v_add_f32_e32 v134, v115, v134
	v_exp_f32_e32 v119, v119
	v_mul_f32_e32 v120, 0x3fb8aa3b, v120
	v_mul_f32_e32 v121, 0x3d800000, v121
	v_sub_f32_e32 v122, v122, v133
	v_add_f32_e32 v134, v116, v134
	v_exp_f32_e32 v120, v120
	v_mul_f32_e32 v121, 0x3fb8aa3b, v121
	v_mul_f32_e32 v122, 0x3d800000, v122
	v_sub_f32_e32 v123, v123, v133
	v_add_f32_e32 v134, v117, v134
	v_exp_f32_e32 v121, v121
	v_mul_f32_e32 v122, 0x3fb8aa3b, v122
	v_mul_f32_e32 v123, 0x3d800000, v123
	v_sub_f32_e32 v124, v124, v133
	v_add_f32_e32 v134, v118, v134
	v_exp_f32_e32 v122, v122
	v_mul_f32_e32 v123, 0x3fb8aa3b, v123
	v_mul_f32_e32 v124, 0x3d800000, v124
	v_sub_f32_e32 v125, v125, v133
	v_add_f32_e32 v134, v119, v134
	v_exp_f32_e32 v123, v123
	v_mul_f32_e32 v124, 0x3fb8aa3b, v124
	v_mul_f32_e32 v125, 0x3d800000, v125
	v_sub_f32_e32 v126, v126, v133
	v_add_f32_e32 v134, v120, v134
	v_exp_f32_e32 v124, v124
	v_mul_f32_e32 v125, 0x3fb8aa3b, v125
	v_mul_f32_e32 v126, 0x3d800000, v126
	v_sub_f32_e32 v127, v127, v133
	v_add_f32_e32 v134, v121, v134
	v_exp_f32_e32 v125, v125
	v_mul_f32_e32 v126, 0x3fb8aa3b, v126
	v_mul_f32_e32 v127, 0x3d800000, v127
	v_add_f32_e32 v134, v122, v134
	v_exp_f32_e32 v126, v126
	v_mul_f32_e32 v127, 0x3fb8aa3b, v127
	v_add_f32_e32 v134, v123, v134
	v_exp_f32_e32 v127, v127
	v_add_f32_e32 v134, v124, v134
	v_sub_f32_e32 v96, v96, v133
	v_add_f32_e32 v134, v125, v134
	v_mul_f32_e32 v96, 0x3d800000, v96
	v_add_f32_e32 v134, v126, v134
	v_mul_f32_e32 v96, 0x3fb8aa3b, v96
	v_add_f32_e32 v137, v127, v134
	v_exp_f32_e32 v134, v96
	v_sub_f32_e32 v96, v97, v133
	v_mul_f32_e32 v96, 0x3d800000, v96
	v_mul_f32_e32 v96, 0x3fb8aa3b, v96
	v_exp_f32_e32 v135, v96
	v_sub_f32_e32 v96, v98, v133
	v_mul_f32_e32 v96, 0x3d800000, v96
	v_mul_f32_e32 v96, 0x3fb8aa3b, v96
	v_exp_f32_e32 v98, v96
	v_sub_f32_e32 v96, v99, v133
	v_sub_f32_e32 v97, v100, v133
	v_mul_f32_e32 v96, 0x3d800000, v96
	v_mul_f32_e32 v97, 0x3d800000, v97
	v_mul_f32_e32 v96, 0x3fb8aa3b, v96
	v_mul_f32_e32 v97, 0x3fb8aa3b, v97
	v_sub_f32_e32 v80, v80, v133
	v_exp_f32_e32 v136, v96
	v_add_f32_e32 v96, v134, v137
	v_exp_f32_e32 v137, v97
	v_sub_f32_e32 v97, v101, v133
	v_mul_f32_e32 v80, 0x3d800000, v80
	v_mul_f32_e32 v97, 0x3d800000, v97
	v_mul_f32_e32 v80, 0x3fb8aa3b, v80
	v_mul_f32_e32 v97, 0x3fb8aa3b, v97
	v_exp_f32_e32 v144, v80
	v_sub_f32_e32 v80, v81, v133
	v_sub_f32_e32 v81, v84, v133
	v_exp_f32_e32 v138, v97
	v_sub_f32_e32 v97, v102, v133
	v_mul_f32_e32 v81, 0x3d800000, v81
	v_mul_f32_e32 v97, 0x3d800000, v97
	v_mul_f32_e32 v81, 0x3fb8aa3b, v81
	v_mul_f32_e32 v97, 0x3fb8aa3b, v97
	v_exp_f32_e32 v150, v81
	v_sub_f32_e32 v81, v85, v133
; DI void attn_prompt_block(const Params& p, int l, int b, int hh, int tt4, char* smem, bfr* Obuf) {
;     ...
;   for (int m = 0; m < 8; ++m)
; #pragma unroll
;     for (int q = 0; q < 16; ++q) {
;       float e = __expf((st[m][q] - mx) * 0.0625f);
;       st[m][q] = e;
;       sum += e;
;     }
	v_exp_f32_e32 v139, v97
	v_sub_f32_e32 v97, v103, v133
	v_mul_f32_e32 v81, 0x3d800000, v81
	v_mul_f32_e32 v97, 0x3d800000, v97
	v_mul_f32_e32 v81, 0x3fb8aa3b, v81
	v_mul_f32_e32 v97, 0x3fb8aa3b, v97
	v_exp_f32_e32 v151, v81
	v_sub_f32_e32 v81, v86, v133
	v_exp_f32_e32 v140, v97
	v_sub_f32_e32 v97, v104, v133
	v_mul_f32_e32 v81, 0x3d800000, v81
	v_mul_f32_e32 v97, 0x3d800000, v97
	v_mul_f32_e32 v81, 0x3fb8aa3b, v81
	v_mul_f32_e32 v97, 0x3fb8aa3b, v97
	v_exp_f32_e32 v152, v81
	v_sub_f32_e32 v81, v87, v133
	v_exp_f32_e32 v141, v97
	v_sub_f32_e32 v97, v105, v133
	v_mul_f32_e32 v81, 0x3d800000, v81
	v_mul_f32_e32 v97, 0x3d800000, v97
	v_mul_f32_e32 v81, 0x3fb8aa3b, v81
	v_mul_f32_e32 v97, 0x3fb8aa3b, v97
	v_exp_f32_e32 v153, v81
	v_sub_f32_e32 v81, v88, v133
	v_exp_f32_e32 v142, v97
	v_sub_f32_e32 v97, v106, v133
	v_mul_f32_e32 v81, 0x3d800000, v81
	v_mul_f32_e32 v97, 0x3d800000, v97
	v_mul_f32_e32 v81, 0x3fb8aa3b, v81
	v_mul_f32_e32 v97, 0x3fb8aa3b, v97
	v_exp_f32_e32 v154, v81
	v_sub_f32_e32 v81, v89, v133
	v_exp_f32_e32 v143, v97
	v_sub_f32_e32 v97, v107, v133
	v_mul_f32_e32 v81, 0x3d800000, v81
	v_mul_f32_e32 v97, 0x3d800000, v97
	v_mul_f32_e32 v81, 0x3fb8aa3b, v81
	v_mul_f32_e32 v97, 0x3fb8aa3b, v97
	v_exp_f32_e32 v155, v81
	v_sub_f32_e32 v81, v90, v133
	v_exp_f32_e32 v107, v97
	v_sub_f32_e32 v97, v108, v133
	v_mul_f32_e32 v81, 0x3d800000, v81
	v_mul_f32_e32 v97, 0x3d800000, v97
	v_mul_f32_e32 v81, 0x3fb8aa3b, v81
	v_add_f32_e32 v96, v135, v96
	v_mul_f32_e32 v97, 0x3fb8aa3b, v97
	v_exp_f32_e32 v156, v81
	v_sub_f32_e32 v81, v91, v133
	v_add_f32_e32 v96, v98, v96
	v_exp_f32_e32 v108, v97
	v_sub_f32_e32 v97, v109, v133
	v_mul_f32_e32 v81, 0x3d800000, v81
	v_add_f32_e32 v96, v136, v96
	v_mul_f32_e32 v97, 0x3d800000, v97
	v_mul_f32_e32 v81, 0x3fb8aa3b, v81
	v_add_f32_e32 v96, v137, v96
	v_mul_f32_e32 v97, 0x3fb8aa3b, v97
	v_exp_f32_e32 v157, v81
	v_sub_f32_e32 v81, v92, v133
	v_sub_f32_e32 v64, v64, v133
	v_add_f32_e32 v96, v138, v96
	v_exp_f32_e32 v109, v97
	v_sub_f32_e32 v97, v110, v133
	v_mul_f32_e32 v81, 0x3d800000, v81
	v_mul_f32_e32 v64, 0x3d800000, v64
	v_add_f32_e32 v96, v139, v96
	v_mul_f32_e32 v97, 0x3d800000, v97
	v_mul_f32_e32 v81, 0x3fb8aa3b, v81
	v_mul_f32_e32 v64, 0x3fb8aa3b, v64
	v_add_f32_e32 v96, v140, v96
	v_mul_f32_e32 v97, 0x3fb8aa3b, v97
	v_mul_f32_e32 v80, 0x3d800000, v80
	v_exp_f32_e32 v158, v81
	v_sub_f32_e32 v81, v93, v133
	v_exp_f32_e32 v90, v64
	v_sub_f32_e32 v64, v65, v133
	v_sub_f32_e32 v65, v68, v133
	v_add_f32_e32 v96, v141, v96
	v_exp_f32_e32 v110, v97
	v_sub_f32_e32 v97, v111, v133
	v_mul_f32_e32 v80, 0x3fb8aa3b, v80
	v_mul_f32_e32 v81, 0x3d800000, v81
	v_mul_f32_e32 v65, 0x3d800000, v65
	v_add_f32_e32 v96, v142, v96
	v_mul_f32_e32 v97, 0x3d800000, v97
	v_exp_f32_e32 v145, v80
	v_sub_f32_e32 v80, v82, v133
	v_mul_f32_e32 v81, 0x3fb8aa3b, v81
	v_mul_f32_e32 v65, 0x3fb8aa3b, v65
	v_add_f32_e32 v96, v143, v96
	v_mul_f32_e32 v97, 0x3fb8aa3b, v97
	v_mul_f32_e32 v80, 0x3d800000, v80
	v_exp_f32_e32 v159, v81
	v_sub_f32_e32 v81, v94, v133
	v_exp_f32_e32 v94, v65
	v_sub_f32_e32 v65, v69, v133
	v_add_f32_e32 v96, v107, v96
	v_exp_f32_e32 v111, v97
	v_mul_f32_e32 v80, 0x3fb8aa3b, v80
	v_mul_f32_e32 v81, 0x3d800000, v81
	v_mul_f32_e32 v65, 0x3d800000, v65
	v_add_f32_e32 v96, v108, v96
	v_exp_f32_e32 v148, v80
	v_sub_f32_e32 v80, v83, v133
	v_mul_f32_e32 v81, 0x3fb8aa3b, v81
	v_mul_f32_e32 v65, 0x3fb8aa3b, v65
	v_add_f32_e32 v96, v109, v96
	v_mul_f32_e32 v80, 0x3d800000, v80
	v_exp_f32_e32 v88, v81
	v_sub_f32_e32 v81, v95, v133
	v_exp_f32_e32 v95, v65
	v_sub_f32_e32 v65, v70, v133
	v_add_f32_e32 v96, v110, v96
	v_mul_f32_e32 v80, 0x3fb8aa3b, v80
	v_mul_f32_e32 v65, 0x3d800000, v65
	v_add_f32_e32 v96, v111, v96
	v_exp_f32_e32 v149, v80
	v_mul_f32_e32 v65, 0x3fb8aa3b, v65
	v_add_f32_e32 v80, v144, v96
	v_exp_f32_e32 v96, v65
	v_sub_f32_e32 v65, v71, v133
	v_add_f32_e32 v80, v145, v80
	v_mul_f32_e32 v65, 0x3d800000, v65
	v_add_f32_e32 v80, v148, v80
	v_mul_f32_e32 v65, 0x3fb8aa3b, v65
	v_add_f32_e32 v80, v149, v80
	v_exp_f32_e32 v97, v65
	v_sub_f32_e32 v65, v72, v133
	v_add_f32_e32 v80, v150, v80
	v_mul_f32_e32 v65, 0x3d800000, v65
	v_add_f32_e32 v80, v151, v80
	v_mul_f32_e32 v65, 0x3fb8aa3b, v65
	v_add_f32_e32 v80, v152, v80
	v_exp_f32_e32 v99, v65
	v_sub_f32_e32 v65, v73, v133
	v_add_f32_e32 v80, v153, v80
	v_mul_f32_e32 v64, 0x3d800000, v64
	v_mul_f32_e32 v65, 0x3d800000, v65
	v_add_f32_e32 v80, v154, v80
	v_mul_f32_e32 v64, 0x3fb8aa3b, v64
	v_mul_f32_e32 v65, 0x3fb8aa3b, v65
	v_add_f32_e32 v80, v155, v80
	v_mul_f32_e32 v81, 0x3d800000, v81
	v_exp_f32_e32 v91, v64
	v_sub_f32_e32 v64, v66, v133
	v_exp_f32_e32 v100, v65
	v_sub_f32_e32 v65, v74, v133
	v_add_f32_e32 v80, v156, v80
	v_mul_f32_e32 v81, 0x3fb8aa3b, v81
	v_mul_f32_e32 v64, 0x3d800000, v64
	v_mul_f32_e32 v65, 0x3d800000, v65
	v_add_f32_e32 v80, v157, v80
	v_exp_f32_e32 v89, v81
	v_mul_f32_e32 v64, 0x3fb8aa3b, v64
	v_mul_f32_e32 v65, 0x3fb8aa3b, v65
	v_add_f32_e32 v80, v158, v80
	v_exp_f32_e32 v92, v64
	v_sub_f32_e32 v64, v67, v133
	v_exp_f32_e32 v101, v65
	v_sub_f32_e32 v65, v75, v133
	v_add_f32_e32 v80, v159, v80
	v_mul_f32_e32 v64, 0x3d800000, v64
	v_mul_f32_e32 v65, 0x3d800000, v65
	v_add_f32_e32 v80, v88, v80
	v_mul_f32_e32 v64, 0x3fb8aa3b, v64
	v_mul_f32_e32 v65, 0x3fb8aa3b, v65
	v_add_f32_e32 v80, v89, v80
	v_exp_f32_e32 v93, v64
	v_exp_f32_e32 v102, v65
	v_sub_f32_e32 v65, v76, v133
	v_add_f32_e32 v64, v90, v80
	v_mul_f32_e32 v65, 0x3d800000, v65
	v_add_f32_e32 v64, v91, v64
	v_mul_f32_e32 v65, 0x3fb8aa3b, v65
	v_add_f32_e32 v64, v92, v64
	v_exp_f32_e32 v103, v65
	v_sub_f32_e32 v65, v77, v133
	v_add_f32_e32 v64, v93, v64
	v_mul_f32_e32 v65, 0x3d800000, v65
; DI void attn_prompt_block(const Params& p, int l, int b, int hh, int tt4, char* smem, bfr* Obuf) {
;     ...
;   float sum = 0.f;
; #pragma unroll
;   for (int m = 0; m < 8; ++m)
; #pragma unroll
;     for (int q = 0; q < 16; ++q) {
;       float e = __expf((st[m][q] - mx) * 0.0625f);
;       st[m][q] = e;
;       sum += e;
;     }
	v_add_f32_e32 v64, v94, v64
	v_mul_f32_e32 v65, 0x3fb8aa3b, v65
	v_add_f32_e32 v64, v95, v64
	v_exp_f32_e32 v104, v65
	v_sub_f32_e32 v65, v78, v133
	v_add_f32_e32 v64, v96, v64
	v_mul_f32_e32 v65, 0x3d800000, v65
	v_add_f32_e32 v64, v97, v64
	v_mul_f32_e32 v65, 0x3fb8aa3b, v65
	v_add_f32_e32 v64, v99, v64
	v_exp_f32_e32 v105, v65
	v_sub_f32_e32 v65, v79, v133
	v_add_f32_e32 v64, v100, v64
	v_mul_f32_e32 v65, 0x3d800000, v65
	v_sub_f32_e32 v48, v48, v133
	v_add_f32_e32 v64, v101, v64
	v_mul_f32_e32 v65, 0x3fb8aa3b, v65
	v_mul_f32_e32 v48, 0x3d800000, v48
	v_sub_f32_e32 v49, v49, v133
	v_add_f32_e32 v64, v102, v64
	v_exp_f32_e32 v106, v65
	v_mul_f32_e32 v48, 0x3fb8aa3b, v48
	v_mul_f32_e32 v49, 0x3d800000, v49
	v_sub_f32_e32 v50, v50, v133
	v_add_f32_e32 v64, v103, v64
	v_exp_f32_e32 v48, v48
	v_mul_f32_e32 v49, 0x3fb8aa3b, v49
	v_mul_f32_e32 v50, 0x3d800000, v50
	v_sub_f32_e32 v51, v51, v133
	v_add_f32_e32 v64, v104, v64
	v_exp_f32_e32 v49, v49
	v_mul_f32_e32 v50, 0x3fb8aa3b, v50
	v_mul_f32_e32 v51, 0x3d800000, v51
	v_sub_f32_e32 v52, v52, v133
	v_add_f32_e32 v64, v105, v64
	v_exp_f32_e32 v50, v50
	v_mul_f32_e32 v51, 0x3fb8aa3b, v51
	v_mul_f32_e32 v52, 0x3d800000, v52
	v_sub_f32_e32 v53, v53, v133
	v_add_f32_e32 v64, v106, v64
	v_exp_f32_e32 v51, v51
	v_mul_f32_e32 v52, 0x3fb8aa3b, v52
	v_mul_f32_e32 v53, 0x3d800000, v53
	v_sub_f32_e32 v54, v54, v133
	v_add_f32_e32 v64, v48, v64
	v_exp_f32_e32 v52, v52
	v_mul_f32_e32 v53, 0x3fb8aa3b, v53
	v_mul_f32_e32 v54, 0x3d800000, v54
	v_sub_f32_e32 v55, v55, v133
	v_add_f32_e32 v64, v49, v64
	v_exp_f32_e32 v53, v53
	v_mul_f32_e32 v54, 0x3fb8aa3b, v54
	v_mul_f32_e32 v55, 0x3d800000, v55
	v_sub_f32_e32 v56, v56, v133
	v_add_f32_e32 v64, v50, v64
	v_exp_f32_e32 v54, v54
	v_mul_f32_e32 v55, 0x3fb8aa3b, v55
	v_mul_f32_e32 v56, 0x3d800000, v56
	v_sub_f32_e32 v57, v57, v133
	v_add_f32_e32 v64, v51, v64
	v_exp_f32_e32 v55, v55
	v_mul_f32_e32 v56, 0x3fb8aa3b, v56
	v_mul_f32_e32 v57, 0x3d800000, v57
	v_sub_f32_e32 v58, v58, v133
	v_add_f32_e32 v64, v52, v64
	v_exp_f32_e32 v56, v56
	v_mul_f32_e32 v57, 0x3fb8aa3b, v57
	v_mul_f32_e32 v58, 0x3d800000, v58
	v_sub_f32_e32 v59, v59, v133
	v_add_f32_e32 v64, v53, v64
	v_exp_f32_e32 v57, v57
	v_mul_f32_e32 v58, 0x3fb8aa3b, v58
	v_mul_f32_e32 v59, 0x3d800000, v59
	v_sub_f32_e32 v60, v60, v133
	v_add_f32_e32 v64, v54, v64
	v_exp_f32_e32 v58, v58
	v_mul_f32_e32 v59, 0x3fb8aa3b, v59
	v_mul_f32_e32 v60, 0x3d800000, v60
	v_sub_f32_e32 v61, v61, v133
	v_add_f32_e32 v64, v55, v64
	v_exp_f32_e32 v59, v59
	v_mul_f32_e32 v60, 0x3fb8aa3b, v60
	v_mul_f32_e32 v61, 0x3d800000, v61
	v_sub_f32_e32 v62, v62, v133
	v_add_f32_e32 v64, v56, v64
	v_exp_f32_e32 v60, v60
	v_mul_f32_e32 v61, 0x3fb8aa3b, v61
	v_mul_f32_e32 v62, 0x3d800000, v62
	v_sub_f32_e32 v63, v63, v133
	v_add_f32_e32 v64, v57, v64
	v_exp_f32_e32 v61, v61
	v_mul_f32_e32 v62, 0x3fb8aa3b, v62
	v_mul_f32_e32 v63, 0x3d800000, v63
	v_sub_f32_e32 v32, v32, v133
	v_add_f32_e32 v64, v58, v64
	v_exp_f32_e32 v62, v62
	v_mul_f32_e32 v63, 0x3fb8aa3b, v63
	v_mul_f32_e32 v32, 0x3d800000, v32
	v_sub_f32_e32 v33, v33, v133
	v_add_f32_e32 v64, v59, v64
	v_exp_f32_e32 v63, v63
	v_mul_f32_e32 v32, 0x3fb8aa3b, v32
	v_mul_f32_e32 v33, 0x3d800000, v33
	v_sub_f32_e32 v34, v34, v133
	v_add_f32_e32 v64, v60, v64
	v_exp_f32_e32 v32, v32
	v_mul_f32_e32 v33, 0x3fb8aa3b, v33
	v_mul_f32_e32 v34, 0x3d800000, v34
	v_sub_f32_e32 v35, v35, v133
	v_add_f32_e32 v64, v61, v64
	v_exp_f32_e32 v33, v33
	v_mul_f32_e32 v34, 0x3fb8aa3b, v34
	v_mul_f32_e32 v35, 0x3d800000, v35
	v_sub_f32_e32 v36, v36, v133
	v_add_f32_e32 v64, v62, v64
	v_exp_f32_e32 v34, v34
	v_mul_f32_e32 v35, 0x3fb8aa3b, v35
	v_mul_f32_e32 v36, 0x3d800000, v36
	v_sub_f32_e32 v37, v37, v133
	v_add_f32_e32 v64, v63, v64
	v_exp_f32_e32 v35, v35
	v_mul_f32_e32 v36, 0x3fb8aa3b, v36
	v_mul_f32_e32 v37, 0x3d800000, v37
	v_sub_f32_e32 v38, v38, v133
	v_add_f32_e32 v64, v32, v64
	v_exp_f32_e32 v36, v36
	v_mul_f32_e32 v37, 0x3fb8aa3b, v37
	v_mul_f32_e32 v38, 0x3d800000, v38
	v_sub_f32_e32 v39, v39, v133
	v_add_f32_e32 v64, v33, v64
	v_exp_f32_e32 v37, v37
	v_mul_f32_e32 v38, 0x3fb8aa3b, v38
	v_mul_f32_e32 v39, 0x3d800000, v39
	v_sub_f32_e32 v40, v40, v133
	v_add_f32_e32 v64, v34, v64
	v_exp_f32_e32 v38, v38
	v_mul_f32_e32 v39, 0x3fb8aa3b, v39
	v_mul_f32_e32 v40, 0x3d800000, v40
	v_sub_f32_e32 v41, v41, v133
	v_add_f32_e32 v64, v35, v64
	v_exp_f32_e32 v39, v39
	v_mul_f32_e32 v40, 0x3fb8aa3b, v40
	v_mul_f32_e32 v41, 0x3d800000, v41
	v_sub_f32_e32 v42, v42, v133
	v_add_f32_e32 v64, v36, v64
	v_exp_f32_e32 v40, v40
	v_mul_f32_e32 v41, 0x3fb8aa3b, v41
	v_mul_f32_e32 v42, 0x3d800000, v42
	v_sub_f32_e32 v43, v43, v133
	v_sub_f32_e32 v0, v0, v133
	v_add_f32_e32 v64, v37, v64
	v_exp_f32_e32 v41, v41
	v_mul_f32_e32 v42, 0x3fb8aa3b, v42
	v_mul_f32_e32 v43, 0x3d800000, v43
	v_sub_f32_e32 v44, v44, v133
	v_mul_f32_e32 v0, 0x3d800000, v0
	v_add_f32_e32 v64, v38, v64
	v_exp_f32_e32 v42, v42
	v_mul_f32_e32 v43, 0x3fb8aa3b, v43
	v_mul_f32_e32 v44, 0x3d800000, v44
	v_sub_f32_e32 v45, v45, v133
	v_mul_f32_e32 v0, 0x3fb8aa3b, v0
	v_add_f32_e32 v64, v39, v64
	v_exp_f32_e32 v43, v43
	v_mul_f32_e32 v44, 0x3fb8aa3b, v44
	v_mul_f32_e32 v45, 0x3d800000, v45
	v_sub_f32_e32 v46, v46, v133
	v_exp_f32_e32 v160, v0
	v_sub_f32_e32 v0, v1, v133
	v_sub_f32_e32 v1, v4, v133
	v_add_f32_e32 v64, v40, v64
	v_exp_f32_e32 v44, v44
	v_mul_f32_e32 v45, 0x3fb8aa3b, v45
	v_mul_f32_e32 v46, 0x3d800000, v46
	v_sub_f32_e32 v47, v47, v133
	v_mul_f32_e32 v1, 0x3d800000, v1
	v_add_f32_e32 v64, v41, v64
	v_exp_f32_e32 v45, v45
	v_mul_f32_e32 v46, 0x3fb8aa3b, v46
	v_mul_f32_e32 v47, 0x3d800000, v47
	v_sub_f32_e32 v16, v16, v133
	v_mul_f32_e32 v1, 0x3fb8aa3b, v1
; DI void attn_prompt_block(const Params& p, int l, int b, int hh, int tt4, char* smem, bfr* Obuf) {
;     ...
;   float sum = 0.f;
; #pragma unroll
;   for (int m = 0; m < 8; ++m)
; #pragma unroll
;     for (int q = 0; q < 16; ++q) {
;       float e = __expf((st[m][q] - mx) * 0.0625f);
;       st[m][q] = e;
;       sum += e;
;     }
;   sum += __shfl_xor(sum, 32);
;   const float inv = 1.0f / sum;
;   bf16x8 pb[8][2];
; #pragma unroll
;   for (int m = 0; m < 8; ++m) { pb[m][0] = pack8(st[m], 0); pb[m][1] = pack8(st[m], 1); }
	v_add_f32_e32 v64, v42, v64
	v_exp_f32_e32 v46, v46
	v_mul_f32_e32 v47, 0x3fb8aa3b, v47
	v_mul_f32_e32 v16, 0x3d800000, v16
	v_sub_f32_e32 v17, v17, v133
	v_exp_f32_e32 v193, v1
	v_sub_f32_e32 v1, v5, v133
	v_add_f32_e32 v64, v43, v64
	v_exp_f32_e32 v47, v47
	v_mul_f32_e32 v16, 0x3fb8aa3b, v16
	v_mul_f32_e32 v17, 0x3d800000, v17
	v_sub_f32_e32 v18, v18, v133
	v_mul_f32_e32 v1, 0x3d800000, v1
	v_add_f32_e32 v64, v44, v64
	v_exp_f32_e32 v16, v16
	v_mul_f32_e32 v17, 0x3fb8aa3b, v17
	v_mul_f32_e32 v18, 0x3d800000, v18
	v_sub_f32_e32 v19, v19, v133
	v_mul_f32_e32 v1, 0x3fb8aa3b, v1
	v_add_f32_e32 v64, v45, v64
	v_exp_f32_e32 v17, v17
	v_mul_f32_e32 v18, 0x3fb8aa3b, v18
	v_mul_f32_e32 v19, 0x3d800000, v19
	v_sub_f32_e32 v20, v20, v133
	v_exp_f32_e32 v195, v1
	v_sub_f32_e32 v1, v6, v133
	v_add_f32_e32 v64, v46, v64
	v_exp_f32_e32 v18, v18
	v_mul_f32_e32 v19, 0x3fb8aa3b, v19
	v_mul_f32_e32 v20, 0x3d800000, v20
	v_sub_f32_e32 v21, v21, v133
	v_mul_f32_e32 v1, 0x3d800000, v1
	v_add_f32_e32 v64, v47, v64
	v_exp_f32_e32 v19, v19
	v_mul_f32_e32 v20, 0x3fb8aa3b, v20
	v_mul_f32_e32 v21, 0x3d800000, v21
	v_sub_f32_e32 v22, v22, v133
	v_mul_f32_e32 v1, 0x3fb8aa3b, v1
	v_add_f32_e32 v64, v16, v64
	v_exp_f32_e32 v20, v20
	v_mul_f32_e32 v21, 0x3fb8aa3b, v21
	v_mul_f32_e32 v22, 0x3d800000, v22
	v_sub_f32_e32 v23, v23, v133
	v_exp_f32_e32 v6, v1
	v_sub_f32_e32 v1, v7, v133
	v_add_f32_e32 v64, v17, v64
	v_exp_f32_e32 v21, v21
	v_mul_f32_e32 v22, 0x3fb8aa3b, v22
	v_mul_f32_e32 v23, 0x3d800000, v23
	v_sub_f32_e32 v24, v24, v133
	v_mul_f32_e32 v1, 0x3d800000, v1
	v_add_f32_e32 v64, v18, v64
	v_exp_f32_e32 v22, v22
	v_mul_f32_e32 v23, 0x3fb8aa3b, v23
	v_mul_f32_e32 v24, 0x3d800000, v24
	v_sub_f32_e32 v25, v25, v133
	v_mul_f32_e32 v1, 0x3fb8aa3b, v1
	v_add_f32_e32 v64, v19, v64
	v_exp_f32_e32 v23, v23
	v_mul_f32_e32 v24, 0x3fb8aa3b, v24
	v_mul_f32_e32 v25, 0x3d800000, v25
	v_sub_f32_e32 v26, v26, v133
	v_exp_f32_e32 v7, v1
	v_sub_f32_e32 v1, v8, v133
	v_add_f32_e32 v64, v20, v64
	v_exp_f32_e32 v24, v24
	v_mul_f32_e32 v25, 0x3fb8aa3b, v25
	v_mul_f32_e32 v26, 0x3d800000, v26
	v_sub_f32_e32 v27, v27, v133
	v_mul_f32_e32 v1, 0x3d800000, v1
	v_add_f32_e32 v64, v21, v64
	v_exp_f32_e32 v25, v25
	v_mul_f32_e32 v26, 0x3fb8aa3b, v26
	v_mul_f32_e32 v27, 0x3d800000, v27
	v_sub_f32_e32 v28, v28, v133
	v_mul_f32_e32 v1, 0x3fb8aa3b, v1
	v_add_f32_e32 v64, v22, v64
	v_exp_f32_e32 v26, v26
	v_mul_f32_e32 v27, 0x3fb8aa3b, v27
	v_mul_f32_e32 v28, 0x3d800000, v28
	v_sub_f32_e32 v29, v29, v133
	v_exp_f32_e32 v8, v1
	v_sub_f32_e32 v1, v9, v133
	v_add_f32_e32 v64, v23, v64
	v_exp_f32_e32 v27, v27
	v_mul_f32_e32 v28, 0x3fb8aa3b, v28
	v_mul_f32_e32 v29, 0x3d800000, v29
	v_sub_f32_e32 v30, v30, v133
	v_mul_f32_e32 v0, 0x3d800000, v0
	v_mul_f32_e32 v1, 0x3d800000, v1
	v_add_f32_e32 v64, v24, v64
	v_exp_f32_e32 v28, v28
	v_mul_f32_e32 v29, 0x3fb8aa3b, v29
	v_mul_f32_e32 v30, 0x3d800000, v30
	v_sub_f32_e32 v31, v31, v133
	v_mul_f32_e32 v0, 0x3fb8aa3b, v0
	v_mul_f32_e32 v1, 0x3fb8aa3b, v1
	v_add_f32_e32 v64, v25, v64
	v_exp_f32_e32 v29, v29
	v_mul_f32_e32 v30, 0x3fb8aa3b, v30
	v_mul_f32_e32 v31, 0x3d800000, v31
	v_exp_f32_e32 v180, v0
	v_sub_f32_e32 v0, v2, v133
	v_exp_f32_e32 v9, v1
	v_sub_f32_e32 v1, v10, v133
	v_add_f32_e32 v64, v26, v64
	v_exp_f32_e32 v30, v30
	v_mul_f32_e32 v31, 0x3fb8aa3b, v31
	v_mul_f32_e32 v0, 0x3d800000, v0
	v_mul_f32_e32 v1, 0x3d800000, v1
	v_add_f32_e32 v64, v27, v64
	v_exp_f32_e32 v31, v31
	v_mul_f32_e32 v0, 0x3fb8aa3b, v0
	v_mul_f32_e32 v1, 0x3fb8aa3b, v1
	v_add_f32_e32 v64, v28, v64
	v_exp_f32_e32 v182, v0
	v_sub_f32_e32 v0, v3, v133
	v_exp_f32_e32 v10, v1
	v_sub_f32_e32 v1, v11, v133
	v_add_f32_e32 v64, v29, v64
	v_mul_f32_e32 v0, 0x3d800000, v0
	v_mul_f32_e32 v1, 0x3d800000, v1
	v_add_f32_e32 v64, v30, v64
	v_mul_f32_e32 v0, 0x3fb8aa3b, v0
	v_mul_f32_e32 v1, 0x3fb8aa3b, v1
	v_add_f32_e32 v64, v31, v64
	v_exp_f32_e32 v183, v0
	v_exp_f32_e32 v11, v1
	v_sub_f32_e32 v1, v12, v133
	v_add_f32_e32 v0, v160, v64
	v_mul_f32_e32 v1, 0x3d800000, v1
	v_add_f32_e32 v0, v180, v0
	v_mul_f32_e32 v1, 0x3fb8aa3b, v1
	v_add_f32_e32 v0, v182, v0
	v_exp_f32_e32 v12, v1
	v_sub_f32_e32 v1, v13, v133
	v_add_f32_e32 v0, v183, v0
	v_mul_f32_e32 v1, 0x3d800000, v1
	v_add_f32_e32 v0, v193, v0
	v_mul_f32_e32 v1, 0x3fb8aa3b, v1
	v_add_f32_e32 v0, v195, v0
	v_exp_f32_e32 v13, v1
	v_sub_f32_e32 v1, v14, v133
	v_add_f32_e32 v0, v6, v0
	v_mul_f32_e32 v1, 0x3d800000, v1
	v_add_f32_e32 v0, v7, v0
	v_mul_f32_e32 v1, 0x3fb8aa3b, v1
	v_add_f32_e32 v0, v8, v0
	v_exp_f32_e32 v14, v1
	v_sub_f32_e32 v1, v15, v133
	v_add_f32_e32 v0, v9, v0
	v_mul_f32_e32 v1, 0x3d800000, v1
	v_add_f32_e32 v0, v10, v0
	v_mul_f32_e32 v1, 0x3fb8aa3b, v1
	v_add_f32_e32 v0, v11, v0
	v_exp_f32_e32 v15, v1
	v_add_f32_e32 v0, v12, v0
	v_add_f32_e32 v0, v13, v0
	v_add_f32_e32 v0, v14, v0
	v_add_f32_e32 v0, v15, v0
	ds_bpermute_b32 v1, v132, v0
	v_cvt_pk_bf16_f32 v68, v144, v145
	v_and_b32_e32 v144, 63, v210
	v_cvt_pk_bf16_f32 v76, v134, v135
	v_cvt_pk_bf16_f32 v77, v98, v136
	s_waitcnt lgkmcnt(0)
; #define MFMA32(a, b, c) __builtin_amdgcn_mfma_f32_32x32x16_bf16((a), (b), (c), 0, 0, 0)
; #define LOADV(v_, tid) do { _Pragma("unroll") for (int i = 0; i < 8; ++i) { const int idx = tid + i * 256, f = idx >> 6; \
;     sr[i] = VTg[(((v_) >> 1) * 4 + (f >> 3)) * 1024 + (((v_) & 1) * 8 + (f & 7)) * 64 + (idx & 63)]; } } while (0)
; DI void attn_prompt_block(const Params& p, int l, int b, int hh, int tt4, char* smem, bfr* Obuf) {
;     ...
;   sum += __shfl_xor(sum, 32);
;   const float inv = 1.0f / sum;
;   bf16x8 pb[8][2];
; #pragma unroll
;   for (int m = 0; m < 8; ++m) { pb[m][0] = pack8(st[m], 0); pb[m][1] = pack8(st[m], 1); }
;   int tidv = threadIdx.x;
;   asm volatile("" : "+v"(tidv));
;   const int lanev = tidv & 63, rv = lanev & 31, hlv = lanev >> 5;
;   const int ooff = (b * 2048 + (tt4 * 4 + (tidv >> 6)) * 32 + rv) * 1024 + hh * 256;
;   f32x16 o[4];
; #pragma unroll
;   for (int v = 0; v < 4; ++v) {
;     if (v < 3) LOADV(v + 1, tidv);
;     if ((v & 1) == 0) {
; #pragma unroll
;       for (int d = 0; d < 4; ++d)
; #pragma unroll
;         for (int q = 0; q < 16; ++q) o[d][q] = 0.f;
;     }
; #pragma unroll
;     for (int kk = 0; kk < 8; ++kk)
; #pragma unroll
;       for (int d = 0; d < 4; ++d) {
;         bf16x8 vf = __builtin_bit_cast(bf16x8, vbuf[(d * 8 + kk) * 64 + lanev]);
;         o[d] = MFMA32(vf, pb[((v & 1) * 8 + kk) >> 1][kk & 1], o[d]);
	v_add_f32_e32 v147, v0, v1
	v_lshlrev_b32_e32 v0, 1, v210
	v_and_b32_e32 v211, 0xfffffc00, v0
	v_or_b32_e32 v0, v194, v211
	v_ashrrev_i32_e32 v1, 31, v0
	v_lshl_add_u64 v[2:3], v[0:1], 4, s[20:21]
	v_add_u32_e32 v1, 0x100, v210
	v_lshlrev_b32_e32 v4, 1, v1
	v_and_or_b32 v216, v1, s43, v144
	v_and_b32_e32 v213, 0xfffffc00, v4
	v_or_b32_e32 v201, 0x200, v216
	v_or_b32_e32 v4, v201, v213
	v_ashrrev_i32_e32 v5, 31, v4
	v_lshl_add_u64 v[4:5], v[4:5], 4, s[20:21]
	v_add_u32_e32 v1, 0x300, v210
	global_load_dwordx4 v[128:131], v[2:3], off
	global_load_dwordx4 v[132:135], v[4:5], off
	v_lshlrev_b32_e32 v4, 1, v1
	v_and_or_b32 v218, v1, s43, v144
	v_and_b32_e32 v217, 0xfffffc00, v4
	v_or_b32_e32 v198, 0x200, v218
	v_add_u32_e32 v2, 0x400, v0
	v_or_b32_e32 v4, v198, v217
	v_ashrrev_i32_e32 v3, 31, v2
	v_ashrrev_i32_e32 v5, 31, v4
	v_lshl_add_u64 v[2:3], v[2:3], 4, s[20:21]
	v_lshl_add_u64 v[4:5], v[4:5], 4, s[20:21]
	v_add_u32_e32 v1, 0x500, v210
	v_cvt_pk_bf16_f32 v78, v137, v138
	v_cvt_pk_bf16_f32 v79, v139, v140
	v_cvt_pk_bf16_f32 v72, v141, v142
	v_cvt_pk_bf16_f32 v73, v143, v107
	global_load_dwordx4 v[136:139], v[2:3], off
	global_load_dwordx4 v[140:143], v[4:5], off
	v_lshlrev_b32_e32 v4, 1, v1
	v_and_or_b32 v220, v1, s43, v144
	v_add_u32_e32 v2, 0x800, v0
	v_and_b32_e32 v219, 0xfffffc00, v4
	v_or_b32_e32 v199, 0x200, v220
	v_ashrrev_i32_e32 v3, 31, v2
	v_or_b32_e32 v4, v199, v219
	v_lshl_add_u64 v[2:3], v[2:3], 4, s[20:21]
	v_ashrrev_i32_e32 v5, 31, v4
	v_cvt_pk_bf16_f32 v69, v148, v149
	v_cvt_pk_bf16_f32 v70, v150, v151
	v_cvt_pk_bf16_f32 v71, v152, v153
	v_cvt_pk_bf16_f32 v64, v154, v155
	v_lshl_add_u64 v[4:5], v[4:5], 4, s[20:21]
	global_load_dwordx4 v[148:151], v[2:3], off
	global_load_dwordx4 v[152:155], v[4:5], off
	v_add_u32_e32 v2, 0x700, v210
	v_lshlrev_b32_e32 v3, 1, v2
	v_and_or_b32 v222, v2, s43, v144
	v_add_u32_e32 v0, 0xc00, v0
	v_and_b32_e32 v221, 0xfffffc00, v3
	v_or_b32_e32 v200, 0x200, v222
	v_ashrrev_i32_e32 v1, 31, v0
	v_or_b32_e32 v2, v200, v221
	v_lshl_add_u64 v[0:1], v[0:1], 4, s[20:21]
	v_ashrrev_i32_e32 v3, 31, v2
	v_cvt_pk_bf16_f32 v65, v156, v157
	v_cvt_pk_bf16_f32 v66, v158, v159
	v_lshl_add_u64 v[2:3], v[2:3], 4, s[20:21]
	global_load_dwordx4 v[156:159], v[0:1], off
	global_load_dwordx4 v[202:205], v[2:3], off
	v_cvt_pk_bf16_f32 v83, v126, v127
	v_cvt_pk_bf16_f32 v126, v94, v95
	v_cvt_pk_bf16_f32 v94, v193, v195
	v_lshlrev_b32_e32 v193, 4, v144
	ds_read_b128 v[0:3], v193
	v_cvt_pk_bf16_f32 v67, v88, v89
	v_cvt_pk_bf16_f32 v88, v8, v9
	v_div_scale_f32 v8, s[22:23], v147, v147, 1.0
	v_cvt_pk_bf16_f32 v95, v6, v7
	v_rcp_f32_e32 v9, v8
	ds_read_b128 v[4:7], v193 offset:8192
	v_cvt_pk_bf16_f32 v84, v112, v113
	v_cvt_pk_bf16_f32 v85, v114, v115
	v_cvt_pk_bf16_f32 v86, v116, v117
	v_cvt_pk_bf16_f32 v87, v118, v119
	v_cvt_pk_bf16_f32 v116, v48, v49
	v_cvt_pk_bf16_f32 v117, v50, v51
	v_cvt_pk_bf16_f32 v118, v52, v53
	v_cvt_pk_bf16_f32 v119, v54, v55
	v_cvt_pk_bf16_f32 v112, v56, v57
	v_cvt_pk_bf16_f32 v113, v58, v59
	v_cvt_pk_bf16_f32 v114, v60, v61
	v_cvt_pk_bf16_f32 v115, v62, v63
	s_waitcnt lgkmcnt(1)
	v_mfma_f32_32x32x16_bf16 v[48:63], v[0:3], v[84:87], 0
	v_fma_f32 v0, -v8, v9, 1.0
	v_cvt_pk_bf16_f32 v89, v10, v11
	v_fmac_f32_e32 v9, v0, v9
	v_div_scale_f32 v10, vcc, 1.0, v147, 1.0
	v_mul_f32_e32 v11, v10, v9
	ds_read_b128 v[0:3], v193 offset:16384
	v_cvt_pk_bf16_f32 v82, v124, v125
	v_cvt_pk_bf16_f32 v124, v90, v91
	v_cvt_pk_bf16_f32 v90, v12, v13
	v_fma_f32 v12, -v8, v11, v10
	v_fmac_f32_e32 v11, v12, v9
	v_cvt_pk_bf16_f32 v81, v122, v123
	v_cvt_pk_bf16_f32 v74, v108, v109
	v_cvt_pk_bf16_f32 v75, v110, v111
	v_cvt_pk_bf16_f32 v122, v103, v104
	v_cvt_pk_bf16_f32 v123, v105, v106
	v_cvt_pk_bf16_f32 v108, v32, v33
	v_cvt_pk_bf16_f32 v109, v34, v35
	v_cvt_pk_bf16_f32 v110, v36, v37
	v_cvt_pk_bf16_f32 v111, v38, v39
	v_cvt_pk_bf16_f32 v104, v40, v41
	v_cvt_pk_bf16_f32 v105, v42, v43
	v_cvt_pk_bf16_f32 v106, v44, v45
	v_cvt_pk_bf16_f32 v107, v46, v47
	s_waitcnt lgkmcnt(1)
	v_mfma_f32_32x32x16_bf16 v[32:47], v[4:7], v[84:87], 0
	v_fma_f32 v4, -v8, v11, v10
	v_div_fmas_f32 v4, v4, v9, v11
	v_cvt_pk_bf16_f32 v125, v92, v93
	v_cvt_pk_bf16_f32 v92, v160, v180
	v_div_fixup_f32 v180, v4, v147, 1.0
	ds_read_b128 v[4:7], v193 offset:24576
	v_lshrrev_b32_e32 v8, 6, v210
	v_cvt_pk_bf16_f32 v80, v120, v121
	v_cvt_pk_bf16_f32 v127, v96, v97
	v_cvt_pk_bf16_f32 v120, v99, v100
	v_cvt_pk_bf16_f32 v121, v101, v102
	v_cvt_pk_bf16_f32 v100, v16, v17
	v_cvt_pk_bf16_f32 v101, v18, v19
	v_cvt_pk_bf16_f32 v102, v20, v21
	v_cvt_pk_bf16_f32 v103, v22, v23
	v_cvt_pk_bf16_f32 v96, v24, v25
	v_cvt_pk_bf16_f32 v97, v26, v27
	v_cvt_pk_bf16_f32 v98, v28, v29
	v_cvt_pk_bf16_f32 v99, v30, v31
	s_waitcnt lgkmcnt(1)
	v_mfma_f32_32x32x16_bf16 v[16:31], v[0:3], v[84:87], 0
	v_add_u32_e32 v0, v8, v146
	v_lshl_add_u32 v0, v0, 5, s52
	v_and_or_b32 v0, v210, 31, v0
	v_lshl_or_b32 v0, v0, 10, s53
	v_ashrrev_i32_e32 v1, 31, v0
	v_cvt_pk_bf16_f32 v93, v182, v183
	v_cvt_pk_bf16_f32 v91, v14, v15
	v_lshl_add_u64 v[182:183], v[0:1], 1, s[14:15]
	v_lshlrev_b32_e32 v195, 4, v210
	s_waitcnt lgkmcnt(0)
	v_mfma_f32_32x32x16_bf16 v[0:15], v[4:7], v[84:87], 0
	ds_read_b128 v[144:147], v193 offset:1024
	ds_read_b128 v[206:209], v193 offset:9216
	s_waitcnt lgkmcnt(1)
	v_mfma_f32_32x32x16_bf16 v[48:63], v[144:147], v[80:83], v[48:63]
	s_waitcnt lgkmcnt(0)
	v_mfma_f32_32x32x16_bf16 v[32:47], v[206:209], v[80:83], v[32:47]
	ds_read_b128 v[144:147], v193 offset:17408
	ds_read_b128 v[206:209], v193 offset:25600
	s_waitcnt lgkmcnt(1)
	v_mfma_f32_32x32x16_bf16 v[16:31], v[144:147], v[80:83], v[16:31]
	s_waitcnt lgkmcnt(0)
; #define MFMA32(a, b, c) __builtin_amdgcn_mfma_f32_32x32x16_bf16((a), (b), (c), 0, 0, 0)
; #define LOADV(v_, tid) do { _Pragma("unroll") for (int i = 0; i < 8; ++i) { const int idx = tid + i * 256, f = idx >> 6; \
;     sr[i] = VTg[(((v_) >> 1) * 4 + (f >> 3)) * 1024 + (((v_) & 1) * 8 + (f & 7)) * 64 + (idx & 63)]; } } while (0)
; #define STOREV(tid) do { _Pragma("unroll") for (int i = 0; i < 8; ++i) vbuf[tid + i * 256] = sr[i]; } while (0)
; DI void attn_prompt_block(const Params& p, int l, int b, int hh, int tt4, char* smem, bfr* Obuf) {
;     ...
;   f32x16 o[4];
; #pragma unroll
;   for (int v = 0; v < 4; ++v) {
;     if (v < 3) LOADV(v + 1, tidv);
;     if ((v & 1) == 0) {
; #pragma unroll
;       for (int d = 0; d < 4; ++d)
; #pragma unroll
;         for (int q = 0; q < 16; ++q) o[d][q] = 0.f;
;     }
; #pragma unroll
;     for (int kk = 0; kk < 8; ++kk)
; #pragma unroll
;       for (int d = 0; d < 4; ++d) {
;         bf16x8 vf = __builtin_bit_cast(bf16x8, vbuf[(d * 8 + kk) * 64 + lanev]);
;         o[d] = MFMA32(vf, pb[((v & 1) * 8 + kk) >> 1][kk & 1], o[d]);
;         if (d == 3) __builtin_amdgcn_sched_barrier(0);
;       }
;     if (v & 1) {
; #pragma unroll
;       for (int d = 0; d < 4; ++d)
; #pragma unroll
;         for (int g4 = 0; g4 < 4; ++g4) {
;           int dim = ((v >> 1) * 4 + d) * 32 + 8 * g4 + 4 * hlv;
;           uint2 ov;
;           ov.x = pack2(o[d][g4 * 4 + 0] * inv, o[d][g4 * 4 + 1] * inv);
;           ov.y = pack2(o[d][g4 * 4 + 2] * inv, o[d][g4 * 4 + 3] * inv);
;           *(uint2*)(Obuf + ooff + dim) = ov;
;         }
;     }
;     __syncthreads();
;     if (v < 3) { STOREV(tidv); __syncthreads(); }
	v_mfma_f32_32x32x16_bf16 v[0:15], v[206:209], v[80:83], v[0:15]
	ds_read_b128 v[144:147], v193 offset:2048
	ds_read_b128 v[206:209], v193 offset:10240
	s_waitcnt lgkmcnt(1)
	v_mfma_f32_32x32x16_bf16 v[48:63], v[144:147], v[76:79], v[48:63]
	s_waitcnt lgkmcnt(0)
	v_mfma_f32_32x32x16_bf16 v[32:47], v[206:209], v[76:79], v[32:47]
	ds_read_b128 v[144:147], v193 offset:18432
	ds_read_b128 v[206:209], v193 offset:26624
	s_waitcnt lgkmcnt(1)
	v_mfma_f32_32x32x16_bf16 v[16:31], v[144:147], v[76:79], v[16:31]
	s_waitcnt lgkmcnt(0)
	v_mfma_f32_32x32x16_bf16 v[0:15], v[206:209], v[76:79], v[0:15]
	ds_read_b128 v[144:147], v193 offset:3072
	ds_read_b128 v[206:209], v193 offset:11264
	s_waitcnt lgkmcnt(1)
	v_mfma_f32_32x32x16_bf16 v[48:63], v[144:147], v[72:75], v[48:63]
	s_waitcnt lgkmcnt(0)
	v_mfma_f32_32x32x16_bf16 v[32:47], v[206:209], v[72:75], v[32:47]
	ds_read_b128 v[144:147], v193 offset:19456
	ds_read_b128 v[206:209], v193 offset:27648
	s_waitcnt lgkmcnt(1)
	v_mfma_f32_32x32x16_bf16 v[16:31], v[144:147], v[72:75], v[16:31]
	s_waitcnt lgkmcnt(0)
	v_mfma_f32_32x32x16_bf16 v[0:15], v[206:209], v[72:75], v[0:15]
	ds_read_b128 v[144:147], v193 offset:4096
	ds_read_b128 v[206:209], v193 offset:12288
	s_waitcnt lgkmcnt(1)
	v_mfma_f32_32x32x16_bf16 v[48:63], v[144:147], v[68:71], v[48:63]
	s_waitcnt lgkmcnt(0)
	v_mfma_f32_32x32x16_bf16 v[32:47], v[206:209], v[68:71], v[32:47]
	ds_read_b128 v[144:147], v193 offset:20480
	ds_read_b128 v[206:209], v193 offset:28672
	s_waitcnt lgkmcnt(1)
	v_mfma_f32_32x32x16_bf16 v[16:31], v[144:147], v[68:71], v[16:31]
	s_waitcnt lgkmcnt(0)
	v_mfma_f32_32x32x16_bf16 v[0:15], v[206:209], v[68:71], v[0:15]
	ds_read_b128 v[144:147], v193 offset:5120
	ds_read_b128 v[206:209], v193 offset:13312
	s_waitcnt lgkmcnt(1)
	v_mfma_f32_32x32x16_bf16 v[48:63], v[144:147], v[64:67], v[48:63]
	s_waitcnt lgkmcnt(0)
	v_mfma_f32_32x32x16_bf16 v[32:47], v[206:209], v[64:67], v[32:47]
	ds_read_b128 v[144:147], v193 offset:21504
	ds_read_b128 v[206:209], v193 offset:29696
	s_waitcnt lgkmcnt(1)
	v_mfma_f32_32x32x16_bf16 v[16:31], v[144:147], v[64:67], v[16:31]
	s_waitcnt lgkmcnt(0)
	v_mfma_f32_32x32x16_bf16 v[0:15], v[206:209], v[64:67], v[0:15]
	ds_read_b128 v[144:147], v193 offset:6144
	ds_read_b128 v[206:209], v193 offset:14336
	s_waitcnt lgkmcnt(1)
	v_mfma_f32_32x32x16_bf16 v[48:63], v[144:147], v[124:127], v[48:63]
	s_waitcnt lgkmcnt(0)
	v_mfma_f32_32x32x16_bf16 v[32:47], v[206:209], v[124:127], v[32:47]
	ds_read_b128 v[144:147], v193 offset:22528
	ds_read_b128 v[206:209], v193 offset:30720
	s_waitcnt lgkmcnt(1)
	v_mfma_f32_32x32x16_bf16 v[16:31], v[144:147], v[124:127], v[16:31]
	s_waitcnt lgkmcnt(0)
	v_mfma_f32_32x32x16_bf16 v[0:15], v[206:209], v[124:127], v[0:15]
	ds_read_b128 v[144:147], v193 offset:7168
	ds_read_b128 v[206:209], v193 offset:15360
	s_waitcnt lgkmcnt(1)
	v_mfma_f32_32x32x16_bf16 v[48:63], v[144:147], v[120:123], v[48:63]
	s_waitcnt lgkmcnt(0)
	v_mfma_f32_32x32x16_bf16 v[32:47], v[206:209], v[120:123], v[32:47]
	ds_read_b128 v[144:147], v193 offset:23552
	ds_read_b128 v[206:209], v193 offset:31744
	s_waitcnt lgkmcnt(1)
	v_mfma_f32_32x32x16_bf16 v[16:31], v[144:147], v[120:123], v[16:31]
	s_waitcnt lgkmcnt(0)
	v_mfma_f32_32x32x16_bf16 v[0:15], v[206:209], v[120:123], v[0:15]
	v_add_u32_e32 v223, 0x1000, v211
	v_add_u32_e32 v213, 0x1000, v213
	s_barrier
	s_waitcnt vmcnt(7)
	ds_write_b128 v195, v[128:131]
	s_waitcnt vmcnt(6)
	ds_write_b128 v195, v[132:135] offset:4096
	s_waitcnt vmcnt(5)
	ds_write_b128 v195, v[136:139] offset:8192
	s_waitcnt vmcnt(4)
	ds_write_b128 v195, v[140:143] offset:12288
	s_waitcnt vmcnt(3)
	ds_write_b128 v195, v[148:151] offset:16384
	s_waitcnt vmcnt(2)
	ds_write_b128 v195, v[152:155] offset:20480
	s_waitcnt vmcnt(1)
	ds_write_b128 v195, v[156:159] offset:24576
	s_waitcnt vmcnt(0)
	ds_write_b128 v195, v[202:205] offset:28672
	v_or_b32_e32 v128, v223, v212
	v_or_b32_e32 v130, v216, v213
	v_ashrrev_i32_e32 v129, 31, v128
	v_ashrrev_i32_e32 v131, 31, v130
	v_lshl_add_u64 v[128:129], v[128:129], 4, s[20:21]
	v_lshl_add_u64 v[132:133], v[130:131], 4, s[20:21]
	s_waitcnt lgkmcnt(0)
	s_barrier
	global_load_dwordx4 v[128:131], v[128:129], off
	s_nop 0
	global_load_dwordx4 v[132:135], v[132:133], off
	ds_read_b128 v[144:147], v193
	v_add_u32_e32 v216, 0x1400, v211
	v_add_u32_e32 v217, 0x1000, v217
	v_or_b32_e32 v136, v216, v212
	v_or_b32_e32 v138, v218, v217
	v_ashrrev_i32_e32 v137, 31, v136
	v_ashrrev_i32_e32 v139, 31, v138
	v_add_u32_e32 v218, 0x1800, v211
	v_add_u32_e32 v219, 0x1000, v219
	v_lshl_add_u64 v[136:137], v[136:137], 4, s[20:21]
	v_lshl_add_u64 v[140:141], v[138:139], 4, s[20:21]
	v_or_b32_e32 v148, v218, v212
	v_or_b32_e32 v150, v220, v219
	global_load_dwordx4 v[136:139], v[136:137], off
	s_nop 0
	global_load_dwordx4 v[140:143], v[140:141], off
	v_ashrrev_i32_e32 v149, 31, v148
	ds_read_b128 v[152:155], v193 offset:8192
	v_ashrrev_i32_e32 v151, 31, v150
	v_lshl_add_u64 v[148:149], v[148:149], 4, s[20:21]
	v_lshl_add_u64 v[150:151], v[150:151], 4, s[20:21]
	s_waitcnt lgkmcnt(1)
	v_mfma_f32_32x32x16_bf16 v[48:63], v[144:147], v[116:119], v[48:63]
	global_load_dwordx4 v[144:147], v[148:149], off
	s_nop 0
	global_load_dwordx4 v[148:151], v[150:151], off
	ds_read_b128 v[156:159], v193 offset:16384
	v_add_u32_e32 v211, 0x1c00, v211
	v_or_b32_e32 v202, v211, v212
	v_add_u32_e32 v212, 0x1000, v221
	v_ashrrev_i32_e32 v203, 31, v202
	s_waitcnt lgkmcnt(1)
	v_mfma_f32_32x32x16_bf16 v[32:47], v[152:155], v[116:119], v[32:47]
	v_or_b32_e32 v154, v222, v212
	v_lshl_add_u64 v[152:153], v[202:203], 4, s[20:21]
	v_ashrrev_i32_e32 v155, 31, v154
	v_lshl_add_u64 v[206:207], v[154:155], 4, s[20:21]
	ds_read_b128 v[202:205], v193 offset:24576
	s_waitcnt lgkmcnt(1)
; #define MFMA32(a, b, c) __builtin_amdgcn_mfma_f32_32x32x16_bf16((a), (b), (c), 0, 0, 0)
; DI void attn_prompt_block(const Params& p, int l, int b, int hh, int tt4, char* smem, bfr* Obuf) {
;     ...
; #pragma unroll
;     for (int kk = 0; kk < 8; ++kk)
; #pragma unroll
;       for (int d = 0; d < 4; ++d) {
;         bf16x8 vf = __builtin_bit_cast(bf16x8, vbuf[(d * 8 + kk) * 64 + lanev]);
;         o[d] = MFMA32(vf, pb[((v & 1) * 8 + kk) >> 1][kk & 1], o[d]);
;         if (d == 3) __builtin_amdgcn_sched_barrier(0);
;       }
;     if (v & 1) {
; #pragma unroll
;       for (int d = 0; d < 4; ++d)
; #pragma unroll
;         for (int g4 = 0; g4 < 4; ++g4) {
;           int dim = ((v >> 1) * 4 + d) * 32 + 8 * g4 + 4 * hlv;
;           uint2 ov;
;           ov.x = pack2(o[d][g4 * 4 + 0] * inv, o[d][g4 * 4 + 1] * inv);
;           ov.y = pack2(o[d][g4 * 4 + 2] * inv, o[d][g4 * 4 + 3] * inv);
;           *(uint2*)(Obuf + ooff + dim) = ov;
;         }
;     }
	v_mfma_f32_32x32x16_bf16 v[16:31], v[156:159], v[116:119], v[16:31]
	global_load_dwordx4 v[152:155], v[152:153], off
	s_nop 0
	global_load_dwordx4 v[156:159], v[206:207], off
	s_waitcnt lgkmcnt(0)
	v_mfma_f32_32x32x16_bf16 v[0:15], v[202:205], v[116:119], v[0:15]
	ds_read_b128 v[202:205], v193 offset:1024
	ds_read_b128 v[206:209], v193 offset:9216
	s_waitcnt lgkmcnt(1)
	v_mfma_f32_32x32x16_bf16 v[48:63], v[202:205], v[112:115], v[48:63]
	s_waitcnt lgkmcnt(0)
	v_mfma_f32_32x32x16_bf16 v[32:47], v[206:209], v[112:115], v[32:47]
	ds_read_b128 v[202:205], v193 offset:17408
	ds_read_b128 v[206:209], v193 offset:25600
	s_waitcnt lgkmcnt(1)
	v_mfma_f32_32x32x16_bf16 v[16:31], v[202:205], v[112:115], v[16:31]
	s_waitcnt lgkmcnt(0)
	v_mfma_f32_32x32x16_bf16 v[0:15], v[206:209], v[112:115], v[0:15]
	ds_read_b128 v[202:205], v193 offset:2048
	ds_read_b128 v[206:209], v193 offset:10240
	s_waitcnt lgkmcnt(1)
	v_mfma_f32_32x32x16_bf16 v[48:63], v[202:205], v[108:111], v[48:63]
	s_waitcnt lgkmcnt(0)
	v_mfma_f32_32x32x16_bf16 v[32:47], v[206:209], v[108:111], v[32:47]
	ds_read_b128 v[202:205], v193 offset:18432
	ds_read_b128 v[206:209], v193 offset:26624
	s_waitcnt lgkmcnt(1)
	v_mfma_f32_32x32x16_bf16 v[16:31], v[202:205], v[108:111], v[16:31]
	s_waitcnt lgkmcnt(0)
	v_mfma_f32_32x32x16_bf16 v[0:15], v[206:209], v[108:111], v[0:15]
	ds_read_b128 v[202:205], v193 offset:3072
	ds_read_b128 v[206:209], v193 offset:11264
	s_waitcnt lgkmcnt(1)
	v_mfma_f32_32x32x16_bf16 v[48:63], v[202:205], v[104:107], v[48:63]
	s_waitcnt lgkmcnt(0)
	v_mfma_f32_32x32x16_bf16 v[32:47], v[206:209], v[104:107], v[32:47]
	ds_read_b128 v[202:205], v193 offset:19456
	ds_read_b128 v[206:209], v193 offset:27648
	s_waitcnt lgkmcnt(1)
	v_mfma_f32_32x32x16_bf16 v[16:31], v[202:205], v[104:107], v[16:31]
	s_waitcnt lgkmcnt(0)
	v_mfma_f32_32x32x16_bf16 v[0:15], v[206:209], v[104:107], v[0:15]
	ds_read_b128 v[202:205], v193 offset:4096
	ds_read_b128 v[206:209], v193 offset:12288
	s_waitcnt lgkmcnt(1)
	v_mfma_f32_32x32x16_bf16 v[48:63], v[202:205], v[100:103], v[48:63]
	s_waitcnt lgkmcnt(0)
	v_mfma_f32_32x32x16_bf16 v[32:47], v[206:209], v[100:103], v[32:47]
	ds_read_b128 v[202:205], v193 offset:20480
	ds_read_b128 v[206:209], v193 offset:28672
	s_waitcnt lgkmcnt(1)
	v_mfma_f32_32x32x16_bf16 v[16:31], v[202:205], v[100:103], v[16:31]
	s_waitcnt lgkmcnt(0)
	v_mfma_f32_32x32x16_bf16 v[0:15], v[206:209], v[100:103], v[0:15]
	ds_read_b128 v[202:205], v193 offset:5120
	ds_read_b128 v[206:209], v193 offset:13312
	s_waitcnt lgkmcnt(1)
	v_mfma_f32_32x32x16_bf16 v[48:63], v[202:205], v[96:99], v[48:63]
	s_waitcnt lgkmcnt(0)
	v_mfma_f32_32x32x16_bf16 v[32:47], v[206:209], v[96:99], v[32:47]
	ds_read_b128 v[202:205], v193 offset:21504
	ds_read_b128 v[206:209], v193 offset:29696
	s_waitcnt lgkmcnt(1)
	v_mfma_f32_32x32x16_bf16 v[16:31], v[202:205], v[96:99], v[16:31]
	s_waitcnt lgkmcnt(0)
	v_mfma_f32_32x32x16_bf16 v[0:15], v[206:209], v[96:99], v[0:15]
	ds_read_b128 v[202:205], v193 offset:6144
	ds_read_b128 v[206:209], v193 offset:14336
	s_waitcnt lgkmcnt(1)
	v_mfma_f32_32x32x16_bf16 v[48:63], v[202:205], v[92:95], v[48:63]
	s_waitcnt lgkmcnt(0)
	v_mfma_f32_32x32x16_bf16 v[32:47], v[206:209], v[92:95], v[32:47]
	ds_read_b128 v[202:205], v193 offset:22528
	ds_read_b128 v[206:209], v193 offset:30720
	s_waitcnt lgkmcnt(1)
	v_mfma_f32_32x32x16_bf16 v[16:31], v[202:205], v[92:95], v[16:31]
	s_waitcnt lgkmcnt(0)
	v_mfma_f32_32x32x16_bf16 v[0:15], v[206:209], v[92:95], v[0:15]
	ds_read_b128 v[202:205], v193 offset:7168
	ds_read_b128 v[206:209], v193 offset:15360
	s_waitcnt lgkmcnt(1)
	v_mfma_f32_32x32x16_bf16 v[48:63], v[202:205], v[88:91], v[48:63]
	s_waitcnt lgkmcnt(0)
	v_mfma_f32_32x32x16_bf16 v[32:47], v[206:209], v[88:91], v[32:47]
	ds_read_b128 v[202:205], v193 offset:23552
	ds_read_b128 v[206:209], v193 offset:31744
	s_waitcnt lgkmcnt(1)
	v_mfma_f32_32x32x16_bf16 v[16:31], v[202:205], v[88:91], v[16:31]
	s_waitcnt lgkmcnt(0)
	v_mfma_f32_32x32x16_bf16 v[0:15], v[206:209], v[88:91], v[0:15]
	s_nop 3
	v_mul_f32_e64 v48, v48, v180
	v_mul_f32_e64 v49, v49, v180
	v_mul_f32_e64 v50, v50, v180
	v_mul_f32_e64 v51, v51, v180
	v_cvt_pk_bf16_f32 v48, v48, v49
	v_cvt_pk_bf16_f32 v49, v50, v51
	v_lshrrev_b32_e32 v50, 2, v210
	v_and_b32_e32 v160, 8, v50
	v_pk_mul_f32 v[0:1], v[0:1], v[180:181] op_sel_hi:[1,0]
	v_pk_mul_f32 v[2:3], v[2:3], v[180:181] op_sel_hi:[1,0]
	v_lshl_add_u64 v[182:183], v[182:183], 0, v[160:161]
	v_cvt_pk_bf16_f32 v0, v0, v1
	v_cvt_pk_bf16_f32 v1, v2, v3
	global_store_dwordx2 v[182:183], v[0:1], off offset:192 sc1
	v_pk_mul_f32 v[0:1], v[4:5], v[180:181] op_sel_hi:[1,0]
	v_pk_mul_f32 v[2:3], v[6:7], v[180:181] op_sel_hi:[1,0]
	v_pk_mul_f32 v[32:33], v[32:33], v[180:181] op_sel_hi:[1,0]
	v_pk_mul_f32 v[34:35], v[34:35], v[180:181] op_sel_hi:[1,0]
	v_pk_mul_f32 v[16:17], v[16:17], v[180:181] op_sel_hi:[1,0]
	v_pk_mul_f32 v[18:19], v[18:19], v[180:181] op_sel_hi:[1,0]
	v_cvt_pk_bf16_f32 v0, v0, v1
	v_cvt_pk_bf16_f32 v1, v2, v3
	v_cvt_pk_bf16_f32 v32, v32, v33
	v_cvt_pk_bf16_f32 v33, v34, v35
	v_cvt_pk_bf16_f32 v16, v16, v17
	v_cvt_pk_bf16_f32 v17, v18, v19
	global_store_dwordx2 v[182:183], v[0:1], off offset:208 sc1
	v_pk_mul_f32 v[0:1], v[8:9], v[180:181] op_sel_hi:[1,0]
	v_pk_mul_f32 v[2:3], v[10:11], v[180:181] op_sel_hi:[1,0]
	global_store_dwordx2 v[182:183], v[48:49], off sc1
	v_pk_mul_f32 v[48:49], v[52:53], v[180:181] op_sel_hi:[1,0]
	v_pk_mul_f32 v[50:51], v[54:55], v[180:181] op_sel_hi:[1,0]
	global_store_dwordx2 v[182:183], v[32:33], off offset:64 sc1
	v_pk_mul_f32 v[32:33], v[36:37], v[180:181] op_sel_hi:[1,0]
	v_pk_mul_f32 v[34:35], v[38:39], v[180:181] op_sel_hi:[1,0]
; #define MFMA32(a, b, c) __builtin_amdgcn_mfma_f32_32x32x16_bf16((a), (b), (c), 0, 0, 0)
; #define LOADV(v_, tid) do { _Pragma("unroll") for (int i = 0; i < 8; ++i) { const int idx = tid + i * 256, f = idx >> 6; \
;     sr[i] = VTg[(((v_) >> 1) * 4 + (f >> 3)) * 1024 + (((v_) & 1) * 8 + (f & 7)) * 64 + (idx & 63)]; } } while (0)
; #define STOREV(tid) do { _Pragma("unroll") for (int i = 0; i < 8; ++i) vbuf[tid + i * 256] = sr[i]; } while (0)
; DI void attn_prompt_block(const Params& p, int l, int b, int hh, int tt4, char* smem, bfr* Obuf) {
;     ...
;   for (int v = 0; v < 4; ++v) {
;     if (v < 3) LOADV(v + 1, tidv);
;     if ((v & 1) == 0) {
; #pragma unroll
;       for (int d = 0; d < 4; ++d)
; #pragma unroll
;         for (int q = 0; q < 16; ++q) o[d][q] = 0.f;
;     }
; #pragma unroll
;     for (int kk = 0; kk < 8; ++kk)
; #pragma unroll
;       for (int d = 0; d < 4; ++d) {
;         bf16x8 vf = __builtin_bit_cast(bf16x8, vbuf[(d * 8 + kk) * 64 + lanev]);
;         o[d] = MFMA32(vf, pb[((v & 1) * 8 + kk) >> 1][kk & 1], o[d]);
;         if (d == 3) __builtin_amdgcn_sched_barrier(0);
;       }
;     if (v & 1) {
; #pragma unroll
;       for (int d = 0; d < 4; ++d)
; #pragma unroll
;         for (int g4 = 0; g4 < 4; ++g4) {
;           int dim = ((v >> 1) * 4 + d) * 32 + 8 * g4 + 4 * hlv;
;           uint2 ov;
;           ov.x = pack2(o[d][g4 * 4 + 0] * inv, o[d][g4 * 4 + 1] * inv);
;           ov.y = pack2(o[d][g4 * 4 + 2] * inv, o[d][g4 * 4 + 3] * inv);
;           *(uint2*)(Obuf + ooff + dim) = ov;
;         }
;     }
;     __syncthreads();
;     if (v < 3) { STOREV(tidv); __syncthreads(); }
	global_store_dwordx2 v[182:183], v[16:17], off offset:128 sc1
	v_pk_mul_f32 v[16:17], v[20:21], v[180:181] op_sel_hi:[1,0]
	v_pk_mul_f32 v[18:19], v[22:23], v[180:181] op_sel_hi:[1,0]
	v_cvt_pk_bf16_f32 v0, v0, v1
	v_cvt_pk_bf16_f32 v1, v2, v3
	v_cvt_pk_bf16_f32 v48, v48, v49
	v_cvt_pk_bf16_f32 v49, v50, v51
	v_cvt_pk_bf16_f32 v32, v32, v33
	v_cvt_pk_bf16_f32 v33, v34, v35
	v_cvt_pk_bf16_f32 v16, v16, v17
	v_cvt_pk_bf16_f32 v17, v18, v19
	global_store_dwordx2 v[182:183], v[0:1], off offset:224 sc1
	v_pk_mul_f32 v[0:1], v[12:13], v[180:181] op_sel_hi:[1,0]
	v_pk_mul_f32 v[2:3], v[14:15], v[180:181] op_sel_hi:[1,0]
	global_store_dwordx2 v[182:183], v[48:49], off offset:16 sc1
	v_pk_mul_f32 v[48:49], v[56:57], v[180:181] op_sel_hi:[1,0]
	v_pk_mul_f32 v[50:51], v[58:59], v[180:181] op_sel_hi:[1,0]
	global_store_dwordx2 v[182:183], v[32:33], off offset:80 sc1
	v_pk_mul_f32 v[32:33], v[40:41], v[180:181] op_sel_hi:[1,0]
	v_pk_mul_f32 v[34:35], v[42:43], v[180:181] op_sel_hi:[1,0]
	global_store_dwordx2 v[182:183], v[16:17], off offset:144 sc1
	v_pk_mul_f32 v[16:17], v[24:25], v[180:181] op_sel_hi:[1,0]
	v_pk_mul_f32 v[18:19], v[26:27], v[180:181] op_sel_hi:[1,0]
	v_cvt_pk_bf16_f32 v0, v0, v1
	v_cvt_pk_bf16_f32 v1, v2, v3
	v_cvt_pk_bf16_f32 v48, v48, v49
	v_cvt_pk_bf16_f32 v49, v50, v51
	v_cvt_pk_bf16_f32 v32, v32, v33
	v_cvt_pk_bf16_f32 v33, v34, v35
	v_cvt_pk_bf16_f32 v16, v16, v17
	v_cvt_pk_bf16_f32 v17, v18, v19
	global_store_dwordx2 v[182:183], v[0:1], off offset:240 sc1
	v_or_b32_e32 v0, v194, v223
	global_store_dwordx2 v[182:183], v[48:49], off offset:32 sc1
	v_pk_mul_f32 v[48:49], v[60:61], v[180:181] op_sel_hi:[1,0]
	v_pk_mul_f32 v[50:51], v[62:63], v[180:181] op_sel_hi:[1,0]
	global_store_dwordx2 v[182:183], v[32:33], off offset:96 sc1
	v_pk_mul_f32 v[32:33], v[44:45], v[180:181] op_sel_hi:[1,0]
	v_pk_mul_f32 v[34:35], v[46:47], v[180:181] op_sel_hi:[1,0]
	global_store_dwordx2 v[182:183], v[16:17], off offset:160 sc1
	v_pk_mul_f32 v[16:17], v[28:29], v[180:181] op_sel_hi:[1,0]
	v_pk_mul_f32 v[18:19], v[30:31], v[180:181] op_sel_hi:[1,0]
	v_ashrrev_i32_e32 v1, 31, v0
	v_or_b32_e32 v2, v213, v201
	v_cvt_pk_bf16_f32 v48, v48, v49
	v_cvt_pk_bf16_f32 v49, v50, v51
	v_cvt_pk_bf16_f32 v32, v32, v33
	v_cvt_pk_bf16_f32 v33, v34, v35
	v_cvt_pk_bf16_f32 v16, v16, v17
	v_cvt_pk_bf16_f32 v17, v18, v19
	v_lshl_add_u64 v[0:1], v[0:1], 4, s[20:21]
	v_ashrrev_i32_e32 v3, 31, v2
	global_store_dwordx2 v[182:183], v[48:49], off offset:48 sc1
	global_store_dwordx2 v[182:183], v[32:33], off offset:112 sc1
	global_store_dwordx2 v[182:183], v[16:17], off offset:176 sc1
	s_barrier
	s_waitcnt vmcnt(23)
	ds_write_b128 v195, v[128:131]
	s_waitcnt vmcnt(22)
	ds_write_b128 v195, v[132:135] offset:4096
	s_waitcnt vmcnt(21)
	ds_write_b128 v195, v[136:139] offset:8192
	s_waitcnt vmcnt(20)
	ds_write_b128 v195, v[140:143] offset:12288
	s_waitcnt vmcnt(19)
	ds_write_b128 v195, v[144:147] offset:16384
	s_waitcnt vmcnt(18)
	ds_write_b128 v195, v[148:151] offset:20480
	s_waitcnt vmcnt(17)
	ds_write_b128 v195, v[152:155] offset:24576
	s_waitcnt vmcnt(16)
	ds_write_b128 v195, v[156:159] offset:28672
	s_waitcnt lgkmcnt(0)
	s_barrier
	v_lshl_add_u64 v[2:3], v[2:3], 4, s[20:21]
	global_load_dwordx4 v[128:131], v[0:1], off
	global_load_dwordx4 v[132:135], v[2:3], off
	v_or_b32_e32 v0, v194, v216
	v_or_b32_e32 v6, v217, v198
	v_ashrrev_i32_e32 v1, 31, v0
	v_ashrrev_i32_e32 v7, 31, v6
	v_lshl_add_u64 v[4:5], v[0:1], 4, s[20:21]
	v_lshl_add_u64 v[6:7], v[6:7], 4, s[20:21]
	ds_read_b128 v[0:3], v193
	global_load_dwordx4 v[136:139], v[4:5], off
	global_load_dwordx4 v[140:143], v[6:7], off
	ds_read_b128 v[4:7], v193 offset:8192
	v_or_b32_e32 v8, v194, v218
	s_waitcnt lgkmcnt(0)
	v_mfma_f32_32x32x16_bf16 v[32:47], v[4:7], v[84:87], 0
	v_or_b32_e32 v4, v194, v211
	v_ashrrev_i32_e32 v9, 31, v8
	v_ashrrev_i32_e32 v5, 31, v4
	v_mfma_f32_32x32x16_bf16 v[48:63], v[0:3], v[84:87], 0
	v_or_b32_e32 v2, v219, v199
	v_lshl_add_u64 v[0:1], v[8:9], 4, s[20:21]
	v_ashrrev_i32_e32 v3, 31, v2
	v_lshl_add_u64 v[8:9], v[4:5], 4, s[20:21]
	v_or_b32_e32 v4, v212, v200
	v_lshl_add_u64 v[2:3], v[2:3], 4, s[20:21]
	v_ashrrev_i32_e32 v5, 31, v4
	global_load_dwordx4 v[144:147], v[0:1], off
	global_load_dwordx4 v[148:151], v[2:3], off
	ds_read_b128 v[0:3], v193 offset:16384
	v_lshl_add_u64 v[10:11], v[4:5], 4, s[20:21]
	ds_read_b128 v[4:7], v193 offset:24576
	global_load_dwordx4 v[152:155], v[8:9], off
	global_load_dwordx4 v[156:159], v[10:11], off
	s_waitcnt lgkmcnt(1)
	v_mfma_f32_32x32x16_bf16 v[16:31], v[0:3], v[84:87], 0
	s_waitcnt lgkmcnt(0)
	v_mfma_f32_32x32x16_bf16 v[0:15], v[4:7], v[84:87], 0
	ds_read_b128 v[84:87], v193 offset:1024
	ds_read_b128 v[198:201], v193 offset:9216
	s_waitcnt lgkmcnt(1)
	v_mfma_f32_32x32x16_bf16 v[48:63], v[84:87], v[80:83], v[48:63]
	s_waitcnt lgkmcnt(0)
	v_mfma_f32_32x32x16_bf16 v[32:47], v[198:201], v[80:83], v[32:47]
	ds_read_b128 v[84:87], v193 offset:17408
	ds_read_b128 v[198:201], v193 offset:25600
	s_waitcnt lgkmcnt(1)
	v_mfma_f32_32x32x16_bf16 v[16:31], v[84:87], v[80:83], v[16:31]
	s_waitcnt lgkmcnt(0)
	v_mfma_f32_32x32x16_bf16 v[0:15], v[198:201], v[80:83], v[0:15]
	ds_read_b128 v[80:83], v193 offset:2048
	ds_read_b128 v[84:87], v193 offset:10240
	s_waitcnt lgkmcnt(1)
	v_mfma_f32_32x32x16_bf16 v[48:63], v[80:83], v[76:79], v[48:63]
	s_waitcnt lgkmcnt(0)
	v_mfma_f32_32x32x16_bf16 v[32:47], v[84:87], v[76:79], v[32:47]
	ds_read_b128 v[80:83], v193 offset:18432
	ds_read_b128 v[84:87], v193 offset:26624
	s_waitcnt lgkmcnt(1)
	v_mfma_f32_32x32x16_bf16 v[16:31], v[80:83], v[76:79], v[16:31]
	s_waitcnt lgkmcnt(0)
; #define MFMA32(a, b, c) __builtin_amdgcn_mfma_f32_32x32x16_bf16((a), (b), (c), 0, 0, 0)
; #define STOREV(tid) do { _Pragma("unroll") for (int i = 0; i < 8; ++i) vbuf[tid + i * 256] = sr[i]; } while (0)
; DI void attn_prompt_block(const Params& p, int l, int b, int hh, int tt4, char* smem, bfr* Obuf) {
;     ...
; #pragma unroll
;     for (int kk = 0; kk < 8; ++kk)
; #pragma unroll
;       for (int d = 0; d < 4; ++d) {
;         bf16x8 vf = __builtin_bit_cast(bf16x8, vbuf[(d * 8 + kk) * 64 + lanev]);
;         o[d] = MFMA32(vf, pb[((v & 1) * 8 + kk) >> 1][kk & 1], o[d]);
;         if (d == 3) __builtin_amdgcn_sched_barrier(0);
;       }
;     if (v & 1) {
; #pragma unroll
;       for (int d = 0; d < 4; ++d)
; #pragma unroll
;         for (int g4 = 0; g4 < 4; ++g4) {
;           int dim = ((v >> 1) * 4 + d) * 32 + 8 * g4 + 4 * hlv;
;           uint2 ov;
;           ov.x = pack2(o[d][g4 * 4 + 0] * inv, o[d][g4 * 4 + 1] * inv);
;           ov.y = pack2(o[d][g4 * 4 + 2] * inv, o[d][g4 * 4 + 3] * inv);
;           *(uint2*)(Obuf + ooff + dim) = ov;
;         }
;     }
;     __syncthreads();
;     if (v < 3) { STOREV(tidv); __syncthreads(); }
	v_mfma_f32_32x32x16_bf16 v[0:15], v[84:87], v[76:79], v[0:15]
	ds_read_b128 v[76:79], v193 offset:3072
	ds_read_b128 v[80:83], v193 offset:11264
	s_waitcnt lgkmcnt(1)
	v_mfma_f32_32x32x16_bf16 v[48:63], v[76:79], v[72:75], v[48:63]
	s_waitcnt lgkmcnt(0)
	v_mfma_f32_32x32x16_bf16 v[32:47], v[80:83], v[72:75], v[32:47]
	ds_read_b128 v[76:79], v193 offset:19456
	ds_read_b128 v[80:83], v193 offset:27648
	s_waitcnt lgkmcnt(1)
	v_mfma_f32_32x32x16_bf16 v[16:31], v[76:79], v[72:75], v[16:31]
	s_waitcnt lgkmcnt(0)
	v_mfma_f32_32x32x16_bf16 v[0:15], v[80:83], v[72:75], v[0:15]
	ds_read_b128 v[72:75], v193 offset:4096
	ds_read_b128 v[76:79], v193 offset:12288
	s_waitcnt lgkmcnt(1)
	v_mfma_f32_32x32x16_bf16 v[48:63], v[72:75], v[68:71], v[48:63]
	s_waitcnt lgkmcnt(0)
	v_mfma_f32_32x32x16_bf16 v[32:47], v[76:79], v[68:71], v[32:47]
	ds_read_b128 v[72:75], v193 offset:20480
	ds_read_b128 v[76:79], v193 offset:28672
	s_waitcnt lgkmcnt(1)
	v_mfma_f32_32x32x16_bf16 v[16:31], v[72:75], v[68:71], v[16:31]
	s_waitcnt lgkmcnt(0)
	v_mfma_f32_32x32x16_bf16 v[0:15], v[76:79], v[68:71], v[0:15]
	ds_read_b128 v[68:71], v193 offset:5120
	ds_read_b128 v[72:75], v193 offset:13312
	s_waitcnt lgkmcnt(1)
	v_mfma_f32_32x32x16_bf16 v[48:63], v[68:71], v[64:67], v[48:63]
	s_waitcnt lgkmcnt(0)
	v_mfma_f32_32x32x16_bf16 v[32:47], v[72:75], v[64:67], v[32:47]
	ds_read_b128 v[68:71], v193 offset:21504
	ds_read_b128 v[72:75], v193 offset:29696
	s_waitcnt lgkmcnt(1)
	v_mfma_f32_32x32x16_bf16 v[16:31], v[68:71], v[64:67], v[16:31]
	s_waitcnt lgkmcnt(0)
	v_mfma_f32_32x32x16_bf16 v[0:15], v[72:75], v[64:67], v[0:15]
	ds_read_b128 v[64:67], v193 offset:6144
	ds_read_b128 v[68:71], v193 offset:14336
	s_waitcnt lgkmcnt(1)
	v_mfma_f32_32x32x16_bf16 v[48:63], v[64:67], v[124:127], v[48:63]
	s_waitcnt lgkmcnt(0)
	v_mfma_f32_32x32x16_bf16 v[32:47], v[68:71], v[124:127], v[32:47]
	ds_read_b128 v[64:67], v193 offset:22528
	ds_read_b128 v[68:71], v193 offset:30720
	s_waitcnt lgkmcnt(1)
	v_mfma_f32_32x32x16_bf16 v[16:31], v[64:67], v[124:127], v[16:31]
	s_waitcnt lgkmcnt(0)
	v_mfma_f32_32x32x16_bf16 v[0:15], v[68:71], v[124:127], v[0:15]
	ds_read_b128 v[64:67], v193 offset:7168
	ds_read_b128 v[68:71], v193 offset:15360
	s_waitcnt lgkmcnt(1)
	v_mfma_f32_32x32x16_bf16 v[48:63], v[64:67], v[120:123], v[48:63]
	s_waitcnt lgkmcnt(0)
	v_mfma_f32_32x32x16_bf16 v[32:47], v[68:71], v[120:123], v[32:47]
	ds_read_b128 v[64:67], v193 offset:23552
	ds_read_b128 v[68:71], v193 offset:31744
	s_waitcnt lgkmcnt(1)
	v_mfma_f32_32x32x16_bf16 v[16:31], v[64:67], v[120:123], v[16:31]
	s_waitcnt lgkmcnt(0)
	v_mfma_f32_32x32x16_bf16 v[0:15], v[68:71], v[120:123], v[0:15]
	s_barrier
	s_waitcnt vmcnt(7)
	ds_write_b128 v195, v[128:131]
	s_waitcnt vmcnt(6)
	ds_write_b128 v195, v[132:135] offset:4096
	s_waitcnt vmcnt(5)
	ds_write_b128 v195, v[136:139] offset:8192
	s_waitcnt vmcnt(4)
	ds_write_b128 v195, v[140:143] offset:12288
	s_waitcnt vmcnt(3)
	ds_write_b128 v195, v[144:147] offset:16384
	s_waitcnt vmcnt(2)
	ds_write_b128 v195, v[148:151] offset:20480
	s_waitcnt vmcnt(1)
	ds_write_b128 v195, v[152:155] offset:24576
	s_waitcnt vmcnt(0)
	ds_write_b128 v195, v[156:159] offset:28672
	s_waitcnt lgkmcnt(0)
	s_barrier
	ds_read_b128 v[64:67], v193
	ds_read_b128 v[68:71], v193 offset:8192
	s_waitcnt lgkmcnt(1)
	v_mfma_f32_32x32x16_bf16 v[48:63], v[64:67], v[116:119], v[48:63]
	s_waitcnt lgkmcnt(0)
	v_mfma_f32_32x32x16_bf16 v[32:47], v[68:71], v[116:119], v[32:47]
	ds_read_b128 v[64:67], v193 offset:16384
	ds_read_b128 v[68:71], v193 offset:24576
	s_waitcnt lgkmcnt(1)
	v_mfma_f32_32x32x16_bf16 v[16:31], v[64:67], v[116:119], v[16:31]
	s_waitcnt lgkmcnt(0)
	v_mfma_f32_32x32x16_bf16 v[0:15], v[68:71], v[116:119], v[0:15]
	ds_read_b128 v[64:67], v193 offset:1024
	ds_read_b128 v[68:71], v193 offset:9216
	s_waitcnt lgkmcnt(1)
	v_mfma_f32_32x32x16_bf16 v[48:63], v[64:67], v[112:115], v[48:63]
	s_waitcnt lgkmcnt(0)
	v_mfma_f32_32x32x16_bf16 v[32:47], v[68:71], v[112:115], v[32:47]
	ds_read_b128 v[64:67], v193 offset:17408
	ds_read_b128 v[68:71], v193 offset:25600
	s_waitcnt lgkmcnt(1)
	v_mfma_f32_32x32x16_bf16 v[16:31], v[64:67], v[112:115], v[16:31]
	s_waitcnt lgkmcnt(0)
	v_mfma_f32_32x32x16_bf16 v[0:15], v[68:71], v[112:115], v[0:15]
	ds_read_b128 v[64:67], v193 offset:2048
	ds_read_b128 v[68:71], v193 offset:10240
	s_waitcnt lgkmcnt(1)
	v_mfma_f32_32x32x16_bf16 v[48:63], v[64:67], v[108:111], v[48:63]
	s_waitcnt lgkmcnt(0)
	v_mfma_f32_32x32x16_bf16 v[32:47], v[68:71], v[108:111], v[32:47]
	ds_read_b128 v[64:67], v193 offset:18432
	ds_read_b128 v[68:71], v193 offset:26624
	s_waitcnt lgkmcnt(1)
	v_mfma_f32_32x32x16_bf16 v[16:31], v[64:67], v[108:111], v[16:31]
	s_waitcnt lgkmcnt(0)
	v_mfma_f32_32x32x16_bf16 v[0:15], v[68:71], v[108:111], v[0:15]
	ds_read_b128 v[64:67], v193 offset:3072
	ds_read_b128 v[68:71], v193 offset:11264
	s_waitcnt lgkmcnt(1)
	v_mfma_f32_32x32x16_bf16 v[48:63], v[64:67], v[104:107], v[48:63]
	s_waitcnt lgkmcnt(0)
	v_mfma_f32_32x32x16_bf16 v[32:47], v[68:71], v[104:107], v[32:47]
	ds_read_b128 v[64:67], v193 offset:19456
	ds_read_b128 v[68:71], v193 offset:27648
	s_waitcnt lgkmcnt(1)
	v_mfma_f32_32x32x16_bf16 v[16:31], v[64:67], v[104:107], v[16:31]
	s_waitcnt lgkmcnt(0)
	v_mfma_f32_32x32x16_bf16 v[0:15], v[68:71], v[104:107], v[0:15]
	ds_read_b128 v[64:67], v193 offset:4096
	ds_read_b128 v[68:71], v193 offset:12288
	s_waitcnt lgkmcnt(1)
	v_mfma_f32_32x32x16_bf16 v[48:63], v[64:67], v[100:103], v[48:63]
	s_waitcnt lgkmcnt(0)
	v_mfma_f32_32x32x16_bf16 v[32:47], v[68:71], v[100:103], v[32:47]
	ds_read_b128 v[64:67], v193 offset:20480
	ds_read_b128 v[68:71], v193 offset:28672
	s_waitcnt lgkmcnt(1)
; #define MFMA32(a, b, c) __builtin_amdgcn_mfma_f32_32x32x16_bf16((a), (b), (c), 0, 0, 0)
; DI void attn_prompt_block(const Params& p, int l, int b, int hh, int tt4, char* smem, bfr* Obuf) {
;     ...
; #pragma unroll
;     for (int kk = 0; kk < 8; ++kk)
; #pragma unroll
;       for (int d = 0; d < 4; ++d) {
;         bf16x8 vf = __builtin_bit_cast(bf16x8, vbuf[(d * 8 + kk) * 64 + lanev]);
;         o[d] = MFMA32(vf, pb[((v & 1) * 8 + kk) >> 1][kk & 1], o[d]);
;         if (d == 3) __builtin_amdgcn_sched_barrier(0);
;       }
;     if (v & 1) {
; #pragma unroll
;       for (int d = 0; d < 4; ++d)
; #pragma unroll
;         for (int g4 = 0; g4 < 4; ++g4) {
;           int dim = ((v >> 1) * 4 + d) * 32 + 8 * g4 + 4 * hlv;
;           uint2 ov;
;           ov.x = pack2(o[d][g4 * 4 + 0] * inv, o[d][g4 * 4 + 1] * inv);
;           ov.y = pack2(o[d][g4 * 4 + 2] * inv, o[d][g4 * 4 + 3] * inv);
;           *(uint2*)(Obuf + ooff + dim) = ov;
;         }
;     }
; DI void phase_attn(const Params& p, int l, char* smem) {
;     ...
;       for (int k = bi; k < 256; k += nb) {
;         int u = 2 * k + (upper ? 1 : 0);
;         if (nb == 256) { const int x = k & 7, j = (k >> 3) * 2 + (upper ? 1 : 0); u = (4 * x + (j >> 4)) * 16 + (j & 15); }
;         const int tt4 = u & 15, hh = (u >> 4) & 3, b = u >> 6;
;         attn_prompt_block(p, l, b, hh, tt4, smem, Obuf);
;       }
	v_mfma_f32_32x32x16_bf16 v[16:31], v[64:67], v[100:103], v[16:31]
	s_waitcnt lgkmcnt(0)
	v_mfma_f32_32x32x16_bf16 v[0:15], v[68:71], v[100:103], v[0:15]
	ds_read_b128 v[64:67], v193 offset:5120
	ds_read_b128 v[68:71], v193 offset:13312
	s_waitcnt lgkmcnt(1)
	v_mfma_f32_32x32x16_bf16 v[48:63], v[64:67], v[96:99], v[48:63]
	s_waitcnt lgkmcnt(0)
	v_mfma_f32_32x32x16_bf16 v[32:47], v[68:71], v[96:99], v[32:47]
	ds_read_b128 v[64:67], v193 offset:21504
	ds_read_b128 v[68:71], v193 offset:29696
	s_waitcnt lgkmcnt(1)
	v_mfma_f32_32x32x16_bf16 v[16:31], v[64:67], v[96:99], v[16:31]
	s_waitcnt lgkmcnt(0)
	v_mfma_f32_32x32x16_bf16 v[0:15], v[68:71], v[96:99], v[0:15]
	ds_read_b128 v[64:67], v193 offset:6144
	ds_read_b128 v[68:71], v193 offset:14336
	s_waitcnt lgkmcnt(1)
	v_mfma_f32_32x32x16_bf16 v[48:63], v[64:67], v[92:95], v[48:63]
	s_waitcnt lgkmcnt(0)
	v_mfma_f32_32x32x16_bf16 v[32:47], v[68:71], v[92:95], v[32:47]
	ds_read_b128 v[64:67], v193 offset:22528
	ds_read_b128 v[68:71], v193 offset:30720
	s_waitcnt lgkmcnt(1)
	v_mfma_f32_32x32x16_bf16 v[16:31], v[64:67], v[92:95], v[16:31]
	s_waitcnt lgkmcnt(0)
	v_mfma_f32_32x32x16_bf16 v[0:15], v[68:71], v[92:95], v[0:15]
	ds_read_b128 v[64:67], v193 offset:7168
	ds_read_b128 v[68:71], v193 offset:15360
	s_waitcnt lgkmcnt(1)
	v_mfma_f32_32x32x16_bf16 v[48:63], v[64:67], v[88:91], v[48:63]
	s_waitcnt lgkmcnt(0)
	v_mfma_f32_32x32x16_bf16 v[32:47], v[68:71], v[88:91], v[32:47]
	ds_read_b128 v[64:67], v193 offset:23552
	ds_read_b128 v[68:71], v193 offset:31744
	s_waitcnt lgkmcnt(1)
	v_mfma_f32_32x32x16_bf16 v[16:31], v[64:67], v[88:91], v[16:31]
	s_waitcnt lgkmcnt(0)
	v_mfma_f32_32x32x16_bf16 v[0:15], v[68:71], v[88:91], v[0:15]
	s_nop 3
	v_mul_f32_e64 v48, v180, v48
	v_mul_f32_e64 v49, v180, v49
	v_mul_f32_e64 v50, v180, v50
	v_mul_f32_e64 v51, v180, v51
	v_mul_f32_e64 v32, v180, v32
	v_mul_f32_e64 v33, v180, v33
	v_pk_mul_f32 v[34:35], v[180:181], v[34:35] op_sel_hi:[0,1]
	v_pk_mul_f32 v[16:17], v[180:181], v[16:17] op_sel_hi:[0,1]
	v_pk_mul_f32 v[18:19], v[180:181], v[18:19] op_sel_hi:[0,1]
	v_pk_mul_f32 v[0:1], v[180:181], v[0:1] op_sel_hi:[0,1]
	v_pk_mul_f32 v[2:3], v[180:181], v[2:3] op_sel_hi:[0,1]
	v_cvt_pk_bf16_f32 v48, v48, v49
	v_cvt_pk_bf16_f32 v49, v50, v51
	v_cvt_pk_bf16_f32 v32, v32, v33
	v_cvt_pk_bf16_f32 v33, v34, v35
	v_cvt_pk_bf16_f32 v16, v16, v17
	v_cvt_pk_bf16_f32 v17, v18, v19
	v_cvt_pk_bf16_f32 v0, v0, v1
	v_cvt_pk_bf16_f32 v1, v2, v3
	global_store_dwordx2 v[182:183], v[48:49], off offset:256 sc1
	v_pk_mul_f32 v[48:49], v[180:181], v[52:53] op_sel_hi:[0,1]
	v_pk_mul_f32 v[50:51], v[180:181], v[54:55] op_sel_hi:[0,1]
	global_store_dwordx2 v[182:183], v[32:33], off offset:320 sc1
	v_pk_mul_f32 v[32:33], v[180:181], v[36:37] op_sel_hi:[0,1]
	v_pk_mul_f32 v[34:35], v[180:181], v[38:39] op_sel_hi:[0,1]
	global_store_dwordx2 v[182:183], v[16:17], off offset:384 sc1
	v_pk_mul_f32 v[16:17], v[180:181], v[20:21] op_sel_hi:[0,1]
	v_pk_mul_f32 v[18:19], v[180:181], v[22:23] op_sel_hi:[0,1]
	global_store_dwordx2 v[182:183], v[0:1], off offset:448 sc1
	v_pk_mul_f32 v[0:1], v[180:181], v[4:5] op_sel_hi:[0,1]
	v_pk_mul_f32 v[2:3], v[180:181], v[6:7] op_sel_hi:[0,1]
	v_cvt_pk_bf16_f32 v48, v48, v49
	v_cvt_pk_bf16_f32 v49, v50, v51
	v_cvt_pk_bf16_f32 v32, v32, v33
	v_cvt_pk_bf16_f32 v33, v34, v35
	v_cvt_pk_bf16_f32 v16, v16, v17
	v_cvt_pk_bf16_f32 v17, v18, v19
	v_cvt_pk_bf16_f32 v0, v0, v1
	v_cvt_pk_bf16_f32 v1, v2, v3
	global_store_dwordx2 v[182:183], v[48:49], off offset:272 sc1
	v_pk_mul_f32 v[48:49], v[180:181], v[56:57] op_sel_hi:[0,1]
	v_pk_mul_f32 v[50:51], v[180:181], v[58:59] op_sel_hi:[0,1]
	global_store_dwordx2 v[182:183], v[32:33], off offset:336 sc1
	v_pk_mul_f32 v[32:33], v[180:181], v[40:41] op_sel_hi:[0,1]
	v_pk_mul_f32 v[34:35], v[180:181], v[42:43] op_sel_hi:[0,1]
	global_store_dwordx2 v[182:183], v[16:17], off offset:400 sc1
	v_pk_mul_f32 v[16:17], v[180:181], v[24:25] op_sel_hi:[0,1]
	v_pk_mul_f32 v[18:19], v[180:181], v[26:27] op_sel_hi:[0,1]
	global_store_dwordx2 v[182:183], v[0:1], off offset:464 sc1
	v_pk_mul_f32 v[0:1], v[180:181], v[8:9] op_sel_hi:[0,1]
	v_pk_mul_f32 v[2:3], v[180:181], v[10:11] op_sel_hi:[0,1]
	v_cvt_pk_bf16_f32 v48, v48, v49
	v_cvt_pk_bf16_f32 v49, v50, v51
	v_cvt_pk_bf16_f32 v32, v32, v33
	v_cvt_pk_bf16_f32 v33, v34, v35
	v_cvt_pk_bf16_f32 v16, v16, v17
	v_cvt_pk_bf16_f32 v17, v18, v19
	v_cvt_pk_bf16_f32 v0, v0, v1
	v_cvt_pk_bf16_f32 v1, v2, v3
	global_store_dwordx2 v[182:183], v[48:49], off offset:288 sc1
	v_pk_mul_f32 v[48:49], v[180:181], v[60:61] op_sel_hi:[0,1]
	v_pk_mul_f32 v[50:51], v[180:181], v[62:63] op_sel_hi:[0,1]
	global_store_dwordx2 v[182:183], v[32:33], off offset:352 sc1
	v_pk_mul_f32 v[32:33], v[180:181], v[44:45] op_sel_hi:[0,1]
	v_pk_mul_f32 v[34:35], v[180:181], v[46:47] op_sel_hi:[0,1]
	global_store_dwordx2 v[182:183], v[16:17], off offset:416 sc1
	v_pk_mul_f32 v[16:17], v[180:181], v[28:29] op_sel_hi:[0,1]
	v_pk_mul_f32 v[18:19], v[180:181], v[30:31] op_sel_hi:[0,1]
	global_store_dwordx2 v[182:183], v[0:1], off offset:480 sc1
	v_pk_mul_f32 v[0:1], v[180:181], v[12:13] op_sel_hi:[0,1]
	v_pk_mul_f32 v[2:3], v[180:181], v[14:15] op_sel_hi:[0,1]
	s_add_i32 s51, s51, s27
	s_add_i32 s25, s25, s30
	s_add_i32 s24, s24, s33
	v_cvt_pk_bf16_f32 v48, v48, v49
	v_cvt_pk_bf16_f32 v49, v50, v51
	v_cvt_pk_bf16_f32 v32, v32, v33
	v_cvt_pk_bf16_f32 v33, v34, v35
	v_cvt_pk_bf16_f32 v16, v16, v17
	v_cvt_pk_bf16_f32 v17, v18, v19
	v_cvt_pk_bf16_f32 v0, v0, v1
	v_cvt_pk_bf16_f32 v1, v2, v3
	s_cmpk_lt_i32 s51, 0x100
	global_store_dwordx2 v[182:183], v[48:49], off offset:304 sc1
	global_store_dwordx2 v[182:183], v[32:33], off offset:368 sc1
	global_store_dwordx2 v[182:183], v[16:17], off offset:432 sc1
	global_store_dwordx2 v[182:183], v[0:1], off offset:496 sc1
	s_barrier
	s_cbranch_scc0 .LBB0_995

; DI float bflo(unsigned u) { return __uint_as_float(u << 16); }
; DI float bfhi(unsigned u) { return __uint_as_float(u & 0xffff0000u); }
; template <int WIN>
; DI void pool_elem(const Params& p, int row, int c) {
;     ...
;   unsigned uu = *(const unsigned*)(P2 + (size_t)row * 2048 + c);
;   const float u0 = bflo(uu), u1 = bfhi(uu);
;   float s0 = u0, s1 = u1, cnt;
;   if (row < NPR) {
;     const int t = row & 2047, b = row >> 11;
;     if (t >= WIN - 1) {
;       cnt = (float)WIN;
;       unsigned w[WIN - 1];
; #pragma unroll
;       for (int j = 1; j < WIN; ++j) w[j - 1] = *(const unsigned*)(P2 + (size_t)(row - j) * 2048 + c);
; #pragma unroll
;       for (int j = 1; j < WIN; ++j) { s0 += bflo(w[j - 1]); s1 += bfhi(w[j - 1]); }
;     ...
;   *(unsigned*)(p.MIX + (size_t)row * 1024 + c) = pack2(s0 / cnt - u0, s1 / cnt - u1);
.Lp13f_w0:
	s_sub_u32 s26, s20, 1
	s_lshl_b32 s27, s26, 12
	s_lshr_b32 s28, s26, 20
	s_add_u32 s22, s8, s27
	s_addc_u32 s23, s9, s28
	global_load_dwordx2 v[16:17], v11, s[22:23]
	s_add_u32 s22, s22, 0x1000
	s_addc_u32 s23, s23, 0
	global_load_dwordx2 v[20:21], v11, s[22:23]
	s_add_u32 s22, s22, 0x1000
	s_addc_u32 s23, s23, 0
	global_load_dwordx2 v[24:25], v11, s[22:23]
	s_add_u32 s22, s22, 0x1000
	s_addc_u32 s23, s23, 0
	global_load_dwordx2 v[28:29], v11, s[22:23]
	s_add_u32 s22, s22, 0x1000
	s_addc_u32 s23, s23, 0
	global_load_dwordx2 v[32:33], v11, s[22:23]
	s_add_u32 s22, s22, 0x1000
	s_addc_u32 s23, s23, 0
	global_load_dwordx2 v[36:37], v11, s[22:23]
	s_add_u32 s22, s22, 0x1000
	s_addc_u32 s23, s23, 0
	global_load_dwordx2 v[40:41], v11, s[22:23]
	s_add_u32 s22, s22, 0x1000
	s_addc_u32 s23, s23, 0
	global_load_dwordx2 v[44:45], v11, s[22:23]
	s_add_u32 s22, s22, 0x1000
	s_addc_u32 s23, s23, 0
	global_load_dwordx2 v[48:49], v11, s[22:23]
	s_add_u32 s22, s22, 0x1000
	s_addc_u32 s23, s23, 0
	global_load_dwordx2 v[52:53], v11, s[22:23]
	s_add_u32 s22, s22, 0x1000
	s_addc_u32 s23, s23, 0
	global_load_dwordx2 v[56:57], v11, s[22:23]
	s_add_u32 s22, s22, 0x1000
	s_addc_u32 s23, s23, 0
	global_load_dwordx2 v[60:61], v11, s[22:23]
	s_add_u32 s22, s22, 0x1000
	s_addc_u32 s23, s23, 0
	global_load_dwordx2 v[64:65], v11, s[22:23]
	s_add_u32 s22, s22, 0x1000
	s_addc_u32 s23, s23, 0
	global_load_dwordx2 v[68:69], v11, s[22:23]
	s_add_u32 s22, s22, 0x1000
	s_addc_u32 s23, s23, 0
	global_load_dwordx2 v[72:73], v11, s[22:23]
	s_add_u32 s22, s22, 0x1000
	s_addc_u32 s23, s23, 0
	global_load_dwordx2 v[76:77], v11, s[22:23]
	s_add_u32 s22, s22, 0x1000
	s_addc_u32 s23, s23, 0
	global_load_dwordx2 v[80:81], v11, s[22:23]
	s_add_u32 s22, s22, 0x1000
	s_addc_u32 s23, s23, 0
	s_waitcnt vmcnt(15)
	v_and_b32_e32 v19, 0xffff0000, v17
	v_lshlrev_b32_e32 v18, 16, v17
	v_and_b32_e32 v17, 0xffff0000, v16
	v_lshlrev_b32_e32 v16, 16, v16
	v_and_b32_e32 v23, 0xffff0000, v21
	v_lshlrev_b32_e32 v22, 16, v21
	v_and_b32_e32 v21, 0xffff0000, v20
	v_lshlrev_b32_e32 v20, 16, v20
	v_add_f32_e32 v140, v20, v16
	v_add_f32_e32 v141, v21, v17
	v_add_f32_e32 v142, v22, v18
	v_add_f32_e32 v143, v23, v19
	v_mul_f32_e32 v140, 0.5, v140
	v_mul_f32_e32 v141, 0.5, v141
	v_mul_f32_e32 v142, 0.5, v142
	v_mul_f32_e32 v143, 0.5, v143
	v_sub_f32_e32 v140, v140, v20
	v_sub_f32_e32 v141, v141, v21
	v_sub_f32_e32 v142, v142, v22
	v_sub_f32_e32 v143, v143, v23
	v_cvt_pk_bf16_f32 v152, v140, v141
	v_cvt_pk_bf16_f32 v153, v142, v143
	s_waitcnt vmcnt(14)
	v_and_b32_e32 v27, 0xffff0000, v25
	v_lshlrev_b32_e32 v26, 16, v25
	v_and_b32_e32 v25, 0xffff0000, v24
	v_lshlrev_b32_e32 v24, 16, v24
	v_add_f32_e32 v140, v24, v20
	v_add_f32_e32 v141, v25, v21
	v_add_f32_e32 v142, v26, v22
	v_add_f32_e32 v143, v27, v23
	v_mul_f32_e32 v140, 0.5, v140
	v_mul_f32_e32 v141, 0.5, v141
	v_mul_f32_e32 v142, 0.5, v142
	v_mul_f32_e32 v143, 0.5, v143
	v_sub_f32_e32 v140, v140, v24
	v_sub_f32_e32 v141, v141, v25
	v_sub_f32_e32 v142, v142, v26
	v_sub_f32_e32 v143, v143, v27
	v_cvt_pk_bf16_f32 v154, v140, v141
	v_cvt_pk_bf16_f32 v155, v142, v143
	s_waitcnt vmcnt(13)
	v_and_b32_e32 v31, 0xffff0000, v29
	v_lshlrev_b32_e32 v30, 16, v29
	v_and_b32_e32 v29, 0xffff0000, v28
	v_lshlrev_b32_e32 v28, 16, v28
	v_add_f32_e32 v140, v28, v24
	v_add_f32_e32 v141, v29, v25
	v_add_f32_e32 v142, v30, v26
	v_add_f32_e32 v143, v31, v27
	v_mul_f32_e32 v140, 0.5, v140
	v_mul_f32_e32 v141, 0.5, v141
	v_mul_f32_e32 v142, 0.5, v142
	v_mul_f32_e32 v143, 0.5, v143
	v_sub_f32_e32 v140, v140, v28
	v_sub_f32_e32 v141, v141, v29
	v_sub_f32_e32 v142, v142, v30
	v_sub_f32_e32 v143, v143, v31
	v_cvt_pk_bf16_f32 v156, v140, v141
	v_cvt_pk_bf16_f32 v157, v142, v143
	s_waitcnt vmcnt(12)
	v_and_b32_e32 v35, 0xffff0000, v33
	v_lshlrev_b32_e32 v34, 16, v33
	v_and_b32_e32 v33, 0xffff0000, v32
	v_lshlrev_b32_e32 v32, 16, v32
	v_add_f32_e32 v140, v32, v28
	v_add_f32_e32 v141, v33, v29
	v_add_f32_e32 v142, v34, v30
	v_add_f32_e32 v143, v35, v31
	v_mul_f32_e32 v140, 0.5, v140
	v_mul_f32_e32 v141, 0.5, v141
	v_mul_f32_e32 v142, 0.5, v142
	v_mul_f32_e32 v143, 0.5, v143
	v_sub_f32_e32 v140, v140, v32
	v_sub_f32_e32 v141, v141, v33
	v_sub_f32_e32 v142, v142, v34
	v_sub_f32_e32 v143, v143, v35
	v_cvt_pk_bf16_f32 v158, v140, v141
	v_cvt_pk_bf16_f32 v159, v142, v143
	s_waitcnt vmcnt(11)
	v_and_b32_e32 v39, 0xffff0000, v37
	v_lshlrev_b32_e32 v38, 16, v37
	v_and_b32_e32 v37, 0xffff0000, v36
	v_lshlrev_b32_e32 v36, 16, v36
	v_add_f32_e32 v140, v36, v32
	v_add_f32_e32 v141, v37, v33
	v_add_f32_e32 v142, v38, v34
	v_add_f32_e32 v143, v39, v35
	v_mul_f32_e32 v140, 0.5, v140
	v_mul_f32_e32 v141, 0.5, v141
	v_mul_f32_e32 v142, 0.5, v142
	v_mul_f32_e32 v143, 0.5, v143
	v_sub_f32_e32 v140, v140, v36
	v_sub_f32_e32 v141, v141, v37
	v_sub_f32_e32 v142, v142, v38
	v_sub_f32_e32 v143, v143, v39
	v_cvt_pk_bf16_f32 v160, v140, v141
	v_cvt_pk_bf16_f32 v161, v142, v143
	s_waitcnt vmcnt(10)
	v_and_b32_e32 v43, 0xffff0000, v41
	v_lshlrev_b32_e32 v42, 16, v41
	v_and_b32_e32 v41, 0xffff0000, v40
	v_lshlrev_b32_e32 v40, 16, v40
	v_add_f32_e32 v140, v40, v36
	v_add_f32_e32 v141, v41, v37
	v_add_f32_e32 v142, v42, v38
	v_add_f32_e32 v143, v43, v39
	v_mul_f32_e32 v140, 0.5, v140
	v_mul_f32_e32 v141, 0.5, v141
	v_mul_f32_e32 v142, 0.5, v142
	v_mul_f32_e32 v143, 0.5, v143
	v_sub_f32_e32 v140, v140, v40
	v_sub_f32_e32 v141, v141, v41
	v_sub_f32_e32 v142, v142, v42
	v_sub_f32_e32 v143, v143, v43
	v_cvt_pk_bf16_f32 v162, v140, v141
	v_cvt_pk_bf16_f32 v163, v142, v143
	s_waitcnt vmcnt(9)
; DI float bflo(unsigned u) { return __uint_as_float(u << 16); }
; DI float bfhi(unsigned u) { return __uint_as_float(u & 0xffff0000u); }
; template <int WIN>
; DI void pool_elem(const Params& p, int row, int c) {
;     ...
;       for (int j = 1; j < WIN; ++j) w[j - 1] = *(const unsigned*)(P2 + (size_t)(row - j) * 2048 + c);
; #pragma unroll
;       for (int j = 1; j < WIN; ++j) { s0 += bflo(w[j - 1]); s1 += bfhi(w[j - 1]); }
;     ...
;   *(unsigned*)(p.MIX + (size_t)row * 1024 + c) = pack2(s0 / cnt - u0, s1 / cnt - u1);
	v_and_b32_e32 v47, 0xffff0000, v45
	v_lshlrev_b32_e32 v46, 16, v45
	v_and_b32_e32 v45, 0xffff0000, v44
	v_lshlrev_b32_e32 v44, 16, v44
	v_add_f32_e32 v140, v44, v40
	v_add_f32_e32 v141, v45, v41
	v_add_f32_e32 v142, v46, v42
	v_add_f32_e32 v143, v47, v43
	v_mul_f32_e32 v140, 0.5, v140
	v_mul_f32_e32 v141, 0.5, v141
	v_mul_f32_e32 v142, 0.5, v142
	v_mul_f32_e32 v143, 0.5, v143
	v_sub_f32_e32 v140, v140, v44
	v_sub_f32_e32 v141, v141, v45
	v_sub_f32_e32 v142, v142, v46
	v_sub_f32_e32 v143, v143, v47
	v_cvt_pk_bf16_f32 v164, v140, v141
	v_cvt_pk_bf16_f32 v165, v142, v143
	s_waitcnt vmcnt(8)
	v_and_b32_e32 v51, 0xffff0000, v49
	v_lshlrev_b32_e32 v50, 16, v49
	v_and_b32_e32 v49, 0xffff0000, v48
	v_lshlrev_b32_e32 v48, 16, v48
	v_add_f32_e32 v140, v48, v44
	v_add_f32_e32 v141, v49, v45
	v_add_f32_e32 v142, v50, v46
	v_add_f32_e32 v143, v51, v47
	v_mul_f32_e32 v140, 0.5, v140
	v_mul_f32_e32 v141, 0.5, v141
	v_mul_f32_e32 v142, 0.5, v142
	v_mul_f32_e32 v143, 0.5, v143
	v_sub_f32_e32 v140, v140, v48
	v_sub_f32_e32 v141, v141, v49
	v_sub_f32_e32 v142, v142, v50
	v_sub_f32_e32 v143, v143, v51
	v_cvt_pk_bf16_f32 v166, v140, v141
	v_cvt_pk_bf16_f32 v167, v142, v143
	s_waitcnt vmcnt(7)
	v_and_b32_e32 v55, 0xffff0000, v53
	v_lshlrev_b32_e32 v54, 16, v53
	v_and_b32_e32 v53, 0xffff0000, v52
	v_lshlrev_b32_e32 v52, 16, v52
	v_add_f32_e32 v140, v52, v48
	v_add_f32_e32 v141, v53, v49
	v_add_f32_e32 v142, v54, v50
	v_add_f32_e32 v143, v55, v51
	v_mul_f32_e32 v140, 0.5, v140
	v_mul_f32_e32 v141, 0.5, v141
	v_mul_f32_e32 v142, 0.5, v142
	v_mul_f32_e32 v143, 0.5, v143
	v_sub_f32_e32 v140, v140, v52
	v_sub_f32_e32 v141, v141, v53
	v_sub_f32_e32 v142, v142, v54
	v_sub_f32_e32 v143, v143, v55
	v_cvt_pk_bf16_f32 v168, v140, v141
	v_cvt_pk_bf16_f32 v169, v142, v143
	s_waitcnt vmcnt(6)
	v_and_b32_e32 v59, 0xffff0000, v57
	v_lshlrev_b32_e32 v58, 16, v57
	v_and_b32_e32 v57, 0xffff0000, v56
	v_lshlrev_b32_e32 v56, 16, v56
	v_add_f32_e32 v140, v56, v52
	v_add_f32_e32 v141, v57, v53
	v_add_f32_e32 v142, v58, v54
	v_add_f32_e32 v143, v59, v55
	v_mul_f32_e32 v140, 0.5, v140
	v_mul_f32_e32 v141, 0.5, v141
	v_mul_f32_e32 v142, 0.5, v142
	v_mul_f32_e32 v143, 0.5, v143
	v_sub_f32_e32 v140, v140, v56
	v_sub_f32_e32 v141, v141, v57
	v_sub_f32_e32 v142, v142, v58
	v_sub_f32_e32 v143, v143, v59
	v_cvt_pk_bf16_f32 v170, v140, v141
	v_cvt_pk_bf16_f32 v171, v142, v143
	s_waitcnt vmcnt(5)
	v_and_b32_e32 v63, 0xffff0000, v61
	v_lshlrev_b32_e32 v62, 16, v61
	v_and_b32_e32 v61, 0xffff0000, v60
	v_lshlrev_b32_e32 v60, 16, v60
	v_add_f32_e32 v140, v60, v56
	v_add_f32_e32 v141, v61, v57
	v_add_f32_e32 v142, v62, v58
	v_add_f32_e32 v143, v63, v59
	v_mul_f32_e32 v140, 0.5, v140
	v_mul_f32_e32 v141, 0.5, v141
	v_mul_f32_e32 v142, 0.5, v142
	v_mul_f32_e32 v143, 0.5, v143
	v_sub_f32_e32 v140, v140, v60
	v_sub_f32_e32 v141, v141, v61
	v_sub_f32_e32 v142, v142, v62
	v_sub_f32_e32 v143, v143, v63
	v_cvt_pk_bf16_f32 v172, v140, v141
	v_cvt_pk_bf16_f32 v173, v142, v143
	s_waitcnt vmcnt(4)
	v_and_b32_e32 v67, 0xffff0000, v65
	v_lshlrev_b32_e32 v66, 16, v65
	v_and_b32_e32 v65, 0xffff0000, v64
	v_lshlrev_b32_e32 v64, 16, v64
	v_add_f32_e32 v140, v64, v60
	v_add_f32_e32 v141, v65, v61
	v_add_f32_e32 v142, v66, v62
	v_add_f32_e32 v143, v67, v63
	v_mul_f32_e32 v140, 0.5, v140
	v_mul_f32_e32 v141, 0.5, v141
	v_mul_f32_e32 v142, 0.5, v142
	v_mul_f32_e32 v143, 0.5, v143
	v_sub_f32_e32 v140, v140, v64
	v_sub_f32_e32 v141, v141, v65
	v_sub_f32_e32 v142, v142, v66
	v_sub_f32_e32 v143, v143, v67
	v_cvt_pk_bf16_f32 v174, v140, v141
	v_cvt_pk_bf16_f32 v175, v142, v143
	s_waitcnt vmcnt(3)
	v_and_b32_e32 v71, 0xffff0000, v69
	v_lshlrev_b32_e32 v70, 16, v69
	v_and_b32_e32 v69, 0xffff0000, v68
	v_lshlrev_b32_e32 v68, 16, v68
	v_add_f32_e32 v140, v68, v64
	v_add_f32_e32 v141, v69, v65
	v_add_f32_e32 v142, v70, v66
	v_add_f32_e32 v143, v71, v67
	v_mul_f32_e32 v140, 0.5, v140
	v_mul_f32_e32 v141, 0.5, v141
	v_mul_f32_e32 v142, 0.5, v142
	v_mul_f32_e32 v143, 0.5, v143
	v_sub_f32_e32 v140, v140, v68
	v_sub_f32_e32 v141, v141, v69
	v_sub_f32_e32 v142, v142, v70
	v_sub_f32_e32 v143, v143, v71
	v_cvt_pk_bf16_f32 v176, v140, v141
	v_cvt_pk_bf16_f32 v177, v142, v143
	s_waitcnt vmcnt(2)
	v_and_b32_e32 v75, 0xffff0000, v73
	v_lshlrev_b32_e32 v74, 16, v73
	v_and_b32_e32 v73, 0xffff0000, v72
	v_lshlrev_b32_e32 v72, 16, v72
	v_add_f32_e32 v140, v72, v68
	v_add_f32_e32 v141, v73, v69
	v_add_f32_e32 v142, v74, v70
	v_add_f32_e32 v143, v75, v71
	v_mul_f32_e32 v140, 0.5, v140
	v_mul_f32_e32 v141, 0.5, v141
	v_mul_f32_e32 v142, 0.5, v142
	v_mul_f32_e32 v143, 0.5, v143
	v_sub_f32_e32 v140, v140, v72
	v_sub_f32_e32 v141, v141, v73
	v_sub_f32_e32 v142, v142, v74
	v_sub_f32_e32 v143, v143, v75
	v_cvt_pk_bf16_f32 v178, v140, v141
	v_cvt_pk_bf16_f32 v179, v142, v143
	s_waitcnt vmcnt(1)
	v_and_b32_e32 v79, 0xffff0000, v77
	v_lshlrev_b32_e32 v78, 16, v77
	v_and_b32_e32 v77, 0xffff0000, v76
	v_lshlrev_b32_e32 v76, 16, v76
	v_add_f32_e32 v140, v76, v72
	v_add_f32_e32 v141, v77, v73
	v_add_f32_e32 v142, v78, v74
	v_add_f32_e32 v143, v79, v75
	v_mul_f32_e32 v140, 0.5, v140
	v_mul_f32_e32 v141, 0.5, v141
	v_mul_f32_e32 v142, 0.5, v142
	v_mul_f32_e32 v143, 0.5, v143
	v_sub_f32_e32 v140, v140, v76
	v_sub_f32_e32 v141, v141, v77
	v_sub_f32_e32 v142, v142, v78
	v_sub_f32_e32 v143, v143, v79
	v_cvt_pk_bf16_f32 v180, v140, v141
	v_cvt_pk_bf16_f32 v181, v142, v143
	s_waitcnt vmcnt(0)
; DI float bflo(unsigned u) { return __uint_as_float(u << 16); }
; DI float bfhi(unsigned u) { return __uint_as_float(u & 0xffff0000u); }
; template <int WIN>
; DI void pool_elem(const Params& p, int row, int c) {
;     ...
;   unsigned uu = *(const unsigned*)(P2 + (size_t)row * 2048 + c);
;   const float u0 = bflo(uu), u1 = bfhi(uu);
;   float s0 = u0, s1 = u1, cnt;
;   if (row < NPR) {
;     const int t = row & 2047, b = row >> 11;
;     if (t >= WIN - 1) {
;       cnt = (float)WIN;
;       unsigned w[WIN - 1];
; #pragma unroll
;       for (int j = 1; j < WIN; ++j) w[j - 1] = *(const unsigned*)(P2 + (size_t)(row - j) * 2048 + c);
; #pragma unroll
;       for (int j = 1; j < WIN; ++j) { s0 += bflo(w[j - 1]); s1 += bfhi(w[j - 1]); }
;     ...
;     if (t >= 2033) {
;       float2 o = {u0, u1};
;       *(float2*)(p.out + O_POOLP + ((size_t)b * 15 + (t - 2033)) * 1024 + c) = o;
;     }
;   } else {
;     const int s = row - NPR;
;     cnt = (float)WIN;
;     const float* sp = p.state_pool + (size_t)s * 15 * 1024 + c;
;     float2 st[15];
; #pragma unroll
;     for (int j = 0; j < 15; ++j) st[j] = *(const float2*)(sp + (size_t)j * 1024);
; #pragma unroll
;     for (int j = 1; j < WIN; ++j) { s0 += st[15 - j].x; s1 += st[15 - j].y; }
;     float* op = p.out + O_POOLS + (size_t)s * 15 * 1024 + c;
; #pragma unroll
;     for (int j = 0; j < 14; ++j) *(float2*)(op + (size_t)j * 1024) = st[j + 1];
;     float2 o = {u0, u1};
;     *(float2*)(op + (size_t)14 * 1024) = o;
;   }
;   *(unsigned*)(p.MIX + (size_t)row * 1024 + c) = pack2(s0 / cnt - u0, s1 / cnt - u1);
	v_and_b32_e32 v83, 0xffff0000, v81
	v_lshlrev_b32_e32 v82, 16, v81
	v_and_b32_e32 v81, 0xffff0000, v80
	v_lshlrev_b32_e32 v80, 16, v80
	v_add_f32_e32 v140, v80, v76
	v_add_f32_e32 v141, v81, v77
	v_add_f32_e32 v142, v82, v78
	v_add_f32_e32 v143, v83, v79
	v_mul_f32_e32 v140, 0.5, v140
	v_mul_f32_e32 v141, 0.5, v141
	v_mul_f32_e32 v142, 0.5, v142
	v_mul_f32_e32 v143, 0.5, v143
	v_sub_f32_e32 v140, v140, v80
	v_sub_f32_e32 v141, v141, v81
	v_sub_f32_e32 v142, v142, v82
	v_sub_f32_e32 v143, v143, v83
	v_cvt_pk_bf16_f32 v182, v140, v141
	v_cvt_pk_bf16_f32 v183, v142, v143
	global_store_dwordx2 v11, v[152:153], s[24:25] sc1
	s_add_u32 s24, s24, 0x800
	s_addc_u32 s25, s25, 0
	global_store_dwordx2 v11, v[154:155], s[24:25] sc1
	s_add_u32 s24, s24, 0x800
	s_addc_u32 s25, s25, 0
	global_store_dwordx2 v11, v[156:157], s[24:25] sc1
	s_add_u32 s24, s24, 0x800
	s_addc_u32 s25, s25, 0
	global_store_dwordx2 v11, v[158:159], s[24:25] sc1
	s_add_u32 s24, s24, 0x800
	s_addc_u32 s25, s25, 0
	global_store_dwordx2 v11, v[160:161], s[24:25] sc1
	s_add_u32 s24, s24, 0x800
	s_addc_u32 s25, s25, 0
	global_store_dwordx2 v11, v[162:163], s[24:25] sc1
	s_add_u32 s24, s24, 0x800
	s_addc_u32 s25, s25, 0
	global_store_dwordx2 v11, v[164:165], s[24:25] sc1
	s_add_u32 s24, s24, 0x800
	s_addc_u32 s25, s25, 0
	global_store_dwordx2 v11, v[166:167], s[24:25] sc1
	s_add_u32 s24, s24, 0x800
	s_addc_u32 s25, s25, 0
	global_store_dwordx2 v11, v[168:169], s[24:25] sc1
	s_add_u32 s24, s24, 0x800
	s_addc_u32 s25, s25, 0
	global_store_dwordx2 v11, v[170:171], s[24:25] sc1
	s_add_u32 s24, s24, 0x800
	s_addc_u32 s25, s25, 0
	global_store_dwordx2 v11, v[172:173], s[24:25] sc1
	s_add_u32 s24, s24, 0x800
	s_addc_u32 s25, s25, 0
	global_store_dwordx2 v11, v[174:175], s[24:25] sc1
	s_add_u32 s24, s24, 0x800
	s_addc_u32 s25, s25, 0
	global_store_dwordx2 v11, v[176:177], s[24:25] sc1
	s_add_u32 s24, s24, 0x800
	s_addc_u32 s25, s25, 0
	global_store_dwordx2 v11, v[178:179], s[24:25] sc1
	s_add_u32 s24, s24, 0x800
	s_addc_u32 s25, s25, 0
	global_store_dwordx2 v11, v[180:181], s[24:25] sc1
	s_add_u32 s24, s24, 0x800
	s_addc_u32 s25, s25, 0
	global_store_dwordx2 v11, v[182:183], s[24:25] sc1
	s_add_u32 s24, s24, 0x800
	s_addc_u32 s25, s25, 0
	s_cmp_eq_u32 s18, 127
	s_cbranch_scc0 .Lp13f_next
	s_mul_i32 s26, s17, 61440
	s_add_u32 s26, s26, 0x431c000
	s_add_u32 s22, s12, s26
	s_addc_u32 s23, s13, 0
	global_store_dwordx4 v12, v[24:27], s[22:23] sc1
	s_add_u32 s22, s22, 0x1000
	s_addc_u32 s23, s23, 0
	global_store_dwordx4 v12, v[28:31], s[22:23] sc1
	s_add_u32 s22, s22, 0x1000
	s_addc_u32 s23, s23, 0
	global_store_dwordx4 v12, v[32:35], s[22:23] sc1
	s_add_u32 s22, s22, 0x1000
	s_addc_u32 s23, s23, 0
	global_store_dwordx4 v12, v[36:39], s[22:23] sc1
	s_add_u32 s22, s22, 0x1000
	s_addc_u32 s23, s23, 0
	global_store_dwordx4 v12, v[40:43], s[22:23] sc1
	s_add_u32 s22, s22, 0x1000
	s_addc_u32 s23, s23, 0
	global_store_dwordx4 v12, v[44:47], s[22:23] sc1
	s_add_u32 s22, s22, 0x1000
	s_addc_u32 s23, s23, 0
	global_store_dwordx4 v12, v[48:51], s[22:23] sc1
	s_add_u32 s22, s22, 0x1000
	s_addc_u32 s23, s23, 0
	global_store_dwordx4 v12, v[52:55], s[22:23] sc1
	s_add_u32 s22, s22, 0x1000
	s_addc_u32 s23, s23, 0
	global_store_dwordx4 v12, v[56:59], s[22:23] sc1
	s_add_u32 s22, s22, 0x1000
	s_addc_u32 s23, s23, 0
	global_store_dwordx4 v12, v[60:63], s[22:23] sc1
	s_add_u32 s22, s22, 0x1000
	s_addc_u32 s23, s23, 0
	global_store_dwordx4 v12, v[64:67], s[22:23] sc1
	s_add_u32 s22, s22, 0x1000
	s_addc_u32 s23, s23, 0
	global_store_dwordx4 v12, v[68:71], s[22:23] sc1
	s_add_u32 s22, s22, 0x1000
	s_addc_u32 s23, s23, 0
	global_store_dwordx4 v12, v[72:75], s[22:23] sc1
	s_add_u32 s22, s22, 0x1000
	s_addc_u32 s23, s23, 0
	global_store_dwordx4 v12, v[76:79], s[22:23] sc1
	s_add_u32 s22, s22, 0x1000
	s_addc_u32 s23, s23, 0
	global_store_dwordx4 v12, v[80:83], s[22:23] sc1
	s_add_u32 s22, s22, 0x1000
	s_addc_u32 s23, s23, 0
	s_branch .Lp13f_next
.Lp13f_w1:
	s_sub_u32 s26, s20, 3
	s_lshl_b32 s27, s26, 12
	s_lshr_b32 s28, s26, 20
	s_add_u32 s22, s8, s27
	s_addc_u32 s23, s9, s28
	global_load_dwordx2 v[16:17], v11, s[22:23]
	s_add_u32 s22, s22, 0x1000
	s_addc_u32 s23, s23, 0
	global_load_dwordx2 v[20:21], v11, s[22:23]
	s_add_u32 s22, s22, 0x1000
	s_addc_u32 s23, s23, 0
	global_load_dwordx2 v[24:25], v11, s[22:23]
	s_add_u32 s22, s22, 0x1000
	s_addc_u32 s23, s23, 0
	global_load_dwordx2 v[28:29], v11, s[22:23]
	s_add_u32 s22, s22, 0x1000
	s_addc_u32 s23, s23, 0
	global_load_dwordx2 v[32:33], v11, s[22:23]
	s_add_u32 s22, s22, 0x1000
	s_addc_u32 s23, s23, 0
	global_load_dwordx2 v[36:37], v11, s[22:23]
	s_add_u32 s22, s22, 0x1000
	s_addc_u32 s23, s23, 0
	global_load_dwordx2 v[40:41], v11, s[22:23]
	s_add_u32 s22, s22, 0x1000
	s_addc_u32 s23, s23, 0
	global_load_dwordx2 v[44:45], v11, s[22:23]
	s_add_u32 s22, s22, 0x1000
	s_addc_u32 s23, s23, 0
	global_load_dwordx2 v[48:49], v11, s[22:23]
	s_add_u32 s22, s22, 0x1000
	s_addc_u32 s23, s23, 0
	global_load_dwordx2 v[52:53], v11, s[22:23]
	s_add_u32 s22, s22, 0x1000
	s_addc_u32 s23, s23, 0
	global_load_dwordx2 v[56:57], v11, s[22:23]
	s_add_u32 s22, s22, 0x1000
	s_addc_u32 s23, s23, 0
	global_load_dwordx2 v[60:61], v11, s[22:23]
	s_add_u32 s22, s22, 0x1000
	s_addc_u32 s23, s23, 0
	global_load_dwordx2 v[64:65], v11, s[22:23]
	s_add_u32 s22, s22, 0x1000
	s_addc_u32 s23, s23, 0
	global_load_dwordx2 v[68:69], v11, s[22:23]
	s_add_u32 s22, s22, 0x1000
	s_addc_u32 s23, s23, 0
	global_load_dwordx2 v[72:73], v11, s[22:23]
	s_add_u32 s22, s22, 0x1000
	s_addc_u32 s23, s23, 0
	global_load_dwordx2 v[76:77], v11, s[22:23]
	s_add_u32 s22, s22, 0x1000
	s_addc_u32 s23, s23, 0
	global_load_dwordx2 v[80:81], v11, s[22:23]
	s_add_u32 s22, s22, 0x1000
	s_addc_u32 s23, s23, 0
	global_load_dwordx2 v[84:85], v11, s[22:23]
	s_add_u32 s22, s22, 0x1000
	s_addc_u32 s23, s23, 0
	global_load_dwordx2 v[88:89], v11, s[22:23]
	s_add_u32 s22, s22, 0x1000
	s_addc_u32 s23, s23, 0
	s_waitcnt vmcnt(15)
; DI float bflo(unsigned u) { return __uint_as_float(u << 16); }
; DI float bfhi(unsigned u) { return __uint_as_float(u & 0xffff0000u); }
; template <int WIN>
; DI void pool_elem(const Params& p, int row, int c) {
;     ...
;       for (int j = 1; j < WIN; ++j) w[j - 1] = *(const unsigned*)(P2 + (size_t)(row - j) * 2048 + c);
; #pragma unroll
;       for (int j = 1; j < WIN; ++j) { s0 += bflo(w[j - 1]); s1 += bfhi(w[j - 1]); }
;     ...
;   *(unsigned*)(p.MIX + (size_t)row * 1024 + c) = pack2(s0 / cnt - u0, s1 / cnt - u1);
	v_and_b32_e32 v19, 0xffff0000, v17
	v_lshlrev_b32_e32 v18, 16, v17
	v_and_b32_e32 v17, 0xffff0000, v16
	v_lshlrev_b32_e32 v16, 16, v16
	v_and_b32_e32 v23, 0xffff0000, v21
	v_lshlrev_b32_e32 v22, 16, v21
	v_and_b32_e32 v21, 0xffff0000, v20
	v_lshlrev_b32_e32 v20, 16, v20
	v_and_b32_e32 v27, 0xffff0000, v25
	v_lshlrev_b32_e32 v26, 16, v25
	v_and_b32_e32 v25, 0xffff0000, v24
	v_lshlrev_b32_e32 v24, 16, v24
	v_and_b32_e32 v31, 0xffff0000, v29
	v_lshlrev_b32_e32 v30, 16, v29
	v_and_b32_e32 v29, 0xffff0000, v28
	v_lshlrev_b32_e32 v28, 16, v28
	v_add_f32_e32 v140, v28, v24
	v_add_f32_e32 v141, v29, v25
	v_add_f32_e32 v142, v30, v26
	v_add_f32_e32 v143, v31, v27
	v_add_f32_e32 v140, v140, v20
	v_add_f32_e32 v141, v141, v21
	v_add_f32_e32 v142, v142, v22
	v_add_f32_e32 v143, v143, v23
	v_add_f32_e32 v140, v140, v16
	v_add_f32_e32 v141, v141, v17
	v_add_f32_e32 v142, v142, v18
	v_add_f32_e32 v143, v143, v19
	v_mul_f32_e32 v140, 0x3e800000, v140
	v_mul_f32_e32 v141, 0x3e800000, v141
	v_mul_f32_e32 v142, 0x3e800000, v142
	v_mul_f32_e32 v143, 0x3e800000, v143
	v_sub_f32_e32 v140, v140, v28
	v_sub_f32_e32 v141, v141, v29
	v_sub_f32_e32 v142, v142, v30
	v_sub_f32_e32 v143, v143, v31
	v_cvt_pk_bf16_f32 v152, v140, v141
	v_cvt_pk_bf16_f32 v153, v142, v143
	s_waitcnt vmcnt(14)
	v_and_b32_e32 v35, 0xffff0000, v33
	v_lshlrev_b32_e32 v34, 16, v33
	v_and_b32_e32 v33, 0xffff0000, v32
	v_lshlrev_b32_e32 v32, 16, v32
	v_add_f32_e32 v140, v32, v28
	v_add_f32_e32 v141, v33, v29
	v_add_f32_e32 v142, v34, v30
	v_add_f32_e32 v143, v35, v31
	v_add_f32_e32 v140, v140, v24
	v_add_f32_e32 v141, v141, v25
	v_add_f32_e32 v142, v142, v26
	v_add_f32_e32 v143, v143, v27
	v_add_f32_e32 v140, v140, v20
	v_add_f32_e32 v141, v141, v21
	v_add_f32_e32 v142, v142, v22
	v_add_f32_e32 v143, v143, v23
	v_mul_f32_e32 v140, 0x3e800000, v140
	v_mul_f32_e32 v141, 0x3e800000, v141
	v_mul_f32_e32 v142, 0x3e800000, v142
	v_mul_f32_e32 v143, 0x3e800000, v143
	v_sub_f32_e32 v140, v140, v32
	v_sub_f32_e32 v141, v141, v33
	v_sub_f32_e32 v142, v142, v34
	v_sub_f32_e32 v143, v143, v35
	v_cvt_pk_bf16_f32 v154, v140, v141
	v_cvt_pk_bf16_f32 v155, v142, v143
	s_waitcnt vmcnt(13)
	v_and_b32_e32 v39, 0xffff0000, v37
	v_lshlrev_b32_e32 v38, 16, v37
	v_and_b32_e32 v37, 0xffff0000, v36
	v_lshlrev_b32_e32 v36, 16, v36
	v_add_f32_e32 v140, v36, v32
	v_add_f32_e32 v141, v37, v33
	v_add_f32_e32 v142, v38, v34
	v_add_f32_e32 v143, v39, v35
	v_add_f32_e32 v140, v140, v28
	v_add_f32_e32 v141, v141, v29
	v_add_f32_e32 v142, v142, v30
	v_add_f32_e32 v143, v143, v31
	v_add_f32_e32 v140, v140, v24
	v_add_f32_e32 v141, v141, v25
	v_add_f32_e32 v142, v142, v26
	v_add_f32_e32 v143, v143, v27
	v_mul_f32_e32 v140, 0x3e800000, v140
	v_mul_f32_e32 v141, 0x3e800000, v141
	v_mul_f32_e32 v142, 0x3e800000, v142
	v_mul_f32_e32 v143, 0x3e800000, v143
	v_sub_f32_e32 v140, v140, v36
	v_sub_f32_e32 v141, v141, v37
	v_sub_f32_e32 v142, v142, v38
	v_sub_f32_e32 v143, v143, v39
	v_cvt_pk_bf16_f32 v156, v140, v141
	v_cvt_pk_bf16_f32 v157, v142, v143
	s_waitcnt vmcnt(12)
	v_and_b32_e32 v43, 0xffff0000, v41
	v_lshlrev_b32_e32 v42, 16, v41
	v_and_b32_e32 v41, 0xffff0000, v40
	v_lshlrev_b32_e32 v40, 16, v40
	v_add_f32_e32 v140, v40, v36
	v_add_f32_e32 v141, v41, v37
	v_add_f32_e32 v142, v42, v38
	v_add_f32_e32 v143, v43, v39
	v_add_f32_e32 v140, v140, v32
	v_add_f32_e32 v141, v141, v33
	v_add_f32_e32 v142, v142, v34
	v_add_f32_e32 v143, v143, v35
	v_add_f32_e32 v140, v140, v28
	v_add_f32_e32 v141, v141, v29
	v_add_f32_e32 v142, v142, v30
	v_add_f32_e32 v143, v143, v31
	v_mul_f32_e32 v140, 0x3e800000, v140
	v_mul_f32_e32 v141, 0x3e800000, v141
	v_mul_f32_e32 v142, 0x3e800000, v142
	v_mul_f32_e32 v143, 0x3e800000, v143
	v_sub_f32_e32 v140, v140, v40
	v_sub_f32_e32 v141, v141, v41
	v_sub_f32_e32 v142, v142, v42
	v_sub_f32_e32 v143, v143, v43
	v_cvt_pk_bf16_f32 v158, v140, v141
	v_cvt_pk_bf16_f32 v159, v142, v143
	s_waitcnt vmcnt(11)
	v_and_b32_e32 v47, 0xffff0000, v45
	v_lshlrev_b32_e32 v46, 16, v45
	v_and_b32_e32 v45, 0xffff0000, v44
	v_lshlrev_b32_e32 v44, 16, v44
	v_add_f32_e32 v140, v44, v40
	v_add_f32_e32 v141, v45, v41
	v_add_f32_e32 v142, v46, v42
	v_add_f32_e32 v143, v47, v43
	v_add_f32_e32 v140, v140, v36
	v_add_f32_e32 v141, v141, v37
	v_add_f32_e32 v142, v142, v38
	v_add_f32_e32 v143, v143, v39
	v_add_f32_e32 v140, v140, v32
	v_add_f32_e32 v141, v141, v33
	v_add_f32_e32 v142, v142, v34
	v_add_f32_e32 v143, v143, v35
	v_mul_f32_e32 v140, 0x3e800000, v140
	v_mul_f32_e32 v141, 0x3e800000, v141
	v_mul_f32_e32 v142, 0x3e800000, v142
	v_mul_f32_e32 v143, 0x3e800000, v143
	v_sub_f32_e32 v140, v140, v44
	v_sub_f32_e32 v141, v141, v45
	v_sub_f32_e32 v142, v142, v46
	v_sub_f32_e32 v143, v143, v47
	v_cvt_pk_bf16_f32 v160, v140, v141
	v_cvt_pk_bf16_f32 v161, v142, v143
	s_waitcnt vmcnt(10)
	v_and_b32_e32 v51, 0xffff0000, v49
	v_lshlrev_b32_e32 v50, 16, v49
	v_and_b32_e32 v49, 0xffff0000, v48
	v_lshlrev_b32_e32 v48, 16, v48
	v_add_f32_e32 v140, v48, v44
	v_add_f32_e32 v141, v49, v45
	v_add_f32_e32 v142, v50, v46
	v_add_f32_e32 v143, v51, v47
	v_add_f32_e32 v140, v140, v40
	v_add_f32_e32 v141, v141, v41
	v_add_f32_e32 v142, v142, v42
	v_add_f32_e32 v143, v143, v43
	v_add_f32_e32 v140, v140, v36
	v_add_f32_e32 v141, v141, v37
	v_add_f32_e32 v142, v142, v38
	v_add_f32_e32 v143, v143, v39
	v_mul_f32_e32 v140, 0x3e800000, v140
	v_mul_f32_e32 v141, 0x3e800000, v141
	v_mul_f32_e32 v142, 0x3e800000, v142
	v_mul_f32_e32 v143, 0x3e800000, v143
	v_sub_f32_e32 v140, v140, v48
	v_sub_f32_e32 v141, v141, v49
	v_sub_f32_e32 v142, v142, v50
	v_sub_f32_e32 v143, v143, v51
	v_cvt_pk_bf16_f32 v162, v140, v141
	v_cvt_pk_bf16_f32 v163, v142, v143
	s_waitcnt vmcnt(9)
; DI float bflo(unsigned u) { return __uint_as_float(u << 16); }
; DI float bfhi(unsigned u) { return __uint_as_float(u & 0xffff0000u); }
; template <int WIN>
; DI void pool_elem(const Params& p, int row, int c) {
;     ...
;       for (int j = 1; j < WIN; ++j) w[j - 1] = *(const unsigned*)(P2 + (size_t)(row - j) * 2048 + c);
; #pragma unroll
;       for (int j = 1; j < WIN; ++j) { s0 += bflo(w[j - 1]); s1 += bfhi(w[j - 1]); }
;     ...
;   *(unsigned*)(p.MIX + (size_t)row * 1024 + c) = pack2(s0 / cnt - u0, s1 / cnt - u1);
	v_and_b32_e32 v55, 0xffff0000, v53
	v_lshlrev_b32_e32 v54, 16, v53
	v_and_b32_e32 v53, 0xffff0000, v52
	v_lshlrev_b32_e32 v52, 16, v52
	v_add_f32_e32 v140, v52, v48
	v_add_f32_e32 v141, v53, v49
	v_add_f32_e32 v142, v54, v50
	v_add_f32_e32 v143, v55, v51
	v_add_f32_e32 v140, v140, v44
	v_add_f32_e32 v141, v141, v45
	v_add_f32_e32 v142, v142, v46
	v_add_f32_e32 v143, v143, v47
	v_add_f32_e32 v140, v140, v40
	v_add_f32_e32 v141, v141, v41
	v_add_f32_e32 v142, v142, v42
	v_add_f32_e32 v143, v143, v43
	v_mul_f32_e32 v140, 0x3e800000, v140
	v_mul_f32_e32 v141, 0x3e800000, v141
	v_mul_f32_e32 v142, 0x3e800000, v142
	v_mul_f32_e32 v143, 0x3e800000, v143
	v_sub_f32_e32 v140, v140, v52
	v_sub_f32_e32 v141, v141, v53
	v_sub_f32_e32 v142, v142, v54
	v_sub_f32_e32 v143, v143, v55
	v_cvt_pk_bf16_f32 v164, v140, v141
	v_cvt_pk_bf16_f32 v165, v142, v143
	s_waitcnt vmcnt(8)
	v_and_b32_e32 v59, 0xffff0000, v57
	v_lshlrev_b32_e32 v58, 16, v57
	v_and_b32_e32 v57, 0xffff0000, v56
	v_lshlrev_b32_e32 v56, 16, v56
	v_add_f32_e32 v140, v56, v52
	v_add_f32_e32 v141, v57, v53
	v_add_f32_e32 v142, v58, v54
	v_add_f32_e32 v143, v59, v55
	v_add_f32_e32 v140, v140, v48
	v_add_f32_e32 v141, v141, v49
	v_add_f32_e32 v142, v142, v50
	v_add_f32_e32 v143, v143, v51
	v_add_f32_e32 v140, v140, v44
	v_add_f32_e32 v141, v141, v45
	v_add_f32_e32 v142, v142, v46
	v_add_f32_e32 v143, v143, v47
	v_mul_f32_e32 v140, 0x3e800000, v140
	v_mul_f32_e32 v141, 0x3e800000, v141
	v_mul_f32_e32 v142, 0x3e800000, v142
	v_mul_f32_e32 v143, 0x3e800000, v143
	v_sub_f32_e32 v140, v140, v56
	v_sub_f32_e32 v141, v141, v57
	v_sub_f32_e32 v142, v142, v58
	v_sub_f32_e32 v143, v143, v59
	v_cvt_pk_bf16_f32 v166, v140, v141
	v_cvt_pk_bf16_f32 v167, v142, v143
	s_waitcnt vmcnt(7)
	v_and_b32_e32 v63, 0xffff0000, v61
	v_lshlrev_b32_e32 v62, 16, v61
	v_and_b32_e32 v61, 0xffff0000, v60
	v_lshlrev_b32_e32 v60, 16, v60
	v_add_f32_e32 v140, v60, v56
	v_add_f32_e32 v141, v61, v57
	v_add_f32_e32 v142, v62, v58
	v_add_f32_e32 v143, v63, v59
	v_add_f32_e32 v140, v140, v52
	v_add_f32_e32 v141, v141, v53
	v_add_f32_e32 v142, v142, v54
	v_add_f32_e32 v143, v143, v55
	v_add_f32_e32 v140, v140, v48
	v_add_f32_e32 v141, v141, v49
	v_add_f32_e32 v142, v142, v50
	v_add_f32_e32 v143, v143, v51
	v_mul_f32_e32 v140, 0x3e800000, v140
	v_mul_f32_e32 v141, 0x3e800000, v141
	v_mul_f32_e32 v142, 0x3e800000, v142
	v_mul_f32_e32 v143, 0x3e800000, v143
	v_sub_f32_e32 v140, v140, v60
	v_sub_f32_e32 v141, v141, v61
	v_sub_f32_e32 v142, v142, v62
	v_sub_f32_e32 v143, v143, v63
	v_cvt_pk_bf16_f32 v168, v140, v141
	v_cvt_pk_bf16_f32 v169, v142, v143
	s_waitcnt vmcnt(6)
	v_and_b32_e32 v67, 0xffff0000, v65
	v_lshlrev_b32_e32 v66, 16, v65
	v_and_b32_e32 v65, 0xffff0000, v64
	v_lshlrev_b32_e32 v64, 16, v64
	v_add_f32_e32 v140, v64, v60
	v_add_f32_e32 v141, v65, v61
	v_add_f32_e32 v142, v66, v62
	v_add_f32_e32 v143, v67, v63
	v_add_f32_e32 v140, v140, v56
	v_add_f32_e32 v141, v141, v57
	v_add_f32_e32 v142, v142, v58
	v_add_f32_e32 v143, v143, v59
	v_add_f32_e32 v140, v140, v52
	v_add_f32_e32 v141, v141, v53
	v_add_f32_e32 v142, v142, v54
	v_add_f32_e32 v143, v143, v55
	v_mul_f32_e32 v140, 0x3e800000, v140
	v_mul_f32_e32 v141, 0x3e800000, v141
	v_mul_f32_e32 v142, 0x3e800000, v142
	v_mul_f32_e32 v143, 0x3e800000, v143
	v_sub_f32_e32 v140, v140, v64
	v_sub_f32_e32 v141, v141, v65
	v_sub_f32_e32 v142, v142, v66
	v_sub_f32_e32 v143, v143, v67
	v_cvt_pk_bf16_f32 v170, v140, v141
	v_cvt_pk_bf16_f32 v171, v142, v143
	s_waitcnt vmcnt(5)
	v_and_b32_e32 v71, 0xffff0000, v69
	v_lshlrev_b32_e32 v70, 16, v69
	v_and_b32_e32 v69, 0xffff0000, v68
	v_lshlrev_b32_e32 v68, 16, v68
	v_add_f32_e32 v140, v68, v64
	v_add_f32_e32 v141, v69, v65
	v_add_f32_e32 v142, v70, v66
	v_add_f32_e32 v143, v71, v67
	v_add_f32_e32 v140, v140, v60
	v_add_f32_e32 v141, v141, v61
	v_add_f32_e32 v142, v142, v62
	v_add_f32_e32 v143, v143, v63
	v_add_f32_e32 v140, v140, v56
	v_add_f32_e32 v141, v141, v57
	v_add_f32_e32 v142, v142, v58
	v_add_f32_e32 v143, v143, v59
	v_mul_f32_e32 v140, 0x3e800000, v140
	v_mul_f32_e32 v141, 0x3e800000, v141
	v_mul_f32_e32 v142, 0x3e800000, v142
	v_mul_f32_e32 v143, 0x3e800000, v143
	v_sub_f32_e32 v140, v140, v68
	v_sub_f32_e32 v141, v141, v69
	v_sub_f32_e32 v142, v142, v70
	v_sub_f32_e32 v143, v143, v71
	v_cvt_pk_bf16_f32 v172, v140, v141
	v_cvt_pk_bf16_f32 v173, v142, v143
	s_waitcnt vmcnt(4)
	v_and_b32_e32 v75, 0xffff0000, v73
	v_lshlrev_b32_e32 v74, 16, v73
	v_and_b32_e32 v73, 0xffff0000, v72
	v_lshlrev_b32_e32 v72, 16, v72
	v_add_f32_e32 v140, v72, v68
	v_add_f32_e32 v141, v73, v69
	v_add_f32_e32 v142, v74, v70
	v_add_f32_e32 v143, v75, v71
	v_add_f32_e32 v140, v140, v64
	v_add_f32_e32 v141, v141, v65
	v_add_f32_e32 v142, v142, v66
	v_add_f32_e32 v143, v143, v67
	v_add_f32_e32 v140, v140, v60
	v_add_f32_e32 v141, v141, v61
	v_add_f32_e32 v142, v142, v62
	v_add_f32_e32 v143, v143, v63
	v_mul_f32_e32 v140, 0x3e800000, v140
	v_mul_f32_e32 v141, 0x3e800000, v141
	v_mul_f32_e32 v142, 0x3e800000, v142
	v_mul_f32_e32 v143, 0x3e800000, v143
	v_sub_f32_e32 v140, v140, v72
	v_sub_f32_e32 v141, v141, v73
	v_sub_f32_e32 v142, v142, v74
	v_sub_f32_e32 v143, v143, v75
	v_cvt_pk_bf16_f32 v174, v140, v141
	v_cvt_pk_bf16_f32 v175, v142, v143
	s_waitcnt vmcnt(3)
; template <int WIN>
; DI void pool_elem(const Params& p, int row, int c) {
;     ...
;     if (t >= 2033) {
;       float2 o = {u0, u1};
;       *(float2*)(p.out + O_POOLP + ((size_t)b * 15 + (t - 2033)) * 1024 + c) = o;
;     }
;   } else {
;     const int s = row - NPR;
;     cnt = (float)WIN;
;     const float* sp = p.state_pool + (size_t)s * 15 * 1024 + c;
;     float2 st[15];
; #pragma unroll
;     for (int j = 0; j < 15; ++j) st[j] = *(const float2*)(sp + (size_t)j * 1024);
; #pragma unroll
;     for (int j = 1; j < WIN; ++j) { s0 += st[15 - j].x; s1 += st[15 - j].y; }
;     float* op = p.out + O_POOLS + (size_t)s * 15 * 1024 + c;
; #pragma unroll
;     for (int j = 0; j < 14; ++j) *(float2*)(op + (size_t)j * 1024) = st[j + 1];
;     float2 o = {u0, u1};
;     *(float2*)(op + (size_t)14 * 1024) = o;
;   }
;   *(unsigned*)(p.MIX + (size_t)row * 1024 + c) = pack2(s0 / cnt - u0, s1 / cnt - u1);
	v_and_b32_e32 v79, 0xffff0000, v77
	v_lshlrev_b32_e32 v78, 16, v77
	v_and_b32_e32 v77, 0xffff0000, v76
	v_lshlrev_b32_e32 v76, 16, v76
	v_add_f32_e32 v140, v76, v72
	v_add_f32_e32 v141, v77, v73
	v_add_f32_e32 v142, v78, v74
	v_add_f32_e32 v143, v79, v75
	v_add_f32_e32 v140, v140, v68
	v_add_f32_e32 v141, v141, v69
	v_add_f32_e32 v142, v142, v70
	v_add_f32_e32 v143, v143, v71
	v_add_f32_e32 v140, v140, v64
	v_add_f32_e32 v141, v141, v65
	v_add_f32_e32 v142, v142, v66
	v_add_f32_e32 v143, v143, v67
	v_mul_f32_e32 v140, 0x3e800000, v140
	v_mul_f32_e32 v141, 0x3e800000, v141
	v_mul_f32_e32 v142, 0x3e800000, v142
	v_mul_f32_e32 v143, 0x3e800000, v143
	v_sub_f32_e32 v140, v140, v76
	v_sub_f32_e32 v141, v141, v77
	v_sub_f32_e32 v142, v142, v78
	v_sub_f32_e32 v143, v143, v79
	v_cvt_pk_bf16_f32 v176, v140, v141
	v_cvt_pk_bf16_f32 v177, v142, v143
	s_waitcnt vmcnt(2)
	v_and_b32_e32 v83, 0xffff0000, v81
	v_lshlrev_b32_e32 v82, 16, v81
	v_and_b32_e32 v81, 0xffff0000, v80
	v_lshlrev_b32_e32 v80, 16, v80
	v_add_f32_e32 v140, v80, v76
	v_add_f32_e32 v141, v81, v77
	v_add_f32_e32 v142, v82, v78
	v_add_f32_e32 v143, v83, v79
	v_add_f32_e32 v140, v140, v72
	v_add_f32_e32 v141, v141, v73
	v_add_f32_e32 v142, v142, v74
	v_add_f32_e32 v143, v143, v75
	v_add_f32_e32 v140, v140, v68
	v_add_f32_e32 v141, v141, v69
	v_add_f32_e32 v142, v142, v70
	v_add_f32_e32 v143, v143, v71
	v_mul_f32_e32 v140, 0x3e800000, v140
	v_mul_f32_e32 v141, 0x3e800000, v141
	v_mul_f32_e32 v142, 0x3e800000, v142
	v_mul_f32_e32 v143, 0x3e800000, v143
	v_sub_f32_e32 v140, v140, v80
	v_sub_f32_e32 v141, v141, v81
	v_sub_f32_e32 v142, v142, v82
	v_sub_f32_e32 v143, v143, v83
	v_cvt_pk_bf16_f32 v178, v140, v141
	v_cvt_pk_bf16_f32 v179, v142, v143
	s_waitcnt vmcnt(1)
	v_and_b32_e32 v87, 0xffff0000, v85
	v_lshlrev_b32_e32 v86, 16, v85
	v_and_b32_e32 v85, 0xffff0000, v84
	v_lshlrev_b32_e32 v84, 16, v84
	v_add_f32_e32 v140, v84, v80
	v_add_f32_e32 v141, v85, v81
	v_add_f32_e32 v142, v86, v82
	v_add_f32_e32 v143, v87, v83
	v_add_f32_e32 v140, v140, v76
	v_add_f32_e32 v141, v141, v77
	v_add_f32_e32 v142, v142, v78
	v_add_f32_e32 v143, v143, v79
	v_add_f32_e32 v140, v140, v72
	v_add_f32_e32 v141, v141, v73
	v_add_f32_e32 v142, v142, v74
	v_add_f32_e32 v143, v143, v75
	v_mul_f32_e32 v140, 0x3e800000, v140
	v_mul_f32_e32 v141, 0x3e800000, v141
	v_mul_f32_e32 v142, 0x3e800000, v142
	v_mul_f32_e32 v143, 0x3e800000, v143
	v_sub_f32_e32 v140, v140, v84
	v_sub_f32_e32 v141, v141, v85
	v_sub_f32_e32 v142, v142, v86
	v_sub_f32_e32 v143, v143, v87
	v_cvt_pk_bf16_f32 v180, v140, v141
	v_cvt_pk_bf16_f32 v181, v142, v143
	s_waitcnt vmcnt(0)
	v_and_b32_e32 v91, 0xffff0000, v89
	v_lshlrev_b32_e32 v90, 16, v89
	v_and_b32_e32 v89, 0xffff0000, v88
	v_lshlrev_b32_e32 v88, 16, v88
	v_add_f32_e32 v140, v88, v84
	v_add_f32_e32 v141, v89, v85
	v_add_f32_e32 v142, v90, v86
	v_add_f32_e32 v143, v91, v87
	v_add_f32_e32 v140, v140, v80
	v_add_f32_e32 v141, v141, v81
	v_add_f32_e32 v142, v142, v82
	v_add_f32_e32 v143, v143, v83
	v_add_f32_e32 v140, v140, v76
	v_add_f32_e32 v141, v141, v77
	v_add_f32_e32 v142, v142, v78
	v_add_f32_e32 v143, v143, v79
	v_mul_f32_e32 v140, 0x3e800000, v140
	v_mul_f32_e32 v141, 0x3e800000, v141
	v_mul_f32_e32 v142, 0x3e800000, v142
	v_mul_f32_e32 v143, 0x3e800000, v143
	v_sub_f32_e32 v140, v140, v88
	v_sub_f32_e32 v141, v141, v89
	v_sub_f32_e32 v142, v142, v90
	v_sub_f32_e32 v143, v143, v91
	v_cvt_pk_bf16_f32 v182, v140, v141
	v_cvt_pk_bf16_f32 v183, v142, v143
	global_store_dwordx2 v11, v[152:153], s[24:25] sc1
	s_add_u32 s24, s24, 0x800
	s_addc_u32 s25, s25, 0
	global_store_dwordx2 v11, v[154:155], s[24:25] sc1
	s_add_u32 s24, s24, 0x800
	s_addc_u32 s25, s25, 0
	global_store_dwordx2 v11, v[156:157], s[24:25] sc1
	s_add_u32 s24, s24, 0x800
	s_addc_u32 s25, s25, 0
	global_store_dwordx2 v11, v[158:159], s[24:25] sc1
	s_add_u32 s24, s24, 0x800
	s_addc_u32 s25, s25, 0
	global_store_dwordx2 v11, v[160:161], s[24:25] sc1
	s_add_u32 s24, s24, 0x800
	s_addc_u32 s25, s25, 0
	global_store_dwordx2 v11, v[162:163], s[24:25] sc1
	s_add_u32 s24, s24, 0x800
	s_addc_u32 s25, s25, 0
	global_store_dwordx2 v11, v[164:165], s[24:25] sc1
	s_add_u32 s24, s24, 0x800
	s_addc_u32 s25, s25, 0
	global_store_dwordx2 v11, v[166:167], s[24:25] sc1
	s_add_u32 s24, s24, 0x800
	s_addc_u32 s25, s25, 0
	global_store_dwordx2 v11, v[168:169], s[24:25] sc1
	s_add_u32 s24, s24, 0x800
	s_addc_u32 s25, s25, 0
	global_store_dwordx2 v11, v[170:171], s[24:25] sc1
	s_add_u32 s24, s24, 0x800
	s_addc_u32 s25, s25, 0
	global_store_dwordx2 v11, v[172:173], s[24:25] sc1
	s_add_u32 s24, s24, 0x800
	s_addc_u32 s25, s25, 0
	global_store_dwordx2 v11, v[174:175], s[24:25] sc1
	s_add_u32 s24, s24, 0x800
	s_addc_u32 s25, s25, 0
	global_store_dwordx2 v11, v[176:177], s[24:25] sc1
	s_add_u32 s24, s24, 0x800
	s_addc_u32 s25, s25, 0
	global_store_dwordx2 v11, v[178:179], s[24:25] sc1
	s_add_u32 s24, s24, 0x800
	s_addc_u32 s25, s25, 0
	global_store_dwordx2 v11, v[180:181], s[24:25] sc1
	s_add_u32 s24, s24, 0x800
	s_addc_u32 s25, s25, 0
	global_store_dwordx2 v11, v[182:183], s[24:25] sc1
	s_add_u32 s24, s24, 0x800
	s_addc_u32 s25, s25, 0
	s_cmp_eq_u32 s18, 127
	s_cbranch_scc0 .Lp13f_next
	s_mul_i32 s26, s17, 61440
	s_add_u32 s26, s26, 0x431c000
	s_add_u32 s22, s12, s26
	s_addc_u32 s23, s13, 0
	global_store_dwordx4 v12, v[32:35], s[22:23] sc1
	s_add_u32 s22, s22, 0x1000
	s_addc_u32 s23, s23, 0
	global_store_dwordx4 v12, v[36:39], s[22:23] sc1
	s_add_u32 s22, s22, 0x1000
	s_addc_u32 s23, s23, 0
	global_store_dwordx4 v12, v[40:43], s[22:23] sc1
	s_add_u32 s22, s22, 0x1000
	s_addc_u32 s23, s23, 0
	global_store_dwordx4 v12, v[44:47], s[22:23] sc1
	s_add_u32 s22, s22, 0x1000
	s_addc_u32 s23, s23, 0
	global_store_dwordx4 v12, v[48:51], s[22:23] sc1
	s_add_u32 s22, s22, 0x1000
	s_addc_u32 s23, s23, 0
	global_store_dwordx4 v12, v[52:55], s[22:23] sc1
	s_add_u32 s22, s22, 0x1000
	s_addc_u32 s23, s23, 0
	global_store_dwordx4 v12, v[56:59], s[22:23] sc1
	s_add_u32 s22, s22, 0x1000
	s_addc_u32 s23, s23, 0
	global_store_dwordx4 v12, v[60:63], s[22:23] sc1
	s_add_u32 s22, s22, 0x1000
	s_addc_u32 s23, s23, 0
	global_store_dwordx4 v12, v[64:67], s[22:23] sc1
	s_add_u32 s22, s22, 0x1000
	s_addc_u32 s23, s23, 0
	global_store_dwordx4 v12, v[68:71], s[22:23] sc1
	s_add_u32 s22, s22, 0x1000
	s_addc_u32 s23, s23, 0
	global_store_dwordx4 v12, v[72:75], s[22:23] sc1
	s_add_u32 s22, s22, 0x1000
	s_addc_u32 s23, s23, 0
	global_store_dwordx4 v12, v[76:79], s[22:23] sc1
	s_add_u32 s22, s22, 0x1000
	s_addc_u32 s23, s23, 0
	global_store_dwordx4 v12, v[80:83], s[22:23] sc1
	s_add_u32 s22, s22, 0x1000
	s_addc_u32 s23, s23, 0
	global_store_dwordx4 v12, v[84:87], s[22:23] sc1
	s_add_u32 s22, s22, 0x1000
	s_addc_u32 s23, s23, 0
	global_store_dwordx4 v12, v[88:91], s[22:23] sc1
	s_add_u32 s22, s22, 0x1000
	s_addc_u32 s23, s23, 0
	s_branch .Lp13f_next
; DI float bflo(unsigned u) { return __uint_as_float(u << 16); }
; DI float bfhi(unsigned u) { return __uint_as_float(u & 0xffff0000u); }
; template <int WIN>
; DI void pool_elem(const Params& p, int row, int c) {
;     ...
;   unsigned uu = *(const unsigned*)(P2 + (size_t)row * 2048 + c);
;   const float u0 = bflo(uu), u1 = bfhi(uu);
;   float s0 = u0, s1 = u1, cnt;
;   if (row < NPR) {
;     const int t = row & 2047, b = row >> 11;
;     if (t >= WIN - 1) {
;       cnt = (float)WIN;
;       unsigned w[WIN - 1];
; #pragma unroll
;       for (int j = 1; j < WIN; ++j) w[j - 1] = *(const unsigned*)(P2 + (size_t)(row - j) * 2048 + c);
; #pragma unroll
;       for (int j = 1; j < WIN; ++j) { s0 += bflo(w[j - 1]); s1 += bfhi(w[j - 1]); }
;     ...
;   *(unsigned*)(p.MIX + (size_t)row * 1024 + c) = pack2(s0 / cnt - u0, s1 / cnt - u1);
.Lp13f_w2:
	s_sub_u32 s26, s20, 7
	s_lshl_b32 s27, s26, 12
	s_lshr_b32 s28, s26, 20
	s_add_u32 s22, s8, s27
	s_addc_u32 s23, s9, s28
	global_load_dwordx2 v[16:17], v11, s[22:23]
	s_add_u32 s22, s22, 0x1000
	s_addc_u32 s23, s23, 0
	global_load_dwordx2 v[20:21], v11, s[22:23]
	s_add_u32 s22, s22, 0x1000
	s_addc_u32 s23, s23, 0
	global_load_dwordx2 v[24:25], v11, s[22:23]
	s_add_u32 s22, s22, 0x1000
	s_addc_u32 s23, s23, 0
	global_load_dwordx2 v[28:29], v11, s[22:23]
	s_add_u32 s22, s22, 0x1000
	s_addc_u32 s23, s23, 0
	global_load_dwordx2 v[32:33], v11, s[22:23]
	s_add_u32 s22, s22, 0x1000
	s_addc_u32 s23, s23, 0
	global_load_dwordx2 v[36:37], v11, s[22:23]
	s_add_u32 s22, s22, 0x1000
	s_addc_u32 s23, s23, 0
	global_load_dwordx2 v[40:41], v11, s[22:23]
	s_add_u32 s22, s22, 0x1000
	s_addc_u32 s23, s23, 0
	global_load_dwordx2 v[44:45], v11, s[22:23]
	s_add_u32 s22, s22, 0x1000
	s_addc_u32 s23, s23, 0
	global_load_dwordx2 v[48:49], v11, s[22:23]
	s_add_u32 s22, s22, 0x1000
	s_addc_u32 s23, s23, 0
	global_load_dwordx2 v[52:53], v11, s[22:23]
	s_add_u32 s22, s22, 0x1000
	s_addc_u32 s23, s23, 0
	global_load_dwordx2 v[56:57], v11, s[22:23]
	s_add_u32 s22, s22, 0x1000
	s_addc_u32 s23, s23, 0
	global_load_dwordx2 v[60:61], v11, s[22:23]
	s_add_u32 s22, s22, 0x1000
	s_addc_u32 s23, s23, 0
	global_load_dwordx2 v[64:65], v11, s[22:23]
	s_add_u32 s22, s22, 0x1000
	s_addc_u32 s23, s23, 0
	global_load_dwordx2 v[68:69], v11, s[22:23]
	s_add_u32 s22, s22, 0x1000
	s_addc_u32 s23, s23, 0
	global_load_dwordx2 v[72:73], v11, s[22:23]
	s_add_u32 s22, s22, 0x1000
	s_addc_u32 s23, s23, 0
	global_load_dwordx2 v[76:77], v11, s[22:23]
	s_add_u32 s22, s22, 0x1000
	s_addc_u32 s23, s23, 0
	global_load_dwordx2 v[80:81], v11, s[22:23]
	s_add_u32 s22, s22, 0x1000
	s_addc_u32 s23, s23, 0
	global_load_dwordx2 v[84:85], v11, s[22:23]
	s_add_u32 s22, s22, 0x1000
	s_addc_u32 s23, s23, 0
	global_load_dwordx2 v[88:89], v11, s[22:23]
	s_add_u32 s22, s22, 0x1000
	s_addc_u32 s23, s23, 0
	global_load_dwordx2 v[92:93], v11, s[22:23]
	s_add_u32 s22, s22, 0x1000
	s_addc_u32 s23, s23, 0
	global_load_dwordx2 v[96:97], v11, s[22:23]
	s_add_u32 s22, s22, 0x1000
	s_addc_u32 s23, s23, 0
	global_load_dwordx2 v[100:101], v11, s[22:23]
	s_add_u32 s22, s22, 0x1000
	s_addc_u32 s23, s23, 0
	global_load_dwordx2 v[104:105], v11, s[22:23]
	s_add_u32 s22, s22, 0x1000
	s_addc_u32 s23, s23, 0
	s_waitcnt vmcnt(15)
	v_and_b32_e32 v19, 0xffff0000, v17
	v_lshlrev_b32_e32 v18, 16, v17
	v_and_b32_e32 v17, 0xffff0000, v16
	v_lshlrev_b32_e32 v16, 16, v16
	v_and_b32_e32 v23, 0xffff0000, v21
	v_lshlrev_b32_e32 v22, 16, v21
	v_and_b32_e32 v21, 0xffff0000, v20
	v_lshlrev_b32_e32 v20, 16, v20
	v_and_b32_e32 v27, 0xffff0000, v25
	v_lshlrev_b32_e32 v26, 16, v25
	v_and_b32_e32 v25, 0xffff0000, v24
	v_lshlrev_b32_e32 v24, 16, v24
	v_and_b32_e32 v31, 0xffff0000, v29
	v_lshlrev_b32_e32 v30, 16, v29
	v_and_b32_e32 v29, 0xffff0000, v28
	v_lshlrev_b32_e32 v28, 16, v28
	v_and_b32_e32 v35, 0xffff0000, v33
	v_lshlrev_b32_e32 v34, 16, v33
	v_and_b32_e32 v33, 0xffff0000, v32
	v_lshlrev_b32_e32 v32, 16, v32
	v_and_b32_e32 v39, 0xffff0000, v37
	v_lshlrev_b32_e32 v38, 16, v37
	v_and_b32_e32 v37, 0xffff0000, v36
	v_lshlrev_b32_e32 v36, 16, v36
	v_and_b32_e32 v43, 0xffff0000, v41
	v_lshlrev_b32_e32 v42, 16, v41
	v_and_b32_e32 v41, 0xffff0000, v40
	v_lshlrev_b32_e32 v40, 16, v40
	v_and_b32_e32 v47, 0xffff0000, v45
	v_lshlrev_b32_e32 v46, 16, v45
	v_and_b32_e32 v45, 0xffff0000, v44
	v_lshlrev_b32_e32 v44, 16, v44
	v_add_f32_e32 v140, v44, v40
	v_add_f32_e32 v141, v45, v41
	v_add_f32_e32 v142, v46, v42
	v_add_f32_e32 v143, v47, v43
	v_add_f32_e32 v140, v140, v36
	v_add_f32_e32 v141, v141, v37
	v_add_f32_e32 v142, v142, v38
	v_add_f32_e32 v143, v143, v39
	v_add_f32_e32 v140, v140, v32
	v_add_f32_e32 v141, v141, v33
	v_add_f32_e32 v142, v142, v34
	v_add_f32_e32 v143, v143, v35
	v_add_f32_e32 v140, v140, v28
	v_add_f32_e32 v141, v141, v29
	v_add_f32_e32 v142, v142, v30
	v_add_f32_e32 v143, v143, v31
	v_add_f32_e32 v140, v140, v24
	v_add_f32_e32 v141, v141, v25
	v_add_f32_e32 v142, v142, v26
	v_add_f32_e32 v143, v143, v27
	v_add_f32_e32 v140, v140, v20
	v_add_f32_e32 v141, v141, v21
	v_add_f32_e32 v142, v142, v22
	v_add_f32_e32 v143, v143, v23
	v_add_f32_e32 v140, v140, v16
	v_add_f32_e32 v141, v141, v17
	v_add_f32_e32 v142, v142, v18
	v_add_f32_e32 v143, v143, v19
	v_mul_f32_e32 v140, 0x3e000000, v140
	v_mul_f32_e32 v141, 0x3e000000, v141
	v_mul_f32_e32 v142, 0x3e000000, v142
	v_mul_f32_e32 v143, 0x3e000000, v143
	v_sub_f32_e32 v140, v140, v44
	v_sub_f32_e32 v141, v141, v45
	v_sub_f32_e32 v142, v142, v46
	v_sub_f32_e32 v143, v143, v47
	v_cvt_pk_bf16_f32 v152, v140, v141
	v_cvt_pk_bf16_f32 v153, v142, v143
	s_waitcnt vmcnt(14)
	v_and_b32_e32 v51, 0xffff0000, v49
	v_lshlrev_b32_e32 v50, 16, v49
	v_and_b32_e32 v49, 0xffff0000, v48
	v_lshlrev_b32_e32 v48, 16, v48
	v_add_f32_e32 v140, v48, v44
	v_add_f32_e32 v141, v49, v45
	v_add_f32_e32 v142, v50, v46
	v_add_f32_e32 v143, v51, v47
	v_add_f32_e32 v140, v140, v40
	v_add_f32_e32 v141, v141, v41
	v_add_f32_e32 v142, v142, v42
	v_add_f32_e32 v143, v143, v43
	v_add_f32_e32 v140, v140, v36
	v_add_f32_e32 v141, v141, v37
	v_add_f32_e32 v142, v142, v38
	v_add_f32_e32 v143, v143, v39
	v_add_f32_e32 v140, v140, v32
	v_add_f32_e32 v141, v141, v33
	v_add_f32_e32 v142, v142, v34
	v_add_f32_e32 v143, v143, v35
	v_add_f32_e32 v140, v140, v28
	v_add_f32_e32 v141, v141, v29
	v_add_f32_e32 v142, v142, v30
	v_add_f32_e32 v143, v143, v31
	v_add_f32_e32 v140, v140, v24
	v_add_f32_e32 v141, v141, v25
	v_add_f32_e32 v142, v142, v26
	v_add_f32_e32 v143, v143, v27
	v_add_f32_e32 v140, v140, v20
	v_add_f32_e32 v141, v141, v21
	v_add_f32_e32 v142, v142, v22
	v_add_f32_e32 v143, v143, v23
	v_mul_f32_e32 v140, 0x3e000000, v140
	v_mul_f32_e32 v141, 0x3e000000, v141
	v_mul_f32_e32 v142, 0x3e000000, v142
	v_mul_f32_e32 v143, 0x3e000000, v143
	v_sub_f32_e32 v140, v140, v48
	v_sub_f32_e32 v141, v141, v49
	v_sub_f32_e32 v142, v142, v50
	v_sub_f32_e32 v143, v143, v51
	v_cvt_pk_bf16_f32 v154, v140, v141
	v_cvt_pk_bf16_f32 v155, v142, v143
	s_waitcnt vmcnt(13)
; DI float bflo(unsigned u) { return __uint_as_float(u << 16); }
; DI float bfhi(unsigned u) { return __uint_as_float(u & 0xffff0000u); }
; template <int WIN>
; DI void pool_elem(const Params& p, int row, int c) {
;     ...
;       for (int j = 1; j < WIN; ++j) w[j - 1] = *(const unsigned*)(P2 + (size_t)(row - j) * 2048 + c);
; #pragma unroll
;       for (int j = 1; j < WIN; ++j) { s0 += bflo(w[j - 1]); s1 += bfhi(w[j - 1]); }
;     ...
;   *(unsigned*)(p.MIX + (size_t)row * 1024 + c) = pack2(s0 / cnt - u0, s1 / cnt - u1);
	v_and_b32_e32 v55, 0xffff0000, v53
	v_lshlrev_b32_e32 v54, 16, v53
	v_and_b32_e32 v53, 0xffff0000, v52
	v_lshlrev_b32_e32 v52, 16, v52
	v_add_f32_e32 v140, v52, v48
	v_add_f32_e32 v141, v53, v49
	v_add_f32_e32 v142, v54, v50
	v_add_f32_e32 v143, v55, v51
	v_add_f32_e32 v140, v140, v44
	v_add_f32_e32 v141, v141, v45
	v_add_f32_e32 v142, v142, v46
	v_add_f32_e32 v143, v143, v47
	v_add_f32_e32 v140, v140, v40
	v_add_f32_e32 v141, v141, v41
	v_add_f32_e32 v142, v142, v42
	v_add_f32_e32 v143, v143, v43
	v_add_f32_e32 v140, v140, v36
	v_add_f32_e32 v141, v141, v37
	v_add_f32_e32 v142, v142, v38
	v_add_f32_e32 v143, v143, v39
	v_add_f32_e32 v140, v140, v32
	v_add_f32_e32 v141, v141, v33
	v_add_f32_e32 v142, v142, v34
	v_add_f32_e32 v143, v143, v35
	v_add_f32_e32 v140, v140, v28
	v_add_f32_e32 v141, v141, v29
	v_add_f32_e32 v142, v142, v30
	v_add_f32_e32 v143, v143, v31
	v_add_f32_e32 v140, v140, v24
	v_add_f32_e32 v141, v141, v25
	v_add_f32_e32 v142, v142, v26
	v_add_f32_e32 v143, v143, v27
	v_mul_f32_e32 v140, 0x3e000000, v140
	v_mul_f32_e32 v141, 0x3e000000, v141
	v_mul_f32_e32 v142, 0x3e000000, v142
	v_mul_f32_e32 v143, 0x3e000000, v143
	v_sub_f32_e32 v140, v140, v52
	v_sub_f32_e32 v141, v141, v53
	v_sub_f32_e32 v142, v142, v54
	v_sub_f32_e32 v143, v143, v55
	v_cvt_pk_bf16_f32 v156, v140, v141
	v_cvt_pk_bf16_f32 v157, v142, v143
	s_waitcnt vmcnt(12)
	v_and_b32_e32 v59, 0xffff0000, v57
	v_lshlrev_b32_e32 v58, 16, v57
	v_and_b32_e32 v57, 0xffff0000, v56
	v_lshlrev_b32_e32 v56, 16, v56
	v_add_f32_e32 v140, v56, v52
	v_add_f32_e32 v141, v57, v53
	v_add_f32_e32 v142, v58, v54
	v_add_f32_e32 v143, v59, v55
	v_add_f32_e32 v140, v140, v48
	v_add_f32_e32 v141, v141, v49
	v_add_f32_e32 v142, v142, v50
	v_add_f32_e32 v143, v143, v51
	v_add_f32_e32 v140, v140, v44
	v_add_f32_e32 v141, v141, v45
	v_add_f32_e32 v142, v142, v46
	v_add_f32_e32 v143, v143, v47
	v_add_f32_e32 v140, v140, v40
	v_add_f32_e32 v141, v141, v41
	v_add_f32_e32 v142, v142, v42
	v_add_f32_e32 v143, v143, v43
	v_add_f32_e32 v140, v140, v36
	v_add_f32_e32 v141, v141, v37
	v_add_f32_e32 v142, v142, v38
	v_add_f32_e32 v143, v143, v39
	v_add_f32_e32 v140, v140, v32
	v_add_f32_e32 v141, v141, v33
	v_add_f32_e32 v142, v142, v34
	v_add_f32_e32 v143, v143, v35
	v_add_f32_e32 v140, v140, v28
	v_add_f32_e32 v141, v141, v29
	v_add_f32_e32 v142, v142, v30
	v_add_f32_e32 v143, v143, v31
	v_mul_f32_e32 v140, 0x3e000000, v140
	v_mul_f32_e32 v141, 0x3e000000, v141
	v_mul_f32_e32 v142, 0x3e000000, v142
	v_mul_f32_e32 v143, 0x3e000000, v143
	v_sub_f32_e32 v140, v140, v56
	v_sub_f32_e32 v141, v141, v57
	v_sub_f32_e32 v142, v142, v58
	v_sub_f32_e32 v143, v143, v59
	v_cvt_pk_bf16_f32 v158, v140, v141
	v_cvt_pk_bf16_f32 v159, v142, v143
	s_waitcnt vmcnt(11)
	v_and_b32_e32 v63, 0xffff0000, v61
	v_lshlrev_b32_e32 v62, 16, v61
	v_and_b32_e32 v61, 0xffff0000, v60
	v_lshlrev_b32_e32 v60, 16, v60
	v_add_f32_e32 v140, v60, v56
	v_add_f32_e32 v141, v61, v57
	v_add_f32_e32 v142, v62, v58
	v_add_f32_e32 v143, v63, v59
	v_add_f32_e32 v140, v140, v52
	v_add_f32_e32 v141, v141, v53
	v_add_f32_e32 v142, v142, v54
	v_add_f32_e32 v143, v143, v55
	v_add_f32_e32 v140, v140, v48
	v_add_f32_e32 v141, v141, v49
	v_add_f32_e32 v142, v142, v50
	v_add_f32_e32 v143, v143, v51
	v_add_f32_e32 v140, v140, v44
	v_add_f32_e32 v141, v141, v45
	v_add_f32_e32 v142, v142, v46
	v_add_f32_e32 v143, v143, v47
	v_add_f32_e32 v140, v140, v40
	v_add_f32_e32 v141, v141, v41
	v_add_f32_e32 v142, v142, v42
	v_add_f32_e32 v143, v143, v43
	v_add_f32_e32 v140, v140, v36
	v_add_f32_e32 v141, v141, v37
	v_add_f32_e32 v142, v142, v38
	v_add_f32_e32 v143, v143, v39
	v_add_f32_e32 v140, v140, v32
	v_add_f32_e32 v141, v141, v33
	v_add_f32_e32 v142, v142, v34
	v_add_f32_e32 v143, v143, v35
	v_mul_f32_e32 v140, 0x3e000000, v140
	v_mul_f32_e32 v141, 0x3e000000, v141
	v_mul_f32_e32 v142, 0x3e000000, v142
	v_mul_f32_e32 v143, 0x3e000000, v143
	v_sub_f32_e32 v140, v140, v60
	v_sub_f32_e32 v141, v141, v61
	v_sub_f32_e32 v142, v142, v62
	v_sub_f32_e32 v143, v143, v63
	v_cvt_pk_bf16_f32 v160, v140, v141
	v_cvt_pk_bf16_f32 v161, v142, v143
	s_waitcnt vmcnt(10)
	v_and_b32_e32 v67, 0xffff0000, v65
	v_lshlrev_b32_e32 v66, 16, v65
	v_and_b32_e32 v65, 0xffff0000, v64
	v_lshlrev_b32_e32 v64, 16, v64
	v_add_f32_e32 v140, v64, v60
	v_add_f32_e32 v141, v65, v61
	v_add_f32_e32 v142, v66, v62
	v_add_f32_e32 v143, v67, v63
	v_add_f32_e32 v140, v140, v56
	v_add_f32_e32 v141, v141, v57
	v_add_f32_e32 v142, v142, v58
	v_add_f32_e32 v143, v143, v59
	v_add_f32_e32 v140, v140, v52
	v_add_f32_e32 v141, v141, v53
	v_add_f32_e32 v142, v142, v54
	v_add_f32_e32 v143, v143, v55
	v_add_f32_e32 v140, v140, v48
	v_add_f32_e32 v141, v141, v49
	v_add_f32_e32 v142, v142, v50
	v_add_f32_e32 v143, v143, v51
	v_add_f32_e32 v140, v140, v44
	v_add_f32_e32 v141, v141, v45
	v_add_f32_e32 v142, v142, v46
	v_add_f32_e32 v143, v143, v47
	v_add_f32_e32 v140, v140, v40
	v_add_f32_e32 v141, v141, v41
	v_add_f32_e32 v142, v142, v42
	v_add_f32_e32 v143, v143, v43
	v_add_f32_e32 v140, v140, v36
	v_add_f32_e32 v141, v141, v37
	v_add_f32_e32 v142, v142, v38
	v_add_f32_e32 v143, v143, v39
	v_mul_f32_e32 v140, 0x3e000000, v140
	v_mul_f32_e32 v141, 0x3e000000, v141
	v_mul_f32_e32 v142, 0x3e000000, v142
	v_mul_f32_e32 v143, 0x3e000000, v143
	v_sub_f32_e32 v140, v140, v64
	v_sub_f32_e32 v141, v141, v65
	v_sub_f32_e32 v142, v142, v66
	v_sub_f32_e32 v143, v143, v67
	v_cvt_pk_bf16_f32 v162, v140, v141
	v_cvt_pk_bf16_f32 v163, v142, v143
	s_waitcnt vmcnt(9)
; DI float bflo(unsigned u) { return __uint_as_float(u << 16); }
; DI float bfhi(unsigned u) { return __uint_as_float(u & 0xffff0000u); }
; template <int WIN>
; DI void pool_elem(const Params& p, int row, int c) {
;     ...
;       for (int j = 1; j < WIN; ++j) w[j - 1] = *(const unsigned*)(P2 + (size_t)(row - j) * 2048 + c);
; #pragma unroll
;       for (int j = 1; j < WIN; ++j) { s0 += bflo(w[j - 1]); s1 += bfhi(w[j - 1]); }
;     ...
;   *(unsigned*)(p.MIX + (size_t)row * 1024 + c) = pack2(s0 / cnt - u0, s1 / cnt - u1);
	v_and_b32_e32 v71, 0xffff0000, v69
	v_lshlrev_b32_e32 v70, 16, v69
	v_and_b32_e32 v69, 0xffff0000, v68
	v_lshlrev_b32_e32 v68, 16, v68
	v_add_f32_e32 v140, v68, v64
	v_add_f32_e32 v141, v69, v65
	v_add_f32_e32 v142, v70, v66
	v_add_f32_e32 v143, v71, v67
	v_add_f32_e32 v140, v140, v60
	v_add_f32_e32 v141, v141, v61
	v_add_f32_e32 v142, v142, v62
	v_add_f32_e32 v143, v143, v63
	v_add_f32_e32 v140, v140, v56
	v_add_f32_e32 v141, v141, v57
	v_add_f32_e32 v142, v142, v58
	v_add_f32_e32 v143, v143, v59
	v_add_f32_e32 v140, v140, v52
	v_add_f32_e32 v141, v141, v53
	v_add_f32_e32 v142, v142, v54
	v_add_f32_e32 v143, v143, v55
	v_add_f32_e32 v140, v140, v48
	v_add_f32_e32 v141, v141, v49
	v_add_f32_e32 v142, v142, v50
	v_add_f32_e32 v143, v143, v51
	v_add_f32_e32 v140, v140, v44
	v_add_f32_e32 v141, v141, v45
	v_add_f32_e32 v142, v142, v46
	v_add_f32_e32 v143, v143, v47
	v_add_f32_e32 v140, v140, v40
	v_add_f32_e32 v141, v141, v41
	v_add_f32_e32 v142, v142, v42
	v_add_f32_e32 v143, v143, v43
	v_mul_f32_e32 v140, 0x3e000000, v140
	v_mul_f32_e32 v141, 0x3e000000, v141
	v_mul_f32_e32 v142, 0x3e000000, v142
	v_mul_f32_e32 v143, 0x3e000000, v143
	v_sub_f32_e32 v140, v140, v68
	v_sub_f32_e32 v141, v141, v69
	v_sub_f32_e32 v142, v142, v70
	v_sub_f32_e32 v143, v143, v71
	v_cvt_pk_bf16_f32 v164, v140, v141
	v_cvt_pk_bf16_f32 v165, v142, v143
	s_waitcnt vmcnt(8)
	v_and_b32_e32 v75, 0xffff0000, v73
	v_lshlrev_b32_e32 v74, 16, v73
	v_and_b32_e32 v73, 0xffff0000, v72
	v_lshlrev_b32_e32 v72, 16, v72
	v_add_f32_e32 v140, v72, v68
	v_add_f32_e32 v141, v73, v69
	v_add_f32_e32 v142, v74, v70
	v_add_f32_e32 v143, v75, v71
	v_add_f32_e32 v140, v140, v64
	v_add_f32_e32 v141, v141, v65
	v_add_f32_e32 v142, v142, v66
	v_add_f32_e32 v143, v143, v67
	v_add_f32_e32 v140, v140, v60
	v_add_f32_e32 v141, v141, v61
	v_add_f32_e32 v142, v142, v62
	v_add_f32_e32 v143, v143, v63
	v_add_f32_e32 v140, v140, v56
	v_add_f32_e32 v141, v141, v57
	v_add_f32_e32 v142, v142, v58
	v_add_f32_e32 v143, v143, v59
	v_add_f32_e32 v140, v140, v52
	v_add_f32_e32 v141, v141, v53
	v_add_f32_e32 v142, v142, v54
	v_add_f32_e32 v143, v143, v55
	v_add_f32_e32 v140, v140, v48
	v_add_f32_e32 v141, v141, v49
	v_add_f32_e32 v142, v142, v50
	v_add_f32_e32 v143, v143, v51
	v_add_f32_e32 v140, v140, v44
	v_add_f32_e32 v141, v141, v45
	v_add_f32_e32 v142, v142, v46
	v_add_f32_e32 v143, v143, v47
	v_mul_f32_e32 v140, 0x3e000000, v140
	v_mul_f32_e32 v141, 0x3e000000, v141
	v_mul_f32_e32 v142, 0x3e000000, v142
	v_mul_f32_e32 v143, 0x3e000000, v143
	v_sub_f32_e32 v140, v140, v72
	v_sub_f32_e32 v141, v141, v73
	v_sub_f32_e32 v142, v142, v74
	v_sub_f32_e32 v143, v143, v75
	v_cvt_pk_bf16_f32 v166, v140, v141
	v_cvt_pk_bf16_f32 v167, v142, v143
	s_waitcnt vmcnt(7)
	v_and_b32_e32 v79, 0xffff0000, v77
	v_lshlrev_b32_e32 v78, 16, v77
	v_and_b32_e32 v77, 0xffff0000, v76
	v_lshlrev_b32_e32 v76, 16, v76
	v_add_f32_e32 v140, v76, v72
	v_add_f32_e32 v141, v77, v73
	v_add_f32_e32 v142, v78, v74
	v_add_f32_e32 v143, v79, v75
	v_add_f32_e32 v140, v140, v68
	v_add_f32_e32 v141, v141, v69
	v_add_f32_e32 v142, v142, v70
	v_add_f32_e32 v143, v143, v71
	v_add_f32_e32 v140, v140, v64
	v_add_f32_e32 v141, v141, v65
	v_add_f32_e32 v142, v142, v66
	v_add_f32_e32 v143, v143, v67
	v_add_f32_e32 v140, v140, v60
	v_add_f32_e32 v141, v141, v61
	v_add_f32_e32 v142, v142, v62
	v_add_f32_e32 v143, v143, v63
	v_add_f32_e32 v140, v140, v56
	v_add_f32_e32 v141, v141, v57
	v_add_f32_e32 v142, v142, v58
	v_add_f32_e32 v143, v143, v59
	v_add_f32_e32 v140, v140, v52
	v_add_f32_e32 v141, v141, v53
	v_add_f32_e32 v142, v142, v54
	v_add_f32_e32 v143, v143, v55
	v_add_f32_e32 v140, v140, v48
	v_add_f32_e32 v141, v141, v49
	v_add_f32_e32 v142, v142, v50
	v_add_f32_e32 v143, v143, v51
	v_mul_f32_e32 v140, 0x3e000000, v140
	v_mul_f32_e32 v141, 0x3e000000, v141
	v_mul_f32_e32 v142, 0x3e000000, v142
	v_mul_f32_e32 v143, 0x3e000000, v143
	v_sub_f32_e32 v140, v140, v76
	v_sub_f32_e32 v141, v141, v77
	v_sub_f32_e32 v142, v142, v78
	v_sub_f32_e32 v143, v143, v79
	v_cvt_pk_bf16_f32 v168, v140, v141
	v_cvt_pk_bf16_f32 v169, v142, v143
	s_waitcnt vmcnt(6)
	v_and_b32_e32 v83, 0xffff0000, v81
	v_lshlrev_b32_e32 v82, 16, v81
	v_and_b32_e32 v81, 0xffff0000, v80
	v_lshlrev_b32_e32 v80, 16, v80
	v_add_f32_e32 v140, v80, v76
	v_add_f32_e32 v141, v81, v77
	v_add_f32_e32 v142, v82, v78
	v_add_f32_e32 v143, v83, v79
	v_add_f32_e32 v140, v140, v72
	v_add_f32_e32 v141, v141, v73
	v_add_f32_e32 v142, v142, v74
	v_add_f32_e32 v143, v143, v75
	v_add_f32_e32 v140, v140, v68
	v_add_f32_e32 v141, v141, v69
	v_add_f32_e32 v142, v142, v70
	v_add_f32_e32 v143, v143, v71
	v_add_f32_e32 v140, v140, v64
	v_add_f32_e32 v141, v141, v65
	v_add_f32_e32 v142, v142, v66
	v_add_f32_e32 v143, v143, v67
	v_add_f32_e32 v140, v140, v60
	v_add_f32_e32 v141, v141, v61
	v_add_f32_e32 v142, v142, v62
	v_add_f32_e32 v143, v143, v63
	v_add_f32_e32 v140, v140, v56
	v_add_f32_e32 v141, v141, v57
	v_add_f32_e32 v142, v142, v58
	v_add_f32_e32 v143, v143, v59
	v_add_f32_e32 v140, v140, v52
	v_add_f32_e32 v141, v141, v53
	v_add_f32_e32 v142, v142, v54
	v_add_f32_e32 v143, v143, v55
	v_mul_f32_e32 v140, 0x3e000000, v140
	v_mul_f32_e32 v141, 0x3e000000, v141
	v_mul_f32_e32 v142, 0x3e000000, v142
	v_mul_f32_e32 v143, 0x3e000000, v143
	v_sub_f32_e32 v140, v140, v80
	v_sub_f32_e32 v141, v141, v81
	v_sub_f32_e32 v142, v142, v82
	v_sub_f32_e32 v143, v143, v83
	v_cvt_pk_bf16_f32 v170, v140, v141
	v_cvt_pk_bf16_f32 v171, v142, v143
	s_waitcnt vmcnt(5)
; DI float bflo(unsigned u) { return __uint_as_float(u << 16); }
; DI float bfhi(unsigned u) { return __uint_as_float(u & 0xffff0000u); }
; template <int WIN>
; DI void pool_elem(const Params& p, int row, int c) {
;     ...
;       for (int j = 1; j < WIN; ++j) w[j - 1] = *(const unsigned*)(P2 + (size_t)(row - j) * 2048 + c);
; #pragma unroll
;       for (int j = 1; j < WIN; ++j) { s0 += bflo(w[j - 1]); s1 += bfhi(w[j - 1]); }
;     ...
;   *(unsigned*)(p.MIX + (size_t)row * 1024 + c) = pack2(s0 / cnt - u0, s1 / cnt - u1);
	v_and_b32_e32 v87, 0xffff0000, v85
	v_lshlrev_b32_e32 v86, 16, v85
	v_and_b32_e32 v85, 0xffff0000, v84
	v_lshlrev_b32_e32 v84, 16, v84
	v_add_f32_e32 v140, v84, v80
	v_add_f32_e32 v141, v85, v81
	v_add_f32_e32 v142, v86, v82
	v_add_f32_e32 v143, v87, v83
	v_add_f32_e32 v140, v140, v76
	v_add_f32_e32 v141, v141, v77
	v_add_f32_e32 v142, v142, v78
	v_add_f32_e32 v143, v143, v79
	v_add_f32_e32 v140, v140, v72
	v_add_f32_e32 v141, v141, v73
	v_add_f32_e32 v142, v142, v74
	v_add_f32_e32 v143, v143, v75
	v_add_f32_e32 v140, v140, v68
	v_add_f32_e32 v141, v141, v69
	v_add_f32_e32 v142, v142, v70
	v_add_f32_e32 v143, v143, v71
	v_add_f32_e32 v140, v140, v64
	v_add_f32_e32 v141, v141, v65
	v_add_f32_e32 v142, v142, v66
	v_add_f32_e32 v143, v143, v67
	v_add_f32_e32 v140, v140, v60
	v_add_f32_e32 v141, v141, v61
	v_add_f32_e32 v142, v142, v62
	v_add_f32_e32 v143, v143, v63
	v_add_f32_e32 v140, v140, v56
	v_add_f32_e32 v141, v141, v57
	v_add_f32_e32 v142, v142, v58
	v_add_f32_e32 v143, v143, v59
	v_mul_f32_e32 v140, 0x3e000000, v140
	v_mul_f32_e32 v141, 0x3e000000, v141
	v_mul_f32_e32 v142, 0x3e000000, v142
	v_mul_f32_e32 v143, 0x3e000000, v143
	v_sub_f32_e32 v140, v140, v84
	v_sub_f32_e32 v141, v141, v85
	v_sub_f32_e32 v142, v142, v86
	v_sub_f32_e32 v143, v143, v87
	v_cvt_pk_bf16_f32 v172, v140, v141
	v_cvt_pk_bf16_f32 v173, v142, v143
	s_waitcnt vmcnt(4)
	v_and_b32_e32 v91, 0xffff0000, v89
	v_lshlrev_b32_e32 v90, 16, v89
	v_and_b32_e32 v89, 0xffff0000, v88
	v_lshlrev_b32_e32 v88, 16, v88
	v_add_f32_e32 v140, v88, v84
	v_add_f32_e32 v141, v89, v85
	v_add_f32_e32 v142, v90, v86
	v_add_f32_e32 v143, v91, v87
	v_add_f32_e32 v140, v140, v80
	v_add_f32_e32 v141, v141, v81
	v_add_f32_e32 v142, v142, v82
	v_add_f32_e32 v143, v143, v83
	v_add_f32_e32 v140, v140, v76
	v_add_f32_e32 v141, v141, v77
	v_add_f32_e32 v142, v142, v78
	v_add_f32_e32 v143, v143, v79
	v_add_f32_e32 v140, v140, v72
	v_add_f32_e32 v141, v141, v73
	v_add_f32_e32 v142, v142, v74
	v_add_f32_e32 v143, v143, v75
	v_add_f32_e32 v140, v140, v68
	v_add_f32_e32 v141, v141, v69
	v_add_f32_e32 v142, v142, v70
	v_add_f32_e32 v143, v143, v71
	v_add_f32_e32 v140, v140, v64
	v_add_f32_e32 v141, v141, v65
	v_add_f32_e32 v142, v142, v66
	v_add_f32_e32 v143, v143, v67
	v_add_f32_e32 v140, v140, v60
	v_add_f32_e32 v141, v141, v61
	v_add_f32_e32 v142, v142, v62
	v_add_f32_e32 v143, v143, v63
	v_mul_f32_e32 v140, 0x3e000000, v140
	v_mul_f32_e32 v141, 0x3e000000, v141
	v_mul_f32_e32 v142, 0x3e000000, v142
	v_mul_f32_e32 v143, 0x3e000000, v143
	v_sub_f32_e32 v140, v140, v88
	v_sub_f32_e32 v141, v141, v89
	v_sub_f32_e32 v142, v142, v90
	v_sub_f32_e32 v143, v143, v91
	v_cvt_pk_bf16_f32 v174, v140, v141
	v_cvt_pk_bf16_f32 v175, v142, v143
	s_waitcnt vmcnt(3)
	v_and_b32_e32 v95, 0xffff0000, v93
	v_lshlrev_b32_e32 v94, 16, v93
	v_and_b32_e32 v93, 0xffff0000, v92
	v_lshlrev_b32_e32 v92, 16, v92
	v_add_f32_e32 v140, v92, v88
	v_add_f32_e32 v141, v93, v89
	v_add_f32_e32 v142, v94, v90
	v_add_f32_e32 v143, v95, v91
	v_add_f32_e32 v140, v140, v84
	v_add_f32_e32 v141, v141, v85
	v_add_f32_e32 v142, v142, v86
	v_add_f32_e32 v143, v143, v87
	v_add_f32_e32 v140, v140, v80
	v_add_f32_e32 v141, v141, v81
	v_add_f32_e32 v142, v142, v82
	v_add_f32_e32 v143, v143, v83
	v_add_f32_e32 v140, v140, v76
	v_add_f32_e32 v141, v141, v77
	v_add_f32_e32 v142, v142, v78
	v_add_f32_e32 v143, v143, v79
	v_add_f32_e32 v140, v140, v72
	v_add_f32_e32 v141, v141, v73
	v_add_f32_e32 v142, v142, v74
	v_add_f32_e32 v143, v143, v75
	v_add_f32_e32 v140, v140, v68
	v_add_f32_e32 v141, v141, v69
	v_add_f32_e32 v142, v142, v70
	v_add_f32_e32 v143, v143, v71
	v_add_f32_e32 v140, v140, v64
	v_add_f32_e32 v141, v141, v65
	v_add_f32_e32 v142, v142, v66
	v_add_f32_e32 v143, v143, v67
	v_mul_f32_e32 v140, 0x3e000000, v140
	v_mul_f32_e32 v141, 0x3e000000, v141
	v_mul_f32_e32 v142, 0x3e000000, v142
	v_mul_f32_e32 v143, 0x3e000000, v143
	v_sub_f32_e32 v140, v140, v92
	v_sub_f32_e32 v141, v141, v93
	v_sub_f32_e32 v142, v142, v94
	v_sub_f32_e32 v143, v143, v95
	v_cvt_pk_bf16_f32 v176, v140, v141
	v_cvt_pk_bf16_f32 v177, v142, v143
	s_waitcnt vmcnt(2)
	v_and_b32_e32 v99, 0xffff0000, v97
	v_lshlrev_b32_e32 v98, 16, v97
	v_and_b32_e32 v97, 0xffff0000, v96
	v_lshlrev_b32_e32 v96, 16, v96
	v_add_f32_e32 v140, v96, v92
	v_add_f32_e32 v141, v97, v93
	v_add_f32_e32 v142, v98, v94
	v_add_f32_e32 v143, v99, v95
	v_add_f32_e32 v140, v140, v88
	v_add_f32_e32 v141, v141, v89
	v_add_f32_e32 v142, v142, v90
	v_add_f32_e32 v143, v143, v91
	v_add_f32_e32 v140, v140, v84
	v_add_f32_e32 v141, v141, v85
	v_add_f32_e32 v142, v142, v86
	v_add_f32_e32 v143, v143, v87
	v_add_f32_e32 v140, v140, v80
	v_add_f32_e32 v141, v141, v81
	v_add_f32_e32 v142, v142, v82
	v_add_f32_e32 v143, v143, v83
	v_add_f32_e32 v140, v140, v76
	v_add_f32_e32 v141, v141, v77
	v_add_f32_e32 v142, v142, v78
	v_add_f32_e32 v143, v143, v79
	v_add_f32_e32 v140, v140, v72
	v_add_f32_e32 v141, v141, v73
	v_add_f32_e32 v142, v142, v74
	v_add_f32_e32 v143, v143, v75
	v_add_f32_e32 v140, v140, v68
	v_add_f32_e32 v141, v141, v69
	v_add_f32_e32 v142, v142, v70
	v_add_f32_e32 v143, v143, v71
	v_mul_f32_e32 v140, 0x3e000000, v140
	v_mul_f32_e32 v141, 0x3e000000, v141
	v_mul_f32_e32 v142, 0x3e000000, v142
	v_mul_f32_e32 v143, 0x3e000000, v143
	v_sub_f32_e32 v140, v140, v96
	v_sub_f32_e32 v141, v141, v97
	v_sub_f32_e32 v142, v142, v98
	v_sub_f32_e32 v143, v143, v99
	v_cvt_pk_bf16_f32 v178, v140, v141
	v_cvt_pk_bf16_f32 v179, v142, v143
	s_waitcnt vmcnt(1)
; template <int WIN>
; DI void pool_elem(const Params& p, int row, int c) {
;     ...
;     if (t >= 2033) {
;       float2 o = {u0, u1};
;       *(float2*)(p.out + O_POOLP + ((size_t)b * 15 + (t - 2033)) * 1024 + c) = o;
;     }
;   } else {
;     const int s = row - NPR;
;     cnt = (float)WIN;
;     const float* sp = p.state_pool + (size_t)s * 15 * 1024 + c;
;     float2 st[15];
; #pragma unroll
;     for (int j = 0; j < 15; ++j) st[j] = *(const float2*)(sp + (size_t)j * 1024);
; #pragma unroll
;     for (int j = 1; j < WIN; ++j) { s0 += st[15 - j].x; s1 += st[15 - j].y; }
;     float* op = p.out + O_POOLS + (size_t)s * 15 * 1024 + c;
; #pragma unroll
;     for (int j = 0; j < 14; ++j) *(float2*)(op + (size_t)j * 1024) = st[j + 1];
;     float2 o = {u0, u1};
;     *(float2*)(op + (size_t)14 * 1024) = o;
;   }
;   *(unsigned*)(p.MIX + (size_t)row * 1024 + c) = pack2(s0 / cnt - u0, s1 / cnt - u1);
	v_and_b32_e32 v103, 0xffff0000, v101
	v_lshlrev_b32_e32 v102, 16, v101
	v_and_b32_e32 v101, 0xffff0000, v100
	v_lshlrev_b32_e32 v100, 16, v100
	v_add_f32_e32 v140, v100, v96
	v_add_f32_e32 v141, v101, v97
	v_add_f32_e32 v142, v102, v98
	v_add_f32_e32 v143, v103, v99
	v_add_f32_e32 v140, v140, v92
	v_add_f32_e32 v141, v141, v93
	v_add_f32_e32 v142, v142, v94
	v_add_f32_e32 v143, v143, v95
	v_add_f32_e32 v140, v140, v88
	v_add_f32_e32 v141, v141, v89
	v_add_f32_e32 v142, v142, v90
	v_add_f32_e32 v143, v143, v91
	v_add_f32_e32 v140, v140, v84
	v_add_f32_e32 v141, v141, v85
	v_add_f32_e32 v142, v142, v86
	v_add_f32_e32 v143, v143, v87
	v_add_f32_e32 v140, v140, v80
	v_add_f32_e32 v141, v141, v81
	v_add_f32_e32 v142, v142, v82
	v_add_f32_e32 v143, v143, v83
	v_add_f32_e32 v140, v140, v76
	v_add_f32_e32 v141, v141, v77
	v_add_f32_e32 v142, v142, v78
	v_add_f32_e32 v143, v143, v79
	v_add_f32_e32 v140, v140, v72
	v_add_f32_e32 v141, v141, v73
	v_add_f32_e32 v142, v142, v74
	v_add_f32_e32 v143, v143, v75
	v_mul_f32_e32 v140, 0x3e000000, v140
	v_mul_f32_e32 v141, 0x3e000000, v141
	v_mul_f32_e32 v142, 0x3e000000, v142
	v_mul_f32_e32 v143, 0x3e000000, v143
	v_sub_f32_e32 v140, v140, v100
	v_sub_f32_e32 v141, v141, v101
	v_sub_f32_e32 v142, v142, v102
	v_sub_f32_e32 v143, v143, v103
	v_cvt_pk_bf16_f32 v180, v140, v141
	v_cvt_pk_bf16_f32 v181, v142, v143
	s_waitcnt vmcnt(0)
	v_and_b32_e32 v107, 0xffff0000, v105
	v_lshlrev_b32_e32 v106, 16, v105
	v_and_b32_e32 v105, 0xffff0000, v104
	v_lshlrev_b32_e32 v104, 16, v104
	v_add_f32_e32 v140, v104, v100
	v_add_f32_e32 v141, v105, v101
	v_add_f32_e32 v142, v106, v102
	v_add_f32_e32 v143, v107, v103
	v_add_f32_e32 v140, v140, v96
	v_add_f32_e32 v141, v141, v97
	v_add_f32_e32 v142, v142, v98
	v_add_f32_e32 v143, v143, v99
	v_add_f32_e32 v140, v140, v92
	v_add_f32_e32 v141, v141, v93
	v_add_f32_e32 v142, v142, v94
	v_add_f32_e32 v143, v143, v95
	v_add_f32_e32 v140, v140, v88
	v_add_f32_e32 v141, v141, v89
	v_add_f32_e32 v142, v142, v90
	v_add_f32_e32 v143, v143, v91
	v_add_f32_e32 v140, v140, v84
	v_add_f32_e32 v141, v141, v85
	v_add_f32_e32 v142, v142, v86
	v_add_f32_e32 v143, v143, v87
	v_add_f32_e32 v140, v140, v80
	v_add_f32_e32 v141, v141, v81
	v_add_f32_e32 v142, v142, v82
	v_add_f32_e32 v143, v143, v83
	v_add_f32_e32 v140, v140, v76
	v_add_f32_e32 v141, v141, v77
	v_add_f32_e32 v142, v142, v78
	v_add_f32_e32 v143, v143, v79
	v_mul_f32_e32 v140, 0x3e000000, v140
	v_mul_f32_e32 v141, 0x3e000000, v141
	v_mul_f32_e32 v142, 0x3e000000, v142
	v_mul_f32_e32 v143, 0x3e000000, v143
	v_sub_f32_e32 v140, v140, v104
	v_sub_f32_e32 v141, v141, v105
	v_sub_f32_e32 v142, v142, v106
	v_sub_f32_e32 v143, v143, v107
	v_cvt_pk_bf16_f32 v182, v140, v141
	v_cvt_pk_bf16_f32 v183, v142, v143
	global_store_dwordx2 v11, v[152:153], s[24:25] sc1
	s_add_u32 s24, s24, 0x800
	s_addc_u32 s25, s25, 0
	global_store_dwordx2 v11, v[154:155], s[24:25] sc1
	s_add_u32 s24, s24, 0x800
	s_addc_u32 s25, s25, 0
	global_store_dwordx2 v11, v[156:157], s[24:25] sc1
	s_add_u32 s24, s24, 0x800
	s_addc_u32 s25, s25, 0
	global_store_dwordx2 v11, v[158:159], s[24:25] sc1
	s_add_u32 s24, s24, 0x800
	s_addc_u32 s25, s25, 0
	global_store_dwordx2 v11, v[160:161], s[24:25] sc1
	s_add_u32 s24, s24, 0x800
	s_addc_u32 s25, s25, 0
	global_store_dwordx2 v11, v[162:163], s[24:25] sc1
	s_add_u32 s24, s24, 0x800
	s_addc_u32 s25, s25, 0
	global_store_dwordx2 v11, v[164:165], s[24:25] sc1
	s_add_u32 s24, s24, 0x800
	s_addc_u32 s25, s25, 0
	global_store_dwordx2 v11, v[166:167], s[24:25] sc1
	s_add_u32 s24, s24, 0x800
	s_addc_u32 s25, s25, 0
	global_store_dwordx2 v11, v[168:169], s[24:25] sc1
	s_add_u32 s24, s24, 0x800
	s_addc_u32 s25, s25, 0
	global_store_dwordx2 v11, v[170:171], s[24:25] sc1
	s_add_u32 s24, s24, 0x800
	s_addc_u32 s25, s25, 0
	global_store_dwordx2 v11, v[172:173], s[24:25] sc1
	s_add_u32 s24, s24, 0x800
	s_addc_u32 s25, s25, 0
	global_store_dwordx2 v11, v[174:175], s[24:25] sc1
	s_add_u32 s24, s24, 0x800
	s_addc_u32 s25, s25, 0
	global_store_dwordx2 v11, v[176:177], s[24:25] sc1
	s_add_u32 s24, s24, 0x800
	s_addc_u32 s25, s25, 0
	global_store_dwordx2 v11, v[178:179], s[24:25] sc1
	s_add_u32 s24, s24, 0x800
	s_addc_u32 s25, s25, 0
	global_store_dwordx2 v11, v[180:181], s[24:25] sc1
	s_add_u32 s24, s24, 0x800
	s_addc_u32 s25, s25, 0
	global_store_dwordx2 v11, v[182:183], s[24:25] sc1
	s_add_u32 s24, s24, 0x800
	s_addc_u32 s25, s25, 0
	s_cmp_eq_u32 s18, 127
	s_cbranch_scc0 .Lp13f_next
	s_mul_i32 s26, s17, 61440
	s_add_u32 s26, s26, 0x431c000
	s_add_u32 s22, s12, s26
	s_addc_u32 s23, s13, 0
	global_store_dwordx4 v12, v[48:51], s[22:23] sc1
	s_add_u32 s22, s22, 0x1000
	s_addc_u32 s23, s23, 0
	global_store_dwordx4 v12, v[52:55], s[22:23] sc1
	s_add_u32 s22, s22, 0x1000
	s_addc_u32 s23, s23, 0
	global_store_dwordx4 v12, v[56:59], s[22:23] sc1
	s_add_u32 s22, s22, 0x1000
	s_addc_u32 s23, s23, 0
	global_store_dwordx4 v12, v[60:63], s[22:23] sc1
	s_add_u32 s22, s22, 0x1000
	s_addc_u32 s23, s23, 0
	global_store_dwordx4 v12, v[64:67], s[22:23] sc1
	s_add_u32 s22, s22, 0x1000
	s_addc_u32 s23, s23, 0
	global_store_dwordx4 v12, v[68:71], s[22:23] sc1
	s_add_u32 s22, s22, 0x1000
	s_addc_u32 s23, s23, 0
	global_store_dwordx4 v12, v[72:75], s[22:23] sc1
	s_add_u32 s22, s22, 0x1000
	s_addc_u32 s23, s23, 0
	global_store_dwordx4 v12, v[76:79], s[22:23] sc1
	s_add_u32 s22, s22, 0x1000
	s_addc_u32 s23, s23, 0
	global_store_dwordx4 v12, v[80:83], s[22:23] sc1
	s_add_u32 s22, s22, 0x1000
	s_addc_u32 s23, s23, 0
	global_store_dwordx4 v12, v[84:87], s[22:23] sc1
	s_add_u32 s22, s22, 0x1000
	s_addc_u32 s23, s23, 0
	global_store_dwordx4 v12, v[88:91], s[22:23] sc1
	s_add_u32 s22, s22, 0x1000
	s_addc_u32 s23, s23, 0
	global_store_dwordx4 v12, v[92:95], s[22:23] sc1
	s_add_u32 s22, s22, 0x1000
	s_addc_u32 s23, s23, 0
	global_store_dwordx4 v12, v[96:99], s[22:23] sc1
	s_add_u32 s22, s22, 0x1000
	s_addc_u32 s23, s23, 0
	global_store_dwordx4 v12, v[100:103], s[22:23] sc1
	s_add_u32 s22, s22, 0x1000
	s_addc_u32 s23, s23, 0
	global_store_dwordx4 v12, v[104:107], s[22:23] sc1
	s_add_u32 s22, s22, 0x1000
	s_addc_u32 s23, s23, 0
	s_branch .Lp13f_next
; DI float bflo(unsigned u) { return __uint_as_float(u << 16); }
; DI float bfhi(unsigned u) { return __uint_as_float(u & 0xffff0000u); }
; template <int WIN>
; DI void pool_elem(const Params& p, int row, int c) {
;     ...
;   unsigned uu = *(const unsigned*)(P2 + (size_t)row * 2048 + c);
;   const float u0 = bflo(uu), u1 = bfhi(uu);
;   float s0 = u0, s1 = u1, cnt;
;   if (row < NPR) {
;     const int t = row & 2047, b = row >> 11;
;     if (t >= WIN - 1) {
;       cnt = (float)WIN;
;       unsigned w[WIN - 1];
; #pragma unroll
;       for (int j = 1; j < WIN; ++j) w[j - 1] = *(const unsigned*)(P2 + (size_t)(row - j) * 2048 + c);
; #pragma unroll
;       for (int j = 1; j < WIN; ++j) { s0 += bflo(w[j - 1]); s1 += bfhi(w[j - 1]); }
.Lp13f_w3:
	s_sub_u32 s26, s20, 15
	s_lshl_b32 s27, s26, 12
	s_lshr_b32 s28, s26, 20
	s_add_u32 s22, s8, s27
	s_addc_u32 s23, s9, s28
	global_load_dwordx2 v[16:17], v11, s[22:23]
	s_add_u32 s22, s22, 0x1000
	s_addc_u32 s23, s23, 0
	global_load_dwordx2 v[20:21], v11, s[22:23]
	s_add_u32 s22, s22, 0x1000
	s_addc_u32 s23, s23, 0
	global_load_dwordx2 v[24:25], v11, s[22:23]
	s_add_u32 s22, s22, 0x1000
	s_addc_u32 s23, s23, 0
	global_load_dwordx2 v[28:29], v11, s[22:23]
	s_add_u32 s22, s22, 0x1000
	s_addc_u32 s23, s23, 0
	global_load_dwordx2 v[32:33], v11, s[22:23]
	s_add_u32 s22, s22, 0x1000
	s_addc_u32 s23, s23, 0
	global_load_dwordx2 v[36:37], v11, s[22:23]
	s_add_u32 s22, s22, 0x1000
	s_addc_u32 s23, s23, 0
	global_load_dwordx2 v[40:41], v11, s[22:23]
	s_add_u32 s22, s22, 0x1000
	s_addc_u32 s23, s23, 0
	global_load_dwordx2 v[44:45], v11, s[22:23]
	s_add_u32 s22, s22, 0x1000
	s_addc_u32 s23, s23, 0
	global_load_dwordx2 v[48:49], v11, s[22:23]
	s_add_u32 s22, s22, 0x1000
	s_addc_u32 s23, s23, 0
	global_load_dwordx2 v[52:53], v11, s[22:23]
	s_add_u32 s22, s22, 0x1000
	s_addc_u32 s23, s23, 0
	global_load_dwordx2 v[56:57], v11, s[22:23]
	s_add_u32 s22, s22, 0x1000
	s_addc_u32 s23, s23, 0
	global_load_dwordx2 v[60:61], v11, s[22:23]
	s_add_u32 s22, s22, 0x1000
	s_addc_u32 s23, s23, 0
	global_load_dwordx2 v[64:65], v11, s[22:23]
	s_add_u32 s22, s22, 0x1000
	s_addc_u32 s23, s23, 0
	global_load_dwordx2 v[68:69], v11, s[22:23]
	s_add_u32 s22, s22, 0x1000
	s_addc_u32 s23, s23, 0
	global_load_dwordx2 v[72:73], v11, s[22:23]
	s_add_u32 s22, s22, 0x1000
	s_addc_u32 s23, s23, 0
	global_load_dwordx2 v[76:77], v11, s[22:23]
	s_add_u32 s22, s22, 0x1000
	s_addc_u32 s23, s23, 0
	global_load_dwordx2 v[80:81], v11, s[22:23]
	s_add_u32 s22, s22, 0x1000
	s_addc_u32 s23, s23, 0
	global_load_dwordx2 v[84:85], v11, s[22:23]
	s_add_u32 s22, s22, 0x1000
	s_addc_u32 s23, s23, 0
	global_load_dwordx2 v[88:89], v11, s[22:23]
	s_add_u32 s22, s22, 0x1000
	s_addc_u32 s23, s23, 0
	global_load_dwordx2 v[92:93], v11, s[22:23]
	s_add_u32 s22, s22, 0x1000
	s_addc_u32 s23, s23, 0
	global_load_dwordx2 v[96:97], v11, s[22:23]
	s_add_u32 s22, s22, 0x1000
	s_addc_u32 s23, s23, 0
	global_load_dwordx2 v[100:101], v11, s[22:23]
	s_add_u32 s22, s22, 0x1000
	s_addc_u32 s23, s23, 0
	global_load_dwordx2 v[104:105], v11, s[22:23]
	s_add_u32 s22, s22, 0x1000
	s_addc_u32 s23, s23, 0
	global_load_dwordx2 v[108:109], v11, s[22:23]
	s_add_u32 s22, s22, 0x1000
	s_addc_u32 s23, s23, 0
	global_load_dwordx2 v[112:113], v11, s[22:23]
	s_add_u32 s22, s22, 0x1000
	s_addc_u32 s23, s23, 0
	global_load_dwordx2 v[116:117], v11, s[22:23]
	s_add_u32 s22, s22, 0x1000
	s_addc_u32 s23, s23, 0
	global_load_dwordx2 v[120:121], v11, s[22:23]
	s_add_u32 s22, s22, 0x1000
	s_addc_u32 s23, s23, 0
	global_load_dwordx2 v[124:125], v11, s[22:23]
	s_add_u32 s22, s22, 0x1000
	s_addc_u32 s23, s23, 0
	global_load_dwordx2 v[128:129], v11, s[22:23]
	s_add_u32 s22, s22, 0x1000
	s_addc_u32 s23, s23, 0
	global_load_dwordx2 v[132:133], v11, s[22:23]
	s_add_u32 s22, s22, 0x1000
	s_addc_u32 s23, s23, 0
	global_load_dwordx2 v[136:137], v11, s[22:23]
	s_add_u32 s22, s22, 0x1000
	s_addc_u32 s23, s23, 0
	s_waitcnt vmcnt(15)
	v_and_b32_e32 v19, 0xffff0000, v17
	v_lshlrev_b32_e32 v18, 16, v17
	v_and_b32_e32 v17, 0xffff0000, v16
	v_lshlrev_b32_e32 v16, 16, v16
	v_and_b32_e32 v23, 0xffff0000, v21
	v_lshlrev_b32_e32 v22, 16, v21
	v_and_b32_e32 v21, 0xffff0000, v20
	v_lshlrev_b32_e32 v20, 16, v20
	v_and_b32_e32 v27, 0xffff0000, v25
	v_lshlrev_b32_e32 v26, 16, v25
	v_and_b32_e32 v25, 0xffff0000, v24
	v_lshlrev_b32_e32 v24, 16, v24
	v_and_b32_e32 v31, 0xffff0000, v29
	v_lshlrev_b32_e32 v30, 16, v29
	v_and_b32_e32 v29, 0xffff0000, v28
	v_lshlrev_b32_e32 v28, 16, v28
	v_and_b32_e32 v35, 0xffff0000, v33
	v_lshlrev_b32_e32 v34, 16, v33
	v_and_b32_e32 v33, 0xffff0000, v32
	v_lshlrev_b32_e32 v32, 16, v32
	v_and_b32_e32 v39, 0xffff0000, v37
	v_lshlrev_b32_e32 v38, 16, v37
	v_and_b32_e32 v37, 0xffff0000, v36
	v_lshlrev_b32_e32 v36, 16, v36
	v_and_b32_e32 v43, 0xffff0000, v41
	v_lshlrev_b32_e32 v42, 16, v41
	v_and_b32_e32 v41, 0xffff0000, v40
	v_lshlrev_b32_e32 v40, 16, v40
	v_and_b32_e32 v47, 0xffff0000, v45
	v_lshlrev_b32_e32 v46, 16, v45
	v_and_b32_e32 v45, 0xffff0000, v44
	v_lshlrev_b32_e32 v44, 16, v44
	v_and_b32_e32 v51, 0xffff0000, v49
	v_lshlrev_b32_e32 v50, 16, v49
	v_and_b32_e32 v49, 0xffff0000, v48
	v_lshlrev_b32_e32 v48, 16, v48
	v_and_b32_e32 v55, 0xffff0000, v53
	v_lshlrev_b32_e32 v54, 16, v53
	v_and_b32_e32 v53, 0xffff0000, v52
	v_lshlrev_b32_e32 v52, 16, v52
	v_and_b32_e32 v59, 0xffff0000, v57
	v_lshlrev_b32_e32 v58, 16, v57
	v_and_b32_e32 v57, 0xffff0000, v56
	v_lshlrev_b32_e32 v56, 16, v56
	v_and_b32_e32 v63, 0xffff0000, v61
	v_lshlrev_b32_e32 v62, 16, v61
	v_and_b32_e32 v61, 0xffff0000, v60
	v_lshlrev_b32_e32 v60, 16, v60
	v_and_b32_e32 v67, 0xffff0000, v65
	v_lshlrev_b32_e32 v66, 16, v65
	v_and_b32_e32 v65, 0xffff0000, v64
	v_lshlrev_b32_e32 v64, 16, v64
	v_and_b32_e32 v71, 0xffff0000, v69
	v_lshlrev_b32_e32 v70, 16, v69
	v_and_b32_e32 v69, 0xffff0000, v68
	v_lshlrev_b32_e32 v68, 16, v68
	v_and_b32_e32 v75, 0xffff0000, v73
	v_lshlrev_b32_e32 v74, 16, v73
	v_and_b32_e32 v73, 0xffff0000, v72
	v_lshlrev_b32_e32 v72, 16, v72
	v_and_b32_e32 v79, 0xffff0000, v77
	v_lshlrev_b32_e32 v78, 16, v77
	v_and_b32_e32 v77, 0xffff0000, v76
	v_lshlrev_b32_e32 v76, 16, v76
	v_add_f32_e32 v140, v76, v72
	v_add_f32_e32 v141, v77, v73
	v_add_f32_e32 v142, v78, v74
	v_add_f32_e32 v143, v79, v75
	v_add_f32_e32 v140, v140, v68
	v_add_f32_e32 v141, v141, v69
	v_add_f32_e32 v142, v142, v70
	v_add_f32_e32 v143, v143, v71
	v_add_f32_e32 v140, v140, v64
; DI float bflo(unsigned u) { return __uint_as_float(u << 16); }
; DI float bfhi(unsigned u) { return __uint_as_float(u & 0xffff0000u); }
; template <int WIN>
; DI void pool_elem(const Params& p, int row, int c) {
;     ...
;       for (int j = 1; j < WIN; ++j) w[j - 1] = *(const unsigned*)(P2 + (size_t)(row - j) * 2048 + c);
; #pragma unroll
;       for (int j = 1; j < WIN; ++j) { s0 += bflo(w[j - 1]); s1 += bfhi(w[j - 1]); }
;     ...
;   *(unsigned*)(p.MIX + (size_t)row * 1024 + c) = pack2(s0 / cnt - u0, s1 / cnt - u1);
	v_add_f32_e32 v141, v141, v65
	v_add_f32_e32 v142, v142, v66
	v_add_f32_e32 v143, v143, v67
	v_add_f32_e32 v140, v140, v60
	v_add_f32_e32 v141, v141, v61
	v_add_f32_e32 v142, v142, v62
	v_add_f32_e32 v143, v143, v63
	v_add_f32_e32 v140, v140, v56
	v_add_f32_e32 v141, v141, v57
	v_add_f32_e32 v142, v142, v58
	v_add_f32_e32 v143, v143, v59
	v_add_f32_e32 v140, v140, v52
	v_add_f32_e32 v141, v141, v53
	v_add_f32_e32 v142, v142, v54
	v_add_f32_e32 v143, v143, v55
	v_add_f32_e32 v140, v140, v48
	v_add_f32_e32 v141, v141, v49
	v_add_f32_e32 v142, v142, v50
	v_add_f32_e32 v143, v143, v51
	v_add_f32_e32 v140, v140, v44
	v_add_f32_e32 v141, v141, v45
	v_add_f32_e32 v142, v142, v46
	v_add_f32_e32 v143, v143, v47
	v_add_f32_e32 v140, v140, v40
	v_add_f32_e32 v141, v141, v41
	v_add_f32_e32 v142, v142, v42
	v_add_f32_e32 v143, v143, v43
	v_add_f32_e32 v140, v140, v36
	v_add_f32_e32 v141, v141, v37
	v_add_f32_e32 v142, v142, v38
	v_add_f32_e32 v143, v143, v39
	v_add_f32_e32 v140, v140, v32
	v_add_f32_e32 v141, v141, v33
	v_add_f32_e32 v142, v142, v34
	v_add_f32_e32 v143, v143, v35
	v_add_f32_e32 v140, v140, v28
	v_add_f32_e32 v141, v141, v29
	v_add_f32_e32 v142, v142, v30
	v_add_f32_e32 v143, v143, v31
	v_add_f32_e32 v140, v140, v24
	v_add_f32_e32 v141, v141, v25
	v_add_f32_e32 v142, v142, v26
	v_add_f32_e32 v143, v143, v27
	v_add_f32_e32 v140, v140, v20
	v_add_f32_e32 v141, v141, v21
	v_add_f32_e32 v142, v142, v22
	v_add_f32_e32 v143, v143, v23
	v_add_f32_e32 v140, v140, v16
	v_add_f32_e32 v141, v141, v17
	v_add_f32_e32 v142, v142, v18
	v_add_f32_e32 v143, v143, v19
	v_mul_f32_e32 v140, 0x3d800000, v140
	v_mul_f32_e32 v141, 0x3d800000, v141
	v_mul_f32_e32 v142, 0x3d800000, v142
	v_mul_f32_e32 v143, 0x3d800000, v143
	v_sub_f32_e32 v140, v140, v76
	v_sub_f32_e32 v141, v141, v77
	v_sub_f32_e32 v142, v142, v78
	v_sub_f32_e32 v143, v143, v79
	v_cvt_pk_bf16_f32 v152, v140, v141
	v_cvt_pk_bf16_f32 v153, v142, v143
	s_waitcnt vmcnt(14)
	v_and_b32_e32 v83, 0xffff0000, v81
	v_lshlrev_b32_e32 v82, 16, v81
	v_and_b32_e32 v81, 0xffff0000, v80
	v_lshlrev_b32_e32 v80, 16, v80
	v_add_f32_e32 v140, v80, v76
	v_add_f32_e32 v141, v81, v77
	v_add_f32_e32 v142, v82, v78
	v_add_f32_e32 v143, v83, v79
	v_add_f32_e32 v140, v140, v72
	v_add_f32_e32 v141, v141, v73
	v_add_f32_e32 v142, v142, v74
	v_add_f32_e32 v143, v143, v75
	v_add_f32_e32 v140, v140, v68
	v_add_f32_e32 v141, v141, v69
	v_add_f32_e32 v142, v142, v70
	v_add_f32_e32 v143, v143, v71
	v_add_f32_e32 v140, v140, v64
	v_add_f32_e32 v141, v141, v65
	v_add_f32_e32 v142, v142, v66
	v_add_f32_e32 v143, v143, v67
	v_add_f32_e32 v140, v140, v60
	v_add_f32_e32 v141, v141, v61
	v_add_f32_e32 v142, v142, v62
	v_add_f32_e32 v143, v143, v63
	v_add_f32_e32 v140, v140, v56
	v_add_f32_e32 v141, v141, v57
	v_add_f32_e32 v142, v142, v58
	v_add_f32_e32 v143, v143, v59
	v_add_f32_e32 v140, v140, v52
	v_add_f32_e32 v141, v141, v53
	v_add_f32_e32 v142, v142, v54
	v_add_f32_e32 v143, v143, v55
	v_add_f32_e32 v140, v140, v48
	v_add_f32_e32 v141, v141, v49
	v_add_f32_e32 v142, v142, v50
	v_add_f32_e32 v143, v143, v51
	v_add_f32_e32 v140, v140, v44
	v_add_f32_e32 v141, v141, v45
	v_add_f32_e32 v142, v142, v46
	v_add_f32_e32 v143, v143, v47
	v_add_f32_e32 v140, v140, v40
	v_add_f32_e32 v141, v141, v41
	v_add_f32_e32 v142, v142, v42
	v_add_f32_e32 v143, v143, v43
	v_add_f32_e32 v140, v140, v36
	v_add_f32_e32 v141, v141, v37
	v_add_f32_e32 v142, v142, v38
	v_add_f32_e32 v143, v143, v39
	v_add_f32_e32 v140, v140, v32
	v_add_f32_e32 v141, v141, v33
	v_add_f32_e32 v142, v142, v34
	v_add_f32_e32 v143, v143, v35
	v_add_f32_e32 v140, v140, v28
	v_add_f32_e32 v141, v141, v29
	v_add_f32_e32 v142, v142, v30
	v_add_f32_e32 v143, v143, v31
	v_add_f32_e32 v140, v140, v24
	v_add_f32_e32 v141, v141, v25
	v_add_f32_e32 v142, v142, v26
	v_add_f32_e32 v143, v143, v27
	v_add_f32_e32 v140, v140, v20
	v_add_f32_e32 v141, v141, v21
	v_add_f32_e32 v142, v142, v22
	v_add_f32_e32 v143, v143, v23
	v_mul_f32_e32 v140, 0x3d800000, v140
	v_mul_f32_e32 v141, 0x3d800000, v141
	v_mul_f32_e32 v142, 0x3d800000, v142
	v_mul_f32_e32 v143, 0x3d800000, v143
	v_sub_f32_e32 v140, v140, v80
	v_sub_f32_e32 v141, v141, v81
	v_sub_f32_e32 v142, v142, v82
	v_sub_f32_e32 v143, v143, v83
	v_cvt_pk_bf16_f32 v154, v140, v141
	v_cvt_pk_bf16_f32 v155, v142, v143
	s_waitcnt vmcnt(13)
	v_and_b32_e32 v87, 0xffff0000, v85
	v_lshlrev_b32_e32 v86, 16, v85
	v_and_b32_e32 v85, 0xffff0000, v84
	v_lshlrev_b32_e32 v84, 16, v84
	v_add_f32_e32 v140, v84, v80
	v_add_f32_e32 v141, v85, v81
	v_add_f32_e32 v142, v86, v82
	v_add_f32_e32 v143, v87, v83
	v_add_f32_e32 v140, v140, v76
	v_add_f32_e32 v141, v141, v77
	v_add_f32_e32 v142, v142, v78
	v_add_f32_e32 v143, v143, v79
	v_add_f32_e32 v140, v140, v72
	v_add_f32_e32 v141, v141, v73
	v_add_f32_e32 v142, v142, v74
	v_add_f32_e32 v143, v143, v75
	v_add_f32_e32 v140, v140, v68
	v_add_f32_e32 v141, v141, v69
	v_add_f32_e32 v142, v142, v70
	v_add_f32_e32 v143, v143, v71
	v_add_f32_e32 v140, v140, v64
	v_add_f32_e32 v141, v141, v65
	v_add_f32_e32 v142, v142, v66
	v_add_f32_e32 v143, v143, v67
	v_add_f32_e32 v140, v140, v60
	v_add_f32_e32 v141, v141, v61
	v_add_f32_e32 v142, v142, v62
	v_add_f32_e32 v143, v143, v63
	v_add_f32_e32 v140, v140, v56
	v_add_f32_e32 v141, v141, v57
	v_add_f32_e32 v142, v142, v58
	v_add_f32_e32 v143, v143, v59
	v_add_f32_e32 v140, v140, v52
	v_add_f32_e32 v141, v141, v53
	v_add_f32_e32 v142, v142, v54
	v_add_f32_e32 v143, v143, v55
	v_add_f32_e32 v140, v140, v48
	v_add_f32_e32 v141, v141, v49
	v_add_f32_e32 v142, v142, v50
	v_add_f32_e32 v143, v143, v51
	v_add_f32_e32 v140, v140, v44
	v_add_f32_e32 v141, v141, v45
	v_add_f32_e32 v142, v142, v46
	v_add_f32_e32 v143, v143, v47
	v_add_f32_e32 v140, v140, v40
	v_add_f32_e32 v141, v141, v41
	v_add_f32_e32 v142, v142, v42
	v_add_f32_e32 v143, v143, v43
	v_add_f32_e32 v140, v140, v36
	v_add_f32_e32 v141, v141, v37
	v_add_f32_e32 v142, v142, v38
	v_add_f32_e32 v143, v143, v39
	v_add_f32_e32 v140, v140, v32
	v_add_f32_e32 v141, v141, v33
	v_add_f32_e32 v142, v142, v34
	v_add_f32_e32 v143, v143, v35
	v_add_f32_e32 v140, v140, v28
	v_add_f32_e32 v141, v141, v29
	v_add_f32_e32 v142, v142, v30
	v_add_f32_e32 v143, v143, v31
	v_add_f32_e32 v140, v140, v24
	v_add_f32_e32 v141, v141, v25
	v_add_f32_e32 v142, v142, v26
	v_add_f32_e32 v143, v143, v27
	v_mul_f32_e32 v140, 0x3d800000, v140
	v_mul_f32_e32 v141, 0x3d800000, v141
	v_mul_f32_e32 v142, 0x3d800000, v142
	v_mul_f32_e32 v143, 0x3d800000, v143
	v_sub_f32_e32 v140, v140, v84
	v_sub_f32_e32 v141, v141, v85
	v_sub_f32_e32 v142, v142, v86
	v_sub_f32_e32 v143, v143, v87
	v_cvt_pk_bf16_f32 v156, v140, v141
	v_cvt_pk_bf16_f32 v157, v142, v143
	s_waitcnt vmcnt(12)
; DI float bflo(unsigned u) { return __uint_as_float(u << 16); }
; DI float bfhi(unsigned u) { return __uint_as_float(u & 0xffff0000u); }
; template <int WIN>
; DI void pool_elem(const Params& p, int row, int c) {
;     ...
;       for (int j = 1; j < WIN; ++j) w[j - 1] = *(const unsigned*)(P2 + (size_t)(row - j) * 2048 + c);
; #pragma unroll
;       for (int j = 1; j < WIN; ++j) { s0 += bflo(w[j - 1]); s1 += bfhi(w[j - 1]); }
;     ...
;   *(unsigned*)(p.MIX + (size_t)row * 1024 + c) = pack2(s0 / cnt - u0, s1 / cnt - u1);
	v_and_b32_e32 v91, 0xffff0000, v89
	v_lshlrev_b32_e32 v90, 16, v89
	v_and_b32_e32 v89, 0xffff0000, v88
	v_lshlrev_b32_e32 v88, 16, v88
	v_add_f32_e32 v140, v88, v84
	v_add_f32_e32 v141, v89, v85
	v_add_f32_e32 v142, v90, v86
	v_add_f32_e32 v143, v91, v87
	v_add_f32_e32 v140, v140, v80
	v_add_f32_e32 v141, v141, v81
	v_add_f32_e32 v142, v142, v82
	v_add_f32_e32 v143, v143, v83
	v_add_f32_e32 v140, v140, v76
	v_add_f32_e32 v141, v141, v77
	v_add_f32_e32 v142, v142, v78
	v_add_f32_e32 v143, v143, v79
	v_add_f32_e32 v140, v140, v72
	v_add_f32_e32 v141, v141, v73
	v_add_f32_e32 v142, v142, v74
	v_add_f32_e32 v143, v143, v75
	v_add_f32_e32 v140, v140, v68
	v_add_f32_e32 v141, v141, v69
	v_add_f32_e32 v142, v142, v70
	v_add_f32_e32 v143, v143, v71
	v_add_f32_e32 v140, v140, v64
	v_add_f32_e32 v141, v141, v65
	v_add_f32_e32 v142, v142, v66
	v_add_f32_e32 v143, v143, v67
	v_add_f32_e32 v140, v140, v60
	v_add_f32_e32 v141, v141, v61
	v_add_f32_e32 v142, v142, v62
	v_add_f32_e32 v143, v143, v63
	v_add_f32_e32 v140, v140, v56
	v_add_f32_e32 v141, v141, v57
	v_add_f32_e32 v142, v142, v58
	v_add_f32_e32 v143, v143, v59
	v_add_f32_e32 v140, v140, v52
	v_add_f32_e32 v141, v141, v53
	v_add_f32_e32 v142, v142, v54
	v_add_f32_e32 v143, v143, v55
	v_add_f32_e32 v140, v140, v48
	v_add_f32_e32 v141, v141, v49
	v_add_f32_e32 v142, v142, v50
	v_add_f32_e32 v143, v143, v51
	v_add_f32_e32 v140, v140, v44
	v_add_f32_e32 v141, v141, v45
	v_add_f32_e32 v142, v142, v46
	v_add_f32_e32 v143, v143, v47
	v_add_f32_e32 v140, v140, v40
	v_add_f32_e32 v141, v141, v41
	v_add_f32_e32 v142, v142, v42
	v_add_f32_e32 v143, v143, v43
	v_add_f32_e32 v140, v140, v36
	v_add_f32_e32 v141, v141, v37
	v_add_f32_e32 v142, v142, v38
	v_add_f32_e32 v143, v143, v39
	v_add_f32_e32 v140, v140, v32
	v_add_f32_e32 v141, v141, v33
	v_add_f32_e32 v142, v142, v34
	v_add_f32_e32 v143, v143, v35
	v_add_f32_e32 v140, v140, v28
	v_add_f32_e32 v141, v141, v29
	v_add_f32_e32 v142, v142, v30
	v_add_f32_e32 v143, v143, v31
	v_mul_f32_e32 v140, 0x3d800000, v140
	v_mul_f32_e32 v141, 0x3d800000, v141
	v_mul_f32_e32 v142, 0x3d800000, v142
	v_mul_f32_e32 v143, 0x3d800000, v143
	v_sub_f32_e32 v140, v140, v88
	v_sub_f32_e32 v141, v141, v89
	v_sub_f32_e32 v142, v142, v90
	v_sub_f32_e32 v143, v143, v91
	v_cvt_pk_bf16_f32 v158, v140, v141
	v_cvt_pk_bf16_f32 v159, v142, v143
	s_waitcnt vmcnt(11)
	v_and_b32_e32 v95, 0xffff0000, v93
	v_lshlrev_b32_e32 v94, 16, v93
	v_and_b32_e32 v93, 0xffff0000, v92
	v_lshlrev_b32_e32 v92, 16, v92
	v_add_f32_e32 v140, v92, v88
	v_add_f32_e32 v141, v93, v89
	v_add_f32_e32 v142, v94, v90
	v_add_f32_e32 v143, v95, v91
	v_add_f32_e32 v140, v140, v84
	v_add_f32_e32 v141, v141, v85
	v_add_f32_e32 v142, v142, v86
	v_add_f32_e32 v143, v143, v87
	v_add_f32_e32 v140, v140, v80
	v_add_f32_e32 v141, v141, v81
	v_add_f32_e32 v142, v142, v82
	v_add_f32_e32 v143, v143, v83
	v_add_f32_e32 v140, v140, v76
	v_add_f32_e32 v141, v141, v77
	v_add_f32_e32 v142, v142, v78
	v_add_f32_e32 v143, v143, v79
	v_add_f32_e32 v140, v140, v72
	v_add_f32_e32 v141, v141, v73
	v_add_f32_e32 v142, v142, v74
	v_add_f32_e32 v143, v143, v75
	v_add_f32_e32 v140, v140, v68
	v_add_f32_e32 v141, v141, v69
	v_add_f32_e32 v142, v142, v70
	v_add_f32_e32 v143, v143, v71
	v_add_f32_e32 v140, v140, v64
	v_add_f32_e32 v141, v141, v65
	v_add_f32_e32 v142, v142, v66
	v_add_f32_e32 v143, v143, v67
	v_add_f32_e32 v140, v140, v60
	v_add_f32_e32 v141, v141, v61
	v_add_f32_e32 v142, v142, v62
	v_add_f32_e32 v143, v143, v63
	v_add_f32_e32 v140, v140, v56
	v_add_f32_e32 v141, v141, v57
	v_add_f32_e32 v142, v142, v58
	v_add_f32_e32 v143, v143, v59
	v_add_f32_e32 v140, v140, v52
	v_add_f32_e32 v141, v141, v53
	v_add_f32_e32 v142, v142, v54
	v_add_f32_e32 v143, v143, v55
	v_add_f32_e32 v140, v140, v48
	v_add_f32_e32 v141, v141, v49
	v_add_f32_e32 v142, v142, v50
	v_add_f32_e32 v143, v143, v51
	v_add_f32_e32 v140, v140, v44
	v_add_f32_e32 v141, v141, v45
	v_add_f32_e32 v142, v142, v46
	v_add_f32_e32 v143, v143, v47
	v_add_f32_e32 v140, v140, v40
	v_add_f32_e32 v141, v141, v41
	v_add_f32_e32 v142, v142, v42
	v_add_f32_e32 v143, v143, v43
	v_add_f32_e32 v140, v140, v36
	v_add_f32_e32 v141, v141, v37
	v_add_f32_e32 v142, v142, v38
	v_add_f32_e32 v143, v143, v39
	v_add_f32_e32 v140, v140, v32
	v_add_f32_e32 v141, v141, v33
	v_add_f32_e32 v142, v142, v34
	v_add_f32_e32 v143, v143, v35
	v_mul_f32_e32 v140, 0x3d800000, v140
	v_mul_f32_e32 v141, 0x3d800000, v141
	v_mul_f32_e32 v142, 0x3d800000, v142
	v_mul_f32_e32 v143, 0x3d800000, v143
	v_sub_f32_e32 v140, v140, v92
	v_sub_f32_e32 v141, v141, v93
	v_sub_f32_e32 v142, v142, v94
	v_sub_f32_e32 v143, v143, v95
	v_cvt_pk_bf16_f32 v160, v140, v141
	v_cvt_pk_bf16_f32 v161, v142, v143
	s_waitcnt vmcnt(10)
; DI float bflo(unsigned u) { return __uint_as_float(u << 16); }
; DI float bfhi(unsigned u) { return __uint_as_float(u & 0xffff0000u); }
; template <int WIN>
; DI void pool_elem(const Params& p, int row, int c) {
;     ...
;       for (int j = 1; j < WIN; ++j) w[j - 1] = *(const unsigned*)(P2 + (size_t)(row - j) * 2048 + c);
; #pragma unroll
;       for (int j = 1; j < WIN; ++j) { s0 += bflo(w[j - 1]); s1 += bfhi(w[j - 1]); }
;     ...
;   *(unsigned*)(p.MIX + (size_t)row * 1024 + c) = pack2(s0 / cnt - u0, s1 / cnt - u1);
	v_and_b32_e32 v99, 0xffff0000, v97
	v_lshlrev_b32_e32 v98, 16, v97
	v_and_b32_e32 v97, 0xffff0000, v96
	v_lshlrev_b32_e32 v96, 16, v96
	v_add_f32_e32 v140, v96, v92
	v_add_f32_e32 v141, v97, v93
	v_add_f32_e32 v142, v98, v94
	v_add_f32_e32 v143, v99, v95
	v_add_f32_e32 v140, v140, v88
	v_add_f32_e32 v141, v141, v89
	v_add_f32_e32 v142, v142, v90
	v_add_f32_e32 v143, v143, v91
	v_add_f32_e32 v140, v140, v84
	v_add_f32_e32 v141, v141, v85
	v_add_f32_e32 v142, v142, v86
	v_add_f32_e32 v143, v143, v87
	v_add_f32_e32 v140, v140, v80
	v_add_f32_e32 v141, v141, v81
	v_add_f32_e32 v142, v142, v82
	v_add_f32_e32 v143, v143, v83
	v_add_f32_e32 v140, v140, v76
	v_add_f32_e32 v141, v141, v77
	v_add_f32_e32 v142, v142, v78
	v_add_f32_e32 v143, v143, v79
	v_add_f32_e32 v140, v140, v72
	v_add_f32_e32 v141, v141, v73
	v_add_f32_e32 v142, v142, v74
	v_add_f32_e32 v143, v143, v75
	v_add_f32_e32 v140, v140, v68
	v_add_f32_e32 v141, v141, v69
	v_add_f32_e32 v142, v142, v70
	v_add_f32_e32 v143, v143, v71
	v_add_f32_e32 v140, v140, v64
	v_add_f32_e32 v141, v141, v65
	v_add_f32_e32 v142, v142, v66
	v_add_f32_e32 v143, v143, v67
	v_add_f32_e32 v140, v140, v60
	v_add_f32_e32 v141, v141, v61
	v_add_f32_e32 v142, v142, v62
	v_add_f32_e32 v143, v143, v63
	v_add_f32_e32 v140, v140, v56
	v_add_f32_e32 v141, v141, v57
	v_add_f32_e32 v142, v142, v58
	v_add_f32_e32 v143, v143, v59
	v_add_f32_e32 v140, v140, v52
	v_add_f32_e32 v141, v141, v53
	v_add_f32_e32 v142, v142, v54
	v_add_f32_e32 v143, v143, v55
	v_add_f32_e32 v140, v140, v48
	v_add_f32_e32 v141, v141, v49
	v_add_f32_e32 v142, v142, v50
	v_add_f32_e32 v143, v143, v51
	v_add_f32_e32 v140, v140, v44
	v_add_f32_e32 v141, v141, v45
	v_add_f32_e32 v142, v142, v46
	v_add_f32_e32 v143, v143, v47
	v_add_f32_e32 v140, v140, v40
	v_add_f32_e32 v141, v141, v41
	v_add_f32_e32 v142, v142, v42
	v_add_f32_e32 v143, v143, v43
	v_add_f32_e32 v140, v140, v36
	v_add_f32_e32 v141, v141, v37
	v_add_f32_e32 v142, v142, v38
	v_add_f32_e32 v143, v143, v39
	v_mul_f32_e32 v140, 0x3d800000, v140
	v_mul_f32_e32 v141, 0x3d800000, v141
	v_mul_f32_e32 v142, 0x3d800000, v142
	v_mul_f32_e32 v143, 0x3d800000, v143
	v_sub_f32_e32 v140, v140, v96
	v_sub_f32_e32 v141, v141, v97
	v_sub_f32_e32 v142, v142, v98
	v_sub_f32_e32 v143, v143, v99
	v_cvt_pk_bf16_f32 v162, v140, v141
	v_cvt_pk_bf16_f32 v163, v142, v143
	s_waitcnt vmcnt(9)
	v_and_b32_e32 v103, 0xffff0000, v101
	v_lshlrev_b32_e32 v102, 16, v101
	v_and_b32_e32 v101, 0xffff0000, v100
	v_lshlrev_b32_e32 v100, 16, v100
	v_add_f32_e32 v140, v100, v96
	v_add_f32_e32 v141, v101, v97
	v_add_f32_e32 v142, v102, v98
	v_add_f32_e32 v143, v103, v99
	v_add_f32_e32 v140, v140, v92
	v_add_f32_e32 v141, v141, v93
	v_add_f32_e32 v142, v142, v94
	v_add_f32_e32 v143, v143, v95
	v_add_f32_e32 v140, v140, v88
	v_add_f32_e32 v141, v141, v89
	v_add_f32_e32 v142, v142, v90
	v_add_f32_e32 v143, v143, v91
	v_add_f32_e32 v140, v140, v84
	v_add_f32_e32 v141, v141, v85
	v_add_f32_e32 v142, v142, v86
	v_add_f32_e32 v143, v143, v87
	v_add_f32_e32 v140, v140, v80
	v_add_f32_e32 v141, v141, v81
	v_add_f32_e32 v142, v142, v82
	v_add_f32_e32 v143, v143, v83
	v_add_f32_e32 v140, v140, v76
	v_add_f32_e32 v141, v141, v77
	v_add_f32_e32 v142, v142, v78
	v_add_f32_e32 v143, v143, v79
	v_add_f32_e32 v140, v140, v72
	v_add_f32_e32 v141, v141, v73
	v_add_f32_e32 v142, v142, v74
	v_add_f32_e32 v143, v143, v75
	v_add_f32_e32 v140, v140, v68
	v_add_f32_e32 v141, v141, v69
	v_add_f32_e32 v142, v142, v70
	v_add_f32_e32 v143, v143, v71
	v_add_f32_e32 v140, v140, v64
	v_add_f32_e32 v141, v141, v65
	v_add_f32_e32 v142, v142, v66
	v_add_f32_e32 v143, v143, v67
	v_add_f32_e32 v140, v140, v60
	v_add_f32_e32 v141, v141, v61
	v_add_f32_e32 v142, v142, v62
	v_add_f32_e32 v143, v143, v63
	v_add_f32_e32 v140, v140, v56
	v_add_f32_e32 v141, v141, v57
	v_add_f32_e32 v142, v142, v58
	v_add_f32_e32 v143, v143, v59
	v_add_f32_e32 v140, v140, v52
	v_add_f32_e32 v141, v141, v53
	v_add_f32_e32 v142, v142, v54
	v_add_f32_e32 v143, v143, v55
	v_add_f32_e32 v140, v140, v48
	v_add_f32_e32 v141, v141, v49
	v_add_f32_e32 v142, v142, v50
	v_add_f32_e32 v143, v143, v51
	v_add_f32_e32 v140, v140, v44
	v_add_f32_e32 v141, v141, v45
	v_add_f32_e32 v142, v142, v46
	v_add_f32_e32 v143, v143, v47
	v_add_f32_e32 v140, v140, v40
	v_add_f32_e32 v141, v141, v41
	v_add_f32_e32 v142, v142, v42
	v_add_f32_e32 v143, v143, v43
	v_mul_f32_e32 v140, 0x3d800000, v140
	v_mul_f32_e32 v141, 0x3d800000, v141
	v_mul_f32_e32 v142, 0x3d800000, v142
	v_mul_f32_e32 v143, 0x3d800000, v143
	v_sub_f32_e32 v140, v140, v100
	v_sub_f32_e32 v141, v141, v101
	v_sub_f32_e32 v142, v142, v102
	v_sub_f32_e32 v143, v143, v103
	v_cvt_pk_bf16_f32 v164, v140, v141
	v_cvt_pk_bf16_f32 v165, v142, v143
	s_waitcnt vmcnt(8)
; DI float bflo(unsigned u) { return __uint_as_float(u << 16); }
; DI float bfhi(unsigned u) { return __uint_as_float(u & 0xffff0000u); }
; template <int WIN>
; DI void pool_elem(const Params& p, int row, int c) {
;     ...
;       for (int j = 1; j < WIN; ++j) w[j - 1] = *(const unsigned*)(P2 + (size_t)(row - j) * 2048 + c);
; #pragma unroll
;       for (int j = 1; j < WIN; ++j) { s0 += bflo(w[j - 1]); s1 += bfhi(w[j - 1]); }
;     ...
;   *(unsigned*)(p.MIX + (size_t)row * 1024 + c) = pack2(s0 / cnt - u0, s1 / cnt - u1);
	v_and_b32_e32 v107, 0xffff0000, v105
	v_lshlrev_b32_e32 v106, 16, v105
	v_and_b32_e32 v105, 0xffff0000, v104
	v_lshlrev_b32_e32 v104, 16, v104
	v_add_f32_e32 v140, v104, v100
	v_add_f32_e32 v141, v105, v101
	v_add_f32_e32 v142, v106, v102
	v_add_f32_e32 v143, v107, v103
	v_add_f32_e32 v140, v140, v96
	v_add_f32_e32 v141, v141, v97
	v_add_f32_e32 v142, v142, v98
	v_add_f32_e32 v143, v143, v99
	v_add_f32_e32 v140, v140, v92
	v_add_f32_e32 v141, v141, v93
	v_add_f32_e32 v142, v142, v94
	v_add_f32_e32 v143, v143, v95
	v_add_f32_e32 v140, v140, v88
	v_add_f32_e32 v141, v141, v89
	v_add_f32_e32 v142, v142, v90
	v_add_f32_e32 v143, v143, v91
	v_add_f32_e32 v140, v140, v84
	v_add_f32_e32 v141, v141, v85
	v_add_f32_e32 v142, v142, v86
	v_add_f32_e32 v143, v143, v87
	v_add_f32_e32 v140, v140, v80
	v_add_f32_e32 v141, v141, v81
	v_add_f32_e32 v142, v142, v82
	v_add_f32_e32 v143, v143, v83
	v_add_f32_e32 v140, v140, v76
	v_add_f32_e32 v141, v141, v77
	v_add_f32_e32 v142, v142, v78
	v_add_f32_e32 v143, v143, v79
	v_add_f32_e32 v140, v140, v72
	v_add_f32_e32 v141, v141, v73
	v_add_f32_e32 v142, v142, v74
	v_add_f32_e32 v143, v143, v75
	v_add_f32_e32 v140, v140, v68
	v_add_f32_e32 v141, v141, v69
	v_add_f32_e32 v142, v142, v70
	v_add_f32_e32 v143, v143, v71
	v_add_f32_e32 v140, v140, v64
	v_add_f32_e32 v141, v141, v65
	v_add_f32_e32 v142, v142, v66
	v_add_f32_e32 v143, v143, v67
	v_add_f32_e32 v140, v140, v60
	v_add_f32_e32 v141, v141, v61
	v_add_f32_e32 v142, v142, v62
	v_add_f32_e32 v143, v143, v63
	v_add_f32_e32 v140, v140, v56
	v_add_f32_e32 v141, v141, v57
	v_add_f32_e32 v142, v142, v58
	v_add_f32_e32 v143, v143, v59
	v_add_f32_e32 v140, v140, v52
	v_add_f32_e32 v141, v141, v53
	v_add_f32_e32 v142, v142, v54
	v_add_f32_e32 v143, v143, v55
	v_add_f32_e32 v140, v140, v48
	v_add_f32_e32 v141, v141, v49
	v_add_f32_e32 v142, v142, v50
	v_add_f32_e32 v143, v143, v51
	v_add_f32_e32 v140, v140, v44
	v_add_f32_e32 v141, v141, v45
	v_add_f32_e32 v142, v142, v46
	v_add_f32_e32 v143, v143, v47
	v_mul_f32_e32 v140, 0x3d800000, v140
	v_mul_f32_e32 v141, 0x3d800000, v141
	v_mul_f32_e32 v142, 0x3d800000, v142
	v_mul_f32_e32 v143, 0x3d800000, v143
	v_sub_f32_e32 v140, v140, v104
	v_sub_f32_e32 v141, v141, v105
	v_sub_f32_e32 v142, v142, v106
	v_sub_f32_e32 v143, v143, v107
	v_cvt_pk_bf16_f32 v166, v140, v141
	v_cvt_pk_bf16_f32 v167, v142, v143
	s_waitcnt vmcnt(7)
	v_and_b32_e32 v111, 0xffff0000, v109
	v_lshlrev_b32_e32 v110, 16, v109
	v_and_b32_e32 v109, 0xffff0000, v108
	v_lshlrev_b32_e32 v108, 16, v108
	v_add_f32_e32 v140, v108, v104
	v_add_f32_e32 v141, v109, v105
	v_add_f32_e32 v142, v110, v106
	v_add_f32_e32 v143, v111, v107
	v_add_f32_e32 v140, v140, v100
	v_add_f32_e32 v141, v141, v101
	v_add_f32_e32 v142, v142, v102
	v_add_f32_e32 v143, v143, v103
	v_add_f32_e32 v140, v140, v96
	v_add_f32_e32 v141, v141, v97
	v_add_f32_e32 v142, v142, v98
	v_add_f32_e32 v143, v143, v99
	v_add_f32_e32 v140, v140, v92
	v_add_f32_e32 v141, v141, v93
	v_add_f32_e32 v142, v142, v94
	v_add_f32_e32 v143, v143, v95
	v_add_f32_e32 v140, v140, v88
	v_add_f32_e32 v141, v141, v89
	v_add_f32_e32 v142, v142, v90
	v_add_f32_e32 v143, v143, v91
	v_add_f32_e32 v140, v140, v84
	v_add_f32_e32 v141, v141, v85
	v_add_f32_e32 v142, v142, v86
	v_add_f32_e32 v143, v143, v87
	v_add_f32_e32 v140, v140, v80
	v_add_f32_e32 v141, v141, v81
	v_add_f32_e32 v142, v142, v82
	v_add_f32_e32 v143, v143, v83
	v_add_f32_e32 v140, v140, v76
	v_add_f32_e32 v141, v141, v77
	v_add_f32_e32 v142, v142, v78
	v_add_f32_e32 v143, v143, v79
	v_add_f32_e32 v140, v140, v72
	v_add_f32_e32 v141, v141, v73
	v_add_f32_e32 v142, v142, v74
	v_add_f32_e32 v143, v143, v75
	v_add_f32_e32 v140, v140, v68
	v_add_f32_e32 v141, v141, v69
	v_add_f32_e32 v142, v142, v70
	v_add_f32_e32 v143, v143, v71
	v_add_f32_e32 v140, v140, v64
	v_add_f32_e32 v141, v141, v65
	v_add_f32_e32 v142, v142, v66
	v_add_f32_e32 v143, v143, v67
	v_add_f32_e32 v140, v140, v60
	v_add_f32_e32 v141, v141, v61
	v_add_f32_e32 v142, v142, v62
	v_add_f32_e32 v143, v143, v63
	v_add_f32_e32 v140, v140, v56
	v_add_f32_e32 v141, v141, v57
	v_add_f32_e32 v142, v142, v58
	v_add_f32_e32 v143, v143, v59
	v_add_f32_e32 v140, v140, v52
	v_add_f32_e32 v141, v141, v53
	v_add_f32_e32 v142, v142, v54
	v_add_f32_e32 v143, v143, v55
	v_add_f32_e32 v140, v140, v48
	v_add_f32_e32 v141, v141, v49
	v_add_f32_e32 v142, v142, v50
	v_add_f32_e32 v143, v143, v51
	v_mul_f32_e32 v140, 0x3d800000, v140
	v_mul_f32_e32 v141, 0x3d800000, v141
	v_mul_f32_e32 v142, 0x3d800000, v142
	v_mul_f32_e32 v143, 0x3d800000, v143
	v_sub_f32_e32 v140, v140, v108
	v_sub_f32_e32 v141, v141, v109
	v_sub_f32_e32 v142, v142, v110
	v_sub_f32_e32 v143, v143, v111
	v_cvt_pk_bf16_f32 v168, v140, v141
	v_cvt_pk_bf16_f32 v169, v142, v143
	s_waitcnt vmcnt(6)
; DI float bflo(unsigned u) { return __uint_as_float(u << 16); }
; DI float bfhi(unsigned u) { return __uint_as_float(u & 0xffff0000u); }
; template <int WIN>
; DI void pool_elem(const Params& p, int row, int c) {
;     ...
;       for (int j = 1; j < WIN; ++j) w[j - 1] = *(const unsigned*)(P2 + (size_t)(row - j) * 2048 + c);
; #pragma unroll
;       for (int j = 1; j < WIN; ++j) { s0 += bflo(w[j - 1]); s1 += bfhi(w[j - 1]); }
;     ...
;   *(unsigned*)(p.MIX + (size_t)row * 1024 + c) = pack2(s0 / cnt - u0, s1 / cnt - u1);
	v_and_b32_e32 v115, 0xffff0000, v113
	v_lshlrev_b32_e32 v114, 16, v113
	v_and_b32_e32 v113, 0xffff0000, v112
	v_lshlrev_b32_e32 v112, 16, v112
	v_add_f32_e32 v140, v112, v108
	v_add_f32_e32 v141, v113, v109
	v_add_f32_e32 v142, v114, v110
	v_add_f32_e32 v143, v115, v111
	v_add_f32_e32 v140, v140, v104
	v_add_f32_e32 v141, v141, v105
	v_add_f32_e32 v142, v142, v106
	v_add_f32_e32 v143, v143, v107
	v_add_f32_e32 v140, v140, v100
	v_add_f32_e32 v141, v141, v101
	v_add_f32_e32 v142, v142, v102
	v_add_f32_e32 v143, v143, v103
	v_add_f32_e32 v140, v140, v96
	v_add_f32_e32 v141, v141, v97
	v_add_f32_e32 v142, v142, v98
	v_add_f32_e32 v143, v143, v99
	v_add_f32_e32 v140, v140, v92
	v_add_f32_e32 v141, v141, v93
	v_add_f32_e32 v142, v142, v94
	v_add_f32_e32 v143, v143, v95
	v_add_f32_e32 v140, v140, v88
	v_add_f32_e32 v141, v141, v89
	v_add_f32_e32 v142, v142, v90
	v_add_f32_e32 v143, v143, v91
	v_add_f32_e32 v140, v140, v84
	v_add_f32_e32 v141, v141, v85
	v_add_f32_e32 v142, v142, v86
	v_add_f32_e32 v143, v143, v87
	v_add_f32_e32 v140, v140, v80
	v_add_f32_e32 v141, v141, v81
	v_add_f32_e32 v142, v142, v82
	v_add_f32_e32 v143, v143, v83
	v_add_f32_e32 v140, v140, v76
	v_add_f32_e32 v141, v141, v77
	v_add_f32_e32 v142, v142, v78
	v_add_f32_e32 v143, v143, v79
	v_add_f32_e32 v140, v140, v72
	v_add_f32_e32 v141, v141, v73
	v_add_f32_e32 v142, v142, v74
	v_add_f32_e32 v143, v143, v75
	v_add_f32_e32 v140, v140, v68
	v_add_f32_e32 v141, v141, v69
	v_add_f32_e32 v142, v142, v70
	v_add_f32_e32 v143, v143, v71
	v_add_f32_e32 v140, v140, v64
	v_add_f32_e32 v141, v141, v65
	v_add_f32_e32 v142, v142, v66
	v_add_f32_e32 v143, v143, v67
	v_add_f32_e32 v140, v140, v60
	v_add_f32_e32 v141, v141, v61
	v_add_f32_e32 v142, v142, v62
	v_add_f32_e32 v143, v143, v63
	v_add_f32_e32 v140, v140, v56
	v_add_f32_e32 v141, v141, v57
	v_add_f32_e32 v142, v142, v58
	v_add_f32_e32 v143, v143, v59
	v_add_f32_e32 v140, v140, v52
	v_add_f32_e32 v141, v141, v53
	v_add_f32_e32 v142, v142, v54
	v_add_f32_e32 v143, v143, v55
	v_mul_f32_e32 v140, 0x3d800000, v140
	v_mul_f32_e32 v141, 0x3d800000, v141
	v_mul_f32_e32 v142, 0x3d800000, v142
	v_mul_f32_e32 v143, 0x3d800000, v143
	v_sub_f32_e32 v140, v140, v112
	v_sub_f32_e32 v141, v141, v113
	v_sub_f32_e32 v142, v142, v114
	v_sub_f32_e32 v143, v143, v115
	v_cvt_pk_bf16_f32 v170, v140, v141
	v_cvt_pk_bf16_f32 v171, v142, v143
	s_waitcnt vmcnt(5)
	v_and_b32_e32 v119, 0xffff0000, v117
	v_lshlrev_b32_e32 v118, 16, v117
	v_and_b32_e32 v117, 0xffff0000, v116
	v_lshlrev_b32_e32 v116, 16, v116
	v_add_f32_e32 v140, v116, v112
	v_add_f32_e32 v141, v117, v113
	v_add_f32_e32 v142, v118, v114
	v_add_f32_e32 v143, v119, v115
	v_add_f32_e32 v140, v140, v108
	v_add_f32_e32 v141, v141, v109
	v_add_f32_e32 v142, v142, v110
	v_add_f32_e32 v143, v143, v111
	v_add_f32_e32 v140, v140, v104
	v_add_f32_e32 v141, v141, v105
	v_add_f32_e32 v142, v142, v106
	v_add_f32_e32 v143, v143, v107
	v_add_f32_e32 v140, v140, v100
	v_add_f32_e32 v141, v141, v101
	v_add_f32_e32 v142, v142, v102
	v_add_f32_e32 v143, v143, v103
	v_add_f32_e32 v140, v140, v96
	v_add_f32_e32 v141, v141, v97
	v_add_f32_e32 v142, v142, v98
	v_add_f32_e32 v143, v143, v99
	v_add_f32_e32 v140, v140, v92
	v_add_f32_e32 v141, v141, v93
	v_add_f32_e32 v142, v142, v94
	v_add_f32_e32 v143, v143, v95
	v_add_f32_e32 v140, v140, v88
	v_add_f32_e32 v141, v141, v89
	v_add_f32_e32 v142, v142, v90
	v_add_f32_e32 v143, v143, v91
	v_add_f32_e32 v140, v140, v84
	v_add_f32_e32 v141, v141, v85
	v_add_f32_e32 v142, v142, v86
	v_add_f32_e32 v143, v143, v87
	v_add_f32_e32 v140, v140, v80
	v_add_f32_e32 v141, v141, v81
	v_add_f32_e32 v142, v142, v82
	v_add_f32_e32 v143, v143, v83
	v_add_f32_e32 v140, v140, v76
	v_add_f32_e32 v141, v141, v77
	v_add_f32_e32 v142, v142, v78
	v_add_f32_e32 v143, v143, v79
	v_add_f32_e32 v140, v140, v72
	v_add_f32_e32 v141, v141, v73
	v_add_f32_e32 v142, v142, v74
	v_add_f32_e32 v143, v143, v75
	v_add_f32_e32 v140, v140, v68
	v_add_f32_e32 v141, v141, v69
	v_add_f32_e32 v142, v142, v70
	v_add_f32_e32 v143, v143, v71
	v_add_f32_e32 v140, v140, v64
	v_add_f32_e32 v141, v141, v65
	v_add_f32_e32 v142, v142, v66
	v_add_f32_e32 v143, v143, v67
	v_add_f32_e32 v140, v140, v60
	v_add_f32_e32 v141, v141, v61
	v_add_f32_e32 v142, v142, v62
	v_add_f32_e32 v143, v143, v63
	v_add_f32_e32 v140, v140, v56
	v_add_f32_e32 v141, v141, v57
	v_add_f32_e32 v142, v142, v58
	v_add_f32_e32 v143, v143, v59
	v_mul_f32_e32 v140, 0x3d800000, v140
	v_mul_f32_e32 v141, 0x3d800000, v141
	v_mul_f32_e32 v142, 0x3d800000, v142
	v_mul_f32_e32 v143, 0x3d800000, v143
	v_sub_f32_e32 v140, v140, v116
	v_sub_f32_e32 v141, v141, v117
	v_sub_f32_e32 v142, v142, v118
	v_sub_f32_e32 v143, v143, v119
	v_cvt_pk_bf16_f32 v172, v140, v141
	v_cvt_pk_bf16_f32 v173, v142, v143
	s_waitcnt vmcnt(4)
; DI float bflo(unsigned u) { return __uint_as_float(u << 16); }
; DI float bfhi(unsigned u) { return __uint_as_float(u & 0xffff0000u); }
; template <int WIN>
; DI void pool_elem(const Params& p, int row, int c) {
;     ...
;       for (int j = 1; j < WIN; ++j) w[j - 1] = *(const unsigned*)(P2 + (size_t)(row - j) * 2048 + c);
; #pragma unroll
;       for (int j = 1; j < WIN; ++j) { s0 += bflo(w[j - 1]); s1 += bfhi(w[j - 1]); }
;     ...
;   *(unsigned*)(p.MIX + (size_t)row * 1024 + c) = pack2(s0 / cnt - u0, s1 / cnt - u1);
	v_and_b32_e32 v123, 0xffff0000, v121
	v_lshlrev_b32_e32 v122, 16, v121
	v_and_b32_e32 v121, 0xffff0000, v120
	v_lshlrev_b32_e32 v120, 16, v120
	v_add_f32_e32 v140, v120, v116
	v_add_f32_e32 v141, v121, v117
	v_add_f32_e32 v142, v122, v118
	v_add_f32_e32 v143, v123, v119
	v_add_f32_e32 v140, v140, v112
	v_add_f32_e32 v141, v141, v113
	v_add_f32_e32 v142, v142, v114
	v_add_f32_e32 v143, v143, v115
	v_add_f32_e32 v140, v140, v108
	v_add_f32_e32 v141, v141, v109
	v_add_f32_e32 v142, v142, v110
	v_add_f32_e32 v143, v143, v111
	v_add_f32_e32 v140, v140, v104
	v_add_f32_e32 v141, v141, v105
	v_add_f32_e32 v142, v142, v106
	v_add_f32_e32 v143, v143, v107
	v_add_f32_e32 v140, v140, v100
	v_add_f32_e32 v141, v141, v101
	v_add_f32_e32 v142, v142, v102
	v_add_f32_e32 v143, v143, v103
	v_add_f32_e32 v140, v140, v96
	v_add_f32_e32 v141, v141, v97
	v_add_f32_e32 v142, v142, v98
	v_add_f32_e32 v143, v143, v99
	v_add_f32_e32 v140, v140, v92
	v_add_f32_e32 v141, v141, v93
	v_add_f32_e32 v142, v142, v94
	v_add_f32_e32 v143, v143, v95
	v_add_f32_e32 v140, v140, v88
	v_add_f32_e32 v141, v141, v89
	v_add_f32_e32 v142, v142, v90
	v_add_f32_e32 v143, v143, v91
	v_add_f32_e32 v140, v140, v84
	v_add_f32_e32 v141, v141, v85
	v_add_f32_e32 v142, v142, v86
	v_add_f32_e32 v143, v143, v87
	v_add_f32_e32 v140, v140, v80
	v_add_f32_e32 v141, v141, v81
	v_add_f32_e32 v142, v142, v82
	v_add_f32_e32 v143, v143, v83
	v_add_f32_e32 v140, v140, v76
	v_add_f32_e32 v141, v141, v77
	v_add_f32_e32 v142, v142, v78
	v_add_f32_e32 v143, v143, v79
	v_add_f32_e32 v140, v140, v72
	v_add_f32_e32 v141, v141, v73
	v_add_f32_e32 v142, v142, v74
	v_add_f32_e32 v143, v143, v75
	v_add_f32_e32 v140, v140, v68
	v_add_f32_e32 v141, v141, v69
	v_add_f32_e32 v142, v142, v70
	v_add_f32_e32 v143, v143, v71
	v_add_f32_e32 v140, v140, v64
	v_add_f32_e32 v141, v141, v65
	v_add_f32_e32 v142, v142, v66
	v_add_f32_e32 v143, v143, v67
	v_add_f32_e32 v140, v140, v60
	v_add_f32_e32 v141, v141, v61
	v_add_f32_e32 v142, v142, v62
	v_add_f32_e32 v143, v143, v63
	v_mul_f32_e32 v140, 0x3d800000, v140
	v_mul_f32_e32 v141, 0x3d800000, v141
	v_mul_f32_e32 v142, 0x3d800000, v142
	v_mul_f32_e32 v143, 0x3d800000, v143
	v_sub_f32_e32 v140, v140, v120
	v_sub_f32_e32 v141, v141, v121
	v_sub_f32_e32 v142, v142, v122
	v_sub_f32_e32 v143, v143, v123
	v_cvt_pk_bf16_f32 v174, v140, v141
	v_cvt_pk_bf16_f32 v175, v142, v143
	s_waitcnt vmcnt(3)
	v_and_b32_e32 v127, 0xffff0000, v125
	v_lshlrev_b32_e32 v126, 16, v125
	v_and_b32_e32 v125, 0xffff0000, v124
	v_lshlrev_b32_e32 v124, 16, v124
	v_add_f32_e32 v140, v124, v120
	v_add_f32_e32 v141, v125, v121
	v_add_f32_e32 v142, v126, v122
	v_add_f32_e32 v143, v127, v123
	v_add_f32_e32 v140, v140, v116
	v_add_f32_e32 v141, v141, v117
	v_add_f32_e32 v142, v142, v118
	v_add_f32_e32 v143, v143, v119
	v_add_f32_e32 v140, v140, v112
	v_add_f32_e32 v141, v141, v113
	v_add_f32_e32 v142, v142, v114
	v_add_f32_e32 v143, v143, v115
	v_add_f32_e32 v140, v140, v108
	v_add_f32_e32 v141, v141, v109
	v_add_f32_e32 v142, v142, v110
	v_add_f32_e32 v143, v143, v111
	v_add_f32_e32 v140, v140, v104
	v_add_f32_e32 v141, v141, v105
	v_add_f32_e32 v142, v142, v106
	v_add_f32_e32 v143, v143, v107
	v_add_f32_e32 v140, v140, v100
	v_add_f32_e32 v141, v141, v101
	v_add_f32_e32 v142, v142, v102
	v_add_f32_e32 v143, v143, v103
	v_add_f32_e32 v140, v140, v96
	v_add_f32_e32 v141, v141, v97
	v_add_f32_e32 v142, v142, v98
	v_add_f32_e32 v143, v143, v99
	v_add_f32_e32 v140, v140, v92
	v_add_f32_e32 v141, v141, v93
	v_add_f32_e32 v142, v142, v94
	v_add_f32_e32 v143, v143, v95
	v_add_f32_e32 v140, v140, v88
	v_add_f32_e32 v141, v141, v89
	v_add_f32_e32 v142, v142, v90
	v_add_f32_e32 v143, v143, v91
	v_add_f32_e32 v140, v140, v84
	v_add_f32_e32 v141, v141, v85
	v_add_f32_e32 v142, v142, v86
	v_add_f32_e32 v143, v143, v87
	v_add_f32_e32 v140, v140, v80
	v_add_f32_e32 v141, v141, v81
	v_add_f32_e32 v142, v142, v82
	v_add_f32_e32 v143, v143, v83
	v_add_f32_e32 v140, v140, v76
	v_add_f32_e32 v141, v141, v77
	v_add_f32_e32 v142, v142, v78
	v_add_f32_e32 v143, v143, v79
	v_add_f32_e32 v140, v140, v72
	v_add_f32_e32 v141, v141, v73
	v_add_f32_e32 v142, v142, v74
	v_add_f32_e32 v143, v143, v75
	v_add_f32_e32 v140, v140, v68
	v_add_f32_e32 v141, v141, v69
	v_add_f32_e32 v142, v142, v70
	v_add_f32_e32 v143, v143, v71
	v_add_f32_e32 v140, v140, v64
	v_add_f32_e32 v141, v141, v65
	v_add_f32_e32 v142, v142, v66
	v_add_f32_e32 v143, v143, v67
	v_mul_f32_e32 v140, 0x3d800000, v140
	v_mul_f32_e32 v141, 0x3d800000, v141
	v_mul_f32_e32 v142, 0x3d800000, v142
	v_mul_f32_e32 v143, 0x3d800000, v143
	v_sub_f32_e32 v140, v140, v124
	v_sub_f32_e32 v141, v141, v125
	v_sub_f32_e32 v142, v142, v126
	v_sub_f32_e32 v143, v143, v127
	v_cvt_pk_bf16_f32 v176, v140, v141
	v_cvt_pk_bf16_f32 v177, v142, v143
	s_waitcnt vmcnt(2)
; DI float bflo(unsigned u) { return __uint_as_float(u << 16); }
; DI float bfhi(unsigned u) { return __uint_as_float(u & 0xffff0000u); }
; template <int WIN>
; DI void pool_elem(const Params& p, int row, int c) {
;     ...
;       for (int j = 1; j < WIN; ++j) w[j - 1] = *(const unsigned*)(P2 + (size_t)(row - j) * 2048 + c);
; #pragma unroll
;       for (int j = 1; j < WIN; ++j) { s0 += bflo(w[j - 1]); s1 += bfhi(w[j - 1]); }
;     ...
;   *(unsigned*)(p.MIX + (size_t)row * 1024 + c) = pack2(s0 / cnt - u0, s1 / cnt - u1);
	v_and_b32_e32 v131, 0xffff0000, v129
	v_lshlrev_b32_e32 v130, 16, v129
	v_and_b32_e32 v129, 0xffff0000, v128
	v_lshlrev_b32_e32 v128, 16, v128
	v_add_f32_e32 v140, v128, v124
	v_add_f32_e32 v141, v129, v125
	v_add_f32_e32 v142, v130, v126
	v_add_f32_e32 v143, v131, v127
	v_add_f32_e32 v140, v140, v120
	v_add_f32_e32 v141, v141, v121
	v_add_f32_e32 v142, v142, v122
	v_add_f32_e32 v143, v143, v123
	v_add_f32_e32 v140, v140, v116
	v_add_f32_e32 v141, v141, v117
	v_add_f32_e32 v142, v142, v118
	v_add_f32_e32 v143, v143, v119
	v_add_f32_e32 v140, v140, v112
	v_add_f32_e32 v141, v141, v113
	v_add_f32_e32 v142, v142, v114
	v_add_f32_e32 v143, v143, v115
	v_add_f32_e32 v140, v140, v108
	v_add_f32_e32 v141, v141, v109
	v_add_f32_e32 v142, v142, v110
	v_add_f32_e32 v143, v143, v111
	v_add_f32_e32 v140, v140, v104
	v_add_f32_e32 v141, v141, v105
	v_add_f32_e32 v142, v142, v106
	v_add_f32_e32 v143, v143, v107
	v_add_f32_e32 v140, v140, v100
	v_add_f32_e32 v141, v141, v101
	v_add_f32_e32 v142, v142, v102
	v_add_f32_e32 v143, v143, v103
	v_add_f32_e32 v140, v140, v96
	v_add_f32_e32 v141, v141, v97
	v_add_f32_e32 v142, v142, v98
	v_add_f32_e32 v143, v143, v99
	v_add_f32_e32 v140, v140, v92
	v_add_f32_e32 v141, v141, v93
	v_add_f32_e32 v142, v142, v94
	v_add_f32_e32 v143, v143, v95
	v_add_f32_e32 v140, v140, v88
	v_add_f32_e32 v141, v141, v89
	v_add_f32_e32 v142, v142, v90
	v_add_f32_e32 v143, v143, v91
	v_add_f32_e32 v140, v140, v84
	v_add_f32_e32 v141, v141, v85
	v_add_f32_e32 v142, v142, v86
	v_add_f32_e32 v143, v143, v87
	v_add_f32_e32 v140, v140, v80
	v_add_f32_e32 v141, v141, v81
	v_add_f32_e32 v142, v142, v82
	v_add_f32_e32 v143, v143, v83
	v_add_f32_e32 v140, v140, v76
	v_add_f32_e32 v141, v141, v77
	v_add_f32_e32 v142, v142, v78
	v_add_f32_e32 v143, v143, v79
	v_add_f32_e32 v140, v140, v72
	v_add_f32_e32 v141, v141, v73
	v_add_f32_e32 v142, v142, v74
	v_add_f32_e32 v143, v143, v75
	v_add_f32_e32 v140, v140, v68
	v_add_f32_e32 v141, v141, v69
	v_add_f32_e32 v142, v142, v70
	v_add_f32_e32 v143, v143, v71
	v_mul_f32_e32 v140, 0x3d800000, v140
	v_mul_f32_e32 v141, 0x3d800000, v141
	v_mul_f32_e32 v142, 0x3d800000, v142
	v_mul_f32_e32 v143, 0x3d800000, v143
	v_sub_f32_e32 v140, v140, v128
	v_sub_f32_e32 v141, v141, v129
	v_sub_f32_e32 v142, v142, v130
	v_sub_f32_e32 v143, v143, v131
	v_cvt_pk_bf16_f32 v178, v140, v141
	v_cvt_pk_bf16_f32 v179, v142, v143
	s_waitcnt vmcnt(1)
	v_and_b32_e32 v135, 0xffff0000, v133
	v_lshlrev_b32_e32 v134, 16, v133
	v_and_b32_e32 v133, 0xffff0000, v132
	v_lshlrev_b32_e32 v132, 16, v132
	v_add_f32_e32 v140, v132, v128
	v_add_f32_e32 v141, v133, v129
	v_add_f32_e32 v142, v134, v130
	v_add_f32_e32 v143, v135, v131
	v_add_f32_e32 v140, v140, v124
	v_add_f32_e32 v141, v141, v125
	v_add_f32_e32 v142, v142, v126
	v_add_f32_e32 v143, v143, v127
	v_add_f32_e32 v140, v140, v120
	v_add_f32_e32 v141, v141, v121
	v_add_f32_e32 v142, v142, v122
	v_add_f32_e32 v143, v143, v123
	v_add_f32_e32 v140, v140, v116
	v_add_f32_e32 v141, v141, v117
	v_add_f32_e32 v142, v142, v118
	v_add_f32_e32 v143, v143, v119
	v_add_f32_e32 v140, v140, v112
	v_add_f32_e32 v141, v141, v113
	v_add_f32_e32 v142, v142, v114
	v_add_f32_e32 v143, v143, v115
	v_add_f32_e32 v140, v140, v108
	v_add_f32_e32 v141, v141, v109
	v_add_f32_e32 v142, v142, v110
	v_add_f32_e32 v143, v143, v111
	v_add_f32_e32 v140, v140, v104
	v_add_f32_e32 v141, v141, v105
	v_add_f32_e32 v142, v142, v106
	v_add_f32_e32 v143, v143, v107
	v_add_f32_e32 v140, v140, v100
	v_add_f32_e32 v141, v141, v101
	v_add_f32_e32 v142, v142, v102
	v_add_f32_e32 v143, v143, v103
	v_add_f32_e32 v140, v140, v96
	v_add_f32_e32 v141, v141, v97
	v_add_f32_e32 v142, v142, v98
	v_add_f32_e32 v143, v143, v99
	v_add_f32_e32 v140, v140, v92
	v_add_f32_e32 v141, v141, v93
	v_add_f32_e32 v142, v142, v94
	v_add_f32_e32 v143, v143, v95
	v_add_f32_e32 v140, v140, v88
	v_add_f32_e32 v141, v141, v89
	v_add_f32_e32 v142, v142, v90
	v_add_f32_e32 v143, v143, v91
	v_add_f32_e32 v140, v140, v84
	v_add_f32_e32 v141, v141, v85
	v_add_f32_e32 v142, v142, v86
	v_add_f32_e32 v143, v143, v87
	v_add_f32_e32 v140, v140, v80
	v_add_f32_e32 v141, v141, v81
	v_add_f32_e32 v142, v142, v82
	v_add_f32_e32 v143, v143, v83
	v_add_f32_e32 v140, v140, v76
	v_add_f32_e32 v141, v141, v77
	v_add_f32_e32 v142, v142, v78
	v_add_f32_e32 v143, v143, v79
	v_add_f32_e32 v140, v140, v72
	v_add_f32_e32 v141, v141, v73
	v_add_f32_e32 v142, v142, v74
	v_add_f32_e32 v143, v143, v75
	v_mul_f32_e32 v140, 0x3d800000, v140
	v_mul_f32_e32 v141, 0x3d800000, v141
	v_mul_f32_e32 v142, 0x3d800000, v142
	v_mul_f32_e32 v143, 0x3d800000, v143
	v_sub_f32_e32 v140, v140, v132
	v_sub_f32_e32 v141, v141, v133
	v_sub_f32_e32 v142, v142, v134
	v_sub_f32_e32 v143, v143, v135
	v_cvt_pk_bf16_f32 v180, v140, v141
	v_cvt_pk_bf16_f32 v181, v142, v143
	s_waitcnt vmcnt(0)
; DI float bflo(unsigned u) { return __uint_as_float(u << 16); }
; DI float bfhi(unsigned u) { return __uint_as_float(u & 0xffff0000u); }
; template <int WIN>
; DI void pool_elem(const Params& p, int row, int c) {
;     ...
;       for (int j = 1; j < WIN; ++j) w[j - 1] = *(const unsigned*)(P2 + (size_t)(row - j) * 2048 + c);
; #pragma unroll
;       for (int j = 1; j < WIN; ++j) { s0 += bflo(w[j - 1]); s1 += bfhi(w[j - 1]); }
;     } else {
;       cnt = (float)(t + 1);
;       for (int j = 1; j <= t; ++j) {
;         unsigned w = *(const unsigned*)(P2 + (size_t)(row - j) * 2048 + c);
;         s0 += bflo(w); s1 += bfhi(w);
;       }
;     }
;     if (t >= 2033) {
;       float2 o = {u0, u1};
;       *(float2*)(p.out + O_POOLP + ((size_t)b * 15 + (t - 2033)) * 1024 + c) = o;
;     }
;     ...
;   *(unsigned*)(p.MIX + (size_t)row * 1024 + c) = pack2(s0 / cnt - u0, s1 / cnt - u1);
	v_and_b32_e32 v139, 0xffff0000, v137
	v_lshlrev_b32_e32 v138, 16, v137
	v_and_b32_e32 v137, 0xffff0000, v136
	v_lshlrev_b32_e32 v136, 16, v136
	v_add_f32_e32 v140, v136, v132
	v_add_f32_e32 v141, v137, v133
	v_add_f32_e32 v142, v138, v134
	v_add_f32_e32 v143, v139, v135
	v_add_f32_e32 v140, v140, v128
	v_add_f32_e32 v141, v141, v129
	v_add_f32_e32 v142, v142, v130
	v_add_f32_e32 v143, v143, v131
	v_add_f32_e32 v140, v140, v124
	v_add_f32_e32 v141, v141, v125
	v_add_f32_e32 v142, v142, v126
	v_add_f32_e32 v143, v143, v127
	v_add_f32_e32 v140, v140, v120
	v_add_f32_e32 v141, v141, v121
	v_add_f32_e32 v142, v142, v122
	v_add_f32_e32 v143, v143, v123
	v_add_f32_e32 v140, v140, v116
	v_add_f32_e32 v141, v141, v117
	v_add_f32_e32 v142, v142, v118
	v_add_f32_e32 v143, v143, v119
	v_add_f32_e32 v140, v140, v112
	v_add_f32_e32 v141, v141, v113
	v_add_f32_e32 v142, v142, v114
	v_add_f32_e32 v143, v143, v115
	v_add_f32_e32 v140, v140, v108
	v_add_f32_e32 v141, v141, v109
	v_add_f32_e32 v142, v142, v110
	v_add_f32_e32 v143, v143, v111
	v_add_f32_e32 v140, v140, v104
	v_add_f32_e32 v141, v141, v105
	v_add_f32_e32 v142, v142, v106
	v_add_f32_e32 v143, v143, v107
	v_add_f32_e32 v140, v140, v100
	v_add_f32_e32 v141, v141, v101
	v_add_f32_e32 v142, v142, v102
	v_add_f32_e32 v143, v143, v103
	v_add_f32_e32 v140, v140, v96
	v_add_f32_e32 v141, v141, v97
	v_add_f32_e32 v142, v142, v98
	v_add_f32_e32 v143, v143, v99
	v_add_f32_e32 v140, v140, v92
	v_add_f32_e32 v141, v141, v93
	v_add_f32_e32 v142, v142, v94
	v_add_f32_e32 v143, v143, v95
	v_add_f32_e32 v140, v140, v88
	v_add_f32_e32 v141, v141, v89
	v_add_f32_e32 v142, v142, v90
	v_add_f32_e32 v143, v143, v91
	v_add_f32_e32 v140, v140, v84
	v_add_f32_e32 v141, v141, v85
	v_add_f32_e32 v142, v142, v86
	v_add_f32_e32 v143, v143, v87
	v_add_f32_e32 v140, v140, v80
	v_add_f32_e32 v141, v141, v81
	v_add_f32_e32 v142, v142, v82
	v_add_f32_e32 v143, v143, v83
	v_add_f32_e32 v140, v140, v76
	v_add_f32_e32 v141, v141, v77
	v_add_f32_e32 v142, v142, v78
	v_add_f32_e32 v143, v143, v79
	v_mul_f32_e32 v140, 0x3d800000, v140
	v_mul_f32_e32 v141, 0x3d800000, v141
	v_mul_f32_e32 v142, 0x3d800000, v142
	v_mul_f32_e32 v143, 0x3d800000, v143
	v_sub_f32_e32 v140, v140, v136
	v_sub_f32_e32 v141, v141, v137
	v_sub_f32_e32 v142, v142, v138
	v_sub_f32_e32 v143, v143, v139
	v_cvt_pk_bf16_f32 v182, v140, v141
	v_cvt_pk_bf16_f32 v183, v142, v143
	global_store_dwordx2 v11, v[152:153], s[24:25] sc1
	s_add_u32 s24, s24, 0x800
	s_addc_u32 s25, s25, 0
	global_store_dwordx2 v11, v[154:155], s[24:25] sc1
	s_add_u32 s24, s24, 0x800
	s_addc_u32 s25, s25, 0
	global_store_dwordx2 v11, v[156:157], s[24:25] sc1
	s_add_u32 s24, s24, 0x800
	s_addc_u32 s25, s25, 0
	global_store_dwordx2 v11, v[158:159], s[24:25] sc1
	s_add_u32 s24, s24, 0x800
	s_addc_u32 s25, s25, 0
	global_store_dwordx2 v11, v[160:161], s[24:25] sc1
	s_add_u32 s24, s24, 0x800
	s_addc_u32 s25, s25, 0
	global_store_dwordx2 v11, v[162:163], s[24:25] sc1
	s_add_u32 s24, s24, 0x800
	s_addc_u32 s25, s25, 0
	global_store_dwordx2 v11, v[164:165], s[24:25] sc1
	s_add_u32 s24, s24, 0x800
	s_addc_u32 s25, s25, 0
	global_store_dwordx2 v11, v[166:167], s[24:25] sc1
	s_add_u32 s24, s24, 0x800
	s_addc_u32 s25, s25, 0
	global_store_dwordx2 v11, v[168:169], s[24:25] sc1
	s_add_u32 s24, s24, 0x800
	s_addc_u32 s25, s25, 0
	global_store_dwordx2 v11, v[170:171], s[24:25] sc1
	s_add_u32 s24, s24, 0x800
	s_addc_u32 s25, s25, 0
	global_store_dwordx2 v11, v[172:173], s[24:25] sc1
	s_add_u32 s24, s24, 0x800
	s_addc_u32 s25, s25, 0
	global_store_dwordx2 v11, v[174:175], s[24:25] sc1
	s_add_u32 s24, s24, 0x800
	s_addc_u32 s25, s25, 0
	global_store_dwordx2 v11, v[176:177], s[24:25] sc1
	s_add_u32 s24, s24, 0x800
	s_addc_u32 s25, s25, 0
	global_store_dwordx2 v11, v[178:179], s[24:25] sc1
	s_add_u32 s24, s24, 0x800
	s_addc_u32 s25, s25, 0
	global_store_dwordx2 v11, v[180:181], s[24:25] sc1
	s_add_u32 s24, s24, 0x800
	s_addc_u32 s25, s25, 0
	global_store_dwordx2 v11, v[182:183], s[24:25] sc1
	s_add_u32 s24, s24, 0x800
	s_addc_u32 s25, s25, 0
	s_cmp_eq_u32 s18, 127
	s_cbranch_scc0 .Lp13f_next
	s_mul_i32 s26, s17, 61440
	s_add_u32 s26, s26, 0x431c000
	s_add_u32 s22, s12, s26
	s_addc_u32 s23, s13, 0
	global_store_dwordx4 v12, v[80:83], s[22:23] sc1
	s_add_u32 s22, s22, 0x1000
	s_addc_u32 s23, s23, 0
	global_store_dwordx4 v12, v[84:87], s[22:23] sc1
	s_add_u32 s22, s22, 0x1000
	s_addc_u32 s23, s23, 0
	global_store_dwordx4 v12, v[88:91], s[22:23] sc1
	s_add_u32 s22, s22, 0x1000
	s_addc_u32 s23, s23, 0
	global_store_dwordx4 v12, v[92:95], s[22:23] sc1
	s_add_u32 s22, s22, 0x1000
	s_addc_u32 s23, s23, 0
	global_store_dwordx4 v12, v[96:99], s[22:23] sc1
	s_add_u32 s22, s22, 0x1000
	s_addc_u32 s23, s23, 0
	global_store_dwordx4 v12, v[100:103], s[22:23] sc1
	s_add_u32 s22, s22, 0x1000
	s_addc_u32 s23, s23, 0
	global_store_dwordx4 v12, v[104:107], s[22:23] sc1
	s_add_u32 s22, s22, 0x1000
	s_addc_u32 s23, s23, 0
	global_store_dwordx4 v12, v[108:111], s[22:23] sc1
	s_add_u32 s22, s22, 0x1000
	s_addc_u32 s23, s23, 0
	global_store_dwordx4 v12, v[112:115], s[22:23] sc1
	s_add_u32 s22, s22, 0x1000
	s_addc_u32 s23, s23, 0
	global_store_dwordx4 v12, v[116:119], s[22:23] sc1
	s_add_u32 s22, s22, 0x1000
	s_addc_u32 s23, s23, 0
	global_store_dwordx4 v12, v[120:123], s[22:23] sc1
	s_add_u32 s22, s22, 0x1000
	s_addc_u32 s23, s23, 0
	global_store_dwordx4 v12, v[124:127], s[22:23] sc1
	s_add_u32 s22, s22, 0x1000
	s_addc_u32 s23, s23, 0
	global_store_dwordx4 v12, v[128:131], s[22:23] sc1
	s_add_u32 s22, s22, 0x1000
	s_addc_u32 s23, s23, 0
	global_store_dwordx4 v12, v[132:135], s[22:23] sc1
	s_add_u32 s22, s22, 0x1000
	s_addc_u32 s23, s23, 0
	global_store_dwordx4 v12, v[136:139], s[22:23] sc1
	s_add_u32 s22, s22, 0x1000
	s_addc_u32 s23, s23, 0
	s_branch .Lp13f_next
; DI float bflo(unsigned u) { return __uint_as_float(u << 16); }
; DI float bfhi(unsigned u) { return __uint_as_float(u & 0xffff0000u); }
; template <int WIN>
; DI void pool_elem(const Params& p, int row, int c) {
;     ...
;     } else {
;       cnt = (float)(t + 1);
;       for (int j = 1; j <= t; ++j) {
;         unsigned w = *(const unsigned*)(P2 + (size_t)(row - j) * 2048 + c);
;         s0 += bflo(w); s1 += bfhi(w);
;       }
;     ...
;   *(unsigned*)(p.MIX + (size_t)row * 1024 + c) = pack2(s0 / cnt - u0, s1 / cnt - u1);
.Lp13f_f0:
	s_sub_u32 s26, s20, 0
	s_lshl_b32 s27, s26, 12
	s_lshr_b32 s28, s26, 20
	s_add_u32 s22, s8, s27
	s_addc_u32 s23, s9, s28
	global_load_dwordx2 v[16:17], v11, s[22:23]
	s_add_u32 s22, s22, 0x1000
	s_addc_u32 s23, s23, 0
	global_load_dwordx2 v[20:21], v11, s[22:23]
	s_add_u32 s22, s22, 0x1000
	s_addc_u32 s23, s23, 0
	global_load_dwordx2 v[24:25], v11, s[22:23]
	s_add_u32 s22, s22, 0x1000
	s_addc_u32 s23, s23, 0
	global_load_dwordx2 v[28:29], v11, s[22:23]
	s_add_u32 s22, s22, 0x1000
	s_addc_u32 s23, s23, 0
	global_load_dwordx2 v[32:33], v11, s[22:23]
	s_add_u32 s22, s22, 0x1000
	s_addc_u32 s23, s23, 0
	global_load_dwordx2 v[36:37], v11, s[22:23]
	s_add_u32 s22, s22, 0x1000
	s_addc_u32 s23, s23, 0
	global_load_dwordx2 v[40:41], v11, s[22:23]
	s_add_u32 s22, s22, 0x1000
	s_addc_u32 s23, s23, 0
	global_load_dwordx2 v[44:45], v11, s[22:23]
	s_add_u32 s22, s22, 0x1000
	s_addc_u32 s23, s23, 0
	global_load_dwordx2 v[48:49], v11, s[22:23]
	s_add_u32 s22, s22, 0x1000
	s_addc_u32 s23, s23, 0
	global_load_dwordx2 v[52:53], v11, s[22:23]
	s_add_u32 s22, s22, 0x1000
	s_addc_u32 s23, s23, 0
	global_load_dwordx2 v[56:57], v11, s[22:23]
	s_add_u32 s22, s22, 0x1000
	s_addc_u32 s23, s23, 0
	global_load_dwordx2 v[60:61], v11, s[22:23]
	s_add_u32 s22, s22, 0x1000
	s_addc_u32 s23, s23, 0
	global_load_dwordx2 v[64:65], v11, s[22:23]
	s_add_u32 s22, s22, 0x1000
	s_addc_u32 s23, s23, 0
	global_load_dwordx2 v[68:69], v11, s[22:23]
	s_add_u32 s22, s22, 0x1000
	s_addc_u32 s23, s23, 0
	global_load_dwordx2 v[72:73], v11, s[22:23]
	s_add_u32 s22, s22, 0x1000
	s_addc_u32 s23, s23, 0
	global_load_dwordx2 v[76:77], v11, s[22:23]
	s_add_u32 s22, s22, 0x1000
	s_addc_u32 s23, s23, 0
	s_waitcnt vmcnt(15)
	v_and_b32_e32 v19, 0xffff0000, v17
	v_lshlrev_b32_e32 v18, 16, v17
	v_and_b32_e32 v17, 0xffff0000, v16
	v_lshlrev_b32_e32 v16, 16, v16
	v_mov_b32_e32 v140, v16
	v_mov_b32_e32 v141, v17
	v_mov_b32_e32 v142, v18
	v_mov_b32_e32 v143, v19
	v_mul_f32_e32 v140, 1.0, v140
	v_mul_f32_e32 v141, 1.0, v141
	v_mul_f32_e32 v142, 1.0, v142
	v_mul_f32_e32 v143, 1.0, v143
	v_sub_f32_e32 v140, v140, v16
	v_sub_f32_e32 v141, v141, v17
	v_sub_f32_e32 v142, v142, v18
	v_sub_f32_e32 v143, v143, v19
	v_cvt_pk_bf16_f32 v152, v140, v141
	v_cvt_pk_bf16_f32 v153, v142, v143
	s_waitcnt vmcnt(14)
	v_and_b32_e32 v23, 0xffff0000, v21
	v_lshlrev_b32_e32 v22, 16, v21
	v_and_b32_e32 v21, 0xffff0000, v20
	v_lshlrev_b32_e32 v20, 16, v20
	v_add_f32_e32 v140, v20, v16
	v_add_f32_e32 v141, v21, v17
	v_add_f32_e32 v142, v22, v18
	v_add_f32_e32 v143, v23, v19
	v_mul_f32_e32 v140, 0.5, v140
	v_mul_f32_e32 v141, 0.5, v141
	v_mul_f32_e32 v142, 0.5, v142
	v_mul_f32_e32 v143, 0.5, v143
	v_sub_f32_e32 v140, v140, v20
	v_sub_f32_e32 v141, v141, v21
	v_sub_f32_e32 v142, v142, v22
	v_sub_f32_e32 v143, v143, v23
	v_cvt_pk_bf16_f32 v154, v140, v141
	v_cvt_pk_bf16_f32 v155, v142, v143
	s_waitcnt vmcnt(13)
	v_and_b32_e32 v27, 0xffff0000, v25
	v_lshlrev_b32_e32 v26, 16, v25
	v_and_b32_e32 v25, 0xffff0000, v24
	v_lshlrev_b32_e32 v24, 16, v24
	v_add_f32_e32 v140, v24, v20
	v_add_f32_e32 v141, v25, v21
	v_add_f32_e32 v142, v26, v22
	v_add_f32_e32 v143, v27, v23
	v_mul_f32_e32 v140, 0.5, v140
	v_mul_f32_e32 v141, 0.5, v141
	v_mul_f32_e32 v142, 0.5, v142
	v_mul_f32_e32 v143, 0.5, v143
	v_sub_f32_e32 v140, v140, v24
	v_sub_f32_e32 v141, v141, v25
	v_sub_f32_e32 v142, v142, v26
	v_sub_f32_e32 v143, v143, v27
	v_cvt_pk_bf16_f32 v156, v140, v141
	v_cvt_pk_bf16_f32 v157, v142, v143
	s_waitcnt vmcnt(12)
	v_and_b32_e32 v31, 0xffff0000, v29
	v_lshlrev_b32_e32 v30, 16, v29
	v_and_b32_e32 v29, 0xffff0000, v28
	v_lshlrev_b32_e32 v28, 16, v28
	v_add_f32_e32 v140, v28, v24
	v_add_f32_e32 v141, v29, v25
	v_add_f32_e32 v142, v30, v26
	v_add_f32_e32 v143, v31, v27
	v_mul_f32_e32 v140, 0.5, v140
	v_mul_f32_e32 v141, 0.5, v141
	v_mul_f32_e32 v142, 0.5, v142
	v_mul_f32_e32 v143, 0.5, v143
	v_sub_f32_e32 v140, v140, v28
	v_sub_f32_e32 v141, v141, v29
	v_sub_f32_e32 v142, v142, v30
	v_sub_f32_e32 v143, v143, v31
	v_cvt_pk_bf16_f32 v158, v140, v141
	v_cvt_pk_bf16_f32 v159, v142, v143
	s_waitcnt vmcnt(11)
	v_and_b32_e32 v35, 0xffff0000, v33
	v_lshlrev_b32_e32 v34, 16, v33
	v_and_b32_e32 v33, 0xffff0000, v32
	v_lshlrev_b32_e32 v32, 16, v32
	v_add_f32_e32 v140, v32, v28
	v_add_f32_e32 v141, v33, v29
	v_add_f32_e32 v142, v34, v30
	v_add_f32_e32 v143, v35, v31
	v_mul_f32_e32 v140, 0.5, v140
	v_mul_f32_e32 v141, 0.5, v141
	v_mul_f32_e32 v142, 0.5, v142
	v_mul_f32_e32 v143, 0.5, v143
	v_sub_f32_e32 v140, v140, v32
	v_sub_f32_e32 v141, v141, v33
	v_sub_f32_e32 v142, v142, v34
	v_sub_f32_e32 v143, v143, v35
	v_cvt_pk_bf16_f32 v160, v140, v141
	v_cvt_pk_bf16_f32 v161, v142, v143
	s_waitcnt vmcnt(10)
	v_and_b32_e32 v39, 0xffff0000, v37
	v_lshlrev_b32_e32 v38, 16, v37
	v_and_b32_e32 v37, 0xffff0000, v36
	v_lshlrev_b32_e32 v36, 16, v36
	v_add_f32_e32 v140, v36, v32
	v_add_f32_e32 v141, v37, v33
	v_add_f32_e32 v142, v38, v34
	v_add_f32_e32 v143, v39, v35
	v_mul_f32_e32 v140, 0.5, v140
	v_mul_f32_e32 v141, 0.5, v141
	v_mul_f32_e32 v142, 0.5, v142
	v_mul_f32_e32 v143, 0.5, v143
	v_sub_f32_e32 v140, v140, v36
	v_sub_f32_e32 v141, v141, v37
	v_sub_f32_e32 v142, v142, v38
	v_sub_f32_e32 v143, v143, v39
	v_cvt_pk_bf16_f32 v162, v140, v141
	v_cvt_pk_bf16_f32 v163, v142, v143
	s_waitcnt vmcnt(9)
	v_and_b32_e32 v43, 0xffff0000, v41
	v_lshlrev_b32_e32 v42, 16, v41
	v_and_b32_e32 v41, 0xffff0000, v40
	v_lshlrev_b32_e32 v40, 16, v40
	v_add_f32_e32 v140, v40, v36
	v_add_f32_e32 v141, v41, v37
	v_add_f32_e32 v142, v42, v38
	v_add_f32_e32 v143, v43, v39
	v_mul_f32_e32 v140, 0.5, v140
	v_mul_f32_e32 v141, 0.5, v141
	v_mul_f32_e32 v142, 0.5, v142
	v_mul_f32_e32 v143, 0.5, v143
	v_sub_f32_e32 v140, v140, v40
	v_sub_f32_e32 v141, v141, v41
	v_sub_f32_e32 v142, v142, v42
	v_sub_f32_e32 v143, v143, v43
	v_cvt_pk_bf16_f32 v164, v140, v141
	v_cvt_pk_bf16_f32 v165, v142, v143
	s_waitcnt vmcnt(8)
; DI float bflo(unsigned u) { return __uint_as_float(u << 16); }
; DI float bfhi(unsigned u) { return __uint_as_float(u & 0xffff0000u); }
; template <int WIN>
; DI void pool_elem(const Params& p, int row, int c) {
;     ...
;     } else {
;       cnt = (float)(t + 1);
;       for (int j = 1; j <= t; ++j) {
;         unsigned w = *(const unsigned*)(P2 + (size_t)(row - j) * 2048 + c);
;         s0 += bflo(w); s1 += bfhi(w);
;       }
;     ...
;   *(unsigned*)(p.MIX + (size_t)row * 1024 + c) = pack2(s0 / cnt - u0, s1 / cnt - u1);
	v_and_b32_e32 v47, 0xffff0000, v45
	v_lshlrev_b32_e32 v46, 16, v45
	v_and_b32_e32 v45, 0xffff0000, v44
	v_lshlrev_b32_e32 v44, 16, v44
	v_add_f32_e32 v140, v44, v40
	v_add_f32_e32 v141, v45, v41
	v_add_f32_e32 v142, v46, v42
	v_add_f32_e32 v143, v47, v43
	v_mul_f32_e32 v140, 0.5, v140
	v_mul_f32_e32 v141, 0.5, v141
	v_mul_f32_e32 v142, 0.5, v142
	v_mul_f32_e32 v143, 0.5, v143
	v_sub_f32_e32 v140, v140, v44
	v_sub_f32_e32 v141, v141, v45
	v_sub_f32_e32 v142, v142, v46
	v_sub_f32_e32 v143, v143, v47
	v_cvt_pk_bf16_f32 v166, v140, v141
	v_cvt_pk_bf16_f32 v167, v142, v143
	s_waitcnt vmcnt(7)
	v_and_b32_e32 v51, 0xffff0000, v49
	v_lshlrev_b32_e32 v50, 16, v49
	v_and_b32_e32 v49, 0xffff0000, v48
	v_lshlrev_b32_e32 v48, 16, v48
	v_add_f32_e32 v140, v48, v44
	v_add_f32_e32 v141, v49, v45
	v_add_f32_e32 v142, v50, v46
	v_add_f32_e32 v143, v51, v47
	v_mul_f32_e32 v140, 0.5, v140
	v_mul_f32_e32 v141, 0.5, v141
	v_mul_f32_e32 v142, 0.5, v142
	v_mul_f32_e32 v143, 0.5, v143
	v_sub_f32_e32 v140, v140, v48
	v_sub_f32_e32 v141, v141, v49
	v_sub_f32_e32 v142, v142, v50
	v_sub_f32_e32 v143, v143, v51
	v_cvt_pk_bf16_f32 v168, v140, v141
	v_cvt_pk_bf16_f32 v169, v142, v143
	s_waitcnt vmcnt(6)
	v_and_b32_e32 v55, 0xffff0000, v53
	v_lshlrev_b32_e32 v54, 16, v53
	v_and_b32_e32 v53, 0xffff0000, v52
	v_lshlrev_b32_e32 v52, 16, v52
	v_add_f32_e32 v140, v52, v48
	v_add_f32_e32 v141, v53, v49
	v_add_f32_e32 v142, v54, v50
	v_add_f32_e32 v143, v55, v51
	v_mul_f32_e32 v140, 0.5, v140
	v_mul_f32_e32 v141, 0.5, v141
	v_mul_f32_e32 v142, 0.5, v142
	v_mul_f32_e32 v143, 0.5, v143
	v_sub_f32_e32 v140, v140, v52
	v_sub_f32_e32 v141, v141, v53
	v_sub_f32_e32 v142, v142, v54
	v_sub_f32_e32 v143, v143, v55
	v_cvt_pk_bf16_f32 v170, v140, v141
	v_cvt_pk_bf16_f32 v171, v142, v143
	s_waitcnt vmcnt(5)
	v_and_b32_e32 v59, 0xffff0000, v57
	v_lshlrev_b32_e32 v58, 16, v57
	v_and_b32_e32 v57, 0xffff0000, v56
	v_lshlrev_b32_e32 v56, 16, v56
	v_add_f32_e32 v140, v56, v52
	v_add_f32_e32 v141, v57, v53
	v_add_f32_e32 v142, v58, v54
	v_add_f32_e32 v143, v59, v55
	v_mul_f32_e32 v140, 0.5, v140
	v_mul_f32_e32 v141, 0.5, v141
	v_mul_f32_e32 v142, 0.5, v142
	v_mul_f32_e32 v143, 0.5, v143
	v_sub_f32_e32 v140, v140, v56
	v_sub_f32_e32 v141, v141, v57
	v_sub_f32_e32 v142, v142, v58
	v_sub_f32_e32 v143, v143, v59
	v_cvt_pk_bf16_f32 v172, v140, v141
	v_cvt_pk_bf16_f32 v173, v142, v143
	s_waitcnt vmcnt(4)
	v_and_b32_e32 v63, 0xffff0000, v61
	v_lshlrev_b32_e32 v62, 16, v61
	v_and_b32_e32 v61, 0xffff0000, v60
	v_lshlrev_b32_e32 v60, 16, v60
	v_add_f32_e32 v140, v60, v56
	v_add_f32_e32 v141, v61, v57
	v_add_f32_e32 v142, v62, v58
	v_add_f32_e32 v143, v63, v59
	v_mul_f32_e32 v140, 0.5, v140
	v_mul_f32_e32 v141, 0.5, v141
	v_mul_f32_e32 v142, 0.5, v142
	v_mul_f32_e32 v143, 0.5, v143
	v_sub_f32_e32 v140, v140, v60
	v_sub_f32_e32 v141, v141, v61
	v_sub_f32_e32 v142, v142, v62
	v_sub_f32_e32 v143, v143, v63
	v_cvt_pk_bf16_f32 v174, v140, v141
	v_cvt_pk_bf16_f32 v175, v142, v143
	s_waitcnt vmcnt(3)
	v_and_b32_e32 v67, 0xffff0000, v65
	v_lshlrev_b32_e32 v66, 16, v65
	v_and_b32_e32 v65, 0xffff0000, v64
	v_lshlrev_b32_e32 v64, 16, v64
	v_add_f32_e32 v140, v64, v60
	v_add_f32_e32 v141, v65, v61
	v_add_f32_e32 v142, v66, v62
	v_add_f32_e32 v143, v67, v63
	v_mul_f32_e32 v140, 0.5, v140
	v_mul_f32_e32 v141, 0.5, v141
	v_mul_f32_e32 v142, 0.5, v142
	v_mul_f32_e32 v143, 0.5, v143
	v_sub_f32_e32 v140, v140, v64
	v_sub_f32_e32 v141, v141, v65
	v_sub_f32_e32 v142, v142, v66
	v_sub_f32_e32 v143, v143, v67
	v_cvt_pk_bf16_f32 v176, v140, v141
	v_cvt_pk_bf16_f32 v177, v142, v143
	s_waitcnt vmcnt(2)
	v_and_b32_e32 v71, 0xffff0000, v69
	v_lshlrev_b32_e32 v70, 16, v69
	v_and_b32_e32 v69, 0xffff0000, v68
	v_lshlrev_b32_e32 v68, 16, v68
	v_add_f32_e32 v140, v68, v64
	v_add_f32_e32 v141, v69, v65
	v_add_f32_e32 v142, v70, v66
	v_add_f32_e32 v143, v71, v67
	v_mul_f32_e32 v140, 0.5, v140
	v_mul_f32_e32 v141, 0.5, v141
	v_mul_f32_e32 v142, 0.5, v142
	v_mul_f32_e32 v143, 0.5, v143
	v_sub_f32_e32 v140, v140, v68
	v_sub_f32_e32 v141, v141, v69
	v_sub_f32_e32 v142, v142, v70
	v_sub_f32_e32 v143, v143, v71
	v_cvt_pk_bf16_f32 v178, v140, v141
	v_cvt_pk_bf16_f32 v179, v142, v143
	s_waitcnt vmcnt(1)
	v_and_b32_e32 v75, 0xffff0000, v73
	v_lshlrev_b32_e32 v74, 16, v73
	v_and_b32_e32 v73, 0xffff0000, v72
	v_lshlrev_b32_e32 v72, 16, v72
	v_add_f32_e32 v140, v72, v68
	v_add_f32_e32 v141, v73, v69
	v_add_f32_e32 v142, v74, v70
	v_add_f32_e32 v143, v75, v71
	v_mul_f32_e32 v140, 0.5, v140
	v_mul_f32_e32 v141, 0.5, v141
	v_mul_f32_e32 v142, 0.5, v142
	v_mul_f32_e32 v143, 0.5, v143
	v_sub_f32_e32 v140, v140, v72
	v_sub_f32_e32 v141, v141, v73
	v_sub_f32_e32 v142, v142, v74
	v_sub_f32_e32 v143, v143, v75
	v_cvt_pk_bf16_f32 v180, v140, v141
	v_cvt_pk_bf16_f32 v181, v142, v143
	s_waitcnt vmcnt(0)
	v_and_b32_e32 v79, 0xffff0000, v77
	v_lshlrev_b32_e32 v78, 16, v77
	v_and_b32_e32 v77, 0xffff0000, v76
	v_lshlrev_b32_e32 v76, 16, v76
	v_add_f32_e32 v140, v76, v72
	v_add_f32_e32 v141, v77, v73
	v_add_f32_e32 v142, v78, v74
	v_add_f32_e32 v143, v79, v75
	v_mul_f32_e32 v140, 0.5, v140
	v_mul_f32_e32 v141, 0.5, v141
	v_mul_f32_e32 v142, 0.5, v142
	v_mul_f32_e32 v143, 0.5, v143
	v_sub_f32_e32 v140, v140, v76
	v_sub_f32_e32 v141, v141, v77
	v_sub_f32_e32 v142, v142, v78
	v_sub_f32_e32 v143, v143, v79
	v_cvt_pk_bf16_f32 v182, v140, v141
	v_cvt_pk_bf16_f32 v183, v142, v143
	global_store_dwordx2 v11, v[152:153], s[24:25] sc1
	s_add_u32 s24, s24, 0x800
	s_addc_u32 s25, s25, 0
	global_store_dwordx2 v11, v[154:155], s[24:25] sc1
	s_add_u32 s24, s24, 0x800
	s_addc_u32 s25, s25, 0
	global_store_dwordx2 v11, v[156:157], s[24:25] sc1
	s_add_u32 s24, s24, 0x800
	s_addc_u32 s25, s25, 0
	global_store_dwordx2 v11, v[158:159], s[24:25] sc1
	s_add_u32 s24, s24, 0x800
	s_addc_u32 s25, s25, 0
	global_store_dwordx2 v11, v[160:161], s[24:25] sc1
	s_add_u32 s24, s24, 0x800
	s_addc_u32 s25, s25, 0
	global_store_dwordx2 v11, v[162:163], s[24:25] sc1
	s_add_u32 s24, s24, 0x800
	s_addc_u32 s25, s25, 0
	global_store_dwordx2 v11, v[164:165], s[24:25] sc1
	s_add_u32 s24, s24, 0x800
	s_addc_u32 s25, s25, 0
	global_store_dwordx2 v11, v[166:167], s[24:25] sc1
	s_add_u32 s24, s24, 0x800
	s_addc_u32 s25, s25, 0
	global_store_dwordx2 v11, v[168:169], s[24:25] sc1
	s_add_u32 s24, s24, 0x800
	s_addc_u32 s25, s25, 0
	global_store_dwordx2 v11, v[170:171], s[24:25] sc1
	s_add_u32 s24, s24, 0x800
	s_addc_u32 s25, s25, 0
	global_store_dwordx2 v11, v[172:173], s[24:25] sc1
	s_add_u32 s24, s24, 0x800
	s_addc_u32 s25, s25, 0
	global_store_dwordx2 v11, v[174:175], s[24:25] sc1
	s_add_u32 s24, s24, 0x800
	s_addc_u32 s25, s25, 0
	global_store_dwordx2 v11, v[176:177], s[24:25] sc1
	s_add_u32 s24, s24, 0x800
	s_addc_u32 s25, s25, 0
	global_store_dwordx2 v11, v[178:179], s[24:25] sc1
	s_add_u32 s24, s24, 0x800
	s_addc_u32 s25, s25, 0
	global_store_dwordx2 v11, v[180:181], s[24:25] sc1
	s_add_u32 s24, s24, 0x800
	s_addc_u32 s25, s25, 0
	global_store_dwordx2 v11, v[182:183], s[24:25] sc1
	s_add_u32 s24, s24, 0x800
	s_addc_u32 s25, s25, 0
	s_branch .Lp13f_next
; DI float bflo(unsigned u) { return __uint_as_float(u << 16); }
; DI float bfhi(unsigned u) { return __uint_as_float(u & 0xffff0000u); }
; template <int WIN>
; DI void pool_elem(const Params& p, int row, int c) {
;     ...
;     } else {
;       cnt = (float)(t + 1);
;       for (int j = 1; j <= t; ++j) {
;         unsigned w = *(const unsigned*)(P2 + (size_t)(row - j) * 2048 + c);
;         s0 += bflo(w); s1 += bfhi(w);
;       }
;     ...
;   *(unsigned*)(p.MIX + (size_t)row * 1024 + c) = pack2(s0 / cnt - u0, s1 / cnt - u1);
.Lp13f_f1:
	s_sub_u32 s26, s20, 0
	s_lshl_b32 s27, s26, 12
	s_lshr_b32 s28, s26, 20
	s_add_u32 s22, s8, s27
	s_addc_u32 s23, s9, s28
	global_load_dwordx2 v[16:17], v11, s[22:23]
	s_add_u32 s22, s22, 0x1000
	s_addc_u32 s23, s23, 0
	global_load_dwordx2 v[20:21], v11, s[22:23]
	s_add_u32 s22, s22, 0x1000
	s_addc_u32 s23, s23, 0
	global_load_dwordx2 v[24:25], v11, s[22:23]
	s_add_u32 s22, s22, 0x1000
	s_addc_u32 s23, s23, 0
	global_load_dwordx2 v[28:29], v11, s[22:23]
	s_add_u32 s22, s22, 0x1000
	s_addc_u32 s23, s23, 0
	global_load_dwordx2 v[32:33], v11, s[22:23]
	s_add_u32 s22, s22, 0x1000
	s_addc_u32 s23, s23, 0
	global_load_dwordx2 v[36:37], v11, s[22:23]
	s_add_u32 s22, s22, 0x1000
	s_addc_u32 s23, s23, 0
	global_load_dwordx2 v[40:41], v11, s[22:23]
	s_add_u32 s22, s22, 0x1000
	s_addc_u32 s23, s23, 0
	global_load_dwordx2 v[44:45], v11, s[22:23]
	s_add_u32 s22, s22, 0x1000
	s_addc_u32 s23, s23, 0
	global_load_dwordx2 v[48:49], v11, s[22:23]
	s_add_u32 s22, s22, 0x1000
	s_addc_u32 s23, s23, 0
	global_load_dwordx2 v[52:53], v11, s[22:23]
	s_add_u32 s22, s22, 0x1000
	s_addc_u32 s23, s23, 0
	global_load_dwordx2 v[56:57], v11, s[22:23]
	s_add_u32 s22, s22, 0x1000
	s_addc_u32 s23, s23, 0
	global_load_dwordx2 v[60:61], v11, s[22:23]
	s_add_u32 s22, s22, 0x1000
	s_addc_u32 s23, s23, 0
	global_load_dwordx2 v[64:65], v11, s[22:23]
	s_add_u32 s22, s22, 0x1000
	s_addc_u32 s23, s23, 0
	global_load_dwordx2 v[68:69], v11, s[22:23]
	s_add_u32 s22, s22, 0x1000
	s_addc_u32 s23, s23, 0
	global_load_dwordx2 v[72:73], v11, s[22:23]
	s_add_u32 s22, s22, 0x1000
	s_addc_u32 s23, s23, 0
	global_load_dwordx2 v[76:77], v11, s[22:23]
	s_add_u32 s22, s22, 0x1000
	s_addc_u32 s23, s23, 0
	s_waitcnt vmcnt(15)
	v_and_b32_e32 v19, 0xffff0000, v17
	v_lshlrev_b32_e32 v18, 16, v17
	v_and_b32_e32 v17, 0xffff0000, v16
	v_lshlrev_b32_e32 v16, 16, v16
	v_mov_b32_e32 v140, v16
	v_mov_b32_e32 v141, v17
	v_mov_b32_e32 v142, v18
	v_mov_b32_e32 v143, v19
	v_mul_f32_e32 v140, 1.0, v140
	v_mul_f32_e32 v141, 1.0, v141
	v_mul_f32_e32 v142, 1.0, v142
	v_mul_f32_e32 v143, 1.0, v143
	v_sub_f32_e32 v140, v140, v16
	v_sub_f32_e32 v141, v141, v17
	v_sub_f32_e32 v142, v142, v18
	v_sub_f32_e32 v143, v143, v19
	v_cvt_pk_bf16_f32 v152, v140, v141
	v_cvt_pk_bf16_f32 v153, v142, v143
	s_waitcnt vmcnt(14)
	v_and_b32_e32 v23, 0xffff0000, v21
	v_lshlrev_b32_e32 v22, 16, v21
	v_and_b32_e32 v21, 0xffff0000, v20
	v_lshlrev_b32_e32 v20, 16, v20
	v_add_f32_e32 v140, v20, v16
	v_add_f32_e32 v141, v21, v17
	v_add_f32_e32 v142, v22, v18
	v_add_f32_e32 v143, v23, v19
	v_mul_f32_e32 v140, 0.5, v140
	v_mul_f32_e32 v141, 0.5, v141
	v_mul_f32_e32 v142, 0.5, v142
	v_mul_f32_e32 v143, 0.5, v143
	v_sub_f32_e32 v140, v140, v20
	v_sub_f32_e32 v141, v141, v21
	v_sub_f32_e32 v142, v142, v22
	v_sub_f32_e32 v143, v143, v23
	v_cvt_pk_bf16_f32 v154, v140, v141
	v_cvt_pk_bf16_f32 v155, v142, v143
	s_waitcnt vmcnt(13)
	v_and_b32_e32 v27, 0xffff0000, v25
	v_lshlrev_b32_e32 v26, 16, v25
	v_and_b32_e32 v25, 0xffff0000, v24
	v_lshlrev_b32_e32 v24, 16, v24
	v_add_f32_e32 v140, v24, v20
	v_add_f32_e32 v141, v25, v21
	v_add_f32_e32 v142, v26, v22
	v_add_f32_e32 v143, v27, v23
	v_add_f32_e32 v140, v140, v16
	v_add_f32_e32 v141, v141, v17
	v_add_f32_e32 v142, v142, v18
	v_add_f32_e32 v143, v143, v19
	v_mov_b32_e32 v151, 0x40400000
	v_div_scale_f32 v146, s[26:27], v151, v151, v140
	v_rcp_f32_e32 v147, v146
	v_div_scale_f32 v148, vcc, v140, v151, v140
	v_fma_f32 v149, -v146, v147, 1.0
	v_fmac_f32_e32 v147, v149, v147
	v_mul_f32_e32 v149, v148, v147
	v_fma_f32 v150, -v146, v149, v148
	v_fmac_f32_e32 v149, v150, v147
	v_fma_f32 v146, -v146, v149, v148
	v_div_fmas_f32 v146, v146, v147, v149
	v_div_fixup_f32 v140, v146, v151, v140
	v_mov_b32_e32 v151, 0x40400000
	v_div_scale_f32 v146, s[26:27], v151, v151, v141
	v_rcp_f32_e32 v147, v146
	v_div_scale_f32 v148, vcc, v141, v151, v141
	v_fma_f32 v149, -v146, v147, 1.0
	v_fmac_f32_e32 v147, v149, v147
	v_mul_f32_e32 v149, v148, v147
	v_fma_f32 v150, -v146, v149, v148
	v_fmac_f32_e32 v149, v150, v147
	v_fma_f32 v146, -v146, v149, v148
	v_div_fmas_f32 v146, v146, v147, v149
	v_div_fixup_f32 v141, v146, v151, v141
	v_mov_b32_e32 v151, 0x40400000
	v_div_scale_f32 v146, s[26:27], v151, v151, v142
	v_rcp_f32_e32 v147, v146
	v_div_scale_f32 v148, vcc, v142, v151, v142
	v_fma_f32 v149, -v146, v147, 1.0
	v_fmac_f32_e32 v147, v149, v147
	v_mul_f32_e32 v149, v148, v147
	v_fma_f32 v150, -v146, v149, v148
	v_fmac_f32_e32 v149, v150, v147
	v_fma_f32 v146, -v146, v149, v148
	v_div_fmas_f32 v146, v146, v147, v149
	v_div_fixup_f32 v142, v146, v151, v142
	v_mov_b32_e32 v151, 0x40400000
	v_div_scale_f32 v146, s[26:27], v151, v151, v143
	v_rcp_f32_e32 v147, v146
	v_div_scale_f32 v148, vcc, v143, v151, v143
	v_fma_f32 v149, -v146, v147, 1.0
	v_fmac_f32_e32 v147, v149, v147
	v_mul_f32_e32 v149, v148, v147
	v_fma_f32 v150, -v146, v149, v148
	v_fmac_f32_e32 v149, v150, v147
	v_fma_f32 v146, -v146, v149, v148
	v_div_fmas_f32 v146, v146, v147, v149
	v_div_fixup_f32 v143, v146, v151, v143
	v_sub_f32_e32 v140, v140, v24
	v_sub_f32_e32 v141, v141, v25
	v_sub_f32_e32 v142, v142, v26
	v_sub_f32_e32 v143, v143, v27
	v_cvt_pk_bf16_f32 v156, v140, v141
	v_cvt_pk_bf16_f32 v157, v142, v143
	s_waitcnt vmcnt(12)
; DI float bflo(unsigned u) { return __uint_as_float(u << 16); }
; DI float bfhi(unsigned u) { return __uint_as_float(u & 0xffff0000u); }
; template <int WIN>
; DI void pool_elem(const Params& p, int row, int c) {
;     ...
;     } else {
;       cnt = (float)(t + 1);
;       for (int j = 1; j <= t; ++j) {
;         unsigned w = *(const unsigned*)(P2 + (size_t)(row - j) * 2048 + c);
;         s0 += bflo(w); s1 += bfhi(w);
;       }
;     ...
;   *(unsigned*)(p.MIX + (size_t)row * 1024 + c) = pack2(s0 / cnt - u0, s1 / cnt - u1);
	v_and_b32_e32 v31, 0xffff0000, v29
	v_lshlrev_b32_e32 v30, 16, v29
	v_and_b32_e32 v29, 0xffff0000, v28
	v_lshlrev_b32_e32 v28, 16, v28
	v_add_f32_e32 v140, v28, v24
	v_add_f32_e32 v141, v29, v25
	v_add_f32_e32 v142, v30, v26
	v_add_f32_e32 v143, v31, v27
	v_add_f32_e32 v140, v140, v20
	v_add_f32_e32 v141, v141, v21
	v_add_f32_e32 v142, v142, v22
	v_add_f32_e32 v143, v143, v23
	v_add_f32_e32 v140, v140, v16
	v_add_f32_e32 v141, v141, v17
	v_add_f32_e32 v142, v142, v18
	v_add_f32_e32 v143, v143, v19
	v_mul_f32_e32 v140, 0x3e800000, v140
	v_mul_f32_e32 v141, 0x3e800000, v141
	v_mul_f32_e32 v142, 0x3e800000, v142
	v_mul_f32_e32 v143, 0x3e800000, v143
	v_sub_f32_e32 v140, v140, v28
	v_sub_f32_e32 v141, v141, v29
	v_sub_f32_e32 v142, v142, v30
	v_sub_f32_e32 v143, v143, v31
	v_cvt_pk_bf16_f32 v158, v140, v141
	v_cvt_pk_bf16_f32 v159, v142, v143
	s_waitcnt vmcnt(11)
	v_and_b32_e32 v35, 0xffff0000, v33
	v_lshlrev_b32_e32 v34, 16, v33
	v_and_b32_e32 v33, 0xffff0000, v32
	v_lshlrev_b32_e32 v32, 16, v32
	v_add_f32_e32 v140, v32, v28
	v_add_f32_e32 v141, v33, v29
	v_add_f32_e32 v142, v34, v30
	v_add_f32_e32 v143, v35, v31
	v_add_f32_e32 v140, v140, v24
	v_add_f32_e32 v141, v141, v25
	v_add_f32_e32 v142, v142, v26
	v_add_f32_e32 v143, v143, v27
	v_add_f32_e32 v140, v140, v20
	v_add_f32_e32 v141, v141, v21
	v_add_f32_e32 v142, v142, v22
	v_add_f32_e32 v143, v143, v23
	v_mul_f32_e32 v140, 0x3e800000, v140
	v_mul_f32_e32 v141, 0x3e800000, v141
	v_mul_f32_e32 v142, 0x3e800000, v142
	v_mul_f32_e32 v143, 0x3e800000, v143
	v_sub_f32_e32 v140, v140, v32
	v_sub_f32_e32 v141, v141, v33
	v_sub_f32_e32 v142, v142, v34
	v_sub_f32_e32 v143, v143, v35
	v_cvt_pk_bf16_f32 v160, v140, v141
	v_cvt_pk_bf16_f32 v161, v142, v143
	s_waitcnt vmcnt(10)
	v_and_b32_e32 v39, 0xffff0000, v37
	v_lshlrev_b32_e32 v38, 16, v37
	v_and_b32_e32 v37, 0xffff0000, v36
	v_lshlrev_b32_e32 v36, 16, v36
	v_add_f32_e32 v140, v36, v32
	v_add_f32_e32 v141, v37, v33
	v_add_f32_e32 v142, v38, v34
	v_add_f32_e32 v143, v39, v35
	v_add_f32_e32 v140, v140, v28
	v_add_f32_e32 v141, v141, v29
	v_add_f32_e32 v142, v142, v30
	v_add_f32_e32 v143, v143, v31
	v_add_f32_e32 v140, v140, v24
	v_add_f32_e32 v141, v141, v25
	v_add_f32_e32 v142, v142, v26
	v_add_f32_e32 v143, v143, v27
	v_mul_f32_e32 v140, 0x3e800000, v140
	v_mul_f32_e32 v141, 0x3e800000, v141
	v_mul_f32_e32 v142, 0x3e800000, v142
	v_mul_f32_e32 v143, 0x3e800000, v143
	v_sub_f32_e32 v140, v140, v36
	v_sub_f32_e32 v141, v141, v37
	v_sub_f32_e32 v142, v142, v38
	v_sub_f32_e32 v143, v143, v39
	v_cvt_pk_bf16_f32 v162, v140, v141
	v_cvt_pk_bf16_f32 v163, v142, v143
	s_waitcnt vmcnt(9)
	v_and_b32_e32 v43, 0xffff0000, v41
	v_lshlrev_b32_e32 v42, 16, v41
	v_and_b32_e32 v41, 0xffff0000, v40
	v_lshlrev_b32_e32 v40, 16, v40
	v_add_f32_e32 v140, v40, v36
	v_add_f32_e32 v141, v41, v37
	v_add_f32_e32 v142, v42, v38
	v_add_f32_e32 v143, v43, v39
	v_add_f32_e32 v140, v140, v32
	v_add_f32_e32 v141, v141, v33
	v_add_f32_e32 v142, v142, v34
	v_add_f32_e32 v143, v143, v35
	v_add_f32_e32 v140, v140, v28
	v_add_f32_e32 v141, v141, v29
	v_add_f32_e32 v142, v142, v30
	v_add_f32_e32 v143, v143, v31
	v_mul_f32_e32 v140, 0x3e800000, v140
	v_mul_f32_e32 v141, 0x3e800000, v141
	v_mul_f32_e32 v142, 0x3e800000, v142
	v_mul_f32_e32 v143, 0x3e800000, v143
	v_sub_f32_e32 v140, v140, v40
	v_sub_f32_e32 v141, v141, v41
	v_sub_f32_e32 v142, v142, v42
	v_sub_f32_e32 v143, v143, v43
	v_cvt_pk_bf16_f32 v164, v140, v141
	v_cvt_pk_bf16_f32 v165, v142, v143
	s_waitcnt vmcnt(8)
	v_and_b32_e32 v47, 0xffff0000, v45
	v_lshlrev_b32_e32 v46, 16, v45
	v_and_b32_e32 v45, 0xffff0000, v44
	v_lshlrev_b32_e32 v44, 16, v44
	v_add_f32_e32 v140, v44, v40
	v_add_f32_e32 v141, v45, v41
	v_add_f32_e32 v142, v46, v42
	v_add_f32_e32 v143, v47, v43
	v_add_f32_e32 v140, v140, v36
	v_add_f32_e32 v141, v141, v37
	v_add_f32_e32 v142, v142, v38
	v_add_f32_e32 v143, v143, v39
	v_add_f32_e32 v140, v140, v32
	v_add_f32_e32 v141, v141, v33
	v_add_f32_e32 v142, v142, v34
	v_add_f32_e32 v143, v143, v35
	v_mul_f32_e32 v140, 0x3e800000, v140
	v_mul_f32_e32 v141, 0x3e800000, v141
	v_mul_f32_e32 v142, 0x3e800000, v142
	v_mul_f32_e32 v143, 0x3e800000, v143
	v_sub_f32_e32 v140, v140, v44
	v_sub_f32_e32 v141, v141, v45
	v_sub_f32_e32 v142, v142, v46
	v_sub_f32_e32 v143, v143, v47
	v_cvt_pk_bf16_f32 v166, v140, v141
	v_cvt_pk_bf16_f32 v167, v142, v143
	s_waitcnt vmcnt(7)
	v_and_b32_e32 v51, 0xffff0000, v49
	v_lshlrev_b32_e32 v50, 16, v49
	v_and_b32_e32 v49, 0xffff0000, v48
	v_lshlrev_b32_e32 v48, 16, v48
	v_add_f32_e32 v140, v48, v44
	v_add_f32_e32 v141, v49, v45
	v_add_f32_e32 v142, v50, v46
	v_add_f32_e32 v143, v51, v47
	v_add_f32_e32 v140, v140, v40
	v_add_f32_e32 v141, v141, v41
	v_add_f32_e32 v142, v142, v42
	v_add_f32_e32 v143, v143, v43
	v_add_f32_e32 v140, v140, v36
	v_add_f32_e32 v141, v141, v37
	v_add_f32_e32 v142, v142, v38
	v_add_f32_e32 v143, v143, v39
	v_mul_f32_e32 v140, 0x3e800000, v140
	v_mul_f32_e32 v141, 0x3e800000, v141
	v_mul_f32_e32 v142, 0x3e800000, v142
	v_mul_f32_e32 v143, 0x3e800000, v143
	v_sub_f32_e32 v140, v140, v48
	v_sub_f32_e32 v141, v141, v49
	v_sub_f32_e32 v142, v142, v50
	v_sub_f32_e32 v143, v143, v51
	v_cvt_pk_bf16_f32 v168, v140, v141
	v_cvt_pk_bf16_f32 v169, v142, v143
	s_waitcnt vmcnt(6)
; DI float bflo(unsigned u) { return __uint_as_float(u << 16); }
; DI float bfhi(unsigned u) { return __uint_as_float(u & 0xffff0000u); }
; template <int WIN>
; DI void pool_elem(const Params& p, int row, int c) {
;     ...
;     } else {
;       cnt = (float)(t + 1);
;       for (int j = 1; j <= t; ++j) {
;         unsigned w = *(const unsigned*)(P2 + (size_t)(row - j) * 2048 + c);
;         s0 += bflo(w); s1 += bfhi(w);
;       }
;     ...
;   *(unsigned*)(p.MIX + (size_t)row * 1024 + c) = pack2(s0 / cnt - u0, s1 / cnt - u1);
	v_and_b32_e32 v55, 0xffff0000, v53
	v_lshlrev_b32_e32 v54, 16, v53
	v_and_b32_e32 v53, 0xffff0000, v52
	v_lshlrev_b32_e32 v52, 16, v52
	v_add_f32_e32 v140, v52, v48
	v_add_f32_e32 v141, v53, v49
	v_add_f32_e32 v142, v54, v50
	v_add_f32_e32 v143, v55, v51
	v_add_f32_e32 v140, v140, v44
	v_add_f32_e32 v141, v141, v45
	v_add_f32_e32 v142, v142, v46
	v_add_f32_e32 v143, v143, v47
	v_add_f32_e32 v140, v140, v40
	v_add_f32_e32 v141, v141, v41
	v_add_f32_e32 v142, v142, v42
	v_add_f32_e32 v143, v143, v43
	v_mul_f32_e32 v140, 0x3e800000, v140
	v_mul_f32_e32 v141, 0x3e800000, v141
	v_mul_f32_e32 v142, 0x3e800000, v142
	v_mul_f32_e32 v143, 0x3e800000, v143
	v_sub_f32_e32 v140, v140, v52
	v_sub_f32_e32 v141, v141, v53
	v_sub_f32_e32 v142, v142, v54
	v_sub_f32_e32 v143, v143, v55
	v_cvt_pk_bf16_f32 v170, v140, v141
	v_cvt_pk_bf16_f32 v171, v142, v143
	s_waitcnt vmcnt(5)
	v_and_b32_e32 v59, 0xffff0000, v57
	v_lshlrev_b32_e32 v58, 16, v57
	v_and_b32_e32 v57, 0xffff0000, v56
	v_lshlrev_b32_e32 v56, 16, v56
	v_add_f32_e32 v140, v56, v52
	v_add_f32_e32 v141, v57, v53
	v_add_f32_e32 v142, v58, v54
	v_add_f32_e32 v143, v59, v55
	v_add_f32_e32 v140, v140, v48
	v_add_f32_e32 v141, v141, v49
	v_add_f32_e32 v142, v142, v50
	v_add_f32_e32 v143, v143, v51
	v_add_f32_e32 v140, v140, v44
	v_add_f32_e32 v141, v141, v45
	v_add_f32_e32 v142, v142, v46
	v_add_f32_e32 v143, v143, v47
	v_mul_f32_e32 v140, 0x3e800000, v140
	v_mul_f32_e32 v141, 0x3e800000, v141
	v_mul_f32_e32 v142, 0x3e800000, v142
	v_mul_f32_e32 v143, 0x3e800000, v143
	v_sub_f32_e32 v140, v140, v56
	v_sub_f32_e32 v141, v141, v57
	v_sub_f32_e32 v142, v142, v58
	v_sub_f32_e32 v143, v143, v59
	v_cvt_pk_bf16_f32 v172, v140, v141
	v_cvt_pk_bf16_f32 v173, v142, v143
	s_waitcnt vmcnt(4)
	v_and_b32_e32 v63, 0xffff0000, v61
	v_lshlrev_b32_e32 v62, 16, v61
	v_and_b32_e32 v61, 0xffff0000, v60
	v_lshlrev_b32_e32 v60, 16, v60
	v_add_f32_e32 v140, v60, v56
	v_add_f32_e32 v141, v61, v57
	v_add_f32_e32 v142, v62, v58
	v_add_f32_e32 v143, v63, v59
	v_add_f32_e32 v140, v140, v52
	v_add_f32_e32 v141, v141, v53
	v_add_f32_e32 v142, v142, v54
	v_add_f32_e32 v143, v143, v55
	v_add_f32_e32 v140, v140, v48
	v_add_f32_e32 v141, v141, v49
	v_add_f32_e32 v142, v142, v50
	v_add_f32_e32 v143, v143, v51
	v_mul_f32_e32 v140, 0x3e800000, v140
	v_mul_f32_e32 v141, 0x3e800000, v141
	v_mul_f32_e32 v142, 0x3e800000, v142
	v_mul_f32_e32 v143, 0x3e800000, v143
	v_sub_f32_e32 v140, v140, v60
	v_sub_f32_e32 v141, v141, v61
	v_sub_f32_e32 v142, v142, v62
	v_sub_f32_e32 v143, v143, v63
	v_cvt_pk_bf16_f32 v174, v140, v141
	v_cvt_pk_bf16_f32 v175, v142, v143
	s_waitcnt vmcnt(3)
	v_and_b32_e32 v67, 0xffff0000, v65
	v_lshlrev_b32_e32 v66, 16, v65
	v_and_b32_e32 v65, 0xffff0000, v64
	v_lshlrev_b32_e32 v64, 16, v64
	v_add_f32_e32 v140, v64, v60
	v_add_f32_e32 v141, v65, v61
	v_add_f32_e32 v142, v66, v62
	v_add_f32_e32 v143, v67, v63
	v_add_f32_e32 v140, v140, v56
	v_add_f32_e32 v141, v141, v57
	v_add_f32_e32 v142, v142, v58
	v_add_f32_e32 v143, v143, v59
	v_add_f32_e32 v140, v140, v52
	v_add_f32_e32 v141, v141, v53
	v_add_f32_e32 v142, v142, v54
	v_add_f32_e32 v143, v143, v55
	v_mul_f32_e32 v140, 0x3e800000, v140
	v_mul_f32_e32 v141, 0x3e800000, v141
	v_mul_f32_e32 v142, 0x3e800000, v142
	v_mul_f32_e32 v143, 0x3e800000, v143
	v_sub_f32_e32 v140, v140, v64
	v_sub_f32_e32 v141, v141, v65
	v_sub_f32_e32 v142, v142, v66
	v_sub_f32_e32 v143, v143, v67
	v_cvt_pk_bf16_f32 v176, v140, v141
	v_cvt_pk_bf16_f32 v177, v142, v143
	s_waitcnt vmcnt(2)
	v_and_b32_e32 v71, 0xffff0000, v69
	v_lshlrev_b32_e32 v70, 16, v69
	v_and_b32_e32 v69, 0xffff0000, v68
	v_lshlrev_b32_e32 v68, 16, v68
	v_add_f32_e32 v140, v68, v64
	v_add_f32_e32 v141, v69, v65
	v_add_f32_e32 v142, v70, v66
	v_add_f32_e32 v143, v71, v67
	v_add_f32_e32 v140, v140, v60
	v_add_f32_e32 v141, v141, v61
	v_add_f32_e32 v142, v142, v62
	v_add_f32_e32 v143, v143, v63
	v_add_f32_e32 v140, v140, v56
	v_add_f32_e32 v141, v141, v57
	v_add_f32_e32 v142, v142, v58
	v_add_f32_e32 v143, v143, v59
	v_mul_f32_e32 v140, 0x3e800000, v140
	v_mul_f32_e32 v141, 0x3e800000, v141
	v_mul_f32_e32 v142, 0x3e800000, v142
	v_mul_f32_e32 v143, 0x3e800000, v143
	v_sub_f32_e32 v140, v140, v68
	v_sub_f32_e32 v141, v141, v69
	v_sub_f32_e32 v142, v142, v70
	v_sub_f32_e32 v143, v143, v71
	v_cvt_pk_bf16_f32 v178, v140, v141
	v_cvt_pk_bf16_f32 v179, v142, v143
	s_waitcnt vmcnt(1)
	v_and_b32_e32 v75, 0xffff0000, v73
	v_lshlrev_b32_e32 v74, 16, v73
	v_and_b32_e32 v73, 0xffff0000, v72
	v_lshlrev_b32_e32 v72, 16, v72
	v_add_f32_e32 v140, v72, v68
	v_add_f32_e32 v141, v73, v69
	v_add_f32_e32 v142, v74, v70
	v_add_f32_e32 v143, v75, v71
	v_add_f32_e32 v140, v140, v64
	v_add_f32_e32 v141, v141, v65
	v_add_f32_e32 v142, v142, v66
	v_add_f32_e32 v143, v143, v67
	v_add_f32_e32 v140, v140, v60
	v_add_f32_e32 v141, v141, v61
	v_add_f32_e32 v142, v142, v62
	v_add_f32_e32 v143, v143, v63
	v_mul_f32_e32 v140, 0x3e800000, v140
	v_mul_f32_e32 v141, 0x3e800000, v141
	v_mul_f32_e32 v142, 0x3e800000, v142
	v_mul_f32_e32 v143, 0x3e800000, v143
	v_sub_f32_e32 v140, v140, v72
	v_sub_f32_e32 v141, v141, v73
	v_sub_f32_e32 v142, v142, v74
	v_sub_f32_e32 v143, v143, v75
	v_cvt_pk_bf16_f32 v180, v140, v141
	v_cvt_pk_bf16_f32 v181, v142, v143
	s_waitcnt vmcnt(0)
; DI float bflo(unsigned u) { return __uint_as_float(u << 16); }
; DI float bfhi(unsigned u) { return __uint_as_float(u & 0xffff0000u); }
; template <int WIN>
; DI void pool_elem(const Params& p, int row, int c) {
;     ...
;     } else {
;       cnt = (float)(t + 1);
;       for (int j = 1; j <= t; ++j) {
;         unsigned w = *(const unsigned*)(P2 + (size_t)(row - j) * 2048 + c);
;         s0 += bflo(w); s1 += bfhi(w);
;       }
;     ...
;   *(unsigned*)(p.MIX + (size_t)row * 1024 + c) = pack2(s0 / cnt - u0, s1 / cnt - u1);
	v_and_b32_e32 v79, 0xffff0000, v77
	v_lshlrev_b32_e32 v78, 16, v77
	v_and_b32_e32 v77, 0xffff0000, v76
	v_lshlrev_b32_e32 v76, 16, v76
	v_add_f32_e32 v140, v76, v72
	v_add_f32_e32 v141, v77, v73
	v_add_f32_e32 v142, v78, v74
	v_add_f32_e32 v143, v79, v75
	v_add_f32_e32 v140, v140, v68
	v_add_f32_e32 v141, v141, v69
	v_add_f32_e32 v142, v142, v70
	v_add_f32_e32 v143, v143, v71
	v_add_f32_e32 v140, v140, v64
	v_add_f32_e32 v141, v141, v65
	v_add_f32_e32 v142, v142, v66
	v_add_f32_e32 v143, v143, v67
	v_mul_f32_e32 v140, 0x3e800000, v140
	v_mul_f32_e32 v141, 0x3e800000, v141
	v_mul_f32_e32 v142, 0x3e800000, v142
	v_mul_f32_e32 v143, 0x3e800000, v143
	v_sub_f32_e32 v140, v140, v76
	v_sub_f32_e32 v141, v141, v77
	v_sub_f32_e32 v142, v142, v78
	v_sub_f32_e32 v143, v143, v79
	v_cvt_pk_bf16_f32 v182, v140, v141
	v_cvt_pk_bf16_f32 v183, v142, v143
	global_store_dwordx2 v11, v[152:153], s[24:25] sc1
	s_add_u32 s24, s24, 0x800
	s_addc_u32 s25, s25, 0
	global_store_dwordx2 v11, v[154:155], s[24:25] sc1
	s_add_u32 s24, s24, 0x800
	s_addc_u32 s25, s25, 0
	global_store_dwordx2 v11, v[156:157], s[24:25] sc1
	s_add_u32 s24, s24, 0x800
	s_addc_u32 s25, s25, 0
	global_store_dwordx2 v11, v[158:159], s[24:25] sc1
	s_add_u32 s24, s24, 0x800
	s_addc_u32 s25, s25, 0
	global_store_dwordx2 v11, v[160:161], s[24:25] sc1
	s_add_u32 s24, s24, 0x800
	s_addc_u32 s25, s25, 0
	global_store_dwordx2 v11, v[162:163], s[24:25] sc1
	s_add_u32 s24, s24, 0x800
	s_addc_u32 s25, s25, 0
	global_store_dwordx2 v11, v[164:165], s[24:25] sc1
	s_add_u32 s24, s24, 0x800
	s_addc_u32 s25, s25, 0
	global_store_dwordx2 v11, v[166:167], s[24:25] sc1
	s_add_u32 s24, s24, 0x800
	s_addc_u32 s25, s25, 0
	global_store_dwordx2 v11, v[168:169], s[24:25] sc1
	s_add_u32 s24, s24, 0x800
	s_addc_u32 s25, s25, 0
	global_store_dwordx2 v11, v[170:171], s[24:25] sc1
	s_add_u32 s24, s24, 0x800
	s_addc_u32 s25, s25, 0
	global_store_dwordx2 v11, v[172:173], s[24:25] sc1
	s_add_u32 s24, s24, 0x800
	s_addc_u32 s25, s25, 0
	global_store_dwordx2 v11, v[174:175], s[24:25] sc1
	s_add_u32 s24, s24, 0x800
	s_addc_u32 s25, s25, 0
	global_store_dwordx2 v11, v[176:177], s[24:25] sc1
	s_add_u32 s24, s24, 0x800
	s_addc_u32 s25, s25, 0
	global_store_dwordx2 v11, v[178:179], s[24:25] sc1
	s_add_u32 s24, s24, 0x800
	s_addc_u32 s25, s25, 0
	global_store_dwordx2 v11, v[180:181], s[24:25] sc1
	s_add_u32 s24, s24, 0x800
	s_addc_u32 s25, s25, 0
	global_store_dwordx2 v11, v[182:183], s[24:25] sc1
	s_add_u32 s24, s24, 0x800
	s_addc_u32 s25, s25, 0
	s_branch .Lp13f_next
.Lp13f_f2:
	s_sub_u32 s26, s20, 0
	s_lshl_b32 s27, s26, 12
	s_lshr_b32 s28, s26, 20
	s_add_u32 s22, s8, s27
	s_addc_u32 s23, s9, s28
	global_load_dwordx2 v[16:17], v11, s[22:23]
	s_add_u32 s22, s22, 0x1000
	s_addc_u32 s23, s23, 0
	global_load_dwordx2 v[20:21], v11, s[22:23]
	s_add_u32 s22, s22, 0x1000
	s_addc_u32 s23, s23, 0
	global_load_dwordx2 v[24:25], v11, s[22:23]
	s_add_u32 s22, s22, 0x1000
	s_addc_u32 s23, s23, 0
	global_load_dwordx2 v[28:29], v11, s[22:23]
	s_add_u32 s22, s22, 0x1000
	s_addc_u32 s23, s23, 0
	global_load_dwordx2 v[32:33], v11, s[22:23]
	s_add_u32 s22, s22, 0x1000
	s_addc_u32 s23, s23, 0
	global_load_dwordx2 v[36:37], v11, s[22:23]
	s_add_u32 s22, s22, 0x1000
	s_addc_u32 s23, s23, 0
	global_load_dwordx2 v[40:41], v11, s[22:23]
	s_add_u32 s22, s22, 0x1000
	s_addc_u32 s23, s23, 0
	global_load_dwordx2 v[44:45], v11, s[22:23]
	s_add_u32 s22, s22, 0x1000
	s_addc_u32 s23, s23, 0
	global_load_dwordx2 v[48:49], v11, s[22:23]
	s_add_u32 s22, s22, 0x1000
	s_addc_u32 s23, s23, 0
	global_load_dwordx2 v[52:53], v11, s[22:23]
	s_add_u32 s22, s22, 0x1000
	s_addc_u32 s23, s23, 0
	global_load_dwordx2 v[56:57], v11, s[22:23]
	s_add_u32 s22, s22, 0x1000
	s_addc_u32 s23, s23, 0
	global_load_dwordx2 v[60:61], v11, s[22:23]
	s_add_u32 s22, s22, 0x1000
	s_addc_u32 s23, s23, 0
	global_load_dwordx2 v[64:65], v11, s[22:23]
	s_add_u32 s22, s22, 0x1000
	s_addc_u32 s23, s23, 0
	global_load_dwordx2 v[68:69], v11, s[22:23]
	s_add_u32 s22, s22, 0x1000
	s_addc_u32 s23, s23, 0
	global_load_dwordx2 v[72:73], v11, s[22:23]
	s_add_u32 s22, s22, 0x1000
	s_addc_u32 s23, s23, 0
	global_load_dwordx2 v[76:77], v11, s[22:23]
	s_add_u32 s22, s22, 0x1000
	s_addc_u32 s23, s23, 0
	s_waitcnt vmcnt(15)
	v_and_b32_e32 v19, 0xffff0000, v17
	v_lshlrev_b32_e32 v18, 16, v17
	v_and_b32_e32 v17, 0xffff0000, v16
	v_lshlrev_b32_e32 v16, 16, v16
	v_mov_b32_e32 v140, v16
	v_mov_b32_e32 v141, v17
	v_mov_b32_e32 v142, v18
	v_mov_b32_e32 v143, v19
	v_mul_f32_e32 v140, 1.0, v140
	v_mul_f32_e32 v141, 1.0, v141
	v_mul_f32_e32 v142, 1.0, v142
	v_mul_f32_e32 v143, 1.0, v143
	v_sub_f32_e32 v140, v140, v16
	v_sub_f32_e32 v141, v141, v17
	v_sub_f32_e32 v142, v142, v18
	v_sub_f32_e32 v143, v143, v19
	v_cvt_pk_bf16_f32 v152, v140, v141
	v_cvt_pk_bf16_f32 v153, v142, v143
	s_waitcnt vmcnt(14)
	v_and_b32_e32 v23, 0xffff0000, v21
	v_lshlrev_b32_e32 v22, 16, v21
	v_and_b32_e32 v21, 0xffff0000, v20
	v_lshlrev_b32_e32 v20, 16, v20
	v_add_f32_e32 v140, v20, v16
	v_add_f32_e32 v141, v21, v17
	v_add_f32_e32 v142, v22, v18
	v_add_f32_e32 v143, v23, v19
	v_mul_f32_e32 v140, 0.5, v140
	v_mul_f32_e32 v141, 0.5, v141
	v_mul_f32_e32 v142, 0.5, v142
	v_mul_f32_e32 v143, 0.5, v143
	v_sub_f32_e32 v140, v140, v20
	v_sub_f32_e32 v141, v141, v21
	v_sub_f32_e32 v142, v142, v22
	v_sub_f32_e32 v143, v143, v23
	v_cvt_pk_bf16_f32 v154, v140, v141
	v_cvt_pk_bf16_f32 v155, v142, v143
	s_waitcnt vmcnt(13)
; DI float bflo(unsigned u) { return __uint_as_float(u << 16); }
; DI float bfhi(unsigned u) { return __uint_as_float(u & 0xffff0000u); }
; template <int WIN>
; DI void pool_elem(const Params& p, int row, int c) {
;     ...
;     } else {
;       cnt = (float)(t + 1);
;       for (int j = 1; j <= t; ++j) {
;         unsigned w = *(const unsigned*)(P2 + (size_t)(row - j) * 2048 + c);
;         s0 += bflo(w); s1 += bfhi(w);
;       }
;     ...
;   *(unsigned*)(p.MIX + (size_t)row * 1024 + c) = pack2(s0 / cnt - u0, s1 / cnt - u1);
	v_and_b32_e32 v27, 0xffff0000, v25
	v_lshlrev_b32_e32 v26, 16, v25
	v_and_b32_e32 v25, 0xffff0000, v24
	v_lshlrev_b32_e32 v24, 16, v24
	v_add_f32_e32 v140, v24, v20
	v_add_f32_e32 v141, v25, v21
	v_add_f32_e32 v142, v26, v22
	v_add_f32_e32 v143, v27, v23
	v_add_f32_e32 v140, v140, v16
	v_add_f32_e32 v141, v141, v17
	v_add_f32_e32 v142, v142, v18
	v_add_f32_e32 v143, v143, v19
	v_mov_b32_e32 v151, 0x40400000
	v_div_scale_f32 v146, s[26:27], v151, v151, v140
	v_rcp_f32_e32 v147, v146
	v_div_scale_f32 v148, vcc, v140, v151, v140
	v_fma_f32 v149, -v146, v147, 1.0
	v_fmac_f32_e32 v147, v149, v147
	v_mul_f32_e32 v149, v148, v147
	v_fma_f32 v150, -v146, v149, v148
	v_fmac_f32_e32 v149, v150, v147
	v_fma_f32 v146, -v146, v149, v148
	v_div_fmas_f32 v146, v146, v147, v149
	v_div_fixup_f32 v140, v146, v151, v140
	v_mov_b32_e32 v151, 0x40400000
	v_div_scale_f32 v146, s[26:27], v151, v151, v141
	v_rcp_f32_e32 v147, v146
	v_div_scale_f32 v148, vcc, v141, v151, v141
	v_fma_f32 v149, -v146, v147, 1.0
	v_fmac_f32_e32 v147, v149, v147
	v_mul_f32_e32 v149, v148, v147
	v_fma_f32 v150, -v146, v149, v148
	v_fmac_f32_e32 v149, v150, v147
	v_fma_f32 v146, -v146, v149, v148
	v_div_fmas_f32 v146, v146, v147, v149
	v_div_fixup_f32 v141, v146, v151, v141
	v_mov_b32_e32 v151, 0x40400000
	v_div_scale_f32 v146, s[26:27], v151, v151, v142
	v_rcp_f32_e32 v147, v146
	v_div_scale_f32 v148, vcc, v142, v151, v142
	v_fma_f32 v149, -v146, v147, 1.0
	v_fmac_f32_e32 v147, v149, v147
	v_mul_f32_e32 v149, v148, v147
	v_fma_f32 v150, -v146, v149, v148
	v_fmac_f32_e32 v149, v150, v147
	v_fma_f32 v146, -v146, v149, v148
	v_div_fmas_f32 v146, v146, v147, v149
	v_div_fixup_f32 v142, v146, v151, v142
	v_mov_b32_e32 v151, 0x40400000
	v_div_scale_f32 v146, s[26:27], v151, v151, v143
	v_rcp_f32_e32 v147, v146
	v_div_scale_f32 v148, vcc, v143, v151, v143
	v_fma_f32 v149, -v146, v147, 1.0
	v_fmac_f32_e32 v147, v149, v147
	v_mul_f32_e32 v149, v148, v147
	v_fma_f32 v150, -v146, v149, v148
	v_fmac_f32_e32 v149, v150, v147
	v_fma_f32 v146, -v146, v149, v148
	v_div_fmas_f32 v146, v146, v147, v149
	v_div_fixup_f32 v143, v146, v151, v143
	v_sub_f32_e32 v140, v140, v24
	v_sub_f32_e32 v141, v141, v25
	v_sub_f32_e32 v142, v142, v26
	v_sub_f32_e32 v143, v143, v27
	v_cvt_pk_bf16_f32 v156, v140, v141
	v_cvt_pk_bf16_f32 v157, v142, v143
	s_waitcnt vmcnt(12)
	v_and_b32_e32 v31, 0xffff0000, v29
	v_lshlrev_b32_e32 v30, 16, v29
	v_and_b32_e32 v29, 0xffff0000, v28
	v_lshlrev_b32_e32 v28, 16, v28
	v_add_f32_e32 v140, v28, v24
	v_add_f32_e32 v141, v29, v25
	v_add_f32_e32 v142, v30, v26
	v_add_f32_e32 v143, v31, v27
	v_add_f32_e32 v140, v140, v20
	v_add_f32_e32 v141, v141, v21
	v_add_f32_e32 v142, v142, v22
	v_add_f32_e32 v143, v143, v23
	v_add_f32_e32 v140, v140, v16
	v_add_f32_e32 v141, v141, v17
	v_add_f32_e32 v142, v142, v18
	v_add_f32_e32 v143, v143, v19
	v_mul_f32_e32 v140, 0x3e800000, v140
	v_mul_f32_e32 v141, 0x3e800000, v141
	v_mul_f32_e32 v142, 0x3e800000, v142
	v_mul_f32_e32 v143, 0x3e800000, v143
	v_sub_f32_e32 v140, v140, v28
	v_sub_f32_e32 v141, v141, v29
	v_sub_f32_e32 v142, v142, v30
	v_sub_f32_e32 v143, v143, v31
	v_cvt_pk_bf16_f32 v158, v140, v141
	v_cvt_pk_bf16_f32 v159, v142, v143
	s_waitcnt vmcnt(11)
	v_and_b32_e32 v35, 0xffff0000, v33
	v_lshlrev_b32_e32 v34, 16, v33
	v_and_b32_e32 v33, 0xffff0000, v32
	v_lshlrev_b32_e32 v32, 16, v32
	v_add_f32_e32 v140, v32, v28
	v_add_f32_e32 v141, v33, v29
	v_add_f32_e32 v142, v34, v30
	v_add_f32_e32 v143, v35, v31
	v_add_f32_e32 v140, v140, v24
	v_add_f32_e32 v141, v141, v25
	v_add_f32_e32 v142, v142, v26
	v_add_f32_e32 v143, v143, v27
	v_add_f32_e32 v140, v140, v20
	v_add_f32_e32 v141, v141, v21
	v_add_f32_e32 v142, v142, v22
	v_add_f32_e32 v143, v143, v23
	v_add_f32_e32 v140, v140, v16
	v_add_f32_e32 v141, v141, v17
	v_add_f32_e32 v142, v142, v18
	v_add_f32_e32 v143, v143, v19
	v_mov_b32_e32 v151, 0x40a00000
	v_div_scale_f32 v146, s[26:27], v151, v151, v140
	v_rcp_f32_e32 v147, v146
	v_div_scale_f32 v148, vcc, v140, v151, v140
	v_fma_f32 v149, -v146, v147, 1.0
	v_fmac_f32_e32 v147, v149, v147
	v_mul_f32_e32 v149, v148, v147
	v_fma_f32 v150, -v146, v149, v148
	v_fmac_f32_e32 v149, v150, v147
	v_fma_f32 v146, -v146, v149, v148
	v_div_fmas_f32 v146, v146, v147, v149
	v_div_fixup_f32 v140, v146, v151, v140
	v_mov_b32_e32 v151, 0x40a00000
	v_div_scale_f32 v146, s[26:27], v151, v151, v141
	v_rcp_f32_e32 v147, v146
	v_div_scale_f32 v148, vcc, v141, v151, v141
	v_fma_f32 v149, -v146, v147, 1.0
	v_fmac_f32_e32 v147, v149, v147
	v_mul_f32_e32 v149, v148, v147
	v_fma_f32 v150, -v146, v149, v148
	v_fmac_f32_e32 v149, v150, v147
	v_fma_f32 v146, -v146, v149, v148
	v_div_fmas_f32 v146, v146, v147, v149
	v_div_fixup_f32 v141, v146, v151, v141
	v_mov_b32_e32 v151, 0x40a00000
	v_div_scale_f32 v146, s[26:27], v151, v151, v142
	v_rcp_f32_e32 v147, v146
	v_div_scale_f32 v148, vcc, v142, v151, v142
	v_fma_f32 v149, -v146, v147, 1.0
	v_fmac_f32_e32 v147, v149, v147
	v_mul_f32_e32 v149, v148, v147
	v_fma_f32 v150, -v146, v149, v148
	v_fmac_f32_e32 v149, v150, v147
	v_fma_f32 v146, -v146, v149, v148
	v_div_fmas_f32 v146, v146, v147, v149
	v_div_fixup_f32 v142, v146, v151, v142
	v_mov_b32_e32 v151, 0x40a00000
	v_div_scale_f32 v146, s[26:27], v151, v151, v143
	v_rcp_f32_e32 v147, v146
	v_div_scale_f32 v148, vcc, v143, v151, v143
	v_fma_f32 v149, -v146, v147, 1.0
	v_fmac_f32_e32 v147, v149, v147
	v_mul_f32_e32 v149, v148, v147
	v_fma_f32 v150, -v146, v149, v148
	v_fmac_f32_e32 v149, v150, v147
	v_fma_f32 v146, -v146, v149, v148
	v_div_fmas_f32 v146, v146, v147, v149
	v_div_fixup_f32 v143, v146, v151, v143
	v_sub_f32_e32 v140, v140, v32
	v_sub_f32_e32 v141, v141, v33
	v_sub_f32_e32 v142, v142, v34
	v_sub_f32_e32 v143, v143, v35
	v_cvt_pk_bf16_f32 v160, v140, v141
	v_cvt_pk_bf16_f32 v161, v142, v143
	s_waitcnt vmcnt(10)
; DI float bflo(unsigned u) { return __uint_as_float(u << 16); }
; DI float bfhi(unsigned u) { return __uint_as_float(u & 0xffff0000u); }
; template <int WIN>
; DI void pool_elem(const Params& p, int row, int c) {
;     ...
;     } else {
;       cnt = (float)(t + 1);
;       for (int j = 1; j <= t; ++j) {
;         unsigned w = *(const unsigned*)(P2 + (size_t)(row - j) * 2048 + c);
;         s0 += bflo(w); s1 += bfhi(w);
;       }
;     ...
;   *(unsigned*)(p.MIX + (size_t)row * 1024 + c) = pack2(s0 / cnt - u0, s1 / cnt - u1);
	v_and_b32_e32 v39, 0xffff0000, v37
	v_lshlrev_b32_e32 v38, 16, v37
	v_and_b32_e32 v37, 0xffff0000, v36
	v_lshlrev_b32_e32 v36, 16, v36
	v_add_f32_e32 v140, v36, v32
	v_add_f32_e32 v141, v37, v33
	v_add_f32_e32 v142, v38, v34
	v_add_f32_e32 v143, v39, v35
	v_add_f32_e32 v140, v140, v28
	v_add_f32_e32 v141, v141, v29
	v_add_f32_e32 v142, v142, v30
	v_add_f32_e32 v143, v143, v31
	v_add_f32_e32 v140, v140, v24
	v_add_f32_e32 v141, v141, v25
	v_add_f32_e32 v142, v142, v26
	v_add_f32_e32 v143, v143, v27
	v_add_f32_e32 v140, v140, v20
	v_add_f32_e32 v141, v141, v21
	v_add_f32_e32 v142, v142, v22
	v_add_f32_e32 v143, v143, v23
	v_add_f32_e32 v140, v140, v16
	v_add_f32_e32 v141, v141, v17
	v_add_f32_e32 v142, v142, v18
	v_add_f32_e32 v143, v143, v19
	v_mov_b32_e32 v151, 0x40c00000
	v_div_scale_f32 v146, s[26:27], v151, v151, v140
	v_rcp_f32_e32 v147, v146
	v_div_scale_f32 v148, vcc, v140, v151, v140
	v_fma_f32 v149, -v146, v147, 1.0
	v_fmac_f32_e32 v147, v149, v147
	v_mul_f32_e32 v149, v148, v147
	v_fma_f32 v150, -v146, v149, v148
	v_fmac_f32_e32 v149, v150, v147
	v_fma_f32 v146, -v146, v149, v148
	v_div_fmas_f32 v146, v146, v147, v149
	v_div_fixup_f32 v140, v146, v151, v140
	v_mov_b32_e32 v151, 0x40c00000
	v_div_scale_f32 v146, s[26:27], v151, v151, v141
	v_rcp_f32_e32 v147, v146
	v_div_scale_f32 v148, vcc, v141, v151, v141
	v_fma_f32 v149, -v146, v147, 1.0
	v_fmac_f32_e32 v147, v149, v147
	v_mul_f32_e32 v149, v148, v147
	v_fma_f32 v150, -v146, v149, v148
	v_fmac_f32_e32 v149, v150, v147
	v_fma_f32 v146, -v146, v149, v148
	v_div_fmas_f32 v146, v146, v147, v149
	v_div_fixup_f32 v141, v146, v151, v141
	v_mov_b32_e32 v151, 0x40c00000
	v_div_scale_f32 v146, s[26:27], v151, v151, v142
	v_rcp_f32_e32 v147, v146
	v_div_scale_f32 v148, vcc, v142, v151, v142
	v_fma_f32 v149, -v146, v147, 1.0
	v_fmac_f32_e32 v147, v149, v147
	v_mul_f32_e32 v149, v148, v147
	v_fma_f32 v150, -v146, v149, v148
	v_fmac_f32_e32 v149, v150, v147
	v_fma_f32 v146, -v146, v149, v148
	v_div_fmas_f32 v146, v146, v147, v149
	v_div_fixup_f32 v142, v146, v151, v142
	v_mov_b32_e32 v151, 0x40c00000
	v_div_scale_f32 v146, s[26:27], v151, v151, v143
	v_rcp_f32_e32 v147, v146
	v_div_scale_f32 v148, vcc, v143, v151, v143
	v_fma_f32 v149, -v146, v147, 1.0
	v_fmac_f32_e32 v147, v149, v147
	v_mul_f32_e32 v149, v148, v147
	v_fma_f32 v150, -v146, v149, v148
	v_fmac_f32_e32 v149, v150, v147
	v_fma_f32 v146, -v146, v149, v148
	v_div_fmas_f32 v146, v146, v147, v149
	v_div_fixup_f32 v143, v146, v151, v143
	v_sub_f32_e32 v140, v140, v36
	v_sub_f32_e32 v141, v141, v37
	v_sub_f32_e32 v142, v142, v38
	v_sub_f32_e32 v143, v143, v39
	v_cvt_pk_bf16_f32 v162, v140, v141
	v_cvt_pk_bf16_f32 v163, v142, v143
	s_waitcnt vmcnt(9)
	v_and_b32_e32 v43, 0xffff0000, v41
	v_lshlrev_b32_e32 v42, 16, v41
	v_and_b32_e32 v41, 0xffff0000, v40
	v_lshlrev_b32_e32 v40, 16, v40
	v_add_f32_e32 v140, v40, v36
	v_add_f32_e32 v141, v41, v37
	v_add_f32_e32 v142, v42, v38
	v_add_f32_e32 v143, v43, v39
	v_add_f32_e32 v140, v140, v32
	v_add_f32_e32 v141, v141, v33
	v_add_f32_e32 v142, v142, v34
	v_add_f32_e32 v143, v143, v35
	v_add_f32_e32 v140, v140, v28
	v_add_f32_e32 v141, v141, v29
	v_add_f32_e32 v142, v142, v30
	v_add_f32_e32 v143, v143, v31
	v_add_f32_e32 v140, v140, v24
	v_add_f32_e32 v141, v141, v25
	v_add_f32_e32 v142, v142, v26
	v_add_f32_e32 v143, v143, v27
	v_add_f32_e32 v140, v140, v20
	v_add_f32_e32 v141, v141, v21
	v_add_f32_e32 v142, v142, v22
	v_add_f32_e32 v143, v143, v23
	v_add_f32_e32 v140, v140, v16
	v_add_f32_e32 v141, v141, v17
	v_add_f32_e32 v142, v142, v18
	v_add_f32_e32 v143, v143, v19
	v_mov_b32_e32 v151, 0x40e00000
	v_div_scale_f32 v146, s[26:27], v151, v151, v140
	v_rcp_f32_e32 v147, v146
	v_div_scale_f32 v148, vcc, v140, v151, v140
	v_fma_f32 v149, -v146, v147, 1.0
	v_fmac_f32_e32 v147, v149, v147
	v_mul_f32_e32 v149, v148, v147
	v_fma_f32 v150, -v146, v149, v148
	v_fmac_f32_e32 v149, v150, v147
	v_fma_f32 v146, -v146, v149, v148
	v_div_fmas_f32 v146, v146, v147, v149
	v_div_fixup_f32 v140, v146, v151, v140
	v_mov_b32_e32 v151, 0x40e00000
	v_div_scale_f32 v146, s[26:27], v151, v151, v141
	v_rcp_f32_e32 v147, v146
	v_div_scale_f32 v148, vcc, v141, v151, v141
	v_fma_f32 v149, -v146, v147, 1.0
	v_fmac_f32_e32 v147, v149, v147
	v_mul_f32_e32 v149, v148, v147
	v_fma_f32 v150, -v146, v149, v148
	v_fmac_f32_e32 v149, v150, v147
	v_fma_f32 v146, -v146, v149, v148
	v_div_fmas_f32 v146, v146, v147, v149
	v_div_fixup_f32 v141, v146, v151, v141
	v_mov_b32_e32 v151, 0x40e00000
	v_div_scale_f32 v146, s[26:27], v151, v151, v142
	v_rcp_f32_e32 v147, v146
	v_div_scale_f32 v148, vcc, v142, v151, v142
	v_fma_f32 v149, -v146, v147, 1.0
	v_fmac_f32_e32 v147, v149, v147
	v_mul_f32_e32 v149, v148, v147
	v_fma_f32 v150, -v146, v149, v148
	v_fmac_f32_e32 v149, v150, v147
	v_fma_f32 v146, -v146, v149, v148
	v_div_fmas_f32 v146, v146, v147, v149
	v_div_fixup_f32 v142, v146, v151, v142
	v_mov_b32_e32 v151, 0x40e00000
	v_div_scale_f32 v146, s[26:27], v151, v151, v143
	v_rcp_f32_e32 v147, v146
	v_div_scale_f32 v148, vcc, v143, v151, v143
	v_fma_f32 v149, -v146, v147, 1.0
	v_fmac_f32_e32 v147, v149, v147
	v_mul_f32_e32 v149, v148, v147
	v_fma_f32 v150, -v146, v149, v148
	v_fmac_f32_e32 v149, v150, v147
	v_fma_f32 v146, -v146, v149, v148
	v_div_fmas_f32 v146, v146, v147, v149
	v_div_fixup_f32 v143, v146, v151, v143
	v_sub_f32_e32 v140, v140, v40
	v_sub_f32_e32 v141, v141, v41
	v_sub_f32_e32 v142, v142, v42
	v_sub_f32_e32 v143, v143, v43
	v_cvt_pk_bf16_f32 v164, v140, v141
	v_cvt_pk_bf16_f32 v165, v142, v143
	s_waitcnt vmcnt(8)
; DI float bflo(unsigned u) { return __uint_as_float(u << 16); }
; DI float bfhi(unsigned u) { return __uint_as_float(u & 0xffff0000u); }
; template <int WIN>
; DI void pool_elem(const Params& p, int row, int c) {
;     ...
;     } else {
;       cnt = (float)(t + 1);
;       for (int j = 1; j <= t; ++j) {
;         unsigned w = *(const unsigned*)(P2 + (size_t)(row - j) * 2048 + c);
;         s0 += bflo(w); s1 += bfhi(w);
;       }
;     ...
;   *(unsigned*)(p.MIX + (size_t)row * 1024 + c) = pack2(s0 / cnt - u0, s1 / cnt - u1);
	v_and_b32_e32 v47, 0xffff0000, v45
	v_lshlrev_b32_e32 v46, 16, v45
	v_and_b32_e32 v45, 0xffff0000, v44
	v_lshlrev_b32_e32 v44, 16, v44
	v_add_f32_e32 v140, v44, v40
	v_add_f32_e32 v141, v45, v41
	v_add_f32_e32 v142, v46, v42
	v_add_f32_e32 v143, v47, v43
	v_add_f32_e32 v140, v140, v36
	v_add_f32_e32 v141, v141, v37
	v_add_f32_e32 v142, v142, v38
	v_add_f32_e32 v143, v143, v39
	v_add_f32_e32 v140, v140, v32
	v_add_f32_e32 v141, v141, v33
	v_add_f32_e32 v142, v142, v34
	v_add_f32_e32 v143, v143, v35
	v_add_f32_e32 v140, v140, v28
	v_add_f32_e32 v141, v141, v29
	v_add_f32_e32 v142, v142, v30
	v_add_f32_e32 v143, v143, v31
	v_add_f32_e32 v140, v140, v24
	v_add_f32_e32 v141, v141, v25
	v_add_f32_e32 v142, v142, v26
	v_add_f32_e32 v143, v143, v27
	v_add_f32_e32 v140, v140, v20
	v_add_f32_e32 v141, v141, v21
	v_add_f32_e32 v142, v142, v22
	v_add_f32_e32 v143, v143, v23
	v_add_f32_e32 v140, v140, v16
	v_add_f32_e32 v141, v141, v17
	v_add_f32_e32 v142, v142, v18
	v_add_f32_e32 v143, v143, v19
	v_mul_f32_e32 v140, 0x3e000000, v140
	v_mul_f32_e32 v141, 0x3e000000, v141
	v_mul_f32_e32 v142, 0x3e000000, v142
	v_mul_f32_e32 v143, 0x3e000000, v143
	v_sub_f32_e32 v140, v140, v44
	v_sub_f32_e32 v141, v141, v45
	v_sub_f32_e32 v142, v142, v46
	v_sub_f32_e32 v143, v143, v47
	v_cvt_pk_bf16_f32 v166, v140, v141
	v_cvt_pk_bf16_f32 v167, v142, v143
	s_waitcnt vmcnt(7)
	v_and_b32_e32 v51, 0xffff0000, v49
	v_lshlrev_b32_e32 v50, 16, v49
	v_and_b32_e32 v49, 0xffff0000, v48
	v_lshlrev_b32_e32 v48, 16, v48
	v_add_f32_e32 v140, v48, v44
	v_add_f32_e32 v141, v49, v45
	v_add_f32_e32 v142, v50, v46
	v_add_f32_e32 v143, v51, v47
	v_add_f32_e32 v140, v140, v40
	v_add_f32_e32 v141, v141, v41
	v_add_f32_e32 v142, v142, v42
	v_add_f32_e32 v143, v143, v43
	v_add_f32_e32 v140, v140, v36
	v_add_f32_e32 v141, v141, v37
	v_add_f32_e32 v142, v142, v38
	v_add_f32_e32 v143, v143, v39
	v_add_f32_e32 v140, v140, v32
	v_add_f32_e32 v141, v141, v33
	v_add_f32_e32 v142, v142, v34
	v_add_f32_e32 v143, v143, v35
	v_add_f32_e32 v140, v140, v28
	v_add_f32_e32 v141, v141, v29
	v_add_f32_e32 v142, v142, v30
	v_add_f32_e32 v143, v143, v31
	v_add_f32_e32 v140, v140, v24
	v_add_f32_e32 v141, v141, v25
	v_add_f32_e32 v142, v142, v26
	v_add_f32_e32 v143, v143, v27
	v_add_f32_e32 v140, v140, v20
	v_add_f32_e32 v141, v141, v21
	v_add_f32_e32 v142, v142, v22
	v_add_f32_e32 v143, v143, v23
	v_mul_f32_e32 v140, 0x3e000000, v140
	v_mul_f32_e32 v141, 0x3e000000, v141
	v_mul_f32_e32 v142, 0x3e000000, v142
	v_mul_f32_e32 v143, 0x3e000000, v143
	v_sub_f32_e32 v140, v140, v48
	v_sub_f32_e32 v141, v141, v49
	v_sub_f32_e32 v142, v142, v50
	v_sub_f32_e32 v143, v143, v51
	v_cvt_pk_bf16_f32 v168, v140, v141
	v_cvt_pk_bf16_f32 v169, v142, v143
	s_waitcnt vmcnt(6)
	v_and_b32_e32 v55, 0xffff0000, v53
	v_lshlrev_b32_e32 v54, 16, v53
	v_and_b32_e32 v53, 0xffff0000, v52
	v_lshlrev_b32_e32 v52, 16, v52
	v_add_f32_e32 v140, v52, v48
	v_add_f32_e32 v141, v53, v49
	v_add_f32_e32 v142, v54, v50
	v_add_f32_e32 v143, v55, v51
	v_add_f32_e32 v140, v140, v44
	v_add_f32_e32 v141, v141, v45
	v_add_f32_e32 v142, v142, v46
	v_add_f32_e32 v143, v143, v47
	v_add_f32_e32 v140, v140, v40
	v_add_f32_e32 v141, v141, v41
	v_add_f32_e32 v142, v142, v42
	v_add_f32_e32 v143, v143, v43
	v_add_f32_e32 v140, v140, v36
	v_add_f32_e32 v141, v141, v37
	v_add_f32_e32 v142, v142, v38
	v_add_f32_e32 v143, v143, v39
	v_add_f32_e32 v140, v140, v32
	v_add_f32_e32 v141, v141, v33
	v_add_f32_e32 v142, v142, v34
	v_add_f32_e32 v143, v143, v35
	v_add_f32_e32 v140, v140, v28
	v_add_f32_e32 v141, v141, v29
	v_add_f32_e32 v142, v142, v30
	v_add_f32_e32 v143, v143, v31
	v_add_f32_e32 v140, v140, v24
	v_add_f32_e32 v141, v141, v25
	v_add_f32_e32 v142, v142, v26
	v_add_f32_e32 v143, v143, v27
	v_mul_f32_e32 v140, 0x3e000000, v140
	v_mul_f32_e32 v141, 0x3e000000, v141
	v_mul_f32_e32 v142, 0x3e000000, v142
	v_mul_f32_e32 v143, 0x3e000000, v143
	v_sub_f32_e32 v140, v140, v52
	v_sub_f32_e32 v141, v141, v53
	v_sub_f32_e32 v142, v142, v54
	v_sub_f32_e32 v143, v143, v55
	v_cvt_pk_bf16_f32 v170, v140, v141
	v_cvt_pk_bf16_f32 v171, v142, v143
	s_waitcnt vmcnt(5)
	v_and_b32_e32 v59, 0xffff0000, v57
	v_lshlrev_b32_e32 v58, 16, v57
	v_and_b32_e32 v57, 0xffff0000, v56
	v_lshlrev_b32_e32 v56, 16, v56
	v_add_f32_e32 v140, v56, v52
	v_add_f32_e32 v141, v57, v53
	v_add_f32_e32 v142, v58, v54
	v_add_f32_e32 v143, v59, v55
	v_add_f32_e32 v140, v140, v48
	v_add_f32_e32 v141, v141, v49
	v_add_f32_e32 v142, v142, v50
	v_add_f32_e32 v143, v143, v51
	v_add_f32_e32 v140, v140, v44
	v_add_f32_e32 v141, v141, v45
	v_add_f32_e32 v142, v142, v46
	v_add_f32_e32 v143, v143, v47
	v_add_f32_e32 v140, v140, v40
	v_add_f32_e32 v141, v141, v41
	v_add_f32_e32 v142, v142, v42
	v_add_f32_e32 v143, v143, v43
	v_add_f32_e32 v140, v140, v36
	v_add_f32_e32 v141, v141, v37
	v_add_f32_e32 v142, v142, v38
	v_add_f32_e32 v143, v143, v39
	v_add_f32_e32 v140, v140, v32
	v_add_f32_e32 v141, v141, v33
	v_add_f32_e32 v142, v142, v34
	v_add_f32_e32 v143, v143, v35
	v_add_f32_e32 v140, v140, v28
	v_add_f32_e32 v141, v141, v29
	v_add_f32_e32 v142, v142, v30
	v_add_f32_e32 v143, v143, v31
	v_mul_f32_e32 v140, 0x3e000000, v140
	v_mul_f32_e32 v141, 0x3e000000, v141
	v_mul_f32_e32 v142, 0x3e000000, v142
	v_mul_f32_e32 v143, 0x3e000000, v143
	v_sub_f32_e32 v140, v140, v56
	v_sub_f32_e32 v141, v141, v57
	v_sub_f32_e32 v142, v142, v58
	v_sub_f32_e32 v143, v143, v59
	v_cvt_pk_bf16_f32 v172, v140, v141
	v_cvt_pk_bf16_f32 v173, v142, v143
	s_waitcnt vmcnt(4)
; DI float bflo(unsigned u) { return __uint_as_float(u << 16); }
; DI float bfhi(unsigned u) { return __uint_as_float(u & 0xffff0000u); }
; template <int WIN>
; DI void pool_elem(const Params& p, int row, int c) {
;     ...
;     } else {
;       cnt = (float)(t + 1);
;       for (int j = 1; j <= t; ++j) {
;         unsigned w = *(const unsigned*)(P2 + (size_t)(row - j) * 2048 + c);
;         s0 += bflo(w); s1 += bfhi(w);
;       }
;     ...
;   *(unsigned*)(p.MIX + (size_t)row * 1024 + c) = pack2(s0 / cnt - u0, s1 / cnt - u1);
	v_and_b32_e32 v63, 0xffff0000, v61
	v_lshlrev_b32_e32 v62, 16, v61
	v_and_b32_e32 v61, 0xffff0000, v60
	v_lshlrev_b32_e32 v60, 16, v60
	v_add_f32_e32 v140, v60, v56
	v_add_f32_e32 v141, v61, v57
	v_add_f32_e32 v142, v62, v58
	v_add_f32_e32 v143, v63, v59
	v_add_f32_e32 v140, v140, v52
	v_add_f32_e32 v141, v141, v53
	v_add_f32_e32 v142, v142, v54
	v_add_f32_e32 v143, v143, v55
	v_add_f32_e32 v140, v140, v48
	v_add_f32_e32 v141, v141, v49
	v_add_f32_e32 v142, v142, v50
	v_add_f32_e32 v143, v143, v51
	v_add_f32_e32 v140, v140, v44
	v_add_f32_e32 v141, v141, v45
	v_add_f32_e32 v142, v142, v46
	v_add_f32_e32 v143, v143, v47
	v_add_f32_e32 v140, v140, v40
	v_add_f32_e32 v141, v141, v41
	v_add_f32_e32 v142, v142, v42
	v_add_f32_e32 v143, v143, v43
	v_add_f32_e32 v140, v140, v36
	v_add_f32_e32 v141, v141, v37
	v_add_f32_e32 v142, v142, v38
	v_add_f32_e32 v143, v143, v39
	v_add_f32_e32 v140, v140, v32
	v_add_f32_e32 v141, v141, v33
	v_add_f32_e32 v142, v142, v34
	v_add_f32_e32 v143, v143, v35
	v_mul_f32_e32 v140, 0x3e000000, v140
	v_mul_f32_e32 v141, 0x3e000000, v141
	v_mul_f32_e32 v142, 0x3e000000, v142
	v_mul_f32_e32 v143, 0x3e000000, v143
	v_sub_f32_e32 v140, v140, v60
	v_sub_f32_e32 v141, v141, v61
	v_sub_f32_e32 v142, v142, v62
	v_sub_f32_e32 v143, v143, v63
	v_cvt_pk_bf16_f32 v174, v140, v141
	v_cvt_pk_bf16_f32 v175, v142, v143
	s_waitcnt vmcnt(3)
	v_and_b32_e32 v67, 0xffff0000, v65
	v_lshlrev_b32_e32 v66, 16, v65
	v_and_b32_e32 v65, 0xffff0000, v64
	v_lshlrev_b32_e32 v64, 16, v64
	v_add_f32_e32 v140, v64, v60
	v_add_f32_e32 v141, v65, v61
	v_add_f32_e32 v142, v66, v62
	v_add_f32_e32 v143, v67, v63
	v_add_f32_e32 v140, v140, v56
	v_add_f32_e32 v141, v141, v57
	v_add_f32_e32 v142, v142, v58
	v_add_f32_e32 v143, v143, v59
	v_add_f32_e32 v140, v140, v52
	v_add_f32_e32 v141, v141, v53
	v_add_f32_e32 v142, v142, v54
	v_add_f32_e32 v143, v143, v55
	v_add_f32_e32 v140, v140, v48
	v_add_f32_e32 v141, v141, v49
	v_add_f32_e32 v142, v142, v50
	v_add_f32_e32 v143, v143, v51
	v_add_f32_e32 v140, v140, v44
	v_add_f32_e32 v141, v141, v45
	v_add_f32_e32 v142, v142, v46
	v_add_f32_e32 v143, v143, v47
	v_add_f32_e32 v140, v140, v40
	v_add_f32_e32 v141, v141, v41
	v_add_f32_e32 v142, v142, v42
	v_add_f32_e32 v143, v143, v43
	v_add_f32_e32 v140, v140, v36
	v_add_f32_e32 v141, v141, v37
	v_add_f32_e32 v142, v142, v38
	v_add_f32_e32 v143, v143, v39
	v_mul_f32_e32 v140, 0x3e000000, v140
	v_mul_f32_e32 v141, 0x3e000000, v141
	v_mul_f32_e32 v142, 0x3e000000, v142
	v_mul_f32_e32 v143, 0x3e000000, v143
	v_sub_f32_e32 v140, v140, v64
	v_sub_f32_e32 v141, v141, v65
	v_sub_f32_e32 v142, v142, v66
	v_sub_f32_e32 v143, v143, v67
	v_cvt_pk_bf16_f32 v176, v140, v141
	v_cvt_pk_bf16_f32 v177, v142, v143
	s_waitcnt vmcnt(2)
	v_and_b32_e32 v71, 0xffff0000, v69
	v_lshlrev_b32_e32 v70, 16, v69
	v_and_b32_e32 v69, 0xffff0000, v68
	v_lshlrev_b32_e32 v68, 16, v68
	v_add_f32_e32 v140, v68, v64
	v_add_f32_e32 v141, v69, v65
	v_add_f32_e32 v142, v70, v66
	v_add_f32_e32 v143, v71, v67
	v_add_f32_e32 v140, v140, v60
	v_add_f32_e32 v141, v141, v61
	v_add_f32_e32 v142, v142, v62
	v_add_f32_e32 v143, v143, v63
	v_add_f32_e32 v140, v140, v56
	v_add_f32_e32 v141, v141, v57
	v_add_f32_e32 v142, v142, v58
	v_add_f32_e32 v143, v143, v59
	v_add_f32_e32 v140, v140, v52
	v_add_f32_e32 v141, v141, v53
	v_add_f32_e32 v142, v142, v54
	v_add_f32_e32 v143, v143, v55
	v_add_f32_e32 v140, v140, v48
	v_add_f32_e32 v141, v141, v49
	v_add_f32_e32 v142, v142, v50
	v_add_f32_e32 v143, v143, v51
	v_add_f32_e32 v140, v140, v44
	v_add_f32_e32 v141, v141, v45
	v_add_f32_e32 v142, v142, v46
	v_add_f32_e32 v143, v143, v47
	v_add_f32_e32 v140, v140, v40
	v_add_f32_e32 v141, v141, v41
	v_add_f32_e32 v142, v142, v42
	v_add_f32_e32 v143, v143, v43
	v_mul_f32_e32 v140, 0x3e000000, v140
	v_mul_f32_e32 v141, 0x3e000000, v141
	v_mul_f32_e32 v142, 0x3e000000, v142
	v_mul_f32_e32 v143, 0x3e000000, v143
	v_sub_f32_e32 v140, v140, v68
	v_sub_f32_e32 v141, v141, v69
	v_sub_f32_e32 v142, v142, v70
	v_sub_f32_e32 v143, v143, v71
	v_cvt_pk_bf16_f32 v178, v140, v141
	v_cvt_pk_bf16_f32 v179, v142, v143
	s_waitcnt vmcnt(1)
	v_and_b32_e32 v75, 0xffff0000, v73
	v_lshlrev_b32_e32 v74, 16, v73
	v_and_b32_e32 v73, 0xffff0000, v72
	v_lshlrev_b32_e32 v72, 16, v72
	v_add_f32_e32 v140, v72, v68
	v_add_f32_e32 v141, v73, v69
	v_add_f32_e32 v142, v74, v70
	v_add_f32_e32 v143, v75, v71
	v_add_f32_e32 v140, v140, v64
	v_add_f32_e32 v141, v141, v65
	v_add_f32_e32 v142, v142, v66
	v_add_f32_e32 v143, v143, v67
	v_add_f32_e32 v140, v140, v60
	v_add_f32_e32 v141, v141, v61
	v_add_f32_e32 v142, v142, v62
	v_add_f32_e32 v143, v143, v63
	v_add_f32_e32 v140, v140, v56
	v_add_f32_e32 v141, v141, v57
	v_add_f32_e32 v142, v142, v58
	v_add_f32_e32 v143, v143, v59
	v_add_f32_e32 v140, v140, v52
	v_add_f32_e32 v141, v141, v53
	v_add_f32_e32 v142, v142, v54
	v_add_f32_e32 v143, v143, v55
	v_add_f32_e32 v140, v140, v48
	v_add_f32_e32 v141, v141, v49
	v_add_f32_e32 v142, v142, v50
	v_add_f32_e32 v143, v143, v51
	v_add_f32_e32 v140, v140, v44
	v_add_f32_e32 v141, v141, v45
	v_add_f32_e32 v142, v142, v46
	v_add_f32_e32 v143, v143, v47
	v_mul_f32_e32 v140, 0x3e000000, v140
	v_mul_f32_e32 v141, 0x3e000000, v141
	v_mul_f32_e32 v142, 0x3e000000, v142
	v_mul_f32_e32 v143, 0x3e000000, v143
	v_sub_f32_e32 v140, v140, v72
	v_sub_f32_e32 v141, v141, v73
	v_sub_f32_e32 v142, v142, v74
	v_sub_f32_e32 v143, v143, v75
	v_cvt_pk_bf16_f32 v180, v140, v141
	v_cvt_pk_bf16_f32 v181, v142, v143
	s_waitcnt vmcnt(0)
; DI float bflo(unsigned u) { return __uint_as_float(u << 16); }
; DI float bfhi(unsigned u) { return __uint_as_float(u & 0xffff0000u); }
; template <int WIN>
; DI void pool_elem(const Params& p, int row, int c) {
;     ...
;     } else {
;       cnt = (float)(t + 1);
;       for (int j = 1; j <= t; ++j) {
;         unsigned w = *(const unsigned*)(P2 + (size_t)(row - j) * 2048 + c);
;         s0 += bflo(w); s1 += bfhi(w);
;       }
;     ...
;   *(unsigned*)(p.MIX + (size_t)row * 1024 + c) = pack2(s0 / cnt - u0, s1 / cnt - u1);
	v_and_b32_e32 v79, 0xffff0000, v77
	v_lshlrev_b32_e32 v78, 16, v77
	v_and_b32_e32 v77, 0xffff0000, v76
	v_lshlrev_b32_e32 v76, 16, v76
	v_add_f32_e32 v140, v76, v72
	v_add_f32_e32 v141, v77, v73
	v_add_f32_e32 v142, v78, v74
	v_add_f32_e32 v143, v79, v75
	v_add_f32_e32 v140, v140, v68
	v_add_f32_e32 v141, v141, v69
	v_add_f32_e32 v142, v142, v70
	v_add_f32_e32 v143, v143, v71
	v_add_f32_e32 v140, v140, v64
	v_add_f32_e32 v141, v141, v65
	v_add_f32_e32 v142, v142, v66
	v_add_f32_e32 v143, v143, v67
	v_add_f32_e32 v140, v140, v60
	v_add_f32_e32 v141, v141, v61
	v_add_f32_e32 v142, v142, v62
	v_add_f32_e32 v143, v143, v63
	v_add_f32_e32 v140, v140, v56
	v_add_f32_e32 v141, v141, v57
	v_add_f32_e32 v142, v142, v58
	v_add_f32_e32 v143, v143, v59
	v_add_f32_e32 v140, v140, v52
	v_add_f32_e32 v141, v141, v53
	v_add_f32_e32 v142, v142, v54
	v_add_f32_e32 v143, v143, v55
	v_add_f32_e32 v140, v140, v48
	v_add_f32_e32 v141, v141, v49
	v_add_f32_e32 v142, v142, v50
	v_add_f32_e32 v143, v143, v51
	v_mul_f32_e32 v140, 0x3e000000, v140
	v_mul_f32_e32 v141, 0x3e000000, v141
	v_mul_f32_e32 v142, 0x3e000000, v142
	v_mul_f32_e32 v143, 0x3e000000, v143
	v_sub_f32_e32 v140, v140, v76
	v_sub_f32_e32 v141, v141, v77
	v_sub_f32_e32 v142, v142, v78
	v_sub_f32_e32 v143, v143, v79
	v_cvt_pk_bf16_f32 v182, v140, v141
	v_cvt_pk_bf16_f32 v183, v142, v143
	global_store_dwordx2 v11, v[152:153], s[24:25] sc1
	s_add_u32 s24, s24, 0x800
	s_addc_u32 s25, s25, 0
	global_store_dwordx2 v11, v[154:155], s[24:25] sc1
	s_add_u32 s24, s24, 0x800
	s_addc_u32 s25, s25, 0
	global_store_dwordx2 v11, v[156:157], s[24:25] sc1
	s_add_u32 s24, s24, 0x800
	s_addc_u32 s25, s25, 0
	global_store_dwordx2 v11, v[158:159], s[24:25] sc1
	s_add_u32 s24, s24, 0x800
	s_addc_u32 s25, s25, 0
	global_store_dwordx2 v11, v[160:161], s[24:25] sc1
	s_add_u32 s24, s24, 0x800
	s_addc_u32 s25, s25, 0
	global_store_dwordx2 v11, v[162:163], s[24:25] sc1
	s_add_u32 s24, s24, 0x800
	s_addc_u32 s25, s25, 0
	global_store_dwordx2 v11, v[164:165], s[24:25] sc1
	s_add_u32 s24, s24, 0x800
	s_addc_u32 s25, s25, 0
	global_store_dwordx2 v11, v[166:167], s[24:25] sc1
	s_add_u32 s24, s24, 0x800
	s_addc_u32 s25, s25, 0
	global_store_dwordx2 v11, v[168:169], s[24:25] sc1
	s_add_u32 s24, s24, 0x800
	s_addc_u32 s25, s25, 0
	global_store_dwordx2 v11, v[170:171], s[24:25] sc1
	s_add_u32 s24, s24, 0x800
	s_addc_u32 s25, s25, 0
	global_store_dwordx2 v11, v[172:173], s[24:25] sc1
	s_add_u32 s24, s24, 0x800
	s_addc_u32 s25, s25, 0
	global_store_dwordx2 v11, v[174:175], s[24:25] sc1
	s_add_u32 s24, s24, 0x800
	s_addc_u32 s25, s25, 0
	global_store_dwordx2 v11, v[176:177], s[24:25] sc1
	s_add_u32 s24, s24, 0x800
	s_addc_u32 s25, s25, 0
	global_store_dwordx2 v11, v[178:179], s[24:25] sc1
	s_add_u32 s24, s24, 0x800
	s_addc_u32 s25, s25, 0
	global_store_dwordx2 v11, v[180:181], s[24:25] sc1
	s_add_u32 s24, s24, 0x800
	s_addc_u32 s25, s25, 0
	global_store_dwordx2 v11, v[182:183], s[24:25] sc1
	s_add_u32 s24, s24, 0x800
	s_addc_u32 s25, s25, 0
	s_branch .Lp13f_next
.Lp13f_f3:
	s_sub_u32 s26, s20, 0
	s_lshl_b32 s27, s26, 12
	s_lshr_b32 s28, s26, 20
	s_add_u32 s22, s8, s27
	s_addc_u32 s23, s9, s28
	global_load_dwordx2 v[16:17], v11, s[22:23]
	s_add_u32 s22, s22, 0x1000
	s_addc_u32 s23, s23, 0
	global_load_dwordx2 v[20:21], v11, s[22:23]
	s_add_u32 s22, s22, 0x1000
	s_addc_u32 s23, s23, 0
	global_load_dwordx2 v[24:25], v11, s[22:23]
	s_add_u32 s22, s22, 0x1000
	s_addc_u32 s23, s23, 0
	global_load_dwordx2 v[28:29], v11, s[22:23]
	s_add_u32 s22, s22, 0x1000
	s_addc_u32 s23, s23, 0
	global_load_dwordx2 v[32:33], v11, s[22:23]
	s_add_u32 s22, s22, 0x1000
	s_addc_u32 s23, s23, 0
	global_load_dwordx2 v[36:37], v11, s[22:23]
	s_add_u32 s22, s22, 0x1000
	s_addc_u32 s23, s23, 0
	global_load_dwordx2 v[40:41], v11, s[22:23]
	s_add_u32 s22, s22, 0x1000
	s_addc_u32 s23, s23, 0
	global_load_dwordx2 v[44:45], v11, s[22:23]
	s_add_u32 s22, s22, 0x1000
	s_addc_u32 s23, s23, 0
	global_load_dwordx2 v[48:49], v11, s[22:23]
	s_add_u32 s22, s22, 0x1000
	s_addc_u32 s23, s23, 0
	global_load_dwordx2 v[52:53], v11, s[22:23]
	s_add_u32 s22, s22, 0x1000
	s_addc_u32 s23, s23, 0
	global_load_dwordx2 v[56:57], v11, s[22:23]
	s_add_u32 s22, s22, 0x1000
	s_addc_u32 s23, s23, 0
	global_load_dwordx2 v[60:61], v11, s[22:23]
	s_add_u32 s22, s22, 0x1000
	s_addc_u32 s23, s23, 0
	global_load_dwordx2 v[64:65], v11, s[22:23]
	s_add_u32 s22, s22, 0x1000
	s_addc_u32 s23, s23, 0
	global_load_dwordx2 v[68:69], v11, s[22:23]
	s_add_u32 s22, s22, 0x1000
	s_addc_u32 s23, s23, 0
	global_load_dwordx2 v[72:73], v11, s[22:23]
	s_add_u32 s22, s22, 0x1000
	s_addc_u32 s23, s23, 0
	global_load_dwordx2 v[76:77], v11, s[22:23]
	s_add_u32 s22, s22, 0x1000
	s_addc_u32 s23, s23, 0
	s_waitcnt vmcnt(15)
	v_and_b32_e32 v19, 0xffff0000, v17
	v_lshlrev_b32_e32 v18, 16, v17
	v_and_b32_e32 v17, 0xffff0000, v16
	v_lshlrev_b32_e32 v16, 16, v16
	v_mov_b32_e32 v140, v16
	v_mov_b32_e32 v141, v17
	v_mov_b32_e32 v142, v18
	v_mov_b32_e32 v143, v19
	v_mul_f32_e32 v140, 1.0, v140
	v_mul_f32_e32 v141, 1.0, v141
	v_mul_f32_e32 v142, 1.0, v142
	v_mul_f32_e32 v143, 1.0, v143
	v_sub_f32_e32 v140, v140, v16
	v_sub_f32_e32 v141, v141, v17
	v_sub_f32_e32 v142, v142, v18
	v_sub_f32_e32 v143, v143, v19
	v_cvt_pk_bf16_f32 v152, v140, v141
	v_cvt_pk_bf16_f32 v153, v142, v143
	s_waitcnt vmcnt(14)
	v_and_b32_e32 v23, 0xffff0000, v21
	v_lshlrev_b32_e32 v22, 16, v21
	v_and_b32_e32 v21, 0xffff0000, v20
	v_lshlrev_b32_e32 v20, 16, v20
	v_add_f32_e32 v140, v20, v16
	v_add_f32_e32 v141, v21, v17
	v_add_f32_e32 v142, v22, v18
	v_add_f32_e32 v143, v23, v19
	v_mul_f32_e32 v140, 0.5, v140
	v_mul_f32_e32 v141, 0.5, v141
	v_mul_f32_e32 v142, 0.5, v142
	v_mul_f32_e32 v143, 0.5, v143
	v_sub_f32_e32 v140, v140, v20
	v_sub_f32_e32 v141, v141, v21
	v_sub_f32_e32 v142, v142, v22
	v_sub_f32_e32 v143, v143, v23
	v_cvt_pk_bf16_f32 v154, v140, v141
	v_cvt_pk_bf16_f32 v155, v142, v143
	s_waitcnt vmcnt(13)
; DI float bflo(unsigned u) { return __uint_as_float(u << 16); }
; DI float bfhi(unsigned u) { return __uint_as_float(u & 0xffff0000u); }
; template <int WIN>
; DI void pool_elem(const Params& p, int row, int c) {
;     ...
;     } else {
;       cnt = (float)(t + 1);
;       for (int j = 1; j <= t; ++j) {
;         unsigned w = *(const unsigned*)(P2 + (size_t)(row - j) * 2048 + c);
;         s0 += bflo(w); s1 += bfhi(w);
;       }
;     ...
;   *(unsigned*)(p.MIX + (size_t)row * 1024 + c) = pack2(s0 / cnt - u0, s1 / cnt - u1);
	v_and_b32_e32 v27, 0xffff0000, v25
	v_lshlrev_b32_e32 v26, 16, v25
	v_and_b32_e32 v25, 0xffff0000, v24
	v_lshlrev_b32_e32 v24, 16, v24
	v_add_f32_e32 v140, v24, v20
	v_add_f32_e32 v141, v25, v21
	v_add_f32_e32 v142, v26, v22
	v_add_f32_e32 v143, v27, v23
	v_add_f32_e32 v140, v140, v16
	v_add_f32_e32 v141, v141, v17
	v_add_f32_e32 v142, v142, v18
	v_add_f32_e32 v143, v143, v19
	v_mov_b32_e32 v151, 0x40400000
	v_div_scale_f32 v146, s[26:27], v151, v151, v140
	v_rcp_f32_e32 v147, v146
	v_div_scale_f32 v148, vcc, v140, v151, v140
	v_fma_f32 v149, -v146, v147, 1.0
	v_fmac_f32_e32 v147, v149, v147
	v_mul_f32_e32 v149, v148, v147
	v_fma_f32 v150, -v146, v149, v148
	v_fmac_f32_e32 v149, v150, v147
	v_fma_f32 v146, -v146, v149, v148
	v_div_fmas_f32 v146, v146, v147, v149
	v_div_fixup_f32 v140, v146, v151, v140
	v_mov_b32_e32 v151, 0x40400000
	v_div_scale_f32 v146, s[26:27], v151, v151, v141
	v_rcp_f32_e32 v147, v146
	v_div_scale_f32 v148, vcc, v141, v151, v141
	v_fma_f32 v149, -v146, v147, 1.0
	v_fmac_f32_e32 v147, v149, v147
	v_mul_f32_e32 v149, v148, v147
	v_fma_f32 v150, -v146, v149, v148
	v_fmac_f32_e32 v149, v150, v147
	v_fma_f32 v146, -v146, v149, v148
	v_div_fmas_f32 v146, v146, v147, v149
	v_div_fixup_f32 v141, v146, v151, v141
	v_mov_b32_e32 v151, 0x40400000
	v_div_scale_f32 v146, s[26:27], v151, v151, v142
	v_rcp_f32_e32 v147, v146
	v_div_scale_f32 v148, vcc, v142, v151, v142
	v_fma_f32 v149, -v146, v147, 1.0
	v_fmac_f32_e32 v147, v149, v147
	v_mul_f32_e32 v149, v148, v147
	v_fma_f32 v150, -v146, v149, v148
	v_fmac_f32_e32 v149, v150, v147
	v_fma_f32 v146, -v146, v149, v148
	v_div_fmas_f32 v146, v146, v147, v149
	v_div_fixup_f32 v142, v146, v151, v142
	v_mov_b32_e32 v151, 0x40400000
	v_div_scale_f32 v146, s[26:27], v151, v151, v143
	v_rcp_f32_e32 v147, v146
	v_div_scale_f32 v148, vcc, v143, v151, v143
	v_fma_f32 v149, -v146, v147, 1.0
	v_fmac_f32_e32 v147, v149, v147
	v_mul_f32_e32 v149, v148, v147
	v_fma_f32 v150, -v146, v149, v148
	v_fmac_f32_e32 v149, v150, v147
	v_fma_f32 v146, -v146, v149, v148
	v_div_fmas_f32 v146, v146, v147, v149
	v_div_fixup_f32 v143, v146, v151, v143
	v_sub_f32_e32 v140, v140, v24
	v_sub_f32_e32 v141, v141, v25
	v_sub_f32_e32 v142, v142, v26
	v_sub_f32_e32 v143, v143, v27
	v_cvt_pk_bf16_f32 v156, v140, v141
	v_cvt_pk_bf16_f32 v157, v142, v143
	s_waitcnt vmcnt(12)
	v_and_b32_e32 v31, 0xffff0000, v29
	v_lshlrev_b32_e32 v30, 16, v29
	v_and_b32_e32 v29, 0xffff0000, v28
	v_lshlrev_b32_e32 v28, 16, v28
	v_add_f32_e32 v140, v28, v24
	v_add_f32_e32 v141, v29, v25
	v_add_f32_e32 v142, v30, v26
	v_add_f32_e32 v143, v31, v27
	v_add_f32_e32 v140, v140, v20
	v_add_f32_e32 v141, v141, v21
	v_add_f32_e32 v142, v142, v22
	v_add_f32_e32 v143, v143, v23
	v_add_f32_e32 v140, v140, v16
	v_add_f32_e32 v141, v141, v17
	v_add_f32_e32 v142, v142, v18
	v_add_f32_e32 v143, v143, v19
	v_mul_f32_e32 v140, 0x3e800000, v140
	v_mul_f32_e32 v141, 0x3e800000, v141
	v_mul_f32_e32 v142, 0x3e800000, v142
	v_mul_f32_e32 v143, 0x3e800000, v143
	v_sub_f32_e32 v140, v140, v28
	v_sub_f32_e32 v141, v141, v29
	v_sub_f32_e32 v142, v142, v30
	v_sub_f32_e32 v143, v143, v31
	v_cvt_pk_bf16_f32 v158, v140, v141
	v_cvt_pk_bf16_f32 v159, v142, v143
	s_waitcnt vmcnt(11)
	v_and_b32_e32 v35, 0xffff0000, v33
	v_lshlrev_b32_e32 v34, 16, v33
	v_and_b32_e32 v33, 0xffff0000, v32
	v_lshlrev_b32_e32 v32, 16, v32
	v_add_f32_e32 v140, v32, v28
	v_add_f32_e32 v141, v33, v29
	v_add_f32_e32 v142, v34, v30
	v_add_f32_e32 v143, v35, v31
	v_add_f32_e32 v140, v140, v24
	v_add_f32_e32 v141, v141, v25
	v_add_f32_e32 v142, v142, v26
	v_add_f32_e32 v143, v143, v27
	v_add_f32_e32 v140, v140, v20
	v_add_f32_e32 v141, v141, v21
	v_add_f32_e32 v142, v142, v22
	v_add_f32_e32 v143, v143, v23
	v_add_f32_e32 v140, v140, v16
	v_add_f32_e32 v141, v141, v17
	v_add_f32_e32 v142, v142, v18
	v_add_f32_e32 v143, v143, v19
	v_mov_b32_e32 v151, 0x40a00000
	v_div_scale_f32 v146, s[26:27], v151, v151, v140
	v_rcp_f32_e32 v147, v146
	v_div_scale_f32 v148, vcc, v140, v151, v140
	v_fma_f32 v149, -v146, v147, 1.0
	v_fmac_f32_e32 v147, v149, v147
	v_mul_f32_e32 v149, v148, v147
	v_fma_f32 v150, -v146, v149, v148
	v_fmac_f32_e32 v149, v150, v147
	v_fma_f32 v146, -v146, v149, v148
	v_div_fmas_f32 v146, v146, v147, v149
	v_div_fixup_f32 v140, v146, v151, v140
	v_mov_b32_e32 v151, 0x40a00000
	v_div_scale_f32 v146, s[26:27], v151, v151, v141
	v_rcp_f32_e32 v147, v146
	v_div_scale_f32 v148, vcc, v141, v151, v141
	v_fma_f32 v149, -v146, v147, 1.0
	v_fmac_f32_e32 v147, v149, v147
	v_mul_f32_e32 v149, v148, v147
	v_fma_f32 v150, -v146, v149, v148
	v_fmac_f32_e32 v149, v150, v147
	v_fma_f32 v146, -v146, v149, v148
	v_div_fmas_f32 v146, v146, v147, v149
	v_div_fixup_f32 v141, v146, v151, v141
	v_mov_b32_e32 v151, 0x40a00000
	v_div_scale_f32 v146, s[26:27], v151, v151, v142
	v_rcp_f32_e32 v147, v146
	v_div_scale_f32 v148, vcc, v142, v151, v142
	v_fma_f32 v149, -v146, v147, 1.0
	v_fmac_f32_e32 v147, v149, v147
	v_mul_f32_e32 v149, v148, v147
	v_fma_f32 v150, -v146, v149, v148
	v_fmac_f32_e32 v149, v150, v147
	v_fma_f32 v146, -v146, v149, v148
	v_div_fmas_f32 v146, v146, v147, v149
	v_div_fixup_f32 v142, v146, v151, v142
	v_mov_b32_e32 v151, 0x40a00000
	v_div_scale_f32 v146, s[26:27], v151, v151, v143
	v_rcp_f32_e32 v147, v146
	v_div_scale_f32 v148, vcc, v143, v151, v143
	v_fma_f32 v149, -v146, v147, 1.0
	v_fmac_f32_e32 v147, v149, v147
	v_mul_f32_e32 v149, v148, v147
	v_fma_f32 v150, -v146, v149, v148
	v_fmac_f32_e32 v149, v150, v147
	v_fma_f32 v146, -v146, v149, v148
	v_div_fmas_f32 v146, v146, v147, v149
	v_div_fixup_f32 v143, v146, v151, v143
	v_sub_f32_e32 v140, v140, v32
	v_sub_f32_e32 v141, v141, v33
	v_sub_f32_e32 v142, v142, v34
	v_sub_f32_e32 v143, v143, v35
	v_cvt_pk_bf16_f32 v160, v140, v141
	v_cvt_pk_bf16_f32 v161, v142, v143
	s_waitcnt vmcnt(10)
; DI float bflo(unsigned u) { return __uint_as_float(u << 16); }
; DI float bfhi(unsigned u) { return __uint_as_float(u & 0xffff0000u); }
; template <int WIN>
; DI void pool_elem(const Params& p, int row, int c) {
;     ...
;     } else {
;       cnt = (float)(t + 1);
;       for (int j = 1; j <= t; ++j) {
;         unsigned w = *(const unsigned*)(P2 + (size_t)(row - j) * 2048 + c);
;         s0 += bflo(w); s1 += bfhi(w);
;       }
;     ...
;   *(unsigned*)(p.MIX + (size_t)row * 1024 + c) = pack2(s0 / cnt - u0, s1 / cnt - u1);
	v_and_b32_e32 v39, 0xffff0000, v37
	v_lshlrev_b32_e32 v38, 16, v37
	v_and_b32_e32 v37, 0xffff0000, v36
	v_lshlrev_b32_e32 v36, 16, v36
	v_add_f32_e32 v140, v36, v32
	v_add_f32_e32 v141, v37, v33
	v_add_f32_e32 v142, v38, v34
	v_add_f32_e32 v143, v39, v35
	v_add_f32_e32 v140, v140, v28
	v_add_f32_e32 v141, v141, v29
	v_add_f32_e32 v142, v142, v30
	v_add_f32_e32 v143, v143, v31
	v_add_f32_e32 v140, v140, v24
	v_add_f32_e32 v141, v141, v25
	v_add_f32_e32 v142, v142, v26
	v_add_f32_e32 v143, v143, v27
	v_add_f32_e32 v140, v140, v20
	v_add_f32_e32 v141, v141, v21
	v_add_f32_e32 v142, v142, v22
	v_add_f32_e32 v143, v143, v23
	v_add_f32_e32 v140, v140, v16
	v_add_f32_e32 v141, v141, v17
	v_add_f32_e32 v142, v142, v18
	v_add_f32_e32 v143, v143, v19
	v_mov_b32_e32 v151, 0x40c00000
	v_div_scale_f32 v146, s[26:27], v151, v151, v140
	v_rcp_f32_e32 v147, v146
	v_div_scale_f32 v148, vcc, v140, v151, v140
	v_fma_f32 v149, -v146, v147, 1.0
	v_fmac_f32_e32 v147, v149, v147
	v_mul_f32_e32 v149, v148, v147
	v_fma_f32 v150, -v146, v149, v148
	v_fmac_f32_e32 v149, v150, v147
	v_fma_f32 v146, -v146, v149, v148
	v_div_fmas_f32 v146, v146, v147, v149
	v_div_fixup_f32 v140, v146, v151, v140
	v_mov_b32_e32 v151, 0x40c00000
	v_div_scale_f32 v146, s[26:27], v151, v151, v141
	v_rcp_f32_e32 v147, v146
	v_div_scale_f32 v148, vcc, v141, v151, v141
	v_fma_f32 v149, -v146, v147, 1.0
	v_fmac_f32_e32 v147, v149, v147
	v_mul_f32_e32 v149, v148, v147
	v_fma_f32 v150, -v146, v149, v148
	v_fmac_f32_e32 v149, v150, v147
	v_fma_f32 v146, -v146, v149, v148
	v_div_fmas_f32 v146, v146, v147, v149
	v_div_fixup_f32 v141, v146, v151, v141
	v_mov_b32_e32 v151, 0x40c00000
	v_div_scale_f32 v146, s[26:27], v151, v151, v142
	v_rcp_f32_e32 v147, v146
	v_div_scale_f32 v148, vcc, v142, v151, v142
	v_fma_f32 v149, -v146, v147, 1.0
	v_fmac_f32_e32 v147, v149, v147
	v_mul_f32_e32 v149, v148, v147
	v_fma_f32 v150, -v146, v149, v148
	v_fmac_f32_e32 v149, v150, v147
	v_fma_f32 v146, -v146, v149, v148
	v_div_fmas_f32 v146, v146, v147, v149
	v_div_fixup_f32 v142, v146, v151, v142
	v_mov_b32_e32 v151, 0x40c00000
	v_div_scale_f32 v146, s[26:27], v151, v151, v143
	v_rcp_f32_e32 v147, v146
	v_div_scale_f32 v148, vcc, v143, v151, v143
	v_fma_f32 v149, -v146, v147, 1.0
	v_fmac_f32_e32 v147, v149, v147
	v_mul_f32_e32 v149, v148, v147
	v_fma_f32 v150, -v146, v149, v148
	v_fmac_f32_e32 v149, v150, v147
	v_fma_f32 v146, -v146, v149, v148
	v_div_fmas_f32 v146, v146, v147, v149
	v_div_fixup_f32 v143, v146, v151, v143
	v_sub_f32_e32 v140, v140, v36
	v_sub_f32_e32 v141, v141, v37
	v_sub_f32_e32 v142, v142, v38
	v_sub_f32_e32 v143, v143, v39
	v_cvt_pk_bf16_f32 v162, v140, v141
	v_cvt_pk_bf16_f32 v163, v142, v143
	s_waitcnt vmcnt(9)
	v_and_b32_e32 v43, 0xffff0000, v41
	v_lshlrev_b32_e32 v42, 16, v41
	v_and_b32_e32 v41, 0xffff0000, v40
	v_lshlrev_b32_e32 v40, 16, v40
	v_add_f32_e32 v140, v40, v36
	v_add_f32_e32 v141, v41, v37
	v_add_f32_e32 v142, v42, v38
	v_add_f32_e32 v143, v43, v39
	v_add_f32_e32 v140, v140, v32
	v_add_f32_e32 v141, v141, v33
	v_add_f32_e32 v142, v142, v34
	v_add_f32_e32 v143, v143, v35
	v_add_f32_e32 v140, v140, v28
	v_add_f32_e32 v141, v141, v29
	v_add_f32_e32 v142, v142, v30
	v_add_f32_e32 v143, v143, v31
	v_add_f32_e32 v140, v140, v24
	v_add_f32_e32 v141, v141, v25
	v_add_f32_e32 v142, v142, v26
	v_add_f32_e32 v143, v143, v27
	v_add_f32_e32 v140, v140, v20
	v_add_f32_e32 v141, v141, v21
	v_add_f32_e32 v142, v142, v22
	v_add_f32_e32 v143, v143, v23
	v_add_f32_e32 v140, v140, v16
	v_add_f32_e32 v141, v141, v17
	v_add_f32_e32 v142, v142, v18
	v_add_f32_e32 v143, v143, v19
	v_mov_b32_e32 v151, 0x40e00000
	v_div_scale_f32 v146, s[26:27], v151, v151, v140
	v_rcp_f32_e32 v147, v146
	v_div_scale_f32 v148, vcc, v140, v151, v140
	v_fma_f32 v149, -v146, v147, 1.0
	v_fmac_f32_e32 v147, v149, v147
	v_mul_f32_e32 v149, v148, v147
	v_fma_f32 v150, -v146, v149, v148
	v_fmac_f32_e32 v149, v150, v147
	v_fma_f32 v146, -v146, v149, v148
	v_div_fmas_f32 v146, v146, v147, v149
	v_div_fixup_f32 v140, v146, v151, v140
	v_mov_b32_e32 v151, 0x40e00000
	v_div_scale_f32 v146, s[26:27], v151, v151, v141
	v_rcp_f32_e32 v147, v146
	v_div_scale_f32 v148, vcc, v141, v151, v141
	v_fma_f32 v149, -v146, v147, 1.0
	v_fmac_f32_e32 v147, v149, v147
	v_mul_f32_e32 v149, v148, v147
	v_fma_f32 v150, -v146, v149, v148
	v_fmac_f32_e32 v149, v150, v147
	v_fma_f32 v146, -v146, v149, v148
	v_div_fmas_f32 v146, v146, v147, v149
	v_div_fixup_f32 v141, v146, v151, v141
	v_mov_b32_e32 v151, 0x40e00000
	v_div_scale_f32 v146, s[26:27], v151, v151, v142
	v_rcp_f32_e32 v147, v146
	v_div_scale_f32 v148, vcc, v142, v151, v142
	v_fma_f32 v149, -v146, v147, 1.0
	v_fmac_f32_e32 v147, v149, v147
	v_mul_f32_e32 v149, v148, v147
	v_fma_f32 v150, -v146, v149, v148
	v_fmac_f32_e32 v149, v150, v147
	v_fma_f32 v146, -v146, v149, v148
	v_div_fmas_f32 v146, v146, v147, v149
	v_div_fixup_f32 v142, v146, v151, v142
	v_mov_b32_e32 v151, 0x40e00000
	v_div_scale_f32 v146, s[26:27], v151, v151, v143
	v_rcp_f32_e32 v147, v146
	v_div_scale_f32 v148, vcc, v143, v151, v143
	v_fma_f32 v149, -v146, v147, 1.0
	v_fmac_f32_e32 v147, v149, v147
	v_mul_f32_e32 v149, v148, v147
	v_fma_f32 v150, -v146, v149, v148
	v_fmac_f32_e32 v149, v150, v147
	v_fma_f32 v146, -v146, v149, v148
	v_div_fmas_f32 v146, v146, v147, v149
	v_div_fixup_f32 v143, v146, v151, v143
	v_sub_f32_e32 v140, v140, v40
	v_sub_f32_e32 v141, v141, v41
	v_sub_f32_e32 v142, v142, v42
	v_sub_f32_e32 v143, v143, v43
	v_cvt_pk_bf16_f32 v164, v140, v141
	v_cvt_pk_bf16_f32 v165, v142, v143
	s_waitcnt vmcnt(8)
; DI float bflo(unsigned u) { return __uint_as_float(u << 16); }
; DI float bfhi(unsigned u) { return __uint_as_float(u & 0xffff0000u); }
; template <int WIN>
; DI void pool_elem(const Params& p, int row, int c) {
;     ...
;     } else {
;       cnt = (float)(t + 1);
;       for (int j = 1; j <= t; ++j) {
;         unsigned w = *(const unsigned*)(P2 + (size_t)(row - j) * 2048 + c);
;         s0 += bflo(w); s1 += bfhi(w);
;       }
;     ...
;   *(unsigned*)(p.MIX + (size_t)row * 1024 + c) = pack2(s0 / cnt - u0, s1 / cnt - u1);
	v_and_b32_e32 v47, 0xffff0000, v45
	v_lshlrev_b32_e32 v46, 16, v45
	v_and_b32_e32 v45, 0xffff0000, v44
	v_lshlrev_b32_e32 v44, 16, v44
	v_add_f32_e32 v140, v44, v40
	v_add_f32_e32 v141, v45, v41
	v_add_f32_e32 v142, v46, v42
	v_add_f32_e32 v143, v47, v43
	v_add_f32_e32 v140, v140, v36
	v_add_f32_e32 v141, v141, v37
	v_add_f32_e32 v142, v142, v38
	v_add_f32_e32 v143, v143, v39
	v_add_f32_e32 v140, v140, v32
	v_add_f32_e32 v141, v141, v33
	v_add_f32_e32 v142, v142, v34
	v_add_f32_e32 v143, v143, v35
	v_add_f32_e32 v140, v140, v28
	v_add_f32_e32 v141, v141, v29
	v_add_f32_e32 v142, v142, v30
	v_add_f32_e32 v143, v143, v31
	v_add_f32_e32 v140, v140, v24
	v_add_f32_e32 v141, v141, v25
	v_add_f32_e32 v142, v142, v26
	v_add_f32_e32 v143, v143, v27
	v_add_f32_e32 v140, v140, v20
	v_add_f32_e32 v141, v141, v21
	v_add_f32_e32 v142, v142, v22
	v_add_f32_e32 v143, v143, v23
	v_add_f32_e32 v140, v140, v16
	v_add_f32_e32 v141, v141, v17
	v_add_f32_e32 v142, v142, v18
	v_add_f32_e32 v143, v143, v19
	v_mul_f32_e32 v140, 0x3e000000, v140
	v_mul_f32_e32 v141, 0x3e000000, v141
	v_mul_f32_e32 v142, 0x3e000000, v142
	v_mul_f32_e32 v143, 0x3e000000, v143
	v_sub_f32_e32 v140, v140, v44
	v_sub_f32_e32 v141, v141, v45
	v_sub_f32_e32 v142, v142, v46
	v_sub_f32_e32 v143, v143, v47
	v_cvt_pk_bf16_f32 v166, v140, v141
	v_cvt_pk_bf16_f32 v167, v142, v143
	s_waitcnt vmcnt(7)
	v_and_b32_e32 v51, 0xffff0000, v49
	v_lshlrev_b32_e32 v50, 16, v49
	v_and_b32_e32 v49, 0xffff0000, v48
	v_lshlrev_b32_e32 v48, 16, v48
	v_add_f32_e32 v140, v48, v44
	v_add_f32_e32 v141, v49, v45
	v_add_f32_e32 v142, v50, v46
	v_add_f32_e32 v143, v51, v47
	v_add_f32_e32 v140, v140, v40
	v_add_f32_e32 v141, v141, v41
	v_add_f32_e32 v142, v142, v42
	v_add_f32_e32 v143, v143, v43
	v_add_f32_e32 v140, v140, v36
	v_add_f32_e32 v141, v141, v37
	v_add_f32_e32 v142, v142, v38
	v_add_f32_e32 v143, v143, v39
	v_add_f32_e32 v140, v140, v32
	v_add_f32_e32 v141, v141, v33
	v_add_f32_e32 v142, v142, v34
	v_add_f32_e32 v143, v143, v35
	v_add_f32_e32 v140, v140, v28
	v_add_f32_e32 v141, v141, v29
	v_add_f32_e32 v142, v142, v30
	v_add_f32_e32 v143, v143, v31
	v_add_f32_e32 v140, v140, v24
	v_add_f32_e32 v141, v141, v25
	v_add_f32_e32 v142, v142, v26
	v_add_f32_e32 v143, v143, v27
	v_add_f32_e32 v140, v140, v20
	v_add_f32_e32 v141, v141, v21
	v_add_f32_e32 v142, v142, v22
	v_add_f32_e32 v143, v143, v23
	v_add_f32_e32 v140, v140, v16
	v_add_f32_e32 v141, v141, v17
	v_add_f32_e32 v142, v142, v18
	v_add_f32_e32 v143, v143, v19
	v_mov_b32_e32 v151, 0x41100000
	v_div_scale_f32 v146, s[26:27], v151, v151, v140
	v_rcp_f32_e32 v147, v146
	v_div_scale_f32 v148, vcc, v140, v151, v140
	v_fma_f32 v149, -v146, v147, 1.0
	v_fmac_f32_e32 v147, v149, v147
	v_mul_f32_e32 v149, v148, v147
	v_fma_f32 v150, -v146, v149, v148
	v_fmac_f32_e32 v149, v150, v147
	v_fma_f32 v146, -v146, v149, v148
	v_div_fmas_f32 v146, v146, v147, v149
	v_div_fixup_f32 v140, v146, v151, v140
	v_mov_b32_e32 v151, 0x41100000
	v_div_scale_f32 v146, s[26:27], v151, v151, v141
	v_rcp_f32_e32 v147, v146
	v_div_scale_f32 v148, vcc, v141, v151, v141
	v_fma_f32 v149, -v146, v147, 1.0
	v_fmac_f32_e32 v147, v149, v147
	v_mul_f32_e32 v149, v148, v147
	v_fma_f32 v150, -v146, v149, v148
	v_fmac_f32_e32 v149, v150, v147
	v_fma_f32 v146, -v146, v149, v148
	v_div_fmas_f32 v146, v146, v147, v149
	v_div_fixup_f32 v141, v146, v151, v141
	v_mov_b32_e32 v151, 0x41100000
	v_div_scale_f32 v146, s[26:27], v151, v151, v142
	v_rcp_f32_e32 v147, v146
	v_div_scale_f32 v148, vcc, v142, v151, v142
	v_fma_f32 v149, -v146, v147, 1.0
	v_fmac_f32_e32 v147, v149, v147
	v_mul_f32_e32 v149, v148, v147
	v_fma_f32 v150, -v146, v149, v148
	v_fmac_f32_e32 v149, v150, v147
	v_fma_f32 v146, -v146, v149, v148
	v_div_fmas_f32 v146, v146, v147, v149
	v_div_fixup_f32 v142, v146, v151, v142
	v_mov_b32_e32 v151, 0x41100000
	v_div_scale_f32 v146, s[26:27], v151, v151, v143
	v_rcp_f32_e32 v147, v146
	v_div_scale_f32 v148, vcc, v143, v151, v143
	v_fma_f32 v149, -v146, v147, 1.0
	v_fmac_f32_e32 v147, v149, v147
	v_mul_f32_e32 v149, v148, v147
	v_fma_f32 v150, -v146, v149, v148
	v_fmac_f32_e32 v149, v150, v147
	v_fma_f32 v146, -v146, v149, v148
	v_div_fmas_f32 v146, v146, v147, v149
	v_div_fixup_f32 v143, v146, v151, v143
	v_sub_f32_e32 v140, v140, v48
	v_sub_f32_e32 v141, v141, v49
	v_sub_f32_e32 v142, v142, v50
	v_sub_f32_e32 v143, v143, v51
	v_cvt_pk_bf16_f32 v168, v140, v141
	v_cvt_pk_bf16_f32 v169, v142, v143
	s_waitcnt vmcnt(6)
; DI float bflo(unsigned u) { return __uint_as_float(u << 16); }
; DI float bfhi(unsigned u) { return __uint_as_float(u & 0xffff0000u); }
; template <int WIN>
; DI void pool_elem(const Params& p, int row, int c) {
;     ...
;     } else {
;       cnt = (float)(t + 1);
;       for (int j = 1; j <= t; ++j) {
;         unsigned w = *(const unsigned*)(P2 + (size_t)(row - j) * 2048 + c);
;         s0 += bflo(w); s1 += bfhi(w);
;       }
;     ...
;   *(unsigned*)(p.MIX + (size_t)row * 1024 + c) = pack2(s0 / cnt - u0, s1 / cnt - u1);
	v_and_b32_e32 v55, 0xffff0000, v53
	v_lshlrev_b32_e32 v54, 16, v53
	v_and_b32_e32 v53, 0xffff0000, v52
	v_lshlrev_b32_e32 v52, 16, v52
	v_add_f32_e32 v140, v52, v48
	v_add_f32_e32 v141, v53, v49
	v_add_f32_e32 v142, v54, v50
	v_add_f32_e32 v143, v55, v51
	v_add_f32_e32 v140, v140, v44
	v_add_f32_e32 v141, v141, v45
	v_add_f32_e32 v142, v142, v46
	v_add_f32_e32 v143, v143, v47
	v_add_f32_e32 v140, v140, v40
	v_add_f32_e32 v141, v141, v41
	v_add_f32_e32 v142, v142, v42
	v_add_f32_e32 v143, v143, v43
	v_add_f32_e32 v140, v140, v36
	v_add_f32_e32 v141, v141, v37
	v_add_f32_e32 v142, v142, v38
	v_add_f32_e32 v143, v143, v39
	v_add_f32_e32 v140, v140, v32
	v_add_f32_e32 v141, v141, v33
	v_add_f32_e32 v142, v142, v34
	v_add_f32_e32 v143, v143, v35
	v_add_f32_e32 v140, v140, v28
	v_add_f32_e32 v141, v141, v29
	v_add_f32_e32 v142, v142, v30
	v_add_f32_e32 v143, v143, v31
	v_add_f32_e32 v140, v140, v24
	v_add_f32_e32 v141, v141, v25
	v_add_f32_e32 v142, v142, v26
	v_add_f32_e32 v143, v143, v27
	v_add_f32_e32 v140, v140, v20
	v_add_f32_e32 v141, v141, v21
	v_add_f32_e32 v142, v142, v22
	v_add_f32_e32 v143, v143, v23
	v_add_f32_e32 v140, v140, v16
	v_add_f32_e32 v141, v141, v17
	v_add_f32_e32 v142, v142, v18
	v_add_f32_e32 v143, v143, v19
	v_mov_b32_e32 v151, 0x41200000
	v_div_scale_f32 v146, s[26:27], v151, v151, v140
	v_rcp_f32_e32 v147, v146
	v_div_scale_f32 v148, vcc, v140, v151, v140
	v_fma_f32 v149, -v146, v147, 1.0
	v_fmac_f32_e32 v147, v149, v147
	v_mul_f32_e32 v149, v148, v147
	v_fma_f32 v150, -v146, v149, v148
	v_fmac_f32_e32 v149, v150, v147
	v_fma_f32 v146, -v146, v149, v148
	v_div_fmas_f32 v146, v146, v147, v149
	v_div_fixup_f32 v140, v146, v151, v140
	v_mov_b32_e32 v151, 0x41200000
	v_div_scale_f32 v146, s[26:27], v151, v151, v141
	v_rcp_f32_e32 v147, v146
	v_div_scale_f32 v148, vcc, v141, v151, v141
	v_fma_f32 v149, -v146, v147, 1.0
	v_fmac_f32_e32 v147, v149, v147
	v_mul_f32_e32 v149, v148, v147
	v_fma_f32 v150, -v146, v149, v148
	v_fmac_f32_e32 v149, v150, v147
	v_fma_f32 v146, -v146, v149, v148
	v_div_fmas_f32 v146, v146, v147, v149
	v_div_fixup_f32 v141, v146, v151, v141
	v_mov_b32_e32 v151, 0x41200000
	v_div_scale_f32 v146, s[26:27], v151, v151, v142
	v_rcp_f32_e32 v147, v146
	v_div_scale_f32 v148, vcc, v142, v151, v142
	v_fma_f32 v149, -v146, v147, 1.0
	v_fmac_f32_e32 v147, v149, v147
	v_mul_f32_e32 v149, v148, v147
	v_fma_f32 v150, -v146, v149, v148
	v_fmac_f32_e32 v149, v150, v147
	v_fma_f32 v146, -v146, v149, v148
	v_div_fmas_f32 v146, v146, v147, v149
	v_div_fixup_f32 v142, v146, v151, v142
	v_mov_b32_e32 v151, 0x41200000
	v_div_scale_f32 v146, s[26:27], v151, v151, v143
	v_rcp_f32_e32 v147, v146
	v_div_scale_f32 v148, vcc, v143, v151, v143
	v_fma_f32 v149, -v146, v147, 1.0
	v_fmac_f32_e32 v147, v149, v147
	v_mul_f32_e32 v149, v148, v147
	v_fma_f32 v150, -v146, v149, v148
	v_fmac_f32_e32 v149, v150, v147
	v_fma_f32 v146, -v146, v149, v148
	v_div_fmas_f32 v146, v146, v147, v149
	v_div_fixup_f32 v143, v146, v151, v143
	v_sub_f32_e32 v140, v140, v52
	v_sub_f32_e32 v141, v141, v53
	v_sub_f32_e32 v142, v142, v54
	v_sub_f32_e32 v143, v143, v55
	v_cvt_pk_bf16_f32 v170, v140, v141
	v_cvt_pk_bf16_f32 v171, v142, v143
	s_waitcnt vmcnt(5)
	v_and_b32_e32 v59, 0xffff0000, v57
	v_lshlrev_b32_e32 v58, 16, v57
	v_and_b32_e32 v57, 0xffff0000, v56
	v_lshlrev_b32_e32 v56, 16, v56
	v_add_f32_e32 v140, v56, v52
	v_add_f32_e32 v141, v57, v53
	v_add_f32_e32 v142, v58, v54
	v_add_f32_e32 v143, v59, v55
	v_add_f32_e32 v140, v140, v48
	v_add_f32_e32 v141, v141, v49
	v_add_f32_e32 v142, v142, v50
	v_add_f32_e32 v143, v143, v51
	v_add_f32_e32 v140, v140, v44
	v_add_f32_e32 v141, v141, v45
	v_add_f32_e32 v142, v142, v46
	v_add_f32_e32 v143, v143, v47
	v_add_f32_e32 v140, v140, v40
	v_add_f32_e32 v141, v141, v41
	v_add_f32_e32 v142, v142, v42
	v_add_f32_e32 v143, v143, v43
	v_add_f32_e32 v140, v140, v36
	v_add_f32_e32 v141, v141, v37
	v_add_f32_e32 v142, v142, v38
	v_add_f32_e32 v143, v143, v39
	v_add_f32_e32 v140, v140, v32
	v_add_f32_e32 v141, v141, v33
	v_add_f32_e32 v142, v142, v34
	v_add_f32_e32 v143, v143, v35
	v_add_f32_e32 v140, v140, v28
	v_add_f32_e32 v141, v141, v29
	v_add_f32_e32 v142, v142, v30
	v_add_f32_e32 v143, v143, v31
	v_add_f32_e32 v140, v140, v24
	v_add_f32_e32 v141, v141, v25
	v_add_f32_e32 v142, v142, v26
	v_add_f32_e32 v143, v143, v27
	v_add_f32_e32 v140, v140, v20
	v_add_f32_e32 v141, v141, v21
	v_add_f32_e32 v142, v142, v22
	v_add_f32_e32 v143, v143, v23
	v_add_f32_e32 v140, v140, v16
	v_add_f32_e32 v141, v141, v17
	v_add_f32_e32 v142, v142, v18
	v_add_f32_e32 v143, v143, v19
	v_mov_b32_e32 v151, 0x41300000
	v_div_scale_f32 v146, s[26:27], v151, v151, v140
	v_rcp_f32_e32 v147, v146
	v_div_scale_f32 v148, vcc, v140, v151, v140
	v_fma_f32 v149, -v146, v147, 1.0
	v_fmac_f32_e32 v147, v149, v147
	v_mul_f32_e32 v149, v148, v147
	v_fma_f32 v150, -v146, v149, v148
	v_fmac_f32_e32 v149, v150, v147
	v_fma_f32 v146, -v146, v149, v148
	v_div_fmas_f32 v146, v146, v147, v149
	v_div_fixup_f32 v140, v146, v151, v140
	v_mov_b32_e32 v151, 0x41300000
	v_div_scale_f32 v146, s[26:27], v151, v151, v141
	v_rcp_f32_e32 v147, v146
	v_div_scale_f32 v148, vcc, v141, v151, v141
	v_fma_f32 v149, -v146, v147, 1.0
	v_fmac_f32_e32 v147, v149, v147
	v_mul_f32_e32 v149, v148, v147
	v_fma_f32 v150, -v146, v149, v148
	v_fmac_f32_e32 v149, v150, v147
	v_fma_f32 v146, -v146, v149, v148
	v_div_fmas_f32 v146, v146, v147, v149
	v_div_fixup_f32 v141, v146, v151, v141
	v_mov_b32_e32 v151, 0x41300000
	v_div_scale_f32 v146, s[26:27], v151, v151, v142
	v_rcp_f32_e32 v147, v146
	v_div_scale_f32 v148, vcc, v142, v151, v142
	v_fma_f32 v149, -v146, v147, 1.0
	v_fmac_f32_e32 v147, v149, v147
	v_mul_f32_e32 v149, v148, v147
	v_fma_f32 v150, -v146, v149, v148
	v_fmac_f32_e32 v149, v150, v147
	v_fma_f32 v146, -v146, v149, v148
	v_div_fmas_f32 v146, v146, v147, v149
	v_div_fixup_f32 v142, v146, v151, v142
	v_mov_b32_e32 v151, 0x41300000
	v_div_scale_f32 v146, s[26:27], v151, v151, v143
	v_rcp_f32_e32 v147, v146
	v_div_scale_f32 v148, vcc, v143, v151, v143
	v_fma_f32 v149, -v146, v147, 1.0
	v_fmac_f32_e32 v147, v149, v147
	v_mul_f32_e32 v149, v148, v147
	v_fma_f32 v150, -v146, v149, v148
	v_fmac_f32_e32 v149, v150, v147
	v_fma_f32 v146, -v146, v149, v148
	v_div_fmas_f32 v146, v146, v147, v149
	v_div_fixup_f32 v143, v146, v151, v143
	v_sub_f32_e32 v140, v140, v56
	v_sub_f32_e32 v141, v141, v57
	v_sub_f32_e32 v142, v142, v58
	v_sub_f32_e32 v143, v143, v59
	v_cvt_pk_bf16_f32 v172, v140, v141
	v_cvt_pk_bf16_f32 v173, v142, v143
	s_waitcnt vmcnt(4)
; DI float bflo(unsigned u) { return __uint_as_float(u << 16); }
; DI float bfhi(unsigned u) { return __uint_as_float(u & 0xffff0000u); }
; template <int WIN>
; DI void pool_elem(const Params& p, int row, int c) {
;     ...
;     } else {
;       cnt = (float)(t + 1);
;       for (int j = 1; j <= t; ++j) {
;         unsigned w = *(const unsigned*)(P2 + (size_t)(row - j) * 2048 + c);
;         s0 += bflo(w); s1 += bfhi(w);
;       }
;     ...
;   *(unsigned*)(p.MIX + (size_t)row * 1024 + c) = pack2(s0 / cnt - u0, s1 / cnt - u1);
	v_and_b32_e32 v63, 0xffff0000, v61
	v_lshlrev_b32_e32 v62, 16, v61
	v_and_b32_e32 v61, 0xffff0000, v60
	v_lshlrev_b32_e32 v60, 16, v60
	v_add_f32_e32 v140, v60, v56
	v_add_f32_e32 v141, v61, v57
	v_add_f32_e32 v142, v62, v58
	v_add_f32_e32 v143, v63, v59
	v_add_f32_e32 v140, v140, v52
	v_add_f32_e32 v141, v141, v53
	v_add_f32_e32 v142, v142, v54
	v_add_f32_e32 v143, v143, v55
	v_add_f32_e32 v140, v140, v48
	v_add_f32_e32 v141, v141, v49
	v_add_f32_e32 v142, v142, v50
	v_add_f32_e32 v143, v143, v51
	v_add_f32_e32 v140, v140, v44
	v_add_f32_e32 v141, v141, v45
	v_add_f32_e32 v142, v142, v46
	v_add_f32_e32 v143, v143, v47
	v_add_f32_e32 v140, v140, v40
	v_add_f32_e32 v141, v141, v41
	v_add_f32_e32 v142, v142, v42
	v_add_f32_e32 v143, v143, v43
	v_add_f32_e32 v140, v140, v36
	v_add_f32_e32 v141, v141, v37
	v_add_f32_e32 v142, v142, v38
	v_add_f32_e32 v143, v143, v39
	v_add_f32_e32 v140, v140, v32
	v_add_f32_e32 v141, v141, v33
	v_add_f32_e32 v142, v142, v34
	v_add_f32_e32 v143, v143, v35
	v_add_f32_e32 v140, v140, v28
	v_add_f32_e32 v141, v141, v29
	v_add_f32_e32 v142, v142, v30
	v_add_f32_e32 v143, v143, v31
	v_add_f32_e32 v140, v140, v24
	v_add_f32_e32 v141, v141, v25
	v_add_f32_e32 v142, v142, v26
	v_add_f32_e32 v143, v143, v27
	v_add_f32_e32 v140, v140, v20
	v_add_f32_e32 v141, v141, v21
	v_add_f32_e32 v142, v142, v22
	v_add_f32_e32 v143, v143, v23
	v_add_f32_e32 v140, v140, v16
	v_add_f32_e32 v141, v141, v17
	v_add_f32_e32 v142, v142, v18
	v_add_f32_e32 v143, v143, v19
	v_mov_b32_e32 v151, 0x41400000
	v_div_scale_f32 v146, s[26:27], v151, v151, v140
	v_rcp_f32_e32 v147, v146
	v_div_scale_f32 v148, vcc, v140, v151, v140
	v_fma_f32 v149, -v146, v147, 1.0
	v_fmac_f32_e32 v147, v149, v147
	v_mul_f32_e32 v149, v148, v147
	v_fma_f32 v150, -v146, v149, v148
	v_fmac_f32_e32 v149, v150, v147
	v_fma_f32 v146, -v146, v149, v148
	v_div_fmas_f32 v146, v146, v147, v149
	v_div_fixup_f32 v140, v146, v151, v140
	v_mov_b32_e32 v151, 0x41400000
	v_div_scale_f32 v146, s[26:27], v151, v151, v141
	v_rcp_f32_e32 v147, v146
	v_div_scale_f32 v148, vcc, v141, v151, v141
	v_fma_f32 v149, -v146, v147, 1.0
	v_fmac_f32_e32 v147, v149, v147
	v_mul_f32_e32 v149, v148, v147
	v_fma_f32 v150, -v146, v149, v148
	v_fmac_f32_e32 v149, v150, v147
	v_fma_f32 v146, -v146, v149, v148
	v_div_fmas_f32 v146, v146, v147, v149
	v_div_fixup_f32 v141, v146, v151, v141
	v_mov_b32_e32 v151, 0x41400000
	v_div_scale_f32 v146, s[26:27], v151, v151, v142
	v_rcp_f32_e32 v147, v146
	v_div_scale_f32 v148, vcc, v142, v151, v142
	v_fma_f32 v149, -v146, v147, 1.0
	v_fmac_f32_e32 v147, v149, v147
	v_mul_f32_e32 v149, v148, v147
	v_fma_f32 v150, -v146, v149, v148
	v_fmac_f32_e32 v149, v150, v147
	v_fma_f32 v146, -v146, v149, v148
	v_div_fmas_f32 v146, v146, v147, v149
	v_div_fixup_f32 v142, v146, v151, v142
	v_mov_b32_e32 v151, 0x41400000
	v_div_scale_f32 v146, s[26:27], v151, v151, v143
	v_rcp_f32_e32 v147, v146
	v_div_scale_f32 v148, vcc, v143, v151, v143
	v_fma_f32 v149, -v146, v147, 1.0
	v_fmac_f32_e32 v147, v149, v147
	v_mul_f32_e32 v149, v148, v147
	v_fma_f32 v150, -v146, v149, v148
	v_fmac_f32_e32 v149, v150, v147
	v_fma_f32 v146, -v146, v149, v148
	v_div_fmas_f32 v146, v146, v147, v149
	v_div_fixup_f32 v143, v146, v151, v143
	v_sub_f32_e32 v140, v140, v60
	v_sub_f32_e32 v141, v141, v61
	v_sub_f32_e32 v142, v142, v62
	v_sub_f32_e32 v143, v143, v63
	v_cvt_pk_bf16_f32 v174, v140, v141
	v_cvt_pk_bf16_f32 v175, v142, v143
	s_waitcnt vmcnt(3)
	v_and_b32_e32 v67, 0xffff0000, v65
	v_lshlrev_b32_e32 v66, 16, v65
	v_and_b32_e32 v65, 0xffff0000, v64
	v_lshlrev_b32_e32 v64, 16, v64
	v_add_f32_e32 v140, v64, v60
	v_add_f32_e32 v141, v65, v61
	v_add_f32_e32 v142, v66, v62
	v_add_f32_e32 v143, v67, v63
	v_add_f32_e32 v140, v140, v56
	v_add_f32_e32 v141, v141, v57
	v_add_f32_e32 v142, v142, v58
	v_add_f32_e32 v143, v143, v59
	v_add_f32_e32 v140, v140, v52
	v_add_f32_e32 v141, v141, v53
	v_add_f32_e32 v142, v142, v54
	v_add_f32_e32 v143, v143, v55
	v_add_f32_e32 v140, v140, v48
	v_add_f32_e32 v141, v141, v49
	v_add_f32_e32 v142, v142, v50
	v_add_f32_e32 v143, v143, v51
	v_add_f32_e32 v140, v140, v44
	v_add_f32_e32 v141, v141, v45
	v_add_f32_e32 v142, v142, v46
	v_add_f32_e32 v143, v143, v47
	v_add_f32_e32 v140, v140, v40
	v_add_f32_e32 v141, v141, v41
	v_add_f32_e32 v142, v142, v42
	v_add_f32_e32 v143, v143, v43
	v_add_f32_e32 v140, v140, v36
	v_add_f32_e32 v141, v141, v37
	v_add_f32_e32 v142, v142, v38
	v_add_f32_e32 v143, v143, v39
	v_add_f32_e32 v140, v140, v32
	v_add_f32_e32 v141, v141, v33
	v_add_f32_e32 v142, v142, v34
	v_add_f32_e32 v143, v143, v35
	v_add_f32_e32 v140, v140, v28
	v_add_f32_e32 v141, v141, v29
	v_add_f32_e32 v142, v142, v30
	v_add_f32_e32 v143, v143, v31
	v_add_f32_e32 v140, v140, v24
	v_add_f32_e32 v141, v141, v25
	v_add_f32_e32 v142, v142, v26
	v_add_f32_e32 v143, v143, v27
	v_add_f32_e32 v140, v140, v20
	v_add_f32_e32 v141, v141, v21
	v_add_f32_e32 v142, v142, v22
	v_add_f32_e32 v143, v143, v23
	v_add_f32_e32 v140, v140, v16
	v_add_f32_e32 v141, v141, v17
	v_add_f32_e32 v142, v142, v18
	v_add_f32_e32 v143, v143, v19
	v_mov_b32_e32 v151, 0x41500000
	v_div_scale_f32 v146, s[26:27], v151, v151, v140
	v_rcp_f32_e32 v147, v146
	v_div_scale_f32 v148, vcc, v140, v151, v140
	v_fma_f32 v149, -v146, v147, 1.0
	v_fmac_f32_e32 v147, v149, v147
	v_mul_f32_e32 v149, v148, v147
	v_fma_f32 v150, -v146, v149, v148
	v_fmac_f32_e32 v149, v150, v147
	v_fma_f32 v146, -v146, v149, v148
	v_div_fmas_f32 v146, v146, v147, v149
	v_div_fixup_f32 v140, v146, v151, v140
	v_mov_b32_e32 v151, 0x41500000
	v_div_scale_f32 v146, s[26:27], v151, v151, v141
	v_rcp_f32_e32 v147, v146
	v_div_scale_f32 v148, vcc, v141, v151, v141
	v_fma_f32 v149, -v146, v147, 1.0
	v_fmac_f32_e32 v147, v149, v147
	v_mul_f32_e32 v149, v148, v147
	v_fma_f32 v150, -v146, v149, v148
	v_fmac_f32_e32 v149, v150, v147
	v_fma_f32 v146, -v146, v149, v148
	v_div_fmas_f32 v146, v146, v147, v149
	v_div_fixup_f32 v141, v146, v151, v141
	v_mov_b32_e32 v151, 0x41500000
	v_div_scale_f32 v146, s[26:27], v151, v151, v142
	v_rcp_f32_e32 v147, v146
	v_div_scale_f32 v148, vcc, v142, v151, v142
	v_fma_f32 v149, -v146, v147, 1.0
	v_fmac_f32_e32 v147, v149, v147
	v_mul_f32_e32 v149, v148, v147
	v_fma_f32 v150, -v146, v149, v148
	v_fmac_f32_e32 v149, v150, v147
	v_fma_f32 v146, -v146, v149, v148
	v_div_fmas_f32 v146, v146, v147, v149
	v_div_fixup_f32 v142, v146, v151, v142
	v_mov_b32_e32 v151, 0x41500000
	v_div_scale_f32 v146, s[26:27], v151, v151, v143
	v_rcp_f32_e32 v147, v146
	v_div_scale_f32 v148, vcc, v143, v151, v143
	v_fma_f32 v149, -v146, v147, 1.0
	v_fmac_f32_e32 v147, v149, v147
	v_mul_f32_e32 v149, v148, v147
	v_fma_f32 v150, -v146, v149, v148
	v_fmac_f32_e32 v149, v150, v147
	v_fma_f32 v146, -v146, v149, v148
	v_div_fmas_f32 v146, v146, v147, v149
	v_div_fixup_f32 v143, v146, v151, v143
	v_sub_f32_e32 v140, v140, v64
	v_sub_f32_e32 v141, v141, v65
	v_sub_f32_e32 v142, v142, v66
	v_sub_f32_e32 v143, v143, v67
	v_cvt_pk_bf16_f32 v176, v140, v141
	v_cvt_pk_bf16_f32 v177, v142, v143
	s_waitcnt vmcnt(2)
; DI float bflo(unsigned u) { return __uint_as_float(u << 16); }
; DI float bfhi(unsigned u) { return __uint_as_float(u & 0xffff0000u); }
; template <int WIN>
; DI void pool_elem(const Params& p, int row, int c) {
;     ...
;     } else {
;       cnt = (float)(t + 1);
;       for (int j = 1; j <= t; ++j) {
;         unsigned w = *(const unsigned*)(P2 + (size_t)(row - j) * 2048 + c);
;         s0 += bflo(w); s1 += bfhi(w);
;       }
;     ...
;   *(unsigned*)(p.MIX + (size_t)row * 1024 + c) = pack2(s0 / cnt - u0, s1 / cnt - u1);
	v_and_b32_e32 v71, 0xffff0000, v69
	v_lshlrev_b32_e32 v70, 16, v69
	v_and_b32_e32 v69, 0xffff0000, v68
	v_lshlrev_b32_e32 v68, 16, v68
	v_add_f32_e32 v140, v68, v64
	v_add_f32_e32 v141, v69, v65
	v_add_f32_e32 v142, v70, v66
	v_add_f32_e32 v143, v71, v67
	v_add_f32_e32 v140, v140, v60
	v_add_f32_e32 v141, v141, v61
	v_add_f32_e32 v142, v142, v62
	v_add_f32_e32 v143, v143, v63
	v_add_f32_e32 v140, v140, v56
	v_add_f32_e32 v141, v141, v57
	v_add_f32_e32 v142, v142, v58
	v_add_f32_e32 v143, v143, v59
	v_add_f32_e32 v140, v140, v52
	v_add_f32_e32 v141, v141, v53
	v_add_f32_e32 v142, v142, v54
	v_add_f32_e32 v143, v143, v55
	v_add_f32_e32 v140, v140, v48
	v_add_f32_e32 v141, v141, v49
	v_add_f32_e32 v142, v142, v50
	v_add_f32_e32 v143, v143, v51
	v_add_f32_e32 v140, v140, v44
	v_add_f32_e32 v141, v141, v45
	v_add_f32_e32 v142, v142, v46
	v_add_f32_e32 v143, v143, v47
	v_add_f32_e32 v140, v140, v40
	v_add_f32_e32 v141, v141, v41
	v_add_f32_e32 v142, v142, v42
	v_add_f32_e32 v143, v143, v43
	v_add_f32_e32 v140, v140, v36
	v_add_f32_e32 v141, v141, v37
	v_add_f32_e32 v142, v142, v38
	v_add_f32_e32 v143, v143, v39
	v_add_f32_e32 v140, v140, v32
	v_add_f32_e32 v141, v141, v33
	v_add_f32_e32 v142, v142, v34
	v_add_f32_e32 v143, v143, v35
	v_add_f32_e32 v140, v140, v28
	v_add_f32_e32 v141, v141, v29
	v_add_f32_e32 v142, v142, v30
	v_add_f32_e32 v143, v143, v31
	v_add_f32_e32 v140, v140, v24
	v_add_f32_e32 v141, v141, v25
	v_add_f32_e32 v142, v142, v26
	v_add_f32_e32 v143, v143, v27
	v_add_f32_e32 v140, v140, v20
	v_add_f32_e32 v141, v141, v21
	v_add_f32_e32 v142, v142, v22
	v_add_f32_e32 v143, v143, v23
	v_add_f32_e32 v140, v140, v16
	v_add_f32_e32 v141, v141, v17
	v_add_f32_e32 v142, v142, v18
	v_add_f32_e32 v143, v143, v19
	v_mov_b32_e32 v151, 0x41600000
	v_div_scale_f32 v146, s[26:27], v151, v151, v140
	v_rcp_f32_e32 v147, v146
	v_div_scale_f32 v148, vcc, v140, v151, v140
	v_fma_f32 v149, -v146, v147, 1.0
	v_fmac_f32_e32 v147, v149, v147
	v_mul_f32_e32 v149, v148, v147
	v_fma_f32 v150, -v146, v149, v148
	v_fmac_f32_e32 v149, v150, v147
	v_fma_f32 v146, -v146, v149, v148
	v_div_fmas_f32 v146, v146, v147, v149
	v_div_fixup_f32 v140, v146, v151, v140
	v_mov_b32_e32 v151, 0x41600000
	v_div_scale_f32 v146, s[26:27], v151, v151, v141
	v_rcp_f32_e32 v147, v146
	v_div_scale_f32 v148, vcc, v141, v151, v141
	v_fma_f32 v149, -v146, v147, 1.0
	v_fmac_f32_e32 v147, v149, v147
	v_mul_f32_e32 v149, v148, v147
	v_fma_f32 v150, -v146, v149, v148
	v_fmac_f32_e32 v149, v150, v147
	v_fma_f32 v146, -v146, v149, v148
	v_div_fmas_f32 v146, v146, v147, v149
	v_div_fixup_f32 v141, v146, v151, v141
	v_mov_b32_e32 v151, 0x41600000
	v_div_scale_f32 v146, s[26:27], v151, v151, v142
	v_rcp_f32_e32 v147, v146
	v_div_scale_f32 v148, vcc, v142, v151, v142
	v_fma_f32 v149, -v146, v147, 1.0
	v_fmac_f32_e32 v147, v149, v147
	v_mul_f32_e32 v149, v148, v147
	v_fma_f32 v150, -v146, v149, v148
	v_fmac_f32_e32 v149, v150, v147
	v_fma_f32 v146, -v146, v149, v148
	v_div_fmas_f32 v146, v146, v147, v149
	v_div_fixup_f32 v142, v146, v151, v142
	v_mov_b32_e32 v151, 0x41600000
	v_div_scale_f32 v146, s[26:27], v151, v151, v143
	v_rcp_f32_e32 v147, v146
	v_div_scale_f32 v148, vcc, v143, v151, v143
	v_fma_f32 v149, -v146, v147, 1.0
	v_fmac_f32_e32 v147, v149, v147
	v_mul_f32_e32 v149, v148, v147
	v_fma_f32 v150, -v146, v149, v148
	v_fmac_f32_e32 v149, v150, v147
	v_fma_f32 v146, -v146, v149, v148
	v_div_fmas_f32 v146, v146, v147, v149
	v_div_fixup_f32 v143, v146, v151, v143
	v_sub_f32_e32 v140, v140, v68
	v_sub_f32_e32 v141, v141, v69
	v_sub_f32_e32 v142, v142, v70
	v_sub_f32_e32 v143, v143, v71
	v_cvt_pk_bf16_f32 v178, v140, v141
	v_cvt_pk_bf16_f32 v179, v142, v143
	s_waitcnt vmcnt(1)
	v_and_b32_e32 v75, 0xffff0000, v73
	v_lshlrev_b32_e32 v74, 16, v73
	v_and_b32_e32 v73, 0xffff0000, v72
	v_lshlrev_b32_e32 v72, 16, v72
	v_add_f32_e32 v140, v72, v68
	v_add_f32_e32 v141, v73, v69
	v_add_f32_e32 v142, v74, v70
	v_add_f32_e32 v143, v75, v71
	v_add_f32_e32 v140, v140, v64
	v_add_f32_e32 v141, v141, v65
	v_add_f32_e32 v142, v142, v66
	v_add_f32_e32 v143, v143, v67
	v_add_f32_e32 v140, v140, v60
	v_add_f32_e32 v141, v141, v61
	v_add_f32_e32 v142, v142, v62
	v_add_f32_e32 v143, v143, v63
	v_add_f32_e32 v140, v140, v56
	v_add_f32_e32 v141, v141, v57
	v_add_f32_e32 v142, v142, v58
	v_add_f32_e32 v143, v143, v59
	v_add_f32_e32 v140, v140, v52
	v_add_f32_e32 v141, v141, v53
	v_add_f32_e32 v142, v142, v54
	v_add_f32_e32 v143, v143, v55
	v_add_f32_e32 v140, v140, v48
	v_add_f32_e32 v141, v141, v49
	v_add_f32_e32 v142, v142, v50
	v_add_f32_e32 v143, v143, v51
	v_add_f32_e32 v140, v140, v44
	v_add_f32_e32 v141, v141, v45
	v_add_f32_e32 v142, v142, v46
	v_add_f32_e32 v143, v143, v47
	v_add_f32_e32 v140, v140, v40
	v_add_f32_e32 v141, v141, v41
	v_add_f32_e32 v142, v142, v42
	v_add_f32_e32 v143, v143, v43
	v_add_f32_e32 v140, v140, v36
	v_add_f32_e32 v141, v141, v37
	v_add_f32_e32 v142, v142, v38
	v_add_f32_e32 v143, v143, v39
	v_add_f32_e32 v140, v140, v32
	v_add_f32_e32 v141, v141, v33
	v_add_f32_e32 v142, v142, v34
	v_add_f32_e32 v143, v143, v35
	v_add_f32_e32 v140, v140, v28
	v_add_f32_e32 v141, v141, v29
	v_add_f32_e32 v142, v142, v30
	v_add_f32_e32 v143, v143, v31
	v_add_f32_e32 v140, v140, v24
	v_add_f32_e32 v141, v141, v25
	v_add_f32_e32 v142, v142, v26
	v_add_f32_e32 v143, v143, v27
	v_add_f32_e32 v140, v140, v20
	v_add_f32_e32 v141, v141, v21
	v_add_f32_e32 v142, v142, v22
	v_add_f32_e32 v143, v143, v23
	v_add_f32_e32 v140, v140, v16
	v_add_f32_e32 v141, v141, v17
	v_add_f32_e32 v142, v142, v18
	v_add_f32_e32 v143, v143, v19
	v_mov_b32_e32 v151, 0x41700000
	v_div_scale_f32 v146, s[26:27], v151, v151, v140
; DI float bflo(unsigned u) { return __uint_as_float(u << 16); }
; DI float bfhi(unsigned u) { return __uint_as_float(u & 0xffff0000u); }
; template <int WIN>
; DI void pool_elem(const Params& p, int row, int c) {
;     ...
;     if (t >= WIN - 1) {
;       cnt = (float)WIN;
;       unsigned w[WIN - 1];
; #pragma unroll
;       for (int j = 1; j < WIN; ++j) w[j - 1] = *(const unsigned*)(P2 + (size_t)(row - j) * 2048 + c);
; #pragma unroll
;       for (int j = 1; j < WIN; ++j) { s0 += bflo(w[j - 1]); s1 += bfhi(w[j - 1]); }
;     } else {
;       cnt = (float)(t + 1);
;       for (int j = 1; j <= t; ++j) {
;         unsigned w = *(const unsigned*)(P2 + (size_t)(row - j) * 2048 + c);
;         s0 += bflo(w); s1 += bfhi(w);
;       }
;     ...
;   *(unsigned*)(p.MIX + (size_t)row * 1024 + c) = pack2(s0 / cnt - u0, s1 / cnt - u1);
	v_rcp_f32_e32 v147, v146
	v_div_scale_f32 v148, vcc, v140, v151, v140
	v_fma_f32 v149, -v146, v147, 1.0
	v_fmac_f32_e32 v147, v149, v147
	v_mul_f32_e32 v149, v148, v147
	v_fma_f32 v150, -v146, v149, v148
	v_fmac_f32_e32 v149, v150, v147
	v_fma_f32 v146, -v146, v149, v148
	v_div_fmas_f32 v146, v146, v147, v149
	v_div_fixup_f32 v140, v146, v151, v140
	v_mov_b32_e32 v151, 0x41700000
	v_div_scale_f32 v146, s[26:27], v151, v151, v141
	v_rcp_f32_e32 v147, v146
	v_div_scale_f32 v148, vcc, v141, v151, v141
	v_fma_f32 v149, -v146, v147, 1.0
	v_fmac_f32_e32 v147, v149, v147
	v_mul_f32_e32 v149, v148, v147
	v_fma_f32 v150, -v146, v149, v148
	v_fmac_f32_e32 v149, v150, v147
	v_fma_f32 v146, -v146, v149, v148
	v_div_fmas_f32 v146, v146, v147, v149
	v_div_fixup_f32 v141, v146, v151, v141
	v_mov_b32_e32 v151, 0x41700000
	v_div_scale_f32 v146, s[26:27], v151, v151, v142
	v_rcp_f32_e32 v147, v146
	v_div_scale_f32 v148, vcc, v142, v151, v142
	v_fma_f32 v149, -v146, v147, 1.0
	v_fmac_f32_e32 v147, v149, v147
	v_mul_f32_e32 v149, v148, v147
	v_fma_f32 v150, -v146, v149, v148
	v_fmac_f32_e32 v149, v150, v147
	v_fma_f32 v146, -v146, v149, v148
	v_div_fmas_f32 v146, v146, v147, v149
	v_div_fixup_f32 v142, v146, v151, v142
	v_mov_b32_e32 v151, 0x41700000
	v_div_scale_f32 v146, s[26:27], v151, v151, v143
	v_rcp_f32_e32 v147, v146
	v_div_scale_f32 v148, vcc, v143, v151, v143
	v_fma_f32 v149, -v146, v147, 1.0
	v_fmac_f32_e32 v147, v149, v147
	v_mul_f32_e32 v149, v148, v147
	v_fma_f32 v150, -v146, v149, v148
	v_fmac_f32_e32 v149, v150, v147
	v_fma_f32 v146, -v146, v149, v148
	v_div_fmas_f32 v146, v146, v147, v149
	v_div_fixup_f32 v143, v146, v151, v143
	v_sub_f32_e32 v140, v140, v72
	v_sub_f32_e32 v141, v141, v73
	v_sub_f32_e32 v142, v142, v74
	v_sub_f32_e32 v143, v143, v75
	v_cvt_pk_bf16_f32 v180, v140, v141
	v_cvt_pk_bf16_f32 v181, v142, v143
	s_waitcnt vmcnt(0)
	v_and_b32_e32 v79, 0xffff0000, v77
	v_lshlrev_b32_e32 v78, 16, v77
	v_and_b32_e32 v77, 0xffff0000, v76
	v_lshlrev_b32_e32 v76, 16, v76
	v_add_f32_e32 v140, v76, v72
	v_add_f32_e32 v141, v77, v73
	v_add_f32_e32 v142, v78, v74
	v_add_f32_e32 v143, v79, v75
	v_add_f32_e32 v140, v140, v68
	v_add_f32_e32 v141, v141, v69
	v_add_f32_e32 v142, v142, v70
	v_add_f32_e32 v143, v143, v71
	v_add_f32_e32 v140, v140, v64
	v_add_f32_e32 v141, v141, v65
	v_add_f32_e32 v142, v142, v66
	v_add_f32_e32 v143, v143, v67
	v_add_f32_e32 v140, v140, v60
	v_add_f32_e32 v141, v141, v61
	v_add_f32_e32 v142, v142, v62
	v_add_f32_e32 v143, v143, v63
	v_add_f32_e32 v140, v140, v56
	v_add_f32_e32 v141, v141, v57
	v_add_f32_e32 v142, v142, v58
	v_add_f32_e32 v143, v143, v59
	v_add_f32_e32 v140, v140, v52
	v_add_f32_e32 v141, v141, v53
	v_add_f32_e32 v142, v142, v54
	v_add_f32_e32 v143, v143, v55
	v_add_f32_e32 v140, v140, v48
	v_add_f32_e32 v141, v141, v49
	v_add_f32_e32 v142, v142, v50
	v_add_f32_e32 v143, v143, v51
	v_add_f32_e32 v140, v140, v44
	v_add_f32_e32 v141, v141, v45
	v_add_f32_e32 v142, v142, v46
	v_add_f32_e32 v143, v143, v47
	v_add_f32_e32 v140, v140, v40
	v_add_f32_e32 v141, v141, v41
	v_add_f32_e32 v142, v142, v42
	v_add_f32_e32 v143, v143, v43
	v_add_f32_e32 v140, v140, v36
	v_add_f32_e32 v141, v141, v37
	v_add_f32_e32 v142, v142, v38
	v_add_f32_e32 v143, v143, v39
	v_add_f32_e32 v140, v140, v32
	v_add_f32_e32 v141, v141, v33
	v_add_f32_e32 v142, v142, v34
	v_add_f32_e32 v143, v143, v35
	v_add_f32_e32 v140, v140, v28
	v_add_f32_e32 v141, v141, v29
	v_add_f32_e32 v142, v142, v30
	v_add_f32_e32 v143, v143, v31
	v_add_f32_e32 v140, v140, v24
	v_add_f32_e32 v141, v141, v25
	v_add_f32_e32 v142, v142, v26
	v_add_f32_e32 v143, v143, v27
	v_add_f32_e32 v140, v140, v20
	v_add_f32_e32 v141, v141, v21
	v_add_f32_e32 v142, v142, v22
	v_add_f32_e32 v143, v143, v23
	v_add_f32_e32 v140, v140, v16
	v_add_f32_e32 v141, v141, v17
	v_add_f32_e32 v142, v142, v18
	v_add_f32_e32 v143, v143, v19
	v_mul_f32_e32 v140, 0x3d800000, v140
	v_mul_f32_e32 v141, 0x3d800000, v141
	v_mul_f32_e32 v142, 0x3d800000, v142
	v_mul_f32_e32 v143, 0x3d800000, v143
	v_sub_f32_e32 v140, v140, v76
	v_sub_f32_e32 v141, v141, v77
	v_sub_f32_e32 v142, v142, v78
	v_sub_f32_e32 v143, v143, v79
	v_cvt_pk_bf16_f32 v182, v140, v141
	v_cvt_pk_bf16_f32 v183, v142, v143
	global_store_dwordx2 v11, v[152:153], s[24:25] sc1
	s_add_u32 s24, s24, 0x800
	s_addc_u32 s25, s25, 0
	global_store_dwordx2 v11, v[154:155], s[24:25] sc1
	s_add_u32 s24, s24, 0x800
	s_addc_u32 s25, s25, 0
	global_store_dwordx2 v11, v[156:157], s[24:25] sc1
	s_add_u32 s24, s24, 0x800
	s_addc_u32 s25, s25, 0
	global_store_dwordx2 v11, v[158:159], s[24:25] sc1
	s_add_u32 s24, s24, 0x800
	s_addc_u32 s25, s25, 0
	global_store_dwordx2 v11, v[160:161], s[24:25] sc1
	s_add_u32 s24, s24, 0x800
	s_addc_u32 s25, s25, 0
	global_store_dwordx2 v11, v[162:163], s[24:25] sc1
	s_add_u32 s24, s24, 0x800
	s_addc_u32 s25, s25, 0
	global_store_dwordx2 v11, v[164:165], s[24:25] sc1
	s_add_u32 s24, s24, 0x800
	s_addc_u32 s25, s25, 0
	global_store_dwordx2 v11, v[166:167], s[24:25] sc1
	s_add_u32 s24, s24, 0x800
	s_addc_u32 s25, s25, 0
	global_store_dwordx2 v11, v[168:169], s[24:25] sc1
	s_add_u32 s24, s24, 0x800
	s_addc_u32 s25, s25, 0
	global_store_dwordx2 v11, v[170:171], s[24:25] sc1
	s_add_u32 s24, s24, 0x800
	s_addc_u32 s25, s25, 0
	global_store_dwordx2 v11, v[172:173], s[24:25] sc1
	s_add_u32 s24, s24, 0x800
	s_addc_u32 s25, s25, 0
	global_store_dwordx2 v11, v[174:175], s[24:25] sc1
	s_add_u32 s24, s24, 0x800
	s_addc_u32 s25, s25, 0
	global_store_dwordx2 v11, v[176:177], s[24:25] sc1
	s_add_u32 s24, s24, 0x800
	s_addc_u32 s25, s25, 0
	global_store_dwordx2 v11, v[178:179], s[24:25] sc1
	s_add_u32 s24, s24, 0x800
	s_addc_u32 s25, s25, 0
	global_store_dwordx2 v11, v[180:181], s[24:25] sc1
	s_add_u32 s24, s24, 0x800
	s_addc_u32 s25, s25, 0
	global_store_dwordx2 v11, v[182:183], s[24:25] sc1
	s_add_u32 s24, s24, 0x800
	s_addc_u32 s25, s25, 0
	s_branch .Lp13f_next

; template <int WIN>
; DI void pool_elem(const Params& p, int row, int c) {
;     ...
;   } else {
;     const int s = row - NPR;
;     cnt = (float)WIN;
;     const float* sp = p.state_pool + (size_t)s * 15 * 1024 + c;
;     float2 st[15];
; #pragma unroll
;     for (int j = 0; j < 15; ++j) st[j] = *(const float2*)(sp + (size_t)j * 1024);
; #pragma unroll
;     for (int j = 1; j < WIN; ++j) { s0 += st[15 - j].x; s1 += st[15 - j].y; }
;     float* op = p.out + O_POOLS + (size_t)s * 15 * 1024 + c;
; #pragma unroll
;     for (int j = 0; j < 14; ++j) *(float2*)(op + (size_t)j * 1024) = st[j + 1];
;     float2 o = {u0, u1};
;     *(float2*)(op + (size_t)14 * 1024) = o;
;   }
; DI void phase_pool(const Params& p) {
;   for (int idx = blockIdx.x * 256 + threadIdx.x; idx < NROW * 512; idx += gridDim.x * 256) {
;     const int row = idx >> 9, c = (idx & 511) * 2;
;     const int gi = c >> 8;
;     if (gi == 0) pool_elem<2>(p, row, c);
;     else if (gi == 1) pool_elem<4>(p, row, c);
;     else if (gi == 2) pool_elem<8>(p, row, c);
;     else pool_elem<16>(p, row, c);
.LBB0_1252:
	v_readfirstlane_b32 s98, v14
	s_nop 3
	s_lshr_b32 s99, s98, 9
	s_cmp_lt_u32 s99, 0x4000
	s_cbranch_scc1 .Lp13_skip
	v_lshlrev_b32_e32 v0, 1, v14
	v_and_b32_e32 v0, 0x3fe, v0
	v_ashrrev_i32_e32 v2, 9, v14
	v_cmp_lt_u32_e32 vcc, s48, v0
	s_and_saveexec_b64 s[0:1], vcc
	s_xor_b64 s[38:39], exec, s[0:1]
	s_cbranch_execz .LBB0_1286
	v_ashrrev_i32_e32 v3, 31, v2
	v_lshlrev_b64 v[8:9], 12, v[2:3]
	v_lshl_add_u64 v[4:5], s[20:21], 0, v[8:9]
	v_lshlrev_b32_e32 v6, 1, v0
	v_mov_b32_e32 v7, v1
	v_lshl_add_u64 v[4:5], v[4:5], 0, v[6:7]
	global_load_dword v5, v[4:5], off
	v_lshrrev_b32_e32 v7, 8, v0
	v_lshlrev_b32_e32 v4, 1, v15
	v_cmp_lt_i32_e64 s[0:1], s49, v2
	v_mov_b32_e32 v11, v1
	v_and_b32_e32 v10, 0x7fc, v4
	v_cmp_lt_i32_e32 vcc, 1, v7
	s_waitcnt vmcnt(0)
	v_lshlrev_b32_e32 v4, 16, v5
	v_and_b32_e32 v5, 0xffff0000, v5
	s_and_saveexec_b64 s[4:5], vcc
	s_xor_b64 s[40:41], exec, s[4:5]
	s_cbranch_execz .LBB0_1275
	v_cmp_ne_u32_e32 vcc, 2, v7
	s_and_saveexec_b64 s[4:5], vcc
	s_xor_b64 s[42:43], exec, s[4:5]
	s_cbranch_execz .LBB0_1264
	s_and_saveexec_b64 s[4:5], s[0:1]
	s_xor_b64 s[44:45], exec, s[4:5]
	s_cbranch_execz .LBB0_1257
	v_add_u32_e32 v42, 0xffffc000, v2
	v_mov_b64_e32 v[6:7], s[18:19]
	v_mad_u64_u32 v[6:7], s[4:5], v42, s51, v[6:7]
	v_lshlrev_b32_e32 v8, 2, v0
	v_mov_b32_e32 v9, v1
	v_lshl_add_u64 v[6:7], v[6:7], 0, v[8:9]
	v_add_co_u32_e32 v10, vcc, 0x1000, v6
	v_mov_b64_e32 v[40:41], s[24:25]
	s_nop 0
	v_addc_co_u32_e32 v11, vcc, 0, v7, vcc
	v_add_co_u32_e32 v12, vcc, 0x2000, v6
	s_mov_b64 s[4:5], vcc
	v_add_co_u32_e32 v16, vcc, 0x3000, v6
	s_mov_b64 s[6:7], vcc
	v_add_co_u32_e32 v18, vcc, 0x4000, v6
	s_mov_b64 s[8:9], vcc
	v_add_co_u32_e32 v20, vcc, 0x5000, v6
	s_mov_b64 s[10:11], vcc
	v_add_co_u32_e32 v22, vcc, 0x6000, v6
	s_mov_b64 s[12:13], vcc
	v_add_co_u32_e32 v24, vcc, 0x7000, v6
	s_mov_b64 s[14:15], vcc
	v_add_co_u32_e32 v26, vcc, 0x8000, v6
	global_load_dwordx2 v[10:11], v[10:11], off
	s_nop 0
	v_addc_co_u32_e32 v27, vcc, 0, v7, vcc
	v_add_co_u32_e32 v28, vcc, 0x9000, v6
	s_nop 1
	v_addc_co_u32_e32 v29, vcc, 0, v7, vcc
	v_add_co_u32_e32 v30, vcc, 0xa000, v6
	s_nop 1
	v_addc_co_u32_e32 v31, vcc, 0, v7, vcc
	v_add_co_u32_e32 v32, vcc, 0xb000, v6
	s_mov_b64 s[16:17], vcc
	v_add_co_u32_e32 v34, vcc, 0xc000, v6
	s_nop 1
	v_addc_co_u32_e32 v35, vcc, 0, v7, vcc
	v_add_co_u32_e32 v36, vcc, 0xd000, v6
	s_nop 1
	v_addc_co_u32_e32 v37, vcc, 0, v7, vcc
	v_add_co_u32_e32 v38, vcc, 0xe000, v6
	s_nop 1
	v_addc_co_u32_e32 v39, vcc, 0, v7, vcc
	global_load_dwordx2 v[34:35], v[34:35], off
	s_nop 0
	global_load_dwordx2 v[36:37], v[36:37], off
	s_nop 0
	global_load_dwordx2 v[38:39], v[38:39], off
	v_addc_co_u32_e64 v33, vcc, 0, v7, s[16:17]
	v_addc_co_u32_e64 v13, vcc, 0, v7, s[4:5]
	v_addc_co_u32_e64 v17, vcc, 0, v7, s[6:7]
	global_load_dwordx2 v[32:33], v[32:33], off
	s_nop 0
	global_load_dwordx2 v[30:31], v[30:31], off
	s_nop 0
	global_load_dwordx2 v[28:29], v[28:29], off
	s_nop 0
	global_load_dwordx2 v[26:27], v[26:27], off
	s_nop 0
	global_load_dwordx2 v[12:13], v[12:13], off
	s_nop 0
	global_load_dwordx2 v[16:17], v[16:17], off
	v_addc_co_u32_e64 v19, vcc, 0, v7, s[8:9]
	v_addc_co_u32_e64 v21, vcc, 0, v7, s[10:11]
	global_load_dwordx2 v[18:19], v[18:19], off
	s_nop 0
	global_load_dwordx2 v[20:21], v[20:21], off
	v_addc_co_u32_e64 v23, vcc, 0, v7, s[12:13]
	v_addc_co_u32_e64 v25, vcc, 0, v7, s[14:15]
	global_load_dwordx2 v[22:23], v[22:23], off
	s_nop 0
	global_load_dwordx2 v[24:25], v[24:25], off
	s_nop 0
	global_load_dwordx2 v[6:7], v[6:7], off
	v_mad_u64_u32 v[40:41], s[4:5], v42, s51, v[40:41]
	v_lshl_add_u64 v[8:9], v[40:41], 0, v[8:9]
	v_add_co_u32_e32 v42, vcc, s52, v8
	s_waitcnt vmcnt(14)
	global_store_dwordx2 v[8:9], v[10:11], off sc1
	v_addc_co_u32_e32 v43, vcc, 0, v9, vcc
	s_waitcnt vmcnt(7)
	global_store_dwordx2 v[42:43], v[12:13], off offset:-4096 sc1
	s_waitcnt vmcnt(7)
	global_store_dwordx2 v[42:43], v[16:17], off sc1
	v_pk_add_f32 v[40:41], v[4:5], v[38:39]
	v_add_co_u32_e32 v42, vcc, s53, v8
	v_pk_add_f32 v[40:41], v[40:41], v[36:37]
	s_nop 0
	v_addc_co_u32_e32 v43, vcc, 0, v9, vcc
	v_pk_add_f32 v[40:41], v[40:41], v[34:35]
	s_waitcnt vmcnt(7)
	global_store_dwordx2 v[42:43], v[18:19], off offset:-4096 sc1
	s_waitcnt vmcnt(7)
	global_store_dwordx2 v[42:43], v[20:21], off sc1
	v_pk_add_f32 v[40:41], v[40:41], v[32:33]
	v_add_co_u32_e32 v42, vcc, s54, v8
	v_pk_add_f32 v[40:41], v[40:41], v[30:31]
	s_nop 0
	v_addc_co_u32_e32 v43, vcc, 0, v9, vcc
	v_pk_add_f32 v[40:41], v[40:41], v[28:29]
	s_waitcnt vmcnt(7)
	global_store_dwordx2 v[42:43], v[22:23], off offset:-4096 sc1
	s_waitcnt vmcnt(7)
	global_store_dwordx2 v[42:43], v[24:25], off sc1
	v_pk_add_f32 v[40:41], v[40:41], v[26:27]
	v_add_co_u32_e32 v42, vcc, s55, v8
	v_pk_add_f32 v[24:25], v[40:41], v[24:25]
	s_nop 0
	v_addc_co_u32_e32 v43, vcc, 0, v9, vcc
	global_store_dwordx2 v[42:43], v[26:27], off offset:-4096 sc1
	global_store_dwordx2 v[42:43], v[28:29], off sc1
	v_add_co_u32_e32 v26, vcc, s56, v8
	v_pk_add_f32 v[22:23], v[24:25], v[22:23]
	s_nop 0
	v_addc_co_u32_e32 v27, vcc, 0, v9, vcc
	v_pk_add_f32 v[20:21], v[22:23], v[20:21]
	global_store_dwordx2 v[26:27], v[30:31], off offset:-4096 sc1
	global_store_dwordx2 v[26:27], v[32:33], off sc1
	v_add_co_u32_e32 v26, vcc, s58, v8
	v_pk_add_f32 v[18:19], v[20:21], v[18:19]
	s_nop 0
	v_addc_co_u32_e32 v27, vcc, 0, v9, vcc
	v_pk_add_f32 v[16:17], v[18:19], v[16:17]
	global_store_dwordx2 v[26:27], v[34:35], off offset:-4096 sc1
	global_store_dwordx2 v[26:27], v[36:37], off sc1
	v_add_co_u32_e32 v26, vcc, s59, v8
	v_pk_add_f32 v[12:13], v[16:17], v[12:13]
	s_nop 0
	v_addc_co_u32_e32 v27, vcc, 0, v9, vcc
	v_pk_add_f32 v[10:11], v[12:13], v[10:11]
	global_store_dwordx2 v[26:27], v[38:39], off sc1
	s_waitcnt vmcnt(14)
	v_pk_add_f32 v[12:13], v[6:7], v[10:11]
	v_add_co_u32_e32 v6, vcc, 0xe000, v8
	s_nop 1
	v_addc_co_u32_e32 v7, vcc, 0, v9, vcc
	global_store_dwordx2 v[6:7], v[4:5], off sc1

; template <int WIN>
; DI void pool_elem(const Params& p, int row, int c) {
;     ...
;     if (t >= 2033) {
;       float2 o = {u0, u1};
;       *(float2*)(p.out + O_POOLP + ((size_t)b * 15 + (t - 2033)) * 1024 + c) = o;
;     }
.LBB0_1261:
	v_ashrrev_i32_e32 v6, 20, v14
	v_mul_i32_i24_e32 v8, 15, v6
	v_ashrrev_i32_e32 v9, 31, v8
	v_add_u32_e32 v10, 0xfffff80f, v16
	v_mov_b32_e32 v11, v1
	v_lshl_add_u64 v[8:9], v[10:11], 0, v[8:9]
	v_lshlrev_b64 v[8:9], 12, v[8:9]
	v_lshl_add_u64 v[8:9], s[26:27], 0, v[8:9]
	v_lshlrev_b32_e32 v10, 2, v0
	v_lshl_add_u64 v[8:9], v[8:9], 0, v[10:11]
	global_store_dwordx2 v[8:9], v[4:5], off sc1

; template <int WIN>
; DI void pool_elem(const Params& p, int row, int c) {
;     ...
;   } else {
;     const int s = row - NPR;
;     cnt = (float)WIN;
;     const float* sp = p.state_pool + (size_t)s * 15 * 1024 + c;
;     float2 st[15];
; #pragma unroll
;     for (int j = 0; j < 15; ++j) st[j] = *(const float2*)(sp + (size_t)j * 1024);
; #pragma unroll
;     for (int j = 1; j < WIN; ++j) { s0 += st[15 - j].x; s1 += st[15 - j].y; }
;     float* op = p.out + O_POOLS + (size_t)s * 15 * 1024 + c;
; #pragma unroll
;     for (int j = 0; j < 14; ++j) *(float2*)(op + (size_t)j * 1024) = st[j + 1];
;     float2 o = {u0, u1};
;     *(float2*)(op + (size_t)14 * 1024) = o;
;   }
.LBB0_1264:
	s_andn2_saveexec_b64 s[4:5], s[42:43]
	s_cbranch_execz .LBB0_1274
	s_and_saveexec_b64 s[6:7], s[0:1]
	s_xor_b64 s[6:7], exec, s[6:7]
	s_cbranch_execz .LBB0_1267
	v_add_u32_e32 v40, 0xffffc000, v2
	v_mov_b64_e32 v[6:7], s[18:19]
	v_mad_u64_u32 v[6:7], s[8:9], v40, s51, v[6:7]
	v_lshlrev_b32_e32 v8, 2, v0
	v_mov_b32_e32 v9, v1
	v_lshl_add_u64 v[6:7], v[6:7], 0, v[8:9]
	v_add_co_u32_e32 v10, vcc, 0x1000, v6
	v_mov_b64_e32 v[38:39], s[24:25]
	s_nop 0
	v_addc_co_u32_e32 v11, vcc, 0, v7, vcc
	v_add_co_u32_e32 v12, vcc, 0x2000, v6
	v_mad_u64_u32 v[38:39], s[8:9], v40, s51, v[38:39]
	s_nop 0
	v_addc_co_u32_e32 v13, vcc, 0, v7, vcc
	v_add_co_u32_e32 v16, vcc, 0x3000, v6
	v_lshl_add_u64 v[8:9], v[38:39], 0, v[8:9]
	s_nop 0
	v_addc_co_u32_e32 v17, vcc, 0, v7, vcc
	v_add_co_u32_e32 v18, vcc, 0x4000, v6
	s_nop 1
	v_addc_co_u32_e32 v19, vcc, 0, v7, vcc
	v_add_co_u32_e32 v20, vcc, 0x5000, v6
	global_load_dwordx2 v[10:11], v[10:11], off
	s_nop 0
	global_load_dwordx2 v[12:13], v[12:13], off
	s_nop 0
	global_load_dwordx2 v[16:17], v[16:17], off
	s_nop 0
	global_load_dwordx2 v[18:19], v[18:19], off
	v_addc_co_u32_e32 v21, vcc, 0, v7, vcc
	v_add_co_u32_e32 v22, vcc, 0x6000, v6
	s_nop 1
	v_addc_co_u32_e32 v23, vcc, 0, v7, vcc
	v_add_co_u32_e32 v24, vcc, 0x7000, v6
	s_nop 1
	v_addc_co_u32_e32 v25, vcc, 0, v7, vcc
	v_add_co_u32_e32 v26, vcc, 0x8000, v6
	s_nop 1
	v_addc_co_u32_e32 v27, vcc, 0, v7, vcc
	v_add_co_u32_e32 v28, vcc, 0x9000, v6
	global_load_dwordx2 v[20:21], v[20:21], off
	s_nop 0
	global_load_dwordx2 v[22:23], v[22:23], off
	s_nop 0
	global_load_dwordx2 v[24:25], v[24:25], off
	s_nop 0
	global_load_dwordx2 v[26:27], v[26:27], off
	v_addc_co_u32_e32 v29, vcc, 0, v7, vcc
	v_add_co_u32_e32 v30, vcc, 0xa000, v6
	global_load_dwordx2 v[28:29], v[28:29], off
	s_nop 0
	v_addc_co_u32_e32 v31, vcc, 0, v7, vcc
	v_add_co_u32_e32 v32, vcc, 0xb000, v6
	s_nop 1
	v_addc_co_u32_e32 v33, vcc, 0, v7, vcc
	v_add_co_u32_e32 v34, vcc, 0xc000, v6
	s_nop 1
	v_addc_co_u32_e32 v35, vcc, 0, v7, vcc
	v_add_co_u32_e32 v36, vcc, 0xd000, v6
	global_load_dwordx2 v[30:31], v[30:31], off
	s_nop 0
	global_load_dwordx2 v[32:33], v[32:33], off
	s_nop 0
	global_load_dwordx2 v[34:35], v[34:35], off
	v_addc_co_u32_e32 v37, vcc, 0, v7, vcc
	v_add_co_u32_e32 v6, vcc, 0xe000, v6
	global_load_dwordx2 v[36:37], v[36:37], off
	s_nop 0
	v_addc_co_u32_e32 v7, vcc, 0, v7, vcc
	global_load_dwordx2 v[6:7], v[6:7], off
	s_waitcnt vmcnt(13)
	global_store_dwordx2 v[8:9], v[10:11], off sc1
	v_add_co_u32_e32 v10, vcc, s52, v8
	s_nop 1
	v_addc_co_u32_e32 v11, vcc, 0, v9, vcc
	s_waitcnt vmcnt(13)
	global_store_dwordx2 v[10:11], v[12:13], off offset:-4096 sc1
	s_waitcnt vmcnt(13)
	global_store_dwordx2 v[10:11], v[16:17], off sc1
	v_add_co_u32_e32 v10, vcc, s53, v8
	s_nop 1
	v_addc_co_u32_e32 v11, vcc, 0, v9, vcc
	s_waitcnt vmcnt(13)
	global_store_dwordx2 v[10:11], v[18:19], off offset:-4096 sc1
	s_waitcnt vmcnt(13)
	global_store_dwordx2 v[10:11], v[20:21], off sc1
	v_add_co_u32_e32 v10, vcc, s54, v8
	s_nop 1
	v_addc_co_u32_e32 v11, vcc, 0, v9, vcc
	s_waitcnt vmcnt(13)
	global_store_dwordx2 v[10:11], v[22:23], off offset:-4096 sc1
	s_waitcnt vmcnt(13)
	global_store_dwordx2 v[10:11], v[24:25], off sc1
	v_add_co_u32_e32 v10, vcc, s55, v8
	s_nop 1
	v_addc_co_u32_e32 v11, vcc, 0, v9, vcc
	s_waitcnt vmcnt(13)
	global_store_dwordx2 v[10:11], v[26:27], off offset:-4096 sc1
	s_waitcnt vmcnt(13)
	global_store_dwordx2 v[10:11], v[28:29], off sc1
	v_add_co_u32_e32 v10, vcc, s56, v8
	s_nop 1
	v_addc_co_u32_e32 v11, vcc, 0, v9, vcc
	s_waitcnt vmcnt(13)
	global_store_dwordx2 v[10:11], v[30:31], off offset:-4096 sc1
	s_waitcnt vmcnt(13)
	global_store_dwordx2 v[10:11], v[32:33], off sc1
	v_add_co_u32_e32 v10, vcc, s58, v8
	s_nop 1
	v_addc_co_u32_e32 v11, vcc, 0, v9, vcc
	s_waitcnt vmcnt(13)
	global_store_dwordx2 v[10:11], v[34:35], off offset:-4096 sc1
	s_waitcnt vmcnt(13)
	global_store_dwordx2 v[10:11], v[36:37], off sc1
	v_add_co_u32_e32 v10, vcc, 0xd000, v8
	s_nop 1
	v_addc_co_u32_e32 v11, vcc, 0, v9, vcc
	s_waitcnt vmcnt(13)
	global_store_dwordx2 v[10:11], v[6:7], off sc1
	v_pk_add_f32 v[6:7], v[4:5], v[6:7]
	s_nop 0
	v_pk_add_f32 v[6:7], v[6:7], v[36:37]
	s_nop 0
	v_pk_add_f32 v[6:7], v[6:7], v[34:35]
	s_nop 0
	v_pk_add_f32 v[6:7], v[6:7], v[32:33]
	s_nop 0
	v_pk_add_f32 v[6:7], v[6:7], v[30:31]
	s_nop 0
	v_pk_add_f32 v[6:7], v[6:7], v[28:29]
	s_nop 0
	v_pk_add_f32 v[12:13], v[6:7], v[26:27]
	v_add_co_u32_e32 v6, vcc, 0xe000, v8
	s_nop 1
	v_addc_co_u32_e32 v7, vcc, 0, v9, vcc
	global_store_dwordx2 v[6:7], v[4:5], off sc1

; template <int WIN>
; DI void pool_elem(const Params& p, int row, int c) {
;     ...
;   } else {
;     const int s = row - NPR;
;     cnt = (float)WIN;
;     const float* sp = p.state_pool + (size_t)s * 15 * 1024 + c;
;     float2 st[15];
; #pragma unroll
;     for (int j = 0; j < 15; ++j) st[j] = *(const float2*)(sp + (size_t)j * 1024);
; #pragma unroll
;     for (int j = 1; j < WIN; ++j) { s0 += st[15 - j].x; s1 += st[15 - j].y; }
;     float* op = p.out + O_POOLS + (size_t)s * 15 * 1024 + c;
; #pragma unroll
;     for (int j = 0; j < 14; ++j) *(float2*)(op + (size_t)j * 1024) = st[j + 1];
;     float2 o = {u0, u1};
;     *(float2*)(op + (size_t)14 * 1024) = o;
;   }
.LBB0_1275:
	s_andn2_saveexec_b64 s[4:5], s[40:41]
	s_cbranch_execz .LBB0_1285
	s_and_saveexec_b64 s[6:7], s[0:1]
	s_xor_b64 s[0:1], exec, s[6:7]
	s_cbranch_execz .LBB0_1278
	v_add_u32_e32 v40, 0xffffc000, v2
	v_mov_b64_e32 v[6:7], s[18:19]
	v_mad_u64_u32 v[6:7], s[6:7], v40, s51, v[6:7]
	v_lshlrev_b32_e32 v8, 2, v0
	v_mov_b32_e32 v9, v1
	v_lshl_add_u64 v[6:7], v[6:7], 0, v[8:9]
	v_add_co_u32_e32 v10, vcc, 0x1000, v6
	v_mov_b64_e32 v[38:39], s[24:25]
	s_nop 0
	v_addc_co_u32_e32 v11, vcc, 0, v7, vcc
	v_add_co_u32_e32 v12, vcc, 0x2000, v6
	v_mad_u64_u32 v[38:39], s[6:7], v40, s51, v[38:39]
	s_nop 0
	v_addc_co_u32_e32 v13, vcc, 0, v7, vcc
	v_add_co_u32_e32 v16, vcc, 0x3000, v6
	v_lshl_add_u64 v[8:9], v[38:39], 0, v[8:9]
	s_nop 0
	v_addc_co_u32_e32 v17, vcc, 0, v7, vcc
	v_add_co_u32_e32 v18, vcc, 0x4000, v6
	s_nop 1
	v_addc_co_u32_e32 v19, vcc, 0, v7, vcc
	v_add_co_u32_e32 v20, vcc, 0x5000, v6
	global_load_dwordx2 v[10:11], v[10:11], off
	s_nop 0
	global_load_dwordx2 v[12:13], v[12:13], off
	s_nop 0
	global_load_dwordx2 v[16:17], v[16:17], off
	s_nop 0
	global_load_dwordx2 v[18:19], v[18:19], off
	v_addc_co_u32_e32 v21, vcc, 0, v7, vcc
	v_add_co_u32_e32 v22, vcc, 0x6000, v6
	s_nop 1
	v_addc_co_u32_e32 v23, vcc, 0, v7, vcc
	v_add_co_u32_e32 v24, vcc, 0x7000, v6
	s_nop 1
	v_addc_co_u32_e32 v25, vcc, 0, v7, vcc
	v_add_co_u32_e32 v26, vcc, 0x8000, v6
	s_nop 1
	v_addc_co_u32_e32 v27, vcc, 0, v7, vcc
	v_add_co_u32_e32 v28, vcc, 0x9000, v6
	global_load_dwordx2 v[20:21], v[20:21], off
	s_nop 0
	global_load_dwordx2 v[22:23], v[22:23], off
	s_nop 0
	global_load_dwordx2 v[24:25], v[24:25], off
	s_nop 0
	global_load_dwordx2 v[26:27], v[26:27], off
	v_addc_co_u32_e32 v29, vcc, 0, v7, vcc
	v_add_co_u32_e32 v30, vcc, 0xa000, v6
	global_load_dwordx2 v[28:29], v[28:29], off
	s_nop 0
	v_addc_co_u32_e32 v31, vcc, 0, v7, vcc
	v_add_co_u32_e32 v32, vcc, 0xb000, v6
	s_nop 1
	v_addc_co_u32_e32 v33, vcc, 0, v7, vcc
	global_load_dwordx2 v[30:31], v[30:31], off
	s_nop 0
	global_load_dwordx2 v[32:33], v[32:33], off
	v_add_co_u32_e32 v34, vcc, 0xc000, v6
	s_nop 1
	v_addc_co_u32_e32 v35, vcc, 0, v7, vcc
	global_load_dwordx2 v[34:35], v[34:35], off
	v_add_co_u32_e32 v36, vcc, 0xd000, v6
	s_nop 1
	v_addc_co_u32_e32 v37, vcc, 0, v7, vcc
	global_load_dwordx2 v[36:37], v[36:37], off
	v_add_co_u32_e32 v6, vcc, 0xe000, v6
	s_nop 1
	v_addc_co_u32_e32 v7, vcc, 0, v7, vcc
	global_load_dwordx2 v[6:7], v[6:7], off
	s_waitcnt vmcnt(13)
	global_store_dwordx2 v[8:9], v[10:11], off sc1
	v_add_co_u32_e32 v10, vcc, s52, v8
	s_nop 1
	v_addc_co_u32_e32 v11, vcc, 0, v9, vcc
	s_waitcnt vmcnt(13)
	global_store_dwordx2 v[10:11], v[12:13], off offset:-4096 sc1
	s_waitcnt vmcnt(13)
	global_store_dwordx2 v[10:11], v[16:17], off sc1
	v_add_co_u32_e32 v10, vcc, s53, v8
	s_nop 1
	v_addc_co_u32_e32 v11, vcc, 0, v9, vcc
	s_waitcnt vmcnt(13)
	global_store_dwordx2 v[10:11], v[18:19], off offset:-4096 sc1
	s_waitcnt vmcnt(13)
	global_store_dwordx2 v[10:11], v[20:21], off sc1
	v_add_co_u32_e32 v10, vcc, s54, v8
	s_nop 1
	v_addc_co_u32_e32 v11, vcc, 0, v9, vcc
	s_waitcnt vmcnt(13)
	global_store_dwordx2 v[10:11], v[22:23], off offset:-4096 sc1
	s_waitcnt vmcnt(13)
	global_store_dwordx2 v[10:11], v[24:25], off sc1
	v_add_co_u32_e32 v10, vcc, s55, v8
	s_nop 1
	v_addc_co_u32_e32 v11, vcc, 0, v9, vcc
	s_waitcnt vmcnt(13)
	global_store_dwordx2 v[10:11], v[26:27], off offset:-4096 sc1
	s_waitcnt vmcnt(13)
	global_store_dwordx2 v[10:11], v[28:29], off sc1
	v_add_co_u32_e32 v10, vcc, s56, v8
	s_nop 1
	v_addc_co_u32_e32 v11, vcc, 0, v9, vcc
	s_waitcnt vmcnt(13)
	global_store_dwordx2 v[10:11], v[30:31], off offset:-4096 sc1
	s_waitcnt vmcnt(13)
	global_store_dwordx2 v[10:11], v[32:33], off sc1
	v_add_co_u32_e32 v10, vcc, s57, v8
	s_nop 1
	v_addc_co_u32_e32 v11, vcc, 0, v9, vcc
	s_waitcnt vmcnt(13)
	global_store_dwordx2 v[10:11], v[34:35], off sc1
	v_add_co_u32_e32 v10, vcc, 0xc000, v8
	s_nop 1
	v_addc_co_u32_e32 v11, vcc, 0, v9, vcc
	s_waitcnt vmcnt(13)
	global_store_dwordx2 v[10:11], v[36:37], off sc1
	v_add_co_u32_e32 v10, vcc, 0xd000, v8
	s_nop 1
	v_addc_co_u32_e32 v11, vcc, 0, v9, vcc
	s_waitcnt vmcnt(13)
	global_store_dwordx2 v[10:11], v[6:7], off sc1
	v_pk_add_f32 v[6:7], v[4:5], v[6:7]
	s_nop 0
	v_pk_add_f32 v[6:7], v[6:7], v[36:37]
	s_nop 0
	v_pk_add_f32 v[12:13], v[6:7], v[34:35]
	v_add_co_u32_e32 v6, vcc, 0xe000, v8
	s_nop 1
	v_addc_co_u32_e32 v7, vcc, 0, v9, vcc
	global_store_dwordx2 v[6:7], v[4:5], off sc1

; DI float bflo(unsigned u) { return __uint_as_float(u << 16); }
; DI float bfhi(unsigned u) { return __uint_as_float(u & 0xffff0000u); }
; template <int WIN>
; DI void pool_elem(const Params& p, int row, int c) {
;     ...
;   unsigned uu = *(const unsigned*)(P2 + (size_t)row * 2048 + c);
;   const float u0 = bflo(uu), u1 = bfhi(uu);
;     ...
;   } else {
;     const int s = row - NPR;
;     cnt = (float)WIN;
;     const float* sp = p.state_pool + (size_t)s * 15 * 1024 + c;
;     float2 st[15];
; #pragma unroll
;     for (int j = 0; j < 15; ++j) st[j] = *(const float2*)(sp + (size_t)j * 1024);
; #pragma unroll
;     for (int j = 1; j < WIN; ++j) { s0 += st[15 - j].x; s1 += st[15 - j].y; }
;     float* op = p.out + O_POOLS + (size_t)s * 15 * 1024 + c;
; #pragma unroll
;     for (int j = 0; j < 14; ++j) *(float2*)(op + (size_t)j * 1024) = st[j + 1];
;     float2 o = {u0, u1};
;     *(float2*)(op + (size_t)14 * 1024) = o;
;   }
.LBB0_1286:
	s_andn2_saveexec_b64 s[0:1], s[38:39]
	s_cbranch_execz .LBB0_1251
	v_ashrrev_i32_e32 v3, 31, v2
	v_lshlrev_b64 v[4:5], 12, v[2:3]
	v_lshl_add_u64 v[4:5], s[20:21], 0, v[4:5]
	v_lshlrev_b32_e32 v8, 1, v0
	v_mov_b32_e32 v9, v1
	v_lshl_add_u64 v[4:5], v[4:5], 0, v[8:9]
	global_load_dword v5, v[4:5], off
	v_cmp_lt_i32_e32 vcc, s49, v2
	s_waitcnt vmcnt(0)
	v_lshlrev_b32_e32 v4, 16, v5
	v_and_b32_e32 v5, 0xffff0000, v5
	s_and_saveexec_b64 s[4:5], vcc
	s_xor_b64 s[4:5], exec, s[4:5]
	s_cbranch_execz .LBB0_1289
	v_add_u32_e32 v40, 0xffffc000, v2
	v_mov_b64_e32 v[6:7], s[18:19]
	v_mad_u64_u32 v[6:7], s[6:7], v40, s51, v[6:7]
	v_lshlrev_b32_e32 v8, 2, v0
	v_mov_b32_e32 v9, v1
	v_lshl_add_u64 v[6:7], v[6:7], 0, v[8:9]
	v_add_co_u32_e32 v10, vcc, 0x1000, v6
	v_mov_b64_e32 v[38:39], s[24:25]
	s_nop 0
	v_addc_co_u32_e32 v11, vcc, 0, v7, vcc
	v_add_co_u32_e32 v12, vcc, 0x2000, v6
	v_mad_u64_u32 v[38:39], s[6:7], v40, s51, v[38:39]
	s_nop 0
	v_addc_co_u32_e32 v13, vcc, 0, v7, vcc
	v_add_co_u32_e32 v16, vcc, 0x3000, v6
	v_lshl_add_u64 v[8:9], v[38:39], 0, v[8:9]
	s_nop 0
	v_addc_co_u32_e32 v17, vcc, 0, v7, vcc
	v_add_co_u32_e32 v18, vcc, 0x4000, v6
	s_nop 1
	v_addc_co_u32_e32 v19, vcc, 0, v7, vcc
	v_add_co_u32_e32 v20, vcc, 0x5000, v6
	global_load_dwordx2 v[10:11], v[10:11], off
	s_nop 0
	global_load_dwordx2 v[12:13], v[12:13], off
	s_nop 0
	global_load_dwordx2 v[16:17], v[16:17], off
	s_nop 0
	global_load_dwordx2 v[18:19], v[18:19], off
	v_addc_co_u32_e32 v21, vcc, 0, v7, vcc
	v_add_co_u32_e32 v22, vcc, 0x6000, v6
	s_nop 1
	v_addc_co_u32_e32 v23, vcc, 0, v7, vcc
	v_add_co_u32_e32 v24, vcc, 0x7000, v6
	s_nop 1
	v_addc_co_u32_e32 v25, vcc, 0, v7, vcc
	v_add_co_u32_e32 v26, vcc, 0x8000, v6
	s_nop 1
	v_addc_co_u32_e32 v27, vcc, 0, v7, vcc
	v_add_co_u32_e32 v28, vcc, 0x9000, v6
	global_load_dwordx2 v[20:21], v[20:21], off
	s_nop 0
	global_load_dwordx2 v[22:23], v[22:23], off
	s_nop 0
	global_load_dwordx2 v[24:25], v[24:25], off
	s_nop 0
	global_load_dwordx2 v[26:27], v[26:27], off
	v_addc_co_u32_e32 v29, vcc, 0, v7, vcc
	v_add_co_u32_e32 v30, vcc, 0xa000, v6
	global_load_dwordx2 v[28:29], v[28:29], off
	s_nop 0
	v_addc_co_u32_e32 v31, vcc, 0, v7, vcc
	v_add_co_u32_e32 v32, vcc, 0xb000, v6
	s_nop 1
	v_addc_co_u32_e32 v33, vcc, 0, v7, vcc
	global_load_dwordx2 v[30:31], v[30:31], off
	s_nop 0
	global_load_dwordx2 v[32:33], v[32:33], off
	v_add_co_u32_e32 v34, vcc, 0xc000, v6
	s_nop 1
	v_addc_co_u32_e32 v35, vcc, 0, v7, vcc
	global_load_dwordx2 v[34:35], v[34:35], off
	v_add_co_u32_e32 v36, vcc, 0xd000, v6
	s_nop 1
	v_addc_co_u32_e32 v37, vcc, 0, v7, vcc
	global_load_dwordx2 v[36:37], v[36:37], off
	v_add_co_u32_e32 v6, vcc, 0xe000, v6
	s_nop 1
	v_addc_co_u32_e32 v7, vcc, 0, v7, vcc
	global_load_dwordx2 v[6:7], v[6:7], off
	s_waitcnt vmcnt(13)
	global_store_dwordx2 v[8:9], v[10:11], off sc1
	v_add_co_u32_e32 v10, vcc, s52, v8
	s_nop 1
	v_addc_co_u32_e32 v11, vcc, 0, v9, vcc
	s_waitcnt vmcnt(13)
	global_store_dwordx2 v[10:11], v[12:13], off offset:-4096 sc1
	s_waitcnt vmcnt(13)
	global_store_dwordx2 v[10:11], v[16:17], off sc1
	v_add_co_u32_e32 v10, vcc, s53, v8
	s_nop 1
	v_addc_co_u32_e32 v11, vcc, 0, v9, vcc
	s_waitcnt vmcnt(13)
	global_store_dwordx2 v[10:11], v[18:19], off offset:-4096 sc1
	s_waitcnt vmcnt(13)
	global_store_dwordx2 v[10:11], v[20:21], off sc1
	v_add_co_u32_e32 v10, vcc, s54, v8
	s_nop 1
	v_addc_co_u32_e32 v11, vcc, 0, v9, vcc
	s_waitcnt vmcnt(13)
	global_store_dwordx2 v[10:11], v[22:23], off offset:-4096 sc1
	s_waitcnt vmcnt(13)
	global_store_dwordx2 v[10:11], v[24:25], off sc1
	v_add_co_u32_e32 v10, vcc, s55, v8
	s_nop 1
	v_addc_co_u32_e32 v11, vcc, 0, v9, vcc
	s_waitcnt vmcnt(13)
	global_store_dwordx2 v[10:11], v[26:27], off offset:-4096 sc1
	s_waitcnt vmcnt(13)
	global_store_dwordx2 v[10:11], v[28:29], off sc1
	v_add_co_u32_e32 v10, vcc, s56, v8
	s_nop 1
	v_addc_co_u32_e32 v11, vcc, 0, v9, vcc
	s_waitcnt vmcnt(13)
	global_store_dwordx2 v[10:11], v[30:31], off offset:-4096 sc1
	s_waitcnt vmcnt(13)
	global_store_dwordx2 v[10:11], v[32:33], off sc1
	v_add_co_u32_e32 v10, vcc, s57, v8
	s_nop 1
	v_addc_co_u32_e32 v11, vcc, 0, v9, vcc
	s_waitcnt vmcnt(13)
	global_store_dwordx2 v[10:11], v[34:35], off sc1
	v_add_co_u32_e32 v10, vcc, 0xc000, v8
	s_nop 1
	v_addc_co_u32_e32 v11, vcc, 0, v9, vcc
	s_waitcnt vmcnt(13)
	global_store_dwordx2 v[10:11], v[36:37], off sc1
	v_add_co_u32_e32 v10, vcc, 0xd000, v8
	s_nop 1
	v_addc_co_u32_e32 v11, vcc, 0, v9, vcc
	v_add_co_u32_e32 v8, vcc, 0xe000, v8
	s_waitcnt vmcnt(13)
	global_store_dwordx2 v[10:11], v[6:7], off sc1
	v_addc_co_u32_e32 v9, vcc, 0, v9, vcc
	v_pk_add_f32 v[6:7], v[4:5], v[6:7]
	global_store_dwordx2 v[8:9], v[4:5], off sc1

; template <int WIN>
; DI void pool_elem(const Params& p, int row, int c) {
;     ...
;     if (t >= 2033) {
;       float2 o = {u0, u1};
;       *(float2*)(p.out + O_POOLP + ((size_t)b * 15 + (t - 2033)) * 1024 + c) = o;
;     }
.LBB0_1292:
	s_or_b64 exec, exec, s[6:7]
	v_cmp_lt_u32_e32 vcc, s60, v10
	s_and_saveexec_b64 s[6:7], vcc
	s_cbranch_execz .LBB0_1249
	v_ashrrev_i32_e32 v8, 20, v14
	v_mul_i32_i24_e32 v12, 15, v8
	v_ashrrev_i32_e32 v13, 31, v12
	v_add_u32_e32 v10, 0xfffff80f, v10
	v_mov_b32_e32 v11, v1
	v_lshl_add_u64 v[10:11], v[10:11], 0, v[12:13]
	v_lshlrev_b64 v[10:11], 12, v[10:11]
	v_lshl_add_u64 v[10:11], s[26:27], 0, v[10:11]
	v_lshlrev_b32_e32 v12, 2, v0
	v_mov_b32_e32 v13, v1
	v_lshl_add_u64 v[10:11], v[10:11], 0, v[12:13]
	global_store_dwordx2 v[10:11], v[4:5], off sc1
	s_branch .LBB0_1249

; #define MFMA32(a, b, c) __builtin_amdgcn_mfma_f32_32x32x16_bf16((a), (b), (c), 0, 0, 0)
; #define LOADK(c_) do { _Pragma("unroll") for (int i = 0; i < 4; ++i) { const int ch = tid + i * 256; \
;     sr[i] = *(const u32x4*)(Kg + (ch >> 2) * 1024 + (c_) * 32 + (ch & 3) * 8); } } while (0)
; #define STOREK() do { _Pragma("unroll") for (int i = 0; i < 4; ++i) { const int ch = tid + i * 256; \
;     *(u32x4*)(kbuf + (ch >> 2) * 40 + (ch & 3) * 8) = sr[i]; } } while (0)
; #define LOADV(v_, tid) do { _Pragma("unroll") for (int i = 0; i < 8; ++i) { const int idx = tid + i * 256, f = idx >> 6; \
;     sr[i] = VTg[(((v_) >> 1) * 4 + (f >> 3)) * 1024 + (((v_) & 1) * 8 + (f & 7)) * 64 + (idx & 63)]; } } while (0)
; #define STOREV(tid) do { _Pragma("unroll") for (int i = 0; i < 8; ++i) vbuf[tid + i * 256] = sr[i]; } while (0)
; DI void attn_prompt_block(const Params& p, int l, int b, int hh, int tt4, char* smem, bfr* Obuf) {
;   int tid = threadIdx.x;
;   asm volatile("" : "+v"(tid));
;   const int lane = tid & 63, wid = tid >> 6, r = lane & 31, hl = lane >> 5;
;   const int row0 = b * 2048 + (tt4 * 4 + wid) * 32;
;   const int qoff = (row0 + r) * 1024 + hh * 256 + hl * 8;
;   const bfr* Kg = p.KB + (size_t)l * 2097152 + (size_t)(b * 256) * 1024 + hh * 256;
;   const u32x4* VTg = (const u32x4*)(p.VT + (size_t)l * 2097152) + (size_t)((b * 4 + hh) * 8) * 16 * 64;
;   bfr* kbuf = (bfr*)smem;
;   u32x4* vbuf = (u32x4*)smem;
;   u32x4 sr[8];
;     ...
;   f32x16 st[8];
; #pragma unroll
;   for (int m = 0; m < 8; ++m)
; #pragma unroll
;     for (int q = 0; q < 16; ++q) st[m][q] = 0.f;
;   LOADK(0);
;   STOREK();
;   __syncthreads();
; #pragma unroll
;   for (int c = 0; c < 8; ++c) {
;     if (c < 7) LOADK(c + 1); else LOADV(0, tid);
;     bf16x8 qf[2];
; #pragma unroll
;     for (int ksl = 0; ksl < 2; ++ksl) qf[ksl] = *(const bf16x8*)(p.ACT2 + qoff + (c * 2 + ksl) * 16);
; #pragma unroll
;     for (int ksl = 0; ksl < 2; ++ksl)
; #pragma unroll
;       for (int m = 0; m < 8; ++m) {
;         bf16x8 kf = *(const bf16x8*)(kbuf + (m * 32 + r) * 40 + ksl * 16 + hl * 8);
;         st[m] = MFMA32(kf, qf[ksl], st[m]);
;       }
;     __syncthreads();
;     if (c < 7) STOREK(); else STOREV(tid);
;     __syncthreads();
.LBB0_1647:
	s_ashr_i32 s48, s16, 6
	s_and_b32 s45, s16, 15
	s_bfe_u32 s47, s16, 0x20004
	s_lshl_b32 s16, s48, 8
	s_ashr_i32 s17, s16, 31
	s_lshl_b64 s[18:19], s[16:17], 11
	s_lshl_b32 s16, s48, 5
	s_lshl_b32 s17, s47, 3
	s_or_b32 s16, s17, s16
	v_mov_b32_e32 v148, v196
	s_ashr_i32 s17, s16, 31
	s_lshl_b32 s43, s48, 11
	s_lshl_b32 s44, s47, 8
	s_lshl_b64 s[16:17], s[16:17], 14
	v_lshlrev_b32_e32 v0, 8, v148
	s_add_u32 s18, s25, s18
	v_and_b32_e32 v10, 0xfffffc00, v0
	s_addc_u32 s19, s26, s19
	s_lshl_b32 s47, s47, 9
	v_ashrrev_i32_e32 v11, 31, v10
	s_add_u32 s18, s18, s47
	v_lshlrev_b32_e32 v147, 4, v148
	v_lshlrev_b64 v[182:183], 1, v[10:11]
	v_add_u32_e32 v2, 0x10000, v10
	v_add_u32_e32 v12, 0x20000, v10
	v_add_u32_e32 v10, 0x30000, v10
	s_addc_u32 s19, s19, 0
	v_and_b32_e32 v160, 48, v147
	v_ashrrev_i32_e32 v3, 31, v2
	v_ashrrev_i32_e32 v13, 31, v12
	v_ashrrev_i32_e32 v11, 31, v10
	v_lshl_add_u64 v[8:9], s[18:19], 0, v[160:161]
	v_lshlrev_b64 v[194:195], 1, v[2:3]
	v_lshlrev_b64 v[220:221], 1, v[12:13]
	v_lshlrev_b64 v[222:223], 1, v[10:11]
	v_lshl_add_u64 v[0:1], v[8:9], 0, v[182:183]
	v_lshl_add_u64 v[4:5], v[8:9], 0, v[194:195]
	v_lshl_add_u64 v[12:13], v[8:9], 0, v[220:221]
	v_lshl_add_u64 v[14:15], v[8:9], 0, v[222:223]
	global_load_dwordx4 v[0:3], v[0:1], off
	s_nop 0
	global_load_dwordx4 v[4:7], v[4:5], off
	s_nop 0
	global_load_dwordx4 v[8:11], v[12:13], off
	s_nop 0
	global_load_dwordx4 v[12:15], v[14:15], off
	v_or_b32_e32 v16, s45, v181
	v_lshrrev_b32_e32 v17, 6, v148
	v_lshlrev_b32_e32 v146, 2, v16
	v_add_u32_e32 v17, v146, v17
	v_and_b32_e32 v18, 31, v148
	v_lshrrev_b32_e32 v16, 2, v148
	v_lshl_add_u32 v17, v17, 5, s43
	v_and_b32_e32 v19, 8, v16
	v_mad_u64_u32 v[130:131], s[48:49], v16, s39, v[160:161]
	v_or_b32_e32 v16, v17, v18
	v_lshlrev_b32_e32 v16, 10, v16
	v_or3_b32 v16, v16, s44, v19
	v_add_u32_e32 v151, 0x100, v148
	v_add_u32_e32 v150, 0x200, v148
	v_add_u32_e32 v149, 0x300, v148
	v_ashrrev_i32_e32 v17, 31, v16
	v_lshrrev_b32_e32 v20, 2, v151
	v_lshrrev_b32_e32 v21, 2, v150
	v_lshrrev_b32_e32 v22, 2, v149
	v_lshl_add_u64 v[128:129], v[16:17], 1, s[12:13]
	v_mad_u64_u32 v[132:133], s[48:49], v20, s39, v[160:161]
	v_mad_u64_u32 v[134:135], s[48:49], v21, s39, v[160:161]
	v_mad_u64_u32 v[136:137], s[48:49], v22, s39, v[160:161]
	s_add_u32 s16, s27, s16
	s_addc_u32 s17, s28, s17
	v_cmp_lt_i32_e32 vcc, v191, v192
	s_waitcnt vmcnt(3)
	ds_write_b128 v130, v[0:3]
	s_waitcnt vmcnt(2)
	ds_write_b128 v132, v[4:7]
	s_waitcnt vmcnt(1)
	ds_write_b128 v134, v[8:11]
	s_waitcnt vmcnt(0)
	ds_write_b128 v136, v[12:15]
	s_waitcnt lgkmcnt(0)
	s_barrier
	global_load_dwordx4 v[0:3], v[128:129], off
	global_load_dwordx4 v[152:155], v[128:129], off offset:32
	v_mul_u32_u24_e32 v4, 0x50, v18
	v_lshl_add_u32 v133, v19, 1, v4
	ds_read_b128 v[4:7], v133
	ds_read_b128 v[138:141], v133 offset:32
	s_waitcnt vmcnt(1) lgkmcnt(1)
	v_mfma_f32_32x32x16_bf16 v[112:127], v[4:7], v[0:3], 0
	ds_read_b128 v[4:7], v133 offset:2560
	ds_read_b128 v[142:145], v133 offset:2592
	s_waitcnt lgkmcnt(1)
	v_mfma_f32_32x32x16_bf16 v[96:111], v[4:7], v[0:3], 0
	ds_read_b128 v[4:7], v133 offset:5120
	ds_read_b128 v[156:159], v133 offset:5152
	s_waitcnt lgkmcnt(1)
	v_mfma_f32_32x32x16_bf16 v[80:95], v[4:7], v[0:3], 0
	ds_read_b128 v[4:7], v133 offset:7680
	ds_read_b128 v[200:203], v133 offset:7712
	s_waitcnt lgkmcnt(1)
	v_mfma_f32_32x32x16_bf16 v[64:79], v[4:7], v[0:3], 0
	ds_read_b128 v[4:7], v133 offset:10240
	ds_read_b128 v[204:207], v133 offset:10272
	s_waitcnt lgkmcnt(1)
	v_mfma_f32_32x32x16_bf16 v[48:63], v[4:7], v[0:3], 0
	ds_read_b128 v[4:7], v133 offset:12800
	ds_read_b128 v[208:211], v133 offset:12832
	s_waitcnt lgkmcnt(1)
	v_mfma_f32_32x32x16_bf16 v[32:47], v[4:7], v[0:3], 0
	ds_read_b128 v[4:7], v133 offset:15360
	ds_read_b128 v[212:215], v133 offset:15392
	s_waitcnt vmcnt(0)
	v_mfma_f32_32x32x16_bf16 v[112:127], v[138:141], v[152:155], v[112:127]
	v_lshl_add_u64 v[138:139], s[18:19], 0, v[182:183]
	v_lshl_add_u64 v[140:141], s[18:19], 0, v[194:195]
	v_mfma_f32_32x32x16_bf16 v[80:95], v[156:159], v[152:155], v[80:95]
	v_lshl_add_u64 v[156:157], s[18:19], 0, v[220:221]
	v_lshl_add_u64 v[158:159], s[18:19], 0, v[222:223]
	v_mfma_f32_32x32x16_bf16 v[96:111], v[142:145], v[152:155], v[96:111]
	v_lshl_add_u64 v[142:143], v[138:139], 0, v[160:161]
	v_lshl_add_u64 v[138:139], v[156:157], 0, v[160:161]
	v_lshl_add_u64 v[144:145], v[140:141], 0, v[160:161]
	v_lshl_add_u64 v[140:141], v[158:159], 0, v[160:161]
	s_waitcnt lgkmcnt(1)
	v_mfma_f32_32x32x16_bf16 v[16:31], v[4:7], v[0:3], 0
	ds_read_b128 v[4:7], v133 offset:17920
	ds_read_b128 v[216:219], v133 offset:17952
	v_mfma_f32_32x32x16_bf16 v[64:79], v[200:203], v[152:155], v[64:79]
	global_load_dwordx4 v[156:159], v[142:143], off offset:64
	global_load_dwordx4 v[200:203], v[144:145], off offset:64
	v_mfma_f32_32x32x16_bf16 v[48:63], v[204:207], v[152:155], v[48:63]
	global_load_dwordx4 v[204:207], v[138:139], off offset:64
	global_load_dwordx4 v[220:223], v[140:141], off offset:64
	s_waitcnt lgkmcnt(0)
	s_barrier
	s_waitcnt vmcnt(3)
	ds_write_b128 v130, v[156:159]
	s_waitcnt vmcnt(2)
	ds_write_b128 v132, v[200:203]
	s_waitcnt vmcnt(1)
	ds_write_b128 v134, v[204:207]
	s_waitcnt vmcnt(0)
	ds_write_b128 v136, v[220:223]
	s_waitcnt lgkmcnt(0)
	s_barrier
; #define MFMA32(a, b, c) __builtin_amdgcn_mfma_f32_32x32x16_bf16((a), (b), (c), 0, 0, 0)
; #define LOADK(c_) do { _Pragma("unroll") for (int i = 0; i < 4; ++i) { const int ch = tid + i * 256; \
;     sr[i] = *(const u32x4*)(Kg + (ch >> 2) * 1024 + (c_) * 32 + (ch & 3) * 8); } } while (0)
; #define STOREK() do { _Pragma("unroll") for (int i = 0; i < 4; ++i) { const int ch = tid + i * 256; \
;     *(u32x4*)(kbuf + (ch >> 2) * 40 + (ch & 3) * 8) = sr[i]; } } while (0)
; #define LOADV(v_, tid) do { _Pragma("unroll") for (int i = 0; i < 8; ++i) { const int idx = tid + i * 256, f = idx >> 6; \
;     sr[i] = VTg[(((v_) >> 1) * 4 + (f >> 3)) * 1024 + (((v_) & 1) * 8 + (f & 7)) * 64 + (idx & 63)]; } } while (0)
; #define STOREV(tid) do { _Pragma("unroll") for (int i = 0; i < 8; ++i) vbuf[tid + i * 256] = sr[i]; } while (0)
; DI void attn_prompt_block(const Params& p, int l, int b, int hh, int tt4, char* smem, bfr* Obuf) {
;     ...
; #pragma unroll
;   for (int c = 0; c < 8; ++c) {
;     if (c < 7) LOADK(c + 1); else LOADV(0, tid);
;     bf16x8 qf[2];
; #pragma unroll
;     for (int ksl = 0; ksl < 2; ++ksl) qf[ksl] = *(const bf16x8*)(p.ACT2 + qoff + (c * 2 + ksl) * 16);
; #pragma unroll
;     for (int ksl = 0; ksl < 2; ++ksl)
; #pragma unroll
;       for (int m = 0; m < 8; ++m) {
;         bf16x8 kf = *(const bf16x8*)(kbuf + (m * 32 + r) * 40 + ksl * 16 + hl * 8);
;         st[m] = MFMA32(kf, qf[ksl], st[m]);
;       }
;     __syncthreads();
;     if (c < 7) STOREK(); else STOREV(tid);
;     __syncthreads();
;   }
	global_load_dwordx4 v[156:159], v[128:129], off offset:64
	global_load_dwordx4 v[200:203], v[128:129], off offset:96
	v_mfma_f32_32x32x16_bf16 v[0:15], v[4:7], v[0:3], 0
	ds_read_b128 v[204:207], v133 offset:32
	v_mfma_f32_32x32x16_bf16 v[32:47], v[208:211], v[152:155], v[32:47]
	v_mfma_f32_32x32x16_bf16 v[16:31], v[212:215], v[152:155], v[16:31]
	v_mfma_f32_32x32x16_bf16 v[0:15], v[216:219], v[152:155], v[0:15]
	ds_read_b128 v[152:155], v133
	s_waitcnt vmcnt(1) lgkmcnt(0)
	v_mfma_f32_32x32x16_bf16 v[112:127], v[152:155], v[156:159], v[112:127]
	ds_read_b128 v[152:155], v133 offset:2560
	ds_read_b128 v[208:211], v133 offset:2592
	s_waitcnt lgkmcnt(1)
	v_mfma_f32_32x32x16_bf16 v[96:111], v[152:155], v[156:159], v[96:111]
	ds_read_b128 v[152:155], v133 offset:5120
	ds_read_b128 v[212:215], v133 offset:5152
	s_waitcnt lgkmcnt(1)
	v_mfma_f32_32x32x16_bf16 v[80:95], v[152:155], v[156:159], v[80:95]
	ds_read_b128 v[152:155], v133 offset:7680
	ds_read_b128 v[216:219], v133 offset:7712
	s_waitcnt lgkmcnt(1)
	v_mfma_f32_32x32x16_bf16 v[64:79], v[152:155], v[156:159], v[64:79]
	ds_read_b128 v[152:155], v133 offset:10240
	ds_read_b128 v[220:223], v133 offset:10272
	s_waitcnt lgkmcnt(1)
	v_mfma_f32_32x32x16_bf16 v[48:63], v[152:155], v[156:159], v[48:63]
	ds_read_b128 v[152:155], v133 offset:12800
	ds_read_b128 v[224:227], v133 offset:12832
	s_waitcnt lgkmcnt(1)
	v_mfma_f32_32x32x16_bf16 v[32:47], v[152:155], v[156:159], v[32:47]
	ds_read_b128 v[152:155], v133 offset:15360
	ds_read_b128 v[228:231], v133 offset:15392
	s_waitcnt lgkmcnt(1)
	v_mfma_f32_32x32x16_bf16 v[16:31], v[152:155], v[156:159], v[16:31]
	ds_read_b128 v[152:155], v133 offset:17920
	ds_read_b128 v[232:235], v133 offset:17952
	s_waitcnt lgkmcnt(1)
	v_mfma_f32_32x32x16_bf16 v[0:15], v[152:155], v[156:159], v[0:15]
	global_load_dwordx4 v[152:155], v[142:143], off offset:128
	global_load_dwordx4 v[156:159], v[144:145], off offset:128
	s_waitcnt vmcnt(2)
	v_mfma_f32_32x32x16_bf16 v[112:127], v[204:207], v[200:203], v[112:127]
	v_mfma_f32_32x32x16_bf16 v[96:111], v[208:211], v[200:203], v[96:111]
	global_load_dwordx4 v[204:207], v[138:139], off offset:128
	global_load_dwordx4 v[208:211], v[140:141], off offset:128
	s_waitcnt lgkmcnt(0)
	s_barrier
	s_waitcnt vmcnt(3)
	ds_write_b128 v130, v[152:155]
	s_waitcnt vmcnt(2)
	ds_write_b128 v132, v[156:159]
	s_waitcnt vmcnt(1)
	ds_write_b128 v134, v[204:207]
	s_waitcnt vmcnt(0)
	ds_write_b128 v136, v[208:211]
	s_waitcnt lgkmcnt(0)
	s_barrier
	global_load_dwordx4 v[152:155], v[128:129], off offset:128
	v_mfma_f32_32x32x16_bf16 v[80:95], v[212:215], v[200:203], v[80:95]
	ds_read_b128 v[156:159], v133
	ds_read_b128 v[204:207], v133 offset:32
	v_mfma_f32_32x32x16_bf16 v[64:79], v[216:219], v[200:203], v[64:79]
	v_mfma_f32_32x32x16_bf16 v[48:63], v[220:223], v[200:203], v[48:63]
	v_mfma_f32_32x32x16_bf16 v[32:47], v[224:227], v[200:203], v[32:47]
	v_mfma_f32_32x32x16_bf16 v[16:31], v[228:231], v[200:203], v[16:31]
	v_mfma_f32_32x32x16_bf16 v[0:15], v[232:235], v[200:203], v[0:15]
	global_load_dwordx4 v[200:203], v[128:129], off offset:160
	s_waitcnt vmcnt(1) lgkmcnt(1)
	v_mfma_f32_32x32x16_bf16 v[112:127], v[156:159], v[152:155], v[112:127]
	ds_read_b128 v[156:159], v133 offset:2560
	ds_read_b128 v[208:211], v133 offset:2592
	s_waitcnt lgkmcnt(1)
	v_mfma_f32_32x32x16_bf16 v[96:111], v[156:159], v[152:155], v[96:111]
	ds_read_b128 v[156:159], v133 offset:5120
	ds_read_b128 v[212:215], v133 offset:5152
	s_waitcnt lgkmcnt(1)
	v_mfma_f32_32x32x16_bf16 v[80:95], v[156:159], v[152:155], v[80:95]
	ds_read_b128 v[156:159], v133 offset:7680
	ds_read_b128 v[216:219], v133 offset:7712
	s_waitcnt lgkmcnt(1)
	v_mfma_f32_32x32x16_bf16 v[64:79], v[156:159], v[152:155], v[64:79]
	ds_read_b128 v[156:159], v133 offset:10240
	ds_read_b128 v[220:223], v133 offset:10272
	s_waitcnt lgkmcnt(1)
	v_mfma_f32_32x32x16_bf16 v[48:63], v[156:159], v[152:155], v[48:63]
	ds_read_b128 v[156:159], v133 offset:12800
	ds_read_b128 v[224:227], v133 offset:12832
	s_waitcnt lgkmcnt(1)
	v_mfma_f32_32x32x16_bf16 v[32:47], v[156:159], v[152:155], v[32:47]
	ds_read_b128 v[156:159], v133 offset:15360
	ds_read_b128 v[228:231], v133 offset:15392
	s_waitcnt lgkmcnt(1)
	v_mfma_f32_32x32x16_bf16 v[16:31], v[156:159], v[152:155], v[16:31]
	ds_read_b128 v[156:159], v133 offset:17920
	ds_read_b128 v[232:235], v133 offset:17952
	s_waitcnt lgkmcnt(1)
	v_mfma_f32_32x32x16_bf16 v[0:15], v[156:159], v[152:155], v[0:15]
	global_load_dwordx4 v[152:155], v[142:143], off offset:192
	global_load_dwordx4 v[156:159], v[144:145], off offset:192
	s_waitcnt vmcnt(2)
	v_mfma_f32_32x32x16_bf16 v[112:127], v[204:207], v[200:203], v[112:127]
	v_mfma_f32_32x32x16_bf16 v[96:111], v[208:211], v[200:203], v[96:111]
	global_load_dwordx4 v[204:207], v[138:139], off offset:192
	global_load_dwordx4 v[208:211], v[140:141], off offset:192
	s_waitcnt lgkmcnt(0)
	s_barrier
	s_waitcnt vmcnt(3)
	ds_write_b128 v130, v[152:155]
	s_waitcnt vmcnt(2)
	ds_write_b128 v132, v[156:159]
	s_waitcnt vmcnt(1)
	ds_write_b128 v134, v[204:207]
	s_waitcnt vmcnt(0)
	ds_write_b128 v136, v[208:211]
	s_waitcnt lgkmcnt(0)
	s_barrier
; #define MFMA32(a, b, c) __builtin_amdgcn_mfma_f32_32x32x16_bf16((a), (b), (c), 0, 0, 0)
; #define LOADK(c_) do { _Pragma("unroll") for (int i = 0; i < 4; ++i) { const int ch = tid + i * 256; \
;     sr[i] = *(const u32x4*)(Kg + (ch >> 2) * 1024 + (c_) * 32 + (ch & 3) * 8); } } while (0)
; #define STOREK() do { _Pragma("unroll") for (int i = 0; i < 4; ++i) { const int ch = tid + i * 256; \
;     *(u32x4*)(kbuf + (ch >> 2) * 40 + (ch & 3) * 8) = sr[i]; } } while (0)
; #define LOADV(v_, tid) do { _Pragma("unroll") for (int i = 0; i < 8; ++i) { const int idx = tid + i * 256, f = idx >> 6; \
;     sr[i] = VTg[(((v_) >> 1) * 4 + (f >> 3)) * 1024 + (((v_) & 1) * 8 + (f & 7)) * 64 + (idx & 63)]; } } while (0)
; #define STOREV(tid) do { _Pragma("unroll") for (int i = 0; i < 8; ++i) vbuf[tid + i * 256] = sr[i]; } while (0)
; DI void attn_prompt_block(const Params& p, int l, int b, int hh, int tt4, char* smem, bfr* Obuf) {
;     ...
; #pragma unroll
;   for (int c = 0; c < 8; ++c) {
;     if (c < 7) LOADK(c + 1); else LOADV(0, tid);
;     bf16x8 qf[2];
; #pragma unroll
;     for (int ksl = 0; ksl < 2; ++ksl) qf[ksl] = *(const bf16x8*)(p.ACT2 + qoff + (c * 2 + ksl) * 16);
; #pragma unroll
;     for (int ksl = 0; ksl < 2; ++ksl)
; #pragma unroll
;       for (int m = 0; m < 8; ++m) {
;         bf16x8 kf = *(const bf16x8*)(kbuf + (m * 32 + r) * 40 + ksl * 16 + hl * 8);
;         st[m] = MFMA32(kf, qf[ksl], st[m]);
;       }
;     __syncthreads();
;     if (c < 7) STOREK(); else STOREV(tid);
;     __syncthreads();
;   }
	global_load_dwordx4 v[152:155], v[128:129], off offset:192
	v_mfma_f32_32x32x16_bf16 v[80:95], v[212:215], v[200:203], v[80:95]
	ds_read_b128 v[156:159], v133
	ds_read_b128 v[204:207], v133 offset:32
	v_mfma_f32_32x32x16_bf16 v[64:79], v[216:219], v[200:203], v[64:79]
	v_mfma_f32_32x32x16_bf16 v[48:63], v[220:223], v[200:203], v[48:63]
	v_mfma_f32_32x32x16_bf16 v[32:47], v[224:227], v[200:203], v[32:47]
	v_mfma_f32_32x32x16_bf16 v[16:31], v[228:231], v[200:203], v[16:31]
	v_mfma_f32_32x32x16_bf16 v[0:15], v[232:235], v[200:203], v[0:15]
	global_load_dwordx4 v[200:203], v[128:129], off offset:224
	s_waitcnt vmcnt(1) lgkmcnt(1)
	v_mfma_f32_32x32x16_bf16 v[112:127], v[156:159], v[152:155], v[112:127]
	ds_read_b128 v[156:159], v133 offset:2560
	ds_read_b128 v[208:211], v133 offset:2592
	s_waitcnt lgkmcnt(1)
	v_mfma_f32_32x32x16_bf16 v[96:111], v[156:159], v[152:155], v[96:111]
	ds_read_b128 v[156:159], v133 offset:5120
	ds_read_b128 v[212:215], v133 offset:5152
	s_waitcnt lgkmcnt(1)
	v_mfma_f32_32x32x16_bf16 v[80:95], v[156:159], v[152:155], v[80:95]
	ds_read_b128 v[156:159], v133 offset:7680
	ds_read_b128 v[216:219], v133 offset:7712
	s_waitcnt lgkmcnt(1)
	v_mfma_f32_32x32x16_bf16 v[64:79], v[156:159], v[152:155], v[64:79]
	ds_read_b128 v[156:159], v133 offset:10240
	ds_read_b128 v[220:223], v133 offset:10272
	s_waitcnt lgkmcnt(1)
	v_mfma_f32_32x32x16_bf16 v[48:63], v[156:159], v[152:155], v[48:63]
	ds_read_b128 v[156:159], v133 offset:12800
	ds_read_b128 v[224:227], v133 offset:12832
	s_waitcnt lgkmcnt(1)
	v_mfma_f32_32x32x16_bf16 v[32:47], v[156:159], v[152:155], v[32:47]
	ds_read_b128 v[156:159], v133 offset:15360
	ds_read_b128 v[228:231], v133 offset:15392
	s_waitcnt lgkmcnt(1)
	v_mfma_f32_32x32x16_bf16 v[16:31], v[156:159], v[152:155], v[16:31]
	ds_read_b128 v[156:159], v133 offset:17920
	ds_read_b128 v[232:235], v133 offset:17952
	s_waitcnt lgkmcnt(1)
	v_mfma_f32_32x32x16_bf16 v[0:15], v[156:159], v[152:155], v[0:15]
	global_load_dwordx4 v[152:155], v[142:143], off offset:256
	global_load_dwordx4 v[156:159], v[144:145], off offset:256
	s_waitcnt vmcnt(2)
	v_mfma_f32_32x32x16_bf16 v[112:127], v[204:207], v[200:203], v[112:127]
	v_mfma_f32_32x32x16_bf16 v[96:111], v[208:211], v[200:203], v[96:111]
	global_load_dwordx4 v[204:207], v[138:139], off offset:256
	global_load_dwordx4 v[208:211], v[140:141], off offset:256
	s_waitcnt lgkmcnt(0)
	s_barrier
	s_waitcnt vmcnt(3)
	ds_write_b128 v130, v[152:155]
	s_waitcnt vmcnt(2)
	ds_write_b128 v132, v[156:159]
	s_waitcnt vmcnt(1)
	ds_write_b128 v134, v[204:207]
	s_waitcnt vmcnt(0)
	ds_write_b128 v136, v[208:211]
	s_waitcnt lgkmcnt(0)
	s_barrier
	global_load_dwordx4 v[152:155], v[128:129], off offset:256
	v_mfma_f32_32x32x16_bf16 v[80:95], v[212:215], v[200:203], v[80:95]
	ds_read_b128 v[156:159], v133
	ds_read_b128 v[204:207], v133 offset:32
	v_mfma_f32_32x32x16_bf16 v[64:79], v[216:219], v[200:203], v[64:79]
	v_mfma_f32_32x32x16_bf16 v[48:63], v[220:223], v[200:203], v[48:63]
	v_mfma_f32_32x32x16_bf16 v[32:47], v[224:227], v[200:203], v[32:47]
	v_mfma_f32_32x32x16_bf16 v[16:31], v[228:231], v[200:203], v[16:31]
	v_mfma_f32_32x32x16_bf16 v[0:15], v[232:235], v[200:203], v[0:15]
	global_load_dwordx4 v[200:203], v[128:129], off offset:288
	s_waitcnt vmcnt(1) lgkmcnt(1)
	v_mfma_f32_32x32x16_bf16 v[112:127], v[156:159], v[152:155], v[112:127]
	ds_read_b128 v[156:159], v133 offset:2560
	ds_read_b128 v[208:211], v133 offset:2592
	s_waitcnt lgkmcnt(1)
	v_mfma_f32_32x32x16_bf16 v[96:111], v[156:159], v[152:155], v[96:111]
	ds_read_b128 v[156:159], v133 offset:5120
	ds_read_b128 v[212:215], v133 offset:5152
	s_waitcnt lgkmcnt(1)
	v_mfma_f32_32x32x16_bf16 v[80:95], v[156:159], v[152:155], v[80:95]
	ds_read_b128 v[156:159], v133 offset:7680
	ds_read_b128 v[216:219], v133 offset:7712
	s_waitcnt lgkmcnt(1)
	v_mfma_f32_32x32x16_bf16 v[64:79], v[156:159], v[152:155], v[64:79]
	ds_read_b128 v[156:159], v133 offset:10240
	ds_read_b128 v[220:223], v133 offset:10272
	s_waitcnt lgkmcnt(1)
	v_mfma_f32_32x32x16_bf16 v[48:63], v[156:159], v[152:155], v[48:63]
	ds_read_b128 v[156:159], v133 offset:12800
	ds_read_b128 v[224:227], v133 offset:12832
	s_waitcnt lgkmcnt(1)
	v_mfma_f32_32x32x16_bf16 v[32:47], v[156:159], v[152:155], v[32:47]
	ds_read_b128 v[156:159], v133 offset:15360
	ds_read_b128 v[228:231], v133 offset:15392
	s_waitcnt lgkmcnt(1)
	v_mfma_f32_32x32x16_bf16 v[16:31], v[156:159], v[152:155], v[16:31]
	ds_read_b128 v[156:159], v133 offset:17920
	ds_read_b128 v[232:235], v133 offset:17952
	s_waitcnt lgkmcnt(1)
	v_mfma_f32_32x32x16_bf16 v[0:15], v[156:159], v[152:155], v[0:15]
	global_load_dwordx4 v[152:155], v[142:143], off offset:320
	global_load_dwordx4 v[156:159], v[144:145], off offset:320
	s_waitcnt vmcnt(2)
	v_mfma_f32_32x32x16_bf16 v[112:127], v[204:207], v[200:203], v[112:127]
	v_mfma_f32_32x32x16_bf16 v[96:111], v[208:211], v[200:203], v[96:111]
	global_load_dwordx4 v[204:207], v[138:139], off offset:320
	global_load_dwordx4 v[208:211], v[140:141], off offset:320
	s_waitcnt lgkmcnt(0)
	s_barrier
	s_waitcnt vmcnt(3)
	ds_write_b128 v130, v[152:155]
	s_waitcnt vmcnt(2)
	ds_write_b128 v132, v[156:159]
	s_waitcnt vmcnt(1)
	ds_write_b128 v134, v[204:207]
	s_waitcnt vmcnt(0)
	ds_write_b128 v136, v[208:211]
	s_waitcnt lgkmcnt(0)
	s_barrier
; #define MFMA32(a, b, c) __builtin_amdgcn_mfma_f32_32x32x16_bf16((a), (b), (c), 0, 0, 0)
; #define LOADK(c_) do { _Pragma("unroll") for (int i = 0; i < 4; ++i) { const int ch = tid + i * 256; \
;     sr[i] = *(const u32x4*)(Kg + (ch >> 2) * 1024 + (c_) * 32 + (ch & 3) * 8); } } while (0)
; #define STOREK() do { _Pragma("unroll") for (int i = 0; i < 4; ++i) { const int ch = tid + i * 256; \
;     *(u32x4*)(kbuf + (ch >> 2) * 40 + (ch & 3) * 8) = sr[i]; } } while (0)
; #define LOADV(v_, tid) do { _Pragma("unroll") for (int i = 0; i < 8; ++i) { const int idx = tid + i * 256, f = idx >> 6; \
;     sr[i] = VTg[(((v_) >> 1) * 4 + (f >> 3)) * 1024 + (((v_) & 1) * 8 + (f & 7)) * 64 + (idx & 63)]; } } while (0)
; #define STOREV(tid) do { _Pragma("unroll") for (int i = 0; i < 8; ++i) vbuf[tid + i * 256] = sr[i]; } while (0)
; DI void attn_prompt_block(const Params& p, int l, int b, int hh, int tt4, char* smem, bfr* Obuf) {
;     ...
; #pragma unroll
;   for (int c = 0; c < 8; ++c) {
;     if (c < 7) LOADK(c + 1); else LOADV(0, tid);
;     bf16x8 qf[2];
; #pragma unroll
;     for (int ksl = 0; ksl < 2; ++ksl) qf[ksl] = *(const bf16x8*)(p.ACT2 + qoff + (c * 2 + ksl) * 16);
; #pragma unroll
;     for (int ksl = 0; ksl < 2; ++ksl)
; #pragma unroll
;       for (int m = 0; m < 8; ++m) {
;         bf16x8 kf = *(const bf16x8*)(kbuf + (m * 32 + r) * 40 + ksl * 16 + hl * 8);
;         st[m] = MFMA32(kf, qf[ksl], st[m]);
;       }
;     __syncthreads();
;     if (c < 7) STOREK(); else STOREV(tid);
;     __syncthreads();
;   }
	global_load_dwordx4 v[152:155], v[128:129], off offset:320
	v_mfma_f32_32x32x16_bf16 v[80:95], v[212:215], v[200:203], v[80:95]
	ds_read_b128 v[156:159], v133
	ds_read_b128 v[204:207], v133 offset:32
	v_mfma_f32_32x32x16_bf16 v[64:79], v[216:219], v[200:203], v[64:79]
	v_mfma_f32_32x32x16_bf16 v[48:63], v[220:223], v[200:203], v[48:63]
	v_mfma_f32_32x32x16_bf16 v[32:47], v[224:227], v[200:203], v[32:47]
	v_mfma_f32_32x32x16_bf16 v[16:31], v[228:231], v[200:203], v[16:31]
	v_mfma_f32_32x32x16_bf16 v[0:15], v[232:235], v[200:203], v[0:15]
	global_load_dwordx4 v[200:203], v[128:129], off offset:352
	s_waitcnt vmcnt(1) lgkmcnt(1)
	v_mfma_f32_32x32x16_bf16 v[112:127], v[156:159], v[152:155], v[112:127]
	ds_read_b128 v[156:159], v133 offset:2560
	ds_read_b128 v[208:211], v133 offset:2592
	s_waitcnt lgkmcnt(1)
	v_mfma_f32_32x32x16_bf16 v[96:111], v[156:159], v[152:155], v[96:111]
	ds_read_b128 v[156:159], v133 offset:5120
	ds_read_b128 v[212:215], v133 offset:5152
	s_waitcnt lgkmcnt(1)
	v_mfma_f32_32x32x16_bf16 v[80:95], v[156:159], v[152:155], v[80:95]
	ds_read_b128 v[156:159], v133 offset:7680
	ds_read_b128 v[216:219], v133 offset:7712
	s_waitcnt lgkmcnt(1)
	v_mfma_f32_32x32x16_bf16 v[64:79], v[156:159], v[152:155], v[64:79]
	ds_read_b128 v[156:159], v133 offset:10240
	ds_read_b128 v[220:223], v133 offset:10272
	s_waitcnt lgkmcnt(1)
	v_mfma_f32_32x32x16_bf16 v[48:63], v[156:159], v[152:155], v[48:63]
	ds_read_b128 v[156:159], v133 offset:12800
	ds_read_b128 v[224:227], v133 offset:12832
	s_waitcnt lgkmcnt(1)
	v_mfma_f32_32x32x16_bf16 v[32:47], v[156:159], v[152:155], v[32:47]
	ds_read_b128 v[156:159], v133 offset:15360
	ds_read_b128 v[228:231], v133 offset:15392
	s_waitcnt lgkmcnt(1)
	v_mfma_f32_32x32x16_bf16 v[16:31], v[156:159], v[152:155], v[16:31]
	ds_read_b128 v[156:159], v133 offset:17920
	ds_read_b128 v[232:235], v133 offset:17952
	s_waitcnt lgkmcnt(1)
	v_mfma_f32_32x32x16_bf16 v[0:15], v[156:159], v[152:155], v[0:15]
	global_load_dwordx4 v[152:155], v[142:143], off offset:384
	global_load_dwordx4 v[156:159], v[144:145], off offset:384
	s_waitcnt vmcnt(2)
	v_mfma_f32_32x32x16_bf16 v[112:127], v[204:207], v[200:203], v[112:127]
	v_mfma_f32_32x32x16_bf16 v[96:111], v[208:211], v[200:203], v[96:111]
	global_load_dwordx4 v[204:207], v[138:139], off offset:384
	global_load_dwordx4 v[208:211], v[140:141], off offset:384
	s_waitcnt lgkmcnt(0)
	s_barrier
	s_waitcnt vmcnt(3)
	ds_write_b128 v130, v[152:155]
	s_waitcnt vmcnt(2)
	ds_write_b128 v132, v[156:159]
	s_waitcnt vmcnt(1)
	ds_write_b128 v134, v[204:207]
	s_waitcnt vmcnt(0)
	ds_write_b128 v136, v[208:211]
	s_waitcnt lgkmcnt(0)
	s_barrier
	global_load_dwordx4 v[152:155], v[128:129], off offset:384
	ds_read_b128 v[156:159], v133
	ds_read_b128 v[204:207], v133 offset:32
	v_mfma_f32_32x32x16_bf16 v[80:95], v[212:215], v[200:203], v[80:95]
	v_mfma_f32_32x32x16_bf16 v[64:79], v[216:219], v[200:203], v[64:79]
	v_mfma_f32_32x32x16_bf16 v[48:63], v[220:223], v[200:203], v[48:63]
	v_mfma_f32_32x32x16_bf16 v[32:47], v[224:227], v[200:203], v[32:47]
	v_mfma_f32_32x32x16_bf16 v[16:31], v[228:231], v[200:203], v[16:31]
	v_mfma_f32_32x32x16_bf16 v[0:15], v[232:235], v[200:203], v[0:15]
	global_load_dwordx4 v[200:203], v[128:129], off offset:416
	s_waitcnt vmcnt(1) lgkmcnt(1)
	v_mfma_f32_32x32x16_bf16 v[112:127], v[156:159], v[152:155], v[112:127]
	ds_read_b128 v[156:159], v133 offset:2560
	ds_read_b128 v[208:211], v133 offset:2592
	s_waitcnt lgkmcnt(1)
	v_mfma_f32_32x32x16_bf16 v[96:111], v[156:159], v[152:155], v[96:111]
	ds_read_b128 v[156:159], v133 offset:5120
	ds_read_b128 v[212:215], v133 offset:5152
	s_waitcnt lgkmcnt(1)
	v_mfma_f32_32x32x16_bf16 v[80:95], v[156:159], v[152:155], v[80:95]
	ds_read_b128 v[156:159], v133 offset:7680
	ds_read_b128 v[216:219], v133 offset:7712
	s_waitcnt lgkmcnt(1)
	v_mfma_f32_32x32x16_bf16 v[64:79], v[156:159], v[152:155], v[64:79]
	ds_read_b128 v[156:159], v133 offset:10240
	ds_read_b128 v[220:223], v133 offset:10272
	s_waitcnt lgkmcnt(1)
	v_mfma_f32_32x32x16_bf16 v[48:63], v[156:159], v[152:155], v[48:63]
	ds_read_b128 v[156:159], v133 offset:12800
	ds_read_b128 v[224:227], v133 offset:12832
	s_waitcnt lgkmcnt(1)
	v_mfma_f32_32x32x16_bf16 v[32:47], v[156:159], v[152:155], v[32:47]
	ds_read_b128 v[156:159], v133 offset:15360
	ds_read_b128 v[228:231], v133 offset:15392
	s_waitcnt lgkmcnt(1)
	v_mfma_f32_32x32x16_bf16 v[16:31], v[156:159], v[152:155], v[16:31]
	ds_read_b128 v[156:159], v133 offset:17920
	ds_read_b128 v[232:235], v133 offset:17952
	s_waitcnt lgkmcnt(1)
	v_mfma_f32_32x32x16_bf16 v[0:15], v[156:159], v[152:155], v[0:15]
	global_load_dwordx4 v[152:155], v[142:143], off offset:448
	s_nop 0
	global_load_dwordx4 v[142:145], v[144:145], off offset:448
	s_nop 0
	global_load_dwordx4 v[156:159], v[138:139], off offset:448
	s_nop 0
	global_load_dwordx4 v[138:141], v[140:141], off offset:448
	s_waitcnt lgkmcnt(0)
	s_barrier
	s_waitcnt vmcnt(3)
	ds_write_b128 v130, v[152:155]
	s_waitcnt vmcnt(2)
	ds_write_b128 v132, v[142:145]
	s_waitcnt vmcnt(1)
	ds_write_b128 v134, v[156:159]
	s_waitcnt vmcnt(0)
	ds_write_b128 v136, v[138:141]
	s_waitcnt lgkmcnt(0)
	s_barrier
; #define MFMA32(a, b, c) __builtin_amdgcn_mfma_f32_32x32x16_bf16((a), (b), (c), 0, 0, 0)
; #define LOADK(c_) do { _Pragma("unroll") for (int i = 0; i < 4; ++i) { const int ch = tid + i * 256; \
;     sr[i] = *(const u32x4*)(Kg + (ch >> 2) * 1024 + (c_) * 32 + (ch & 3) * 8); } } while (0)
; #define STOREK() do { _Pragma("unroll") for (int i = 0; i < 4; ++i) { const int ch = tid + i * 256; \
;     *(u32x4*)(kbuf + (ch >> 2) * 40 + (ch & 3) * 8) = sr[i]; } } while (0)
; #define LOADV(v_, tid) do { _Pragma("unroll") for (int i = 0; i < 8; ++i) { const int idx = tid + i * 256, f = idx >> 6; \
;     sr[i] = VTg[(((v_) >> 1) * 4 + (f >> 3)) * 1024 + (((v_) & 1) * 8 + (f & 7)) * 64 + (idx & 63)]; } } while (0)
; #define STOREV(tid) do { _Pragma("unroll") for (int i = 0; i < 8; ++i) vbuf[tid + i * 256] = sr[i]; } while (0)
; DI void attn_prompt_block(const Params& p, int l, int b, int hh, int tt4, char* smem, bfr* Obuf) {
;     ...
;   for (int c = 0; c < 8; ++c) {
;     if (c < 7) LOADK(c + 1); else LOADV(0, tid);
;     bf16x8 qf[2];
; #pragma unroll
;     for (int ksl = 0; ksl < 2; ++ksl) qf[ksl] = *(const bf16x8*)(p.ACT2 + qoff + (c * 2 + ksl) * 16);
; #pragma unroll
;     for (int ksl = 0; ksl < 2; ++ksl)
; #pragma unroll
;       for (int m = 0; m < 8; ++m) {
;         bf16x8 kf = *(const bf16x8*)(kbuf + (m * 32 + r) * 40 + ksl * 16 + hl * 8);
;         st[m] = MFMA32(kf, qf[ksl], st[m]);
;       }
;     __syncthreads();
;     if (c < 7) STOREK(); else STOREV(tid);
;     __syncthreads();
;   }
;   float mx = -3.0e38f;
; #pragma unroll
;   for (int m = 0; m < 8; ++m)
; #pragma unroll
;     for (int q = 0; q < 16; ++q) mx = fmaxf(mx, st[m][q]);
	global_load_dwordx4 v[134:137], v[128:129], off offset:448
	v_lshlrev_b32_e32 v138, 1, v151
	v_and_b32_e32 v132, 63, v148
	v_lshlrev_b32_e32 v130, 1, v148
	v_and_b32_e32 v152, 0x1ff, v148
	v_and_b32_e32 v138, 0xfffffc00, v138
	v_and_b32_e32 v139, 0x1c0, v151
	v_and_or_b32 v158, v130, s38, v152
	v_or3_b32 v138, v139, v138, v132
	v_ashrrev_i32_e32 v159, 31, v158
	v_ashrrev_i32_e32 v139, 31, v138
	v_lshl_add_u64 v[130:131], v[158:159], 4, s[16:17]
	v_lshl_add_u64 v[142:143], v[138:139], 4, s[16:17]
	global_load_dwordx4 v[138:141], v[130:131], off
	s_nop 0
	global_load_dwordx4 v[142:145], v[142:143], off
	v_mfma_f32_32x32x16_bf16 v[112:127], v[204:207], v[200:203], v[112:127]
	global_load_dwordx4 v[154:157], v[128:129], off offset:480
	v_lshlrev_b32_e32 v130, 1, v150
	v_and_or_b32 v130, v130, s38, v152
	v_ashrrev_i32_e32 v131, 31, v130
	v_lshl_add_u64 v[130:131], v[130:131], 4, s[16:17]
	global_load_dwordx4 v[150:153], v[130:131], off
	v_mfma_f32_32x32x16_bf16 v[96:111], v[208:211], v[200:203], v[96:111]
	v_mfma_f32_32x32x16_bf16 v[80:95], v[212:215], v[200:203], v[80:95]
	v_mfma_f32_32x32x16_bf16 v[64:79], v[216:219], v[200:203], v[64:79]
	v_mfma_f32_32x32x16_bf16 v[48:63], v[220:223], v[200:203], v[48:63]
	v_mfma_f32_32x32x16_bf16 v[32:47], v[224:227], v[200:203], v[32:47]
	v_mfma_f32_32x32x16_bf16 v[16:31], v[228:231], v[200:203], v[16:31]
	v_mfma_f32_32x32x16_bf16 v[0:15], v[232:235], v[200:203], v[0:15]
	ds_read_b128 v[128:131], v133
	ds_read_b128 v[200:203], v133 offset:32
	ds_read_b128 v[204:207], v133 offset:2560
	s_waitcnt vmcnt(4) lgkmcnt(2)
	v_mfma_f32_32x32x16_bf16 v[112:127], v[128:131], v[134:137], v[112:127]
	v_lshlrev_b32_e32 v128, 1, v149
	v_and_b32_e32 v128, 0xfffffc00, v128
	v_and_b32_e32 v129, 0x1c0, v149
	v_or3_b32 v182, v129, v128, v132
	ds_read_b128 v[128:131], v133 offset:5120
	ds_read_b128 v[208:211], v133 offset:2592
	v_ashrrev_i32_e32 v183, 31, v182
	v_lshl_add_u64 v[182:183], v[182:183], 4, s[16:17]
	s_waitcnt lgkmcnt(1)
	v_mfma_f32_32x32x16_bf16 v[80:95], v[128:131], v[134:137], v[80:95]
	v_add_u32_e32 v128, 0x500, v148
	v_lshlrev_b32_e32 v129, 1, v128
	v_and_b32_e32 v129, 0xfffffc00, v129
	v_and_b32_e32 v128, 0x1c0, v128
	v_or3_b32 v194, v128, v129, v132
	v_ashrrev_i32_e32 v195, 31, v194
	v_lshl_add_u64 v[194:195], v[194:195], 4, s[16:17]
	v_mfma_f32_32x32x16_bf16 v[96:111], v[204:207], v[134:137], v[96:111]
	global_load_dwordx4 v[204:207], v[182:183], off
	ds_read_b128 v[212:215], v133 offset:7680
	ds_read_b128 v[216:219], v133 offset:5152
	ds_read_b128 v[128:131], v133 offset:10240
	ds_read_b128 v[220:223], v133 offset:7712
	v_add_u32_e32 v182, 0x800, v158
	v_ashrrev_i32_e32 v183, 31, v182
	v_lshl_add_u64 v[182:183], v[182:183], 4, s[16:17]
	v_add_u32_e32 v158, 0xc00, v158
	s_waitcnt vmcnt(2)
	v_mfma_f32_32x32x16_bf16 v[112:127], v[200:203], v[154:157], v[112:127]
	v_ashrrev_i32_e32 v159, 31, v158
	s_waitcnt lgkmcnt(1)
	v_mfma_f32_32x32x16_bf16 v[48:63], v[128:131], v[134:137], v[48:63]
	v_add_u32_e32 v130, 0x700, v148
	v_lshlrev_b32_e32 v131, 1, v130
	v_and_b32_e32 v131, 0xfffffc00, v131
	v_and_b32_e32 v130, 0x1c0, v130
	v_or3_b32 v130, v130, v131, v132
	s_nop 3
	v_max3_f32 v132, v112, s41, v113
	v_max3_f32 v132, v132, v114, v115
	v_mfma_f32_32x32x16_bf16 v[96:111], v[208:211], v[154:157], v[96:111]
	v_max3_f32 v132, v132, v116, v117
	v_max3_f32 v132, v132, v118, v119
	v_max3_f32 v132, v132, v120, v121
	v_max3_f32 v132, v132, v122, v123
	v_max3_f32 v132, v132, v124, v125
	v_max3_f32 v132, v132, v126, v127
	v_ashrrev_i32_e32 v131, 31, v130
	v_mfma_f32_32x32x16_bf16 v[64:79], v[212:215], v[134:137], v[64:79]
	s_nop 3
	v_max3_f32 v132, v132, v96, v97
	v_max3_f32 v132, v132, v98, v99
	v_max3_f32 v132, v132, v100, v101
	v_max3_f32 v132, v132, v102, v103
	v_max3_f32 v132, v132, v104, v105
	v_max3_f32 v132, v132, v106, v107
	v_max3_f32 v132, v132, v108, v109
	v_mfma_f32_32x32x16_bf16 v[80:95], v[216:219], v[154:157], v[80:95]
	v_max3_f32 v132, v132, v110, v111
	global_load_dwordx4 v[212:215], v[182:183], off
	global_load_dwordx4 v[224:227], v[194:195], off
	ds_read_b128 v[228:231], v133 offset:12800
	ds_read_b128 v[232:235], v133 offset:10272
	ds_read_b128 v[236:239], v133 offset:15360
	ds_read_b128 v[240:243], v133 offset:12832
	v_lshl_add_u64 v[128:129], v[158:159], 4, s[16:17]
	v_lshl_add_u64 v[130:131], v[130:131], 4, s[16:17]
	v_mov_b32_e32 v210, v196
	s_nop 1
	v_max3_f32 v132, v132, v80, v81
	s_waitcnt lgkmcnt(4)
	v_mfma_f32_32x32x16_bf16 v[64:79], v[220:223], v[154:157], v[64:79]
	v_max3_f32 v132, v132, v82, v83
	v_max3_f32 v132, v132, v84, v85
	v_max3_f32 v132, v132, v86, v87
	v_max3_f32 v132, v132, v88, v89
	v_max3_f32 v132, v132, v90, v91
	v_max3_f32 v132, v132, v92, v93
	v_max3_f32 v132, v132, v94, v95
	s_waitcnt lgkmcnt(3)
	v_mfma_f32_32x32x16_bf16 v[32:47], v[228:231], v[134:137], v[32:47]
	s_nop 2
	v_max3_f32 v132, v132, v64, v65
	v_max3_f32 v132, v132, v66, v67
	v_max3_f32 v132, v132, v68, v69
	v_max3_f32 v132, v132, v70, v71
	v_max3_f32 v132, v132, v72, v73
	v_max3_f32 v132, v132, v74, v75
	v_max3_f32 v132, v132, v76, v77
	s_waitcnt lgkmcnt(2)
	v_mfma_f32_32x32x16_bf16 v[48:63], v[232:235], v[154:157], v[48:63]
	global_load_dwordx4 v[228:231], v[128:129], off
	s_nop 0
	global_load_dwordx4 v[128:131], v[130:131], off
	ds_read_b128 v[244:247], v133 offset:15392
	v_max3_f32 v132, v132, v78, v79
	s_nop 6
	v_max3_f32 v132, v132, v48, v49
	s_waitcnt lgkmcnt(2)
	v_mfma_f32_32x32x16_bf16 v[16:31], v[236:239], v[134:137], v[16:31]
	v_max3_f32 v132, v132, v50, v51
	v_max3_f32 v132, v132, v52, v53
	v_max3_f32 v132, v132, v54, v55
	ds_read_b128 v[236:239], v133 offset:17920
	ds_read_b128 v[248:251], v133 offset:17952
	v_max3_f32 v132, v132, v56, v57
	v_max3_f32 v132, v132, v58, v59
	v_max3_f32 v132, v132, v60, v61
	s_waitcnt lgkmcnt(3)
	v_mfma_f32_32x32x16_bf16 v[32:47], v[240:243], v[154:157], v[32:47]
	v_max3_f32 v132, v132, v62, v63
	s_waitcnt lgkmcnt(0)
	s_barrier
; #define STOREK() do { _Pragma("unroll") for (int i = 0; i < 4; ++i) { const int ch = tid + i * 256; \
;     *(u32x4*)(kbuf + (ch >> 2) * 40 + (ch & 3) * 8) = sr[i]; } } while (0)
; #define STOREV(tid) do { _Pragma("unroll") for (int i = 0; i < 8; ++i) vbuf[tid + i * 256] = sr[i]; } while (0)
; DI void attn_prompt_block(const Params& p, int l, int b, int hh, int tt4, char* smem, bfr* Obuf) {
;     ...
;     if (c < 7) STOREK(); else STOREV(tid);
;     __syncthreads();
;   }
;   float mx = -3.0e38f;
; #pragma unroll
;   for (int m = 0; m < 8; ++m)
; #pragma unroll
;     for (int q = 0; q < 16; ++q) mx = fmaxf(mx, st[m][q]);
;   mx = fmaxf(mx, __shfl_xor(mx, 32));
;   float sum = 0.f;
; #pragma unroll
;   for (int m = 0; m < 8; ++m)
; #pragma unroll
;     for (int q = 0; q < 16; ++q) {
;       float e = __expf((st[m][q] - mx) * 0.0625f);
;       st[m][q] = e;
;       sum += e;
;     }
	ds_write_b128 v147, v[138:141]
	ds_write_b128 v147, v[142:145] offset:4096
	s_waitcnt vmcnt(5)
	ds_write_b128 v147, v[150:153] offset:8192
	s_waitcnt vmcnt(4)
	ds_write_b128 v147, v[204:207] offset:12288
	s_waitcnt vmcnt(3)
	ds_write_b128 v147, v[212:215] offset:16384
	s_waitcnt vmcnt(2)
	ds_write_b128 v147, v[224:227] offset:20480
	s_waitcnt vmcnt(1)
	ds_write_b128 v147, v[228:231] offset:24576
	v_max3_f32 v132, v132, v32, v33
	v_mfma_f32_32x32x16_bf16 v[16:31], v[244:247], v[154:157], v[16:31]
	v_max3_f32 v132, v132, v34, v35
	v_max3_f32 v132, v132, v36, v37
	v_max3_f32 v132, v132, v38, v39
	v_max3_f32 v132, v132, v40, v41
	v_max3_f32 v132, v132, v42, v43
	v_max3_f32 v132, v132, v44, v45
	v_max3_f32 v132, v132, v46, v47
	v_mfma_f32_32x32x16_bf16 v[0:15], v[236:239], v[134:137], v[0:15]
	s_nop 3
	v_max3_f32 v132, v132, v16, v17
	v_max3_f32 v132, v132, v18, v19
	v_max3_f32 v132, v132, v20, v21
	v_max3_f32 v132, v132, v22, v23
	v_max3_f32 v132, v132, v24, v25
	v_max3_f32 v132, v132, v26, v27
	v_max3_f32 v132, v132, v28, v29
	v_mfma_f32_32x32x16_bf16 v[0:15], v[248:251], v[154:157], v[0:15]
	v_max3_f32 v132, v132, v30, v31
	s_waitcnt vmcnt(0)
	ds_write_b128 v147, v[128:131] offset:28672
	s_waitcnt lgkmcnt(0)
	s_barrier
	s_nop 6
	v_max3_f32 v132, v132, v0, v1
	v_max3_f32 v132, v132, v2, v3
	v_max3_f32 v132, v132, v4, v5
	v_max3_f32 v132, v132, v6, v7
	v_max3_f32 v132, v132, v8, v9
	v_max3_f32 v132, v132, v10, v11
	v_max3_f32 v132, v132, v12, v13
	v_max3_f32 v133, v132, v14, v15
	v_cndmask_b32_e32 v132, v190, v191, vcc
	v_lshlrev_b32_e32 v132, 2, v132
	ds_bpermute_b32 v134, v132, v133
	v_and_b32_e32 v212, 0x1ff, v210
	v_or_b32_e32 v194, 0x200, v212
	s_waitcnt lgkmcnt(0)
	v_max_f32_e32 v134, v134, v134
	v_max_f32_e32 v133, v133, v134
	v_sub_f32_e32 v112, v112, v133
	v_mul_f32_e32 v112, 0x3d800000, v112
	v_sub_f32_e32 v113, v113, v133
	v_mul_f32_e32 v112, 0x3fb8aa3b, v112
	v_mul_f32_e32 v113, 0x3d800000, v113
	v_sub_f32_e32 v114, v114, v133
	v_exp_f32_e32 v112, v112
	v_mul_f32_e32 v113, 0x3fb8aa3b, v113
	v_mul_f32_e32 v114, 0x3d800000, v114
	v_sub_f32_e32 v115, v115, v133
	v_exp_f32_e32 v113, v113
	v_mul_f32_e32 v114, 0x3fb8aa3b, v114
	v_mul_f32_e32 v115, 0x3d800000, v115
	v_sub_f32_e32 v116, v116, v133
	v_exp_f32_e32 v114, v114
	v_mul_f32_e32 v115, 0x3fb8aa3b, v115
	v_mul_f32_e32 v116, 0x3d800000, v116
	v_sub_f32_e32 v117, v117, v133
	v_exp_f32_e32 v115, v115
	v_mul_f32_e32 v116, 0x3fb8aa3b, v116
	v_mul_f32_e32 v117, 0x3d800000, v117
	v_sub_f32_e32 v118, v118, v133
	v_add_f32_e32 v134, 0, v112
	v_exp_f32_e32 v116, v116
	v_mul_f32_e32 v117, 0x3fb8aa3b, v117
	v_mul_f32_e32 v118, 0x3d800000, v118
	v_sub_f32_e32 v119, v119, v133
	v_add_f32_e32 v134, v113, v134
	v_exp_f32_e32 v117, v117
	v_mul_f32_e32 v118, 0x3fb8aa3b, v118
	v_mul_f32_e32 v119, 0x3d800000, v119
	v_sub_f32_e32 v120, v120, v133
	v_add_f32_e32 v134, v114, v134
	v_exp_f32_e32 v118, v118
	v_mul_f32_e32 v119, 0x3fb8aa3b, v119
	v_mul_f32_e32 v120, 0x3d800000, v120
	v_sub_f32_e32 v121, v121, v133
	v_add_f32_e32 v134, v115, v134
	v_exp_f32_e32 v119, v119
	v_mul_f32_e32 v120, 0x3fb8aa3b, v120
	v_mul_f32_e32 v121, 0x3d800000, v121
	v_sub_f32_e32 v122, v122, v133
	v_add_f32_e32 v134, v116, v134
	v_exp_f32_e32 v120, v120
	v_mul_f32_e32 v121, 0x3fb8aa3b, v121
	v_mul_f32_e32 v122, 0x3d800000, v122
	v_sub_f32_e32 v123, v123, v133
	v_add_f32_e32 v134, v117, v134
	v_exp_f32_e32 v121, v121
	v_mul_f32_e32 v122, 0x3fb8aa3b, v122
	v_mul_f32_e32 v123, 0x3d800000, v123
	v_sub_f32_e32 v124, v124, v133
	v_add_f32_e32 v134, v118, v134
	v_exp_f32_e32 v122, v122
	v_mul_f32_e32 v123, 0x3fb8aa3b, v123
	v_mul_f32_e32 v124, 0x3d800000, v124
	v_sub_f32_e32 v125, v125, v133
	v_add_f32_e32 v134, v119, v134
	v_exp_f32_e32 v123, v123
	v_mul_f32_e32 v124, 0x3fb8aa3b, v124
	v_mul_f32_e32 v125, 0x3d800000, v125
	v_sub_f32_e32 v126, v126, v133
	v_add_f32_e32 v134, v120, v134
	v_exp_f32_e32 v124, v124
	v_mul_f32_e32 v125, 0x3fb8aa3b, v125
	v_mul_f32_e32 v126, 0x3d800000, v126
	v_sub_f32_e32 v127, v127, v133
	v_add_f32_e32 v134, v121, v134
	v_exp_f32_e32 v125, v125
	v_mul_f32_e32 v126, 0x3fb8aa3b, v126
	v_mul_f32_e32 v127, 0x3d800000, v127
	v_add_f32_e32 v134, v122, v134
	v_exp_f32_e32 v126, v126
	v_mul_f32_e32 v127, 0x3fb8aa3b, v127
	v_add_f32_e32 v134, v123, v134
	v_exp_f32_e32 v127, v127
	v_add_f32_e32 v134, v124, v134
	v_sub_f32_e32 v96, v96, v133
	v_add_f32_e32 v134, v125, v134
	v_mul_f32_e32 v96, 0x3d800000, v96
	v_add_f32_e32 v134, v126, v134
	v_mul_f32_e32 v96, 0x3fb8aa3b, v96
	v_add_f32_e32 v137, v127, v134
	v_exp_f32_e32 v134, v96
	v_sub_f32_e32 v96, v97, v133
	v_mul_f32_e32 v96, 0x3d800000, v96
	v_mul_f32_e32 v96, 0x3fb8aa3b, v96
	v_exp_f32_e32 v135, v96
	v_sub_f32_e32 v96, v98, v133
	v_mul_f32_e32 v96, 0x3d800000, v96
	v_mul_f32_e32 v96, 0x3fb8aa3b, v96
	v_exp_f32_e32 v98, v96
	v_sub_f32_e32 v96, v99, v133
	v_sub_f32_e32 v97, v100, v133
	v_mul_f32_e32 v96, 0x3d800000, v96
	v_mul_f32_e32 v97, 0x3d800000, v97
	v_mul_f32_e32 v96, 0x3fb8aa3b, v96
	v_mul_f32_e32 v97, 0x3fb8aa3b, v97
	v_sub_f32_e32 v80, v80, v133
	v_exp_f32_e32 v136, v96
	v_add_f32_e32 v96, v134, v137
	v_exp_f32_e32 v137, v97
	v_sub_f32_e32 v97, v101, v133
	v_mul_f32_e32 v80, 0x3d800000, v80
	v_mul_f32_e32 v97, 0x3d800000, v97
	v_mul_f32_e32 v80, 0x3fb8aa3b, v80
	v_mul_f32_e32 v97, 0x3fb8aa3b, v97
	v_exp_f32_e32 v144, v80
	v_sub_f32_e32 v80, v81, v133
	v_sub_f32_e32 v81, v84, v133
	v_exp_f32_e32 v138, v97
	v_sub_f32_e32 v97, v102, v133
	v_mul_f32_e32 v81, 0x3d800000, v81
	v_mul_f32_e32 v97, 0x3d800000, v97
	v_mul_f32_e32 v81, 0x3fb8aa3b, v81
	v_mul_f32_e32 v97, 0x3fb8aa3b, v97
	v_exp_f32_e32 v150, v81
	v_sub_f32_e32 v81, v85, v133
	v_exp_f32_e32 v139, v97
; DI void attn_prompt_block(const Params& p, int l, int b, int hh, int tt4, char* smem, bfr* Obuf) {
;     ...
;   float sum = 0.f;
; #pragma unroll
;   for (int m = 0; m < 8; ++m)
; #pragma unroll
;     for (int q = 0; q < 16; ++q) {
;       float e = __expf((st[m][q] - mx) * 0.0625f);
;       st[m][q] = e;
;       sum += e;
;     }
	v_sub_f32_e32 v97, v103, v133
	v_mul_f32_e32 v81, 0x3d800000, v81
	v_mul_f32_e32 v97, 0x3d800000, v97
	v_mul_f32_e32 v81, 0x3fb8aa3b, v81
	v_mul_f32_e32 v97, 0x3fb8aa3b, v97
	v_exp_f32_e32 v151, v81
	v_sub_f32_e32 v81, v86, v133
	v_exp_f32_e32 v140, v97
	v_sub_f32_e32 v97, v104, v133
	v_mul_f32_e32 v81, 0x3d800000, v81
	v_mul_f32_e32 v97, 0x3d800000, v97
	v_mul_f32_e32 v81, 0x3fb8aa3b, v81
	v_mul_f32_e32 v97, 0x3fb8aa3b, v97
	v_exp_f32_e32 v152, v81
	v_sub_f32_e32 v81, v87, v133
	v_exp_f32_e32 v141, v97
	v_sub_f32_e32 v97, v105, v133
	v_mul_f32_e32 v81, 0x3d800000, v81
	v_mul_f32_e32 v97, 0x3d800000, v97
	v_mul_f32_e32 v81, 0x3fb8aa3b, v81
	v_mul_f32_e32 v97, 0x3fb8aa3b, v97
	v_exp_f32_e32 v153, v81
	v_sub_f32_e32 v81, v88, v133
	v_exp_f32_e32 v142, v97
	v_sub_f32_e32 v97, v106, v133
	v_mul_f32_e32 v81, 0x3d800000, v81
	v_mul_f32_e32 v97, 0x3d800000, v97
	v_mul_f32_e32 v81, 0x3fb8aa3b, v81
	v_mul_f32_e32 v97, 0x3fb8aa3b, v97
	v_exp_f32_e32 v154, v81
	v_sub_f32_e32 v81, v89, v133
	v_exp_f32_e32 v143, v97
	v_sub_f32_e32 v97, v107, v133
	v_mul_f32_e32 v81, 0x3d800000, v81
	v_mul_f32_e32 v97, 0x3d800000, v97
	v_mul_f32_e32 v81, 0x3fb8aa3b, v81
	v_mul_f32_e32 v97, 0x3fb8aa3b, v97
	v_exp_f32_e32 v155, v81
	v_sub_f32_e32 v81, v90, v133
	v_exp_f32_e32 v107, v97
	v_sub_f32_e32 v97, v108, v133
	v_mul_f32_e32 v81, 0x3d800000, v81
	v_mul_f32_e32 v97, 0x3d800000, v97
	v_mul_f32_e32 v81, 0x3fb8aa3b, v81
	v_add_f32_e32 v96, v135, v96
	v_mul_f32_e32 v97, 0x3fb8aa3b, v97
	v_exp_f32_e32 v156, v81
	v_sub_f32_e32 v81, v91, v133
	v_add_f32_e32 v96, v98, v96
	v_exp_f32_e32 v108, v97
	v_sub_f32_e32 v97, v109, v133
	v_mul_f32_e32 v81, 0x3d800000, v81
	v_add_f32_e32 v96, v136, v96
	v_mul_f32_e32 v97, 0x3d800000, v97
	v_mul_f32_e32 v81, 0x3fb8aa3b, v81
	v_add_f32_e32 v96, v137, v96
	v_mul_f32_e32 v97, 0x3fb8aa3b, v97
	v_exp_f32_e32 v157, v81
	v_sub_f32_e32 v81, v92, v133
	v_sub_f32_e32 v64, v64, v133
	v_add_f32_e32 v96, v138, v96
	v_exp_f32_e32 v109, v97
	v_sub_f32_e32 v97, v110, v133
	v_mul_f32_e32 v81, 0x3d800000, v81
	v_mul_f32_e32 v64, 0x3d800000, v64
	v_add_f32_e32 v96, v139, v96
	v_mul_f32_e32 v97, 0x3d800000, v97
	v_mul_f32_e32 v81, 0x3fb8aa3b, v81
	v_mul_f32_e32 v64, 0x3fb8aa3b, v64
	v_add_f32_e32 v96, v140, v96
	v_mul_f32_e32 v97, 0x3fb8aa3b, v97
	v_mul_f32_e32 v80, 0x3d800000, v80
	v_exp_f32_e32 v158, v81
	v_sub_f32_e32 v81, v93, v133
	v_exp_f32_e32 v90, v64
	v_sub_f32_e32 v64, v65, v133
	v_sub_f32_e32 v65, v68, v133
	v_add_f32_e32 v96, v141, v96
	v_exp_f32_e32 v110, v97
	v_sub_f32_e32 v97, v111, v133
	v_mul_f32_e32 v80, 0x3fb8aa3b, v80
	v_mul_f32_e32 v81, 0x3d800000, v81
	v_mul_f32_e32 v65, 0x3d800000, v65
	v_add_f32_e32 v96, v142, v96
	v_mul_f32_e32 v97, 0x3d800000, v97
	v_exp_f32_e32 v145, v80
	v_sub_f32_e32 v80, v82, v133
	v_mul_f32_e32 v81, 0x3fb8aa3b, v81
	v_mul_f32_e32 v65, 0x3fb8aa3b, v65
	v_add_f32_e32 v96, v143, v96
	v_mul_f32_e32 v97, 0x3fb8aa3b, v97
	v_mul_f32_e32 v80, 0x3d800000, v80
	v_exp_f32_e32 v159, v81
	v_sub_f32_e32 v81, v94, v133
	v_exp_f32_e32 v94, v65
	v_sub_f32_e32 v65, v69, v133
	v_add_f32_e32 v96, v107, v96
	v_exp_f32_e32 v111, v97
	v_mul_f32_e32 v80, 0x3fb8aa3b, v80
	v_mul_f32_e32 v81, 0x3d800000, v81
	v_mul_f32_e32 v65, 0x3d800000, v65
	v_add_f32_e32 v96, v108, v96
	v_exp_f32_e32 v148, v80
	v_sub_f32_e32 v80, v83, v133
	v_mul_f32_e32 v81, 0x3fb8aa3b, v81
	v_mul_f32_e32 v65, 0x3fb8aa3b, v65
	v_add_f32_e32 v96, v109, v96
	v_mul_f32_e32 v80, 0x3d800000, v80
	v_exp_f32_e32 v88, v81
	v_sub_f32_e32 v81, v95, v133
	v_exp_f32_e32 v95, v65
	v_sub_f32_e32 v65, v70, v133
	v_add_f32_e32 v96, v110, v96
	v_mul_f32_e32 v80, 0x3fb8aa3b, v80
	v_mul_f32_e32 v65, 0x3d800000, v65
	v_add_f32_e32 v96, v111, v96
	v_exp_f32_e32 v149, v80
	v_mul_f32_e32 v65, 0x3fb8aa3b, v65
	v_add_f32_e32 v80, v144, v96
	v_exp_f32_e32 v96, v65
	v_sub_f32_e32 v65, v71, v133
	v_add_f32_e32 v80, v145, v80
	v_mul_f32_e32 v65, 0x3d800000, v65
	v_add_f32_e32 v80, v148, v80
	v_mul_f32_e32 v65, 0x3fb8aa3b, v65
	v_add_f32_e32 v80, v149, v80
	v_exp_f32_e32 v97, v65
	v_sub_f32_e32 v65, v72, v133
	v_add_f32_e32 v80, v150, v80
	v_mul_f32_e32 v65, 0x3d800000, v65
	v_add_f32_e32 v80, v151, v80
	v_mul_f32_e32 v65, 0x3fb8aa3b, v65
	v_add_f32_e32 v80, v152, v80
	v_exp_f32_e32 v99, v65
	v_sub_f32_e32 v65, v73, v133
	v_add_f32_e32 v80, v153, v80
	v_mul_f32_e32 v64, 0x3d800000, v64
	v_mul_f32_e32 v65, 0x3d800000, v65
	v_add_f32_e32 v80, v154, v80
	v_mul_f32_e32 v64, 0x3fb8aa3b, v64
	v_mul_f32_e32 v65, 0x3fb8aa3b, v65
	v_add_f32_e32 v80, v155, v80
	v_mul_f32_e32 v81, 0x3d800000, v81
	v_exp_f32_e32 v91, v64
	v_sub_f32_e32 v64, v66, v133
	v_exp_f32_e32 v100, v65
	v_sub_f32_e32 v65, v74, v133
	v_add_f32_e32 v80, v156, v80
	v_mul_f32_e32 v81, 0x3fb8aa3b, v81
	v_mul_f32_e32 v64, 0x3d800000, v64
	v_mul_f32_e32 v65, 0x3d800000, v65
	v_add_f32_e32 v80, v157, v80
	v_exp_f32_e32 v89, v81
	v_mul_f32_e32 v64, 0x3fb8aa3b, v64
	v_mul_f32_e32 v65, 0x3fb8aa3b, v65
	v_add_f32_e32 v80, v158, v80
	v_exp_f32_e32 v92, v64
	v_sub_f32_e32 v64, v67, v133
	v_exp_f32_e32 v101, v65
	v_sub_f32_e32 v65, v75, v133
	v_add_f32_e32 v80, v159, v80
	v_mul_f32_e32 v64, 0x3d800000, v64
	v_mul_f32_e32 v65, 0x3d800000, v65
	v_add_f32_e32 v80, v88, v80
	v_mul_f32_e32 v64, 0x3fb8aa3b, v64
	v_mul_f32_e32 v65, 0x3fb8aa3b, v65
	v_add_f32_e32 v80, v89, v80
	v_exp_f32_e32 v93, v64
	v_exp_f32_e32 v102, v65
	v_sub_f32_e32 v65, v76, v133
	v_add_f32_e32 v64, v90, v80
	v_mul_f32_e32 v65, 0x3d800000, v65
	v_add_f32_e32 v64, v91, v64
	v_mul_f32_e32 v65, 0x3fb8aa3b, v65
	v_add_f32_e32 v64, v92, v64
	v_exp_f32_e32 v103, v65
	v_sub_f32_e32 v65, v77, v133
	v_add_f32_e32 v64, v93, v64
	v_mul_f32_e32 v65, 0x3d800000, v65
	v_add_f32_e32 v64, v94, v64
; DI void attn_prompt_block(const Params& p, int l, int b, int hh, int tt4, char* smem, bfr* Obuf) {
;     ...
;   float sum = 0.f;
; #pragma unroll
;   for (int m = 0; m < 8; ++m)
; #pragma unroll
;     for (int q = 0; q < 16; ++q) {
;       float e = __expf((st[m][q] - mx) * 0.0625f);
;       st[m][q] = e;
;       sum += e;
;     }
	v_mul_f32_e32 v65, 0x3fb8aa3b, v65
	v_add_f32_e32 v64, v95, v64
	v_exp_f32_e32 v104, v65
	v_sub_f32_e32 v65, v78, v133
	v_add_f32_e32 v64, v96, v64
	v_mul_f32_e32 v65, 0x3d800000, v65
	v_add_f32_e32 v64, v97, v64
	v_mul_f32_e32 v65, 0x3fb8aa3b, v65
	v_add_f32_e32 v64, v99, v64
	v_exp_f32_e32 v105, v65
	v_sub_f32_e32 v65, v79, v133
	v_add_f32_e32 v64, v100, v64
	v_mul_f32_e32 v65, 0x3d800000, v65
	v_sub_f32_e32 v48, v48, v133
	v_add_f32_e32 v64, v101, v64
	v_mul_f32_e32 v65, 0x3fb8aa3b, v65
	v_mul_f32_e32 v48, 0x3d800000, v48
	v_sub_f32_e32 v49, v49, v133
	v_add_f32_e32 v64, v102, v64
	v_exp_f32_e32 v106, v65
	v_mul_f32_e32 v48, 0x3fb8aa3b, v48
	v_mul_f32_e32 v49, 0x3d800000, v49
	v_sub_f32_e32 v50, v50, v133
	v_add_f32_e32 v64, v103, v64
	v_exp_f32_e32 v48, v48
	v_mul_f32_e32 v49, 0x3fb8aa3b, v49
	v_mul_f32_e32 v50, 0x3d800000, v50
	v_sub_f32_e32 v51, v51, v133
	v_add_f32_e32 v64, v104, v64
	v_exp_f32_e32 v49, v49
	v_mul_f32_e32 v50, 0x3fb8aa3b, v50
	v_mul_f32_e32 v51, 0x3d800000, v51
	v_sub_f32_e32 v52, v52, v133
	v_add_f32_e32 v64, v105, v64
	v_exp_f32_e32 v50, v50
	v_mul_f32_e32 v51, 0x3fb8aa3b, v51
	v_mul_f32_e32 v52, 0x3d800000, v52
	v_sub_f32_e32 v53, v53, v133
	v_add_f32_e32 v64, v106, v64
	v_exp_f32_e32 v51, v51
	v_mul_f32_e32 v52, 0x3fb8aa3b, v52
	v_mul_f32_e32 v53, 0x3d800000, v53
	v_sub_f32_e32 v54, v54, v133
	v_add_f32_e32 v64, v48, v64
	v_exp_f32_e32 v52, v52
	v_mul_f32_e32 v53, 0x3fb8aa3b, v53
	v_mul_f32_e32 v54, 0x3d800000, v54
	v_sub_f32_e32 v55, v55, v133
	v_add_f32_e32 v64, v49, v64
	v_exp_f32_e32 v53, v53
	v_mul_f32_e32 v54, 0x3fb8aa3b, v54
	v_mul_f32_e32 v55, 0x3d800000, v55
	v_sub_f32_e32 v56, v56, v133
	v_add_f32_e32 v64, v50, v64
	v_exp_f32_e32 v54, v54
	v_mul_f32_e32 v55, 0x3fb8aa3b, v55
	v_mul_f32_e32 v56, 0x3d800000, v56
	v_sub_f32_e32 v57, v57, v133
	v_add_f32_e32 v64, v51, v64
	v_exp_f32_e32 v55, v55
	v_mul_f32_e32 v56, 0x3fb8aa3b, v56
	v_mul_f32_e32 v57, 0x3d800000, v57
	v_sub_f32_e32 v58, v58, v133
	v_add_f32_e32 v64, v52, v64
	v_exp_f32_e32 v56, v56
	v_mul_f32_e32 v57, 0x3fb8aa3b, v57
	v_mul_f32_e32 v58, 0x3d800000, v58
	v_sub_f32_e32 v59, v59, v133
	v_add_f32_e32 v64, v53, v64
	v_exp_f32_e32 v57, v57
	v_mul_f32_e32 v58, 0x3fb8aa3b, v58
	v_mul_f32_e32 v59, 0x3d800000, v59
	v_sub_f32_e32 v60, v60, v133
	v_add_f32_e32 v64, v54, v64
	v_exp_f32_e32 v58, v58
	v_mul_f32_e32 v59, 0x3fb8aa3b, v59
	v_mul_f32_e32 v60, 0x3d800000, v60
	v_sub_f32_e32 v61, v61, v133
	v_add_f32_e32 v64, v55, v64
	v_exp_f32_e32 v59, v59
	v_mul_f32_e32 v60, 0x3fb8aa3b, v60
	v_mul_f32_e32 v61, 0x3d800000, v61
	v_sub_f32_e32 v62, v62, v133
	v_add_f32_e32 v64, v56, v64
	v_exp_f32_e32 v60, v60
	v_mul_f32_e32 v61, 0x3fb8aa3b, v61
	v_mul_f32_e32 v62, 0x3d800000, v62
	v_sub_f32_e32 v63, v63, v133
	v_add_f32_e32 v64, v57, v64
	v_exp_f32_e32 v61, v61
	v_mul_f32_e32 v62, 0x3fb8aa3b, v62
	v_mul_f32_e32 v63, 0x3d800000, v63
	v_sub_f32_e32 v32, v32, v133
	v_add_f32_e32 v64, v58, v64
	v_exp_f32_e32 v62, v62
	v_mul_f32_e32 v63, 0x3fb8aa3b, v63
	v_mul_f32_e32 v32, 0x3d800000, v32
	v_sub_f32_e32 v33, v33, v133
	v_add_f32_e32 v64, v59, v64
	v_exp_f32_e32 v63, v63
	v_mul_f32_e32 v32, 0x3fb8aa3b, v32
	v_mul_f32_e32 v33, 0x3d800000, v33
	v_sub_f32_e32 v34, v34, v133
	v_add_f32_e32 v64, v60, v64
	v_exp_f32_e32 v32, v32
	v_mul_f32_e32 v33, 0x3fb8aa3b, v33
	v_mul_f32_e32 v34, 0x3d800000, v34
	v_sub_f32_e32 v35, v35, v133
	v_add_f32_e32 v64, v61, v64
	v_exp_f32_e32 v33, v33
	v_mul_f32_e32 v34, 0x3fb8aa3b, v34
	v_mul_f32_e32 v35, 0x3d800000, v35
	v_sub_f32_e32 v36, v36, v133
	v_add_f32_e32 v64, v62, v64
	v_exp_f32_e32 v34, v34
	v_mul_f32_e32 v35, 0x3fb8aa3b, v35
	v_mul_f32_e32 v36, 0x3d800000, v36
	v_sub_f32_e32 v37, v37, v133
	v_add_f32_e32 v64, v63, v64
	v_exp_f32_e32 v35, v35
	v_mul_f32_e32 v36, 0x3fb8aa3b, v36
	v_mul_f32_e32 v37, 0x3d800000, v37
	v_sub_f32_e32 v38, v38, v133
	v_add_f32_e32 v64, v32, v64
	v_exp_f32_e32 v36, v36
	v_mul_f32_e32 v37, 0x3fb8aa3b, v37
	v_mul_f32_e32 v38, 0x3d800000, v38
	v_sub_f32_e32 v39, v39, v133
	v_add_f32_e32 v64, v33, v64
	v_exp_f32_e32 v37, v37
	v_mul_f32_e32 v38, 0x3fb8aa3b, v38
	v_mul_f32_e32 v39, 0x3d800000, v39
	v_sub_f32_e32 v40, v40, v133
	v_add_f32_e32 v64, v34, v64
	v_exp_f32_e32 v38, v38
	v_mul_f32_e32 v39, 0x3fb8aa3b, v39
	v_mul_f32_e32 v40, 0x3d800000, v40
	v_sub_f32_e32 v41, v41, v133
	v_add_f32_e32 v64, v35, v64
	v_exp_f32_e32 v39, v39
	v_mul_f32_e32 v40, 0x3fb8aa3b, v40
	v_mul_f32_e32 v41, 0x3d800000, v41
	v_sub_f32_e32 v42, v42, v133
	v_add_f32_e32 v64, v36, v64
	v_exp_f32_e32 v40, v40
	v_mul_f32_e32 v41, 0x3fb8aa3b, v41
	v_mul_f32_e32 v42, 0x3d800000, v42
	v_sub_f32_e32 v43, v43, v133
	v_sub_f32_e32 v0, v0, v133
	v_add_f32_e32 v64, v37, v64
	v_exp_f32_e32 v41, v41
	v_mul_f32_e32 v42, 0x3fb8aa3b, v42
	v_mul_f32_e32 v43, 0x3d800000, v43
	v_sub_f32_e32 v44, v44, v133
	v_mul_f32_e32 v0, 0x3d800000, v0
	v_add_f32_e32 v64, v38, v64
	v_exp_f32_e32 v42, v42
	v_mul_f32_e32 v43, 0x3fb8aa3b, v43
	v_mul_f32_e32 v44, 0x3d800000, v44
	v_sub_f32_e32 v45, v45, v133
	v_mul_f32_e32 v0, 0x3fb8aa3b, v0
	v_add_f32_e32 v64, v39, v64
	v_exp_f32_e32 v43, v43
	v_mul_f32_e32 v44, 0x3fb8aa3b, v44
	v_mul_f32_e32 v45, 0x3d800000, v45
	v_sub_f32_e32 v46, v46, v133
	v_exp_f32_e32 v160, v0
	v_sub_f32_e32 v0, v1, v133
	v_sub_f32_e32 v1, v4, v133
	v_add_f32_e32 v64, v40, v64
	v_exp_f32_e32 v44, v44
	v_mul_f32_e32 v45, 0x3fb8aa3b, v45
	v_mul_f32_e32 v46, 0x3d800000, v46
	v_sub_f32_e32 v47, v47, v133
	v_mul_f32_e32 v1, 0x3d800000, v1
	v_add_f32_e32 v64, v41, v64
	v_exp_f32_e32 v45, v45
	v_mul_f32_e32 v46, 0x3fb8aa3b, v46
	v_mul_f32_e32 v47, 0x3d800000, v47
	v_sub_f32_e32 v16, v16, v133
	v_mul_f32_e32 v1, 0x3fb8aa3b, v1
	v_add_f32_e32 v64, v42, v64
; DI void attn_prompt_block(const Params& p, int l, int b, int hh, int tt4, char* smem, bfr* Obuf) {
;     ...
;   float sum = 0.f;
; #pragma unroll
;   for (int m = 0; m < 8; ++m)
; #pragma unroll
;     for (int q = 0; q < 16; ++q) {
;       float e = __expf((st[m][q] - mx) * 0.0625f);
;       st[m][q] = e;
;       sum += e;
;     }
;   sum += __shfl_xor(sum, 32);
;   const float inv = 1.0f / sum;
;   bf16x8 pb[8][2];
; #pragma unroll
;   for (int m = 0; m < 8; ++m) { pb[m][0] = pack8(st[m], 0); pb[m][1] = pack8(st[m], 1); }
	v_exp_f32_e32 v46, v46
	v_mul_f32_e32 v47, 0x3fb8aa3b, v47
	v_mul_f32_e32 v16, 0x3d800000, v16
	v_sub_f32_e32 v17, v17, v133
	v_exp_f32_e32 v193, v1
	v_sub_f32_e32 v1, v5, v133
	v_add_f32_e32 v64, v43, v64
	v_exp_f32_e32 v47, v47
	v_mul_f32_e32 v16, 0x3fb8aa3b, v16
	v_mul_f32_e32 v17, 0x3d800000, v17
	v_sub_f32_e32 v18, v18, v133
	v_mul_f32_e32 v1, 0x3d800000, v1
	v_add_f32_e32 v64, v44, v64
	v_exp_f32_e32 v16, v16
	v_mul_f32_e32 v17, 0x3fb8aa3b, v17
	v_mul_f32_e32 v18, 0x3d800000, v18
	v_sub_f32_e32 v19, v19, v133
	v_mul_f32_e32 v1, 0x3fb8aa3b, v1
	v_add_f32_e32 v64, v45, v64
	v_exp_f32_e32 v17, v17
	v_mul_f32_e32 v18, 0x3fb8aa3b, v18
	v_mul_f32_e32 v19, 0x3d800000, v19
	v_sub_f32_e32 v20, v20, v133
	v_exp_f32_e32 v195, v1
	v_sub_f32_e32 v1, v6, v133
	v_add_f32_e32 v64, v46, v64
	v_exp_f32_e32 v18, v18
	v_mul_f32_e32 v19, 0x3fb8aa3b, v19
	v_mul_f32_e32 v20, 0x3d800000, v20
	v_sub_f32_e32 v21, v21, v133
	v_mul_f32_e32 v1, 0x3d800000, v1
	v_add_f32_e32 v64, v47, v64
	v_exp_f32_e32 v19, v19
	v_mul_f32_e32 v20, 0x3fb8aa3b, v20
	v_mul_f32_e32 v21, 0x3d800000, v21
	v_sub_f32_e32 v22, v22, v133
	v_mul_f32_e32 v1, 0x3fb8aa3b, v1
	v_add_f32_e32 v64, v16, v64
	v_exp_f32_e32 v20, v20
	v_mul_f32_e32 v21, 0x3fb8aa3b, v21
	v_mul_f32_e32 v22, 0x3d800000, v22
	v_sub_f32_e32 v23, v23, v133
	v_exp_f32_e32 v6, v1
	v_sub_f32_e32 v1, v7, v133
	v_add_f32_e32 v64, v17, v64
	v_exp_f32_e32 v21, v21
	v_mul_f32_e32 v22, 0x3fb8aa3b, v22
	v_mul_f32_e32 v23, 0x3d800000, v23
	v_sub_f32_e32 v24, v24, v133
	v_mul_f32_e32 v1, 0x3d800000, v1
	v_add_f32_e32 v64, v18, v64
	v_exp_f32_e32 v22, v22
	v_mul_f32_e32 v23, 0x3fb8aa3b, v23
	v_mul_f32_e32 v24, 0x3d800000, v24
	v_sub_f32_e32 v25, v25, v133
	v_mul_f32_e32 v1, 0x3fb8aa3b, v1
	v_add_f32_e32 v64, v19, v64
	v_exp_f32_e32 v23, v23
	v_mul_f32_e32 v24, 0x3fb8aa3b, v24
	v_mul_f32_e32 v25, 0x3d800000, v25
	v_sub_f32_e32 v26, v26, v133
	v_exp_f32_e32 v7, v1
	v_sub_f32_e32 v1, v8, v133
	v_add_f32_e32 v64, v20, v64
	v_exp_f32_e32 v24, v24
	v_mul_f32_e32 v25, 0x3fb8aa3b, v25
	v_mul_f32_e32 v26, 0x3d800000, v26
	v_sub_f32_e32 v27, v27, v133
	v_mul_f32_e32 v1, 0x3d800000, v1
	v_add_f32_e32 v64, v21, v64
	v_exp_f32_e32 v25, v25
	v_mul_f32_e32 v26, 0x3fb8aa3b, v26
	v_mul_f32_e32 v27, 0x3d800000, v27
	v_sub_f32_e32 v28, v28, v133
	v_mul_f32_e32 v1, 0x3fb8aa3b, v1
	v_add_f32_e32 v64, v22, v64
	v_exp_f32_e32 v26, v26
	v_mul_f32_e32 v27, 0x3fb8aa3b, v27
	v_mul_f32_e32 v28, 0x3d800000, v28
	v_sub_f32_e32 v29, v29, v133
	v_exp_f32_e32 v8, v1
	v_sub_f32_e32 v1, v9, v133
	v_add_f32_e32 v64, v23, v64
	v_exp_f32_e32 v27, v27
	v_mul_f32_e32 v28, 0x3fb8aa3b, v28
	v_mul_f32_e32 v29, 0x3d800000, v29
	v_sub_f32_e32 v30, v30, v133
	v_mul_f32_e32 v0, 0x3d800000, v0
	v_mul_f32_e32 v1, 0x3d800000, v1
	v_add_f32_e32 v64, v24, v64
	v_exp_f32_e32 v28, v28
	v_mul_f32_e32 v29, 0x3fb8aa3b, v29
	v_mul_f32_e32 v30, 0x3d800000, v30
	v_sub_f32_e32 v31, v31, v133
	v_mul_f32_e32 v0, 0x3fb8aa3b, v0
	v_mul_f32_e32 v1, 0x3fb8aa3b, v1
	v_add_f32_e32 v64, v25, v64
	v_exp_f32_e32 v29, v29
	v_mul_f32_e32 v30, 0x3fb8aa3b, v30
	v_mul_f32_e32 v31, 0x3d800000, v31
	v_exp_f32_e32 v180, v0
	v_sub_f32_e32 v0, v2, v133
	v_exp_f32_e32 v9, v1
	v_sub_f32_e32 v1, v10, v133
	v_add_f32_e32 v64, v26, v64
	v_exp_f32_e32 v30, v30
	v_mul_f32_e32 v31, 0x3fb8aa3b, v31
	v_mul_f32_e32 v0, 0x3d800000, v0
	v_mul_f32_e32 v1, 0x3d800000, v1
	v_add_f32_e32 v64, v27, v64
	v_exp_f32_e32 v31, v31
	v_mul_f32_e32 v0, 0x3fb8aa3b, v0
	v_mul_f32_e32 v1, 0x3fb8aa3b, v1
	v_add_f32_e32 v64, v28, v64
	v_exp_f32_e32 v182, v0
	v_sub_f32_e32 v0, v3, v133
	v_exp_f32_e32 v10, v1
	v_sub_f32_e32 v1, v11, v133
	v_add_f32_e32 v64, v29, v64
	v_mul_f32_e32 v0, 0x3d800000, v0
	v_mul_f32_e32 v1, 0x3d800000, v1
	v_add_f32_e32 v64, v30, v64
	v_mul_f32_e32 v0, 0x3fb8aa3b, v0
	v_mul_f32_e32 v1, 0x3fb8aa3b, v1
	v_add_f32_e32 v64, v31, v64
	v_exp_f32_e32 v183, v0
	v_exp_f32_e32 v11, v1
	v_sub_f32_e32 v1, v12, v133
	v_add_f32_e32 v0, v160, v64
	v_mul_f32_e32 v1, 0x3d800000, v1
	v_add_f32_e32 v0, v180, v0
	v_mul_f32_e32 v1, 0x3fb8aa3b, v1
	v_add_f32_e32 v0, v182, v0
	v_exp_f32_e32 v12, v1
	v_sub_f32_e32 v1, v13, v133
	v_add_f32_e32 v0, v183, v0
	v_mul_f32_e32 v1, 0x3d800000, v1
	v_add_f32_e32 v0, v193, v0
	v_mul_f32_e32 v1, 0x3fb8aa3b, v1
	v_add_f32_e32 v0, v195, v0
	v_exp_f32_e32 v13, v1
	v_sub_f32_e32 v1, v14, v133
	v_add_f32_e32 v0, v6, v0
	v_mul_f32_e32 v1, 0x3d800000, v1
	v_add_f32_e32 v0, v7, v0
	v_mul_f32_e32 v1, 0x3fb8aa3b, v1
	v_add_f32_e32 v0, v8, v0
	v_exp_f32_e32 v14, v1
	v_sub_f32_e32 v1, v15, v133
	v_add_f32_e32 v0, v9, v0
	v_mul_f32_e32 v1, 0x3d800000, v1
	v_add_f32_e32 v0, v10, v0
	v_mul_f32_e32 v1, 0x3fb8aa3b, v1
	v_add_f32_e32 v0, v11, v0
	v_exp_f32_e32 v15, v1
	v_add_f32_e32 v0, v12, v0
	v_add_f32_e32 v0, v13, v0
	v_add_f32_e32 v0, v14, v0
	v_add_f32_e32 v0, v15, v0
	ds_bpermute_b32 v1, v132, v0
	v_cvt_pk_bf16_f32 v68, v144, v145
	v_and_b32_e32 v144, 63, v210
	v_cvt_pk_bf16_f32 v76, v134, v135
	v_cvt_pk_bf16_f32 v77, v98, v136
	s_waitcnt lgkmcnt(0)
; #define MFMA32(a, b, c) __builtin_amdgcn_mfma_f32_32x32x16_bf16((a), (b), (c), 0, 0, 0)
; #define LOADV(v_, tid) do { _Pragma("unroll") for (int i = 0; i < 8; ++i) { const int idx = tid + i * 256, f = idx >> 6; \
;     sr[i] = VTg[(((v_) >> 1) * 4 + (f >> 3)) * 1024 + (((v_) & 1) * 8 + (f & 7)) * 64 + (idx & 63)]; } } while (0)
; DI void attn_prompt_block(const Params& p, int l, int b, int hh, int tt4, char* smem, bfr* Obuf) {
;     ...
;   sum += __shfl_xor(sum, 32);
;   const float inv = 1.0f / sum;
;   bf16x8 pb[8][2];
; #pragma unroll
;   for (int m = 0; m < 8; ++m) { pb[m][0] = pack8(st[m], 0); pb[m][1] = pack8(st[m], 1); }
;   int tidv = threadIdx.x;
;   asm volatile("" : "+v"(tidv));
;   const int lanev = tidv & 63, rv = lanev & 31, hlv = lanev >> 5;
;   const int ooff = (b * 2048 + (tt4 * 4 + (tidv >> 6)) * 32 + rv) * 1024 + hh * 256;
;   f32x16 o[4];
; #pragma unroll
;   for (int v = 0; v < 4; ++v) {
;     if (v < 3) LOADV(v + 1, tidv);
;     if ((v & 1) == 0) {
; #pragma unroll
;       for (int d = 0; d < 4; ++d)
; #pragma unroll
;         for (int q = 0; q < 16; ++q) o[d][q] = 0.f;
;     }
; #pragma unroll
;     for (int kk = 0; kk < 8; ++kk)
; #pragma unroll
;       for (int d = 0; d < 4; ++d) {
;         bf16x8 vf = __builtin_bit_cast(bf16x8, vbuf[(d * 8 + kk) * 64 + lanev]);
;         o[d] = MFMA32(vf, pb[((v & 1) * 8 + kk) >> 1][kk & 1], o[d]);
	v_add_f32_e32 v147, v0, v1
	v_lshlrev_b32_e32 v0, 1, v210
	v_and_b32_e32 v211, 0xfffffc00, v0
	v_or_b32_e32 v0, v194, v211
	v_ashrrev_i32_e32 v1, 31, v0
	v_lshl_add_u64 v[2:3], v[0:1], 4, s[16:17]
	v_add_u32_e32 v1, 0x100, v210
	v_lshlrev_b32_e32 v4, 1, v1
	v_and_or_b32 v214, v1, s40, v144
	v_and_b32_e32 v213, 0xfffffc00, v4
	v_or_b32_e32 v201, 0x200, v214
	v_or_b32_e32 v4, v201, v213
	v_ashrrev_i32_e32 v5, 31, v4
	v_lshl_add_u64 v[4:5], v[4:5], 4, s[16:17]
	v_add_u32_e32 v1, 0x300, v210
	global_load_dwordx4 v[128:131], v[2:3], off
	global_load_dwordx4 v[132:135], v[4:5], off
	v_lshlrev_b32_e32 v4, 1, v1
	v_and_or_b32 v216, v1, s40, v144
	v_and_b32_e32 v215, 0xfffffc00, v4
	v_or_b32_e32 v197, 0x200, v216
	v_add_u32_e32 v2, 0x400, v0
	v_or_b32_e32 v4, v197, v215
	v_ashrrev_i32_e32 v3, 31, v2
	v_ashrrev_i32_e32 v5, 31, v4
	v_lshl_add_u64 v[2:3], v[2:3], 4, s[16:17]
	v_lshl_add_u64 v[4:5], v[4:5], 4, s[16:17]
	v_add_u32_e32 v1, 0x500, v210
	v_cvt_pk_bf16_f32 v78, v137, v138
	v_cvt_pk_bf16_f32 v79, v139, v140
	v_cvt_pk_bf16_f32 v72, v141, v142
	v_cvt_pk_bf16_f32 v73, v143, v107
	global_load_dwordx4 v[136:139], v[2:3], off
	global_load_dwordx4 v[140:143], v[4:5], off
	v_lshlrev_b32_e32 v4, 1, v1
	v_and_or_b32 v218, v1, s40, v144
	v_add_u32_e32 v2, 0x800, v0
	v_and_b32_e32 v217, 0xfffffc00, v4
	v_or_b32_e32 v199, 0x200, v218
	v_ashrrev_i32_e32 v3, 31, v2
	v_or_b32_e32 v4, v199, v217
	v_lshl_add_u64 v[2:3], v[2:3], 4, s[16:17]
	v_ashrrev_i32_e32 v5, 31, v4
	v_cvt_pk_bf16_f32 v69, v148, v149
	v_cvt_pk_bf16_f32 v70, v150, v151
	v_cvt_pk_bf16_f32 v71, v152, v153
	v_cvt_pk_bf16_f32 v64, v154, v155
	v_lshl_add_u64 v[4:5], v[4:5], 4, s[16:17]
	global_load_dwordx4 v[148:151], v[2:3], off
	global_load_dwordx4 v[152:155], v[4:5], off
	v_add_u32_e32 v2, 0x700, v210
	v_lshlrev_b32_e32 v3, 1, v2
	v_and_or_b32 v220, v2, s40, v144
	v_add_u32_e32 v0, 0xc00, v0
	v_and_b32_e32 v219, 0xfffffc00, v3
	v_or_b32_e32 v200, 0x200, v220
	v_ashrrev_i32_e32 v1, 31, v0
	v_or_b32_e32 v2, v200, v219
	v_lshl_add_u64 v[0:1], v[0:1], 4, s[16:17]
	v_ashrrev_i32_e32 v3, 31, v2
	v_cvt_pk_bf16_f32 v65, v156, v157
	v_cvt_pk_bf16_f32 v66, v158, v159
	v_lshl_add_u64 v[2:3], v[2:3], 4, s[16:17]
	global_load_dwordx4 v[156:159], v[0:1], off
	global_load_dwordx4 v[202:205], v[2:3], off
	v_cvt_pk_bf16_f32 v83, v126, v127
	v_cvt_pk_bf16_f32 v126, v94, v95
	v_cvt_pk_bf16_f32 v94, v193, v195
	v_lshlrev_b32_e32 v193, 4, v144
	ds_read_b128 v[0:3], v193
	v_cvt_pk_bf16_f32 v67, v88, v89
	v_cvt_pk_bf16_f32 v88, v8, v9
	v_div_scale_f32 v8, s[18:19], v147, v147, 1.0
	v_cvt_pk_bf16_f32 v95, v6, v7
	v_rcp_f32_e32 v9, v8
	ds_read_b128 v[4:7], v193 offset:8192
	v_cvt_pk_bf16_f32 v84, v112, v113
	v_cvt_pk_bf16_f32 v85, v114, v115
	v_cvt_pk_bf16_f32 v86, v116, v117
	v_cvt_pk_bf16_f32 v87, v118, v119
	v_cvt_pk_bf16_f32 v116, v48, v49
	v_cvt_pk_bf16_f32 v117, v50, v51
	v_cvt_pk_bf16_f32 v118, v52, v53
	v_cvt_pk_bf16_f32 v119, v54, v55
	v_cvt_pk_bf16_f32 v112, v56, v57
	v_cvt_pk_bf16_f32 v113, v58, v59
	v_cvt_pk_bf16_f32 v114, v60, v61
	v_cvt_pk_bf16_f32 v115, v62, v63
	s_waitcnt lgkmcnt(1)
	v_mfma_f32_32x32x16_bf16 v[48:63], v[0:3], v[84:87], 0
	v_fma_f32 v0, -v8, v9, 1.0
	v_cvt_pk_bf16_f32 v89, v10, v11
	v_fmac_f32_e32 v9, v0, v9
	v_div_scale_f32 v10, vcc, 1.0, v147, 1.0
	v_mul_f32_e32 v11, v10, v9
	ds_read_b128 v[0:3], v193 offset:16384
	v_cvt_pk_bf16_f32 v82, v124, v125
	v_cvt_pk_bf16_f32 v124, v90, v91
	v_cvt_pk_bf16_f32 v90, v12, v13
	v_fma_f32 v12, -v8, v11, v10
	v_fmac_f32_e32 v11, v12, v9
	v_cvt_pk_bf16_f32 v81, v122, v123
	v_cvt_pk_bf16_f32 v74, v108, v109
	v_cvt_pk_bf16_f32 v75, v110, v111
	v_cvt_pk_bf16_f32 v122, v103, v104
	v_cvt_pk_bf16_f32 v123, v105, v106
	v_cvt_pk_bf16_f32 v108, v32, v33
	v_cvt_pk_bf16_f32 v109, v34, v35
	v_cvt_pk_bf16_f32 v110, v36, v37
	v_cvt_pk_bf16_f32 v111, v38, v39
	v_cvt_pk_bf16_f32 v104, v40, v41
	v_cvt_pk_bf16_f32 v105, v42, v43
	v_cvt_pk_bf16_f32 v106, v44, v45
	v_cvt_pk_bf16_f32 v107, v46, v47
	s_waitcnt lgkmcnt(1)
	v_mfma_f32_32x32x16_bf16 v[32:47], v[4:7], v[84:87], 0
	v_fma_f32 v4, -v8, v11, v10
	v_div_fmas_f32 v4, v4, v9, v11
	v_cvt_pk_bf16_f32 v125, v92, v93
	v_cvt_pk_bf16_f32 v92, v160, v180
	v_div_fixup_f32 v180, v4, v147, 1.0
	ds_read_b128 v[4:7], v193 offset:24576
	v_lshrrev_b32_e32 v8, 6, v210
	v_cvt_pk_bf16_f32 v80, v120, v121
	v_cvt_pk_bf16_f32 v127, v96, v97
	v_cvt_pk_bf16_f32 v120, v99, v100
	v_cvt_pk_bf16_f32 v121, v101, v102
	v_cvt_pk_bf16_f32 v100, v16, v17
	v_cvt_pk_bf16_f32 v101, v18, v19
	v_cvt_pk_bf16_f32 v102, v20, v21
	v_cvt_pk_bf16_f32 v103, v22, v23
	v_cvt_pk_bf16_f32 v96, v24, v25
	v_cvt_pk_bf16_f32 v97, v26, v27
	v_cvt_pk_bf16_f32 v98, v28, v29
	v_cvt_pk_bf16_f32 v99, v30, v31
	s_waitcnt lgkmcnt(1)
	v_mfma_f32_32x32x16_bf16 v[16:31], v[0:3], v[84:87], 0
	v_add_u32_e32 v0, v8, v146
	v_lshl_add_u32 v0, v0, 5, s43
	v_and_or_b32 v0, v210, 31, v0
	v_lshl_or_b32 v0, v0, 10, s44
	v_ashrrev_i32_e32 v1, 31, v0
	v_cvt_pk_bf16_f32 v93, v182, v183
	v_cvt_pk_bf16_f32 v91, v14, v15
	v_lshl_add_u64 v[182:183], v[0:1], 1, s[14:15]
	v_lshlrev_b32_e32 v195, 4, v210
	s_waitcnt lgkmcnt(0)
	v_mfma_f32_32x32x16_bf16 v[0:15], v[4:7], v[84:87], 0
	ds_read_b128 v[144:147], v193 offset:1024
	ds_read_b128 v[206:209], v193 offset:9216
	s_waitcnt lgkmcnt(1)
	v_mfma_f32_32x32x16_bf16 v[48:63], v[144:147], v[80:83], v[48:63]
	s_waitcnt lgkmcnt(0)
	v_mfma_f32_32x32x16_bf16 v[32:47], v[206:209], v[80:83], v[32:47]
	ds_read_b128 v[144:147], v193 offset:17408
	ds_read_b128 v[206:209], v193 offset:25600
	s_waitcnt lgkmcnt(1)
	v_mfma_f32_32x32x16_bf16 v[16:31], v[144:147], v[80:83], v[16:31]
	s_waitcnt lgkmcnt(0)
; #define MFMA32(a, b, c) __builtin_amdgcn_mfma_f32_32x32x16_bf16((a), (b), (c), 0, 0, 0)
; #define LOADV(v_, tid) do { _Pragma("unroll") for (int i = 0; i < 8; ++i) { const int idx = tid + i * 256, f = idx >> 6; \
;     sr[i] = VTg[(((v_) >> 1) * 4 + (f >> 3)) * 1024 + (((v_) & 1) * 8 + (f & 7)) * 64 + (idx & 63)]; } } while (0)
; #define STOREV(tid) do { _Pragma("unroll") for (int i = 0; i < 8; ++i) vbuf[tid + i * 256] = sr[i]; } while (0)
; DI void attn_prompt_block(const Params& p, int l, int b, int hh, int tt4, char* smem, bfr* Obuf) {
;     ...
;   f32x16 o[4];
; #pragma unroll
;   for (int v = 0; v < 4; ++v) {
;     if (v < 3) LOADV(v + 1, tidv);
;     if ((v & 1) == 0) {
; #pragma unroll
;       for (int d = 0; d < 4; ++d)
; #pragma unroll
;         for (int q = 0; q < 16; ++q) o[d][q] = 0.f;
;     }
; #pragma unroll
;     for (int kk = 0; kk < 8; ++kk)
; #pragma unroll
;       for (int d = 0; d < 4; ++d) {
;         bf16x8 vf = __builtin_bit_cast(bf16x8, vbuf[(d * 8 + kk) * 64 + lanev]);
;         o[d] = MFMA32(vf, pb[((v & 1) * 8 + kk) >> 1][kk & 1], o[d]);
;         if (d == 3) __builtin_amdgcn_sched_barrier(0);
;       }
;     if (v & 1) {
; #pragma unroll
;       for (int d = 0; d < 4; ++d)
; #pragma unroll
;         for (int g4 = 0; g4 < 4; ++g4) {
;           int dim = ((v >> 1) * 4 + d) * 32 + 8 * g4 + 4 * hlv;
;           uint2 ov;
;           ov.x = pack2(o[d][g4 * 4 + 0] * inv, o[d][g4 * 4 + 1] * inv);
;           ov.y = pack2(o[d][g4 * 4 + 2] * inv, o[d][g4 * 4 + 3] * inv);
;           *(uint2*)(Obuf + ooff + dim) = ov;
;         }
;     }
;     __syncthreads();
;     if (v < 3) { STOREV(tidv); __syncthreads(); }
	v_mfma_f32_32x32x16_bf16 v[0:15], v[206:209], v[80:83], v[0:15]
	ds_read_b128 v[144:147], v193 offset:2048
	ds_read_b128 v[206:209], v193 offset:10240
	s_waitcnt lgkmcnt(1)
	v_mfma_f32_32x32x16_bf16 v[48:63], v[144:147], v[76:79], v[48:63]
	s_waitcnt lgkmcnt(0)
	v_mfma_f32_32x32x16_bf16 v[32:47], v[206:209], v[76:79], v[32:47]
	ds_read_b128 v[144:147], v193 offset:18432
	ds_read_b128 v[206:209], v193 offset:26624
	s_waitcnt lgkmcnt(1)
	v_mfma_f32_32x32x16_bf16 v[16:31], v[144:147], v[76:79], v[16:31]
	s_waitcnt lgkmcnt(0)
	v_mfma_f32_32x32x16_bf16 v[0:15], v[206:209], v[76:79], v[0:15]
	ds_read_b128 v[144:147], v193 offset:3072
	ds_read_b128 v[206:209], v193 offset:11264
	s_waitcnt lgkmcnt(1)
	v_mfma_f32_32x32x16_bf16 v[48:63], v[144:147], v[72:75], v[48:63]
	s_waitcnt lgkmcnt(0)
	v_mfma_f32_32x32x16_bf16 v[32:47], v[206:209], v[72:75], v[32:47]
	ds_read_b128 v[144:147], v193 offset:19456
	ds_read_b128 v[206:209], v193 offset:27648
	s_waitcnt lgkmcnt(1)
	v_mfma_f32_32x32x16_bf16 v[16:31], v[144:147], v[72:75], v[16:31]
	s_waitcnt lgkmcnt(0)
	v_mfma_f32_32x32x16_bf16 v[0:15], v[206:209], v[72:75], v[0:15]
	ds_read_b128 v[144:147], v193 offset:4096
	ds_read_b128 v[206:209], v193 offset:12288
	s_waitcnt lgkmcnt(1)
	v_mfma_f32_32x32x16_bf16 v[48:63], v[144:147], v[68:71], v[48:63]
	s_waitcnt lgkmcnt(0)
	v_mfma_f32_32x32x16_bf16 v[32:47], v[206:209], v[68:71], v[32:47]
	ds_read_b128 v[144:147], v193 offset:20480
	ds_read_b128 v[206:209], v193 offset:28672
	s_waitcnt lgkmcnt(1)
	v_mfma_f32_32x32x16_bf16 v[16:31], v[144:147], v[68:71], v[16:31]
	s_waitcnt lgkmcnt(0)
	v_mfma_f32_32x32x16_bf16 v[0:15], v[206:209], v[68:71], v[0:15]
	ds_read_b128 v[144:147], v193 offset:5120
	ds_read_b128 v[206:209], v193 offset:13312
	s_waitcnt lgkmcnt(1)
	v_mfma_f32_32x32x16_bf16 v[48:63], v[144:147], v[64:67], v[48:63]
	s_waitcnt lgkmcnt(0)
	v_mfma_f32_32x32x16_bf16 v[32:47], v[206:209], v[64:67], v[32:47]
	ds_read_b128 v[144:147], v193 offset:21504
	ds_read_b128 v[206:209], v193 offset:29696
	s_waitcnt lgkmcnt(1)
	v_mfma_f32_32x32x16_bf16 v[16:31], v[144:147], v[64:67], v[16:31]
	s_waitcnt lgkmcnt(0)
	v_mfma_f32_32x32x16_bf16 v[0:15], v[206:209], v[64:67], v[0:15]
	ds_read_b128 v[144:147], v193 offset:6144
	ds_read_b128 v[206:209], v193 offset:14336
	s_waitcnt lgkmcnt(1)
	v_mfma_f32_32x32x16_bf16 v[48:63], v[144:147], v[124:127], v[48:63]
	s_waitcnt lgkmcnt(0)
	v_mfma_f32_32x32x16_bf16 v[32:47], v[206:209], v[124:127], v[32:47]
	ds_read_b128 v[144:147], v193 offset:22528
	ds_read_b128 v[206:209], v193 offset:30720
	s_waitcnt lgkmcnt(1)
	v_mfma_f32_32x32x16_bf16 v[16:31], v[144:147], v[124:127], v[16:31]
	s_waitcnt lgkmcnt(0)
	v_mfma_f32_32x32x16_bf16 v[0:15], v[206:209], v[124:127], v[0:15]
	ds_read_b128 v[144:147], v193 offset:7168
	ds_read_b128 v[206:209], v193 offset:15360
	s_waitcnt lgkmcnt(1)
	v_mfma_f32_32x32x16_bf16 v[48:63], v[144:147], v[120:123], v[48:63]
	s_waitcnt lgkmcnt(0)
	v_mfma_f32_32x32x16_bf16 v[32:47], v[206:209], v[120:123], v[32:47]
	ds_read_b128 v[144:147], v193 offset:23552
	ds_read_b128 v[206:209], v193 offset:31744
	s_waitcnt lgkmcnt(1)
	v_mfma_f32_32x32x16_bf16 v[16:31], v[144:147], v[120:123], v[16:31]
	s_waitcnt lgkmcnt(0)
	v_mfma_f32_32x32x16_bf16 v[0:15], v[206:209], v[120:123], v[0:15]
	v_add_u32_e32 v221, 0x1000, v211
	v_add_u32_e32 v213, 0x1000, v213
	s_barrier
	s_waitcnt vmcnt(7)
	ds_write_b128 v195, v[128:131]
	s_waitcnt vmcnt(6)
	ds_write_b128 v195, v[132:135] offset:4096
	s_waitcnt vmcnt(5)
	ds_write_b128 v195, v[136:139] offset:8192
	s_waitcnt vmcnt(4)
	ds_write_b128 v195, v[140:143] offset:12288
	s_waitcnt vmcnt(3)
	ds_write_b128 v195, v[148:151] offset:16384
	s_waitcnt vmcnt(2)
	ds_write_b128 v195, v[152:155] offset:20480
	s_waitcnt vmcnt(1)
	ds_write_b128 v195, v[156:159] offset:24576
	s_waitcnt vmcnt(0)
	ds_write_b128 v195, v[202:205] offset:28672
	v_or_b32_e32 v128, v221, v212
	v_or_b32_e32 v130, v214, v213
	v_ashrrev_i32_e32 v129, 31, v128
	v_ashrrev_i32_e32 v131, 31, v130
	v_lshl_add_u64 v[128:129], v[128:129], 4, s[16:17]
	v_lshl_add_u64 v[132:133], v[130:131], 4, s[16:17]
	s_waitcnt lgkmcnt(0)
	s_barrier
	global_load_dwordx4 v[128:131], v[128:129], off
	s_nop 0
	global_load_dwordx4 v[132:135], v[132:133], off
	ds_read_b128 v[144:147], v193
	v_add_u32_e32 v214, 0x1400, v211
	v_add_u32_e32 v215, 0x1000, v215
	v_or_b32_e32 v136, v214, v212
	v_or_b32_e32 v138, v216, v215
	v_ashrrev_i32_e32 v137, 31, v136
	v_ashrrev_i32_e32 v139, 31, v138
	v_add_u32_e32 v216, 0x1800, v211
	v_add_u32_e32 v217, 0x1000, v217
	v_lshl_add_u64 v[136:137], v[136:137], 4, s[16:17]
	v_lshl_add_u64 v[140:141], v[138:139], 4, s[16:17]
	v_or_b32_e32 v148, v216, v212
	v_or_b32_e32 v150, v218, v217
	global_load_dwordx4 v[136:139], v[136:137], off
	s_nop 0
	global_load_dwordx4 v[140:143], v[140:141], off
	v_ashrrev_i32_e32 v149, 31, v148
	ds_read_b128 v[152:155], v193 offset:8192
	v_ashrrev_i32_e32 v151, 31, v150
	v_lshl_add_u64 v[148:149], v[148:149], 4, s[16:17]
	v_lshl_add_u64 v[150:151], v[150:151], 4, s[16:17]
	s_waitcnt lgkmcnt(1)
	v_mfma_f32_32x32x16_bf16 v[48:63], v[144:147], v[116:119], v[48:63]
	global_load_dwordx4 v[144:147], v[148:149], off
	s_nop 0
	global_load_dwordx4 v[148:151], v[150:151], off
	ds_read_b128 v[156:159], v193 offset:16384
	v_add_u32_e32 v211, 0x1c00, v211
	v_or_b32_e32 v202, v211, v212
	v_add_u32_e32 v212, 0x1000, v219
	v_ashrrev_i32_e32 v203, 31, v202
	s_waitcnt lgkmcnt(1)
	v_mfma_f32_32x32x16_bf16 v[32:47], v[152:155], v[116:119], v[32:47]
	v_or_b32_e32 v154, v220, v212
	v_lshl_add_u64 v[152:153], v[202:203], 4, s[16:17]
	v_ashrrev_i32_e32 v155, 31, v154
	v_lshl_add_u64 v[206:207], v[154:155], 4, s[16:17]
	ds_read_b128 v[202:205], v193 offset:24576
	s_waitcnt lgkmcnt(1)
; #define MFMA32(a, b, c) __builtin_amdgcn_mfma_f32_32x32x16_bf16((a), (b), (c), 0, 0, 0)
; #define LOADV(v_, tid) do { _Pragma("unroll") for (int i = 0; i < 8; ++i) { const int idx = tid + i * 256, f = idx >> 6; \
;     sr[i] = VTg[(((v_) >> 1) * 4 + (f >> 3)) * 1024 + (((v_) & 1) * 8 + (f & 7)) * 64 + (idx & 63)]; } } while (0)
; DI void attn_prompt_block(const Params& p, int l, int b, int hh, int tt4, char* smem, bfr* Obuf) {
;     ...
;   for (int v = 0; v < 4; ++v) {
;     if (v < 3) LOADV(v + 1, tidv);
;     if ((v & 1) == 0) {
; #pragma unroll
;       for (int d = 0; d < 4; ++d)
; #pragma unroll
;         for (int q = 0; q < 16; ++q) o[d][q] = 0.f;
;     }
; #pragma unroll
;     for (int kk = 0; kk < 8; ++kk)
; #pragma unroll
;       for (int d = 0; d < 4; ++d) {
;         bf16x8 vf = __builtin_bit_cast(bf16x8, vbuf[(d * 8 + kk) * 64 + lanev]);
;         o[d] = MFMA32(vf, pb[((v & 1) * 8 + kk) >> 1][kk & 1], o[d]);
;         if (d == 3) __builtin_amdgcn_sched_barrier(0);
;       }
;     if (v & 1) {
; #pragma unroll
;       for (int d = 0; d < 4; ++d)
; #pragma unroll
;         for (int g4 = 0; g4 < 4; ++g4) {
;           int dim = ((v >> 1) * 4 + d) * 32 + 8 * g4 + 4 * hlv;
;           uint2 ov;
;           ov.x = pack2(o[d][g4 * 4 + 0] * inv, o[d][g4 * 4 + 1] * inv);
;           ov.y = pack2(o[d][g4 * 4 + 2] * inv, o[d][g4 * 4 + 3] * inv);
;           *(uint2*)(Obuf + ooff + dim) = ov;
;         }
;     }
	v_mfma_f32_32x32x16_bf16 v[16:31], v[156:159], v[116:119], v[16:31]
	global_load_dwordx4 v[152:155], v[152:153], off
	s_nop 0
	global_load_dwordx4 v[156:159], v[206:207], off
	s_waitcnt lgkmcnt(0)
	v_mfma_f32_32x32x16_bf16 v[0:15], v[202:205], v[116:119], v[0:15]
	ds_read_b128 v[202:205], v193 offset:1024
	ds_read_b128 v[206:209], v193 offset:9216
	s_waitcnt lgkmcnt(1)
	v_mfma_f32_32x32x16_bf16 v[48:63], v[202:205], v[112:115], v[48:63]
	s_waitcnt lgkmcnt(0)
	v_mfma_f32_32x32x16_bf16 v[32:47], v[206:209], v[112:115], v[32:47]
	ds_read_b128 v[202:205], v193 offset:17408
	ds_read_b128 v[206:209], v193 offset:25600
	s_waitcnt lgkmcnt(1)
	v_mfma_f32_32x32x16_bf16 v[16:31], v[202:205], v[112:115], v[16:31]
	s_waitcnt lgkmcnt(0)
	v_mfma_f32_32x32x16_bf16 v[0:15], v[206:209], v[112:115], v[0:15]
	ds_read_b128 v[202:205], v193 offset:2048
	ds_read_b128 v[206:209], v193 offset:10240
	s_waitcnt lgkmcnt(1)
	v_mfma_f32_32x32x16_bf16 v[48:63], v[202:205], v[108:111], v[48:63]
	s_waitcnt lgkmcnt(0)
	v_mfma_f32_32x32x16_bf16 v[32:47], v[206:209], v[108:111], v[32:47]
	ds_read_b128 v[202:205], v193 offset:18432
	ds_read_b128 v[206:209], v193 offset:26624
	s_waitcnt lgkmcnt(1)
	v_mfma_f32_32x32x16_bf16 v[16:31], v[202:205], v[108:111], v[16:31]
	s_waitcnt lgkmcnt(0)
	v_mfma_f32_32x32x16_bf16 v[0:15], v[206:209], v[108:111], v[0:15]
	ds_read_b128 v[202:205], v193 offset:3072
	ds_read_b128 v[206:209], v193 offset:11264
	s_waitcnt lgkmcnt(1)
	v_mfma_f32_32x32x16_bf16 v[48:63], v[202:205], v[104:107], v[48:63]
	s_waitcnt lgkmcnt(0)
	v_mfma_f32_32x32x16_bf16 v[32:47], v[206:209], v[104:107], v[32:47]
	ds_read_b128 v[202:205], v193 offset:19456
	ds_read_b128 v[206:209], v193 offset:27648
	s_waitcnt lgkmcnt(1)
	v_mfma_f32_32x32x16_bf16 v[16:31], v[202:205], v[104:107], v[16:31]
	s_waitcnt lgkmcnt(0)
	v_mfma_f32_32x32x16_bf16 v[0:15], v[206:209], v[104:107], v[0:15]
	ds_read_b128 v[202:205], v193 offset:4096
	ds_read_b128 v[206:209], v193 offset:12288
	s_waitcnt lgkmcnt(1)
	v_mfma_f32_32x32x16_bf16 v[48:63], v[202:205], v[100:103], v[48:63]
	s_waitcnt lgkmcnt(0)
	v_mfma_f32_32x32x16_bf16 v[32:47], v[206:209], v[100:103], v[32:47]
	ds_read_b128 v[202:205], v193 offset:20480
	ds_read_b128 v[206:209], v193 offset:28672
	s_waitcnt lgkmcnt(1)
	v_mfma_f32_32x32x16_bf16 v[16:31], v[202:205], v[100:103], v[16:31]
	s_waitcnt lgkmcnt(0)
	v_mfma_f32_32x32x16_bf16 v[0:15], v[206:209], v[100:103], v[0:15]
	ds_read_b128 v[202:205], v193 offset:5120
	ds_read_b128 v[206:209], v193 offset:13312
	s_waitcnt lgkmcnt(1)
	v_mfma_f32_32x32x16_bf16 v[48:63], v[202:205], v[96:99], v[48:63]
	s_waitcnt lgkmcnt(0)
	v_mfma_f32_32x32x16_bf16 v[32:47], v[206:209], v[96:99], v[32:47]
	ds_read_b128 v[202:205], v193 offset:21504
	ds_read_b128 v[206:209], v193 offset:29696
	s_waitcnt lgkmcnt(1)
	v_mfma_f32_32x32x16_bf16 v[16:31], v[202:205], v[96:99], v[16:31]
	s_waitcnt lgkmcnt(0)
	v_mfma_f32_32x32x16_bf16 v[0:15], v[206:209], v[96:99], v[0:15]
	ds_read_b128 v[202:205], v193 offset:6144
	ds_read_b128 v[206:209], v193 offset:14336
	s_waitcnt lgkmcnt(1)
	v_mfma_f32_32x32x16_bf16 v[48:63], v[202:205], v[92:95], v[48:63]
	s_waitcnt lgkmcnt(0)
	v_mfma_f32_32x32x16_bf16 v[32:47], v[206:209], v[92:95], v[32:47]
	ds_read_b128 v[202:205], v193 offset:22528
	ds_read_b128 v[206:209], v193 offset:30720
	s_waitcnt lgkmcnt(1)
	v_mfma_f32_32x32x16_bf16 v[16:31], v[202:205], v[92:95], v[16:31]
	s_waitcnt lgkmcnt(0)
	v_mfma_f32_32x32x16_bf16 v[0:15], v[206:209], v[92:95], v[0:15]
	ds_read_b128 v[202:205], v193 offset:7168
	ds_read_b128 v[206:209], v193 offset:15360
	s_waitcnt lgkmcnt(1)
	v_mfma_f32_32x32x16_bf16 v[48:63], v[202:205], v[88:91], v[48:63]
	s_waitcnt lgkmcnt(0)
	v_mfma_f32_32x32x16_bf16 v[32:47], v[206:209], v[88:91], v[32:47]
	ds_read_b128 v[202:205], v193 offset:23552
	ds_read_b128 v[206:209], v193 offset:31744
	s_waitcnt lgkmcnt(1)
	v_mfma_f32_32x32x16_bf16 v[16:31], v[202:205], v[88:91], v[16:31]
	s_waitcnt lgkmcnt(0)
	v_mfma_f32_32x32x16_bf16 v[0:15], v[206:209], v[88:91], v[0:15]
	s_nop 3
	v_mul_f32_e64 v48, v48, v180
	v_mul_f32_e64 v49, v49, v180
	v_mul_f32_e64 v50, v50, v180
	v_mul_f32_e64 v51, v51, v180
	v_cvt_pk_bf16_f32 v48, v48, v49
	v_cvt_pk_bf16_f32 v49, v50, v51
	v_lshrrev_b32_e32 v50, 2, v210
	v_and_b32_e32 v160, 8, v50
	v_pk_mul_f32 v[0:1], v[0:1], v[180:181] op_sel_hi:[1,0]
	v_pk_mul_f32 v[2:3], v[2:3], v[180:181] op_sel_hi:[1,0]
	v_lshl_add_u64 v[182:183], v[182:183], 0, v[160:161]
	v_cvt_pk_bf16_f32 v0, v0, v1
	v_cvt_pk_bf16_f32 v1, v2, v3
	global_store_dwordx2 v[182:183], v[0:1], off offset:192 sc1
	v_pk_mul_f32 v[0:1], v[4:5], v[180:181] op_sel_hi:[1,0]
	v_pk_mul_f32 v[2:3], v[6:7], v[180:181] op_sel_hi:[1,0]
	v_pk_mul_f32 v[32:33], v[32:33], v[180:181] op_sel_hi:[1,0]
	v_pk_mul_f32 v[34:35], v[34:35], v[180:181] op_sel_hi:[1,0]
	v_pk_mul_f32 v[16:17], v[16:17], v[180:181] op_sel_hi:[1,0]
	v_pk_mul_f32 v[18:19], v[18:19], v[180:181] op_sel_hi:[1,0]
	v_cvt_pk_bf16_f32 v0, v0, v1
	v_cvt_pk_bf16_f32 v1, v2, v3
	v_cvt_pk_bf16_f32 v32, v32, v33
	v_cvt_pk_bf16_f32 v33, v34, v35
	v_cvt_pk_bf16_f32 v16, v16, v17
	v_cvt_pk_bf16_f32 v17, v18, v19
	global_store_dwordx2 v[182:183], v[0:1], off offset:208 sc1
	v_pk_mul_f32 v[0:1], v[8:9], v[180:181] op_sel_hi:[1,0]
	v_pk_mul_f32 v[2:3], v[10:11], v[180:181] op_sel_hi:[1,0]
	global_store_dwordx2 v[182:183], v[48:49], off sc1
	v_pk_mul_f32 v[48:49], v[52:53], v[180:181] op_sel_hi:[1,0]
	v_pk_mul_f32 v[50:51], v[54:55], v[180:181] op_sel_hi:[1,0]
	global_store_dwordx2 v[182:183], v[32:33], off offset:64 sc1
	v_pk_mul_f32 v[32:33], v[36:37], v[180:181] op_sel_hi:[1,0]
	v_pk_mul_f32 v[34:35], v[38:39], v[180:181] op_sel_hi:[1,0]
; #define STOREV(tid) do { _Pragma("unroll") for (int i = 0; i < 8; ++i) vbuf[tid + i * 256] = sr[i]; } while (0)
; DI void attn_prompt_block(const Params& p, int l, int b, int hh, int tt4, char* smem, bfr* Obuf) {
;     ...
;     if (v & 1) {
; #pragma unroll
;       for (int d = 0; d < 4; ++d)
; #pragma unroll
;         for (int g4 = 0; g4 < 4; ++g4) {
;           int dim = ((v >> 1) * 4 + d) * 32 + 8 * g4 + 4 * hlv;
;           uint2 ov;
;           ov.x = pack2(o[d][g4 * 4 + 0] * inv, o[d][g4 * 4 + 1] * inv);
;           ov.y = pack2(o[d][g4 * 4 + 2] * inv, o[d][g4 * 4 + 3] * inv);
;           *(uint2*)(Obuf + ooff + dim) = ov;
;         }
;     }
;     __syncthreads();
;     if (v < 3) { STOREV(tidv); __syncthreads(); }
	global_store_dwordx2 v[182:183], v[16:17], off offset:128 sc1
	v_pk_mul_f32 v[16:17], v[20:21], v[180:181] op_sel_hi:[1,0]
	v_pk_mul_f32 v[18:19], v[22:23], v[180:181] op_sel_hi:[1,0]
	v_cvt_pk_bf16_f32 v0, v0, v1
	v_cvt_pk_bf16_f32 v1, v2, v3
	v_cvt_pk_bf16_f32 v48, v48, v49
	v_cvt_pk_bf16_f32 v49, v50, v51
	v_cvt_pk_bf16_f32 v32, v32, v33
	v_cvt_pk_bf16_f32 v33, v34, v35
	v_cvt_pk_bf16_f32 v16, v16, v17
	v_cvt_pk_bf16_f32 v17, v18, v19
	global_store_dwordx2 v[182:183], v[0:1], off offset:224 sc1
	v_pk_mul_f32 v[0:1], v[12:13], v[180:181] op_sel_hi:[1,0]
	v_pk_mul_f32 v[2:3], v[14:15], v[180:181] op_sel_hi:[1,0]
	global_store_dwordx2 v[182:183], v[48:49], off offset:16 sc1
	v_pk_mul_f32 v[48:49], v[56:57], v[180:181] op_sel_hi:[1,0]
	v_pk_mul_f32 v[50:51], v[58:59], v[180:181] op_sel_hi:[1,0]
	global_store_dwordx2 v[182:183], v[32:33], off offset:80 sc1
	v_pk_mul_f32 v[32:33], v[40:41], v[180:181] op_sel_hi:[1,0]
	v_pk_mul_f32 v[34:35], v[42:43], v[180:181] op_sel_hi:[1,0]
	global_store_dwordx2 v[182:183], v[16:17], off offset:144 sc1
	v_pk_mul_f32 v[16:17], v[24:25], v[180:181] op_sel_hi:[1,0]
	v_pk_mul_f32 v[18:19], v[26:27], v[180:181] op_sel_hi:[1,0]
	v_cvt_pk_bf16_f32 v0, v0, v1
	v_cvt_pk_bf16_f32 v1, v2, v3
	v_cvt_pk_bf16_f32 v48, v48, v49
	v_cvt_pk_bf16_f32 v49, v50, v51
	v_cvt_pk_bf16_f32 v32, v32, v33
	v_cvt_pk_bf16_f32 v33, v34, v35
	v_cvt_pk_bf16_f32 v16, v16, v17
	v_cvt_pk_bf16_f32 v17, v18, v19
	global_store_dwordx2 v[182:183], v[0:1], off offset:240 sc1
	v_or_b32_e32 v0, v194, v221
	global_store_dwordx2 v[182:183], v[48:49], off offset:32 sc1
	v_pk_mul_f32 v[48:49], v[60:61], v[180:181] op_sel_hi:[1,0]
	v_pk_mul_f32 v[50:51], v[62:63], v[180:181] op_sel_hi:[1,0]
	global_store_dwordx2 v[182:183], v[32:33], off offset:96 sc1
	v_pk_mul_f32 v[32:33], v[44:45], v[180:181] op_sel_hi:[1,0]
	v_pk_mul_f32 v[34:35], v[46:47], v[180:181] op_sel_hi:[1,0]
	global_store_dwordx2 v[182:183], v[16:17], off offset:160 sc1
	v_pk_mul_f32 v[16:17], v[28:29], v[180:181] op_sel_hi:[1,0]
	v_pk_mul_f32 v[18:19], v[30:31], v[180:181] op_sel_hi:[1,0]
	v_ashrrev_i32_e32 v1, 31, v0
	v_or_b32_e32 v2, v213, v201
	v_cvt_pk_bf16_f32 v48, v48, v49
	v_cvt_pk_bf16_f32 v49, v50, v51
	v_cvt_pk_bf16_f32 v32, v32, v33
	v_cvt_pk_bf16_f32 v33, v34, v35
	v_cvt_pk_bf16_f32 v16, v16, v17
	v_cvt_pk_bf16_f32 v17, v18, v19
	v_lshl_add_u64 v[0:1], v[0:1], 4, s[16:17]
	v_ashrrev_i32_e32 v3, 31, v2
	global_store_dwordx2 v[182:183], v[48:49], off offset:48 sc1
	global_store_dwordx2 v[182:183], v[32:33], off offset:112 sc1
	global_store_dwordx2 v[182:183], v[16:17], off offset:176 sc1
	s_barrier
	s_waitcnt vmcnt(23)
	ds_write_b128 v195, v[128:131]
	s_waitcnt vmcnt(22)
	ds_write_b128 v195, v[132:135] offset:4096
	s_waitcnt vmcnt(21)
	ds_write_b128 v195, v[136:139] offset:8192
	s_waitcnt vmcnt(20)
	ds_write_b128 v195, v[140:143] offset:12288
	s_waitcnt vmcnt(19)
	ds_write_b128 v195, v[144:147] offset:16384
	s_waitcnt vmcnt(18)
	ds_write_b128 v195, v[148:151] offset:20480
	s_waitcnt vmcnt(17)
	ds_write_b128 v195, v[152:155] offset:24576
	s_waitcnt vmcnt(16)
	ds_write_b128 v195, v[156:159] offset:28672
	s_waitcnt lgkmcnt(0)
	s_barrier
	v_lshl_add_u64 v[2:3], v[2:3], 4, s[16:17]
	global_load_dwordx4 v[128:131], v[0:1], off
	global_load_dwordx4 v[132:135], v[2:3], off
	v_or_b32_e32 v0, v194, v214
	v_or_b32_e32 v6, v215, v197
	v_ashrrev_i32_e32 v1, 31, v0
	v_ashrrev_i32_e32 v7, 31, v6
	v_lshl_add_u64 v[4:5], v[0:1], 4, s[16:17]
	v_lshl_add_u64 v[6:7], v[6:7], 4, s[16:17]
	ds_read_b128 v[0:3], v193
	global_load_dwordx4 v[136:139], v[4:5], off
	global_load_dwordx4 v[140:143], v[6:7], off
	ds_read_b128 v[4:7], v193 offset:8192
	v_or_b32_e32 v8, v194, v216
	s_waitcnt lgkmcnt(0)
	v_mfma_f32_32x32x16_bf16 v[32:47], v[4:7], v[84:87], 0
	v_or_b32_e32 v4, v194, v211
	v_ashrrev_i32_e32 v9, 31, v8
	v_ashrrev_i32_e32 v5, 31, v4
	v_mfma_f32_32x32x16_bf16 v[48:63], v[0:3], v[84:87], 0
	v_or_b32_e32 v2, v217, v199
	v_lshl_add_u64 v[0:1], v[8:9], 4, s[16:17]
	v_ashrrev_i32_e32 v3, 31, v2
	v_lshl_add_u64 v[8:9], v[4:5], 4, s[16:17]
	v_or_b32_e32 v4, v212, v200
	v_lshl_add_u64 v[2:3], v[2:3], 4, s[16:17]
	v_ashrrev_i32_e32 v5, 31, v4
	global_load_dwordx4 v[144:147], v[0:1], off
	global_load_dwordx4 v[148:151], v[2:3], off
	ds_read_b128 v[0:3], v193 offset:16384
	v_lshl_add_u64 v[10:11], v[4:5], 4, s[16:17]
	ds_read_b128 v[4:7], v193 offset:24576
	global_load_dwordx4 v[152:155], v[8:9], off
	global_load_dwordx4 v[156:159], v[10:11], off
	s_waitcnt lgkmcnt(1)
	v_mfma_f32_32x32x16_bf16 v[16:31], v[0:3], v[84:87], 0
	s_waitcnt lgkmcnt(0)
	v_mfma_f32_32x32x16_bf16 v[0:15], v[4:7], v[84:87], 0
	ds_read_b128 v[84:87], v193 offset:1024
	ds_read_b128 v[200:203], v193 offset:9216
	s_waitcnt lgkmcnt(1)
	v_mfma_f32_32x32x16_bf16 v[48:63], v[84:87], v[80:83], v[48:63]
	s_waitcnt lgkmcnt(0)
	v_mfma_f32_32x32x16_bf16 v[32:47], v[200:203], v[80:83], v[32:47]
	ds_read_b128 v[84:87], v193 offset:17408
	ds_read_b128 v[200:203], v193 offset:25600
	s_waitcnt lgkmcnt(1)
	v_mfma_f32_32x32x16_bf16 v[16:31], v[84:87], v[80:83], v[16:31]
	s_waitcnt lgkmcnt(0)
	v_mfma_f32_32x32x16_bf16 v[0:15], v[200:203], v[80:83], v[0:15]
	ds_read_b128 v[80:83], v193 offset:2048
	ds_read_b128 v[84:87], v193 offset:10240
	s_waitcnt lgkmcnt(1)
	v_mfma_f32_32x32x16_bf16 v[48:63], v[80:83], v[76:79], v[48:63]
	s_waitcnt lgkmcnt(0)
	v_mfma_f32_32x32x16_bf16 v[32:47], v[84:87], v[76:79], v[32:47]
	ds_read_b128 v[80:83], v193 offset:18432
	ds_read_b128 v[84:87], v193 offset:26624
	s_waitcnt lgkmcnt(1)
	v_mfma_f32_32x32x16_bf16 v[16:31], v[80:83], v[76:79], v[16:31]
	s_waitcnt lgkmcnt(0)
; #define MFMA32(a, b, c) __builtin_amdgcn_mfma_f32_32x32x16_bf16((a), (b), (c), 0, 0, 0)
; #define LOADV(v_, tid) do { _Pragma("unroll") for (int i = 0; i < 8; ++i) { const int idx = tid + i * 256, f = idx >> 6; \
;     sr[i] = VTg[(((v_) >> 1) * 4 + (f >> 3)) * 1024 + (((v_) & 1) * 8 + (f & 7)) * 64 + (idx & 63)]; } } while (0)
; #define STOREV(tid) do { _Pragma("unroll") for (int i = 0; i < 8; ++i) vbuf[tid + i * 256] = sr[i]; } while (0)
; DI void attn_prompt_block(const Params& p, int l, int b, int hh, int tt4, char* smem, bfr* Obuf) {
;     ...
;   f32x16 o[4];
; #pragma unroll
;   for (int v = 0; v < 4; ++v) {
;     if (v < 3) LOADV(v + 1, tidv);
;     if ((v & 1) == 0) {
; #pragma unroll
;       for (int d = 0; d < 4; ++d)
; #pragma unroll
;         for (int q = 0; q < 16; ++q) o[d][q] = 0.f;
;     }
; #pragma unroll
;     for (int kk = 0; kk < 8; ++kk)
; #pragma unroll
;       for (int d = 0; d < 4; ++d) {
;         bf16x8 vf = __builtin_bit_cast(bf16x8, vbuf[(d * 8 + kk) * 64 + lanev]);
;         o[d] = MFMA32(vf, pb[((v & 1) * 8 + kk) >> 1][kk & 1], o[d]);
;         if (d == 3) __builtin_amdgcn_sched_barrier(0);
;       }
;     if (v & 1) {
; #pragma unroll
;       for (int d = 0; d < 4; ++d)
; #pragma unroll
;         for (int g4 = 0; g4 < 4; ++g4) {
;           int dim = ((v >> 1) * 4 + d) * 32 + 8 * g4 + 4 * hlv;
;           uint2 ov;
;           ov.x = pack2(o[d][g4 * 4 + 0] * inv, o[d][g4 * 4 + 1] * inv);
;           ov.y = pack2(o[d][g4 * 4 + 2] * inv, o[d][g4 * 4 + 3] * inv);
;           *(uint2*)(Obuf + ooff + dim) = ov;
;         }
;     }
;     __syncthreads();
;     if (v < 3) { STOREV(tidv); __syncthreads(); }
	v_mfma_f32_32x32x16_bf16 v[0:15], v[84:87], v[76:79], v[0:15]
	ds_read_b128 v[76:79], v193 offset:3072
	ds_read_b128 v[80:83], v193 offset:11264
	s_waitcnt lgkmcnt(1)
	v_mfma_f32_32x32x16_bf16 v[48:63], v[76:79], v[72:75], v[48:63]
	s_waitcnt lgkmcnt(0)
	v_mfma_f32_32x32x16_bf16 v[32:47], v[80:83], v[72:75], v[32:47]
	ds_read_b128 v[76:79], v193 offset:19456
	ds_read_b128 v[80:83], v193 offset:27648
	s_waitcnt lgkmcnt(1)
	v_mfma_f32_32x32x16_bf16 v[16:31], v[76:79], v[72:75], v[16:31]
	s_waitcnt lgkmcnt(0)
	v_mfma_f32_32x32x16_bf16 v[0:15], v[80:83], v[72:75], v[0:15]
	ds_read_b128 v[72:75], v193 offset:4096
	ds_read_b128 v[76:79], v193 offset:12288
	s_waitcnt lgkmcnt(1)
	v_mfma_f32_32x32x16_bf16 v[48:63], v[72:75], v[68:71], v[48:63]
	s_waitcnt lgkmcnt(0)
	v_mfma_f32_32x32x16_bf16 v[32:47], v[76:79], v[68:71], v[32:47]
	ds_read_b128 v[72:75], v193 offset:20480
	ds_read_b128 v[76:79], v193 offset:28672
	s_waitcnt lgkmcnt(1)
	v_mfma_f32_32x32x16_bf16 v[16:31], v[72:75], v[68:71], v[16:31]
	s_waitcnt lgkmcnt(0)
	v_mfma_f32_32x32x16_bf16 v[0:15], v[76:79], v[68:71], v[0:15]
	ds_read_b128 v[68:71], v193 offset:5120
	ds_read_b128 v[72:75], v193 offset:13312
	s_waitcnt lgkmcnt(1)
	v_mfma_f32_32x32x16_bf16 v[48:63], v[68:71], v[64:67], v[48:63]
	s_waitcnt lgkmcnt(0)
	v_mfma_f32_32x32x16_bf16 v[32:47], v[72:75], v[64:67], v[32:47]
	ds_read_b128 v[68:71], v193 offset:21504
	ds_read_b128 v[72:75], v193 offset:29696
	s_waitcnt lgkmcnt(1)
	v_mfma_f32_32x32x16_bf16 v[16:31], v[68:71], v[64:67], v[16:31]
	s_waitcnt lgkmcnt(0)
	v_mfma_f32_32x32x16_bf16 v[0:15], v[72:75], v[64:67], v[0:15]
	ds_read_b128 v[64:67], v193 offset:6144
	ds_read_b128 v[68:71], v193 offset:14336
	s_waitcnt lgkmcnt(1)
	v_mfma_f32_32x32x16_bf16 v[48:63], v[64:67], v[124:127], v[48:63]
	s_waitcnt lgkmcnt(0)
	v_mfma_f32_32x32x16_bf16 v[32:47], v[68:71], v[124:127], v[32:47]
	ds_read_b128 v[64:67], v193 offset:22528
	ds_read_b128 v[68:71], v193 offset:30720
	s_waitcnt lgkmcnt(1)
	v_mfma_f32_32x32x16_bf16 v[16:31], v[64:67], v[124:127], v[16:31]
	s_waitcnt lgkmcnt(0)
	v_mfma_f32_32x32x16_bf16 v[0:15], v[68:71], v[124:127], v[0:15]
	ds_read_b128 v[64:67], v193 offset:7168
	ds_read_b128 v[68:71], v193 offset:15360
	s_waitcnt lgkmcnt(1)
	v_mfma_f32_32x32x16_bf16 v[48:63], v[64:67], v[120:123], v[48:63]
	s_waitcnt lgkmcnt(0)
	v_mfma_f32_32x32x16_bf16 v[32:47], v[68:71], v[120:123], v[32:47]
	ds_read_b128 v[64:67], v193 offset:23552
	ds_read_b128 v[68:71], v193 offset:31744
	s_waitcnt lgkmcnt(1)
	v_mfma_f32_32x32x16_bf16 v[16:31], v[64:67], v[120:123], v[16:31]
	s_waitcnt lgkmcnt(0)
	v_mfma_f32_32x32x16_bf16 v[0:15], v[68:71], v[120:123], v[0:15]
	s_barrier
	s_waitcnt vmcnt(7)
	ds_write_b128 v195, v[128:131]
	s_waitcnt vmcnt(6)
	ds_write_b128 v195, v[132:135] offset:4096
	s_waitcnt vmcnt(5)
	ds_write_b128 v195, v[136:139] offset:8192
	s_waitcnt vmcnt(4)
	ds_write_b128 v195, v[140:143] offset:12288
	s_waitcnt vmcnt(3)
	ds_write_b128 v195, v[144:147] offset:16384
	s_waitcnt vmcnt(2)
	ds_write_b128 v195, v[148:151] offset:20480
	s_waitcnt vmcnt(1)
	ds_write_b128 v195, v[152:155] offset:24576
	s_waitcnt vmcnt(0)
	ds_write_b128 v195, v[156:159] offset:28672
	s_waitcnt lgkmcnt(0)
	s_barrier
	ds_read_b128 v[64:67], v193
	ds_read_b128 v[68:71], v193 offset:8192
	s_waitcnt lgkmcnt(1)
	v_mfma_f32_32x32x16_bf16 v[48:63], v[64:67], v[116:119], v[48:63]
	s_waitcnt lgkmcnt(0)
	v_mfma_f32_32x32x16_bf16 v[32:47], v[68:71], v[116:119], v[32:47]
	ds_read_b128 v[64:67], v193 offset:16384
	ds_read_b128 v[68:71], v193 offset:24576
	s_waitcnt lgkmcnt(1)
	v_mfma_f32_32x32x16_bf16 v[16:31], v[64:67], v[116:119], v[16:31]
	s_waitcnt lgkmcnt(0)
	v_mfma_f32_32x32x16_bf16 v[0:15], v[68:71], v[116:119], v[0:15]
	ds_read_b128 v[64:67], v193 offset:1024
	ds_read_b128 v[68:71], v193 offset:9216
	s_waitcnt lgkmcnt(1)
	v_mfma_f32_32x32x16_bf16 v[48:63], v[64:67], v[112:115], v[48:63]
	s_waitcnt lgkmcnt(0)
	v_mfma_f32_32x32x16_bf16 v[32:47], v[68:71], v[112:115], v[32:47]
	ds_read_b128 v[64:67], v193 offset:17408
	ds_read_b128 v[68:71], v193 offset:25600
	s_waitcnt lgkmcnt(1)
	v_mfma_f32_32x32x16_bf16 v[16:31], v[64:67], v[112:115], v[16:31]
	s_waitcnt lgkmcnt(0)
	v_mfma_f32_32x32x16_bf16 v[0:15], v[68:71], v[112:115], v[0:15]
	ds_read_b128 v[64:67], v193 offset:2048
	ds_read_b128 v[68:71], v193 offset:10240
	s_waitcnt lgkmcnt(1)
	v_mfma_f32_32x32x16_bf16 v[48:63], v[64:67], v[108:111], v[48:63]
	s_waitcnt lgkmcnt(0)
	v_mfma_f32_32x32x16_bf16 v[32:47], v[68:71], v[108:111], v[32:47]
	ds_read_b128 v[64:67], v193 offset:18432
	ds_read_b128 v[68:71], v193 offset:26624
	s_waitcnt lgkmcnt(1)
	v_mfma_f32_32x32x16_bf16 v[16:31], v[64:67], v[108:111], v[16:31]
	s_waitcnt lgkmcnt(0)
	v_mfma_f32_32x32x16_bf16 v[0:15], v[68:71], v[108:111], v[0:15]
	ds_read_b128 v[64:67], v193 offset:3072
	ds_read_b128 v[68:71], v193 offset:11264
	s_waitcnt lgkmcnt(1)
	v_mfma_f32_32x32x16_bf16 v[48:63], v[64:67], v[104:107], v[48:63]
	s_waitcnt lgkmcnt(0)
	v_mfma_f32_32x32x16_bf16 v[32:47], v[68:71], v[104:107], v[32:47]
	ds_read_b128 v[64:67], v193 offset:19456
	ds_read_b128 v[68:71], v193 offset:27648
	s_waitcnt lgkmcnt(1)
	v_mfma_f32_32x32x16_bf16 v[16:31], v[64:67], v[104:107], v[16:31]
	s_waitcnt lgkmcnt(0)
	v_mfma_f32_32x32x16_bf16 v[0:15], v[68:71], v[104:107], v[0:15]
	ds_read_b128 v[64:67], v193 offset:4096
	ds_read_b128 v[68:71], v193 offset:12288
	s_waitcnt lgkmcnt(1)
	v_mfma_f32_32x32x16_bf16 v[48:63], v[64:67], v[100:103], v[48:63]
	s_waitcnt lgkmcnt(0)
	v_mfma_f32_32x32x16_bf16 v[32:47], v[68:71], v[100:103], v[32:47]
	ds_read_b128 v[64:67], v193 offset:20480
	ds_read_b128 v[68:71], v193 offset:28672
	s_waitcnt lgkmcnt(1)
; #define MFMA32(a, b, c) __builtin_amdgcn_mfma_f32_32x32x16_bf16((a), (b), (c), 0, 0, 0)
; #define STOREV(tid) do { _Pragma("unroll") for (int i = 0; i < 8; ++i) vbuf[tid + i * 256] = sr[i]; } while (0)
; DI void attn_prompt_block(const Params& p, int l, int b, int hh, int tt4, char* smem, bfr* Obuf) {
;     ...
; #pragma unroll
;     for (int kk = 0; kk < 8; ++kk)
; #pragma unroll
;       for (int d = 0; d < 4; ++d) {
;         bf16x8 vf = __builtin_bit_cast(bf16x8, vbuf[(d * 8 + kk) * 64 + lanev]);
;         o[d] = MFMA32(vf, pb[((v & 1) * 8 + kk) >> 1][kk & 1], o[d]);
;         if (d == 3) __builtin_amdgcn_sched_barrier(0);
;       }
;     if (v & 1) {
; #pragma unroll
;       for (int d = 0; d < 4; ++d)
; #pragma unroll
;         for (int g4 = 0; g4 < 4; ++g4) {
;           int dim = ((v >> 1) * 4 + d) * 32 + 8 * g4 + 4 * hlv;
;           uint2 ov;
;           ov.x = pack2(o[d][g4 * 4 + 0] * inv, o[d][g4 * 4 + 1] * inv);
;           ov.y = pack2(o[d][g4 * 4 + 2] * inv, o[d][g4 * 4 + 3] * inv);
;           *(uint2*)(Obuf + ooff + dim) = ov;
;         }
;     }
;     __syncthreads();
;     if (v < 3) { STOREV(tidv); __syncthreads(); }
; DI void phase_attn(const Params& p, int l, char* smem) {
;     ...
;       for (int k = bi; k < 256; k += nb) {
;         int u = 2 * k + (upper ? 1 : 0);
;         if (nb == 256) { const int x = k & 7, j = (k >> 3) * 2 + (upper ? 1 : 0); u = (4 * x + (j >> 4)) * 16 + (j & 15); }
;         const int tt4 = u & 15, hh = (u >> 4) & 3, b = u >> 6;
;         attn_prompt_block(p, l, b, hh, tt4, smem, Obuf);
	v_mfma_f32_32x32x16_bf16 v[16:31], v[64:67], v[100:103], v[16:31]
	s_waitcnt lgkmcnt(0)
	v_mfma_f32_32x32x16_bf16 v[0:15], v[68:71], v[100:103], v[0:15]
	ds_read_b128 v[64:67], v193 offset:5120
	ds_read_b128 v[68:71], v193 offset:13312
	s_waitcnt lgkmcnt(1)
	v_mfma_f32_32x32x16_bf16 v[48:63], v[64:67], v[96:99], v[48:63]
	s_waitcnt lgkmcnt(0)
	v_mfma_f32_32x32x16_bf16 v[32:47], v[68:71], v[96:99], v[32:47]
	ds_read_b128 v[64:67], v193 offset:21504
	ds_read_b128 v[68:71], v193 offset:29696
	s_waitcnt lgkmcnt(1)
	v_mfma_f32_32x32x16_bf16 v[16:31], v[64:67], v[96:99], v[16:31]
	s_waitcnt lgkmcnt(0)
	v_mfma_f32_32x32x16_bf16 v[0:15], v[68:71], v[96:99], v[0:15]
	ds_read_b128 v[64:67], v193 offset:6144
	ds_read_b128 v[68:71], v193 offset:14336
	s_waitcnt lgkmcnt(1)
	v_mfma_f32_32x32x16_bf16 v[48:63], v[64:67], v[92:95], v[48:63]
	s_waitcnt lgkmcnt(0)
	v_mfma_f32_32x32x16_bf16 v[32:47], v[68:71], v[92:95], v[32:47]
	ds_read_b128 v[64:67], v193 offset:22528
	ds_read_b128 v[68:71], v193 offset:30720
	s_waitcnt lgkmcnt(1)
	v_mfma_f32_32x32x16_bf16 v[16:31], v[64:67], v[92:95], v[16:31]
	s_waitcnt lgkmcnt(0)
	v_mfma_f32_32x32x16_bf16 v[0:15], v[68:71], v[92:95], v[0:15]
	ds_read_b128 v[64:67], v193 offset:7168
	ds_read_b128 v[68:71], v193 offset:15360
	s_waitcnt lgkmcnt(1)
	v_mfma_f32_32x32x16_bf16 v[48:63], v[64:67], v[88:91], v[48:63]
	s_waitcnt lgkmcnt(0)
	v_mfma_f32_32x32x16_bf16 v[32:47], v[68:71], v[88:91], v[32:47]
	ds_read_b128 v[64:67], v193 offset:23552
	ds_read_b128 v[68:71], v193 offset:31744
	s_waitcnt lgkmcnt(1)
	v_mfma_f32_32x32x16_bf16 v[16:31], v[64:67], v[88:91], v[16:31]
	s_waitcnt lgkmcnt(0)
	v_mfma_f32_32x32x16_bf16 v[0:15], v[68:71], v[88:91], v[0:15]
	s_nop 3
	v_mul_f32_e64 v48, v180, v48
	v_mul_f32_e64 v49, v180, v49
	v_mul_f32_e64 v50, v180, v50
	v_mul_f32_e64 v51, v180, v51
	v_mul_f32_e64 v32, v180, v32
	v_mul_f32_e64 v33, v180, v33
	v_pk_mul_f32 v[34:35], v[180:181], v[34:35] op_sel_hi:[0,1]
	v_pk_mul_f32 v[16:17], v[180:181], v[16:17] op_sel_hi:[0,1]
	v_pk_mul_f32 v[18:19], v[180:181], v[18:19] op_sel_hi:[0,1]
	v_pk_mul_f32 v[0:1], v[180:181], v[0:1] op_sel_hi:[0,1]
	v_pk_mul_f32 v[2:3], v[180:181], v[2:3] op_sel_hi:[0,1]
	v_cvt_pk_bf16_f32 v48, v48, v49
	v_cvt_pk_bf16_f32 v49, v50, v51
	v_cvt_pk_bf16_f32 v32, v32, v33
	v_cvt_pk_bf16_f32 v33, v34, v35
	v_cvt_pk_bf16_f32 v16, v16, v17
	v_cvt_pk_bf16_f32 v17, v18, v19
	v_cvt_pk_bf16_f32 v0, v0, v1
	v_cvt_pk_bf16_f32 v1, v2, v3
	global_store_dwordx2 v[182:183], v[48:49], off offset:256 sc1
	v_pk_mul_f32 v[48:49], v[180:181], v[52:53] op_sel_hi:[0,1]
	v_pk_mul_f32 v[50:51], v[180:181], v[54:55] op_sel_hi:[0,1]
	global_store_dwordx2 v[182:183], v[32:33], off offset:320 sc1
	v_pk_mul_f32 v[32:33], v[180:181], v[36:37] op_sel_hi:[0,1]
	v_pk_mul_f32 v[34:35], v[180:181], v[38:39] op_sel_hi:[0,1]
	global_store_dwordx2 v[182:183], v[16:17], off offset:384 sc1
	v_pk_mul_f32 v[16:17], v[180:181], v[20:21] op_sel_hi:[0,1]
	v_pk_mul_f32 v[18:19], v[180:181], v[22:23] op_sel_hi:[0,1]
	global_store_dwordx2 v[182:183], v[0:1], off offset:448 sc1
	v_pk_mul_f32 v[0:1], v[180:181], v[4:5] op_sel_hi:[0,1]
	v_pk_mul_f32 v[2:3], v[180:181], v[6:7] op_sel_hi:[0,1]
	v_cvt_pk_bf16_f32 v48, v48, v49
	v_cvt_pk_bf16_f32 v49, v50, v51
	v_cvt_pk_bf16_f32 v32, v32, v33
	v_cvt_pk_bf16_f32 v33, v34, v35
	v_cvt_pk_bf16_f32 v16, v16, v17
	v_cvt_pk_bf16_f32 v17, v18, v19
	v_cvt_pk_bf16_f32 v0, v0, v1
	v_cvt_pk_bf16_f32 v1, v2, v3
	global_store_dwordx2 v[182:183], v[48:49], off offset:272 sc1
	v_pk_mul_f32 v[48:49], v[180:181], v[56:57] op_sel_hi:[0,1]
	v_pk_mul_f32 v[50:51], v[180:181], v[58:59] op_sel_hi:[0,1]
	global_store_dwordx2 v[182:183], v[32:33], off offset:336 sc1
	v_pk_mul_f32 v[32:33], v[180:181], v[40:41] op_sel_hi:[0,1]
	v_pk_mul_f32 v[34:35], v[180:181], v[42:43] op_sel_hi:[0,1]
	global_store_dwordx2 v[182:183], v[16:17], off offset:400 sc1
	v_pk_mul_f32 v[16:17], v[180:181], v[24:25] op_sel_hi:[0,1]
	v_pk_mul_f32 v[18:19], v[180:181], v[26:27] op_sel_hi:[0,1]
	global_store_dwordx2 v[182:183], v[0:1], off offset:464 sc1
	v_pk_mul_f32 v[0:1], v[180:181], v[8:9] op_sel_hi:[0,1]
	v_pk_mul_f32 v[2:3], v[180:181], v[10:11] op_sel_hi:[0,1]
	v_cvt_pk_bf16_f32 v48, v48, v49
	v_cvt_pk_bf16_f32 v49, v50, v51
	v_cvt_pk_bf16_f32 v32, v32, v33
	v_cvt_pk_bf16_f32 v33, v34, v35
	v_cvt_pk_bf16_f32 v16, v16, v17
	v_cvt_pk_bf16_f32 v17, v18, v19
	v_cvt_pk_bf16_f32 v0, v0, v1
	v_cvt_pk_bf16_f32 v1, v2, v3
	global_store_dwordx2 v[182:183], v[48:49], off offset:288 sc1
	v_pk_mul_f32 v[48:49], v[180:181], v[60:61] op_sel_hi:[0,1]
	v_pk_mul_f32 v[50:51], v[180:181], v[62:63] op_sel_hi:[0,1]
	global_store_dwordx2 v[182:183], v[32:33], off offset:352 sc1
	v_pk_mul_f32 v[32:33], v[180:181], v[44:45] op_sel_hi:[0,1]
	v_pk_mul_f32 v[34:35], v[180:181], v[46:47] op_sel_hi:[0,1]
	global_store_dwordx2 v[182:183], v[16:17], off offset:416 sc1
	v_pk_mul_f32 v[16:17], v[180:181], v[28:29] op_sel_hi:[0,1]
	v_pk_mul_f32 v[18:19], v[180:181], v[30:31] op_sel_hi:[0,1]
	global_store_dwordx2 v[182:183], v[0:1], off offset:480 sc1
	v_pk_mul_f32 v[0:1], v[180:181], v[12:13] op_sel_hi:[0,1]
	v_pk_mul_f32 v[2:3], v[180:181], v[14:15] op_sel_hi:[0,1]
	s_add_i32 s42, s42, s23
	s_add_i32 s21, s21, s30
	s_add_i32 s20, s20, s33
	v_cvt_pk_bf16_f32 v48, v48, v49
	v_cvt_pk_bf16_f32 v49, v50, v51
	v_cvt_pk_bf16_f32 v32, v32, v33
	v_cvt_pk_bf16_f32 v33, v34, v35
	v_cvt_pk_bf16_f32 v16, v16, v17
	v_cvt_pk_bf16_f32 v17, v18, v19
	v_cvt_pk_bf16_f32 v0, v0, v1
	v_cvt_pk_bf16_f32 v1, v2, v3
	s_cmpk_lt_i32 s42, 0x100
	global_store_dwordx2 v[182:183], v[48:49], off offset:304 sc1
	global_store_dwordx2 v[182:183], v[32:33], off offset:368 sc1
	global_store_dwordx2 v[182:183], v[16:17], off offset:432 sc1
	global_store_dwordx2 v[182:183], v[0:1], off offset:496 sc1
	s_barrier
	s_cbranch_scc0 .LBB0_1618

; DI void phase_final_norm(const Params& p) {
;   const float* ss = p.SS + 3 * NROW;
;   for (int i = blockIdx.x * 256 + threadIdx.x; i < NROW * 256; i += gridDim.x * 256) {
;     const int row = i >> 8, c4 = i & 255;
;     float4 v = ((const float4*)p.X)[i];
;     float4 g = ((const float4*)p.norm_final)[c4];
;     const float inv = rsqrtf(ss[row] * (1.0f / 1024.0f) + EPSF);
;     float4 o = {v.x * inv * g.x, v.y * inv * g.y, v.z * inv * g.z, v.w * inv * g.w};
;     ((float4*)(p.out + O_Y))[i] = o;
;   }
.LBB0_1798:
	v_ashrrev_i32_e32 v4, 8, v198
	v_ashrrev_i32_e32 v5, 31, v4
	v_lshl_add_u64 v[4:5], v[4:5], 2, s[10:11]
	global_load_dword v3, v[4:5], off
	v_ashrrev_i32_e32 v199, 31, v198
	v_lshlrev_b64 v[12:13], 4, v[198:199]
	v_lshl_add_u64 v[14:15], s[6:7], 0, v[12:13]
	global_load_dwordx4 v[4:7], v[14:15], off
	global_load_dwordx4 v[8:11], v[0:1], off
	v_add_u32_e32 v198, s14, v198
	v_cmp_lt_i32_e32 vcc, s16, v198
	v_lshl_add_u64 v[12:13], s[4:5], 0, v[12:13]
	s_or_b64 s[12:13], vcc, s[12:13]
	s_waitcnt vmcnt(2)
	v_fmamk_f32 v3, v3, 0x3a800000, v2
	v_mul_f32_e32 v14, 0x4b800000, v3
	v_cmp_gt_f32_e64 s[0:1], s15, v3
	s_nop 1
	v_cndmask_b32_e64 v3, v3, v14, s[0:1]
	v_rsq_f32_e32 v3, v3
	s_nop 0
	v_mul_f32_e32 v14, 0x45800000, v3
	v_cndmask_b32_e64 v14, v3, v14, s[0:1]
	s_waitcnt vmcnt(1)
	v_pk_mul_f32 v[4:5], v[4:5], v[14:15] op_sel_hi:[1,0]
	v_pk_mul_f32 v[6:7], v[6:7], v[14:15] op_sel_hi:[1,0]
	s_waitcnt vmcnt(0)
	v_pk_mul_f32 v[4:5], v[8:9], v[4:5]
	v_pk_mul_f32 v[6:7], v[10:11], v[6:7]
	global_store_dwordx4 v[12:13], v[4:7], off sc1
	s_andn2_b64 exec, exec, s[12:13]
	s_cbranch_execnz .LBB0_1798
